# k3 plus: removed 1600 s_nop 0 pads that hipcc put after inline-asm packed-f32 ops (no dst-sel forwarding hazard for v_pk_*_f32), each deletion checked against wait-state tables; more bit-trick deletio
# speedup vs baseline: 1.0332x; 1.0049x over previous
.LBB0_199:
	ds_read2_b32 v[52:53], v89 offset1:65
	ds_read2_b32 v[78:79], v89 offset0:130 offset1:195
	s_ashr_i32 s28, s35, 31
	s_waitcnt lgkmcnt(1)
	v_cvt_pk_bf16_f32 v106, v52, v53
	s_waitcnt lgkmcnt(0)
	ds_read2_b32 v[52:53], v101 offset0:4 offset1:69
	v_cvt_pk_bf16_f32 v107, v78, v79
	ds_read2_b32 v[78:79], v101 offset0:134 offset1:199
	s_waitcnt lgkmcnt(1)
	v_cvt_pk_bf16_f32 v108, v52, v53
	s_waitcnt lgkmcnt(0)
	v_cvt_pk_bf16_f32 v109, v78, v79
	v_or_b32_e32 v51, s35, v88
	v_mul_lo_u32 v78, s39, v51
	s_mul_i32 s35, s38, s28
	v_mad_u64_u32 v[52:53], s[28:29], s38, v51, 0
	v_add3_u32 v53, v53, s35, v78
	ds_read2_b32 v[78:79], v90 offset1:65
	v_lshl_add_u64 v[52:53], v[52:53], 1, s[36:37]
	s_ashr_i32 s35, s34, 31
	v_lshl_add_u64 v[52:53], s[34:35], 1, v[52:53]
	v_lshl_add_u64 v[110:111], v[70:71], 1, v[52:53]
	global_store_dwordx4 v[110:111], v[106:109], off
	s_waitcnt lgkmcnt(0)
	s_nop 0
	ds_read2_b32 v[108:109], v90 offset0:130 offset1:195
	v_cvt_pk_bf16_f32 v106, v78, v79
	ds_read2_b32 v[78:79], v102 offset0:4 offset1:69
	s_waitcnt lgkmcnt(1)
	v_cvt_pk_bf16_f32 v107, v108, v109
	ds_read2_b32 v[110:111], v102 offset0:134 offset1:199
	s_waitcnt lgkmcnt(1)
	v_cvt_pk_bf16_f32 v108, v78, v79
	ds_read2_b32 v[78:79], v91 offset1:65
	s_waitcnt lgkmcnt(1)
	v_cvt_pk_bf16_f32 v109, v110, v111
	v_lshl_add_u64 v[110:111], v[72:73], 1, v[52:53]
	global_store_dwordx4 v[110:111], v[106:109], off
	s_waitcnt lgkmcnt(0)
	v_cvt_pk_bf16_f32 v106, v78, v79
	ds_read2_b32 v[108:109], v91 offset0:130 offset1:195
	ds_read2_b32 v[78:79], v103 offset0:4 offset1:69
	s_waitcnt lgkmcnt(1)
	v_cvt_pk_bf16_f32 v107, v108, v109
	ds_read2_b32 v[102:103], v103 offset0:134 offset1:199
	s_waitcnt lgkmcnt(1)
	v_cvt_pk_bf16_f32 v108, v78, v79
	ds_read2_b32 v[78:79], v92 offset1:65
	s_waitcnt lgkmcnt(1)
	v_cvt_pk_bf16_f32 v109, v102, v103
	v_lshl_add_u64 v[102:103], v[74:75], 1, v[52:53]
	global_store_dwordx4 v[102:103], v[106:109], off
	s_waitcnt lgkmcnt(0)
	v_cvt_pk_bf16_f32 v102, v78, v79
	ds_read2_b32 v[106:107], v92 offset0:130 offset1:195
	ds_read2_b32 v[78:79], v104 offset0:4 offset1:69
	s_waitcnt lgkmcnt(1)
	v_cvt_pk_bf16_f32 v103, v106, v107
	ds_read2_b32 v[106:107], v104 offset0:134 offset1:199
	s_waitcnt lgkmcnt(1)
	v_cvt_pk_bf16_f32 v104, v78, v79
	s_waitcnt lgkmcnt(0)
	v_bfe_u32 v51, v106, 16, 1
	v_add3_u32 v51, v106, v51, s84
	v_bfe_u32 v78, v107, 16, 1
	v_lshrrev_b32_e32 v51, 16, v51
	v_add3_u32 v78, v107, v78, s84
	v_and_or_b32 v105, v78, s85, v51
	v_lshl_add_u64 v[52:53], v[76:77], 1, v[52:53]
	global_store_dwordx4 v[52:53], v[102:105], off
	s_waitcnt lgkmcnt(0)
	s_barrier

.LBB0_308:
	ds_read2_b32 v[52:53], v89 offset1:65
	ds_read2_b32 v[78:79], v89 offset0:130 offset1:195
	s_ashr_i32 s28, s35, 31
	s_waitcnt lgkmcnt(1)
	v_cvt_pk_bf16_f32 v102, v52, v53
	v_add_u32_e32 v101, 0x400, v89
	s_waitcnt lgkmcnt(0)
	v_cvt_pk_bf16_f32 v103, v78, v79
	ds_read2_b32 v[52:53], v101 offset0:4 offset1:69
	ds_read2_b32 v[78:79], v101 offset0:134 offset1:199
	s_waitcnt lgkmcnt(1)
	v_cvt_pk_bf16_f32 v104, v52, v53
	s_waitcnt lgkmcnt(0)
	v_cvt_pk_bf16_f32 v105, v78, v79
	v_or_b32_e32 v51, s35, v88
	v_mul_lo_u32 v78, s39, v51
	s_mul_i32 s35, s38, s28
	v_mad_u64_u32 v[52:53], s[28:29], s38, v51, 0
	v_add3_u32 v53, v53, s35, v78
	v_lshl_add_u64 v[52:53], v[52:53], 1, s[36:37]
	ds_read2_b32 v[78:79], v90 offset1:65
	s_ashr_i32 s35, s34, 31
	v_lshl_add_u64 v[52:53], s[34:35], 1, v[52:53]
	v_lshl_add_u64 v[106:107], v[70:71], 1, v[52:53]
	global_store_dwordx4 v[106:107], v[102:105], off
	ds_read2_b32 v[102:103], v90 offset0:130 offset1:195
	s_waitcnt lgkmcnt(1)
	v_cvt_pk_bf16_f32 v104, v78, v79
	s_waitcnt lgkmcnt(0)
	v_cvt_pk_bf16_f32 v105, v102, v103
	v_add_u32_e32 v102, 0x400, v90
	ds_read2_b32 v[78:79], v102 offset0:4 offset1:69
	ds_read2_b32 v[108:109], v102 offset0:134 offset1:199
	s_waitcnt lgkmcnt(1)
	v_cvt_pk_bf16_f32 v106, v78, v79
	ds_read2_b32 v[78:79], v91 offset1:65
	s_waitcnt lgkmcnt(1)
	v_cvt_pk_bf16_f32 v107, v108, v109
	v_lshl_add_u64 v[108:109], v[72:73], 1, v[52:53]
	global_store_dwordx4 v[108:109], v[104:107], off
	s_waitcnt lgkmcnt(0)
	v_cvt_pk_bf16_f32 v104, v78, v79
	ds_read2_b32 v[106:107], v91 offset0:130 offset1:195
	v_add_u32_e32 v103, 0x400, v91
	ds_read2_b32 v[78:79], v103 offset0:4 offset1:69
	s_waitcnt lgkmcnt(1)
	v_cvt_pk_bf16_f32 v105, v106, v107
	ds_read2_b32 v[108:109], v103 offset0:134 offset1:199
	s_waitcnt lgkmcnt(1)
	v_cvt_pk_bf16_f32 v106, v78, v79
	s_waitcnt lgkmcnt(0)
	v_cvt_pk_bf16_f32 v107, v108, v109
	ds_read2_b32 v[78:79], v92 offset1:65
	v_lshl_add_u64 v[108:109], v[74:75], 1, v[52:53]
	global_store_dwordx4 v[108:109], v[104:107], off
	ds_read2_b32 v[104:105], v92 offset0:130 offset1:195
	s_waitcnt lgkmcnt(1)
	v_cvt_pk_bf16_f32 v106, v78, v79
	s_waitcnt lgkmcnt(0)
	v_cvt_pk_bf16_f32 v107, v104, v105
	v_add_u32_e32 v104, 0x400, v92
	ds_read2_b32 v[78:79], v104 offset0:4 offset1:69
	ds_read2_b32 v[110:111], v104 offset0:134 offset1:199
	s_waitcnt lgkmcnt(1)
	v_cvt_pk_bf16_f32 v108, v78, v79
	s_waitcnt lgkmcnt(0)
	v_bfe_u32 v51, v110, 16, 1
	v_add3_u32 v51, v110, v51, s84
	v_bfe_u32 v78, v111, 16, 1
	v_lshrrev_b32_e32 v51, 16, v51
	v_add3_u32 v78, v111, v78, s84
	v_and_or_b32 v109, v78, s85, v51
	v_lshl_add_u64 v[52:53], v[76:77], 1, v[52:53]
	global_store_dwordx4 v[52:53], v[106:109], off
	s_waitcnt lgkmcnt(0)
	s_barrier
	s_add_i32 s28, s24, s87
	s_cmpk_gt_i32 s28, 0x127f
	s_cbranch_scc1 .LBB0_200
	s_cmpk_gt_i32 s28, 0xe3f
	s_cbranch_scc0 .LBB0_312
	s_add_i32 s29, s80, s67
	s_cmpk_gt_u32 s28, 0x123f
	s_cbranch_scc0 .LBB0_313
	s_add_i32 s34, s78, s68
	s_and_b32 s34, s34, 0x7fffff00
	s_and_b32 s35, s29, 0x3c0
	s_add_i32 s34, s34, 0xfffedc00
	s_mov_b64 s[36:37], s[22:23]
	s_mov_b64 s[38:39], 0x400
	s_cbranch_execz .LBB0_314
	s_branch .LBB0_315

.LBB0_885:
	ds_read2_b32 v[52:53], v89 offset1:65
	ds_read2_b32 v[78:79], v89 offset0:130 offset1:195
	s_waitcnt lgkmcnt(1)
	v_cvt_pk_bf16_f32 v106, v52, v53
	s_waitcnt lgkmcnt(0)
	ds_read2_b32 v[52:53], v101 offset0:4 offset1:69
	v_cvt_pk_bf16_f32 v107, v78, v79
	ds_read2_b32 v[78:79], v101 offset0:134 offset1:199
	s_waitcnt lgkmcnt(1)
	v_cvt_pk_bf16_f32 v108, v52, v53
	s_waitcnt lgkmcnt(0)
	v_cvt_pk_bf16_f32 v109, v78, v79
	v_or_b32_e32 v51, s21, v88
	s_ashr_i32 s21, s21, 31
	v_mul_lo_u32 v78, s23, v51
	s_mul_i32 s21, s22, s21
	v_mad_u64_u32 v[52:53], s[22:23], s22, v51, 0
	v_add3_u32 v53, v53, s21, v78
	ds_read2_b32 v[78:79], v90 offset1:65
	v_lshl_add_u64 v[52:53], v[52:53], 1, s[26:27]
	s_ashr_i32 s21, s20, 31
	v_lshl_add_u64 v[52:53], s[20:21], 1, v[52:53]
	v_lshl_add_u64 v[110:111], v[70:71], 1, v[52:53]
	global_store_dwordx4 v[110:111], v[106:109], off
	s_waitcnt lgkmcnt(0)
	s_nop 0
	ds_read2_b32 v[108:109], v90 offset0:130 offset1:195
	v_cvt_pk_bf16_f32 v106, v78, v79
	ds_read2_b32 v[78:79], v102 offset0:4 offset1:69
	s_waitcnt lgkmcnt(1)
	v_cvt_pk_bf16_f32 v107, v108, v109
	ds_read2_b32 v[110:111], v102 offset0:134 offset1:199
	s_waitcnt lgkmcnt(1)
	v_cvt_pk_bf16_f32 v108, v78, v79
	ds_read2_b32 v[78:79], v91 offset1:65
	s_waitcnt lgkmcnt(1)
	v_cvt_pk_bf16_f32 v109, v110, v111
	v_lshl_add_u64 v[110:111], v[72:73], 1, v[52:53]
	global_store_dwordx4 v[110:111], v[106:109], off
	s_waitcnt lgkmcnt(0)
	v_cvt_pk_bf16_f32 v106, v78, v79
	ds_read2_b32 v[108:109], v91 offset0:130 offset1:195
	ds_read2_b32 v[78:79], v103 offset0:4 offset1:69
	s_waitcnt lgkmcnt(1)
	v_cvt_pk_bf16_f32 v107, v108, v109
	ds_read2_b32 v[102:103], v103 offset0:134 offset1:199
	s_waitcnt lgkmcnt(1)
	v_cvt_pk_bf16_f32 v108, v78, v79
	ds_read2_b32 v[78:79], v92 offset1:65
	s_waitcnt lgkmcnt(1)
	v_cvt_pk_bf16_f32 v109, v102, v103
	v_lshl_add_u64 v[102:103], v[74:75], 1, v[52:53]
	global_store_dwordx4 v[102:103], v[106:109], off
	s_waitcnt lgkmcnt(0)
	v_cvt_pk_bf16_f32 v102, v78, v79
	ds_read2_b32 v[106:107], v92 offset0:130 offset1:195
	ds_read2_b32 v[78:79], v104 offset0:4 offset1:69
	s_waitcnt lgkmcnt(1)
	v_cvt_pk_bf16_f32 v103, v106, v107
	ds_read2_b32 v[106:107], v104 offset0:134 offset1:199
	s_waitcnt lgkmcnt(1)
	v_cvt_pk_bf16_f32 v104, v78, v79
	s_waitcnt lgkmcnt(0)
	v_bfe_u32 v51, v106, 16, 1
	v_add3_u32 v51, v106, v51, s80
	v_bfe_u32 v78, v107, 16, 1
	v_lshrrev_b32_e32 v51, 16, v51
	v_add3_u32 v78, v107, v78, s80
	v_and_or_b32 v105, v78, s81, v51
	v_lshl_add_u64 v[52:53], v[76:77], 1, v[52:53]
	global_store_dwordx4 v[52:53], v[102:105], off
	s_waitcnt lgkmcnt(0)
	s_barrier

.LBB0_994:
	ds_read2_b32 v[52:53], v89 offset1:65
	ds_read2_b32 v[78:79], v89 offset0:130 offset1:195
	s_add_i32 s28, s62, s83
	s_waitcnt lgkmcnt(1)
	v_cvt_pk_bf16_f32 v102, v52, v53
	v_add_u32_e32 v101, 0x400, v89
	s_waitcnt lgkmcnt(0)
	v_cvt_pk_bf16_f32 v103, v78, v79
	ds_read2_b32 v[52:53], v101 offset0:4 offset1:69
	ds_read2_b32 v[78:79], v101 offset0:134 offset1:199
	s_waitcnt lgkmcnt(1)
	v_cvt_pk_bf16_f32 v104, v52, v53
	s_waitcnt lgkmcnt(0)
	v_cvt_pk_bf16_f32 v105, v78, v79
	v_or_b32_e32 v51, s21, v88
	s_ashr_i32 s21, s21, 31
	v_mul_lo_u32 v78, s23, v51
	s_mul_i32 s21, s22, s21
	v_mad_u64_u32 v[52:53], s[22:23], s22, v51, 0
	v_add3_u32 v53, v53, s21, v78
	v_lshl_add_u64 v[52:53], v[52:53], 1, s[26:27]
	ds_read2_b32 v[78:79], v90 offset1:65
	s_ashr_i32 s21, s20, 31
	v_lshl_add_u64 v[52:53], s[20:21], 1, v[52:53]
	v_lshl_add_u64 v[106:107], v[70:71], 1, v[52:53]
	global_store_dwordx4 v[106:107], v[102:105], off
	ds_read2_b32 v[102:103], v90 offset0:130 offset1:195
	s_waitcnt lgkmcnt(1)
	v_cvt_pk_bf16_f32 v104, v78, v79
	s_waitcnt lgkmcnt(0)
	v_cvt_pk_bf16_f32 v105, v102, v103
	v_add_u32_e32 v102, 0x400, v90
	ds_read2_b32 v[78:79], v102 offset0:4 offset1:69
	ds_read2_b32 v[108:109], v102 offset0:134 offset1:199
	s_waitcnt lgkmcnt(1)
	v_cvt_pk_bf16_f32 v106, v78, v79
	ds_read2_b32 v[78:79], v91 offset1:65
	s_waitcnt lgkmcnt(1)
	v_cvt_pk_bf16_f32 v107, v108, v109
	v_lshl_add_u64 v[108:109], v[72:73], 1, v[52:53]
	global_store_dwordx4 v[108:109], v[104:107], off
	s_waitcnt lgkmcnt(0)
	v_cvt_pk_bf16_f32 v104, v78, v79
	ds_read2_b32 v[106:107], v91 offset0:130 offset1:195
	v_add_u32_e32 v103, 0x400, v91
	ds_read2_b32 v[78:79], v103 offset0:4 offset1:69
	s_waitcnt lgkmcnt(1)
	v_cvt_pk_bf16_f32 v105, v106, v107
	ds_read2_b32 v[108:109], v103 offset0:134 offset1:199
	s_waitcnt lgkmcnt(1)
	v_cvt_pk_bf16_f32 v106, v78, v79
	s_waitcnt lgkmcnt(0)
	v_cvt_pk_bf16_f32 v107, v108, v109
	ds_read2_b32 v[78:79], v92 offset1:65
	v_lshl_add_u64 v[108:109], v[74:75], 1, v[52:53]
	global_store_dwordx4 v[108:109], v[104:107], off
	ds_read2_b32 v[104:105], v92 offset0:130 offset1:195
	s_waitcnt lgkmcnt(1)
	v_cvt_pk_bf16_f32 v106, v78, v79
	s_waitcnt lgkmcnt(0)
	v_cvt_pk_bf16_f32 v107, v104, v105
	v_add_u32_e32 v104, 0x400, v92
	ds_read2_b32 v[78:79], v104 offset0:4 offset1:69
	ds_read2_b32 v[110:111], v104 offset0:134 offset1:199
	s_waitcnt lgkmcnt(1)
	v_cvt_pk_bf16_f32 v108, v78, v79
	s_waitcnt lgkmcnt(0)
	v_bfe_u32 v51, v110, 16, 1
	v_add3_u32 v51, v110, v51, s80
	v_bfe_u32 v78, v111, 16, 1
	v_lshrrev_b32_e32 v51, 16, v51
	v_add3_u32 v78, v111, v78, s80
	v_and_or_b32 v109, v78, s81, v51
	v_lshl_add_u64 v[52:53], v[76:77], 1, v[52:53]
	global_store_dwordx4 v[52:53], v[106:109], off
	s_waitcnt lgkmcnt(0)
	s_barrier
	s_cmpk_gt_i32 s28, 0x43f
	s_cbranch_scc1 .LBB0_886
	s_addk_i32 s28, 0xe40
	s_cmpk_gt_i32 s28, 0xe3f
	s_mov_b64 s[34:35], -1
	s_cbranch_scc0 .LBB0_1001
	s_add_i32 s29, s76, s69
	s_cmpk_gt_u32 s28, 0x123f
	s_mov_b64 s[26:27], -1
	s_cbranch_scc0 .LBB0_998
	s_add_i32 s20, s74, s64
	s_and_b32 s20, s20, 0xffffff00
	s_and_b32 s21, s29, 0x3c0
	s_add_i32 s20, s20, 0xfffedc00
	s_mov_b64 s[26:27], 0

.LBB0_1295:
	s_or_b64 exec, exec, s[0:1]
	v_mul_u32_u24_e32 v38, 0x88, v138
	s_waitcnt lgkmcnt(0)
	v_pk_add_f32 v[74:75], v[42:43], v[58:59]
	v_pk_add_f32 v[42:43], v[42:43], v[58:59] neg_lo:[0,1] neg_hi:[0,1]
	v_pk_add_f32 v[58:59], v[50:51], v[66:67]
	v_pk_add_f32 v[50:51], v[50:51], v[66:67] neg_lo:[0,1] neg_hi:[0,1]
	v_lshl_add_u32 v146, v143, 11, v77
	v_add_u32_e32 v147, v76, v38
	v_pk_add_f32 v[66:67], v[74:75], v[58:59]
	v_pk_add_f32 v[58:59], v[74:75], v[58:59] neg_lo:[0,1] neg_hi:[0,1]
	v_pk_add_f32 v[74:75], v[42:43], v[50:51] op_sel:[0,1] op_sel_hi:[1,0] neg_hi:[0,1]
	v_pk_add_f32 v[76:77], v[42:43], v[50:51] op_sel:[0,1] op_sel_hi:[1,0] neg_lo:[0,1]
	v_pk_add_f32 v[42:43], v[44:45], v[60:61]
	v_pk_add_f32 v[44:45], v[44:45], v[60:61] neg_lo:[0,1] neg_hi:[0,1]
	v_pk_add_f32 v[50:51], v[52:53], v[68:69]
	v_pk_add_f32 v[52:53], v[52:53], v[68:69] neg_lo:[0,1] neg_hi:[0,1]
	v_pk_add_f32 v[60:61], v[42:43], v[50:51]
	v_pk_add_f32 v[50:51], v[42:43], v[50:51] neg_lo:[0,1] neg_hi:[0,1]
	v_pk_add_f32 v[42:43], v[44:45], v[52:53] op_sel:[0,1] op_sel_hi:[1,0] neg_hi:[0,1]
	v_pk_add_f32 v[52:53], v[44:45], v[52:53] op_sel:[0,1] op_sel_hi:[1,0] neg_lo:[0,1]
	v_pk_add_f32 v[44:45], v[46:47], v[62:63]
	v_pk_add_f32 v[46:47], v[46:47], v[62:63] neg_lo:[0,1] neg_hi:[0,1]
	v_pk_add_f32 v[62:63], v[54:55], v[70:71]
	v_pk_add_f32 v[54:55], v[54:55], v[70:71] neg_lo:[0,1] neg_hi:[0,1]
	v_pk_add_f32 v[68:69], v[44:45], v[62:63]
	v_pk_add_f32 v[62:63], v[44:45], v[62:63] neg_lo:[0,1] neg_hi:[0,1]
	v_pk_add_f32 v[70:71], v[46:47], v[54:55] op_sel:[0,1] op_sel_hi:[1,0] neg_hi:[0,1]
	v_pk_add_f32 v[54:55], v[46:47], v[54:55] op_sel:[0,1] op_sel_hi:[1,0] neg_lo:[0,1]
	v_pk_add_f32 v[44:45], v[48:49], v[64:65]
	v_pk_add_f32 v[46:47], v[48:49], v[64:65] neg_lo:[0,1] neg_hi:[0,1]
	v_pk_add_f32 v[48:49], v[56:57], v[72:73]
	v_pk_add_f32 v[56:57], v[56:57], v[72:73] neg_lo:[0,1] neg_hi:[0,1]
	v_pk_add_f32 v[64:65], v[44:45], v[48:49]
	v_pk_add_f32 v[72:73], v[44:45], v[48:49] neg_lo:[0,1] neg_hi:[0,1]
	v_mov_b64_e32 v[48:49], s[20:21]
	v_pk_mul_f32 v[44:45], v[42:43], v[48:49] op_sel:[0,0] op_sel_hi:[0,1]
	v_pk_add_f32 v[78:79], v[46:47], v[56:57] op_sel:[0,1] op_sel_hi:[1,0] neg_hi:[0,1]
	v_pk_add_f32 v[56:57], v[46:47], v[56:57] op_sel:[0,1] op_sel_hi:[1,0] neg_lo:[0,1]
	v_and_b32_e32 v38, 15, v145
	v_pk_fma_f32 v[80:81], v[42:43], v[48:49], v[44:45] op_sel:[1,1,0] op_sel_hi:[1,0,1] neg_lo:[0,1,0]
	v_mov_b64_e32 v[44:45], s[50:51]
	v_pk_mul_f32 v[42:43], v[70:71], v[44:45] op_sel:[0,0] op_sel_hi:[0,1]
	v_mul_f32_e32 v34, 0x39800000, v34
	v_pk_fma_f32 v[70:71], v[70:71], v[44:45], v[42:43] op_sel:[1,1,0] op_sel_hi:[1,0,1] neg_lo:[0,1,0]
	v_mov_b64_e32 v[42:43], s[54:55]
	v_pk_mul_f32 v[46:47], v[78:79], v[42:43] op_sel:[0,0] op_sel_hi:[0,1]
	v_cvt_f32_ubyte0_e32 v38, v38
	v_pk_fma_f32 v[78:79], v[78:79], v[42:43], v[46:47] op_sel:[1,1,0] op_sel_hi:[1,0,1] neg_lo:[0,1,0]
	v_pk_mul_f32 v[46:47], v[50:51], v[44:45] op_sel:[0,0] op_sel_hi:[0,1]
	v_mul_f32_e32 v39, 0x3b800000, v38
	v_pk_fma_f32 v[82:83], v[50:51], v[44:45], v[46:47] op_sel:[1,1,0] op_sel_hi:[1,0,1] neg_lo:[0,1,0]
	v_mov_b64_e32 v[50:51], s[14:15]
	v_pk_mul_f32 v[46:47], v[62:63], v[50:51] op_sel:[0,0] op_sel_hi:[0,1]
	v_cos_f32_e32 v38, v34
	v_pk_fma_f32 v[62:63], v[62:63], v[50:51], v[46:47] op_sel:[1,1,0] op_sel_hi:[1,0,1] neg_lo:[0,1,0]
	v_mov_b64_e32 v[46:47], s[58:59]
	v_pk_mul_f32 v[84:85], v[72:73], v[46:47] op_sel:[0,0] op_sel_hi:[0,1]
	v_sin_f32_e32 v34, v34
	v_pk_fma_f32 v[72:73], v[72:73], v[46:47], v[84:85] op_sel:[1,1,0] op_sel_hi:[1,0,1] neg_lo:[0,1,0]
	v_pk_mul_f32 v[84:85], v[52:53], v[42:43] op_sel:[0,0] op_sel_hi:[0,1]
	v_cos_f32_e32 v40, v39
	v_pk_fma_f32 v[84:85], v[52:53], v[42:43], v[84:85] op_sel:[1,1,0] op_sel_hi:[1,0,1] neg_lo:[0,1,0]
	v_pk_mul_f32 v[52:53], v[54:55], v[46:47] op_sel:[0,0] op_sel_hi:[0,1]
	v_sin_f32_e32 v41, v39
	v_pk_fma_f32 v[54:55], v[54:55], v[46:47], v[52:53] op_sel:[1,1,0] op_sel_hi:[1,0,1] neg_lo:[0,1,0]
	v_mov_b64_e32 v[52:53], s[60:61]
	v_pk_mul_f32 v[86:87], v[56:57], v[52:53] op_sel:[0,0] op_sel_hi:[0,1]
	v_xor_b32_e32 v39, 0x80000000, v34
	v_pk_fma_f32 v[56:57], v[56:57], v[52:53], v[86:87] op_sel:[1,1,0] op_sel_hi:[1,0,1] neg_lo:[0,1,0]
	v_pk_add_f32 v[86:87], v[66:67], v[68:69]
	v_pk_add_f32 v[66:67], v[66:67], v[68:69] neg_lo:[0,1] neg_hi:[0,1]
	v_pk_add_f32 v[68:69], v[60:61], v[64:65]
	v_pk_add_f32 v[60:61], v[60:61], v[64:65] neg_lo:[0,1] neg_hi:[0,1]
	v_pk_add_f32 v[64:65], v[86:87], v[68:69]
	v_pk_add_f32 v[68:69], v[86:87], v[68:69] neg_lo:[0,1] neg_hi:[0,1]
	v_pk_add_f32 v[86:87], v[66:67], v[60:61] op_sel:[0,1] op_sel_hi:[1,0] neg_hi:[0,1]
	v_pk_add_f32 v[60:61], v[66:67], v[60:61] op_sel:[0,1] op_sel_hi:[1,0] neg_lo:[0,1]
	v_pk_add_f32 v[66:67], v[74:75], v[70:71]
	v_pk_add_f32 v[70:71], v[74:75], v[70:71] neg_lo:[0,1] neg_hi:[0,1]
	v_pk_add_f32 v[74:75], v[80:81], v[78:79]
	v_pk_add_f32 v[78:79], v[80:81], v[78:79] neg_lo:[0,1] neg_hi:[0,1]
	v_pk_add_f32 v[80:81], v[66:67], v[74:75]
	v_pk_add_f32 v[66:67], v[66:67], v[74:75] neg_lo:[0,1] neg_hi:[0,1]
	v_pk_add_f32 v[74:75], v[70:71], v[78:79] op_sel:[0,1] op_sel_hi:[1,0] neg_hi:[0,1]
	v_pk_add_f32 v[70:71], v[70:71], v[78:79] op_sel:[0,1] op_sel_hi:[1,0] neg_lo:[0,1]
	v_pk_add_f32 v[78:79], v[58:59], v[62:63]
	v_pk_add_f32 v[58:59], v[58:59], v[62:63] neg_lo:[0,1] neg_hi:[0,1]
	v_pk_add_f32 v[62:63], v[82:83], v[72:73]
	v_pk_add_f32 v[72:73], v[82:83], v[72:73] neg_lo:[0,1] neg_hi:[0,1]
	v_pk_add_f32 v[82:83], v[78:79], v[62:63]
	v_pk_add_f32 v[62:63], v[78:79], v[62:63] neg_lo:[0,1] neg_hi:[0,1]
	v_pk_add_f32 v[78:79], v[58:59], v[72:73] op_sel:[0,1] op_sel_hi:[1,0] neg_hi:[0,1]
	v_pk_add_f32 v[58:59], v[58:59], v[72:73] op_sel:[0,1] op_sel_hi:[1,0] neg_lo:[0,1]
	v_pk_add_f32 v[72:73], v[76:77], v[54:55]
	v_pk_add_f32 v[54:55], v[76:77], v[54:55] neg_lo:[0,1] neg_hi:[0,1]
	v_pk_add_f32 v[76:77], v[84:85], v[56:57]
	v_pk_add_f32 v[56:57], v[84:85], v[56:57] neg_lo:[0,1] neg_hi:[0,1]
	v_pk_add_f32 v[84:85], v[72:73], v[76:77]
	v_pk_add_f32 v[72:73], v[72:73], v[76:77] neg_lo:[0,1] neg_hi:[0,1]
	v_pk_add_f32 v[76:77], v[54:55], v[56:57] op_sel:[0,1] op_sel_hi:[1,0] neg_hi:[0,1]
	v_pk_add_f32 v[54:55], v[54:55], v[56:57] op_sel:[0,1] op_sel_hi:[1,0] neg_lo:[0,1]
	v_mov_b32_e32 v56, v38
	v_mov_b32_e32 v57, v39
	s_barrier
	ds_write_b64 v144, v[64:65]
	v_pk_mul_f32 v[64:65], v[80:81], v[56:57] op_sel:[0,0] op_sel_hi:[0,1]
	v_xor_b32_e32 v41, 0x80000000, v41
	v_pk_fma_f32 v[64:65], v[80:81], v[56:57], v[64:65] op_sel:[1,1,0] op_sel_hi:[1,0,1] neg_lo:[0,1,0]
	ds_write_b64 v144, v[64:65] offset:2176
	v_pk_mul_f32 v[64:65], v[56:57], v[56:57] op_sel:[0,0] op_sel_hi:[0,1]
	s_add_u32 s0, s89, s82
	v_pk_fma_f32 v[64:65], v[56:57], v[56:57], v[64:65] op_sel:[1,1,0] op_sel_hi:[1,0,1] neg_lo:[0,1,0]
	s_addc_u32 s1, s88, s83
	v_pk_mul_f32 v[80:81], v[82:83], v[64:65] op_sel:[0,0] op_sel_hi:[0,1]
	s_add_u32 s6, s0, 0x2000000
	v_pk_fma_f32 v[80:81], v[82:83], v[64:65], v[80:81] op_sel:[1,1,0] op_sel_hi:[1,0,1] neg_lo:[0,1,0]
	ds_write_b64 v144, v[80:81] offset:4352
	v_pk_mul_f32 v[80:81], v[64:65], v[56:57] op_sel:[0,0] op_sel_hi:[0,1]
	s_addc_u32 s7, s1, 0
	v_pk_fma_f32 v[64:65], v[64:65], v[56:57], v[80:81] op_sel:[1,1,0] op_sel_hi:[1,0,1] neg_lo:[0,1,0]
	v_pk_mul_f32 v[80:81], v[84:85], v[64:65] op_sel:[0,0] op_sel_hi:[0,1]
	v_pk_fma_f32 v[80:81], v[84:85], v[64:65], v[80:81] op_sel:[1,1,0] op_sel_hi:[1,0,1] neg_lo:[0,1,0]
	ds_write_b64 v144, v[80:81] offset:6528
	v_pk_mul_f32 v[80:81], v[64:65], v[56:57] op_sel:[0,0] op_sel_hi:[0,1]
	v_pk_fma_f32 v[64:65], v[64:65], v[56:57], v[80:81] op_sel:[1,1,0] op_sel_hi:[1,0,1] neg_lo:[0,1,0]
	v_pk_mul_f32 v[80:81], v[86:87], v[64:65] op_sel:[0,0] op_sel_hi:[0,1]
	v_pk_fma_f32 v[80:81], v[86:87], v[64:65], v[80:81] op_sel:[1,1,0] op_sel_hi:[1,0,1] neg_lo:[0,1,0]
	ds_write_b64 v144, v[80:81] offset:8704
	v_pk_mul_f32 v[80:81], v[64:65], v[56:57] op_sel:[0,0] op_sel_hi:[0,1]
	v_pk_fma_f32 v[64:65], v[64:65], v[56:57], v[80:81] op_sel:[1,1,0] op_sel_hi:[1,0,1] neg_lo:[0,1,0]
	v_pk_mul_f32 v[80:81], v[74:75], v[64:65] op_sel:[0,0] op_sel_hi:[0,1]
	v_pk_fma_f32 v[74:75], v[74:75], v[64:65], v[80:81] op_sel:[1,1,0] op_sel_hi:[1,0,1] neg_lo:[0,1,0]
	ds_write_b64 v144, v[74:75] offset:10880
	v_pk_mul_f32 v[74:75], v[64:65], v[56:57] op_sel:[0,0] op_sel_hi:[0,1]
	v_pk_fma_f32 v[64:65], v[64:65], v[56:57], v[74:75] op_sel:[1,1,0] op_sel_hi:[1,0,1] neg_lo:[0,1,0]
	v_pk_mul_f32 v[74:75], v[78:79], v[64:65] op_sel:[0,0] op_sel_hi:[0,1]
	v_pk_fma_f32 v[74:75], v[78:79], v[64:65], v[74:75] op_sel:[1,1,0] op_sel_hi:[1,0,1] neg_lo:[0,1,0]
	ds_write_b64 v144, v[74:75] offset:13056
	v_pk_mul_f32 v[74:75], v[64:65], v[56:57] op_sel:[0,0] op_sel_hi:[0,1]
	v_pk_fma_f32 v[64:65], v[64:65], v[56:57], v[74:75] op_sel:[1,1,0] op_sel_hi:[1,0,1] neg_lo:[0,1,0]
	v_pk_mul_f32 v[74:75], v[76:77], v[64:65] op_sel:[0,0] op_sel_hi:[0,1]
	v_pk_fma_f32 v[74:75], v[76:77], v[64:65], v[74:75] op_sel:[1,1,0] op_sel_hi:[1,0,1] neg_lo:[0,1,0]
	ds_write_b64 v144, v[74:75] offset:15232
	v_pk_mul_f32 v[74:75], v[64:65], v[56:57] op_sel:[0,0] op_sel_hi:[0,1]
	v_pk_fma_f32 v[64:65], v[64:65], v[56:57], v[74:75] op_sel:[1,1,0] op_sel_hi:[1,0,1] neg_lo:[0,1,0]
	v_pk_mul_f32 v[74:75], v[68:69], v[64:65] op_sel:[0,0] op_sel_hi:[0,1]
	v_pk_fma_f32 v[68:69], v[68:69], v[64:65], v[74:75] op_sel:[1,1,0] op_sel_hi:[1,0,1] neg_lo:[0,1,0]
	ds_write_b64 v144, v[68:69] offset:17408
	v_pk_mul_f32 v[68:69], v[64:65], v[56:57] op_sel:[0,0] op_sel_hi:[0,1]
	v_pk_fma_f32 v[64:65], v[64:65], v[56:57], v[68:69] op_sel:[1,1,0] op_sel_hi:[1,0,1] neg_lo:[0,1,0]
	v_pk_mul_f32 v[68:69], v[66:67], v[64:65] op_sel:[0,0] op_sel_hi:[0,1]
	v_pk_fma_f32 v[66:67], v[66:67], v[64:65], v[68:69] op_sel:[1,1,0] op_sel_hi:[1,0,1] neg_lo:[0,1,0]
	ds_write_b64 v144, v[66:67] offset:19584
	v_pk_mul_f32 v[66:67], v[64:65], v[56:57] op_sel:[0,0] op_sel_hi:[0,1]
	v_pk_fma_f32 v[64:65], v[64:65], v[56:57], v[66:67] op_sel:[1,1,0] op_sel_hi:[1,0,1] neg_lo:[0,1,0]
	v_pk_mul_f32 v[66:67], v[62:63], v[64:65] op_sel:[0,0] op_sel_hi:[0,1]
	v_pk_fma_f32 v[62:63], v[62:63], v[64:65], v[66:67] op_sel:[1,1,0] op_sel_hi:[1,0,1] neg_lo:[0,1,0]
	ds_write_b64 v144, v[62:63] offset:21760
	v_pk_mul_f32 v[62:63], v[64:65], v[56:57] op_sel:[0,0] op_sel_hi:[0,1]
	v_pk_fma_f32 v[62:63], v[64:65], v[56:57], v[62:63] op_sel:[1,1,0] op_sel_hi:[1,0,1] neg_lo:[0,1,0]
	v_pk_mul_f32 v[64:65], v[72:73], v[62:63] op_sel:[0,0] op_sel_hi:[0,1]
	v_pk_fma_f32 v[64:65], v[72:73], v[62:63], v[64:65] op_sel:[1,1,0] op_sel_hi:[1,0,1] neg_lo:[0,1,0]
	ds_write_b64 v144, v[64:65] offset:23936
	v_pk_mul_f32 v[64:65], v[62:63], v[56:57] op_sel:[0,0] op_sel_hi:[0,1]
	v_pk_fma_f32 v[62:63], v[62:63], v[56:57], v[64:65] op_sel:[1,1,0] op_sel_hi:[1,0,1] neg_lo:[0,1,0]
	v_pk_mul_f32 v[64:65], v[60:61], v[62:63] op_sel:[0,0] op_sel_hi:[0,1]
	v_pk_fma_f32 v[60:61], v[60:61], v[62:63], v[64:65] op_sel:[1,1,0] op_sel_hi:[1,0,1] neg_lo:[0,1,0]
	ds_write_b64 v144, v[60:61] offset:26112
	v_pk_mul_f32 v[60:61], v[62:63], v[56:57] op_sel:[0,0] op_sel_hi:[0,1]
	v_pk_fma_f32 v[60:61], v[62:63], v[56:57], v[60:61] op_sel:[1,1,0] op_sel_hi:[1,0,1] neg_lo:[0,1,0]
	v_pk_mul_f32 v[62:63], v[70:71], v[60:61] op_sel:[0,0] op_sel_hi:[0,1]
	v_pk_fma_f32 v[62:63], v[70:71], v[60:61], v[62:63] op_sel:[1,1,0] op_sel_hi:[1,0,1] neg_lo:[0,1,0]
	ds_write_b64 v144, v[62:63] offset:28288
	v_pk_mul_f32 v[62:63], v[60:61], v[56:57] op_sel:[0,0] op_sel_hi:[0,1]
	v_pk_fma_f32 v[60:61], v[60:61], v[56:57], v[62:63] op_sel:[1,1,0] op_sel_hi:[1,0,1] neg_lo:[0,1,0]
	v_pk_mul_f32 v[62:63], v[58:59], v[60:61] op_sel:[0,0] op_sel_hi:[0,1]
	v_pk_fma_f32 v[58:59], v[58:59], v[60:61], v[62:63] op_sel:[1,1,0] op_sel_hi:[1,0,1] neg_lo:[0,1,0]
	ds_write_b64 v144, v[58:59] offset:30464
	v_pk_mul_f32 v[58:59], v[60:61], v[56:57] op_sel:[0,0] op_sel_hi:[0,1]
	v_pk_fma_f32 v[56:57], v[60:61], v[56:57], v[58:59] op_sel:[1,1,0] op_sel_hi:[1,0,1] neg_lo:[0,1,0]
	v_pk_mul_f32 v[58:59], v[54:55], v[56:57] op_sel:[0,0] op_sel_hi:[0,1]
	v_pk_fma_f32 v[54:55], v[54:55], v[56:57], v[58:59] op_sel:[1,1,0] op_sel_hi:[1,0,1] neg_lo:[0,1,0]
	ds_write_b64 v144, v[54:55] offset:32640
	s_waitcnt lgkmcnt(0)
	s_barrier
	ds_read2_b64 v[54:57], v146 offset1:17
	ds_read2_b64 v[58:61], v146 offset0:34 offset1:51
	ds_read2_b64 v[62:65], v146 offset0:68 offset1:85
	ds_read2_b64 v[66:69], v146 offset0:136 offset1:153
	ds_read2_b64 v[70:73], v146 offset0:102 offset1:119
	ds_read2_b64 v[74:77], v146 offset0:204 offset1:221
	ds_read2_b64 v[78:81], v146 offset0:170 offset1:187
	ds_read2_b64 v[82:85], v146 offset0:238 offset1:255
	s_waitcnt lgkmcnt(4)
	v_pk_add_f32 v[86:87], v[54:55], v[66:67]
	v_pk_add_f32 v[54:55], v[54:55], v[66:67] neg_lo:[0,1] neg_hi:[0,1]
	s_waitcnt lgkmcnt(2)
	v_pk_add_f32 v[66:67], v[62:63], v[74:75]
	v_pk_add_f32 v[62:63], v[62:63], v[74:75] neg_lo:[0,1] neg_hi:[0,1]
	v_pk_add_f32 v[74:75], v[86:87], v[66:67]
	v_pk_add_f32 v[66:67], v[86:87], v[66:67] neg_lo:[0,1] neg_hi:[0,1]
	v_pk_add_f32 v[86:87], v[54:55], v[62:63] op_sel:[0,1] op_sel_hi:[1,0] neg_hi:[0,1]
	v_pk_add_f32 v[54:55], v[54:55], v[62:63] op_sel:[0,1] op_sel_hi:[1,0] neg_lo:[0,1]
	v_pk_add_f32 v[62:63], v[56:57], v[68:69]
	v_pk_add_f32 v[56:57], v[56:57], v[68:69] neg_lo:[0,1] neg_hi:[0,1]
	v_pk_add_f32 v[68:69], v[64:65], v[76:77]
	v_pk_add_f32 v[64:65], v[64:65], v[76:77] neg_lo:[0,1] neg_hi:[0,1]
	v_pk_add_f32 v[76:77], v[62:63], v[68:69]
	v_pk_add_f32 v[62:63], v[62:63], v[68:69] neg_lo:[0,1] neg_hi:[0,1]
	v_pk_add_f32 v[68:69], v[56:57], v[64:65] op_sel:[0,1] op_sel_hi:[1,0] neg_hi:[0,1]
	v_pk_add_f32 v[56:57], v[56:57], v[64:65] op_sel:[0,1] op_sel_hi:[1,0] neg_lo:[0,1]
	s_waitcnt lgkmcnt(1)
	v_pk_add_f32 v[64:65], v[58:59], v[78:79]
	v_pk_add_f32 v[58:59], v[58:59], v[78:79] neg_lo:[0,1] neg_hi:[0,1]
	s_waitcnt lgkmcnt(0)
	v_pk_add_f32 v[78:79], v[70:71], v[82:83]
	v_pk_add_f32 v[70:71], v[70:71], v[82:83] neg_lo:[0,1] neg_hi:[0,1]
	v_pk_add_f32 v[82:83], v[64:65], v[78:79]
	v_pk_add_f32 v[64:65], v[64:65], v[78:79] neg_lo:[0,1] neg_hi:[0,1]
	v_pk_add_f32 v[78:79], v[58:59], v[70:71] op_sel:[0,1] op_sel_hi:[1,0] neg_hi:[0,1]
	v_pk_add_f32 v[58:59], v[58:59], v[70:71] op_sel:[0,1] op_sel_hi:[1,0] neg_lo:[0,1]
	v_pk_add_f32 v[70:71], v[60:61], v[80:81]
	v_pk_add_f32 v[60:61], v[60:61], v[80:81] neg_lo:[0,1] neg_hi:[0,1]
	v_pk_add_f32 v[80:81], v[72:73], v[84:85]
	v_pk_add_f32 v[72:73], v[72:73], v[84:85] neg_lo:[0,1] neg_hi:[0,1]
	v_pk_add_f32 v[84:85], v[70:71], v[80:81]
	v_pk_add_f32 v[70:71], v[70:71], v[80:81] neg_lo:[0,1] neg_hi:[0,1]
	v_pk_add_f32 v[80:81], v[60:61], v[72:73] op_sel:[0,1] op_sel_hi:[1,0] neg_hi:[0,1]
	v_pk_add_f32 v[60:61], v[60:61], v[72:73] op_sel:[0,1] op_sel_hi:[1,0] neg_lo:[0,1]
	v_pk_mul_f32 v[72:73], v[68:69], v[48:49] op_sel:[0,0] op_sel_hi:[0,1]
	v_pk_fma_f32 v[68:69], v[68:69], v[48:49], v[72:73] op_sel:[1,1,0] op_sel_hi:[1,0,1] neg_lo:[0,1,0]
	v_pk_mul_f32 v[72:73], v[78:79], v[44:45] op_sel:[0,0] op_sel_hi:[0,1]
	v_pk_fma_f32 v[72:73], v[78:79], v[44:45], v[72:73] op_sel:[1,1,0] op_sel_hi:[1,0,1] neg_lo:[0,1,0]
	v_pk_mul_f32 v[78:79], v[80:81], v[42:43] op_sel:[0,0] op_sel_hi:[0,1]
	v_pk_fma_f32 v[78:79], v[80:81], v[42:43], v[78:79] op_sel:[1,1,0] op_sel_hi:[1,0,1] neg_lo:[0,1,0]
	v_pk_mul_f32 v[80:81], v[62:63], v[44:45] op_sel:[0,0] op_sel_hi:[0,1]
	v_pk_fma_f32 v[62:63], v[62:63], v[44:45], v[80:81] op_sel:[1,1,0] op_sel_hi:[1,0,1] neg_lo:[0,1,0]
	v_pk_mul_f32 v[80:81], v[64:65], v[50:51] op_sel:[0,0] op_sel_hi:[0,1]
	v_pk_fma_f32 v[64:65], v[64:65], v[50:51], v[80:81] op_sel:[1,1,0] op_sel_hi:[1,0,1] neg_lo:[0,1,0]
	v_pk_mul_f32 v[80:81], v[70:71], v[46:47] op_sel:[0,0] op_sel_hi:[0,1]
	v_pk_fma_f32 v[70:71], v[70:71], v[46:47], v[80:81] op_sel:[1,1,0] op_sel_hi:[1,0,1] neg_lo:[0,1,0]
	v_pk_mul_f32 v[80:81], v[56:57], v[42:43] op_sel:[0,0] op_sel_hi:[0,1]
	v_pk_fma_f32 v[56:57], v[56:57], v[42:43], v[80:81] op_sel:[1,1,0] op_sel_hi:[1,0,1] neg_lo:[0,1,0]
	v_pk_mul_f32 v[80:81], v[58:59], v[46:47] op_sel:[0,0] op_sel_hi:[0,1]
	v_pk_fma_f32 v[58:59], v[58:59], v[46:47], v[80:81] op_sel:[1,1,0] op_sel_hi:[1,0,1] neg_lo:[0,1,0]
	v_pk_mul_f32 v[80:81], v[60:61], v[52:53] op_sel:[0,0] op_sel_hi:[0,1]
	v_pk_fma_f32 v[60:61], v[60:61], v[52:53], v[80:81] op_sel:[1,1,0] op_sel_hi:[1,0,1] neg_lo:[0,1,0]
	v_pk_add_f32 v[80:81], v[74:75], v[82:83]
	v_pk_add_f32 v[74:75], v[74:75], v[82:83] neg_lo:[0,1] neg_hi:[0,1]
	v_pk_add_f32 v[82:83], v[76:77], v[84:85]
	v_pk_add_f32 v[76:77], v[76:77], v[84:85] neg_lo:[0,1] neg_hi:[0,1]
	v_pk_add_f32 v[84:85], v[80:81], v[82:83]
	v_pk_add_f32 v[80:81], v[80:81], v[82:83] neg_lo:[0,1] neg_hi:[0,1]
	v_pk_add_f32 v[82:83], v[74:75], v[76:77] op_sel:[0,1] op_sel_hi:[1,0] neg_hi:[0,1]
	v_pk_add_f32 v[74:75], v[74:75], v[76:77] op_sel:[0,1] op_sel_hi:[1,0] neg_lo:[0,1]
	v_pk_add_f32 v[76:77], v[86:87], v[72:73]
	v_pk_add_f32 v[72:73], v[86:87], v[72:73] neg_lo:[0,1] neg_hi:[0,1]
	v_pk_add_f32 v[86:87], v[68:69], v[78:79]
	v_pk_add_f32 v[68:69], v[68:69], v[78:79] neg_lo:[0,1] neg_hi:[0,1]
	v_pk_add_f32 v[78:79], v[76:77], v[86:87]
	v_pk_add_f32 v[76:77], v[76:77], v[86:87] neg_lo:[0,1] neg_hi:[0,1]
	v_pk_add_f32 v[86:87], v[72:73], v[68:69] op_sel:[0,1] op_sel_hi:[1,0] neg_hi:[0,1]
	v_pk_add_f32 v[68:69], v[72:73], v[68:69] op_sel:[0,1] op_sel_hi:[1,0] neg_lo:[0,1]
	v_pk_add_f32 v[72:73], v[66:67], v[64:65]
	v_pk_add_f32 v[64:65], v[66:67], v[64:65] neg_lo:[0,1] neg_hi:[0,1]
	v_pk_add_f32 v[66:67], v[62:63], v[70:71]
	v_pk_add_f32 v[62:63], v[62:63], v[70:71] neg_lo:[0,1] neg_hi:[0,1]
	v_pk_add_f32 v[70:71], v[72:73], v[66:67]
	v_pk_add_f32 v[66:67], v[72:73], v[66:67] neg_lo:[0,1] neg_hi:[0,1]
	v_pk_add_f32 v[72:73], v[64:65], v[62:63] op_sel:[0,1] op_sel_hi:[1,0] neg_hi:[0,1]
	v_pk_add_f32 v[62:63], v[64:65], v[62:63] op_sel:[0,1] op_sel_hi:[1,0] neg_lo:[0,1]
	v_pk_add_f32 v[64:65], v[54:55], v[58:59]
	v_pk_add_f32 v[54:55], v[54:55], v[58:59] neg_lo:[0,1] neg_hi:[0,1]
	v_pk_add_f32 v[58:59], v[56:57], v[60:61]
	v_pk_add_f32 v[56:57], v[56:57], v[60:61] neg_lo:[0,1] neg_hi:[0,1]
	v_pk_add_f32 v[60:61], v[64:65], v[58:59]
	v_pk_add_f32 v[58:59], v[64:65], v[58:59] neg_lo:[0,1] neg_hi:[0,1]
	v_pk_add_f32 v[64:65], v[54:55], v[56:57] op_sel:[0,1] op_sel_hi:[1,0] neg_hi:[0,1]
	v_pk_add_f32 v[54:55], v[54:55], v[56:57] op_sel:[0,1] op_sel_hi:[1,0] neg_lo:[0,1]
	v_mov_b32_e32 v56, v40
	v_mov_b32_e32 v57, v41
	s_nop 0
	v_pk_mul_f32 v[88:89], v[78:79], v[56:57] op_sel:[0,0] op_sel_hi:[0,1]
	v_pk_fma_f32 v[78:79], v[78:79], v[56:57], v[88:89] op_sel:[1,1,0] op_sel_hi:[1,0,1] neg_lo:[0,1,0]
	ds_write2_b64 v146, v[84:85], v[78:79] offset1:17
	v_pk_mul_f32 v[78:79], v[56:57], v[56:57] op_sel:[0,0] op_sel_hi:[0,1]
	v_pk_fma_f32 v[78:79], v[56:57], v[56:57], v[78:79] op_sel:[1,1,0] op_sel_hi:[1,0,1] neg_lo:[0,1,0]
	v_pk_mul_f32 v[84:85], v[70:71], v[78:79] op_sel:[0,0] op_sel_hi:[0,1]
	v_pk_fma_f32 v[70:71], v[70:71], v[78:79], v[84:85] op_sel:[1,1,0] op_sel_hi:[1,0,1] neg_lo:[0,1,0]
	v_pk_mul_f32 v[84:85], v[78:79], v[56:57] op_sel:[0,0] op_sel_hi:[0,1]
	v_pk_fma_f32 v[78:79], v[78:79], v[56:57], v[84:85] op_sel:[1,1,0] op_sel_hi:[1,0,1] neg_lo:[0,1,0]
	v_pk_mul_f32 v[84:85], v[60:61], v[78:79] op_sel:[0,0] op_sel_hi:[0,1]
	v_pk_fma_f32 v[60:61], v[60:61], v[78:79], v[84:85] op_sel:[1,1,0] op_sel_hi:[1,0,1] neg_lo:[0,1,0]
	ds_write2_b64 v146, v[70:71], v[60:61] offset0:34 offset1:51
	v_pk_mul_f32 v[60:61], v[78:79], v[56:57] op_sel:[0,0] op_sel_hi:[0,1]
	v_pk_fma_f32 v[60:61], v[78:79], v[56:57], v[60:61] op_sel:[1,1,0] op_sel_hi:[1,0,1] neg_lo:[0,1,0]
	v_pk_mul_f32 v[70:71], v[82:83], v[60:61] op_sel:[0,0] op_sel_hi:[0,1]
	v_pk_mul_f32 v[78:79], v[60:61], v[56:57] op_sel:[0,0] op_sel_hi:[0,1]
	v_pk_fma_f32 v[70:71], v[82:83], v[60:61], v[70:71] op_sel:[1,1,0] op_sel_hi:[1,0,1] neg_lo:[0,1,0]
	v_pk_fma_f32 v[60:61], v[60:61], v[56:57], v[78:79] op_sel:[1,1,0] op_sel_hi:[1,0,1] neg_lo:[0,1,0]
	v_pk_mul_f32 v[78:79], v[86:87], v[60:61] op_sel:[0,0] op_sel_hi:[0,1]
	v_pk_fma_f32 v[78:79], v[86:87], v[60:61], v[78:79] op_sel:[1,1,0] op_sel_hi:[1,0,1] neg_lo:[0,1,0]
	ds_write2_b64 v146, v[70:71], v[78:79] offset0:68 offset1:85
	v_pk_mul_f32 v[70:71], v[60:61], v[56:57] op_sel:[0,0] op_sel_hi:[0,1]
	v_pk_fma_f32 v[60:61], v[60:61], v[56:57], v[70:71] op_sel:[1,1,0] op_sel_hi:[1,0,1] neg_lo:[0,1,0]
	v_pk_mul_f32 v[70:71], v[72:73], v[60:61] op_sel:[0,0] op_sel_hi:[0,1]
	v_pk_fma_f32 v[70:71], v[72:73], v[60:61], v[70:71] op_sel:[1,1,0] op_sel_hi:[1,0,1] neg_lo:[0,1,0]
	v_pk_mul_f32 v[72:73], v[60:61], v[56:57] op_sel:[0,0] op_sel_hi:[0,1]
	v_pk_fma_f32 v[60:61], v[60:61], v[56:57], v[72:73] op_sel:[1,1,0] op_sel_hi:[1,0,1] neg_lo:[0,1,0]
	v_pk_mul_f32 v[72:73], v[64:65], v[60:61] op_sel:[0,0] op_sel_hi:[0,1]
	v_pk_fma_f32 v[64:65], v[64:65], v[60:61], v[72:73] op_sel:[1,1,0] op_sel_hi:[1,0,1] neg_lo:[0,1,0]
	ds_write2_b64 v146, v[70:71], v[64:65] offset0:102 offset1:119
	v_pk_mul_f32 v[64:65], v[60:61], v[56:57] op_sel:[0,0] op_sel_hi:[0,1]
	v_pk_fma_f32 v[60:61], v[60:61], v[56:57], v[64:65] op_sel:[1,1,0] op_sel_hi:[1,0,1] neg_lo:[0,1,0]
	v_pk_mul_f32 v[64:65], v[80:81], v[60:61] op_sel:[0,0] op_sel_hi:[0,1]
	v_pk_mul_f32 v[70:71], v[60:61], v[56:57] op_sel:[0,0] op_sel_hi:[0,1]
	v_pk_fma_f32 v[64:65], v[80:81], v[60:61], v[64:65] op_sel:[1,1,0] op_sel_hi:[1,0,1] neg_lo:[0,1,0]
	v_pk_fma_f32 v[60:61], v[60:61], v[56:57], v[70:71] op_sel:[1,1,0] op_sel_hi:[1,0,1] neg_lo:[0,1,0]
	v_pk_mul_f32 v[70:71], v[76:77], v[60:61] op_sel:[0,0] op_sel_hi:[0,1]
	v_pk_fma_f32 v[70:71], v[76:77], v[60:61], v[70:71] op_sel:[1,1,0] op_sel_hi:[1,0,1] neg_lo:[0,1,0]
	ds_write2_b64 v146, v[64:65], v[70:71] offset0:136 offset1:153
	v_pk_mul_f32 v[64:65], v[60:61], v[56:57] op_sel:[0,0] op_sel_hi:[0,1]
	v_pk_fma_f32 v[60:61], v[60:61], v[56:57], v[64:65] op_sel:[1,1,0] op_sel_hi:[1,0,1] neg_lo:[0,1,0]
	v_pk_mul_f32 v[64:65], v[66:67], v[60:61] op_sel:[0,0] op_sel_hi:[0,1]
	v_pk_fma_f32 v[64:65], v[66:67], v[60:61], v[64:65] op_sel:[1,1,0] op_sel_hi:[1,0,1] neg_lo:[0,1,0]
	v_pk_mul_f32 v[66:67], v[60:61], v[56:57] op_sel:[0,0] op_sel_hi:[0,1]
	v_pk_fma_f32 v[60:61], v[60:61], v[56:57], v[66:67] op_sel:[1,1,0] op_sel_hi:[1,0,1] neg_lo:[0,1,0]
	v_pk_mul_f32 v[66:67], v[58:59], v[60:61] op_sel:[0,0] op_sel_hi:[0,1]
	v_pk_fma_f32 v[58:59], v[58:59], v[60:61], v[66:67] op_sel:[1,1,0] op_sel_hi:[1,0,1] neg_lo:[0,1,0]
	ds_write2_b64 v146, v[64:65], v[58:59] offset0:170 offset1:187
	v_pk_mul_f32 v[58:59], v[60:61], v[56:57] op_sel:[0,0] op_sel_hi:[0,1]
	v_pk_fma_f32 v[58:59], v[60:61], v[56:57], v[58:59] op_sel:[1,1,0] op_sel_hi:[1,0,1] neg_lo:[0,1,0]
	v_pk_mul_f32 v[60:61], v[74:75], v[58:59] op_sel:[0,0] op_sel_hi:[0,1]
	v_pk_mul_f32 v[64:65], v[58:59], v[56:57] op_sel:[0,0] op_sel_hi:[0,1]
	v_pk_fma_f32 v[60:61], v[74:75], v[58:59], v[60:61] op_sel:[1,1,0] op_sel_hi:[1,0,1] neg_lo:[0,1,0]
	v_pk_fma_f32 v[58:59], v[58:59], v[56:57], v[64:65] op_sel:[1,1,0] op_sel_hi:[1,0,1] neg_lo:[0,1,0]
	v_pk_mul_f32 v[64:65], v[68:69], v[58:59] op_sel:[0,0] op_sel_hi:[0,1]
	v_pk_fma_f32 v[64:65], v[68:69], v[58:59], v[64:65] op_sel:[1,1,0] op_sel_hi:[1,0,1] neg_lo:[0,1,0]
	ds_write2_b64 v146, v[60:61], v[64:65] offset0:204 offset1:221
	v_pk_mul_f32 v[60:61], v[58:59], v[56:57] op_sel:[0,0] op_sel_hi:[0,1]
	v_pk_fma_f32 v[58:59], v[58:59], v[56:57], v[60:61] op_sel:[1,1,0] op_sel_hi:[1,0,1] neg_lo:[0,1,0]
	v_pk_mul_f32 v[60:61], v[62:63], v[58:59] op_sel:[0,0] op_sel_hi:[0,1]
	v_pk_fma_f32 v[60:61], v[62:63], v[58:59], v[60:61] op_sel:[1,1,0] op_sel_hi:[1,0,1] neg_lo:[0,1,0]
	v_pk_mul_f32 v[62:63], v[58:59], v[56:57] op_sel:[0,0] op_sel_hi:[0,1]
	v_pk_fma_f32 v[56:57], v[58:59], v[56:57], v[62:63] op_sel:[1,1,0] op_sel_hi:[1,0,1] neg_lo:[0,1,0]
	v_pk_mul_f32 v[58:59], v[54:55], v[56:57] op_sel:[0,0] op_sel_hi:[0,1]
	v_pk_fma_f32 v[54:55], v[54:55], v[56:57], v[58:59] op_sel:[1,1,0] op_sel_hi:[1,0,1] neg_lo:[0,1,0]
	ds_write2_b64 v146, v[60:61], v[54:55] offset0:238 offset1:255
	s_waitcnt lgkmcnt(0)
	s_barrier
	ds_read2_b64 v[54:57], v147 offset1:1
	ds_read2_b64 v[58:61], v147 offset0:2 offset1:3
	ds_read2_b64 v[62:65], v147 offset0:8 offset1:9
	ds_read2_b64 v[66:69], v147 offset0:4 offset1:5
	ds_read2_b64 v[82:85], v147 offset0:6 offset1:7
	ds_read2_b64 v[78:81], v147 offset0:12 offset1:13
	ds_read2_b64 v[86:89], v147 offset0:10 offset1:11
	ds_read2_b64 v[90:93], v147 offset0:14 offset1:15
	s_waitcnt lgkmcnt(5)
	v_pk_add_f32 v[70:71], v[54:55], v[62:63]
	v_pk_add_f32 v[54:55], v[54:55], v[62:63] neg_lo:[0,1] neg_hi:[0,1]
	s_waitcnt lgkmcnt(2)
	v_pk_add_f32 v[62:63], v[66:67], v[78:79]
	v_pk_add_f32 v[66:67], v[66:67], v[78:79] neg_lo:[0,1] neg_hi:[0,1]
	v_pk_add_f32 v[78:79], v[70:71], v[62:63]
	v_pk_add_f32 v[72:73], v[70:71], v[62:63] neg_lo:[0,1] neg_hi:[0,1]
	v_pk_add_f32 v[76:77], v[54:55], v[66:67] op_sel:[0,1] op_sel_hi:[1,0] neg_hi:[0,1]
	v_pk_add_f32 v[74:75], v[54:55], v[66:67] op_sel:[0,1] op_sel_hi:[1,0] neg_lo:[0,1]
	v_pk_add_f32 v[54:55], v[56:57], v[64:65]
	v_pk_add_f32 v[56:57], v[56:57], v[64:65] neg_lo:[0,1] neg_hi:[0,1]
	v_pk_add_f32 v[62:63], v[68:69], v[80:81]
	v_pk_add_f32 v[64:65], v[68:69], v[80:81] neg_lo:[0,1] neg_hi:[0,1]
	v_pk_add_f32 v[80:81], v[54:55], v[62:63]
	v_pk_add_f32 v[54:55], v[54:55], v[62:63] neg_lo:[0,1] neg_hi:[0,1]
	v_pk_add_f32 v[62:63], v[56:57], v[64:65] op_sel:[0,1] op_sel_hi:[1,0] neg_hi:[0,1]
	v_pk_add_f32 v[56:57], v[56:57], v[64:65] op_sel:[0,1] op_sel_hi:[1,0] neg_lo:[0,1]
	s_waitcnt lgkmcnt(1)
	v_pk_add_f32 v[64:65], v[58:59], v[86:87]
	v_pk_add_f32 v[58:59], v[58:59], v[86:87] neg_lo:[0,1] neg_hi:[0,1]
	s_waitcnt lgkmcnt(0)
	v_pk_add_f32 v[66:67], v[82:83], v[90:91]
	v_pk_add_f32 v[68:69], v[82:83], v[90:91] neg_lo:[0,1] neg_hi:[0,1]
	v_pk_add_f32 v[82:83], v[64:65], v[66:67]
	v_pk_add_f32 v[64:65], v[64:65], v[66:67] neg_lo:[0,1] neg_hi:[0,1]
	v_pk_add_f32 v[66:67], v[58:59], v[68:69] op_sel:[0,1] op_sel_hi:[1,0] neg_hi:[0,1]
	v_pk_add_f32 v[58:59], v[58:59], v[68:69] op_sel:[0,1] op_sel_hi:[1,0] neg_lo:[0,1]
	v_pk_add_f32 v[68:69], v[60:61], v[88:89]
	v_pk_add_f32 v[60:61], v[60:61], v[88:89] neg_lo:[0,1] neg_hi:[0,1]
	v_pk_add_f32 v[70:71], v[84:85], v[92:93]
	v_pk_add_f32 v[84:85], v[84:85], v[92:93] neg_lo:[0,1] neg_hi:[0,1]
	v_pk_add_f32 v[86:87], v[68:69], v[70:71]
	v_pk_add_f32 v[68:69], v[68:69], v[70:71] neg_lo:[0,1] neg_hi:[0,1]
	v_pk_add_f32 v[70:71], v[60:61], v[84:85] op_sel:[0,1] op_sel_hi:[1,0] neg_hi:[0,1]
	v_pk_add_f32 v[60:61], v[60:61], v[84:85] op_sel:[0,1] op_sel_hi:[1,0] neg_lo:[0,1]
	v_pk_mul_f32 v[84:85], v[62:63], v[48:49] op_sel:[0,0] op_sel_hi:[0,1]
	v_pk_fma_f32 v[90:91], v[62:63], v[48:49], v[84:85] op_sel:[1,1,0] op_sel_hi:[1,0,1] neg_lo:[0,1,0]
	v_pk_mul_f32 v[48:49], v[66:67], v[44:45] op_sel:[0,0] op_sel_hi:[0,1]
	s_barrier
	v_pk_fma_f32 v[94:95], v[66:67], v[44:45], v[48:49] op_sel:[1,1,0] op_sel_hi:[1,0,1] neg_lo:[0,1,0]
	v_pk_mul_f32 v[48:49], v[70:71], v[42:43] op_sel:[0,0] op_sel_hi:[0,1]
	v_pk_fma_f32 v[110:111], v[70:71], v[42:43], v[48:49] op_sel:[1,1,0] op_sel_hi:[1,0,1] neg_lo:[0,1,0]
	v_pk_mul_f32 v[48:49], v[54:55], v[44:45] op_sel:[0,0] op_sel_hi:[0,1]
	v_pk_fma_f32 v[108:109], v[54:55], v[44:45], v[48:49] op_sel:[1,1,0] op_sel_hi:[1,0,1] neg_lo:[0,1,0]
	v_pk_mul_f32 v[44:45], v[64:65], v[50:51] op_sel:[0,0] op_sel_hi:[0,1]
	v_pk_fma_f32 v[112:113], v[64:65], v[50:51], v[44:45] op_sel:[1,1,0] op_sel_hi:[1,0,1] neg_lo:[0,1,0]
	v_pk_mul_f32 v[44:45], v[68:69], v[46:47] op_sel:[0,0] op_sel_hi:[0,1]
	v_pk_fma_f32 v[116:117], v[68:69], v[46:47], v[44:45] op_sel:[1,1,0] op_sel_hi:[1,0,1] neg_lo:[0,1,0]
	v_pk_mul_f32 v[44:45], v[56:57], v[42:43] op_sel:[0,0] op_sel_hi:[0,1]
	v_pk_fma_f32 v[92:93], v[56:57], v[42:43], v[44:45] op_sel:[1,1,0] op_sel_hi:[1,0,1] neg_lo:[0,1,0]
	v_pk_mul_f32 v[42:43], v[58:59], v[46:47] op_sel:[0,0] op_sel_hi:[0,1]
	v_pk_add_f32 v[44:45], v[80:81], v[86:87] neg_lo:[0,1] neg_hi:[0,1]
	v_pk_fma_f32 v[118:119], v[58:59], v[46:47], v[42:43] op_sel:[1,1,0] op_sel_hi:[1,0,1] neg_lo:[0,1,0]
	v_pk_mul_f32 v[42:43], v[60:61], v[52:53] op_sel:[0,0] op_sel_hi:[0,1]
	v_pk_fma_f32 v[114:115], v[60:61], v[52:53], v[42:43] op_sel:[1,1,0] op_sel_hi:[1,0,1] neg_lo:[0,1,0]
	v_pk_add_f32 v[42:43], v[78:79], v[82:83] neg_lo:[0,1] neg_hi:[0,1]
	s_nop 0
	v_pk_add_f32 v[84:85], v[42:43], v[44:45] op_sel:[0,1] op_sel_hi:[1,0] neg_hi:[0,1]
	v_pk_add_f32 v[88:89], v[42:43], v[44:45] op_sel:[0,1] op_sel_hi:[1,0] neg_lo:[0,1]
	v_pk_add_f32 v[42:43], v[76:77], v[94:95] neg_lo:[0,1] neg_hi:[0,1]
	v_pk_add_f32 v[44:45], v[90:91], v[110:111] neg_lo:[0,1] neg_hi:[0,1]
	s_nop 0
	v_pk_add_f32 v[96:97], v[42:43], v[44:45] op_sel:[0,1] op_sel_hi:[1,0] neg_hi:[0,1]
	v_pk_add_f32 v[98:99], v[42:43], v[44:45] op_sel:[0,1] op_sel_hi:[1,0] neg_lo:[0,1]
	v_pk_add_f32 v[42:43], v[72:73], v[112:113] neg_lo:[0,1] neg_hi:[0,1]
	v_pk_add_f32 v[44:45], v[108:109], v[116:117] neg_lo:[0,1] neg_hi:[0,1]
	s_nop 0
	v_pk_add_f32 v[100:101], v[42:43], v[44:45] op_sel:[0,1] op_sel_hi:[1,0] neg_hi:[0,1]
	v_pk_add_f32 v[102:103], v[42:43], v[44:45] op_sel:[0,1] op_sel_hi:[1,0] neg_lo:[0,1]
	v_pk_add_f32 v[42:43], v[74:75], v[118:119] neg_lo:[0,1] neg_hi:[0,1]
	v_pk_add_f32 v[44:45], v[92:93], v[114:115] neg_lo:[0,1] neg_hi:[0,1]
	s_nop 0
	v_pk_add_f32 v[104:105], v[42:43], v[44:45] op_sel:[0,1] op_sel_hi:[1,0] neg_hi:[0,1]
	v_pk_add_f32 v[106:107], v[42:43], v[44:45] op_sel:[0,1] op_sel_hi:[1,0] neg_lo:[0,1]
	v_mov_b32_e32 v43, v138
	v_mov_b32_e32 v42, 0
	v_sub_u32_e32 v34, 0x1000, v43
	v_cndmask_b32_e32 v44, v34, v43, vcc
	v_cmp_gt_i32_e64 s[0:1], s33, v44
	v_mov_b32_e32 v34, 0
	s_and_saveexec_b64 s[82:83], s[0:1]
	s_cbranch_execz .LBB0_1297
	v_add_u32_e32 v44, v44, v120
	v_ashrrev_i32_e32 v45, 31, v44
	v_lshl_add_u64 v[44:45], v[44:45], 2, s[6:7]
	global_load_dword v34, v[44:45], off

.LBB0_1328:
	s_or_b64 exec, exec, s[0:1]
	s_addk_i32 s6, 0x800
	s_waitcnt lgkmcnt(0)
	ds_write_b64 v43, v[122:123]
	s_cmpk_lg_u32 s6, 0x8000
	v_add_u32_e32 v43, 0x880, v43
	v_mov_b64_e32 v[122:123], s[18:19]
	v_pk_mul_f32 v[154:155], v[120:121], v[122:123] op_sel:[0,0] op_sel_hi:[0,1]
	v_pk_fma_f32 v[120:121], v[120:121], v[122:123], v[154:155] op_sel:[1,1,0] op_sel_hi:[1,0,1] neg_lo:[0,1,0]
	s_cbranch_scc0 .LBB0_1331
.LBB0_1329:
	v_add_u32_e32 v45, s6, v151
	ds_read_b64 v[122:123], v45
	s_and_saveexec_b64 s[0:1], s[4:5]
	s_cbranch_execz .LBB0_1328
	s_waitcnt lgkmcnt(0)
	v_pk_mul_f32 v[154:155], v[122:123], v[120:121] op_sel:[0,0] op_sel_hi:[0,1]
	v_pk_fma_f32 v[122:123], v[122:123], v[120:121], v[154:155] op_sel:[1,1,0] op_sel_hi:[1,0,1] neg_lo:[0,1,0]
	s_branch .LBB0_1328
.LBB0_1331:
	v_mov_b32_e32 v120, v30
	v_mov_b32_e32 v121, v26
	v_mov_b32_e32 v26, v31
	v_mov_b32_e32 v30, v32
	v_mov_b32_e32 v31, v28
	v_mov_b32_e32 v28, v33
	v_pk_add_f32 v[26:27], v[120:121], v[26:27]
	v_pk_add_f32 v[28:29], v[30:31], v[28:29]
	v_pk_add_f32 v[32:33], v[90:91], v[110:111]
	v_pk_add_f32 v[26:27], v[26:27], v[28:29]
	v_pk_add_f32 v[28:29], v[80:81], v[86:87]
	v_add_f32_e32 v43, v26, v27
	v_add_f32_e32 v43, 0x358637bd, v43
	v_mul_f32_e32 v43, 0x46000000, v43
	v_div_scale_f32 v45, s[0:1], v43, v43, 1.0
	v_rcp_f32_e32 v47, v45
	v_pk_add_f32 v[26:27], v[78:79], v[82:83]
	v_fma_f32 v49, -v45, v47, 1.0
	v_fmac_f32_e32 v47, v49, v47
	v_div_scale_f32 v49, vcc, 1.0, v43, 1.0
	v_mul_f32_e32 v51, v49, v47
	v_fma_f32 v53, -v45, v51, v49
	v_pk_add_f32 v[30:31], v[26:27], v[28:29]
	v_pk_add_f32 v[26:27], v[26:27], v[28:29] neg_lo:[0,1] neg_hi:[0,1]
	v_pk_add_f32 v[28:29], v[76:77], v[94:95]
	v_fmac_f32_e32 v51, v53, v47
	v_pk_add_f32 v[76:77], v[28:29], v[32:33]
	v_pk_add_f32 v[28:29], v[28:29], v[32:33] neg_lo:[0,1] neg_hi:[0,1]
	v_pk_add_f32 v[32:33], v[72:73], v[112:113]
	v_pk_add_f32 v[72:73], v[108:109], v[116:117]
	v_fma_f32 v45, -v45, v51, v49
	v_pk_add_f32 v[78:79], v[32:33], v[72:73]
	v_pk_add_f32 v[32:33], v[32:33], v[72:73] neg_lo:[0,1] neg_hi:[0,1]
	v_pk_add_f32 v[72:73], v[74:75], v[118:119]
	v_pk_add_f32 v[74:75], v[92:93], v[114:115]
	v_div_fmas_f32 v45, v45, v47, v51
	v_pk_add_f32 v[108:109], v[72:73], v[74:75]
	v_pk_add_f32 v[110:111], v[72:73], v[74:75] neg_lo:[0,1] neg_hi:[0,1]
	v_div_fixup_f32 v112, v45, v43, 1.0
	v_pk_mul_f32 v[94:95], v[112:113], v[30:31] op_sel_hi:[0,1]
	v_pk_mul_f32 v[92:93], v[112:113], v[84:85] op_sel_hi:[0,1]
	v_pk_mul_f32 v[90:91], v[112:113], v[26:27] op_sel_hi:[0,1]
	v_pk_mul_f32 v[88:89], v[112:113], v[88:89] op_sel_hi:[0,1]
	v_pk_mul_f32 v[86:87], v[112:113], v[76:77] op_sel_hi:[0,1]
	v_pk_mul_f32 v[84:85], v[112:113], v[96:97] op_sel_hi:[0,1]
	v_pk_mul_f32 v[82:83], v[112:113], v[28:29] op_sel_hi:[0,1]
	v_pk_mul_f32 v[80:81], v[112:113], v[98:99] op_sel_hi:[0,1]
	v_pk_mul_f32 v[78:79], v[112:113], v[78:79] op_sel_hi:[0,1]
	v_pk_mul_f32 v[76:77], v[112:113], v[100:101] op_sel_hi:[0,1]
	v_pk_mul_f32 v[74:75], v[112:113], v[32:33] op_sel_hi:[0,1]
	v_pk_mul_f32 v[72:73], v[112:113], v[102:103] op_sel_hi:[0,1]
	v_pk_mul_f32 v[32:33], v[112:113], v[108:109] op_sel_hi:[0,1]
	v_pk_mul_f32 v[30:31], v[112:113], v[104:105] op_sel_hi:[0,1]
	v_pk_mul_f32 v[28:29], v[112:113], v[110:111] op_sel_hi:[0,1]
	v_pk_mul_f32 v[26:27], v[112:113], v[106:107] op_sel_hi:[0,1]
	ds_read_b64 v[96:97], v144
	ds_read_b64 v[98:99], v144 offset:2176
	ds_read_b64 v[100:101], v144 offset:4352
	ds_read_b64 v[102:103], v144 offset:6528
	ds_read_b64 v[104:105], v144 offset:8704
	ds_read_b64 v[106:107], v144 offset:10880
	ds_read_b64 v[108:109], v144 offset:13056
	ds_read_b64 v[110:111], v144 offset:15232
	ds_read_b64 v[112:113], v144 offset:17408
	ds_read_b64 v[114:115], v144 offset:19584
	ds_read_b64 v[116:117], v144 offset:21760
	ds_read_b64 v[118:119], v144 offset:23936
	ds_read_b64 v[120:121], v144 offset:26112
	ds_read_b64 v[122:123], v144 offset:28288
	ds_read_b64 v[154:155], v144 offset:30464
	ds_read_b64 v[156:157], v144 offset:32640
	s_waitcnt lgkmcnt(7)
	v_pk_add_f32 v[158:159], v[96:97], v[112:113]
	v_pk_add_f32 v[96:97], v[96:97], v[112:113] neg_lo:[0,1] neg_hi:[0,1]
	s_waitcnt lgkmcnt(3)
	v_pk_add_f32 v[112:113], v[104:105], v[120:121]
	v_pk_add_f32 v[104:105], v[104:105], v[120:121] neg_lo:[0,1] neg_hi:[0,1]
	v_pk_add_f32 v[120:121], v[158:159], v[112:113]
	v_pk_add_f32 v[112:113], v[158:159], v[112:113] neg_lo:[0,1] neg_hi:[0,1]
	v_pk_add_f32 v[158:159], v[96:97], v[104:105] op_sel:[0,1] op_sel_hi:[1,0] neg_hi:[0,1]
	v_pk_add_f32 v[160:161], v[96:97], v[104:105] op_sel:[0,1] op_sel_hi:[1,0] neg_lo:[0,1]
	v_pk_add_f32 v[96:97], v[98:99], v[114:115]
	v_pk_add_f32 v[98:99], v[98:99], v[114:115] neg_lo:[0,1] neg_hi:[0,1]
	s_waitcnt lgkmcnt(2)
	v_pk_add_f32 v[104:105], v[106:107], v[122:123]
	v_pk_add_f32 v[106:107], v[106:107], v[122:123] neg_lo:[0,1] neg_hi:[0,1]
	v_pk_add_f32 v[114:115], v[96:97], v[104:105]
	v_pk_add_f32 v[104:105], v[96:97], v[104:105] neg_lo:[0,1] neg_hi:[0,1]
	v_pk_add_f32 v[96:97], v[98:99], v[106:107] op_sel:[0,1] op_sel_hi:[1,0] neg_hi:[0,1]
	v_pk_add_f32 v[106:107], v[98:99], v[106:107] op_sel:[0,1] op_sel_hi:[1,0] neg_lo:[0,1]
	v_pk_add_f32 v[98:99], v[100:101], v[116:117]
	v_pk_add_f32 v[100:101], v[100:101], v[116:117] neg_lo:[0,1] neg_hi:[0,1]
	s_waitcnt lgkmcnt(1)
	v_pk_add_f32 v[116:117], v[108:109], v[154:155]
	v_pk_add_f32 v[108:109], v[108:109], v[154:155] neg_lo:[0,1] neg_hi:[0,1]
	v_pk_add_f32 v[122:123], v[98:99], v[116:117]
	v_pk_add_f32 v[116:117], v[98:99], v[116:117] neg_lo:[0,1] neg_hi:[0,1]
	v_pk_add_f32 v[154:155], v[100:101], v[108:109] op_sel:[0,1] op_sel_hi:[1,0] neg_hi:[0,1]
	v_pk_add_f32 v[108:109], v[100:101], v[108:109] op_sel:[0,1] op_sel_hi:[1,0] neg_lo:[0,1]
	v_pk_add_f32 v[98:99], v[102:103], v[118:119]
	v_pk_add_f32 v[100:101], v[102:103], v[118:119] neg_lo:[0,1] neg_hi:[0,1]
	s_waitcnt lgkmcnt(0)
	v_pk_add_f32 v[102:103], v[110:111], v[156:157]
	v_pk_add_f32 v[110:111], v[110:111], v[156:157] neg_lo:[0,1] neg_hi:[0,1]
	v_pk_add_f32 v[118:119], v[98:99], v[102:103]
	v_pk_add_f32 v[156:157], v[98:99], v[102:103] neg_lo:[0,1] neg_hi:[0,1]
	v_mov_b64_e32 v[102:103], s[20:21]
	v_pk_mul_f32 v[98:99], v[96:97], v[102:103] op_sel:[0,0] op_sel_hi:[0,1]
	v_pk_add_f32 v[162:163], v[100:101], v[110:111] op_sel:[0,1] op_sel_hi:[1,0] neg_hi:[0,1]
	v_pk_add_f32 v[110:111], v[100:101], v[110:111] op_sel:[0,1] op_sel_hi:[1,0] neg_lo:[0,1]
	v_pk_fma_f32 v[164:165], v[96:97], v[102:103], v[98:99] op_sel:[1,1,0] op_sel_hi:[1,0,1] neg_lo:[0,1,0]
	v_mov_b64_e32 v[98:99], s[50:51]
	v_pk_mul_f32 v[96:97], v[154:155], v[98:99] op_sel:[0,0] op_sel_hi:[0,1]
	v_pk_fma_f32 v[154:155], v[154:155], v[98:99], v[96:97] op_sel:[1,1,0] op_sel_hi:[1,0,1] neg_lo:[0,1,0]
	v_mov_b64_e32 v[96:97], s[54:55]
	v_pk_mul_f32 v[100:101], v[162:163], v[96:97] op_sel:[0,0] op_sel_hi:[0,1]
	v_pk_fma_f32 v[162:163], v[162:163], v[96:97], v[100:101] op_sel:[1,1,0] op_sel_hi:[1,0,1] neg_lo:[0,1,0]
	v_pk_mul_f32 v[100:101], v[104:105], v[98:99] op_sel:[0,0] op_sel_hi:[0,1]
	v_pk_fma_f32 v[166:167], v[104:105], v[98:99], v[100:101] op_sel:[1,1,0] op_sel_hi:[1,0,1] neg_lo:[0,1,0]
	v_mov_b64_e32 v[104:105], s[14:15]
	v_pk_mul_f32 v[100:101], v[116:117], v[104:105] op_sel:[0,0] op_sel_hi:[0,1]
	v_pk_fma_f32 v[116:117], v[116:117], v[104:105], v[100:101] op_sel:[1,1,0] op_sel_hi:[1,0,1] neg_lo:[0,1,0]
	v_mov_b64_e32 v[100:101], s[58:59]
	v_pk_mul_f32 v[168:169], v[156:157], v[100:101] op_sel:[0,0] op_sel_hi:[0,1]
	v_pk_fma_f32 v[156:157], v[156:157], v[100:101], v[168:169] op_sel:[1,1,0] op_sel_hi:[1,0,1] neg_lo:[0,1,0]
	v_pk_mul_f32 v[168:169], v[106:107], v[96:97] op_sel:[0,0] op_sel_hi:[0,1]
	v_pk_fma_f32 v[168:169], v[106:107], v[96:97], v[168:169] op_sel:[1,1,0] op_sel_hi:[1,0,1] neg_lo:[0,1,0]
	v_pk_mul_f32 v[106:107], v[108:109], v[100:101] op_sel:[0,0] op_sel_hi:[0,1]
	v_pk_fma_f32 v[108:109], v[108:109], v[100:101], v[106:107] op_sel:[1,1,0] op_sel_hi:[1,0,1] neg_lo:[0,1,0]
	v_mov_b64_e32 v[106:107], s[60:61]
	v_pk_mul_f32 v[170:171], v[110:111], v[106:107] op_sel:[0,0] op_sel_hi:[0,1]
	v_pk_fma_f32 v[110:111], v[110:111], v[106:107], v[170:171] op_sel:[1,1,0] op_sel_hi:[1,0,1] neg_lo:[0,1,0]
	v_pk_add_f32 v[170:171], v[120:121], v[122:123]
	v_pk_add_f32 v[120:121], v[120:121], v[122:123] neg_lo:[0,1] neg_hi:[0,1]
	v_pk_add_f32 v[122:123], v[114:115], v[118:119]
	v_pk_add_f32 v[114:115], v[114:115], v[118:119] neg_lo:[0,1] neg_hi:[0,1]
	v_pk_add_f32 v[118:119], v[170:171], v[122:123]
	v_pk_add_f32 v[122:123], v[170:171], v[122:123] neg_lo:[0,1] neg_hi:[0,1]
	v_pk_add_f32 v[170:171], v[120:121], v[114:115] op_sel:[0,1] op_sel_hi:[1,0] neg_hi:[0,1]
	v_pk_add_f32 v[114:115], v[120:121], v[114:115] op_sel:[0,1] op_sel_hi:[1,0] neg_lo:[0,1]
	v_pk_add_f32 v[120:121], v[158:159], v[154:155]
	v_pk_add_f32 v[154:155], v[158:159], v[154:155] neg_lo:[0,1] neg_hi:[0,1]
	v_pk_add_f32 v[158:159], v[164:165], v[162:163]
	v_pk_add_f32 v[162:163], v[164:165], v[162:163] neg_lo:[0,1] neg_hi:[0,1]
	v_pk_add_f32 v[164:165], v[120:121], v[158:159]
	v_pk_add_f32 v[120:121], v[120:121], v[158:159] neg_lo:[0,1] neg_hi:[0,1]
	v_pk_add_f32 v[158:159], v[154:155], v[162:163] op_sel:[0,1] op_sel_hi:[1,0] neg_hi:[0,1]
	v_pk_add_f32 v[154:155], v[154:155], v[162:163] op_sel:[0,1] op_sel_hi:[1,0] neg_lo:[0,1]
	v_pk_add_f32 v[162:163], v[112:113], v[116:117]
	v_pk_add_f32 v[112:113], v[112:113], v[116:117] neg_lo:[0,1] neg_hi:[0,1]
	v_pk_add_f32 v[116:117], v[166:167], v[156:157]
	v_pk_add_f32 v[156:157], v[166:167], v[156:157] neg_lo:[0,1] neg_hi:[0,1]
	v_pk_add_f32 v[166:167], v[162:163], v[116:117]
	v_pk_add_f32 v[116:117], v[162:163], v[116:117] neg_lo:[0,1] neg_hi:[0,1]
	v_pk_add_f32 v[162:163], v[112:113], v[156:157] op_sel:[0,1] op_sel_hi:[1,0] neg_hi:[0,1]
	v_pk_add_f32 v[112:113], v[112:113], v[156:157] op_sel:[0,1] op_sel_hi:[1,0] neg_lo:[0,1]
	v_pk_add_f32 v[156:157], v[160:161], v[108:109]
	v_pk_add_f32 v[108:109], v[160:161], v[108:109] neg_lo:[0,1] neg_hi:[0,1]
	v_pk_add_f32 v[160:161], v[168:169], v[110:111]
	v_pk_add_f32 v[110:111], v[168:169], v[110:111] neg_lo:[0,1] neg_hi:[0,1]
	v_pk_add_f32 v[168:169], v[156:157], v[160:161]
	v_pk_add_f32 v[156:157], v[156:157], v[160:161] neg_lo:[0,1] neg_hi:[0,1]
	v_pk_add_f32 v[160:161], v[108:109], v[110:111] op_sel:[0,1] op_sel_hi:[1,0] neg_hi:[0,1]
	v_pk_add_f32 v[108:109], v[108:109], v[110:111] op_sel:[0,1] op_sel_hi:[1,0] neg_lo:[0,1]
	v_mov_b32_e32 v110, v38
	v_mov_b32_e32 v111, v39
	ds_write_b64 v144, v[118:119]
	v_pk_mul_f32 v[118:119], v[164:165], v[110:111] op_sel:[0,0] op_sel_hi:[0,1]
	v_pk_fma_f32 v[118:119], v[164:165], v[110:111], v[118:119] op_sel:[1,1,0] op_sel_hi:[1,0,1] neg_lo:[0,1,0]
	ds_write_b64 v144, v[118:119] offset:2176
	v_pk_mul_f32 v[118:119], v[110:111], v[110:111] op_sel:[0,0] op_sel_hi:[0,1]
	v_pk_fma_f32 v[118:119], v[110:111], v[110:111], v[118:119] op_sel:[1,1,0] op_sel_hi:[1,0,1] neg_lo:[0,1,0]
	v_pk_mul_f32 v[164:165], v[166:167], v[118:119] op_sel:[0,0] op_sel_hi:[0,1]
	v_pk_fma_f32 v[164:165], v[166:167], v[118:119], v[164:165] op_sel:[1,1,0] op_sel_hi:[1,0,1] neg_lo:[0,1,0]
	ds_write_b64 v144, v[164:165] offset:4352
	v_pk_mul_f32 v[164:165], v[118:119], v[110:111] op_sel:[0,0] op_sel_hi:[0,1]
	v_pk_fma_f32 v[118:119], v[118:119], v[110:111], v[164:165] op_sel:[1,1,0] op_sel_hi:[1,0,1] neg_lo:[0,1,0]
	v_pk_mul_f32 v[164:165], v[168:169], v[118:119] op_sel:[0,0] op_sel_hi:[0,1]
	v_pk_fma_f32 v[164:165], v[168:169], v[118:119], v[164:165] op_sel:[1,1,0] op_sel_hi:[1,0,1] neg_lo:[0,1,0]
	ds_write_b64 v144, v[164:165] offset:6528
	v_pk_mul_f32 v[164:165], v[118:119], v[110:111] op_sel:[0,0] op_sel_hi:[0,1]
	v_pk_fma_f32 v[118:119], v[118:119], v[110:111], v[164:165] op_sel:[1,1,0] op_sel_hi:[1,0,1] neg_lo:[0,1,0]
	v_pk_mul_f32 v[164:165], v[170:171], v[118:119] op_sel:[0,0] op_sel_hi:[0,1]
	v_pk_fma_f32 v[164:165], v[170:171], v[118:119], v[164:165] op_sel:[1,1,0] op_sel_hi:[1,0,1] neg_lo:[0,1,0]
	ds_write_b64 v144, v[164:165] offset:8704
	v_pk_mul_f32 v[164:165], v[118:119], v[110:111] op_sel:[0,0] op_sel_hi:[0,1]
	v_pk_fma_f32 v[118:119], v[118:119], v[110:111], v[164:165] op_sel:[1,1,0] op_sel_hi:[1,0,1] neg_lo:[0,1,0]
	v_pk_mul_f32 v[164:165], v[158:159], v[118:119] op_sel:[0,0] op_sel_hi:[0,1]
	v_pk_fma_f32 v[158:159], v[158:159], v[118:119], v[164:165] op_sel:[1,1,0] op_sel_hi:[1,0,1] neg_lo:[0,1,0]
	ds_write_b64 v144, v[158:159] offset:10880
	v_pk_mul_f32 v[158:159], v[118:119], v[110:111] op_sel:[0,0] op_sel_hi:[0,1]
	v_pk_fma_f32 v[118:119], v[118:119], v[110:111], v[158:159] op_sel:[1,1,0] op_sel_hi:[1,0,1] neg_lo:[0,1,0]
	v_pk_mul_f32 v[158:159], v[162:163], v[118:119] op_sel:[0,0] op_sel_hi:[0,1]
	v_pk_fma_f32 v[158:159], v[162:163], v[118:119], v[158:159] op_sel:[1,1,0] op_sel_hi:[1,0,1] neg_lo:[0,1,0]
	ds_write_b64 v144, v[158:159] offset:13056
	v_pk_mul_f32 v[158:159], v[118:119], v[110:111] op_sel:[0,0] op_sel_hi:[0,1]
	v_pk_fma_f32 v[118:119], v[118:119], v[110:111], v[158:159] op_sel:[1,1,0] op_sel_hi:[1,0,1] neg_lo:[0,1,0]
	v_pk_mul_f32 v[158:159], v[160:161], v[118:119] op_sel:[0,0] op_sel_hi:[0,1]
	v_pk_fma_f32 v[158:159], v[160:161], v[118:119], v[158:159] op_sel:[1,1,0] op_sel_hi:[1,0,1] neg_lo:[0,1,0]
	ds_write_b64 v144, v[158:159] offset:15232
	v_pk_mul_f32 v[158:159], v[118:119], v[110:111] op_sel:[0,0] op_sel_hi:[0,1]
	v_pk_fma_f32 v[118:119], v[118:119], v[110:111], v[158:159] op_sel:[1,1,0] op_sel_hi:[1,0,1] neg_lo:[0,1,0]
	v_pk_mul_f32 v[158:159], v[122:123], v[118:119] op_sel:[0,0] op_sel_hi:[0,1]
	v_pk_fma_f32 v[122:123], v[122:123], v[118:119], v[158:159] op_sel:[1,1,0] op_sel_hi:[1,0,1] neg_lo:[0,1,0]
	ds_write_b64 v144, v[122:123] offset:17408
	v_pk_mul_f32 v[122:123], v[118:119], v[110:111] op_sel:[0,0] op_sel_hi:[0,1]
	v_pk_fma_f32 v[118:119], v[118:119], v[110:111], v[122:123] op_sel:[1,1,0] op_sel_hi:[1,0,1] neg_lo:[0,1,0]
	v_pk_mul_f32 v[122:123], v[120:121], v[118:119] op_sel:[0,0] op_sel_hi:[0,1]
	v_pk_fma_f32 v[120:121], v[120:121], v[118:119], v[122:123] op_sel:[1,1,0] op_sel_hi:[1,0,1] neg_lo:[0,1,0]
	ds_write_b64 v144, v[120:121] offset:19584
	v_pk_mul_f32 v[120:121], v[118:119], v[110:111] op_sel:[0,0] op_sel_hi:[0,1]
	v_pk_fma_f32 v[118:119], v[118:119], v[110:111], v[120:121] op_sel:[1,1,0] op_sel_hi:[1,0,1] neg_lo:[0,1,0]
	v_pk_mul_f32 v[120:121], v[116:117], v[118:119] op_sel:[0,0] op_sel_hi:[0,1]
	v_pk_fma_f32 v[116:117], v[116:117], v[118:119], v[120:121] op_sel:[1,1,0] op_sel_hi:[1,0,1] neg_lo:[0,1,0]
	ds_write_b64 v144, v[116:117] offset:21760
	v_pk_mul_f32 v[116:117], v[118:119], v[110:111] op_sel:[0,0] op_sel_hi:[0,1]
	v_pk_fma_f32 v[116:117], v[118:119], v[110:111], v[116:117] op_sel:[1,1,0] op_sel_hi:[1,0,1] neg_lo:[0,1,0]
	v_pk_mul_f32 v[118:119], v[156:157], v[116:117] op_sel:[0,0] op_sel_hi:[0,1]
	v_pk_fma_f32 v[118:119], v[156:157], v[116:117], v[118:119] op_sel:[1,1,0] op_sel_hi:[1,0,1] neg_lo:[0,1,0]
	ds_write_b64 v144, v[118:119] offset:23936
	v_pk_mul_f32 v[118:119], v[116:117], v[110:111] op_sel:[0,0] op_sel_hi:[0,1]
	v_pk_fma_f32 v[116:117], v[116:117], v[110:111], v[118:119] op_sel:[1,1,0] op_sel_hi:[1,0,1] neg_lo:[0,1,0]
	v_pk_mul_f32 v[118:119], v[114:115], v[116:117] op_sel:[0,0] op_sel_hi:[0,1]
	v_pk_fma_f32 v[114:115], v[114:115], v[116:117], v[118:119] op_sel:[1,1,0] op_sel_hi:[1,0,1] neg_lo:[0,1,0]
	ds_write_b64 v144, v[114:115] offset:26112
	v_pk_mul_f32 v[114:115], v[116:117], v[110:111] op_sel:[0,0] op_sel_hi:[0,1]
	v_pk_fma_f32 v[114:115], v[116:117], v[110:111], v[114:115] op_sel:[1,1,0] op_sel_hi:[1,0,1] neg_lo:[0,1,0]
	v_pk_mul_f32 v[116:117], v[154:155], v[114:115] op_sel:[0,0] op_sel_hi:[0,1]
	v_pk_fma_f32 v[116:117], v[154:155], v[114:115], v[116:117] op_sel:[1,1,0] op_sel_hi:[1,0,1] neg_lo:[0,1,0]
	ds_write_b64 v144, v[116:117] offset:28288
	v_pk_mul_f32 v[116:117], v[114:115], v[110:111] op_sel:[0,0] op_sel_hi:[0,1]
	v_pk_fma_f32 v[114:115], v[114:115], v[110:111], v[116:117] op_sel:[1,1,0] op_sel_hi:[1,0,1] neg_lo:[0,1,0]
	v_pk_mul_f32 v[116:117], v[112:113], v[114:115] op_sel:[0,0] op_sel_hi:[0,1]
	v_pk_fma_f32 v[112:113], v[112:113], v[114:115], v[116:117] op_sel:[1,1,0] op_sel_hi:[1,0,1] neg_lo:[0,1,0]
	ds_write_b64 v144, v[112:113] offset:30464
	v_pk_mul_f32 v[112:113], v[114:115], v[110:111] op_sel:[0,0] op_sel_hi:[0,1]
	v_pk_fma_f32 v[110:111], v[114:115], v[110:111], v[112:113] op_sel:[1,1,0] op_sel_hi:[1,0,1] neg_lo:[0,1,0]
	v_pk_mul_f32 v[112:113], v[108:109], v[110:111] op_sel:[0,0] op_sel_hi:[0,1]
	v_pk_fma_f32 v[108:109], v[108:109], v[110:111], v[112:113] op_sel:[1,1,0] op_sel_hi:[1,0,1] neg_lo:[0,1,0]
	ds_write_b64 v144, v[108:109] offset:32640
	s_waitcnt lgkmcnt(0)
	s_barrier
	ds_read2_b64 v[108:111], v146 offset1:17
	ds_read2_b64 v[112:115], v146 offset0:34 offset1:51
	ds_read2_b64 v[116:119], v146 offset0:68 offset1:85
	ds_read2_b64 v[120:123], v146 offset0:136 offset1:153
	ds_read2_b64 v[154:157], v146 offset0:102 offset1:119
	ds_read2_b64 v[158:161], v146 offset0:204 offset1:221
	ds_read2_b64 v[162:165], v146 offset0:170 offset1:187
	ds_read2_b64 v[166:169], v146 offset0:238 offset1:255
	s_waitcnt lgkmcnt(4)
	v_pk_add_f32 v[170:171], v[108:109], v[120:121]
	v_pk_add_f32 v[108:109], v[108:109], v[120:121] neg_lo:[0,1] neg_hi:[0,1]
	s_waitcnt lgkmcnt(2)
	v_pk_add_f32 v[120:121], v[116:117], v[158:159]
	v_pk_add_f32 v[116:117], v[116:117], v[158:159] neg_lo:[0,1] neg_hi:[0,1]
	v_pk_add_f32 v[158:159], v[170:171], v[120:121]
	v_pk_add_f32 v[120:121], v[170:171], v[120:121] neg_lo:[0,1] neg_hi:[0,1]
	v_pk_add_f32 v[170:171], v[108:109], v[116:117] op_sel:[0,1] op_sel_hi:[1,0] neg_hi:[0,1]
	v_pk_add_f32 v[108:109], v[108:109], v[116:117] op_sel:[0,1] op_sel_hi:[1,0] neg_lo:[0,1]
	v_pk_add_f32 v[116:117], v[110:111], v[122:123]
	v_pk_add_f32 v[110:111], v[110:111], v[122:123] neg_lo:[0,1] neg_hi:[0,1]
	v_pk_add_f32 v[122:123], v[118:119], v[160:161]
	v_pk_add_f32 v[118:119], v[118:119], v[160:161] neg_lo:[0,1] neg_hi:[0,1]
	v_pk_add_f32 v[160:161], v[116:117], v[122:123]
	v_pk_add_f32 v[116:117], v[116:117], v[122:123] neg_lo:[0,1] neg_hi:[0,1]
	v_pk_add_f32 v[122:123], v[110:111], v[118:119] op_sel:[0,1] op_sel_hi:[1,0] neg_hi:[0,1]
	v_pk_add_f32 v[110:111], v[110:111], v[118:119] op_sel:[0,1] op_sel_hi:[1,0] neg_lo:[0,1]
	s_waitcnt lgkmcnt(1)
	v_pk_add_f32 v[118:119], v[112:113], v[162:163]
	v_pk_add_f32 v[112:113], v[112:113], v[162:163] neg_lo:[0,1] neg_hi:[0,1]
	s_waitcnt lgkmcnt(0)
	v_pk_add_f32 v[162:163], v[154:155], v[166:167]
	v_pk_add_f32 v[154:155], v[154:155], v[166:167] neg_lo:[0,1] neg_hi:[0,1]
	v_pk_add_f32 v[166:167], v[118:119], v[162:163]
	v_pk_add_f32 v[118:119], v[118:119], v[162:163] neg_lo:[0,1] neg_hi:[0,1]
	v_pk_add_f32 v[162:163], v[112:113], v[154:155] op_sel:[0,1] op_sel_hi:[1,0] neg_hi:[0,1]
	v_pk_add_f32 v[112:113], v[112:113], v[154:155] op_sel:[0,1] op_sel_hi:[1,0] neg_lo:[0,1]
	v_pk_add_f32 v[154:155], v[114:115], v[164:165]
	v_pk_add_f32 v[114:115], v[114:115], v[164:165] neg_lo:[0,1] neg_hi:[0,1]
	v_pk_add_f32 v[164:165], v[156:157], v[168:169]
	v_pk_add_f32 v[156:157], v[156:157], v[168:169] neg_lo:[0,1] neg_hi:[0,1]
	v_pk_add_f32 v[168:169], v[154:155], v[164:165]
	v_pk_add_f32 v[154:155], v[154:155], v[164:165] neg_lo:[0,1] neg_hi:[0,1]
	v_pk_add_f32 v[164:165], v[114:115], v[156:157] op_sel:[0,1] op_sel_hi:[1,0] neg_hi:[0,1]
	v_pk_add_f32 v[114:115], v[114:115], v[156:157] op_sel:[0,1] op_sel_hi:[1,0] neg_lo:[0,1]
	v_pk_mul_f32 v[156:157], v[122:123], v[102:103] op_sel:[0,0] op_sel_hi:[0,1]
	v_pk_fma_f32 v[122:123], v[122:123], v[102:103], v[156:157] op_sel:[1,1,0] op_sel_hi:[1,0,1] neg_lo:[0,1,0]
	v_pk_mul_f32 v[156:157], v[162:163], v[98:99] op_sel:[0,0] op_sel_hi:[0,1]
	v_pk_fma_f32 v[156:157], v[162:163], v[98:99], v[156:157] op_sel:[1,1,0] op_sel_hi:[1,0,1] neg_lo:[0,1,0]
	v_pk_mul_f32 v[162:163], v[164:165], v[96:97] op_sel:[0,0] op_sel_hi:[0,1]
	v_pk_fma_f32 v[162:163], v[164:165], v[96:97], v[162:163] op_sel:[1,1,0] op_sel_hi:[1,0,1] neg_lo:[0,1,0]
	v_pk_mul_f32 v[164:165], v[116:117], v[98:99] op_sel:[0,0] op_sel_hi:[0,1]
	v_pk_fma_f32 v[116:117], v[116:117], v[98:99], v[164:165] op_sel:[1,1,0] op_sel_hi:[1,0,1] neg_lo:[0,1,0]
	v_pk_mul_f32 v[164:165], v[118:119], v[104:105] op_sel:[0,0] op_sel_hi:[0,1]
	v_pk_fma_f32 v[118:119], v[118:119], v[104:105], v[164:165] op_sel:[1,1,0] op_sel_hi:[1,0,1] neg_lo:[0,1,0]
	v_pk_mul_f32 v[164:165], v[154:155], v[100:101] op_sel:[0,0] op_sel_hi:[0,1]
	v_pk_fma_f32 v[154:155], v[154:155], v[100:101], v[164:165] op_sel:[1,1,0] op_sel_hi:[1,0,1] neg_lo:[0,1,0]
	v_pk_mul_f32 v[164:165], v[110:111], v[96:97] op_sel:[0,0] op_sel_hi:[0,1]
	v_pk_fma_f32 v[110:111], v[110:111], v[96:97], v[164:165] op_sel:[1,1,0] op_sel_hi:[1,0,1] neg_lo:[0,1,0]
	v_pk_mul_f32 v[164:165], v[112:113], v[100:101] op_sel:[0,0] op_sel_hi:[0,1]
	v_pk_fma_f32 v[112:113], v[112:113], v[100:101], v[164:165] op_sel:[1,1,0] op_sel_hi:[1,0,1] neg_lo:[0,1,0]
	v_pk_mul_f32 v[164:165], v[114:115], v[106:107] op_sel:[0,0] op_sel_hi:[0,1]
	v_pk_fma_f32 v[114:115], v[114:115], v[106:107], v[164:165] op_sel:[1,1,0] op_sel_hi:[1,0,1] neg_lo:[0,1,0]
	v_pk_add_f32 v[164:165], v[158:159], v[166:167]
	v_pk_add_f32 v[158:159], v[158:159], v[166:167] neg_lo:[0,1] neg_hi:[0,1]
	v_pk_add_f32 v[166:167], v[160:161], v[168:169]
	v_pk_add_f32 v[160:161], v[160:161], v[168:169] neg_lo:[0,1] neg_hi:[0,1]
	v_pk_add_f32 v[168:169], v[164:165], v[166:167]
	v_pk_add_f32 v[164:165], v[164:165], v[166:167] neg_lo:[0,1] neg_hi:[0,1]
	v_pk_add_f32 v[166:167], v[158:159], v[160:161] op_sel:[0,1] op_sel_hi:[1,0] neg_hi:[0,1]
	v_pk_add_f32 v[158:159], v[158:159], v[160:161] op_sel:[0,1] op_sel_hi:[1,0] neg_lo:[0,1]
	v_pk_add_f32 v[160:161], v[170:171], v[156:157]
	v_pk_add_f32 v[156:157], v[170:171], v[156:157] neg_lo:[0,1] neg_hi:[0,1]
	v_pk_add_f32 v[170:171], v[122:123], v[162:163]
	v_pk_add_f32 v[122:123], v[122:123], v[162:163] neg_lo:[0,1] neg_hi:[0,1]
	v_pk_add_f32 v[162:163], v[160:161], v[170:171]
	v_pk_add_f32 v[160:161], v[160:161], v[170:171] neg_lo:[0,1] neg_hi:[0,1]
	v_pk_add_f32 v[170:171], v[156:157], v[122:123] op_sel:[0,1] op_sel_hi:[1,0] neg_hi:[0,1]
	v_pk_add_f32 v[122:123], v[156:157], v[122:123] op_sel:[0,1] op_sel_hi:[1,0] neg_lo:[0,1]
	v_pk_add_f32 v[156:157], v[120:121], v[118:119]
	v_pk_add_f32 v[118:119], v[120:121], v[118:119] neg_lo:[0,1] neg_hi:[0,1]
	v_pk_add_f32 v[120:121], v[116:117], v[154:155]
	v_pk_add_f32 v[116:117], v[116:117], v[154:155] neg_lo:[0,1] neg_hi:[0,1]
	v_pk_add_f32 v[154:155], v[156:157], v[120:121]
	v_pk_add_f32 v[120:121], v[156:157], v[120:121] neg_lo:[0,1] neg_hi:[0,1]
	v_pk_add_f32 v[156:157], v[118:119], v[116:117] op_sel:[0,1] op_sel_hi:[1,0] neg_hi:[0,1]
	v_pk_add_f32 v[116:117], v[118:119], v[116:117] op_sel:[0,1] op_sel_hi:[1,0] neg_lo:[0,1]
	v_pk_add_f32 v[118:119], v[108:109], v[112:113]
	v_pk_add_f32 v[108:109], v[108:109], v[112:113] neg_lo:[0,1] neg_hi:[0,1]
	v_pk_add_f32 v[112:113], v[110:111], v[114:115]
	v_pk_add_f32 v[110:111], v[110:111], v[114:115] neg_lo:[0,1] neg_hi:[0,1]
	v_pk_add_f32 v[114:115], v[118:119], v[112:113]
	v_pk_add_f32 v[112:113], v[118:119], v[112:113] neg_lo:[0,1] neg_hi:[0,1]
	v_pk_add_f32 v[118:119], v[108:109], v[110:111] op_sel:[0,1] op_sel_hi:[1,0] neg_hi:[0,1]
	v_pk_add_f32 v[108:109], v[108:109], v[110:111] op_sel:[0,1] op_sel_hi:[1,0] neg_lo:[0,1]
	v_mov_b32_e32 v110, v40
	v_mov_b32_e32 v111, v41
	s_nop 0
	v_pk_mul_f32 v[172:173], v[162:163], v[110:111] op_sel:[0,0] op_sel_hi:[0,1]
	v_pk_fma_f32 v[162:163], v[162:163], v[110:111], v[172:173] op_sel:[1,1,0] op_sel_hi:[1,0,1] neg_lo:[0,1,0]
	ds_write2_b64 v146, v[168:169], v[162:163] offset1:17
	v_pk_mul_f32 v[162:163], v[110:111], v[110:111] op_sel:[0,0] op_sel_hi:[0,1]
	v_pk_fma_f32 v[162:163], v[110:111], v[110:111], v[162:163] op_sel:[1,1,0] op_sel_hi:[1,0,1] neg_lo:[0,1,0]
	v_pk_mul_f32 v[168:169], v[154:155], v[162:163] op_sel:[0,0] op_sel_hi:[0,1]
	v_pk_fma_f32 v[154:155], v[154:155], v[162:163], v[168:169] op_sel:[1,1,0] op_sel_hi:[1,0,1] neg_lo:[0,1,0]
	v_pk_mul_f32 v[168:169], v[162:163], v[110:111] op_sel:[0,0] op_sel_hi:[0,1]
	v_pk_fma_f32 v[162:163], v[162:163], v[110:111], v[168:169] op_sel:[1,1,0] op_sel_hi:[1,0,1] neg_lo:[0,1,0]
	v_pk_mul_f32 v[168:169], v[114:115], v[162:163] op_sel:[0,0] op_sel_hi:[0,1]
	v_pk_fma_f32 v[114:115], v[114:115], v[162:163], v[168:169] op_sel:[1,1,0] op_sel_hi:[1,0,1] neg_lo:[0,1,0]
	ds_write2_b64 v146, v[154:155], v[114:115] offset0:34 offset1:51
	v_pk_mul_f32 v[114:115], v[162:163], v[110:111] op_sel:[0,0] op_sel_hi:[0,1]
	v_pk_fma_f32 v[114:115], v[162:163], v[110:111], v[114:115] op_sel:[1,1,0] op_sel_hi:[1,0,1] neg_lo:[0,1,0]
	v_pk_mul_f32 v[154:155], v[166:167], v[114:115] op_sel:[0,0] op_sel_hi:[0,1]
	v_pk_mul_f32 v[162:163], v[114:115], v[110:111] op_sel:[0,0] op_sel_hi:[0,1]
	v_pk_fma_f32 v[154:155], v[166:167], v[114:115], v[154:155] op_sel:[1,1,0] op_sel_hi:[1,0,1] neg_lo:[0,1,0]
	v_pk_fma_f32 v[114:115], v[114:115], v[110:111], v[162:163] op_sel:[1,1,0] op_sel_hi:[1,0,1] neg_lo:[0,1,0]
	v_pk_mul_f32 v[162:163], v[170:171], v[114:115] op_sel:[0,0] op_sel_hi:[0,1]
	v_pk_fma_f32 v[162:163], v[170:171], v[114:115], v[162:163] op_sel:[1,1,0] op_sel_hi:[1,0,1] neg_lo:[0,1,0]
	ds_write2_b64 v146, v[154:155], v[162:163] offset0:68 offset1:85
	v_pk_mul_f32 v[154:155], v[114:115], v[110:111] op_sel:[0,0] op_sel_hi:[0,1]
	v_pk_fma_f32 v[114:115], v[114:115], v[110:111], v[154:155] op_sel:[1,1,0] op_sel_hi:[1,0,1] neg_lo:[0,1,0]
	v_pk_mul_f32 v[154:155], v[156:157], v[114:115] op_sel:[0,0] op_sel_hi:[0,1]
	v_pk_fma_f32 v[154:155], v[156:157], v[114:115], v[154:155] op_sel:[1,1,0] op_sel_hi:[1,0,1] neg_lo:[0,1,0]
	v_pk_mul_f32 v[156:157], v[114:115], v[110:111] op_sel:[0,0] op_sel_hi:[0,1]
	v_pk_fma_f32 v[114:115], v[114:115], v[110:111], v[156:157] op_sel:[1,1,0] op_sel_hi:[1,0,1] neg_lo:[0,1,0]
	v_pk_mul_f32 v[156:157], v[118:119], v[114:115] op_sel:[0,0] op_sel_hi:[0,1]
	v_pk_fma_f32 v[118:119], v[118:119], v[114:115], v[156:157] op_sel:[1,1,0] op_sel_hi:[1,0,1] neg_lo:[0,1,0]
	ds_write2_b64 v146, v[154:155], v[118:119] offset0:102 offset1:119
	v_pk_mul_f32 v[118:119], v[114:115], v[110:111] op_sel:[0,0] op_sel_hi:[0,1]
	v_pk_fma_f32 v[114:115], v[114:115], v[110:111], v[118:119] op_sel:[1,1,0] op_sel_hi:[1,0,1] neg_lo:[0,1,0]
	v_pk_mul_f32 v[118:119], v[164:165], v[114:115] op_sel:[0,0] op_sel_hi:[0,1]
	v_pk_mul_f32 v[154:155], v[114:115], v[110:111] op_sel:[0,0] op_sel_hi:[0,1]
	v_pk_fma_f32 v[118:119], v[164:165], v[114:115], v[118:119] op_sel:[1,1,0] op_sel_hi:[1,0,1] neg_lo:[0,1,0]
	v_pk_fma_f32 v[114:115], v[114:115], v[110:111], v[154:155] op_sel:[1,1,0] op_sel_hi:[1,0,1] neg_lo:[0,1,0]
	v_pk_mul_f32 v[154:155], v[160:161], v[114:115] op_sel:[0,0] op_sel_hi:[0,1]
	v_pk_fma_f32 v[154:155], v[160:161], v[114:115], v[154:155] op_sel:[1,1,0] op_sel_hi:[1,0,1] neg_lo:[0,1,0]
	ds_write2_b64 v146, v[118:119], v[154:155] offset0:136 offset1:153
	v_pk_mul_f32 v[118:119], v[114:115], v[110:111] op_sel:[0,0] op_sel_hi:[0,1]
	v_pk_fma_f32 v[114:115], v[114:115], v[110:111], v[118:119] op_sel:[1,1,0] op_sel_hi:[1,0,1] neg_lo:[0,1,0]
	v_pk_mul_f32 v[118:119], v[120:121], v[114:115] op_sel:[0,0] op_sel_hi:[0,1]
	v_pk_fma_f32 v[118:119], v[120:121], v[114:115], v[118:119] op_sel:[1,1,0] op_sel_hi:[1,0,1] neg_lo:[0,1,0]
	v_pk_mul_f32 v[120:121], v[114:115], v[110:111] op_sel:[0,0] op_sel_hi:[0,1]
	v_pk_fma_f32 v[114:115], v[114:115], v[110:111], v[120:121] op_sel:[1,1,0] op_sel_hi:[1,0,1] neg_lo:[0,1,0]
	v_pk_mul_f32 v[120:121], v[112:113], v[114:115] op_sel:[0,0] op_sel_hi:[0,1]
	v_pk_fma_f32 v[112:113], v[112:113], v[114:115], v[120:121] op_sel:[1,1,0] op_sel_hi:[1,0,1] neg_lo:[0,1,0]
	ds_write2_b64 v146, v[118:119], v[112:113] offset0:170 offset1:187
	v_pk_mul_f32 v[112:113], v[114:115], v[110:111] op_sel:[0,0] op_sel_hi:[0,1]
	v_pk_fma_f32 v[112:113], v[114:115], v[110:111], v[112:113] op_sel:[1,1,0] op_sel_hi:[1,0,1] neg_lo:[0,1,0]
	v_pk_mul_f32 v[114:115], v[158:159], v[112:113] op_sel:[0,0] op_sel_hi:[0,1]
	v_pk_mul_f32 v[118:119], v[112:113], v[110:111] op_sel:[0,0] op_sel_hi:[0,1]
	v_pk_fma_f32 v[114:115], v[158:159], v[112:113], v[114:115] op_sel:[1,1,0] op_sel_hi:[1,0,1] neg_lo:[0,1,0]
	v_pk_fma_f32 v[112:113], v[112:113], v[110:111], v[118:119] op_sel:[1,1,0] op_sel_hi:[1,0,1] neg_lo:[0,1,0]
	v_pk_mul_f32 v[118:119], v[122:123], v[112:113] op_sel:[0,0] op_sel_hi:[0,1]
	v_pk_fma_f32 v[118:119], v[122:123], v[112:113], v[118:119] op_sel:[1,1,0] op_sel_hi:[1,0,1] neg_lo:[0,1,0]
	ds_write2_b64 v146, v[114:115], v[118:119] offset0:204 offset1:221
	v_pk_mul_f32 v[114:115], v[112:113], v[110:111] op_sel:[0,0] op_sel_hi:[0,1]
	v_pk_fma_f32 v[112:113], v[112:113], v[110:111], v[114:115] op_sel:[1,1,0] op_sel_hi:[1,0,1] neg_lo:[0,1,0]
	v_pk_mul_f32 v[114:115], v[116:117], v[112:113] op_sel:[0,0] op_sel_hi:[0,1]
	v_pk_fma_f32 v[114:115], v[116:117], v[112:113], v[114:115] op_sel:[1,1,0] op_sel_hi:[1,0,1] neg_lo:[0,1,0]
	v_pk_mul_f32 v[116:117], v[112:113], v[110:111] op_sel:[0,0] op_sel_hi:[0,1]
	v_pk_fma_f32 v[110:111], v[112:113], v[110:111], v[116:117] op_sel:[1,1,0] op_sel_hi:[1,0,1] neg_lo:[0,1,0]
	v_pk_mul_f32 v[112:113], v[108:109], v[110:111] op_sel:[0,0] op_sel_hi:[0,1]
	v_pk_fma_f32 v[108:109], v[108:109], v[110:111], v[112:113] op_sel:[1,1,0] op_sel_hi:[1,0,1] neg_lo:[0,1,0]
	ds_write2_b64 v146, v[114:115], v[108:109] offset0:238 offset1:255
	s_waitcnt lgkmcnt(0)
	s_barrier
	ds_read2_b64 v[108:111], v147 offset1:1
	ds_read2_b64 v[112:115], v147 offset0:2 offset1:3
	ds_read2_b64 v[116:119], v147 offset0:8 offset1:9
	ds_read2_b64 v[120:123], v147 offset0:4 offset1:5
	ds_read2_b64 v[154:157], v147 offset0:6 offset1:7
	ds_read2_b64 v[158:161], v147 offset0:12 offset1:13
	ds_read2_b64 v[162:165], v147 offset0:10 offset1:11
	ds_read2_b64 v[166:169], v147 offset0:14 offset1:15
	s_waitcnt lgkmcnt(5)
	v_pk_add_f32 v[170:171], v[108:109], v[116:117]
	v_pk_add_f32 v[108:109], v[108:109], v[116:117] neg_lo:[0,1] neg_hi:[0,1]
	s_waitcnt lgkmcnt(2)
	v_pk_add_f32 v[116:117], v[120:121], v[158:159]
	v_pk_add_f32 v[120:121], v[120:121], v[158:159] neg_lo:[0,1] neg_hi:[0,1]
	v_pk_add_f32 v[158:159], v[170:171], v[116:117]
	v_pk_add_f32 v[116:117], v[170:171], v[116:117] neg_lo:[0,1] neg_hi:[0,1]
	v_pk_add_f32 v[170:171], v[108:109], v[120:121] op_sel:[0,1] op_sel_hi:[1,0] neg_hi:[0,1]
	v_pk_add_f32 v[108:109], v[108:109], v[120:121] op_sel:[0,1] op_sel_hi:[1,0] neg_lo:[0,1]
	v_pk_add_f32 v[120:121], v[110:111], v[118:119]
	v_pk_add_f32 v[110:111], v[110:111], v[118:119] neg_lo:[0,1] neg_hi:[0,1]
	v_pk_add_f32 v[118:119], v[122:123], v[160:161]
	v_pk_add_f32 v[122:123], v[122:123], v[160:161] neg_lo:[0,1] neg_hi:[0,1]
	v_pk_add_f32 v[160:161], v[120:121], v[118:119]
	v_pk_add_f32 v[118:119], v[120:121], v[118:119] neg_lo:[0,1] neg_hi:[0,1]
	v_pk_add_f32 v[120:121], v[110:111], v[122:123] op_sel:[0,1] op_sel_hi:[1,0] neg_hi:[0,1]
	v_pk_add_f32 v[110:111], v[110:111], v[122:123] op_sel:[0,1] op_sel_hi:[1,0] neg_lo:[0,1]
	s_waitcnt lgkmcnt(1)
	v_pk_add_f32 v[122:123], v[112:113], v[162:163]
	v_pk_add_f32 v[112:113], v[112:113], v[162:163] neg_lo:[0,1] neg_hi:[0,1]
	s_waitcnt lgkmcnt(0)
	v_pk_add_f32 v[162:163], v[154:155], v[166:167]
	v_pk_add_f32 v[154:155], v[154:155], v[166:167] neg_lo:[0,1] neg_hi:[0,1]
	v_pk_add_f32 v[166:167], v[122:123], v[162:163]
	v_pk_add_f32 v[122:123], v[122:123], v[162:163] neg_lo:[0,1] neg_hi:[0,1]
	v_pk_add_f32 v[162:163], v[112:113], v[154:155] op_sel:[0,1] op_sel_hi:[1,0] neg_hi:[0,1]
	v_pk_add_f32 v[112:113], v[112:113], v[154:155] op_sel:[0,1] op_sel_hi:[1,0] neg_lo:[0,1]
	v_pk_add_f32 v[154:155], v[114:115], v[164:165]
	v_pk_add_f32 v[114:115], v[114:115], v[164:165] neg_lo:[0,1] neg_hi:[0,1]
	v_pk_add_f32 v[164:165], v[156:157], v[168:169]
	v_pk_add_f32 v[156:157], v[156:157], v[168:169] neg_lo:[0,1] neg_hi:[0,1]
	v_pk_add_f32 v[168:169], v[154:155], v[164:165]
	v_pk_add_f32 v[154:155], v[154:155], v[164:165] neg_lo:[0,1] neg_hi:[0,1]
	v_pk_add_f32 v[164:165], v[114:115], v[156:157] op_sel:[0,1] op_sel_hi:[1,0] neg_hi:[0,1]
	v_pk_add_f32 v[114:115], v[114:115], v[156:157] op_sel:[0,1] op_sel_hi:[1,0] neg_lo:[0,1]
	v_pk_mul_f32 v[156:157], v[120:121], v[102:103] op_sel:[0,0] op_sel_hi:[0,1]
	v_pk_fma_f32 v[102:103], v[120:121], v[102:103], v[156:157] op_sel:[1,1,0] op_sel_hi:[1,0,1] neg_lo:[0,1,0]
	v_pk_mul_f32 v[120:121], v[162:163], v[98:99] op_sel:[0,0] op_sel_hi:[0,1]
	v_pk_mul_f32 v[156:157], v[164:165], v[96:97] op_sel:[0,0] op_sel_hi:[0,1]
	v_pk_fma_f32 v[120:121], v[162:163], v[98:99], v[120:121] op_sel:[1,1,0] op_sel_hi:[1,0,1] neg_lo:[0,1,0]
	v_pk_mul_f32 v[162:163], v[118:119], v[98:99] op_sel:[0,0] op_sel_hi:[0,1]
	v_pk_fma_f32 v[156:157], v[164:165], v[96:97], v[156:157] op_sel:[1,1,0] op_sel_hi:[1,0,1] neg_lo:[0,1,0]
	v_pk_fma_f32 v[98:99], v[118:119], v[98:99], v[162:163] op_sel:[1,1,0] op_sel_hi:[1,0,1] neg_lo:[0,1,0]
	v_pk_mul_f32 v[118:119], v[122:123], v[104:105] op_sel:[0,0] op_sel_hi:[0,1]
	v_pk_fma_f32 v[104:105], v[122:123], v[104:105], v[118:119] op_sel:[1,1,0] op_sel_hi:[1,0,1] neg_lo:[0,1,0]
	v_pk_mul_f32 v[118:119], v[154:155], v[100:101] op_sel:[0,0] op_sel_hi:[0,1]
	v_pk_mul_f32 v[122:123], v[110:111], v[96:97] op_sel:[0,0] op_sel_hi:[0,1]
	v_pk_fma_f32 v[96:97], v[110:111], v[96:97], v[122:123] op_sel:[1,1,0] op_sel_hi:[1,0,1] neg_lo:[0,1,0]
	v_pk_mul_f32 v[110:111], v[112:113], v[100:101] op_sel:[0,0] op_sel_hi:[0,1]
	v_pk_fma_f32 v[118:119], v[154:155], v[100:101], v[118:119] op_sel:[1,1,0] op_sel_hi:[1,0,1] neg_lo:[0,1,0]
	v_pk_add_f32 v[122:123], v[160:161], v[168:169] neg_lo:[0,1] neg_hi:[0,1]
	v_pk_fma_f32 v[100:101], v[112:113], v[100:101], v[110:111] op_sel:[1,1,0] op_sel_hi:[1,0,1] neg_lo:[0,1,0]
	v_pk_mul_f32 v[110:111], v[114:115], v[106:107] op_sel:[0,0] op_sel_hi:[0,1]
	v_pk_add_f32 v[112:113], v[158:159], v[166:167] neg_lo:[0,1] neg_hi:[0,1]
	v_pk_fma_f32 v[106:107], v[114:115], v[106:107], v[110:111] op_sel:[1,1,0] op_sel_hi:[1,0,1] neg_lo:[0,1,0]
	v_pk_add_f32 v[110:111], v[158:159], v[166:167]
	v_pk_add_f32 v[114:115], v[160:161], v[168:169]
	v_pk_add_f32 v[158:159], v[102:103], v[156:157]
	v_pk_add_f32 v[154:155], v[110:111], v[114:115]
	v_pk_add_f32 v[110:111], v[110:111], v[114:115] neg_lo:[0,1] neg_hi:[0,1]
	v_pk_add_f32 v[114:115], v[112:113], v[122:123] op_sel:[0,1] op_sel_hi:[1,0] neg_hi:[0,1]
	v_pk_add_f32 v[112:113], v[112:113], v[122:123] op_sel:[0,1] op_sel_hi:[1,0] neg_lo:[0,1]
	v_pk_add_f32 v[122:123], v[170:171], v[120:121]
	v_pk_add_f32 v[120:121], v[170:171], v[120:121] neg_lo:[0,1] neg_hi:[0,1]
	v_pk_add_f32 v[102:103], v[102:103], v[156:157] neg_lo:[0,1] neg_hi:[0,1]
	v_pk_add_f32 v[156:157], v[122:123], v[158:159]
	v_pk_add_f32 v[122:123], v[122:123], v[158:159] neg_lo:[0,1] neg_hi:[0,1]
	v_pk_add_f32 v[158:159], v[120:121], v[102:103] op_sel:[0,1] op_sel_hi:[1,0] neg_hi:[0,1]
	v_pk_add_f32 v[102:103], v[120:121], v[102:103] op_sel:[0,1] op_sel_hi:[1,0] neg_lo:[0,1]
	v_pk_add_f32 v[120:121], v[116:117], v[104:105]
	v_pk_add_f32 v[104:105], v[116:117], v[104:105] neg_lo:[0,1] neg_hi:[0,1]
	v_pk_add_f32 v[116:117], v[98:99], v[118:119]
	v_pk_add_f32 v[98:99], v[98:99], v[118:119] neg_lo:[0,1] neg_hi:[0,1]
	v_pk_add_f32 v[118:119], v[120:121], v[116:117]
	v_pk_add_f32 v[116:117], v[120:121], v[116:117] neg_lo:[0,1] neg_hi:[0,1]
	v_pk_add_f32 v[120:121], v[104:105], v[98:99] op_sel:[0,1] op_sel_hi:[1,0] neg_hi:[0,1]
	v_pk_add_f32 v[98:99], v[104:105], v[98:99] op_sel:[0,1] op_sel_hi:[1,0] neg_lo:[0,1]
	v_pk_add_f32 v[104:105], v[108:109], v[100:101]
	v_pk_add_f32 v[100:101], v[108:109], v[100:101] neg_lo:[0,1] neg_hi:[0,1]
	v_pk_add_f32 v[108:109], v[96:97], v[106:107]
	v_pk_add_f32 v[96:97], v[96:97], v[106:107] neg_lo:[0,1] neg_hi:[0,1]
	v_pk_add_f32 v[106:107], v[104:105], v[108:109]
	v_pk_add_f32 v[104:105], v[104:105], v[108:109] neg_lo:[0,1] neg_hi:[0,1]
	v_pk_add_f32 v[108:109], v[100:101], v[96:97] op_sel:[0,1] op_sel_hi:[1,0] neg_hi:[0,1]
	v_pk_add_f32 v[96:97], v[100:101], v[96:97] op_sel:[0,1] op_sel_hi:[1,0] neg_lo:[0,1]
	v_pk_mul_f32 v[100:101], v[154:155], v[94:95] op_sel:[0,0] op_sel_hi:[0,1]
	v_pk_fma_f32 v[94:95], v[154:155], v[94:95], v[100:101] op_sel:[1,1,0] op_sel_hi:[1,0,1] neg_lo:[0,1,0]
	v_pk_mul_f32 v[100:101], v[114:115], v[92:93] op_sel:[0,0] op_sel_hi:[0,1]
	v_pk_fma_f32 v[92:93], v[114:115], v[92:93], v[100:101] op_sel:[1,1,0] op_sel_hi:[1,0,1] neg_lo:[0,1,0]
	v_pk_mul_f32 v[100:101], v[110:111], v[90:91] op_sel:[0,0] op_sel_hi:[0,1]
	v_pk_fma_f32 v[90:91], v[110:111], v[90:91], v[100:101] op_sel:[1,1,0] op_sel_hi:[1,0,1] neg_lo:[0,1,0]
	v_pk_mul_f32 v[100:101], v[112:113], v[88:89] op_sel:[0,0] op_sel_hi:[0,1]
	v_pk_fma_f32 v[88:89], v[112:113], v[88:89], v[100:101] op_sel:[1,1,0] op_sel_hi:[1,0,1] neg_lo:[0,1,0]
	v_pk_mul_f32 v[100:101], v[156:157], v[86:87] op_sel:[0,0] op_sel_hi:[0,1]
	v_pk_fma_f32 v[86:87], v[156:157], v[86:87], v[100:101] op_sel:[1,1,0] op_sel_hi:[1,0,1] neg_lo:[0,1,0]
	v_pk_mul_f32 v[100:101], v[158:159], v[84:85] op_sel:[0,0] op_sel_hi:[0,1]
	v_pk_fma_f32 v[84:85], v[158:159], v[84:85], v[100:101] op_sel:[1,1,0] op_sel_hi:[1,0,1] neg_lo:[0,1,0]
	v_pk_mul_f32 v[100:101], v[122:123], v[82:83] op_sel:[0,0] op_sel_hi:[0,1]
	v_pk_fma_f32 v[82:83], v[122:123], v[82:83], v[100:101] op_sel:[1,1,0] op_sel_hi:[1,0,1] neg_lo:[0,1,0]
	v_pk_mul_f32 v[100:101], v[102:103], v[80:81] op_sel:[0,0] op_sel_hi:[0,1]
	v_pk_fma_f32 v[80:81], v[102:103], v[80:81], v[100:101] op_sel:[1,1,0] op_sel_hi:[1,0,1] neg_lo:[0,1,0]
	v_pk_mul_f32 v[100:101], v[118:119], v[78:79] op_sel:[0,0] op_sel_hi:[0,1]
	v_pk_fma_f32 v[78:79], v[118:119], v[78:79], v[100:101] op_sel:[1,1,0] op_sel_hi:[1,0,1] neg_lo:[0,1,0]
	v_pk_mul_f32 v[100:101], v[120:121], v[76:77] op_sel:[0,0] op_sel_hi:[0,1]
	v_pk_fma_f32 v[76:77], v[120:121], v[76:77], v[100:101] op_sel:[1,1,0] op_sel_hi:[1,0,1] neg_lo:[0,1,0]
	v_pk_mul_f32 v[100:101], v[116:117], v[74:75] op_sel:[0,0] op_sel_hi:[0,1]
	v_pk_fma_f32 v[74:75], v[116:117], v[74:75], v[100:101] op_sel:[1,1,0] op_sel_hi:[1,0,1] neg_lo:[0,1,0]
	v_pk_mul_f32 v[100:101], v[98:99], v[72:73] op_sel:[0,0] op_sel_hi:[0,1]
	v_pk_fma_f32 v[72:73], v[98:99], v[72:73], v[100:101] op_sel:[1,1,0] op_sel_hi:[1,0,1] neg_lo:[0,1,0]
	v_pk_mul_f32 v[98:99], v[106:107], v[32:33] op_sel:[0,0] op_sel_hi:[0,1]
	v_pk_fma_f32 v[32:33], v[106:107], v[32:33], v[98:99] op_sel:[1,1,0] op_sel_hi:[1,0,1] neg_lo:[0,1,0]
	v_pk_mul_f32 v[98:99], v[108:109], v[30:31] op_sel:[0,0] op_sel_hi:[0,1]
	v_pk_fma_f32 v[30:31], v[108:109], v[30:31], v[98:99] op_sel:[1,1,0] op_sel_hi:[1,0,1] neg_lo:[0,1,0]
	v_pk_mul_f32 v[98:99], v[104:105], v[28:29] op_sel:[0,0] op_sel_hi:[0,1]
	v_pk_fma_f32 v[28:29], v[104:105], v[28:29], v[98:99] op_sel:[1,1,0] op_sel_hi:[1,0,1] neg_lo:[0,1,0]
	v_pk_mul_f32 v[98:99], v[96:97], v[26:27] op_sel:[0,0] op_sel_hi:[0,1]
	v_pk_fma_f32 v[26:27], v[96:97], v[26:27], v[98:99] op_sel:[1,1,0] op_sel_hi:[1,0,1] neg_lo:[0,1,0]
	v_pk_add_f32 v[96:97], v[94:95], v[90:91]
	v_pk_add_f32 v[90:91], v[94:95], v[90:91] neg_lo:[0,1] neg_hi:[0,1]
	v_pk_add_f32 v[94:95], v[92:93], v[88:89]
	v_pk_add_f32 v[88:89], v[92:93], v[88:89] neg_lo:[0,1] neg_hi:[0,1]
	v_pk_add_f32 v[92:93], v[96:97], v[94:95]
	v_pk_add_f32 v[94:95], v[96:97], v[94:95] neg_lo:[0,1] neg_hi:[0,1]
	v_pk_add_f32 v[96:97], v[90:91], v[88:89] op_sel:[0,1] op_sel_hi:[1,0] neg_lo:[0,1]
	v_pk_add_f32 v[88:89], v[90:91], v[88:89] op_sel:[0,1] op_sel_hi:[1,0] neg_hi:[0,1]
	v_pk_add_f32 v[90:91], v[86:87], v[82:83]
	v_pk_add_f32 v[82:83], v[86:87], v[82:83] neg_lo:[0,1] neg_hi:[0,1]
	v_pk_add_f32 v[86:87], v[84:85], v[80:81]
	v_pk_add_f32 v[80:81], v[84:85], v[80:81] neg_lo:[0,1] neg_hi:[0,1]
	v_pk_add_f32 v[84:85], v[90:91], v[86:87]
	v_pk_add_f32 v[86:87], v[90:91], v[86:87] neg_lo:[0,1] neg_hi:[0,1]
	v_pk_add_f32 v[90:91], v[82:83], v[80:81] op_sel:[0,1] op_sel_hi:[1,0] neg_lo:[0,1]
	v_pk_add_f32 v[80:81], v[82:83], v[80:81] op_sel:[0,1] op_sel_hi:[1,0] neg_hi:[0,1]
	v_pk_add_f32 v[82:83], v[78:79], v[74:75]
	v_pk_add_f32 v[74:75], v[78:79], v[74:75] neg_lo:[0,1] neg_hi:[0,1]
	v_pk_add_f32 v[78:79], v[76:77], v[72:73]
	v_pk_add_f32 v[72:73], v[76:77], v[72:73] neg_lo:[0,1] neg_hi:[0,1]
	v_pk_add_f32 v[76:77], v[82:83], v[78:79]
	v_pk_add_f32 v[78:79], v[82:83], v[78:79] neg_lo:[0,1] neg_hi:[0,1]
	v_pk_add_f32 v[82:83], v[74:75], v[72:73] op_sel:[0,1] op_sel_hi:[1,0] neg_lo:[0,1]
	v_pk_add_f32 v[74:75], v[74:75], v[72:73] op_sel:[0,1] op_sel_hi:[1,0] neg_hi:[0,1]
	v_pk_add_f32 v[72:73], v[32:33], v[28:29]
	v_pk_add_f32 v[28:29], v[32:33], v[28:29] neg_lo:[0,1] neg_hi:[0,1]
	v_pk_add_f32 v[32:33], v[30:31], v[26:27]
	v_pk_add_f32 v[26:27], v[30:31], v[26:27] neg_lo:[0,1] neg_hi:[0,1]
	v_pk_add_f32 v[98:99], v[72:73], v[32:33]
	v_pk_add_f32 v[100:101], v[72:73], v[32:33] neg_lo:[0,1] neg_hi:[0,1]
	v_pk_add_f32 v[30:31], v[28:29], v[26:27] op_sel:[0,1] op_sel_hi:[1,0] neg_lo:[0,1]
	v_pk_add_f32 v[102:103], v[28:29], v[26:27] op_sel:[0,1] op_sel_hi:[1,0] neg_hi:[0,1]
	v_mov_b64_e32 v[32:33], s[62:63]
	v_pk_mul_f32 v[26:27], v[90:91], v[32:33] op_sel:[0,0] op_sel_hi:[0,1]
	v_mov_b64_e32 v[28:29], s[64:65]
	v_pk_fma_f32 v[90:91], v[90:91], v[32:33], v[26:27] op_sel:[1,1,0] op_sel_hi:[1,0,1] neg_lo:[0,1,0]
	v_pk_mul_f32 v[26:27], v[82:83], v[28:29] op_sel:[0,0] op_sel_hi:[0,1]
	v_pk_fma_f32 v[82:83], v[82:83], v[28:29], v[26:27] op_sel:[1,1,0] op_sel_hi:[1,0,1] neg_lo:[0,1,0]
	v_mov_b64_e32 v[26:27], s[66:67]
	v_pk_mul_f32 v[72:73], v[30:31], v[26:27] op_sel:[0,0] op_sel_hi:[0,1]
	v_pk_fma_f32 v[104:105], v[30:31], v[26:27], v[72:73] op_sel:[1,1,0] op_sel_hi:[1,0,1] neg_lo:[0,1,0]
	v_pk_mul_f32 v[30:31], v[86:87], v[28:29] op_sel:[0,0] op_sel_hi:[0,1]
	v_mov_b64_e32 v[72:73], s[68:69]
	v_pk_fma_f32 v[86:87], v[86:87], v[28:29], v[30:31] op_sel:[1,1,0] op_sel_hi:[1,0,1] neg_lo:[0,1,0]
	v_pk_mul_f32 v[30:31], v[78:79], v[72:73] op_sel:[0,0] op_sel_hi:[0,1]
	v_pk_fma_f32 v[78:79], v[78:79], v[72:73], v[30:31] op_sel:[1,1,0] op_sel_hi:[1,0,1] neg_lo:[0,1,0]
	v_mov_b64_e32 v[30:31], s[70:71]
	v_pk_mul_f32 v[106:107], v[100:101], v[30:31] op_sel:[0,0] op_sel_hi:[0,1]
	v_pk_fma_f32 v[100:101], v[100:101], v[30:31], v[106:107] op_sel:[1,1,0] op_sel_hi:[1,0,1] neg_lo:[0,1,0]
	v_pk_mul_f32 v[106:107], v[80:81], v[26:27] op_sel:[0,0] op_sel_hi:[0,1]
	v_pk_fma_f32 v[80:81], v[80:81], v[26:27], v[106:107] op_sel:[1,1,0] op_sel_hi:[1,0,1] neg_lo:[0,1,0]
	v_pk_mul_f32 v[106:107], v[74:75], v[30:31] op_sel:[0,0] op_sel_hi:[0,1]
	v_pk_fma_f32 v[106:107], v[74:75], v[30:31], v[106:107] op_sel:[1,1,0] op_sel_hi:[1,0,1] neg_lo:[0,1,0]
	v_mov_b64_e32 v[74:75], s[72:73]
	v_pk_mul_f32 v[108:109], v[102:103], v[74:75] op_sel:[0,0] op_sel_hi:[0,1]
	v_pk_fma_f32 v[102:103], v[102:103], v[74:75], v[108:109] op_sel:[1,1,0] op_sel_hi:[1,0,1] neg_lo:[0,1,0]
	v_pk_add_f32 v[108:109], v[92:93], v[76:77]
	v_pk_add_f32 v[76:77], v[92:93], v[76:77] neg_lo:[0,1] neg_hi:[0,1]
	v_pk_add_f32 v[92:93], v[84:85], v[98:99]
	v_pk_add_f32 v[84:85], v[84:85], v[98:99] neg_lo:[0,1] neg_hi:[0,1]
	v_pk_add_f32 v[98:99], v[108:109], v[92:93]
	v_pk_add_f32 v[92:93], v[108:109], v[92:93] neg_lo:[0,1] neg_hi:[0,1]
	v_pk_add_f32 v[108:109], v[76:77], v[84:85] op_sel:[0,1] op_sel_hi:[1,0] neg_lo:[0,1]
	v_pk_add_f32 v[76:77], v[76:77], v[84:85] op_sel:[0,1] op_sel_hi:[1,0] neg_hi:[0,1]
	v_pk_add_f32 v[84:85], v[96:97], v[82:83]
	v_pk_add_f32 v[82:83], v[96:97], v[82:83] neg_lo:[0,1] neg_hi:[0,1]
	v_pk_add_f32 v[96:97], v[90:91], v[104:105]
	v_pk_add_f32 v[90:91], v[90:91], v[104:105] neg_lo:[0,1] neg_hi:[0,1]
	v_pk_add_f32 v[104:105], v[84:85], v[96:97]
	v_pk_add_f32 v[84:85], v[84:85], v[96:97] neg_lo:[0,1] neg_hi:[0,1]
	v_pk_add_f32 v[96:97], v[82:83], v[90:91] op_sel:[0,1] op_sel_hi:[1,0] neg_lo:[0,1]
	v_pk_add_f32 v[82:83], v[82:83], v[90:91] op_sel:[0,1] op_sel_hi:[1,0] neg_hi:[0,1]
	v_pk_add_f32 v[90:91], v[94:95], v[78:79]
	v_pk_add_f32 v[78:79], v[94:95], v[78:79] neg_lo:[0,1] neg_hi:[0,1]
	v_pk_add_f32 v[94:95], v[86:87], v[100:101]
	v_pk_add_f32 v[86:87], v[86:87], v[100:101] neg_lo:[0,1] neg_hi:[0,1]
	v_pk_add_f32 v[100:101], v[90:91], v[94:95]
	v_pk_add_f32 v[90:91], v[90:91], v[94:95] neg_lo:[0,1] neg_hi:[0,1]
	v_pk_add_f32 v[94:95], v[78:79], v[86:87] op_sel:[0,1] op_sel_hi:[1,0] neg_lo:[0,1]
	v_pk_add_f32 v[78:79], v[78:79], v[86:87] op_sel:[0,1] op_sel_hi:[1,0] neg_hi:[0,1]
	v_pk_add_f32 v[86:87], v[88:89], v[106:107]
	v_pk_add_f32 v[88:89], v[88:89], v[106:107] neg_lo:[0,1] neg_hi:[0,1]
	v_pk_add_f32 v[106:107], v[80:81], v[102:103]
	v_pk_add_f32 v[80:81], v[80:81], v[102:103] neg_lo:[0,1] neg_hi:[0,1]
	v_pk_add_f32 v[102:103], v[86:87], v[106:107]
	v_pk_add_f32 v[86:87], v[86:87], v[106:107] neg_lo:[0,1] neg_hi:[0,1]
	v_pk_add_f32 v[106:107], v[88:89], v[80:81] op_sel:[0,1] op_sel_hi:[1,0] neg_lo:[0,1]
	v_pk_add_f32 v[80:81], v[88:89], v[80:81] op_sel:[0,1] op_sel_hi:[1,0] neg_hi:[0,1]
	ds_write2_b64 v147, v[98:99], v[104:105] offset1:1
	ds_write2_b64 v147, v[100:101], v[102:103] offset0:2 offset1:3
	ds_write2_b64 v147, v[108:109], v[96:97] offset0:4 offset1:5
	ds_write2_b64 v147, v[94:95], v[106:107] offset0:6 offset1:7
	ds_write2_b64 v147, v[92:93], v[84:85] offset0:8 offset1:9
	ds_write2_b64 v147, v[90:91], v[86:87] offset0:10 offset1:11
	ds_write2_b64 v147, v[76:77], v[82:83] offset0:12 offset1:13
	ds_write2_b64 v147, v[78:79], v[80:81] offset0:14 offset1:15
	v_mov_b32_e32 v86, v40
	v_mov_b32_e32 v87, v41
	s_waitcnt lgkmcnt(0)
	s_barrier
	ds_read2_b64 v[76:79], v146 offset1:17
	ds_read2_b64 v[80:83], v146 offset0:34 offset1:51
	s_waitcnt lgkmcnt(1)
	v_pk_mul_f32 v[84:85], v[78:79], v[86:87] op_sel:[0,0] op_sel_hi:[0,1] neg_hi:[0,1]
	v_pk_fma_f32 v[88:89], v[78:79], v[86:87], v[84:85] op_sel:[1,1,0] op_sel_hi:[1,0,1]
	v_pk_mul_f32 v[78:79], v[86:87], v[86:87] op_sel:[0,0] op_sel_hi:[0,1]
	v_pk_fma_f32 v[78:79], v[86:87], v[86:87], v[78:79] op_sel:[1,1,0] op_sel_hi:[1,0,1] neg_lo:[0,1,0]
	s_waitcnt lgkmcnt(0)
	v_pk_mul_f32 v[84:85], v[80:81], v[78:79] op_sel:[0,0] op_sel_hi:[0,1] neg_hi:[0,1]
	v_pk_fma_f32 v[90:91], v[80:81], v[78:79], v[84:85] op_sel:[1,1,0] op_sel_hi:[1,0,1]
	v_pk_mul_f32 v[80:81], v[78:79], v[86:87] op_sel:[0,0] op_sel_hi:[0,1]
	v_pk_fma_f32 v[84:85], v[78:79], v[86:87], v[80:81] op_sel:[1,1,0] op_sel_hi:[1,0,1] neg_lo:[0,1,0]
	ds_read2_b64 v[78:81], v146 offset0:68 offset1:85
	v_pk_mul_f32 v[92:93], v[82:83], v[84:85] op_sel:[0,0] op_sel_hi:[0,1] neg_hi:[0,1]
	v_pk_fma_f32 v[92:93], v[82:83], v[84:85], v[92:93] op_sel:[1,1,0] op_sel_hi:[1,0,1]
	v_pk_mul_f32 v[82:83], v[84:85], v[86:87] op_sel:[0,0] op_sel_hi:[0,1]
	v_pk_fma_f32 v[82:83], v[84:85], v[86:87], v[82:83] op_sel:[1,1,0] op_sel_hi:[1,0,1] neg_lo:[0,1,0]
	s_waitcnt lgkmcnt(0)
	v_pk_mul_f32 v[84:85], v[78:79], v[82:83] op_sel:[0,0] op_sel_hi:[0,1] neg_hi:[0,1]
	v_pk_fma_f32 v[94:95], v[78:79], v[82:83], v[84:85] op_sel:[1,1,0] op_sel_hi:[1,0,1]
	v_pk_mul_f32 v[78:79], v[82:83], v[86:87] op_sel:[0,0] op_sel_hi:[0,1]
	v_pk_fma_f32 v[78:79], v[82:83], v[86:87], v[78:79] op_sel:[1,1,0] op_sel_hi:[1,0,1] neg_lo:[0,1,0]
	ds_read2_b64 v[82:85], v146 offset0:102 offset1:119
	v_pk_mul_f32 v[96:97], v[80:81], v[78:79] op_sel:[0,0] op_sel_hi:[0,1] neg_hi:[0,1]
	v_pk_fma_f32 v[96:97], v[80:81], v[78:79], v[96:97] op_sel:[1,1,0] op_sel_hi:[1,0,1]
	v_pk_mul_f32 v[80:81], v[78:79], v[86:87] op_sel:[0,0] op_sel_hi:[0,1]
	v_pk_fma_f32 v[78:79], v[78:79], v[86:87], v[80:81] op_sel:[1,1,0] op_sel_hi:[1,0,1] neg_lo:[0,1,0]
	s_waitcnt lgkmcnt(0)
	v_pk_mul_f32 v[80:81], v[82:83], v[78:79] op_sel:[0,0] op_sel_hi:[0,1] neg_hi:[0,1]
	v_pk_fma_f32 v[98:99], v[82:83], v[78:79], v[80:81] op_sel:[1,1,0] op_sel_hi:[1,0,1]
	v_pk_mul_f32 v[80:81], v[78:79], v[86:87] op_sel:[0,0] op_sel_hi:[0,1]
	v_pk_fma_f32 v[82:83], v[78:79], v[86:87], v[80:81] op_sel:[1,1,0] op_sel_hi:[1,0,1] neg_lo:[0,1,0]
	ds_read2_b64 v[78:81], v146 offset0:136 offset1:153
	v_pk_mul_f32 v[100:101], v[84:85], v[82:83] op_sel:[0,0] op_sel_hi:[0,1] neg_hi:[0,1]
	v_pk_fma_f32 v[100:101], v[84:85], v[82:83], v[100:101] op_sel:[1,1,0] op_sel_hi:[1,0,1]
	v_pk_mul_f32 v[84:85], v[82:83], v[86:87] op_sel:[0,0] op_sel_hi:[0,1]
	v_pk_fma_f32 v[82:83], v[82:83], v[86:87], v[84:85] op_sel:[1,1,0] op_sel_hi:[1,0,1] neg_lo:[0,1,0]
	s_waitcnt lgkmcnt(0)
	v_pk_mul_f32 v[84:85], v[78:79], v[82:83] op_sel:[0,0] op_sel_hi:[0,1] neg_hi:[0,1]
	v_pk_fma_f32 v[102:103], v[78:79], v[82:83], v[84:85] op_sel:[1,1,0] op_sel_hi:[1,0,1]
	v_pk_mul_f32 v[78:79], v[82:83], v[86:87] op_sel:[0,0] op_sel_hi:[0,1]
	v_pk_fma_f32 v[78:79], v[82:83], v[86:87], v[78:79] op_sel:[1,1,0] op_sel_hi:[1,0,1] neg_lo:[0,1,0]
	ds_read2_b64 v[82:85], v146 offset0:170 offset1:187
	v_pk_mul_f32 v[104:105], v[80:81], v[78:79] op_sel:[0,0] op_sel_hi:[0,1] neg_hi:[0,1]
	v_pk_fma_f32 v[104:105], v[80:81], v[78:79], v[104:105] op_sel:[1,1,0] op_sel_hi:[1,0,1]
	v_pk_mul_f32 v[80:81], v[78:79], v[86:87] op_sel:[0,0] op_sel_hi:[0,1]
	v_pk_fma_f32 v[78:79], v[78:79], v[86:87], v[80:81] op_sel:[1,1,0] op_sel_hi:[1,0,1] neg_lo:[0,1,0]
	s_waitcnt lgkmcnt(0)
	v_pk_mul_f32 v[80:81], v[82:83], v[78:79] op_sel:[0,0] op_sel_hi:[0,1] neg_hi:[0,1]
	v_pk_fma_f32 v[106:107], v[82:83], v[78:79], v[80:81] op_sel:[1,1,0] op_sel_hi:[1,0,1]
	v_pk_mul_f32 v[80:81], v[78:79], v[86:87] op_sel:[0,0] op_sel_hi:[0,1]
	v_pk_fma_f32 v[82:83], v[78:79], v[86:87], v[80:81] op_sel:[1,1,0] op_sel_hi:[1,0,1] neg_lo:[0,1,0]
	ds_read2_b64 v[78:81], v146 offset0:204 offset1:221
	v_pk_mul_f32 v[108:109], v[84:85], v[82:83] op_sel:[0,0] op_sel_hi:[0,1] neg_hi:[0,1]
	v_pk_fma_f32 v[108:109], v[84:85], v[82:83], v[108:109] op_sel:[1,1,0] op_sel_hi:[1,0,1]
	v_pk_mul_f32 v[84:85], v[82:83], v[86:87] op_sel:[0,0] op_sel_hi:[0,1]
	v_pk_fma_f32 v[82:83], v[82:83], v[86:87], v[84:85] op_sel:[1,1,0] op_sel_hi:[1,0,1] neg_lo:[0,1,0]
	s_waitcnt lgkmcnt(0)
	v_pk_mul_f32 v[84:85], v[78:79], v[82:83] op_sel:[0,0] op_sel_hi:[0,1] neg_hi:[0,1]
	v_pk_fma_f32 v[78:79], v[78:79], v[82:83], v[84:85] op_sel:[1,1,0] op_sel_hi:[1,0,1]
	v_pk_mul_f32 v[84:85], v[82:83], v[86:87] op_sel:[0,0] op_sel_hi:[0,1]
	v_pk_fma_f32 v[110:111], v[82:83], v[86:87], v[84:85] op_sel:[1,1,0] op_sel_hi:[1,0,1] neg_lo:[0,1,0]
	ds_read2_b64 v[82:85], v146 offset0:238 offset1:255
	v_pk_mul_f32 v[112:113], v[80:81], v[110:111] op_sel:[0,0] op_sel_hi:[0,1] neg_hi:[0,1]
	v_pk_fma_f32 v[80:81], v[80:81], v[110:111], v[112:113] op_sel:[1,1,0] op_sel_hi:[1,0,1]
	v_pk_mul_f32 v[112:113], v[110:111], v[86:87] op_sel:[0,0] op_sel_hi:[0,1]
	v_pk_fma_f32 v[110:111], v[110:111], v[86:87], v[112:113] op_sel:[1,1,0] op_sel_hi:[1,0,1] neg_lo:[0,1,0]
	s_waitcnt lgkmcnt(0)
	v_pk_mul_f32 v[112:113], v[82:83], v[110:111] op_sel:[0,0] op_sel_hi:[0,1] neg_hi:[0,1]
	v_pk_fma_f32 v[82:83], v[82:83], v[110:111], v[112:113] op_sel:[1,1,0] op_sel_hi:[1,0,1]
	v_pk_mul_f32 v[112:113], v[110:111], v[86:87] op_sel:[0,0] op_sel_hi:[0,1]
	v_pk_fma_f32 v[86:87], v[110:111], v[86:87], v[112:113] op_sel:[1,1,0] op_sel_hi:[1,0,1] neg_lo:[0,1,0]
	v_pk_mul_f32 v[110:111], v[84:85], v[86:87] op_sel:[0,0] op_sel_hi:[0,1] neg_hi:[0,1]
	v_pk_fma_f32 v[84:85], v[84:85], v[86:87], v[110:111] op_sel:[1,1,0] op_sel_hi:[1,0,1]
	v_pk_add_f32 v[86:87], v[76:77], v[102:103]
	v_pk_add_f32 v[76:77], v[76:77], v[102:103] neg_lo:[0,1] neg_hi:[0,1]
	v_pk_add_f32 v[102:103], v[94:95], v[78:79]
	v_pk_add_f32 v[78:79], v[94:95], v[78:79] neg_lo:[0,1] neg_hi:[0,1]
	v_pk_add_f32 v[94:95], v[86:87], v[102:103]
	v_pk_add_f32 v[86:87], v[86:87], v[102:103] neg_lo:[0,1] neg_hi:[0,1]
	v_pk_add_f32 v[102:103], v[76:77], v[78:79] op_sel:[0,1] op_sel_hi:[1,0] neg_lo:[0,1]
	v_pk_add_f32 v[76:77], v[76:77], v[78:79] op_sel:[0,1] op_sel_hi:[1,0] neg_hi:[0,1]
	v_pk_add_f32 v[78:79], v[88:89], v[104:105]
	v_pk_add_f32 v[88:89], v[88:89], v[104:105] neg_lo:[0,1] neg_hi:[0,1]
	v_pk_add_f32 v[104:105], v[96:97], v[80:81]
	v_pk_add_f32 v[80:81], v[96:97], v[80:81] neg_lo:[0,1] neg_hi:[0,1]
	v_pk_add_f32 v[96:97], v[78:79], v[104:105]
	v_pk_add_f32 v[78:79], v[78:79], v[104:105] neg_lo:[0,1] neg_hi:[0,1]
	v_pk_add_f32 v[104:105], v[88:89], v[80:81] op_sel:[0,1] op_sel_hi:[1,0] neg_lo:[0,1]
	v_pk_add_f32 v[80:81], v[88:89], v[80:81] op_sel:[0,1] op_sel_hi:[1,0] neg_hi:[0,1]
	v_pk_add_f32 v[88:89], v[90:91], v[106:107]
	v_pk_add_f32 v[90:91], v[90:91], v[106:107] neg_lo:[0,1] neg_hi:[0,1]
	v_pk_add_f32 v[106:107], v[98:99], v[82:83]
	v_pk_add_f32 v[82:83], v[98:99], v[82:83] neg_lo:[0,1] neg_hi:[0,1]
	v_pk_add_f32 v[98:99], v[88:89], v[106:107]
	v_pk_add_f32 v[88:89], v[88:89], v[106:107] neg_lo:[0,1] neg_hi:[0,1]
	v_pk_add_f32 v[106:107], v[90:91], v[82:83] op_sel:[0,1] op_sel_hi:[1,0] neg_lo:[0,1]
	v_pk_add_f32 v[82:83], v[90:91], v[82:83] op_sel:[0,1] op_sel_hi:[1,0] neg_hi:[0,1]
	v_pk_add_f32 v[90:91], v[92:93], v[108:109]
	v_pk_add_f32 v[92:93], v[92:93], v[108:109] neg_lo:[0,1] neg_hi:[0,1]
	v_pk_add_f32 v[108:109], v[100:101], v[84:85]
	v_pk_add_f32 v[84:85], v[100:101], v[84:85] neg_lo:[0,1] neg_hi:[0,1]
	v_pk_add_f32 v[100:101], v[90:91], v[108:109]
	v_pk_add_f32 v[90:91], v[90:91], v[108:109] neg_lo:[0,1] neg_hi:[0,1]
	v_pk_add_f32 v[108:109], v[92:93], v[84:85] op_sel:[0,1] op_sel_hi:[1,0] neg_lo:[0,1]
	v_pk_add_f32 v[84:85], v[92:93], v[84:85] op_sel:[0,1] op_sel_hi:[1,0] neg_hi:[0,1]
	v_pk_mul_f32 v[92:93], v[104:105], v[32:33] op_sel:[0,0] op_sel_hi:[0,1]
	v_pk_fma_f32 v[92:93], v[104:105], v[32:33], v[92:93] op_sel:[1,1,0] op_sel_hi:[1,0,1] neg_lo:[0,1,0]
	v_pk_mul_f32 v[104:105], v[106:107], v[28:29] op_sel:[0,0] op_sel_hi:[0,1]
	v_pk_fma_f32 v[104:105], v[106:107], v[28:29], v[104:105] op_sel:[1,1,0] op_sel_hi:[1,0,1] neg_lo:[0,1,0]
	v_pk_mul_f32 v[106:107], v[108:109], v[26:27] op_sel:[0,0] op_sel_hi:[0,1]
	v_pk_fma_f32 v[106:107], v[108:109], v[26:27], v[106:107] op_sel:[1,1,0] op_sel_hi:[1,0,1] neg_lo:[0,1,0]
	v_pk_mul_f32 v[108:109], v[78:79], v[28:29] op_sel:[0,0] op_sel_hi:[0,1]
	v_pk_fma_f32 v[78:79], v[78:79], v[28:29], v[108:109] op_sel:[1,1,0] op_sel_hi:[1,0,1] neg_lo:[0,1,0]
	v_pk_mul_f32 v[108:109], v[88:89], v[72:73] op_sel:[0,0] op_sel_hi:[0,1]
	v_pk_fma_f32 v[88:89], v[88:89], v[72:73], v[108:109] op_sel:[1,1,0] op_sel_hi:[1,0,1] neg_lo:[0,1,0]
	v_pk_mul_f32 v[108:109], v[90:91], v[30:31] op_sel:[0,0] op_sel_hi:[0,1]
	v_pk_fma_f32 v[90:91], v[90:91], v[30:31], v[108:109] op_sel:[1,1,0] op_sel_hi:[1,0,1] neg_lo:[0,1,0]
	v_pk_mul_f32 v[108:109], v[80:81], v[26:27] op_sel:[0,0] op_sel_hi:[0,1]
	v_pk_fma_f32 v[80:81], v[80:81], v[26:27], v[108:109] op_sel:[1,1,0] op_sel_hi:[1,0,1] neg_lo:[0,1,0]
	v_pk_mul_f32 v[108:109], v[82:83], v[30:31] op_sel:[0,0] op_sel_hi:[0,1]
	v_pk_fma_f32 v[82:83], v[82:83], v[30:31], v[108:109] op_sel:[1,1,0] op_sel_hi:[1,0,1] neg_lo:[0,1,0]
	v_pk_mul_f32 v[108:109], v[84:85], v[74:75] op_sel:[0,0] op_sel_hi:[0,1]
	v_pk_fma_f32 v[84:85], v[84:85], v[74:75], v[108:109] op_sel:[1,1,0] op_sel_hi:[1,0,1] neg_lo:[0,1,0]
	v_pk_add_f32 v[108:109], v[94:95], v[98:99]
	v_pk_add_f32 v[94:95], v[94:95], v[98:99] neg_lo:[0,1] neg_hi:[0,1]
	v_pk_add_f32 v[98:99], v[96:97], v[100:101]
	v_pk_add_f32 v[96:97], v[96:97], v[100:101] neg_lo:[0,1] neg_hi:[0,1]
	v_pk_add_f32 v[100:101], v[108:109], v[98:99]
	v_pk_add_f32 v[98:99], v[108:109], v[98:99] neg_lo:[0,1] neg_hi:[0,1]
	v_pk_add_f32 v[108:109], v[94:95], v[96:97] op_sel:[0,1] op_sel_hi:[1,0] neg_lo:[0,1]
	v_pk_add_f32 v[94:95], v[94:95], v[96:97] op_sel:[0,1] op_sel_hi:[1,0] neg_hi:[0,1]
	v_pk_add_f32 v[96:97], v[102:103], v[104:105]
	v_pk_add_f32 v[102:103], v[102:103], v[104:105] neg_lo:[0,1] neg_hi:[0,1]
	v_pk_add_f32 v[104:105], v[92:93], v[106:107]
	v_pk_add_f32 v[92:93], v[92:93], v[106:107] neg_lo:[0,1] neg_hi:[0,1]
	v_pk_add_f32 v[106:107], v[96:97], v[104:105]
	v_pk_add_f32 v[96:97], v[96:97], v[104:105] neg_lo:[0,1] neg_hi:[0,1]
	v_pk_add_f32 v[104:105], v[102:103], v[92:93] op_sel:[0,1] op_sel_hi:[1,0] neg_lo:[0,1]
	v_pk_add_f32 v[92:93], v[102:103], v[92:93] op_sel:[0,1] op_sel_hi:[1,0] neg_hi:[0,1]
	v_pk_add_f32 v[102:103], v[86:87], v[88:89]
	v_pk_add_f32 v[86:87], v[86:87], v[88:89] neg_lo:[0,1] neg_hi:[0,1]
	v_pk_add_f32 v[88:89], v[78:79], v[90:91]
	v_pk_add_f32 v[78:79], v[78:79], v[90:91] neg_lo:[0,1] neg_hi:[0,1]
	v_pk_add_f32 v[90:91], v[102:103], v[88:89]
	v_pk_add_f32 v[88:89], v[102:103], v[88:89] neg_lo:[0,1] neg_hi:[0,1]
	v_pk_add_f32 v[102:103], v[86:87], v[78:79] op_sel:[0,1] op_sel_hi:[1,0] neg_lo:[0,1]
	v_pk_add_f32 v[78:79], v[86:87], v[78:79] op_sel:[0,1] op_sel_hi:[1,0] neg_hi:[0,1]
	v_pk_add_f32 v[86:87], v[76:77], v[82:83]
	v_pk_add_f32 v[76:77], v[76:77], v[82:83] neg_lo:[0,1] neg_hi:[0,1]
	v_pk_add_f32 v[82:83], v[80:81], v[84:85]
	v_pk_add_f32 v[80:81], v[80:81], v[84:85] neg_lo:[0,1] neg_hi:[0,1]
	v_pk_add_f32 v[84:85], v[86:87], v[82:83]
	v_pk_add_f32 v[82:83], v[86:87], v[82:83] neg_lo:[0,1] neg_hi:[0,1]
	v_pk_add_f32 v[86:87], v[76:77], v[80:81] op_sel:[0,1] op_sel_hi:[1,0] neg_lo:[0,1]
	v_pk_add_f32 v[76:77], v[76:77], v[80:81] op_sel:[0,1] op_sel_hi:[1,0] neg_hi:[0,1]
	ds_write2_b64 v146, v[100:101], v[106:107] offset1:17
	ds_write2_b64 v146, v[90:91], v[84:85] offset0:34 offset1:51
	ds_write2_b64 v146, v[108:109], v[104:105] offset0:68 offset1:85
	ds_write2_b64 v146, v[102:103], v[86:87] offset0:102 offset1:119
	ds_write2_b64 v146, v[98:99], v[96:97] offset0:136 offset1:153
	ds_write2_b64 v146, v[88:89], v[82:83] offset0:170 offset1:187
	ds_write2_b64 v146, v[94:95], v[92:93] offset0:204 offset1:221
	ds_write2_b64 v146, v[78:79], v[76:77] offset0:238 offset1:255
	v_mov_b32_e32 v77, v39
	v_mov_b32_e32 v76, v38
	s_waitcnt lgkmcnt(0)
	s_barrier
	ds_read_b64 v[78:79], v144 offset:2176
	ds_read_b64 v[80:81], v144 offset:4352
	ds_read_b64 v[82:83], v144 offset:6528
	ds_read_b64 v[84:85], v144
	s_waitcnt lgkmcnt(3)
	v_pk_mul_f32 v[86:87], v[78:79], v[76:77] op_sel:[0,0] op_sel_hi:[0,1] neg_hi:[0,1]
	v_pk_fma_f32 v[78:79], v[78:79], v[76:77], v[86:87] op_sel:[1,1,0] op_sel_hi:[1,0,1]
	v_pk_mul_f32 v[86:87], v[76:77], v[76:77] op_sel:[0,0] op_sel_hi:[0,1]
	ds_read_b64 v[90:91], v144 offset:8704
	v_pk_fma_f32 v[86:87], v[76:77], v[76:77], v[86:87] op_sel:[1,1,0] op_sel_hi:[1,0,1] neg_lo:[0,1,0]
	s_waitcnt lgkmcnt(3)
	v_pk_mul_f32 v[88:89], v[80:81], v[86:87] op_sel:[0,0] op_sel_hi:[0,1] neg_hi:[0,1]
	v_pk_fma_f32 v[80:81], v[80:81], v[86:87], v[88:89] op_sel:[1,1,0] op_sel_hi:[1,0,1]
	v_pk_mul_f32 v[88:89], v[86:87], v[76:77] op_sel:[0,0] op_sel_hi:[0,1]
	v_pk_fma_f32 v[86:87], v[86:87], v[76:77], v[88:89] op_sel:[1,1,0] op_sel_hi:[1,0,1] neg_lo:[0,1,0]
	s_waitcnt lgkmcnt(2)
	v_pk_mul_f32 v[88:89], v[82:83], v[86:87] op_sel:[0,0] op_sel_hi:[0,1] neg_hi:[0,1]
	v_pk_fma_f32 v[82:83], v[82:83], v[86:87], v[88:89] op_sel:[1,1,0] op_sel_hi:[1,0,1]
	v_pk_mul_f32 v[88:89], v[86:87], v[76:77] op_sel:[0,0] op_sel_hi:[0,1]
	v_pk_fma_f32 v[86:87], v[86:87], v[76:77], v[88:89] op_sel:[1,1,0] op_sel_hi:[1,0,1] neg_lo:[0,1,0]
	ds_read_b64 v[88:89], v144 offset:10880
	ds_read_b64 v[92:93], v144 offset:13056
	ds_read_b64 v[94:95], v144 offset:15232
	s_waitcnt lgkmcnt(3)
	v_pk_mul_f32 v[96:97], v[90:91], v[86:87] op_sel:[0,0] op_sel_hi:[0,1] neg_hi:[0,1]
	ds_read_b64 v[98:99], v144 offset:17408
	v_pk_fma_f32 v[90:91], v[90:91], v[86:87], v[96:97] op_sel:[1,1,0] op_sel_hi:[1,0,1]
	v_pk_mul_f32 v[96:97], v[86:87], v[76:77] op_sel:[0,0] op_sel_hi:[0,1]
	v_pk_fma_f32 v[86:87], v[86:87], v[76:77], v[96:97] op_sel:[1,1,0] op_sel_hi:[1,0,1] neg_lo:[0,1,0]
	s_waitcnt lgkmcnt(3)
	v_pk_mul_f32 v[96:97], v[88:89], v[86:87] op_sel:[0,0] op_sel_hi:[0,1] neg_hi:[0,1]
	v_pk_fma_f32 v[88:89], v[88:89], v[86:87], v[96:97] op_sel:[1,1,0] op_sel_hi:[1,0,1]
	v_pk_mul_f32 v[96:97], v[86:87], v[76:77] op_sel:[0,0] op_sel_hi:[0,1]
	v_pk_fma_f32 v[86:87], v[86:87], v[76:77], v[96:97] op_sel:[1,1,0] op_sel_hi:[1,0,1] neg_lo:[0,1,0]
	s_waitcnt lgkmcnt(2)
	v_pk_mul_f32 v[96:97], v[92:93], v[86:87] op_sel:[0,0] op_sel_hi:[0,1] neg_hi:[0,1]
	v_pk_fma_f32 v[92:93], v[92:93], v[86:87], v[96:97] op_sel:[1,1,0] op_sel_hi:[1,0,1]
	v_pk_mul_f32 v[96:97], v[86:87], v[76:77] op_sel:[0,0] op_sel_hi:[0,1]
	v_pk_fma_f32 v[86:87], v[86:87], v[76:77], v[96:97] op_sel:[1,1,0] op_sel_hi:[1,0,1] neg_lo:[0,1,0]
	s_waitcnt lgkmcnt(1)
	v_pk_mul_f32 v[96:97], v[94:95], v[86:87] op_sel:[0,0] op_sel_hi:[0,1] neg_hi:[0,1]
	v_pk_fma_f32 v[94:95], v[94:95], v[86:87], v[96:97] op_sel:[1,1,0] op_sel_hi:[1,0,1]
	v_pk_mul_f32 v[96:97], v[86:87], v[76:77] op_sel:[0,0] op_sel_hi:[0,1]
	v_pk_fma_f32 v[86:87], v[86:87], v[76:77], v[96:97] op_sel:[1,1,0] op_sel_hi:[1,0,1] neg_lo:[0,1,0]
	ds_read_b64 v[96:97], v144 offset:19584
	ds_read_b64 v[100:101], v144 offset:21760
	ds_read_b64 v[102:103], v144 offset:23936
	s_waitcnt lgkmcnt(3)
	v_pk_mul_f32 v[104:105], v[98:99], v[86:87] op_sel:[0,0] op_sel_hi:[0,1] neg_hi:[0,1]
	ds_read_b64 v[106:107], v144 offset:26112
	v_pk_fma_f32 v[98:99], v[98:99], v[86:87], v[104:105] op_sel:[1,1,0] op_sel_hi:[1,0,1]
	v_pk_mul_f32 v[104:105], v[86:87], v[76:77] op_sel:[0,0] op_sel_hi:[0,1]
	v_pk_fma_f32 v[86:87], v[86:87], v[76:77], v[104:105] op_sel:[1,1,0] op_sel_hi:[1,0,1] neg_lo:[0,1,0]
	s_waitcnt lgkmcnt(3)
	v_pk_mul_f32 v[104:105], v[96:97], v[86:87] op_sel:[0,0] op_sel_hi:[0,1] neg_hi:[0,1]
	v_pk_fma_f32 v[96:97], v[96:97], v[86:87], v[104:105] op_sel:[1,1,0] op_sel_hi:[1,0,1]
	v_pk_mul_f32 v[104:105], v[86:87], v[76:77] op_sel:[0,0] op_sel_hi:[0,1]
	v_pk_fma_f32 v[86:87], v[86:87], v[76:77], v[104:105] op_sel:[1,1,0] op_sel_hi:[1,0,1] neg_lo:[0,1,0]
	s_waitcnt lgkmcnt(2)
	v_pk_mul_f32 v[104:105], v[100:101], v[86:87] op_sel:[0,0] op_sel_hi:[0,1] neg_hi:[0,1]
	v_pk_fma_f32 v[100:101], v[100:101], v[86:87], v[104:105] op_sel:[1,1,0] op_sel_hi:[1,0,1]
	v_pk_mul_f32 v[104:105], v[86:87], v[76:77] op_sel:[0,0] op_sel_hi:[0,1]
	v_pk_fma_f32 v[86:87], v[86:87], v[76:77], v[104:105] op_sel:[1,1,0] op_sel_hi:[1,0,1] neg_lo:[0,1,0]
	s_waitcnt lgkmcnt(1)
	v_pk_mul_f32 v[104:105], v[102:103], v[86:87] op_sel:[0,0] op_sel_hi:[0,1] neg_hi:[0,1]
	v_pk_fma_f32 v[102:103], v[102:103], v[86:87], v[104:105] op_sel:[1,1,0] op_sel_hi:[1,0,1]
	v_pk_mul_f32 v[104:105], v[86:87], v[76:77] op_sel:[0,0] op_sel_hi:[0,1]
	v_pk_fma_f32 v[86:87], v[86:87], v[76:77], v[104:105] op_sel:[1,1,0] op_sel_hi:[1,0,1] neg_lo:[0,1,0]
	ds_read_b64 v[104:105], v144 offset:28288
	ds_read_b64 v[108:109], v144 offset:30464
	ds_read_b64 v[110:111], v144 offset:32640
	s_waitcnt lgkmcnt(3)
	v_pk_mul_f32 v[112:113], v[106:107], v[86:87] op_sel:[0,0] op_sel_hi:[0,1] neg_hi:[0,1]
	v_pk_fma_f32 v[106:107], v[106:107], v[86:87], v[112:113] op_sel:[1,1,0] op_sel_hi:[1,0,1]
	v_pk_mul_f32 v[112:113], v[86:87], v[76:77] op_sel:[0,0] op_sel_hi:[0,1]
	v_pk_fma_f32 v[86:87], v[86:87], v[76:77], v[112:113] op_sel:[1,1,0] op_sel_hi:[1,0,1] neg_lo:[0,1,0]
	s_waitcnt lgkmcnt(2)
	v_pk_mul_f32 v[112:113], v[104:105], v[86:87] op_sel:[0,0] op_sel_hi:[0,1] neg_hi:[0,1]
	v_pk_fma_f32 v[104:105], v[104:105], v[86:87], v[112:113] op_sel:[1,1,0] op_sel_hi:[1,0,1]
	v_pk_mul_f32 v[112:113], v[86:87], v[76:77] op_sel:[0,0] op_sel_hi:[0,1]
	v_pk_fma_f32 v[86:87], v[86:87], v[76:77], v[112:113] op_sel:[1,1,0] op_sel_hi:[1,0,1] neg_lo:[0,1,0]
	s_waitcnt lgkmcnt(1)
	v_pk_mul_f32 v[112:113], v[108:109], v[86:87] op_sel:[0,0] op_sel_hi:[0,1] neg_hi:[0,1]
	v_pk_fma_f32 v[108:109], v[108:109], v[86:87], v[112:113] op_sel:[1,1,0] op_sel_hi:[1,0,1]
	v_pk_mul_f32 v[112:113], v[86:87], v[76:77] op_sel:[0,0] op_sel_hi:[0,1]
	v_pk_fma_f32 v[76:77], v[86:87], v[76:77], v[112:113] op_sel:[1,1,0] op_sel_hi:[1,0,1] neg_lo:[0,1,0]
	s_waitcnt lgkmcnt(0)
	v_pk_mul_f32 v[86:87], v[110:111], v[76:77] op_sel:[0,0] op_sel_hi:[0,1] neg_hi:[0,1]
	v_pk_fma_f32 v[76:77], v[110:111], v[76:77], v[86:87] op_sel:[1,1,0] op_sel_hi:[1,0,1]
	v_pk_add_f32 v[86:87], v[84:85], v[98:99]
	v_pk_add_f32 v[84:85], v[84:85], v[98:99] neg_lo:[0,1] neg_hi:[0,1]
	v_pk_add_f32 v[98:99], v[90:91], v[106:107]
	v_pk_add_f32 v[90:91], v[90:91], v[106:107] neg_lo:[0,1] neg_hi:[0,1]
	v_pk_add_f32 v[106:107], v[86:87], v[98:99]
	v_pk_add_f32 v[98:99], v[86:87], v[98:99] neg_lo:[0,1] neg_hi:[0,1]
	v_pk_add_f32 v[86:87], v[84:85], v[90:91] op_sel:[0,1] op_sel_hi:[1,0] neg_lo:[0,1]
	v_pk_add_f32 v[110:111], v[84:85], v[90:91] op_sel:[0,1] op_sel_hi:[1,0] neg_hi:[0,1]
	v_pk_add_f32 v[84:85], v[78:79], v[96:97]
	v_pk_add_f32 v[78:79], v[78:79], v[96:97] neg_lo:[0,1] neg_hi:[0,1]
	v_pk_add_f32 v[90:91], v[88:89], v[104:105]
	v_pk_add_f32 v[88:89], v[88:89], v[104:105] neg_lo:[0,1] neg_hi:[0,1]
	v_pk_add_f32 v[96:97], v[84:85], v[90:91]
	v_pk_add_f32 v[84:85], v[84:85], v[90:91] neg_lo:[0,1] neg_hi:[0,1]
	v_pk_add_f32 v[90:91], v[78:79], v[88:89] op_sel:[0,1] op_sel_hi:[1,0] neg_lo:[0,1]
	v_pk_add_f32 v[78:79], v[78:79], v[88:89] op_sel:[0,1] op_sel_hi:[1,0] neg_hi:[0,1]
	v_pk_add_f32 v[88:89], v[80:81], v[100:101]
	v_pk_add_f32 v[80:81], v[80:81], v[100:101] neg_lo:[0,1] neg_hi:[0,1]
	v_pk_add_f32 v[100:101], v[92:93], v[108:109]
	v_pk_add_f32 v[92:93], v[92:93], v[108:109] neg_lo:[0,1] neg_hi:[0,1]
	v_pk_add_f32 v[104:105], v[88:89], v[100:101]
	v_pk_add_f32 v[88:89], v[88:89], v[100:101] neg_lo:[0,1] neg_hi:[0,1]
	v_pk_add_f32 v[100:101], v[80:81], v[92:93] op_sel:[0,1] op_sel_hi:[1,0] neg_lo:[0,1]
	v_pk_add_f32 v[80:81], v[80:81], v[92:93] op_sel:[0,1] op_sel_hi:[1,0] neg_hi:[0,1]
	v_pk_add_f32 v[92:93], v[82:83], v[102:103]
	v_pk_add_f32 v[82:83], v[82:83], v[102:103] neg_lo:[0,1] neg_hi:[0,1]
	v_pk_add_f32 v[102:103], v[94:95], v[76:77]
	v_pk_add_f32 v[76:77], v[94:95], v[76:77] neg_lo:[0,1] neg_hi:[0,1]
	v_pk_add_f32 v[94:95], v[92:93], v[102:103]
	v_pk_add_f32 v[92:93], v[92:93], v[102:103] neg_lo:[0,1] neg_hi:[0,1]
	v_pk_add_f32 v[102:103], v[82:83], v[76:77] op_sel:[0,1] op_sel_hi:[1,0] neg_lo:[0,1]
	v_pk_add_f32 v[76:77], v[82:83], v[76:77] op_sel:[0,1] op_sel_hi:[1,0] neg_hi:[0,1]
	v_pk_mul_f32 v[82:83], v[90:91], v[32:33] op_sel:[0,0] op_sel_hi:[0,1]
	v_pk_fma_f32 v[32:33], v[90:91], v[32:33], v[82:83] op_sel:[1,1,0] op_sel_hi:[1,0,1] neg_lo:[0,1,0]
	v_pk_mul_f32 v[82:83], v[100:101], v[28:29] op_sel:[0,0] op_sel_hi:[0,1]
	v_pk_mul_f32 v[90:91], v[102:103], v[26:27] op_sel:[0,0] op_sel_hi:[0,1]
	v_pk_fma_f32 v[82:83], v[100:101], v[28:29], v[82:83] op_sel:[1,1,0] op_sel_hi:[1,0,1] neg_lo:[0,1,0]
	v_pk_mul_f32 v[100:101], v[84:85], v[28:29] op_sel:[0,0] op_sel_hi:[0,1]
	v_pk_fma_f32 v[90:91], v[102:103], v[26:27], v[90:91] op_sel:[1,1,0] op_sel_hi:[1,0,1] neg_lo:[0,1,0]
	v_pk_fma_f32 v[108:109], v[84:85], v[28:29], v[100:101] op_sel:[1,1,0] op_sel_hi:[1,0,1] neg_lo:[0,1,0]
	v_pk_mul_f32 v[28:29], v[88:89], v[72:73] op_sel:[0,0] op_sel_hi:[0,1]
	v_pk_add_f32 v[84:85], v[32:33], v[90:91]
	v_pk_fma_f32 v[72:73], v[88:89], v[72:73], v[28:29] op_sel:[1,1,0] op_sel_hi:[1,0,1] neg_lo:[0,1,0]
	v_pk_mul_f32 v[28:29], v[92:93], v[30:31] op_sel:[0,0] op_sel_hi:[0,1]
	v_pk_fma_f32 v[88:89], v[92:93], v[30:31], v[28:29] op_sel:[1,1,0] op_sel_hi:[1,0,1] neg_lo:[0,1,0]
	v_pk_mul_f32 v[28:29], v[78:79], v[26:27] op_sel:[0,0] op_sel_hi:[0,1]
	v_pk_fma_f32 v[112:113], v[78:79], v[26:27], v[28:29] op_sel:[1,1,0] op_sel_hi:[1,0,1] neg_lo:[0,1,0]
	v_pk_mul_f32 v[26:27], v[80:81], v[30:31] op_sel:[0,0] op_sel_hi:[0,1]
	v_pk_add_f32 v[28:29], v[96:97], v[94:95] neg_lo:[0,1] neg_hi:[0,1]
	v_pk_fma_f32 v[114:115], v[80:81], v[30:31], v[26:27] op_sel:[1,1,0] op_sel_hi:[1,0,1] neg_lo:[0,1,0]
	v_pk_mul_f32 v[26:27], v[76:77], v[74:75] op_sel:[0,0] op_sel_hi:[0,1]
	v_pk_add_f32 v[30:31], v[32:33], v[90:91] neg_lo:[0,1] neg_hi:[0,1]
	v_pk_fma_f32 v[116:117], v[76:77], v[74:75], v[26:27] op_sel:[1,1,0] op_sel_hi:[1,0,1] neg_lo:[0,1,0]
	v_pk_add_f32 v[26:27], v[106:107], v[104:105] neg_lo:[0,1] neg_hi:[0,1]
	v_pk_add_f32 v[80:81], v[86:87], v[82:83]
	v_pk_add_f32 v[76:77], v[26:27], v[28:29] op_sel:[0,1] op_sel_hi:[1,0] neg_lo:[0,1]
	v_pk_add_f32 v[26:27], v[26:27], v[28:29] op_sel:[0,1] op_sel_hi:[1,0] neg_hi:[0,1]
	v_pk_add_f32 v[28:29], v[86:87], v[82:83] neg_lo:[0,1] neg_hi:[0,1]
	v_pk_add_f32 v[32:33], v[108:109], v[88:89] neg_lo:[0,1] neg_hi:[0,1]
	v_pk_add_f32 v[82:83], v[28:29], v[30:31] op_sel:[0,1] op_sel_hi:[1,0] neg_lo:[0,1]
	v_pk_add_f32 v[28:29], v[28:29], v[30:31] op_sel:[0,1] op_sel_hi:[1,0] neg_hi:[0,1]
	v_pk_add_f32 v[30:31], v[98:99], v[72:73] neg_lo:[0,1] neg_hi:[0,1]
	v_pk_add_f32 v[74:75], v[106:107], v[104:105]
	v_pk_add_f32 v[78:79], v[96:97], v[94:95]
	v_pk_add_f32 v[86:87], v[98:99], v[72:73]
	v_pk_add_f32 v[90:91], v[108:109], v[88:89]
	v_pk_add_f32 v[88:89], v[30:31], v[32:33] op_sel:[0,1] op_sel_hi:[1,0] neg_lo:[0,1]
	v_pk_add_f32 v[30:31], v[30:31], v[32:33] op_sel:[0,1] op_sel_hi:[1,0] neg_hi:[0,1]
	v_pk_add_f32 v[92:93], v[110:111], v[114:115]
	v_pk_add_f32 v[32:33], v[110:111], v[114:115] neg_lo:[0,1] neg_hi:[0,1]
	v_pk_add_f32 v[96:97], v[112:113], v[116:117]
	v_pk_add_f32 v[72:73], v[112:113], v[116:117] neg_lo:[0,1] neg_hi:[0,1]
	v_pk_add_f32 v[100:101], v[74:75], v[78:79]
	v_pk_add_f32 v[102:103], v[80:81], v[84:85]
	v_pk_add_f32 v[104:105], v[86:87], v[90:91]
	v_pk_add_f32 v[98:99], v[92:93], v[96:97]
	v_pk_add_f32 v[94:95], v[32:33], v[72:73] op_sel:[0,1] op_sel_hi:[1,0] neg_lo:[0,1]
	v_pk_add_f32 v[32:33], v[32:33], v[72:73] op_sel:[0,1] op_sel_hi:[1,0] neg_hi:[0,1]
	v_mov_b32_e32 v72, v36
	v_mov_b32_e32 v73, v37
	s_and_saveexec_b64 s[0:1], s[4:5]
	s_xor_b64 s[0:1], exec, s[0:1]
	s_cbranch_execz .LBB0_1333
	v_mov_b64_e32 v[106:107], s[16:17]
	v_pk_mul_f32 v[108:109], v[72:73], v[106:107] op_sel:[0,0] op_sel_hi:[0,1]
	v_pk_fma_f32 v[106:107], v[72:73], v[106:107], v[108:109] op_sel:[1,1,0] op_sel_hi:[1,0,1] neg_lo:[0,1,0]
	v_pk_mul_f32 v[108:109], v[100:101], v[106:107] op_sel:[0,0] op_sel_hi:[0,1] neg_hi:[0,1]
	v_pk_fma_f32 v[100:101], v[100:101], v[106:107], v[108:109] op_sel:[1,1,0] op_sel_hi:[1,0,1]
	v_mov_b64_e32 v[106:107], s[18:19]
	v_pk_mul_f32 v[108:109], v[72:73], v[106:107] op_sel:[0,0] op_sel_hi:[0,1]
	v_pk_fma_f32 v[106:107], v[72:73], v[106:107], v[108:109] op_sel:[1,1,0] op_sel_hi:[1,0,1] neg_lo:[0,1,0]
	v_pk_mul_f32 v[108:109], v[102:103], v[106:107] op_sel:[0,0] op_sel_hi:[0,1] neg_hi:[0,1]
	v_pk_fma_f32 v[102:103], v[102:103], v[106:107], v[108:109] op_sel:[1,1,0] op_sel_hi:[1,0,1]
	v_mov_b64_e32 v[106:107], s[20:21]
	v_pk_mul_f32 v[108:109], v[72:73], v[106:107] op_sel:[0,0] op_sel_hi:[0,1]
	v_pk_fma_f32 v[106:107], v[72:73], v[106:107], v[108:109] op_sel:[1,1,0] op_sel_hi:[1,0,1] neg_lo:[0,1,0]
	v_pk_mul_f32 v[108:109], v[104:105], v[106:107] op_sel:[0,0] op_sel_hi:[0,1] neg_hi:[0,1]
	v_pk_fma_f32 v[104:105], v[104:105], v[106:107], v[108:109] op_sel:[1,1,0] op_sel_hi:[1,0,1]
	v_mov_b64_e32 v[106:107], s[22:23]
	v_pk_mul_f32 v[108:109], v[72:73], v[106:107] op_sel:[0,0] op_sel_hi:[0,1]
	v_pk_fma_f32 v[106:107], v[72:73], v[106:107], v[108:109] op_sel:[1,1,0] op_sel_hi:[1,0,1] neg_lo:[0,1,0]
	v_pk_mul_f32 v[108:109], v[98:99], v[106:107] op_sel:[0,0] op_sel_hi:[0,1] neg_hi:[0,1]
	v_pk_fma_f32 v[98:99], v[98:99], v[106:107], v[108:109] op_sel:[1,1,0] op_sel_hi:[1,0,1]
	ds_write_b64 v144, v[100:101]
	ds_write_b64 v144, v[102:103] offset:2176
	ds_write_b64 v144, v[104:105] offset:4352
	ds_write_b64 v144, v[98:99] offset:6528
	v_mov_b64_e32 v[98:99], s[50:51]
	v_pk_mul_f32 v[100:101], v[72:73], v[98:99] op_sel:[0,0] op_sel_hi:[0,1]
	s_nop 0
	v_pk_fma_f32 v[98:99], v[72:73], v[98:99], v[100:101] op_sel:[1,1,0] op_sel_hi:[1,0,1] neg_lo:[0,1,0]
	v_pk_mul_f32 v[100:101], v[76:77], v[98:99] op_sel:[0,0] op_sel_hi:[0,1] neg_hi:[0,1]
	v_pk_fma_f32 v[76:77], v[76:77], v[98:99], v[100:101] op_sel:[1,1,0] op_sel_hi:[1,0,1]
	v_mov_b64_e32 v[98:99], s[52:53]
	v_pk_mul_f32 v[100:101], v[72:73], v[98:99] op_sel:[0,0] op_sel_hi:[0,1]
	v_pk_fma_f32 v[98:99], v[72:73], v[98:99], v[100:101] op_sel:[1,1,0] op_sel_hi:[1,0,1] neg_lo:[0,1,0]
	v_pk_mul_f32 v[100:101], v[82:83], v[98:99] op_sel:[0,0] op_sel_hi:[0,1] neg_hi:[0,1]
	v_pk_fma_f32 v[82:83], v[82:83], v[98:99], v[100:101] op_sel:[1,1,0] op_sel_hi:[1,0,1]
	v_mov_b64_e32 v[98:99], s[54:55]
	v_pk_mul_f32 v[100:101], v[72:73], v[98:99] op_sel:[0,0] op_sel_hi:[0,1]
	v_pk_fma_f32 v[98:99], v[72:73], v[98:99], v[100:101] op_sel:[1,1,0] op_sel_hi:[1,0,1] neg_lo:[0,1,0]
	v_pk_mul_f32 v[100:101], v[88:89], v[98:99] op_sel:[0,0] op_sel_hi:[0,1] neg_hi:[0,1]
	v_pk_fma_f32 v[88:89], v[88:89], v[98:99], v[100:101] op_sel:[1,1,0] op_sel_hi:[1,0,1]
	v_mov_b64_e32 v[98:99], s[56:57]
	v_pk_mul_f32 v[100:101], v[72:73], v[98:99] op_sel:[0,0] op_sel_hi:[0,1]
	v_pk_fma_f32 v[98:99], v[72:73], v[98:99], v[100:101] op_sel:[1,1,0] op_sel_hi:[1,0,1] neg_lo:[0,1,0]
	v_pk_mul_f32 v[100:101], v[94:95], v[98:99] op_sel:[0,0] op_sel_hi:[0,1] neg_hi:[0,1]
	s_nop 0
	v_pk_fma_f32 v[94:95], v[94:95], v[98:99], v[100:101] op_sel:[1,1,0] op_sel_hi:[1,0,1]

.LBB0_1335:
	s_or_b64 exec, exec, s[0:1]
	v_pk_add_f32 v[98:99], v[74:75], v[78:79] neg_lo:[0,1] neg_hi:[0,1]
	v_pk_add_f32 v[80:81], v[80:81], v[84:85] neg_lo:[0,1] neg_hi:[0,1]
	v_pk_add_f32 v[78:79], v[86:87], v[90:91] neg_lo:[0,1] neg_hi:[0,1]
	v_pk_add_f32 v[74:75], v[92:93], v[96:97] neg_lo:[0,1] neg_hi:[0,1]
	ds_write_b64 v144, v[76:77] offset:8704
	ds_write_b64 v144, v[82:83] offset:10880
	ds_write_b64 v144, v[88:89] offset:13056
	ds_write_b64 v144, v[94:95] offset:15232
	s_and_saveexec_b64 s[0:1], s[4:5]
	s_xor_b64 s[0:1], exec, s[0:1]
	s_cbranch_execz .LBB0_1337
	v_mov_b64_e32 v[76:77], s[14:15]
	v_pk_mul_f32 v[82:83], v[72:73], v[76:77] op_sel:[0,0] op_sel_hi:[0,1]
	s_mov_b32 s6, s19
	v_pk_fma_f32 v[76:77], v[72:73], v[76:77], v[82:83] op_sel:[1,1,0] op_sel_hi:[1,0,1] neg_lo:[0,1,0]
	s_mov_b32 s7, s57
	v_pk_mul_f32 v[82:83], v[98:99], v[76:77] op_sel:[0,0] op_sel_hi:[0,1] neg_hi:[0,1]
	v_pk_fma_f32 v[76:77], v[98:99], v[76:77], v[82:83] op_sel:[1,1,0] op_sel_hi:[1,0,1]
	v_mov_b64_e32 v[82:83], s[6:7]
	v_pk_mul_f32 v[84:85], v[72:73], v[82:83] op_sel:[0,0] op_sel_hi:[0,1]
	s_mov_b32 s6, s21
	v_pk_fma_f32 v[82:83], v[72:73], v[82:83], v[84:85] op_sel:[1,1,0] op_sel_hi:[1,0,1] neg_lo:[0,1,0]
	s_mov_b32 s7, s55
	v_pk_mul_f32 v[84:85], v[80:81], v[82:83] op_sel:[0,0] op_sel_hi:[0,1] neg_hi:[0,1]
	s_nop 0
	v_pk_fma_f32 v[80:81], v[80:81], v[82:83], v[84:85] op_sel:[1,1,0] op_sel_hi:[1,0,1]
	v_mov_b64_e32 v[82:83], s[6:7]
	v_pk_mul_f32 v[84:85], v[72:73], v[82:83] op_sel:[0,0] op_sel_hi:[0,1]
	s_mov_b32 s6, s23
	v_pk_fma_f32 v[82:83], v[72:73], v[82:83], v[84:85] op_sel:[1,1,0] op_sel_hi:[1,0,1] neg_lo:[0,1,0]
	s_mov_b32 s7, s53
	v_pk_mul_f32 v[84:85], v[78:79], v[82:83] op_sel:[0,0] op_sel_hi:[0,1] neg_hi:[0,1]
	v_pk_fma_f32 v[78:79], v[78:79], v[82:83], v[84:85] op_sel:[1,1,0] op_sel_hi:[1,0,1]
	v_mov_b64_e32 v[82:83], s[6:7]
	v_pk_mul_f32 v[84:85], v[72:73], v[82:83] op_sel:[0,0] op_sel_hi:[0,1]
	s_mov_b32 s6, s53
	v_pk_fma_f32 v[82:83], v[72:73], v[82:83], v[84:85] op_sel:[1,1,0] op_sel_hi:[1,0,1] neg_lo:[0,1,0]
	s_mov_b32 s7, s23
	v_pk_mul_f32 v[84:85], v[74:75], v[82:83] op_sel:[0,0] op_sel_hi:[0,1] neg_hi:[0,1]
	v_pk_fma_f32 v[74:75], v[74:75], v[82:83], v[84:85] op_sel:[1,1,0] op_sel_hi:[1,0,1]
	ds_write_b64 v144, v[76:77] offset:17408
	ds_write_b64 v144, v[80:81] offset:19584
	ds_write_b64 v144, v[78:79] offset:21760
	ds_write_b64 v144, v[74:75] offset:23936
	v_mov_b64_e32 v[74:75], s[58:59]
	v_pk_mul_f32 v[76:77], v[72:73], v[74:75] op_sel:[0,0] op_sel_hi:[0,1]
	s_nop 0
	v_pk_fma_f32 v[74:75], v[72:73], v[74:75], v[76:77] op_sel:[1,1,0] op_sel_hi:[1,0,1] neg_lo:[0,1,0]
	v_pk_mul_f32 v[76:77], v[26:27], v[74:75] op_sel:[0,0] op_sel_hi:[0,1] neg_hi:[0,1]
	v_pk_fma_f32 v[26:27], v[26:27], v[74:75], v[76:77] op_sel:[1,1,0] op_sel_hi:[1,0,1]
	v_mov_b64_e32 v[74:75], s[6:7]
	v_pk_mul_f32 v[76:77], v[72:73], v[74:75] op_sel:[0,0] op_sel_hi:[0,1]
	s_mov_b32 s6, s57
	v_pk_fma_f32 v[74:75], v[72:73], v[74:75], v[76:77] op_sel:[1,1,0] op_sel_hi:[1,0,1] neg_lo:[0,1,0]
	s_mov_b32 s7, s19
	v_pk_mul_f32 v[76:77], v[28:29], v[74:75] op_sel:[0,0] op_sel_hi:[0,1] neg_hi:[0,1]
	v_pk_fma_f32 v[28:29], v[28:29], v[74:75], v[76:77] op_sel:[1,1,0] op_sel_hi:[1,0,1]
	v_mov_b64_e32 v[74:75], s[72:73]
	v_pk_mul_f32 v[76:77], v[72:73], v[74:75] op_sel:[0,0] op_sel_hi:[0,1]
	v_pk_fma_f32 v[74:75], v[72:73], v[74:75], v[76:77] op_sel:[1,1,0] op_sel_hi:[1,0,1] neg_lo:[0,1,0]
	v_pk_mul_f32 v[76:77], v[30:31], v[74:75] op_sel:[0,0] op_sel_hi:[0,1] neg_hi:[0,1]
	v_pk_fma_f32 v[30:31], v[30:31], v[74:75], v[76:77] op_sel:[1,1,0] op_sel_hi:[1,0,1]
	v_mov_b64_e32 v[74:75], s[6:7]
	v_pk_mul_f32 v[76:77], v[72:73], v[74:75] op_sel:[0,0] op_sel_hi:[0,1]
	v_pk_fma_f32 v[72:73], v[72:73], v[74:75], v[76:77] op_sel:[1,1,0] op_sel_hi:[1,0,1] neg_lo:[0,1,0]
	v_pk_mul_f32 v[74:75], v[32:33], v[72:73] op_sel:[0,0] op_sel_hi:[0,1] neg_hi:[0,1]
	s_nop 0
	v_pk_fma_f32 v[32:33], v[32:33], v[72:73], v[74:75] op_sel:[1,1,0] op_sel_hi:[1,0,1]

.LBB0_1407:
	s_or_b64 exec, exec, s[0:1]
	v_pk_add_f32 v[44:45], v[42:43], v[60:61]
	v_pk_add_f32 v[42:43], v[42:43], v[60:61] neg_lo:[0,1] neg_hi:[0,1]
	v_pk_add_f32 v[60:61], v[52:53], v[68:69]
	v_pk_add_f32 v[52:53], v[52:53], v[68:69] neg_lo:[0,1] neg_hi:[0,1]
	v_pk_add_f32 v[68:69], v[44:45], v[60:61]
	v_pk_add_f32 v[60:61], v[44:45], v[60:61] neg_lo:[0,1] neg_hi:[0,1]
	s_waitcnt lgkmcnt(1)
	v_pk_add_f32 v[76:77], v[42:43], v[52:53] op_sel:[0,1] op_sel_hi:[1,0] neg_hi:[0,1]
	s_waitcnt lgkmcnt(0)
	v_pk_add_f32 v[78:79], v[42:43], v[52:53] op_sel:[0,1] op_sel_hi:[1,0] neg_lo:[0,1]
	v_pk_add_f32 v[42:43], v[46:47], v[62:63]
	v_pk_add_f32 v[44:45], v[46:47], v[62:63] neg_lo:[0,1] neg_hi:[0,1]
	v_pk_add_f32 v[46:47], v[54:55], v[70:71]
	v_pk_add_f32 v[52:53], v[54:55], v[70:71] neg_lo:[0,1] neg_hi:[0,1]
	v_pk_add_f32 v[54:55], v[42:43], v[46:47]
	v_pk_add_f32 v[46:47], v[42:43], v[46:47] neg_lo:[0,1] neg_hi:[0,1]
	v_pk_add_f32 v[42:43], v[44:45], v[52:53] op_sel:[0,1] op_sel_hi:[1,0] neg_hi:[0,1]
	v_pk_add_f32 v[52:53], v[44:45], v[52:53] op_sel:[0,1] op_sel_hi:[1,0] neg_lo:[0,1]
	v_pk_add_f32 v[44:45], v[48:49], v[64:65]
	v_pk_add_f32 v[48:49], v[48:49], v[64:65] neg_lo:[0,1] neg_hi:[0,1]
	v_pk_add_f32 v[62:63], v[56:57], v[72:73]
	v_pk_add_f32 v[56:57], v[56:57], v[72:73] neg_lo:[0,1] neg_hi:[0,1]
	v_pk_add_f32 v[64:65], v[44:45], v[62:63]
	v_pk_add_f32 v[62:63], v[44:45], v[62:63] neg_lo:[0,1] neg_hi:[0,1]
	v_pk_add_f32 v[70:71], v[48:49], v[56:57] op_sel:[0,1] op_sel_hi:[1,0] neg_hi:[0,1]
	v_pk_add_f32 v[56:57], v[48:49], v[56:57] op_sel:[0,1] op_sel_hi:[1,0] neg_lo:[0,1]
	v_pk_add_f32 v[44:45], v[50:51], v[66:67]
	v_pk_add_f32 v[48:49], v[50:51], v[66:67] neg_lo:[0,1] neg_hi:[0,1]
	v_pk_add_f32 v[50:51], v[58:59], v[74:75]
	v_pk_add_f32 v[58:59], v[58:59], v[74:75] neg_lo:[0,1] neg_hi:[0,1]
	v_pk_add_f32 v[66:67], v[44:45], v[50:51]
	v_pk_add_f32 v[72:73], v[44:45], v[50:51] neg_lo:[0,1] neg_hi:[0,1]
	v_pk_add_f32 v[50:51], v[48:49], v[58:59] op_sel:[0,1] op_sel_hi:[1,0] neg_hi:[0,1]
	v_pk_add_f32 v[58:59], v[48:49], v[58:59] op_sel:[0,1] op_sel_hi:[1,0] neg_lo:[0,1]
	v_mov_b64_e32 v[48:49], s[20:21]
	v_pk_mul_f32 v[44:45], v[42:43], v[48:49] op_sel:[0,0] op_sel_hi:[0,1]
	v_pk_fma_f32 v[74:75], v[42:43], v[48:49], v[44:45] op_sel:[1,1,0] op_sel_hi:[1,0,1] neg_lo:[0,1,0]
	v_mov_b64_e32 v[44:45], s[50:51]
	v_pk_mul_f32 v[42:43], v[70:71], v[44:45] op_sel:[0,0] op_sel_hi:[0,1]
	s_barrier
	v_pk_fma_f32 v[70:71], v[70:71], v[44:45], v[42:43] op_sel:[1,1,0] op_sel_hi:[1,0,1] neg_lo:[0,1,0]
	v_mov_b64_e32 v[42:43], s[54:55]
	v_pk_mul_f32 v[80:81], v[50:51], v[42:43] op_sel:[0,0] op_sel_hi:[0,1]
	v_pk_fma_f32 v[80:81], v[50:51], v[42:43], v[80:81] op_sel:[1,1,0] op_sel_hi:[1,0,1] neg_lo:[0,1,0]
	v_pk_mul_f32 v[50:51], v[46:47], v[44:45] op_sel:[0,0] op_sel_hi:[0,1]
	s_mov_b32 s28, 0
	v_pk_fma_f32 v[82:83], v[46:47], v[44:45], v[50:51] op_sel:[1,1,0] op_sel_hi:[1,0,1] neg_lo:[0,1,0]
	v_mov_b64_e32 v[50:51], s[14:15]
	v_pk_mul_f32 v[46:47], v[62:63], v[50:51] op_sel:[0,0] op_sel_hi:[0,1]
	v_mov_b32_e32 v34, v144
	v_pk_fma_f32 v[62:63], v[62:63], v[50:51], v[46:47] op_sel:[1,1,0] op_sel_hi:[1,0,1] neg_lo:[0,1,0]
	v_mov_b64_e32 v[46:47], s[58:59]
	v_pk_mul_f32 v[84:85], v[72:73], v[46:47] op_sel:[0,0] op_sel_hi:[0,1]
	v_pk_fma_f32 v[72:73], v[72:73], v[46:47], v[84:85] op_sel:[1,1,0] op_sel_hi:[1,0,1] neg_lo:[0,1,0]
	v_pk_mul_f32 v[84:85], v[52:53], v[42:43] op_sel:[0,0] op_sel_hi:[0,1]
	v_pk_fma_f32 v[84:85], v[52:53], v[42:43], v[84:85] op_sel:[1,1,0] op_sel_hi:[1,0,1] neg_lo:[0,1,0]
	v_pk_mul_f32 v[52:53], v[56:57], v[46:47] op_sel:[0,0] op_sel_hi:[0,1]
	v_pk_fma_f32 v[56:57], v[56:57], v[46:47], v[52:53] op_sel:[1,1,0] op_sel_hi:[1,0,1] neg_lo:[0,1,0]
	v_mov_b64_e32 v[52:53], s[60:61]
	v_pk_mul_f32 v[86:87], v[58:59], v[52:53] op_sel:[0,0] op_sel_hi:[0,1]
	v_pk_fma_f32 v[58:59], v[58:59], v[52:53], v[86:87] op_sel:[1,1,0] op_sel_hi:[1,0,1] neg_lo:[0,1,0]
	v_pk_add_f32 v[86:87], v[68:69], v[64:65]
	v_pk_add_f32 v[64:65], v[68:69], v[64:65] neg_lo:[0,1] neg_hi:[0,1]
	v_pk_add_f32 v[68:69], v[54:55], v[66:67]
	v_pk_add_f32 v[54:55], v[54:55], v[66:67] neg_lo:[0,1] neg_hi:[0,1]
	v_pk_add_f32 v[66:67], v[86:87], v[68:69]
	v_pk_add_f32 v[68:69], v[86:87], v[68:69] neg_lo:[0,1] neg_hi:[0,1]
	v_pk_add_f32 v[86:87], v[64:65], v[54:55] op_sel:[0,1] op_sel_hi:[1,0] neg_hi:[0,1]
	v_pk_add_f32 v[54:55], v[64:65], v[54:55] op_sel:[0,1] op_sel_hi:[1,0] neg_lo:[0,1]
	v_pk_add_f32 v[64:65], v[76:77], v[70:71]
	v_pk_add_f32 v[70:71], v[76:77], v[70:71] neg_lo:[0,1] neg_hi:[0,1]
	v_pk_add_f32 v[76:77], v[74:75], v[80:81]
	v_pk_add_f32 v[74:75], v[74:75], v[80:81] neg_lo:[0,1] neg_hi:[0,1]
	v_pk_add_f32 v[80:81], v[64:65], v[76:77]
	v_pk_add_f32 v[64:65], v[64:65], v[76:77] neg_lo:[0,1] neg_hi:[0,1]
	v_pk_add_f32 v[76:77], v[70:71], v[74:75] op_sel:[0,1] op_sel_hi:[1,0] neg_hi:[0,1]
	v_pk_add_f32 v[70:71], v[70:71], v[74:75] op_sel:[0,1] op_sel_hi:[1,0] neg_lo:[0,1]
	v_pk_add_f32 v[74:75], v[60:61], v[62:63]
	v_pk_add_f32 v[60:61], v[60:61], v[62:63] neg_lo:[0,1] neg_hi:[0,1]
	v_pk_add_f32 v[62:63], v[82:83], v[72:73]
	v_pk_add_f32 v[72:73], v[82:83], v[72:73] neg_lo:[0,1] neg_hi:[0,1]
	v_pk_add_f32 v[82:83], v[74:75], v[62:63]
	v_pk_add_f32 v[62:63], v[74:75], v[62:63] neg_lo:[0,1] neg_hi:[0,1]
	v_pk_add_f32 v[74:75], v[60:61], v[72:73] op_sel:[0,1] op_sel_hi:[1,0] neg_hi:[0,1]
	v_pk_add_f32 v[60:61], v[60:61], v[72:73] op_sel:[0,1] op_sel_hi:[1,0] neg_lo:[0,1]
	v_pk_add_f32 v[72:73], v[78:79], v[56:57]
	v_pk_add_f32 v[56:57], v[78:79], v[56:57] neg_lo:[0,1] neg_hi:[0,1]
	v_pk_add_f32 v[78:79], v[84:85], v[58:59]
	v_pk_add_f32 v[58:59], v[84:85], v[58:59] neg_lo:[0,1] neg_hi:[0,1]
	v_pk_add_f32 v[84:85], v[72:73], v[78:79]
	v_pk_add_f32 v[72:73], v[72:73], v[78:79] neg_lo:[0,1] neg_hi:[0,1]
	v_pk_add_f32 v[78:79], v[56:57], v[58:59] op_sel:[0,1] op_sel_hi:[1,0] neg_hi:[0,1]
	v_pk_add_f32 v[56:57], v[56:57], v[58:59] op_sel:[0,1] op_sel_hi:[1,0] neg_lo:[0,1]
	v_mov_b32_e32 v59, v39
	v_mov_b32_e32 v58, v38
	ds_write_b64 v144, v[66:67]
	v_pk_mul_f32 v[66:67], v[80:81], v[58:59] op_sel:[0,0] op_sel_hi:[0,1]
	v_pk_fma_f32 v[66:67], v[80:81], v[58:59], v[66:67] op_sel:[1,1,0] op_sel_hi:[1,0,1] neg_lo:[0,1,0]
	ds_write_b64 v144, v[66:67] offset:2176
	v_pk_mul_f32 v[66:67], v[58:59], v[58:59] op_sel:[0,0] op_sel_hi:[0,1]
	v_pk_fma_f32 v[66:67], v[58:59], v[58:59], v[66:67] op_sel:[1,1,0] op_sel_hi:[1,0,1] neg_lo:[0,1,0]
	v_pk_mul_f32 v[80:81], v[82:83], v[66:67] op_sel:[0,0] op_sel_hi:[0,1]
	v_pk_fma_f32 v[80:81], v[82:83], v[66:67], v[80:81] op_sel:[1,1,0] op_sel_hi:[1,0,1] neg_lo:[0,1,0]
	ds_write_b64 v144, v[80:81] offset:4352
	v_pk_mul_f32 v[80:81], v[66:67], v[58:59] op_sel:[0,0] op_sel_hi:[0,1]
	v_pk_fma_f32 v[66:67], v[66:67], v[58:59], v[80:81] op_sel:[1,1,0] op_sel_hi:[1,0,1] neg_lo:[0,1,0]
	v_pk_mul_f32 v[80:81], v[84:85], v[66:67] op_sel:[0,0] op_sel_hi:[0,1]
	v_pk_fma_f32 v[80:81], v[84:85], v[66:67], v[80:81] op_sel:[1,1,0] op_sel_hi:[1,0,1] neg_lo:[0,1,0]
	ds_write_b64 v144, v[80:81] offset:6528
	v_pk_mul_f32 v[80:81], v[66:67], v[58:59] op_sel:[0,0] op_sel_hi:[0,1]
	v_pk_fma_f32 v[66:67], v[66:67], v[58:59], v[80:81] op_sel:[1,1,0] op_sel_hi:[1,0,1] neg_lo:[0,1,0]
	v_pk_mul_f32 v[80:81], v[86:87], v[66:67] op_sel:[0,0] op_sel_hi:[0,1]
	v_pk_fma_f32 v[80:81], v[86:87], v[66:67], v[80:81] op_sel:[1,1,0] op_sel_hi:[1,0,1] neg_lo:[0,1,0]
	ds_write_b64 v144, v[80:81] offset:8704
	v_pk_mul_f32 v[80:81], v[66:67], v[58:59] op_sel:[0,0] op_sel_hi:[0,1]
	v_pk_fma_f32 v[66:67], v[66:67], v[58:59], v[80:81] op_sel:[1,1,0] op_sel_hi:[1,0,1] neg_lo:[0,1,0]
	v_pk_mul_f32 v[80:81], v[76:77], v[66:67] op_sel:[0,0] op_sel_hi:[0,1]
	v_pk_fma_f32 v[76:77], v[76:77], v[66:67], v[80:81] op_sel:[1,1,0] op_sel_hi:[1,0,1] neg_lo:[0,1,0]
	ds_write_b64 v144, v[76:77] offset:10880
	v_pk_mul_f32 v[76:77], v[66:67], v[58:59] op_sel:[0,0] op_sel_hi:[0,1]
	v_pk_fma_f32 v[66:67], v[66:67], v[58:59], v[76:77] op_sel:[1,1,0] op_sel_hi:[1,0,1] neg_lo:[0,1,0]
	v_pk_mul_f32 v[76:77], v[74:75], v[66:67] op_sel:[0,0] op_sel_hi:[0,1]
	v_pk_fma_f32 v[74:75], v[74:75], v[66:67], v[76:77] op_sel:[1,1,0] op_sel_hi:[1,0,1] neg_lo:[0,1,0]
	ds_write_b64 v144, v[74:75] offset:13056
	v_pk_mul_f32 v[74:75], v[66:67], v[58:59] op_sel:[0,0] op_sel_hi:[0,1]
	v_pk_fma_f32 v[66:67], v[66:67], v[58:59], v[74:75] op_sel:[1,1,0] op_sel_hi:[1,0,1] neg_lo:[0,1,0]
	v_pk_mul_f32 v[74:75], v[78:79], v[66:67] op_sel:[0,0] op_sel_hi:[0,1]
	v_pk_fma_f32 v[74:75], v[78:79], v[66:67], v[74:75] op_sel:[1,1,0] op_sel_hi:[1,0,1] neg_lo:[0,1,0]
	ds_write_b64 v144, v[74:75] offset:15232
	v_pk_mul_f32 v[74:75], v[66:67], v[58:59] op_sel:[0,0] op_sel_hi:[0,1]
	v_pk_fma_f32 v[66:67], v[66:67], v[58:59], v[74:75] op_sel:[1,1,0] op_sel_hi:[1,0,1] neg_lo:[0,1,0]
	v_pk_mul_f32 v[74:75], v[68:69], v[66:67] op_sel:[0,0] op_sel_hi:[0,1]
	v_pk_fma_f32 v[68:69], v[68:69], v[66:67], v[74:75] op_sel:[1,1,0] op_sel_hi:[1,0,1] neg_lo:[0,1,0]
	ds_write_b64 v144, v[68:69] offset:17408
	v_pk_mul_f32 v[68:69], v[66:67], v[58:59] op_sel:[0,0] op_sel_hi:[0,1]
	v_pk_fma_f32 v[66:67], v[66:67], v[58:59], v[68:69] op_sel:[1,1,0] op_sel_hi:[1,0,1] neg_lo:[0,1,0]
	v_pk_mul_f32 v[68:69], v[64:65], v[66:67] op_sel:[0,0] op_sel_hi:[0,1]
	v_pk_fma_f32 v[64:65], v[64:65], v[66:67], v[68:69] op_sel:[1,1,0] op_sel_hi:[1,0,1] neg_lo:[0,1,0]
	ds_write_b64 v144, v[64:65] offset:19584
	v_pk_mul_f32 v[64:65], v[66:67], v[58:59] op_sel:[0,0] op_sel_hi:[0,1]
	v_pk_fma_f32 v[64:65], v[66:67], v[58:59], v[64:65] op_sel:[1,1,0] op_sel_hi:[1,0,1] neg_lo:[0,1,0]
	v_pk_mul_f32 v[66:67], v[62:63], v[64:65] op_sel:[0,0] op_sel_hi:[0,1]
	v_pk_fma_f32 v[62:63], v[62:63], v[64:65], v[66:67] op_sel:[1,1,0] op_sel_hi:[1,0,1] neg_lo:[0,1,0]
	ds_write_b64 v144, v[62:63] offset:21760
	v_pk_mul_f32 v[62:63], v[64:65], v[58:59] op_sel:[0,0] op_sel_hi:[0,1]
	v_pk_fma_f32 v[62:63], v[64:65], v[58:59], v[62:63] op_sel:[1,1,0] op_sel_hi:[1,0,1] neg_lo:[0,1,0]
	v_pk_mul_f32 v[64:65], v[72:73], v[62:63] op_sel:[0,0] op_sel_hi:[0,1]
	v_pk_fma_f32 v[64:65], v[72:73], v[62:63], v[64:65] op_sel:[1,1,0] op_sel_hi:[1,0,1] neg_lo:[0,1,0]
	ds_write_b64 v144, v[64:65] offset:23936
	v_pk_mul_f32 v[64:65], v[62:63], v[58:59] op_sel:[0,0] op_sel_hi:[0,1]
	v_pk_fma_f32 v[62:63], v[62:63], v[58:59], v[64:65] op_sel:[1,1,0] op_sel_hi:[1,0,1] neg_lo:[0,1,0]
	v_pk_mul_f32 v[64:65], v[54:55], v[62:63] op_sel:[0,0] op_sel_hi:[0,1]
	v_pk_fma_f32 v[54:55], v[54:55], v[62:63], v[64:65] op_sel:[1,1,0] op_sel_hi:[1,0,1] neg_lo:[0,1,0]
	ds_write_b64 v144, v[54:55] offset:26112
	v_pk_mul_f32 v[54:55], v[62:63], v[58:59] op_sel:[0,0] op_sel_hi:[0,1]
	v_pk_fma_f32 v[54:55], v[62:63], v[58:59], v[54:55] op_sel:[1,1,0] op_sel_hi:[1,0,1] neg_lo:[0,1,0]
	v_pk_mul_f32 v[62:63], v[70:71], v[54:55] op_sel:[0,0] op_sel_hi:[0,1]
	v_pk_fma_f32 v[62:63], v[70:71], v[54:55], v[62:63] op_sel:[1,1,0] op_sel_hi:[1,0,1] neg_lo:[0,1,0]
	ds_write_b64 v144, v[62:63] offset:28288
	v_pk_mul_f32 v[62:63], v[54:55], v[58:59] op_sel:[0,0] op_sel_hi:[0,1]
	v_pk_fma_f32 v[54:55], v[54:55], v[58:59], v[62:63] op_sel:[1,1,0] op_sel_hi:[1,0,1] neg_lo:[0,1,0]
	v_pk_mul_f32 v[62:63], v[60:61], v[54:55] op_sel:[0,0] op_sel_hi:[0,1]
	v_pk_fma_f32 v[60:61], v[60:61], v[54:55], v[62:63] op_sel:[1,1,0] op_sel_hi:[1,0,1] neg_lo:[0,1,0]
	ds_write_b64 v144, v[60:61] offset:30464
	v_pk_mul_f32 v[60:61], v[54:55], v[58:59] op_sel:[0,0] op_sel_hi:[0,1]
	v_pk_fma_f32 v[54:55], v[54:55], v[58:59], v[60:61] op_sel:[1,1,0] op_sel_hi:[1,0,1] neg_lo:[0,1,0]
	v_pk_mul_f32 v[58:59], v[56:57], v[54:55] op_sel:[0,0] op_sel_hi:[0,1]
	v_pk_fma_f32 v[54:55], v[56:57], v[54:55], v[58:59] op_sel:[1,1,0] op_sel_hi:[1,0,1] neg_lo:[0,1,0]
	ds_write_b64 v144, v[54:55] offset:32640
	s_waitcnt lgkmcnt(0)
	s_barrier
	ds_read2_b64 v[54:57], v146 offset1:17
	ds_read2_b64 v[58:61], v146 offset0:34 offset1:51
	ds_read2_b64 v[62:65], v146 offset0:68 offset1:85
	ds_read2_b64 v[66:69], v146 offset0:136 offset1:153
	ds_read2_b64 v[70:73], v146 offset0:102 offset1:119
	ds_read2_b64 v[74:77], v146 offset0:204 offset1:221
	ds_read2_b64 v[78:81], v146 offset0:170 offset1:187
	ds_read2_b64 v[82:85], v146 offset0:238 offset1:255
	s_waitcnt lgkmcnt(4)
	v_pk_add_f32 v[86:87], v[54:55], v[66:67]
	v_pk_add_f32 v[54:55], v[54:55], v[66:67] neg_lo:[0,1] neg_hi:[0,1]
	s_waitcnt lgkmcnt(2)
	v_pk_add_f32 v[66:67], v[62:63], v[74:75]
	v_pk_add_f32 v[62:63], v[62:63], v[74:75] neg_lo:[0,1] neg_hi:[0,1]
	v_pk_add_f32 v[74:75], v[86:87], v[66:67]
	v_pk_add_f32 v[66:67], v[86:87], v[66:67] neg_lo:[0,1] neg_hi:[0,1]
	v_pk_add_f32 v[86:87], v[54:55], v[62:63] op_sel:[0,1] op_sel_hi:[1,0] neg_hi:[0,1]
	v_pk_add_f32 v[54:55], v[54:55], v[62:63] op_sel:[0,1] op_sel_hi:[1,0] neg_lo:[0,1]
	v_pk_add_f32 v[62:63], v[56:57], v[68:69]
	v_pk_add_f32 v[56:57], v[56:57], v[68:69] neg_lo:[0,1] neg_hi:[0,1]
	v_pk_add_f32 v[68:69], v[64:65], v[76:77]
	v_pk_add_f32 v[64:65], v[64:65], v[76:77] neg_lo:[0,1] neg_hi:[0,1]
	v_pk_add_f32 v[76:77], v[62:63], v[68:69]
	v_pk_add_f32 v[62:63], v[62:63], v[68:69] neg_lo:[0,1] neg_hi:[0,1]
	v_pk_add_f32 v[68:69], v[56:57], v[64:65] op_sel:[0,1] op_sel_hi:[1,0] neg_hi:[0,1]
	v_pk_add_f32 v[56:57], v[56:57], v[64:65] op_sel:[0,1] op_sel_hi:[1,0] neg_lo:[0,1]
	s_waitcnt lgkmcnt(1)
	v_pk_add_f32 v[64:65], v[58:59], v[78:79]
	v_pk_add_f32 v[58:59], v[58:59], v[78:79] neg_lo:[0,1] neg_hi:[0,1]
	s_waitcnt lgkmcnt(0)
	v_pk_add_f32 v[78:79], v[70:71], v[82:83]
	v_pk_add_f32 v[70:71], v[70:71], v[82:83] neg_lo:[0,1] neg_hi:[0,1]
	v_pk_add_f32 v[82:83], v[64:65], v[78:79]
	v_pk_add_f32 v[64:65], v[64:65], v[78:79] neg_lo:[0,1] neg_hi:[0,1]
	v_pk_add_f32 v[78:79], v[58:59], v[70:71] op_sel:[0,1] op_sel_hi:[1,0] neg_hi:[0,1]
	v_pk_add_f32 v[58:59], v[58:59], v[70:71] op_sel:[0,1] op_sel_hi:[1,0] neg_lo:[0,1]
	v_pk_add_f32 v[70:71], v[60:61], v[80:81]
	v_pk_add_f32 v[60:61], v[60:61], v[80:81] neg_lo:[0,1] neg_hi:[0,1]
	v_pk_add_f32 v[80:81], v[72:73], v[84:85]
	v_pk_add_f32 v[72:73], v[72:73], v[84:85] neg_lo:[0,1] neg_hi:[0,1]
	v_pk_add_f32 v[84:85], v[70:71], v[80:81]
	v_pk_add_f32 v[70:71], v[70:71], v[80:81] neg_lo:[0,1] neg_hi:[0,1]
	v_pk_add_f32 v[80:81], v[60:61], v[72:73] op_sel:[0,1] op_sel_hi:[1,0] neg_hi:[0,1]
	v_pk_add_f32 v[60:61], v[60:61], v[72:73] op_sel:[0,1] op_sel_hi:[1,0] neg_lo:[0,1]
	v_pk_mul_f32 v[72:73], v[68:69], v[48:49] op_sel:[0,0] op_sel_hi:[0,1]
	v_pk_fma_f32 v[68:69], v[68:69], v[48:49], v[72:73] op_sel:[1,1,0] op_sel_hi:[1,0,1] neg_lo:[0,1,0]
	v_pk_mul_f32 v[72:73], v[78:79], v[44:45] op_sel:[0,0] op_sel_hi:[0,1]
	v_pk_fma_f32 v[72:73], v[78:79], v[44:45], v[72:73] op_sel:[1,1,0] op_sel_hi:[1,0,1] neg_lo:[0,1,0]
	v_pk_mul_f32 v[78:79], v[80:81], v[42:43] op_sel:[0,0] op_sel_hi:[0,1]
	v_pk_fma_f32 v[78:79], v[80:81], v[42:43], v[78:79] op_sel:[1,1,0] op_sel_hi:[1,0,1] neg_lo:[0,1,0]
	v_pk_mul_f32 v[80:81], v[62:63], v[44:45] op_sel:[0,0] op_sel_hi:[0,1]
	v_pk_fma_f32 v[62:63], v[62:63], v[44:45], v[80:81] op_sel:[1,1,0] op_sel_hi:[1,0,1] neg_lo:[0,1,0]
	v_pk_mul_f32 v[80:81], v[64:65], v[50:51] op_sel:[0,0] op_sel_hi:[0,1]
	v_pk_fma_f32 v[64:65], v[64:65], v[50:51], v[80:81] op_sel:[1,1,0] op_sel_hi:[1,0,1] neg_lo:[0,1,0]
	v_pk_mul_f32 v[80:81], v[70:71], v[46:47] op_sel:[0,0] op_sel_hi:[0,1]
	v_pk_fma_f32 v[70:71], v[70:71], v[46:47], v[80:81] op_sel:[1,1,0] op_sel_hi:[1,0,1] neg_lo:[0,1,0]
	v_pk_mul_f32 v[80:81], v[56:57], v[42:43] op_sel:[0,0] op_sel_hi:[0,1]
	v_pk_fma_f32 v[56:57], v[56:57], v[42:43], v[80:81] op_sel:[1,1,0] op_sel_hi:[1,0,1] neg_lo:[0,1,0]
	v_pk_mul_f32 v[80:81], v[58:59], v[46:47] op_sel:[0,0] op_sel_hi:[0,1]
	v_pk_fma_f32 v[58:59], v[58:59], v[46:47], v[80:81] op_sel:[1,1,0] op_sel_hi:[1,0,1] neg_lo:[0,1,0]
	v_pk_mul_f32 v[80:81], v[60:61], v[52:53] op_sel:[0,0] op_sel_hi:[0,1]
	v_pk_fma_f32 v[60:61], v[60:61], v[52:53], v[80:81] op_sel:[1,1,0] op_sel_hi:[1,0,1] neg_lo:[0,1,0]
	v_pk_add_f32 v[80:81], v[74:75], v[82:83]
	v_pk_add_f32 v[74:75], v[74:75], v[82:83] neg_lo:[0,1] neg_hi:[0,1]
	v_pk_add_f32 v[82:83], v[76:77], v[84:85]
	v_pk_add_f32 v[76:77], v[76:77], v[84:85] neg_lo:[0,1] neg_hi:[0,1]
	v_pk_add_f32 v[84:85], v[80:81], v[82:83]
	v_pk_add_f32 v[80:81], v[80:81], v[82:83] neg_lo:[0,1] neg_hi:[0,1]
	v_pk_add_f32 v[82:83], v[74:75], v[76:77] op_sel:[0,1] op_sel_hi:[1,0] neg_hi:[0,1]
	v_pk_add_f32 v[74:75], v[74:75], v[76:77] op_sel:[0,1] op_sel_hi:[1,0] neg_lo:[0,1]
	v_pk_add_f32 v[76:77], v[86:87], v[72:73]
	v_pk_add_f32 v[72:73], v[86:87], v[72:73] neg_lo:[0,1] neg_hi:[0,1]
	v_pk_add_f32 v[86:87], v[68:69], v[78:79]
	v_pk_add_f32 v[68:69], v[68:69], v[78:79] neg_lo:[0,1] neg_hi:[0,1]
	v_pk_add_f32 v[78:79], v[76:77], v[86:87]
	v_pk_add_f32 v[76:77], v[76:77], v[86:87] neg_lo:[0,1] neg_hi:[0,1]
	v_pk_add_f32 v[86:87], v[72:73], v[68:69] op_sel:[0,1] op_sel_hi:[1,0] neg_hi:[0,1]
	v_pk_add_f32 v[68:69], v[72:73], v[68:69] op_sel:[0,1] op_sel_hi:[1,0] neg_lo:[0,1]
	v_pk_add_f32 v[72:73], v[66:67], v[64:65]
	v_pk_add_f32 v[64:65], v[66:67], v[64:65] neg_lo:[0,1] neg_hi:[0,1]
	v_pk_add_f32 v[66:67], v[62:63], v[70:71]
	v_pk_add_f32 v[62:63], v[62:63], v[70:71] neg_lo:[0,1] neg_hi:[0,1]
	v_pk_add_f32 v[70:71], v[72:73], v[66:67]
	v_pk_add_f32 v[66:67], v[72:73], v[66:67] neg_lo:[0,1] neg_hi:[0,1]
	v_pk_add_f32 v[72:73], v[64:65], v[62:63] op_sel:[0,1] op_sel_hi:[1,0] neg_hi:[0,1]
	v_pk_add_f32 v[62:63], v[64:65], v[62:63] op_sel:[0,1] op_sel_hi:[1,0] neg_lo:[0,1]
	v_pk_add_f32 v[64:65], v[54:55], v[58:59]
	v_pk_add_f32 v[54:55], v[54:55], v[58:59] neg_lo:[0,1] neg_hi:[0,1]
	v_pk_add_f32 v[58:59], v[56:57], v[60:61]
	v_pk_add_f32 v[56:57], v[56:57], v[60:61] neg_lo:[0,1] neg_hi:[0,1]
	v_pk_add_f32 v[60:61], v[64:65], v[58:59]
	v_pk_add_f32 v[58:59], v[64:65], v[58:59] neg_lo:[0,1] neg_hi:[0,1]
	v_pk_add_f32 v[64:65], v[54:55], v[56:57] op_sel:[0,1] op_sel_hi:[1,0] neg_hi:[0,1]
	v_pk_add_f32 v[54:55], v[54:55], v[56:57] op_sel:[0,1] op_sel_hi:[1,0] neg_lo:[0,1]
	v_mov_b32_e32 v57, v41
	v_mov_b32_e32 v56, v40
	s_nop 0
	v_pk_mul_f32 v[88:89], v[78:79], v[56:57] op_sel:[0,0] op_sel_hi:[0,1]
	v_pk_fma_f32 v[78:79], v[78:79], v[56:57], v[88:89] op_sel:[1,1,0] op_sel_hi:[1,0,1] neg_lo:[0,1,0]
	ds_write2_b64 v146, v[84:85], v[78:79] offset1:17
	v_pk_mul_f32 v[78:79], v[56:57], v[56:57] op_sel:[0,0] op_sel_hi:[0,1]
	v_pk_fma_f32 v[78:79], v[56:57], v[56:57], v[78:79] op_sel:[1,1,0] op_sel_hi:[1,0,1] neg_lo:[0,1,0]
	v_pk_mul_f32 v[84:85], v[70:71], v[78:79] op_sel:[0,0] op_sel_hi:[0,1]
	v_pk_fma_f32 v[70:71], v[70:71], v[78:79], v[84:85] op_sel:[1,1,0] op_sel_hi:[1,0,1] neg_lo:[0,1,0]
	v_pk_mul_f32 v[84:85], v[78:79], v[56:57] op_sel:[0,0] op_sel_hi:[0,1]
	v_pk_fma_f32 v[78:79], v[78:79], v[56:57], v[84:85] op_sel:[1,1,0] op_sel_hi:[1,0,1] neg_lo:[0,1,0]
	v_pk_mul_f32 v[84:85], v[60:61], v[78:79] op_sel:[0,0] op_sel_hi:[0,1]
	v_pk_fma_f32 v[60:61], v[60:61], v[78:79], v[84:85] op_sel:[1,1,0] op_sel_hi:[1,0,1] neg_lo:[0,1,0]
	ds_write2_b64 v146, v[70:71], v[60:61] offset0:34 offset1:51
	v_pk_mul_f32 v[60:61], v[78:79], v[56:57] op_sel:[0,0] op_sel_hi:[0,1]
	v_pk_fma_f32 v[60:61], v[78:79], v[56:57], v[60:61] op_sel:[1,1,0] op_sel_hi:[1,0,1] neg_lo:[0,1,0]
	v_pk_mul_f32 v[70:71], v[82:83], v[60:61] op_sel:[0,0] op_sel_hi:[0,1]
	v_pk_mul_f32 v[78:79], v[60:61], v[56:57] op_sel:[0,0] op_sel_hi:[0,1]
	v_pk_fma_f32 v[70:71], v[82:83], v[60:61], v[70:71] op_sel:[1,1,0] op_sel_hi:[1,0,1] neg_lo:[0,1,0]
	v_pk_fma_f32 v[60:61], v[60:61], v[56:57], v[78:79] op_sel:[1,1,0] op_sel_hi:[1,0,1] neg_lo:[0,1,0]
	v_pk_mul_f32 v[78:79], v[86:87], v[60:61] op_sel:[0,0] op_sel_hi:[0,1]
	v_pk_fma_f32 v[78:79], v[86:87], v[60:61], v[78:79] op_sel:[1,1,0] op_sel_hi:[1,0,1] neg_lo:[0,1,0]
	ds_write2_b64 v146, v[70:71], v[78:79] offset0:68 offset1:85
	v_pk_mul_f32 v[70:71], v[60:61], v[56:57] op_sel:[0,0] op_sel_hi:[0,1]
	v_pk_fma_f32 v[60:61], v[60:61], v[56:57], v[70:71] op_sel:[1,1,0] op_sel_hi:[1,0,1] neg_lo:[0,1,0]
	v_pk_mul_f32 v[70:71], v[72:73], v[60:61] op_sel:[0,0] op_sel_hi:[0,1]
	v_pk_fma_f32 v[70:71], v[72:73], v[60:61], v[70:71] op_sel:[1,1,0] op_sel_hi:[1,0,1] neg_lo:[0,1,0]
	v_pk_mul_f32 v[72:73], v[60:61], v[56:57] op_sel:[0,0] op_sel_hi:[0,1]
	v_pk_fma_f32 v[60:61], v[60:61], v[56:57], v[72:73] op_sel:[1,1,0] op_sel_hi:[1,0,1] neg_lo:[0,1,0]
	v_pk_mul_f32 v[72:73], v[64:65], v[60:61] op_sel:[0,0] op_sel_hi:[0,1]
	v_pk_fma_f32 v[64:65], v[64:65], v[60:61], v[72:73] op_sel:[1,1,0] op_sel_hi:[1,0,1] neg_lo:[0,1,0]
	ds_write2_b64 v146, v[70:71], v[64:65] offset0:102 offset1:119
	v_pk_mul_f32 v[64:65], v[60:61], v[56:57] op_sel:[0,0] op_sel_hi:[0,1]
	v_pk_fma_f32 v[60:61], v[60:61], v[56:57], v[64:65] op_sel:[1,1,0] op_sel_hi:[1,0,1] neg_lo:[0,1,0]
	v_pk_mul_f32 v[64:65], v[80:81], v[60:61] op_sel:[0,0] op_sel_hi:[0,1]
	v_pk_mul_f32 v[70:71], v[60:61], v[56:57] op_sel:[0,0] op_sel_hi:[0,1]
	v_pk_fma_f32 v[64:65], v[80:81], v[60:61], v[64:65] op_sel:[1,1,0] op_sel_hi:[1,0,1] neg_lo:[0,1,0]
	v_pk_fma_f32 v[60:61], v[60:61], v[56:57], v[70:71] op_sel:[1,1,0] op_sel_hi:[1,0,1] neg_lo:[0,1,0]
	v_pk_mul_f32 v[70:71], v[76:77], v[60:61] op_sel:[0,0] op_sel_hi:[0,1]
	v_pk_fma_f32 v[70:71], v[76:77], v[60:61], v[70:71] op_sel:[1,1,0] op_sel_hi:[1,0,1] neg_lo:[0,1,0]
	ds_write2_b64 v146, v[64:65], v[70:71] offset0:136 offset1:153
	v_pk_mul_f32 v[64:65], v[60:61], v[56:57] op_sel:[0,0] op_sel_hi:[0,1]
	v_pk_fma_f32 v[60:61], v[60:61], v[56:57], v[64:65] op_sel:[1,1,0] op_sel_hi:[1,0,1] neg_lo:[0,1,0]
	v_pk_mul_f32 v[64:65], v[66:67], v[60:61] op_sel:[0,0] op_sel_hi:[0,1]
	v_pk_fma_f32 v[64:65], v[66:67], v[60:61], v[64:65] op_sel:[1,1,0] op_sel_hi:[1,0,1] neg_lo:[0,1,0]
	v_pk_mul_f32 v[66:67], v[60:61], v[56:57] op_sel:[0,0] op_sel_hi:[0,1]
	v_pk_fma_f32 v[60:61], v[60:61], v[56:57], v[66:67] op_sel:[1,1,0] op_sel_hi:[1,0,1] neg_lo:[0,1,0]
	v_pk_mul_f32 v[66:67], v[58:59], v[60:61] op_sel:[0,0] op_sel_hi:[0,1]
	v_pk_fma_f32 v[58:59], v[58:59], v[60:61], v[66:67] op_sel:[1,1,0] op_sel_hi:[1,0,1] neg_lo:[0,1,0]
	ds_write2_b64 v146, v[64:65], v[58:59] offset0:170 offset1:187
	v_pk_mul_f32 v[58:59], v[60:61], v[56:57] op_sel:[0,0] op_sel_hi:[0,1]
	v_pk_fma_f32 v[58:59], v[60:61], v[56:57], v[58:59] op_sel:[1,1,0] op_sel_hi:[1,0,1] neg_lo:[0,1,0]
	v_pk_mul_f32 v[60:61], v[74:75], v[58:59] op_sel:[0,0] op_sel_hi:[0,1]
	v_pk_mul_f32 v[64:65], v[58:59], v[56:57] op_sel:[0,0] op_sel_hi:[0,1]
	v_pk_fma_f32 v[60:61], v[74:75], v[58:59], v[60:61] op_sel:[1,1,0] op_sel_hi:[1,0,1] neg_lo:[0,1,0]
	v_pk_fma_f32 v[58:59], v[58:59], v[56:57], v[64:65] op_sel:[1,1,0] op_sel_hi:[1,0,1] neg_lo:[0,1,0]
	v_pk_mul_f32 v[64:65], v[68:69], v[58:59] op_sel:[0,0] op_sel_hi:[0,1]
	v_pk_fma_f32 v[64:65], v[68:69], v[58:59], v[64:65] op_sel:[1,1,0] op_sel_hi:[1,0,1] neg_lo:[0,1,0]
	ds_write2_b64 v146, v[60:61], v[64:65] offset0:204 offset1:221
	v_pk_mul_f32 v[60:61], v[58:59], v[56:57] op_sel:[0,0] op_sel_hi:[0,1]
	v_pk_fma_f32 v[58:59], v[58:59], v[56:57], v[60:61] op_sel:[1,1,0] op_sel_hi:[1,0,1] neg_lo:[0,1,0]
	v_pk_mul_f32 v[60:61], v[62:63], v[58:59] op_sel:[0,0] op_sel_hi:[0,1]
	v_pk_fma_f32 v[60:61], v[62:63], v[58:59], v[60:61] op_sel:[1,1,0] op_sel_hi:[1,0,1] neg_lo:[0,1,0]
	v_pk_mul_f32 v[62:63], v[58:59], v[56:57] op_sel:[0,0] op_sel_hi:[0,1]
	v_pk_fma_f32 v[56:57], v[58:59], v[56:57], v[62:63] op_sel:[1,1,0] op_sel_hi:[1,0,1] neg_lo:[0,1,0]
	v_pk_mul_f32 v[58:59], v[54:55], v[56:57] op_sel:[0,0] op_sel_hi:[0,1]
	v_pk_fma_f32 v[54:55], v[54:55], v[56:57], v[58:59] op_sel:[1,1,0] op_sel_hi:[1,0,1] neg_lo:[0,1,0]
	ds_write2_b64 v146, v[60:61], v[54:55] offset0:238 offset1:255
	s_waitcnt lgkmcnt(0)
	s_barrier
	ds_read2_b64 v[60:63], v147 offset1:1
	ds_read2_b64 v[64:67], v147 offset0:2 offset1:3
	ds_read2_b64 v[68:71], v147 offset0:8 offset1:9
	ds_read2_b64 v[72:75], v147 offset0:4 offset1:5
	ds_read2_b64 v[76:79], v147 offset0:6 offset1:7
	ds_read2_b64 v[80:83], v147 offset0:12 offset1:13
	ds_read2_b64 v[84:87], v147 offset0:10 offset1:11
	ds_read2_b64 v[88:91], v147 offset0:14 offset1:15
	s_waitcnt lgkmcnt(5)
	v_pk_add_f32 v[54:55], v[60:61], v[68:69]
	v_pk_add_f32 v[68:69], v[60:61], v[68:69] neg_lo:[0,1] neg_hi:[0,1]
	s_waitcnt lgkmcnt(2)
	v_pk_add_f32 v[56:57], v[72:73], v[80:81]
	v_pk_add_f32 v[72:73], v[72:73], v[80:81] neg_lo:[0,1] neg_hi:[0,1]
	v_pk_add_f32 v[60:61], v[54:55], v[56:57]
	v_pk_add_f32 v[56:57], v[54:55], v[56:57] neg_lo:[0,1] neg_hi:[0,1]
	v_pk_add_f32 v[58:59], v[68:69], v[72:73] op_sel:[0,1] op_sel_hi:[1,0] neg_hi:[0,1]
	v_pk_add_f32 v[54:55], v[68:69], v[72:73] op_sel:[0,1] op_sel_hi:[1,0] neg_lo:[0,1]
	v_pk_add_f32 v[68:69], v[62:63], v[70:71]
	v_pk_add_f32 v[70:71], v[62:63], v[70:71] neg_lo:[0,1] neg_hi:[0,1]
	v_pk_add_f32 v[72:73], v[74:75], v[82:83]
	v_pk_add_f32 v[74:75], v[74:75], v[82:83] neg_lo:[0,1] neg_hi:[0,1]
	v_pk_add_f32 v[62:63], v[68:69], v[72:73]
	v_pk_add_f32 v[68:69], v[68:69], v[72:73] neg_lo:[0,1] neg_hi:[0,1]
	v_pk_add_f32 v[72:73], v[70:71], v[74:75] op_sel:[0,1] op_sel_hi:[1,0] neg_hi:[0,1]
	v_pk_add_f32 v[70:71], v[70:71], v[74:75] op_sel:[0,1] op_sel_hi:[1,0] neg_lo:[0,1]
	s_waitcnt lgkmcnt(1)
	v_pk_add_f32 v[74:75], v[64:65], v[84:85]
	v_pk_add_f32 v[80:81], v[64:65], v[84:85] neg_lo:[0,1] neg_hi:[0,1]
	s_waitcnt lgkmcnt(0)
	v_pk_add_f32 v[82:83], v[76:77], v[88:89]
	v_pk_add_f32 v[76:77], v[76:77], v[88:89] neg_lo:[0,1] neg_hi:[0,1]
	v_pk_add_f32 v[64:65], v[74:75], v[82:83]
	v_pk_add_f32 v[74:75], v[74:75], v[82:83] neg_lo:[0,1] neg_hi:[0,1]
	v_pk_add_f32 v[82:83], v[80:81], v[76:77] op_sel:[0,1] op_sel_hi:[1,0] neg_hi:[0,1]
	v_pk_add_f32 v[76:77], v[80:81], v[76:77] op_sel:[0,1] op_sel_hi:[1,0] neg_lo:[0,1]
	v_pk_add_f32 v[80:81], v[66:67], v[86:87]
	v_pk_add_f32 v[84:85], v[66:67], v[86:87] neg_lo:[0,1] neg_hi:[0,1]
	v_pk_add_f32 v[86:87], v[78:79], v[90:91]
	v_pk_add_f32 v[78:79], v[78:79], v[90:91] neg_lo:[0,1] neg_hi:[0,1]
	v_pk_add_f32 v[66:67], v[80:81], v[86:87]
	v_pk_add_f32 v[86:87], v[80:81], v[86:87] neg_lo:[0,1] neg_hi:[0,1]
	v_pk_add_f32 v[80:81], v[84:85], v[78:79] op_sel:[0,1] op_sel_hi:[1,0] neg_hi:[0,1]
	v_pk_add_f32 v[90:91], v[84:85], v[78:79] op_sel:[0,1] op_sel_hi:[1,0] neg_lo:[0,1]
	v_pk_mul_f32 v[78:79], v[72:73], v[48:49] op_sel:[0,0] op_sel_hi:[0,1]
	v_pk_fma_f32 v[48:49], v[72:73], v[48:49], v[78:79] op_sel:[1,1,0] op_sel_hi:[1,0,1] neg_lo:[0,1,0]
	v_pk_mul_f32 v[72:73], v[82:83], v[44:45] op_sel:[0,0] op_sel_hi:[0,1]
	s_barrier
	v_pk_fma_f32 v[78:79], v[82:83], v[44:45], v[72:73] op_sel:[1,1,0] op_sel_hi:[1,0,1] neg_lo:[0,1,0]
	v_pk_mul_f32 v[72:73], v[80:81], v[42:43] op_sel:[0,0] op_sel_hi:[0,1]
	v_pk_fma_f32 v[80:81], v[80:81], v[42:43], v[72:73] op_sel:[1,1,0] op_sel_hi:[1,0,1] neg_lo:[0,1,0]
	v_pk_mul_f32 v[72:73], v[68:69], v[44:45] op_sel:[0,0] op_sel_hi:[0,1]
	v_pk_fma_f32 v[44:45], v[68:69], v[44:45], v[72:73] op_sel:[1,1,0] op_sel_hi:[1,0,1] neg_lo:[0,1,0]
	v_pk_mul_f32 v[68:69], v[74:75], v[50:51] op_sel:[0,0] op_sel_hi:[0,1]
	v_pk_fma_f32 v[84:85], v[74:75], v[50:51], v[68:69] op_sel:[1,1,0] op_sel_hi:[1,0,1] neg_lo:[0,1,0]
	v_pk_mul_f32 v[50:51], v[86:87], v[46:47] op_sel:[0,0] op_sel_hi:[0,1]
	v_pk_add_f32 v[68:69], v[58:59], v[78:79] neg_lo:[0,1] neg_hi:[0,1]
	v_pk_fma_f32 v[88:89], v[86:87], v[46:47], v[50:51] op_sel:[1,1,0] op_sel_hi:[1,0,1] neg_lo:[0,1,0]
	v_pk_mul_f32 v[50:51], v[70:71], v[42:43] op_sel:[0,0] op_sel_hi:[0,1]
	v_pk_add_f32 v[72:73], v[56:57], v[84:85] neg_lo:[0,1] neg_hi:[0,1]
	v_pk_fma_f32 v[82:83], v[70:71], v[42:43], v[50:51] op_sel:[1,1,0] op_sel_hi:[1,0,1] neg_lo:[0,1,0]
	v_pk_mul_f32 v[42:43], v[76:77], v[46:47] op_sel:[0,0] op_sel_hi:[0,1]
	v_pk_add_f32 v[50:51], v[62:63], v[66:67] neg_lo:[0,1] neg_hi:[0,1]
	v_pk_fma_f32 v[86:87], v[76:77], v[46:47], v[42:43] op_sel:[1,1,0] op_sel_hi:[1,0,1] neg_lo:[0,1,0]
	v_pk_mul_f32 v[42:43], v[90:91], v[52:53] op_sel:[0,0] op_sel_hi:[0,1]
	v_pk_add_f32 v[46:47], v[60:61], v[64:65] neg_lo:[0,1] neg_hi:[0,1]
	v_pk_fma_f32 v[52:53], v[90:91], v[52:53], v[42:43] op_sel:[1,1,0] op_sel_hi:[1,0,1] neg_lo:[0,1,0]
	v_pk_add_f32 v[70:71], v[48:49], v[80:81] neg_lo:[0,1] neg_hi:[0,1]
	v_pk_add_f32 v[74:75], v[44:45], v[88:89] neg_lo:[0,1] neg_hi:[0,1]
	v_pk_add_f32 v[76:77], v[54:55], v[86:87] neg_lo:[0,1] neg_hi:[0,1]
	v_pk_add_f32 v[90:91], v[82:83], v[52:53] neg_lo:[0,1] neg_hi:[0,1]
	v_pk_add_f32 v[42:43], v[46:47], v[50:51] op_sel:[0,1] op_sel_hi:[1,0] neg_hi:[0,1]
	v_pk_add_f32 v[46:47], v[46:47], v[50:51] op_sel:[0,1] op_sel_hi:[1,0] neg_lo:[0,1]
	v_pk_add_f32 v[50:51], v[68:69], v[70:71] op_sel:[0,1] op_sel_hi:[1,0] neg_hi:[0,1]
	v_pk_add_f32 v[68:69], v[68:69], v[70:71] op_sel:[0,1] op_sel_hi:[1,0] neg_lo:[0,1]
	v_pk_add_f32 v[70:71], v[72:73], v[74:75] op_sel:[0,1] op_sel_hi:[1,0] neg_hi:[0,1]
	v_pk_add_f32 v[72:73], v[72:73], v[74:75] op_sel:[0,1] op_sel_hi:[1,0] neg_lo:[0,1]
	v_pk_add_f32 v[74:75], v[76:77], v[90:91] op_sel:[0,1] op_sel_hi:[1,0] neg_hi:[0,1]
	v_pk_add_f32 v[76:77], v[76:77], v[90:91] op_sel:[0,1] op_sel_hi:[1,0] neg_lo:[0,1]
	v_mov_b32_e32 v90, v36
	v_mov_b32_e32 v91, v37
	s_branch .LBB0_1409
.LBB0_1408:
	s_or_b64 exec, exec, s[0:1]
	s_addk_i32 s28, 0x800
	s_waitcnt lgkmcnt(0)
	ds_write_b64 v34, v[92:93]
	s_cmpk_lg_u32 s28, 0x8000
	v_add_u32_e32 v34, 0x880, v34
	v_mov_b64_e32 v[92:93], s[18:19]
	v_pk_mul_f32 v[96:97], v[90:91], v[92:93] op_sel:[0,0] op_sel_hi:[0,1]
	v_pk_fma_f32 v[90:91], v[90:91], v[92:93], v[96:97] op_sel:[1,1,0] op_sel_hi:[1,0,1] neg_lo:[0,1,0]
	s_cbranch_scc0 .LBB0_1411
.LBB0_1409:
	v_add_u32_e32 v92, s28, v151
	ds_read_b64 v[92:93], v92
	s_and_saveexec_b64 s[0:1], s[4:5]
	s_cbranch_execz .LBB0_1408
	s_waitcnt lgkmcnt(0)
	v_pk_mul_f32 v[96:97], v[92:93], v[90:91] op_sel:[0,0] op_sel_hi:[0,1]
	v_pk_fma_f32 v[92:93], v[92:93], v[90:91], v[96:97] op_sel:[1,1,0] op_sel_hi:[1,0,1] neg_lo:[0,1,0]
	s_branch .LBB0_1408
.LBB0_1411:
	v_mov_b32_e32 v90, v30
	v_mov_b32_e32 v91, v26
	v_mov_b32_e32 v26, v31
	v_mov_b32_e32 v30, v32
	v_mov_b32_e32 v31, v28
	v_mov_b32_e32 v28, v33
	v_pk_add_f32 v[26:27], v[90:91], v[26:27]
	v_pk_add_f32 v[28:29], v[30:31], v[28:29]
	v_pk_add_f32 v[30:31], v[62:63], v[66:67]
	v_pk_add_f32 v[26:27], v[26:27], v[28:29]
	v_pk_add_f32 v[28:29], v[60:61], v[64:65]
	v_add_f32_e32 v34, v26, v27
	v_add_f32_e32 v34, 0x358637bd, v34
	v_mul_f32_e32 v34, 0x46000000, v34
	v_pk_add_f32 v[60:61], v[48:49], v[80:81]
	v_div_scale_f32 v48, s[0:1], v34, v34, 1.0
	v_rcp_f32_e32 v49, v48
	v_pk_add_f32 v[62:63], v[56:57], v[84:85]
	v_pk_add_f32 v[58:59], v[58:59], v[78:79]
	v_pk_add_f32 v[44:45], v[44:45], v[88:89]
	v_fma_f32 v56, -v48, v49, 1.0
	v_fmac_f32_e32 v49, v56, v49
	v_div_scale_f32 v56, vcc, 1.0, v34, 1.0
	v_mul_f32_e32 v57, v56, v49
	v_fma_f32 v78, -v48, v57, v56
	v_fmac_f32_e32 v57, v78, v49
	v_fma_f32 v48, -v48, v57, v56
	v_pk_add_f32 v[54:55], v[54:55], v[86:87]
	v_pk_add_f32 v[52:53], v[82:83], v[52:53]
	v_div_fmas_f32 v48, v48, v49, v57
	v_pk_add_f32 v[26:27], v[28:29], v[30:31]
	v_pk_add_f32 v[32:33], v[58:59], v[60:61]
	v_pk_add_f32 v[64:65], v[62:63], v[44:45]
	v_pk_add_f32 v[66:67], v[54:55], v[52:53]
	v_div_fixup_f32 v34, v48, v34, 1.0
	v_pk_add_f32 v[28:29], v[28:29], v[30:31] neg_lo:[0,1] neg_hi:[0,1]
	v_pk_add_f32 v[30:31], v[58:59], v[60:61] neg_lo:[0,1] neg_hi:[0,1]
	v_pk_add_f32 v[54:55], v[54:55], v[52:53] neg_lo:[0,1] neg_hi:[0,1]
	v_pk_mul_f32 v[56:57], v[34:35], v[26:27] op_sel_hi:[0,1]
	v_pk_mul_f32 v[48:49], v[34:35], v[32:33] op_sel_hi:[0,1]
	v_pk_mul_f32 v[32:33], v[34:35], v[64:65] op_sel_hi:[0,1]
	v_pk_mul_f32 v[26:27], v[34:35], v[66:67] op_sel_hi:[0,1]
	v_pk_add_f32 v[44:45], v[62:63], v[44:45] neg_lo:[0,1] neg_hi:[0,1]
	v_pk_mul_f32 v[60:61], v[34:35], v[28:29] op_sel_hi:[0,1]
	v_pk_mul_f32 v[52:53], v[34:35], v[30:31] op_sel_hi:[0,1]
	v_pk_mul_f32 v[28:29], v[34:35], v[54:55] op_sel_hi:[0,1]
	v_pk_mul_f32 v[64:65], v[34:35], v[42:43] op_sel_hi:[0,1]
	v_pk_mul_f32 v[62:63], v[34:35], v[46:47] op_sel_hi:[0,1]
	v_pk_mul_f32 v[58:59], v[34:35], v[50:51] op_sel_hi:[0,1]
	v_pk_mul_f32 v[54:55], v[34:35], v[68:69] op_sel_hi:[0,1]
	v_pk_mul_f32 v[50:51], v[34:35], v[70:71] op_sel_hi:[0,1]
	v_pk_mul_f32 v[46:47], v[34:35], v[72:73] op_sel_hi:[0,1]
	v_pk_mul_f32 v[42:43], v[34:35], v[74:75] op_sel_hi:[0,1]
	v_pk_mul_f32 v[30:31], v[34:35], v[76:77] op_sel_hi:[0,1]
	ds_read_b64 v[66:67], v144
	ds_read_b64 v[68:69], v144 offset:2176
	ds_read_b64 v[70:71], v144 offset:4352
	ds_read_b64 v[72:73], v144 offset:6528
	ds_read_b64 v[74:75], v144 offset:8704
	ds_read_b64 v[76:77], v144 offset:10880
	ds_read_b64 v[78:79], v144 offset:13056
	ds_read_b64 v[80:81], v144 offset:15232
	ds_read_b64 v[82:83], v144 offset:17408
	ds_read_b64 v[84:85], v144 offset:19584
	ds_read_b64 v[86:87], v144 offset:21760
	ds_read_b64 v[88:89], v144 offset:23936
	ds_read_b64 v[90:91], v144 offset:26112
	ds_read_b64 v[92:93], v144 offset:28288
	ds_read_b64 v[96:97], v144 offset:30464
	ds_read_b64 v[98:99], v144 offset:32640
	s_waitcnt lgkmcnt(7)
	v_pk_add_f32 v[100:101], v[66:67], v[82:83]
	v_pk_add_f32 v[66:67], v[66:67], v[82:83] neg_lo:[0,1] neg_hi:[0,1]
	s_waitcnt lgkmcnt(3)
	v_pk_add_f32 v[82:83], v[74:75], v[90:91]
	v_pk_add_f32 v[74:75], v[74:75], v[90:91] neg_lo:[0,1] neg_hi:[0,1]
	v_pk_add_f32 v[90:91], v[100:101], v[82:83]
	v_pk_add_f32 v[82:83], v[100:101], v[82:83] neg_lo:[0,1] neg_hi:[0,1]
	v_pk_add_f32 v[100:101], v[66:67], v[74:75] op_sel:[0,1] op_sel_hi:[1,0] neg_hi:[0,1]
	v_pk_add_f32 v[102:103], v[66:67], v[74:75] op_sel:[0,1] op_sel_hi:[1,0] neg_lo:[0,1]
	v_pk_add_f32 v[66:67], v[68:69], v[84:85]
	v_pk_add_f32 v[68:69], v[68:69], v[84:85] neg_lo:[0,1] neg_hi:[0,1]
	s_waitcnt lgkmcnt(2)
	v_pk_add_f32 v[74:75], v[76:77], v[92:93]
	v_pk_add_f32 v[76:77], v[76:77], v[92:93] neg_lo:[0,1] neg_hi:[0,1]
	v_pk_add_f32 v[84:85], v[66:67], v[74:75]
	v_pk_add_f32 v[74:75], v[66:67], v[74:75] neg_lo:[0,1] neg_hi:[0,1]
	v_pk_add_f32 v[66:67], v[68:69], v[76:77] op_sel:[0,1] op_sel_hi:[1,0] neg_hi:[0,1]
	v_pk_add_f32 v[76:77], v[68:69], v[76:77] op_sel:[0,1] op_sel_hi:[1,0] neg_lo:[0,1]
	v_pk_add_f32 v[68:69], v[70:71], v[86:87]
	v_pk_add_f32 v[70:71], v[70:71], v[86:87] neg_lo:[0,1] neg_hi:[0,1]
	s_waitcnt lgkmcnt(1)
	v_pk_add_f32 v[86:87], v[78:79], v[96:97]
	v_pk_add_f32 v[78:79], v[78:79], v[96:97] neg_lo:[0,1] neg_hi:[0,1]
	v_pk_add_f32 v[92:93], v[68:69], v[86:87]
	v_pk_add_f32 v[86:87], v[68:69], v[86:87] neg_lo:[0,1] neg_hi:[0,1]
	v_pk_add_f32 v[96:97], v[70:71], v[78:79] op_sel:[0,1] op_sel_hi:[1,0] neg_hi:[0,1]
	v_pk_add_f32 v[78:79], v[70:71], v[78:79] op_sel:[0,1] op_sel_hi:[1,0] neg_lo:[0,1]
	v_pk_add_f32 v[68:69], v[72:73], v[88:89]
	v_pk_add_f32 v[70:71], v[72:73], v[88:89] neg_lo:[0,1] neg_hi:[0,1]
	s_waitcnt lgkmcnt(0)
	v_pk_add_f32 v[72:73], v[80:81], v[98:99]
	v_pk_add_f32 v[80:81], v[80:81], v[98:99] neg_lo:[0,1] neg_hi:[0,1]
	v_pk_add_f32 v[88:89], v[68:69], v[72:73]
	v_pk_add_f32 v[98:99], v[68:69], v[72:73] neg_lo:[0,1] neg_hi:[0,1]
	v_mov_b64_e32 v[72:73], s[20:21]
	v_pk_mul_f32 v[68:69], v[66:67], v[72:73] op_sel:[0,0] op_sel_hi:[0,1]
	v_pk_add_f32 v[104:105], v[70:71], v[80:81] op_sel:[0,1] op_sel_hi:[1,0] neg_hi:[0,1]
	v_pk_add_f32 v[80:81], v[70:71], v[80:81] op_sel:[0,1] op_sel_hi:[1,0] neg_lo:[0,1]
	s_add_i32 s82, s74, s24
	v_pk_fma_f32 v[106:107], v[66:67], v[72:73], v[68:69] op_sel:[1,1,0] op_sel_hi:[1,0,1] neg_lo:[0,1,0]
	v_mov_b64_e32 v[68:69], s[50:51]
	v_pk_mul_f32 v[66:67], v[96:97], v[68:69] op_sel:[0,0] op_sel_hi:[0,1]
	s_cmpk_gt_i32 s82, 0x3ff
	v_pk_fma_f32 v[96:97], v[96:97], v[68:69], v[66:67] op_sel:[1,1,0] op_sel_hi:[1,0,1] neg_lo:[0,1,0]
	v_mov_b64_e32 v[66:67], s[54:55]
	v_pk_mul_f32 v[70:71], v[104:105], v[66:67] op_sel:[0,0] op_sel_hi:[0,1]
	v_pk_mul_f32 v[44:45], v[34:35], v[44:45] op_sel_hi:[0,1]
	v_pk_fma_f32 v[104:105], v[104:105], v[66:67], v[70:71] op_sel:[1,1,0] op_sel_hi:[1,0,1] neg_lo:[0,1,0]
	v_pk_mul_f32 v[70:71], v[74:75], v[68:69] op_sel:[0,0] op_sel_hi:[0,1]
	s_cselect_b64 s[80:81], -1, 0
	v_pk_fma_f32 v[108:109], v[74:75], v[68:69], v[70:71] op_sel:[1,1,0] op_sel_hi:[1,0,1] neg_lo:[0,1,0]
	v_mov_b64_e32 v[74:75], s[14:15]
	v_pk_mul_f32 v[70:71], v[86:87], v[74:75] op_sel:[0,0] op_sel_hi:[0,1]
	s_cmpk_lt_i32 s82, 0x400
	v_pk_fma_f32 v[86:87], v[86:87], v[74:75], v[70:71] op_sel:[1,1,0] op_sel_hi:[1,0,1] neg_lo:[0,1,0]
	v_mov_b64_e32 v[70:71], s[58:59]
	v_pk_mul_f32 v[110:111], v[98:99], v[70:71] op_sel:[0,0] op_sel_hi:[0,1]
	s_cselect_b32 s0, s82, -1
	v_pk_fma_f32 v[98:99], v[98:99], v[70:71], v[110:111] op_sel:[1,1,0] op_sel_hi:[1,0,1] neg_lo:[0,1,0]
	v_pk_mul_f32 v[110:111], v[76:77], v[66:67] op_sel:[0,0] op_sel_hi:[0,1]
	s_cmp_lt_i32 s0, 0
	v_pk_fma_f32 v[110:111], v[76:77], v[66:67], v[110:111] op_sel:[1,1,0] op_sel_hi:[1,0,1] neg_lo:[0,1,0]
	v_pk_mul_f32 v[76:77], v[78:79], v[70:71] op_sel:[0,0] op_sel_hi:[0,1]
	v_pk_fma_f32 v[78:79], v[78:79], v[70:71], v[76:77] op_sel:[1,1,0] op_sel_hi:[1,0,1] neg_lo:[0,1,0]
	v_mov_b64_e32 v[76:77], s[60:61]
	v_pk_mul_f32 v[112:113], v[80:81], v[76:77] op_sel:[0,0] op_sel_hi:[0,1]
	v_pk_fma_f32 v[80:81], v[80:81], v[76:77], v[112:113] op_sel:[1,1,0] op_sel_hi:[1,0,1] neg_lo:[0,1,0]
	v_pk_add_f32 v[112:113], v[90:91], v[92:93]
	v_pk_add_f32 v[90:91], v[90:91], v[92:93] neg_lo:[0,1] neg_hi:[0,1]
	v_pk_add_f32 v[92:93], v[84:85], v[88:89]
	v_pk_add_f32 v[84:85], v[84:85], v[88:89] neg_lo:[0,1] neg_hi:[0,1]
	v_pk_add_f32 v[88:89], v[112:113], v[92:93]
	v_pk_add_f32 v[92:93], v[112:113], v[92:93] neg_lo:[0,1] neg_hi:[0,1]
	v_pk_add_f32 v[112:113], v[90:91], v[84:85] op_sel:[0,1] op_sel_hi:[1,0] neg_hi:[0,1]
	v_pk_add_f32 v[84:85], v[90:91], v[84:85] op_sel:[0,1] op_sel_hi:[1,0] neg_lo:[0,1]
	v_pk_add_f32 v[90:91], v[100:101], v[96:97]
	v_pk_add_f32 v[96:97], v[100:101], v[96:97] neg_lo:[0,1] neg_hi:[0,1]
	v_pk_add_f32 v[100:101], v[106:107], v[104:105]
	v_pk_add_f32 v[104:105], v[106:107], v[104:105] neg_lo:[0,1] neg_hi:[0,1]
	v_pk_add_f32 v[106:107], v[90:91], v[100:101]
	v_pk_add_f32 v[90:91], v[90:91], v[100:101] neg_lo:[0,1] neg_hi:[0,1]
	v_pk_add_f32 v[100:101], v[96:97], v[104:105] op_sel:[0,1] op_sel_hi:[1,0] neg_hi:[0,1]
	v_pk_add_f32 v[96:97], v[96:97], v[104:105] op_sel:[0,1] op_sel_hi:[1,0] neg_lo:[0,1]
	v_pk_add_f32 v[104:105], v[82:83], v[86:87]
	v_pk_add_f32 v[82:83], v[82:83], v[86:87] neg_lo:[0,1] neg_hi:[0,1]
	v_pk_add_f32 v[86:87], v[108:109], v[98:99]
	v_pk_add_f32 v[98:99], v[108:109], v[98:99] neg_lo:[0,1] neg_hi:[0,1]
	v_pk_add_f32 v[108:109], v[104:105], v[86:87]
	v_pk_add_f32 v[86:87], v[104:105], v[86:87] neg_lo:[0,1] neg_hi:[0,1]
	v_pk_add_f32 v[104:105], v[82:83], v[98:99] op_sel:[0,1] op_sel_hi:[1,0] neg_hi:[0,1]
	v_pk_add_f32 v[82:83], v[82:83], v[98:99] op_sel:[0,1] op_sel_hi:[1,0] neg_lo:[0,1]
	v_pk_add_f32 v[98:99], v[102:103], v[78:79]
	v_pk_add_f32 v[78:79], v[102:103], v[78:79] neg_lo:[0,1] neg_hi:[0,1]
	v_pk_add_f32 v[102:103], v[110:111], v[80:81]
	v_pk_add_f32 v[80:81], v[110:111], v[80:81] neg_lo:[0,1] neg_hi:[0,1]
	v_pk_add_f32 v[110:111], v[98:99], v[102:103]
	v_pk_add_f32 v[98:99], v[98:99], v[102:103] neg_lo:[0,1] neg_hi:[0,1]
	v_pk_add_f32 v[102:103], v[78:79], v[80:81] op_sel:[0,1] op_sel_hi:[1,0] neg_hi:[0,1]
	v_pk_add_f32 v[78:79], v[78:79], v[80:81] op_sel:[0,1] op_sel_hi:[1,0] neg_lo:[0,1]
	v_mov_b32_e32 v80, v38
	v_mov_b32_e32 v81, v39
	ds_write_b64 v144, v[88:89]
	v_pk_mul_f32 v[88:89], v[106:107], v[80:81] op_sel:[0,0] op_sel_hi:[0,1]
	v_pk_fma_f32 v[88:89], v[106:107], v[80:81], v[88:89] op_sel:[1,1,0] op_sel_hi:[1,0,1] neg_lo:[0,1,0]
	ds_write_b64 v144, v[88:89] offset:2176
	v_pk_mul_f32 v[88:89], v[80:81], v[80:81] op_sel:[0,0] op_sel_hi:[0,1]
	v_pk_fma_f32 v[88:89], v[80:81], v[80:81], v[88:89] op_sel:[1,1,0] op_sel_hi:[1,0,1] neg_lo:[0,1,0]
	v_pk_mul_f32 v[106:107], v[108:109], v[88:89] op_sel:[0,0] op_sel_hi:[0,1]
	v_pk_fma_f32 v[106:107], v[108:109], v[88:89], v[106:107] op_sel:[1,1,0] op_sel_hi:[1,0,1] neg_lo:[0,1,0]
	ds_write_b64 v144, v[106:107] offset:4352
	v_pk_mul_f32 v[106:107], v[88:89], v[80:81] op_sel:[0,0] op_sel_hi:[0,1]
	v_pk_fma_f32 v[88:89], v[88:89], v[80:81], v[106:107] op_sel:[1,1,0] op_sel_hi:[1,0,1] neg_lo:[0,1,0]
	v_pk_mul_f32 v[106:107], v[110:111], v[88:89] op_sel:[0,0] op_sel_hi:[0,1]
	v_pk_fma_f32 v[106:107], v[110:111], v[88:89], v[106:107] op_sel:[1,1,0] op_sel_hi:[1,0,1] neg_lo:[0,1,0]
	ds_write_b64 v144, v[106:107] offset:6528
	v_pk_mul_f32 v[106:107], v[88:89], v[80:81] op_sel:[0,0] op_sel_hi:[0,1]
	v_pk_fma_f32 v[88:89], v[88:89], v[80:81], v[106:107] op_sel:[1,1,0] op_sel_hi:[1,0,1] neg_lo:[0,1,0]
	v_pk_mul_f32 v[106:107], v[112:113], v[88:89] op_sel:[0,0] op_sel_hi:[0,1]
	v_pk_fma_f32 v[106:107], v[112:113], v[88:89], v[106:107] op_sel:[1,1,0] op_sel_hi:[1,0,1] neg_lo:[0,1,0]
	ds_write_b64 v144, v[106:107] offset:8704
	v_pk_mul_f32 v[106:107], v[88:89], v[80:81] op_sel:[0,0] op_sel_hi:[0,1]
	v_pk_fma_f32 v[88:89], v[88:89], v[80:81], v[106:107] op_sel:[1,1,0] op_sel_hi:[1,0,1] neg_lo:[0,1,0]
	v_pk_mul_f32 v[106:107], v[100:101], v[88:89] op_sel:[0,0] op_sel_hi:[0,1]
	v_pk_fma_f32 v[100:101], v[100:101], v[88:89], v[106:107] op_sel:[1,1,0] op_sel_hi:[1,0,1] neg_lo:[0,1,0]
	ds_write_b64 v144, v[100:101] offset:10880
	v_pk_mul_f32 v[100:101], v[88:89], v[80:81] op_sel:[0,0] op_sel_hi:[0,1]
	v_pk_fma_f32 v[88:89], v[88:89], v[80:81], v[100:101] op_sel:[1,1,0] op_sel_hi:[1,0,1] neg_lo:[0,1,0]
	v_pk_mul_f32 v[100:101], v[104:105], v[88:89] op_sel:[0,0] op_sel_hi:[0,1]
	v_pk_fma_f32 v[100:101], v[104:105], v[88:89], v[100:101] op_sel:[1,1,0] op_sel_hi:[1,0,1] neg_lo:[0,1,0]
	ds_write_b64 v144, v[100:101] offset:13056
	v_pk_mul_f32 v[100:101], v[88:89], v[80:81] op_sel:[0,0] op_sel_hi:[0,1]
	v_pk_fma_f32 v[88:89], v[88:89], v[80:81], v[100:101] op_sel:[1,1,0] op_sel_hi:[1,0,1] neg_lo:[0,1,0]
	v_pk_mul_f32 v[100:101], v[102:103], v[88:89] op_sel:[0,0] op_sel_hi:[0,1]
	v_pk_fma_f32 v[100:101], v[102:103], v[88:89], v[100:101] op_sel:[1,1,0] op_sel_hi:[1,0,1] neg_lo:[0,1,0]
	ds_write_b64 v144, v[100:101] offset:15232
	v_pk_mul_f32 v[100:101], v[88:89], v[80:81] op_sel:[0,0] op_sel_hi:[0,1]
	v_pk_fma_f32 v[88:89], v[88:89], v[80:81], v[100:101] op_sel:[1,1,0] op_sel_hi:[1,0,1] neg_lo:[0,1,0]
	v_pk_mul_f32 v[100:101], v[92:93], v[88:89] op_sel:[0,0] op_sel_hi:[0,1]
	v_pk_fma_f32 v[92:93], v[92:93], v[88:89], v[100:101] op_sel:[1,1,0] op_sel_hi:[1,0,1] neg_lo:[0,1,0]
	ds_write_b64 v144, v[92:93] offset:17408
	v_pk_mul_f32 v[92:93], v[88:89], v[80:81] op_sel:[0,0] op_sel_hi:[0,1]
	v_pk_fma_f32 v[88:89], v[88:89], v[80:81], v[92:93] op_sel:[1,1,0] op_sel_hi:[1,0,1] neg_lo:[0,1,0]
	v_pk_mul_f32 v[92:93], v[90:91], v[88:89] op_sel:[0,0] op_sel_hi:[0,1]
	v_pk_fma_f32 v[90:91], v[90:91], v[88:89], v[92:93] op_sel:[1,1,0] op_sel_hi:[1,0,1] neg_lo:[0,1,0]
	ds_write_b64 v144, v[90:91] offset:19584
	v_pk_mul_f32 v[90:91], v[88:89], v[80:81] op_sel:[0,0] op_sel_hi:[0,1]
	v_pk_fma_f32 v[88:89], v[88:89], v[80:81], v[90:91] op_sel:[1,1,0] op_sel_hi:[1,0,1] neg_lo:[0,1,0]
	v_pk_mul_f32 v[90:91], v[86:87], v[88:89] op_sel:[0,0] op_sel_hi:[0,1]
	v_pk_fma_f32 v[86:87], v[86:87], v[88:89], v[90:91] op_sel:[1,1,0] op_sel_hi:[1,0,1] neg_lo:[0,1,0]
	ds_write_b64 v144, v[86:87] offset:21760
	v_pk_mul_f32 v[86:87], v[88:89], v[80:81] op_sel:[0,0] op_sel_hi:[0,1]
	v_pk_fma_f32 v[86:87], v[88:89], v[80:81], v[86:87] op_sel:[1,1,0] op_sel_hi:[1,0,1] neg_lo:[0,1,0]
	v_pk_mul_f32 v[88:89], v[98:99], v[86:87] op_sel:[0,0] op_sel_hi:[0,1]
	v_pk_fma_f32 v[88:89], v[98:99], v[86:87], v[88:89] op_sel:[1,1,0] op_sel_hi:[1,0,1] neg_lo:[0,1,0]
	ds_write_b64 v144, v[88:89] offset:23936
	v_pk_mul_f32 v[88:89], v[86:87], v[80:81] op_sel:[0,0] op_sel_hi:[0,1]
	v_pk_fma_f32 v[86:87], v[86:87], v[80:81], v[88:89] op_sel:[1,1,0] op_sel_hi:[1,0,1] neg_lo:[0,1,0]
	v_pk_mul_f32 v[88:89], v[84:85], v[86:87] op_sel:[0,0] op_sel_hi:[0,1]
	v_pk_fma_f32 v[84:85], v[84:85], v[86:87], v[88:89] op_sel:[1,1,0] op_sel_hi:[1,0,1] neg_lo:[0,1,0]
	ds_write_b64 v144, v[84:85] offset:26112
	v_pk_mul_f32 v[84:85], v[86:87], v[80:81] op_sel:[0,0] op_sel_hi:[0,1]
	v_pk_fma_f32 v[84:85], v[86:87], v[80:81], v[84:85] op_sel:[1,1,0] op_sel_hi:[1,0,1] neg_lo:[0,1,0]
	v_pk_mul_f32 v[86:87], v[96:97], v[84:85] op_sel:[0,0] op_sel_hi:[0,1]
	v_pk_fma_f32 v[86:87], v[96:97], v[84:85], v[86:87] op_sel:[1,1,0] op_sel_hi:[1,0,1] neg_lo:[0,1,0]
	ds_write_b64 v144, v[86:87] offset:28288
	v_pk_mul_f32 v[86:87], v[84:85], v[80:81] op_sel:[0,0] op_sel_hi:[0,1]
	v_pk_fma_f32 v[84:85], v[84:85], v[80:81], v[86:87] op_sel:[1,1,0] op_sel_hi:[1,0,1] neg_lo:[0,1,0]
	v_pk_mul_f32 v[86:87], v[82:83], v[84:85] op_sel:[0,0] op_sel_hi:[0,1]
	v_pk_fma_f32 v[82:83], v[82:83], v[84:85], v[86:87] op_sel:[1,1,0] op_sel_hi:[1,0,1] neg_lo:[0,1,0]
	ds_write_b64 v144, v[82:83] offset:30464
	v_pk_mul_f32 v[82:83], v[84:85], v[80:81] op_sel:[0,0] op_sel_hi:[0,1]
	v_pk_fma_f32 v[80:81], v[84:85], v[80:81], v[82:83] op_sel:[1,1,0] op_sel_hi:[1,0,1] neg_lo:[0,1,0]
	v_pk_mul_f32 v[82:83], v[78:79], v[80:81] op_sel:[0,0] op_sel_hi:[0,1]
	v_pk_fma_f32 v[78:79], v[78:79], v[80:81], v[82:83] op_sel:[1,1,0] op_sel_hi:[1,0,1] neg_lo:[0,1,0]
	ds_write_b64 v144, v[78:79] offset:32640
	s_waitcnt lgkmcnt(0)
	s_barrier
	ds_read2_b64 v[78:81], v146 offset1:17
	ds_read2_b64 v[82:85], v146 offset0:34 offset1:51
	ds_read2_b64 v[86:89], v146 offset0:68 offset1:85
	ds_read2_b64 v[90:93], v146 offset0:136 offset1:153
	ds_read2_b64 v[96:99], v146 offset0:102 offset1:119
	ds_read2_b64 v[100:103], v146 offset0:204 offset1:221
	ds_read2_b64 v[104:107], v146 offset0:170 offset1:187
	ds_read2_b64 v[108:111], v146 offset0:238 offset1:255
	s_waitcnt lgkmcnt(4)
	v_pk_add_f32 v[112:113], v[78:79], v[90:91]
	v_pk_add_f32 v[78:79], v[78:79], v[90:91] neg_lo:[0,1] neg_hi:[0,1]
	s_waitcnt lgkmcnt(2)
	v_pk_add_f32 v[90:91], v[86:87], v[100:101]
	v_pk_add_f32 v[86:87], v[86:87], v[100:101] neg_lo:[0,1] neg_hi:[0,1]
	v_pk_add_f32 v[100:101], v[112:113], v[90:91]
	v_pk_add_f32 v[90:91], v[112:113], v[90:91] neg_lo:[0,1] neg_hi:[0,1]
	v_pk_add_f32 v[112:113], v[78:79], v[86:87] op_sel:[0,1] op_sel_hi:[1,0] neg_hi:[0,1]
	v_pk_add_f32 v[78:79], v[78:79], v[86:87] op_sel:[0,1] op_sel_hi:[1,0] neg_lo:[0,1]
	v_pk_add_f32 v[86:87], v[80:81], v[92:93]
	v_pk_add_f32 v[80:81], v[80:81], v[92:93] neg_lo:[0,1] neg_hi:[0,1]
	v_pk_add_f32 v[92:93], v[88:89], v[102:103]
	v_pk_add_f32 v[88:89], v[88:89], v[102:103] neg_lo:[0,1] neg_hi:[0,1]
	v_pk_add_f32 v[102:103], v[86:87], v[92:93]
	v_pk_add_f32 v[86:87], v[86:87], v[92:93] neg_lo:[0,1] neg_hi:[0,1]
	v_pk_add_f32 v[92:93], v[80:81], v[88:89] op_sel:[0,1] op_sel_hi:[1,0] neg_hi:[0,1]
	v_pk_add_f32 v[80:81], v[80:81], v[88:89] op_sel:[0,1] op_sel_hi:[1,0] neg_lo:[0,1]
	s_waitcnt lgkmcnt(1)
	v_pk_add_f32 v[88:89], v[82:83], v[104:105]
	v_pk_add_f32 v[82:83], v[82:83], v[104:105] neg_lo:[0,1] neg_hi:[0,1]
	s_waitcnt lgkmcnt(0)
	v_pk_add_f32 v[104:105], v[96:97], v[108:109]
	v_pk_add_f32 v[96:97], v[96:97], v[108:109] neg_lo:[0,1] neg_hi:[0,1]
	v_pk_add_f32 v[108:109], v[88:89], v[104:105]
	v_pk_add_f32 v[88:89], v[88:89], v[104:105] neg_lo:[0,1] neg_hi:[0,1]
	v_pk_add_f32 v[104:105], v[82:83], v[96:97] op_sel:[0,1] op_sel_hi:[1,0] neg_hi:[0,1]
	v_pk_add_f32 v[82:83], v[82:83], v[96:97] op_sel:[0,1] op_sel_hi:[1,0] neg_lo:[0,1]
	v_pk_add_f32 v[96:97], v[84:85], v[106:107]
	v_pk_add_f32 v[84:85], v[84:85], v[106:107] neg_lo:[0,1] neg_hi:[0,1]
	v_pk_add_f32 v[106:107], v[98:99], v[110:111]
	v_pk_add_f32 v[98:99], v[98:99], v[110:111] neg_lo:[0,1] neg_hi:[0,1]
	v_pk_add_f32 v[110:111], v[96:97], v[106:107]
	v_pk_add_f32 v[96:97], v[96:97], v[106:107] neg_lo:[0,1] neg_hi:[0,1]
	v_pk_add_f32 v[106:107], v[84:85], v[98:99] op_sel:[0,1] op_sel_hi:[1,0] neg_hi:[0,1]
	v_pk_add_f32 v[84:85], v[84:85], v[98:99] op_sel:[0,1] op_sel_hi:[1,0] neg_lo:[0,1]
	v_pk_mul_f32 v[98:99], v[92:93], v[72:73] op_sel:[0,0] op_sel_hi:[0,1]
	v_pk_fma_f32 v[92:93], v[92:93], v[72:73], v[98:99] op_sel:[1,1,0] op_sel_hi:[1,0,1] neg_lo:[0,1,0]
	v_pk_mul_f32 v[98:99], v[104:105], v[68:69] op_sel:[0,0] op_sel_hi:[0,1]
	v_pk_fma_f32 v[98:99], v[104:105], v[68:69], v[98:99] op_sel:[1,1,0] op_sel_hi:[1,0,1] neg_lo:[0,1,0]
	v_pk_mul_f32 v[104:105], v[106:107], v[66:67] op_sel:[0,0] op_sel_hi:[0,1]
	v_pk_fma_f32 v[104:105], v[106:107], v[66:67], v[104:105] op_sel:[1,1,0] op_sel_hi:[1,0,1] neg_lo:[0,1,0]
	v_pk_mul_f32 v[106:107], v[86:87], v[68:69] op_sel:[0,0] op_sel_hi:[0,1]
	v_pk_fma_f32 v[86:87], v[86:87], v[68:69], v[106:107] op_sel:[1,1,0] op_sel_hi:[1,0,1] neg_lo:[0,1,0]
	v_pk_mul_f32 v[106:107], v[88:89], v[74:75] op_sel:[0,0] op_sel_hi:[0,1]
	v_pk_fma_f32 v[88:89], v[88:89], v[74:75], v[106:107] op_sel:[1,1,0] op_sel_hi:[1,0,1] neg_lo:[0,1,0]
	v_pk_mul_f32 v[106:107], v[96:97], v[70:71] op_sel:[0,0] op_sel_hi:[0,1]
	v_pk_fma_f32 v[96:97], v[96:97], v[70:71], v[106:107] op_sel:[1,1,0] op_sel_hi:[1,0,1] neg_lo:[0,1,0]
	v_pk_mul_f32 v[106:107], v[80:81], v[66:67] op_sel:[0,0] op_sel_hi:[0,1]
	v_pk_fma_f32 v[80:81], v[80:81], v[66:67], v[106:107] op_sel:[1,1,0] op_sel_hi:[1,0,1] neg_lo:[0,1,0]
	v_pk_mul_f32 v[106:107], v[82:83], v[70:71] op_sel:[0,0] op_sel_hi:[0,1]
	v_pk_fma_f32 v[82:83], v[82:83], v[70:71], v[106:107] op_sel:[1,1,0] op_sel_hi:[1,0,1] neg_lo:[0,1,0]
	v_pk_mul_f32 v[106:107], v[84:85], v[76:77] op_sel:[0,0] op_sel_hi:[0,1]
	v_pk_fma_f32 v[84:85], v[84:85], v[76:77], v[106:107] op_sel:[1,1,0] op_sel_hi:[1,0,1] neg_lo:[0,1,0]
	v_pk_add_f32 v[106:107], v[100:101], v[108:109]
	v_pk_add_f32 v[100:101], v[100:101], v[108:109] neg_lo:[0,1] neg_hi:[0,1]
	v_pk_add_f32 v[108:109], v[102:103], v[110:111]
	v_pk_add_f32 v[102:103], v[102:103], v[110:111] neg_lo:[0,1] neg_hi:[0,1]
	v_pk_add_f32 v[110:111], v[106:107], v[108:109]
	v_pk_add_f32 v[106:107], v[106:107], v[108:109] neg_lo:[0,1] neg_hi:[0,1]
	v_pk_add_f32 v[108:109], v[100:101], v[102:103] op_sel:[0,1] op_sel_hi:[1,0] neg_hi:[0,1]
	v_pk_add_f32 v[100:101], v[100:101], v[102:103] op_sel:[0,1] op_sel_hi:[1,0] neg_lo:[0,1]
	v_pk_add_f32 v[102:103], v[112:113], v[98:99]
	v_pk_add_f32 v[98:99], v[112:113], v[98:99] neg_lo:[0,1] neg_hi:[0,1]
	v_pk_add_f32 v[112:113], v[92:93], v[104:105]
	v_pk_add_f32 v[92:93], v[92:93], v[104:105] neg_lo:[0,1] neg_hi:[0,1]
	v_pk_add_f32 v[104:105], v[102:103], v[112:113]
	v_pk_add_f32 v[102:103], v[102:103], v[112:113] neg_lo:[0,1] neg_hi:[0,1]
	v_pk_add_f32 v[112:113], v[98:99], v[92:93] op_sel:[0,1] op_sel_hi:[1,0] neg_hi:[0,1]
	v_pk_add_f32 v[92:93], v[98:99], v[92:93] op_sel:[0,1] op_sel_hi:[1,0] neg_lo:[0,1]
	v_pk_add_f32 v[98:99], v[90:91], v[88:89]
	v_pk_add_f32 v[88:89], v[90:91], v[88:89] neg_lo:[0,1] neg_hi:[0,1]
	v_pk_add_f32 v[90:91], v[86:87], v[96:97]
	v_pk_add_f32 v[86:87], v[86:87], v[96:97] neg_lo:[0,1] neg_hi:[0,1]
	v_pk_add_f32 v[96:97], v[98:99], v[90:91]
	v_pk_add_f32 v[90:91], v[98:99], v[90:91] neg_lo:[0,1] neg_hi:[0,1]
	v_pk_add_f32 v[98:99], v[88:89], v[86:87] op_sel:[0,1] op_sel_hi:[1,0] neg_hi:[0,1]
	v_pk_add_f32 v[86:87], v[88:89], v[86:87] op_sel:[0,1] op_sel_hi:[1,0] neg_lo:[0,1]
	v_pk_add_f32 v[88:89], v[78:79], v[82:83]
	v_pk_add_f32 v[78:79], v[78:79], v[82:83] neg_lo:[0,1] neg_hi:[0,1]
	v_pk_add_f32 v[82:83], v[80:81], v[84:85]
	v_pk_add_f32 v[80:81], v[80:81], v[84:85] neg_lo:[0,1] neg_hi:[0,1]
	v_pk_add_f32 v[84:85], v[88:89], v[82:83]
	v_pk_add_f32 v[82:83], v[88:89], v[82:83] neg_lo:[0,1] neg_hi:[0,1]
	v_pk_add_f32 v[88:89], v[78:79], v[80:81] op_sel:[0,1] op_sel_hi:[1,0] neg_hi:[0,1]
	v_pk_add_f32 v[78:79], v[78:79], v[80:81] op_sel:[0,1] op_sel_hi:[1,0] neg_lo:[0,1]
	v_mov_b32_e32 v80, v40
	v_mov_b32_e32 v81, v41
	s_nop 0
	v_pk_mul_f32 v[114:115], v[104:105], v[80:81] op_sel:[0,0] op_sel_hi:[0,1]
	v_pk_fma_f32 v[104:105], v[104:105], v[80:81], v[114:115] op_sel:[1,1,0] op_sel_hi:[1,0,1] neg_lo:[0,1,0]
	ds_write2_b64 v146, v[110:111], v[104:105] offset1:17
	v_pk_mul_f32 v[104:105], v[80:81], v[80:81] op_sel:[0,0] op_sel_hi:[0,1]
	v_pk_fma_f32 v[104:105], v[80:81], v[80:81], v[104:105] op_sel:[1,1,0] op_sel_hi:[1,0,1] neg_lo:[0,1,0]
	v_pk_mul_f32 v[110:111], v[96:97], v[104:105] op_sel:[0,0] op_sel_hi:[0,1]
	v_pk_fma_f32 v[96:97], v[96:97], v[104:105], v[110:111] op_sel:[1,1,0] op_sel_hi:[1,0,1] neg_lo:[0,1,0]
	v_pk_mul_f32 v[110:111], v[104:105], v[80:81] op_sel:[0,0] op_sel_hi:[0,1]
	v_pk_fma_f32 v[104:105], v[104:105], v[80:81], v[110:111] op_sel:[1,1,0] op_sel_hi:[1,0,1] neg_lo:[0,1,0]
	v_pk_mul_f32 v[110:111], v[84:85], v[104:105] op_sel:[0,0] op_sel_hi:[0,1]
	v_pk_fma_f32 v[84:85], v[84:85], v[104:105], v[110:111] op_sel:[1,1,0] op_sel_hi:[1,0,1] neg_lo:[0,1,0]
	ds_write2_b64 v146, v[96:97], v[84:85] offset0:34 offset1:51
	v_pk_mul_f32 v[84:85], v[104:105], v[80:81] op_sel:[0,0] op_sel_hi:[0,1]
	v_pk_fma_f32 v[84:85], v[104:105], v[80:81], v[84:85] op_sel:[1,1,0] op_sel_hi:[1,0,1] neg_lo:[0,1,0]
	v_pk_mul_f32 v[96:97], v[108:109], v[84:85] op_sel:[0,0] op_sel_hi:[0,1]
	v_pk_mul_f32 v[104:105], v[84:85], v[80:81] op_sel:[0,0] op_sel_hi:[0,1]
	v_pk_fma_f32 v[96:97], v[108:109], v[84:85], v[96:97] op_sel:[1,1,0] op_sel_hi:[1,0,1] neg_lo:[0,1,0]
	v_pk_fma_f32 v[84:85], v[84:85], v[80:81], v[104:105] op_sel:[1,1,0] op_sel_hi:[1,0,1] neg_lo:[0,1,0]
	v_pk_mul_f32 v[104:105], v[112:113], v[84:85] op_sel:[0,0] op_sel_hi:[0,1]
	v_pk_fma_f32 v[104:105], v[112:113], v[84:85], v[104:105] op_sel:[1,1,0] op_sel_hi:[1,0,1] neg_lo:[0,1,0]
	ds_write2_b64 v146, v[96:97], v[104:105] offset0:68 offset1:85
	v_pk_mul_f32 v[96:97], v[84:85], v[80:81] op_sel:[0,0] op_sel_hi:[0,1]
	v_pk_fma_f32 v[84:85], v[84:85], v[80:81], v[96:97] op_sel:[1,1,0] op_sel_hi:[1,0,1] neg_lo:[0,1,0]
	v_pk_mul_f32 v[96:97], v[98:99], v[84:85] op_sel:[0,0] op_sel_hi:[0,1]
	v_pk_fma_f32 v[96:97], v[98:99], v[84:85], v[96:97] op_sel:[1,1,0] op_sel_hi:[1,0,1] neg_lo:[0,1,0]
	v_pk_mul_f32 v[98:99], v[84:85], v[80:81] op_sel:[0,0] op_sel_hi:[0,1]
	v_pk_fma_f32 v[84:85], v[84:85], v[80:81], v[98:99] op_sel:[1,1,0] op_sel_hi:[1,0,1] neg_lo:[0,1,0]
	v_pk_mul_f32 v[98:99], v[88:89], v[84:85] op_sel:[0,0] op_sel_hi:[0,1]
	v_pk_fma_f32 v[88:89], v[88:89], v[84:85], v[98:99] op_sel:[1,1,0] op_sel_hi:[1,0,1] neg_lo:[0,1,0]
	ds_write2_b64 v146, v[96:97], v[88:89] offset0:102 offset1:119
	v_pk_mul_f32 v[88:89], v[84:85], v[80:81] op_sel:[0,0] op_sel_hi:[0,1]
	v_pk_fma_f32 v[84:85], v[84:85], v[80:81], v[88:89] op_sel:[1,1,0] op_sel_hi:[1,0,1] neg_lo:[0,1,0]
	v_pk_mul_f32 v[88:89], v[106:107], v[84:85] op_sel:[0,0] op_sel_hi:[0,1]
	v_pk_mul_f32 v[96:97], v[84:85], v[80:81] op_sel:[0,0] op_sel_hi:[0,1]
	v_pk_fma_f32 v[88:89], v[106:107], v[84:85], v[88:89] op_sel:[1,1,0] op_sel_hi:[1,0,1] neg_lo:[0,1,0]
	v_pk_fma_f32 v[84:85], v[84:85], v[80:81], v[96:97] op_sel:[1,1,0] op_sel_hi:[1,0,1] neg_lo:[0,1,0]
	v_pk_mul_f32 v[96:97], v[102:103], v[84:85] op_sel:[0,0] op_sel_hi:[0,1]
	v_pk_fma_f32 v[96:97], v[102:103], v[84:85], v[96:97] op_sel:[1,1,0] op_sel_hi:[1,0,1] neg_lo:[0,1,0]
	ds_write2_b64 v146, v[88:89], v[96:97] offset0:136 offset1:153
	v_pk_mul_f32 v[88:89], v[84:85], v[80:81] op_sel:[0,0] op_sel_hi:[0,1]
	v_pk_fma_f32 v[84:85], v[84:85], v[80:81], v[88:89] op_sel:[1,1,0] op_sel_hi:[1,0,1] neg_lo:[0,1,0]
	v_pk_mul_f32 v[88:89], v[90:91], v[84:85] op_sel:[0,0] op_sel_hi:[0,1]
	v_pk_fma_f32 v[88:89], v[90:91], v[84:85], v[88:89] op_sel:[1,1,0] op_sel_hi:[1,0,1] neg_lo:[0,1,0]
	v_pk_mul_f32 v[90:91], v[84:85], v[80:81] op_sel:[0,0] op_sel_hi:[0,1]
	v_pk_fma_f32 v[84:85], v[84:85], v[80:81], v[90:91] op_sel:[1,1,0] op_sel_hi:[1,0,1] neg_lo:[0,1,0]
	v_pk_mul_f32 v[90:91], v[82:83], v[84:85] op_sel:[0,0] op_sel_hi:[0,1]
	v_pk_fma_f32 v[82:83], v[82:83], v[84:85], v[90:91] op_sel:[1,1,0] op_sel_hi:[1,0,1] neg_lo:[0,1,0]
	ds_write2_b64 v146, v[88:89], v[82:83] offset0:170 offset1:187
	v_pk_mul_f32 v[82:83], v[84:85], v[80:81] op_sel:[0,0] op_sel_hi:[0,1]
	v_pk_fma_f32 v[82:83], v[84:85], v[80:81], v[82:83] op_sel:[1,1,0] op_sel_hi:[1,0,1] neg_lo:[0,1,0]
	v_pk_mul_f32 v[84:85], v[100:101], v[82:83] op_sel:[0,0] op_sel_hi:[0,1]
	v_pk_mul_f32 v[88:89], v[82:83], v[80:81] op_sel:[0,0] op_sel_hi:[0,1]
	v_pk_fma_f32 v[84:85], v[100:101], v[82:83], v[84:85] op_sel:[1,1,0] op_sel_hi:[1,0,1] neg_lo:[0,1,0]
	v_pk_fma_f32 v[82:83], v[82:83], v[80:81], v[88:89] op_sel:[1,1,0] op_sel_hi:[1,0,1] neg_lo:[0,1,0]
	v_pk_mul_f32 v[88:89], v[92:93], v[82:83] op_sel:[0,0] op_sel_hi:[0,1]
	v_pk_fma_f32 v[88:89], v[92:93], v[82:83], v[88:89] op_sel:[1,1,0] op_sel_hi:[1,0,1] neg_lo:[0,1,0]
	ds_write2_b64 v146, v[84:85], v[88:89] offset0:204 offset1:221
	v_pk_mul_f32 v[84:85], v[82:83], v[80:81] op_sel:[0,0] op_sel_hi:[0,1]
	v_pk_fma_f32 v[82:83], v[82:83], v[80:81], v[84:85] op_sel:[1,1,0] op_sel_hi:[1,0,1] neg_lo:[0,1,0]
	v_pk_mul_f32 v[84:85], v[86:87], v[82:83] op_sel:[0,0] op_sel_hi:[0,1]
	v_pk_fma_f32 v[84:85], v[86:87], v[82:83], v[84:85] op_sel:[1,1,0] op_sel_hi:[1,0,1] neg_lo:[0,1,0]
	v_pk_mul_f32 v[86:87], v[82:83], v[80:81] op_sel:[0,0] op_sel_hi:[0,1]
	v_pk_fma_f32 v[80:81], v[82:83], v[80:81], v[86:87] op_sel:[1,1,0] op_sel_hi:[1,0,1] neg_lo:[0,1,0]
	v_pk_mul_f32 v[82:83], v[78:79], v[80:81] op_sel:[0,0] op_sel_hi:[0,1]
	v_pk_fma_f32 v[78:79], v[78:79], v[80:81], v[82:83] op_sel:[1,1,0] op_sel_hi:[1,0,1] neg_lo:[0,1,0]
	ds_write2_b64 v146, v[84:85], v[78:79] offset0:238 offset1:255
	s_waitcnt lgkmcnt(0)
	s_barrier
	ds_read2_b64 v[78:81], v147 offset1:1
	ds_read2_b64 v[82:85], v147 offset0:2 offset1:3
	ds_read2_b64 v[86:89], v147 offset0:8 offset1:9
	ds_read2_b64 v[90:93], v147 offset0:4 offset1:5
	ds_read2_b64 v[96:99], v147 offset0:6 offset1:7
	ds_read2_b64 v[100:103], v147 offset0:12 offset1:13
	ds_read2_b64 v[104:107], v147 offset0:10 offset1:11
	ds_read2_b64 v[108:111], v147 offset0:14 offset1:15
	s_waitcnt lgkmcnt(5)
	v_pk_add_f32 v[112:113], v[78:79], v[86:87]
	v_pk_add_f32 v[78:79], v[78:79], v[86:87] neg_lo:[0,1] neg_hi:[0,1]
	s_waitcnt lgkmcnt(2)
	v_pk_add_f32 v[86:87], v[90:91], v[100:101]
	v_pk_add_f32 v[90:91], v[90:91], v[100:101] neg_lo:[0,1] neg_hi:[0,1]
	v_pk_add_f32 v[100:101], v[112:113], v[86:87]
	v_pk_add_f32 v[86:87], v[112:113], v[86:87] neg_lo:[0,1] neg_hi:[0,1]
	v_pk_add_f32 v[112:113], v[78:79], v[90:91] op_sel:[0,1] op_sel_hi:[1,0] neg_hi:[0,1]
	v_pk_add_f32 v[78:79], v[78:79], v[90:91] op_sel:[0,1] op_sel_hi:[1,0] neg_lo:[0,1]
	v_pk_add_f32 v[90:91], v[80:81], v[88:89]
	v_pk_add_f32 v[80:81], v[80:81], v[88:89] neg_lo:[0,1] neg_hi:[0,1]
	v_pk_add_f32 v[88:89], v[92:93], v[102:103]
	v_pk_add_f32 v[92:93], v[92:93], v[102:103] neg_lo:[0,1] neg_hi:[0,1]
	v_pk_add_f32 v[102:103], v[90:91], v[88:89]
	v_pk_add_f32 v[88:89], v[90:91], v[88:89] neg_lo:[0,1] neg_hi:[0,1]
	v_pk_add_f32 v[90:91], v[80:81], v[92:93] op_sel:[0,1] op_sel_hi:[1,0] neg_hi:[0,1]
	v_pk_add_f32 v[80:81], v[80:81], v[92:93] op_sel:[0,1] op_sel_hi:[1,0] neg_lo:[0,1]
	s_waitcnt lgkmcnt(1)
	v_pk_add_f32 v[92:93], v[82:83], v[104:105]
	v_pk_add_f32 v[82:83], v[82:83], v[104:105] neg_lo:[0,1] neg_hi:[0,1]
	s_waitcnt lgkmcnt(0)
	v_pk_add_f32 v[104:105], v[96:97], v[108:109]
	v_pk_add_f32 v[96:97], v[96:97], v[108:109] neg_lo:[0,1] neg_hi:[0,1]
	v_pk_add_f32 v[108:109], v[92:93], v[104:105]
	v_pk_add_f32 v[92:93], v[92:93], v[104:105] neg_lo:[0,1] neg_hi:[0,1]
	v_pk_add_f32 v[104:105], v[82:83], v[96:97] op_sel:[0,1] op_sel_hi:[1,0] neg_hi:[0,1]
	v_pk_add_f32 v[82:83], v[82:83], v[96:97] op_sel:[0,1] op_sel_hi:[1,0] neg_lo:[0,1]
	v_pk_add_f32 v[96:97], v[84:85], v[106:107]
	v_pk_add_f32 v[84:85], v[84:85], v[106:107] neg_lo:[0,1] neg_hi:[0,1]
	v_pk_add_f32 v[106:107], v[98:99], v[110:111]
	v_pk_add_f32 v[98:99], v[98:99], v[110:111] neg_lo:[0,1] neg_hi:[0,1]
	v_pk_add_f32 v[110:111], v[96:97], v[106:107]
	v_pk_add_f32 v[96:97], v[96:97], v[106:107] neg_lo:[0,1] neg_hi:[0,1]
	v_pk_add_f32 v[106:107], v[84:85], v[98:99] op_sel:[0,1] op_sel_hi:[1,0] neg_hi:[0,1]
	v_pk_add_f32 v[84:85], v[84:85], v[98:99] op_sel:[0,1] op_sel_hi:[1,0] neg_lo:[0,1]
	v_pk_mul_f32 v[98:99], v[90:91], v[72:73] op_sel:[0,0] op_sel_hi:[0,1]
	v_pk_fma_f32 v[72:73], v[90:91], v[72:73], v[98:99] op_sel:[1,1,0] op_sel_hi:[1,0,1] neg_lo:[0,1,0]
	v_pk_mul_f32 v[90:91], v[104:105], v[68:69] op_sel:[0,0] op_sel_hi:[0,1]
	v_pk_mul_f32 v[98:99], v[106:107], v[66:67] op_sel:[0,0] op_sel_hi:[0,1]
	v_pk_fma_f32 v[90:91], v[104:105], v[68:69], v[90:91] op_sel:[1,1,0] op_sel_hi:[1,0,1] neg_lo:[0,1,0]
	v_pk_mul_f32 v[104:105], v[88:89], v[68:69] op_sel:[0,0] op_sel_hi:[0,1]
	v_pk_fma_f32 v[98:99], v[106:107], v[66:67], v[98:99] op_sel:[1,1,0] op_sel_hi:[1,0,1] neg_lo:[0,1,0]
	v_pk_fma_f32 v[68:69], v[88:89], v[68:69], v[104:105] op_sel:[1,1,0] op_sel_hi:[1,0,1] neg_lo:[0,1,0]
	v_pk_mul_f32 v[88:89], v[92:93], v[74:75] op_sel:[0,0] op_sel_hi:[0,1]
	v_pk_fma_f32 v[74:75], v[92:93], v[74:75], v[88:89] op_sel:[1,1,0] op_sel_hi:[1,0,1] neg_lo:[0,1,0]
	v_pk_mul_f32 v[88:89], v[96:97], v[70:71] op_sel:[0,0] op_sel_hi:[0,1]
	v_pk_mul_f32 v[92:93], v[80:81], v[66:67] op_sel:[0,0] op_sel_hi:[0,1]
	v_pk_fma_f32 v[66:67], v[80:81], v[66:67], v[92:93] op_sel:[1,1,0] op_sel_hi:[1,0,1] neg_lo:[0,1,0]
	v_pk_mul_f32 v[80:81], v[82:83], v[70:71] op_sel:[0,0] op_sel_hi:[0,1]
	v_pk_fma_f32 v[88:89], v[96:97], v[70:71], v[88:89] op_sel:[1,1,0] op_sel_hi:[1,0,1] neg_lo:[0,1,0]
	v_pk_add_f32 v[92:93], v[102:103], v[110:111] neg_lo:[0,1] neg_hi:[0,1]
	v_pk_fma_f32 v[70:71], v[82:83], v[70:71], v[80:81] op_sel:[1,1,0] op_sel_hi:[1,0,1] neg_lo:[0,1,0]
	v_pk_mul_f32 v[80:81], v[84:85], v[76:77] op_sel:[0,0] op_sel_hi:[0,1]
	v_pk_add_f32 v[82:83], v[100:101], v[108:109] neg_lo:[0,1] neg_hi:[0,1]
	v_pk_fma_f32 v[76:77], v[84:85], v[76:77], v[80:81] op_sel:[1,1,0] op_sel_hi:[1,0,1] neg_lo:[0,1,0]
	v_pk_add_f32 v[80:81], v[100:101], v[108:109]
	v_pk_add_f32 v[84:85], v[102:103], v[110:111]
	v_pk_add_f32 v[100:101], v[72:73], v[98:99]
	v_pk_add_f32 v[96:97], v[80:81], v[84:85]
	v_pk_add_f32 v[80:81], v[80:81], v[84:85] neg_lo:[0,1] neg_hi:[0,1]
	v_pk_add_f32 v[84:85], v[82:83], v[92:93] op_sel:[0,1] op_sel_hi:[1,0] neg_hi:[0,1]
	v_pk_add_f32 v[82:83], v[82:83], v[92:93] op_sel:[0,1] op_sel_hi:[1,0] neg_lo:[0,1]
	v_pk_add_f32 v[92:93], v[112:113], v[90:91]
	v_pk_add_f32 v[90:91], v[112:113], v[90:91] neg_lo:[0,1] neg_hi:[0,1]
	v_pk_add_f32 v[72:73], v[72:73], v[98:99] neg_lo:[0,1] neg_hi:[0,1]
	v_pk_add_f32 v[98:99], v[92:93], v[100:101]
	v_pk_add_f32 v[92:93], v[92:93], v[100:101] neg_lo:[0,1] neg_hi:[0,1]
	v_pk_add_f32 v[100:101], v[90:91], v[72:73] op_sel:[0,1] op_sel_hi:[1,0] neg_hi:[0,1]
	v_pk_add_f32 v[72:73], v[90:91], v[72:73] op_sel:[0,1] op_sel_hi:[1,0] neg_lo:[0,1]
	v_pk_add_f32 v[90:91], v[86:87], v[74:75]
	v_pk_add_f32 v[74:75], v[86:87], v[74:75] neg_lo:[0,1] neg_hi:[0,1]
	v_pk_add_f32 v[86:87], v[68:69], v[88:89]
	v_pk_add_f32 v[68:69], v[68:69], v[88:89] neg_lo:[0,1] neg_hi:[0,1]
	v_pk_add_f32 v[88:89], v[90:91], v[86:87]
	v_pk_add_f32 v[86:87], v[90:91], v[86:87] neg_lo:[0,1] neg_hi:[0,1]
	v_pk_add_f32 v[90:91], v[74:75], v[68:69] op_sel:[0,1] op_sel_hi:[1,0] neg_hi:[0,1]
	v_pk_add_f32 v[68:69], v[74:75], v[68:69] op_sel:[0,1] op_sel_hi:[1,0] neg_lo:[0,1]
	v_pk_add_f32 v[74:75], v[78:79], v[70:71]
	v_pk_add_f32 v[70:71], v[78:79], v[70:71] neg_lo:[0,1] neg_hi:[0,1]
	v_pk_add_f32 v[78:79], v[66:67], v[76:77]
	v_pk_add_f32 v[66:67], v[66:67], v[76:77] neg_lo:[0,1] neg_hi:[0,1]
	v_pk_add_f32 v[76:77], v[74:75], v[78:79]
	v_pk_add_f32 v[74:75], v[74:75], v[78:79] neg_lo:[0,1] neg_hi:[0,1]
	v_pk_add_f32 v[78:79], v[70:71], v[66:67] op_sel:[0,1] op_sel_hi:[1,0] neg_hi:[0,1]
	v_pk_add_f32 v[66:67], v[70:71], v[66:67] op_sel:[0,1] op_sel_hi:[1,0] neg_lo:[0,1]
	v_pk_mul_f32 v[70:71], v[96:97], v[56:57] op_sel:[0,0] op_sel_hi:[0,1]
	v_pk_fma_f32 v[56:57], v[96:97], v[56:57], v[70:71] op_sel:[1,1,0] op_sel_hi:[1,0,1] neg_lo:[0,1,0]
	v_pk_mul_f32 v[70:71], v[84:85], v[64:65] op_sel:[0,0] op_sel_hi:[0,1]
	v_pk_fma_f32 v[64:65], v[84:85], v[64:65], v[70:71] op_sel:[1,1,0] op_sel_hi:[1,0,1] neg_lo:[0,1,0]
	v_pk_mul_f32 v[70:71], v[80:81], v[60:61] op_sel:[0,0] op_sel_hi:[0,1]
	v_pk_fma_f32 v[60:61], v[80:81], v[60:61], v[70:71] op_sel:[1,1,0] op_sel_hi:[1,0,1] neg_lo:[0,1,0]
	v_pk_mul_f32 v[70:71], v[82:83], v[62:63] op_sel:[0,0] op_sel_hi:[0,1]
	v_pk_fma_f32 v[62:63], v[82:83], v[62:63], v[70:71] op_sel:[1,1,0] op_sel_hi:[1,0,1] neg_lo:[0,1,0]
	v_pk_mul_f32 v[70:71], v[98:99], v[48:49] op_sel:[0,0] op_sel_hi:[0,1]
	v_pk_fma_f32 v[48:49], v[98:99], v[48:49], v[70:71] op_sel:[1,1,0] op_sel_hi:[1,0,1] neg_lo:[0,1,0]
	v_pk_mul_f32 v[70:71], v[100:101], v[58:59] op_sel:[0,0] op_sel_hi:[0,1]
	v_pk_fma_f32 v[58:59], v[100:101], v[58:59], v[70:71] op_sel:[1,1,0] op_sel_hi:[1,0,1] neg_lo:[0,1,0]
	v_pk_mul_f32 v[70:71], v[92:93], v[52:53] op_sel:[0,0] op_sel_hi:[0,1]
	v_pk_fma_f32 v[52:53], v[92:93], v[52:53], v[70:71] op_sel:[1,1,0] op_sel_hi:[1,0,1] neg_lo:[0,1,0]
	v_pk_mul_f32 v[70:71], v[72:73], v[54:55] op_sel:[0,0] op_sel_hi:[0,1]
	v_pk_fma_f32 v[54:55], v[72:73], v[54:55], v[70:71] op_sel:[1,1,0] op_sel_hi:[1,0,1] neg_lo:[0,1,0]
	v_pk_mul_f32 v[70:71], v[88:89], v[32:33] op_sel:[0,0] op_sel_hi:[0,1]
	v_pk_fma_f32 v[32:33], v[88:89], v[32:33], v[70:71] op_sel:[1,1,0] op_sel_hi:[1,0,1] neg_lo:[0,1,0]
	v_pk_mul_f32 v[70:71], v[90:91], v[50:51] op_sel:[0,0] op_sel_hi:[0,1]
	v_pk_fma_f32 v[50:51], v[90:91], v[50:51], v[70:71] op_sel:[1,1,0] op_sel_hi:[1,0,1] neg_lo:[0,1,0]
	v_pk_mul_f32 v[70:71], v[86:87], v[44:45] op_sel:[0,0] op_sel_hi:[0,1]
	v_pk_fma_f32 v[44:45], v[86:87], v[44:45], v[70:71] op_sel:[1,1,0] op_sel_hi:[1,0,1] neg_lo:[0,1,0]
	v_pk_mul_f32 v[70:71], v[68:69], v[46:47] op_sel:[0,0] op_sel_hi:[0,1]
	v_pk_fma_f32 v[46:47], v[68:69], v[46:47], v[70:71] op_sel:[1,1,0] op_sel_hi:[1,0,1] neg_lo:[0,1,0]
	v_pk_mul_f32 v[68:69], v[76:77], v[26:27] op_sel:[0,0] op_sel_hi:[0,1]
	v_pk_fma_f32 v[26:27], v[76:77], v[26:27], v[68:69] op_sel:[1,1,0] op_sel_hi:[1,0,1] neg_lo:[0,1,0]
	v_pk_mul_f32 v[68:69], v[78:79], v[42:43] op_sel:[0,0] op_sel_hi:[0,1]
	v_pk_fma_f32 v[42:43], v[78:79], v[42:43], v[68:69] op_sel:[1,1,0] op_sel_hi:[1,0,1] neg_lo:[0,1,0]
	v_pk_mul_f32 v[68:69], v[74:75], v[28:29] op_sel:[0,0] op_sel_hi:[0,1]
	v_pk_fma_f32 v[28:29], v[74:75], v[28:29], v[68:69] op_sel:[1,1,0] op_sel_hi:[1,0,1] neg_lo:[0,1,0]
	v_pk_mul_f32 v[68:69], v[66:67], v[30:31] op_sel:[0,0] op_sel_hi:[0,1]
	v_pk_fma_f32 v[30:31], v[66:67], v[30:31], v[68:69] op_sel:[1,1,0] op_sel_hi:[1,0,1] neg_lo:[0,1,0]
	s_cbranch_scc1 .LBB0_1413
	s_mul_i32 s83, s0, 0x4400
	s_mul_hi_u32 s1, s0, 0x4400
	s_add_u32 s28, s11, s83
	s_addc_u32 s29, s10, s1
	s_add_i32 s1, s0, 0x400
	s_add_i32 s87, s83, 0x1100000
	s_mul_hi_u32 s1, s1, 0x4400
	v_lshlrev_b32_e32 v2, 3, v145
	s_add_u32 s92, s11, s87
	v_ashrrev_i32_e32 v3, 31, v2
	s_addc_u32 s93, s10, s1
	s_addk_i32 s0, 0x800
	s_add_i32 s83, s83, 0x2200000
	v_lshlrev_b64 v[18:19], 1, v[2:3]
	v_add_u32_e32 v2, 0x1000, v2
	s_mul_hi_u32 s1, s0, 0x4400
	s_add_u32 s0, s11, s83
	v_ashrrev_i32_e32 v3, 31, v2
	s_addc_u32 s1, s10, s1
	v_lshlrev_b64 v[20:21], 1, v[2:3]
	v_lshl_add_u64 v[4:5], s[28:29], 0, v[18:19]
	v_lshl_add_u64 v[6:7], s[28:29], 0, v[20:21]
	v_lshl_add_u64 v[10:11], s[92:93], 0, v[18:19]
	v_lshl_add_u64 v[14:15], s[92:93], 0, v[20:21]
	v_lshl_add_u64 v[18:19], s[0:1], 0, v[18:19]
	v_lshl_add_u64 v[22:23], s[0:1], 0, v[20:21]
	global_load_dwordx4 v[2:5], v[4:5], off
	s_nop 0
	global_load_dwordx4 v[6:9], v[6:7], off
	s_nop 0
	global_load_dwordx4 v[10:13], v[10:11], off
	s_nop 0
	global_load_dwordx4 v[14:17], v[14:15], off
	s_nop 0
	global_load_dwordx4 v[18:21], v[18:19], off
	s_nop 0
	global_load_dwordx4 v[22:25], v[22:23], off
.LBB0_1413:
	v_pk_add_f32 v[66:67], v[56:57], v[60:61]
	v_pk_add_f32 v[56:57], v[56:57], v[60:61] neg_lo:[0,1] neg_hi:[0,1]
	v_pk_add_f32 v[60:61], v[64:65], v[62:63]
	v_pk_add_f32 v[62:63], v[64:65], v[62:63] neg_lo:[0,1] neg_hi:[0,1]
	v_pk_add_f32 v[64:65], v[66:67], v[60:61]
	v_pk_add_f32 v[60:61], v[66:67], v[60:61] neg_lo:[0,1] neg_hi:[0,1]
	v_pk_add_f32 v[66:67], v[56:57], v[62:63] op_sel:[0,1] op_sel_hi:[1,0] neg_lo:[0,1]
	v_pk_add_f32 v[56:57], v[56:57], v[62:63] op_sel:[0,1] op_sel_hi:[1,0] neg_hi:[0,1]
	v_pk_add_f32 v[62:63], v[48:49], v[52:53]
	v_pk_add_f32 v[48:49], v[48:49], v[52:53] neg_lo:[0,1] neg_hi:[0,1]
	v_pk_add_f32 v[52:53], v[58:59], v[54:55]
	v_pk_add_f32 v[54:55], v[58:59], v[54:55] neg_lo:[0,1] neg_hi:[0,1]
	v_pk_add_f32 v[58:59], v[62:63], v[52:53]
	v_pk_add_f32 v[52:53], v[62:63], v[52:53] neg_lo:[0,1] neg_hi:[0,1]
	v_pk_add_f32 v[62:63], v[48:49], v[54:55] op_sel:[0,1] op_sel_hi:[1,0] neg_lo:[0,1]
	v_pk_add_f32 v[48:49], v[48:49], v[54:55] op_sel:[0,1] op_sel_hi:[1,0] neg_hi:[0,1]
	v_pk_add_f32 v[54:55], v[32:33], v[44:45]
	v_pk_add_f32 v[32:33], v[32:33], v[44:45] neg_lo:[0,1] neg_hi:[0,1]
	v_pk_add_f32 v[44:45], v[50:51], v[46:47]
	v_pk_add_f32 v[46:47], v[50:51], v[46:47] neg_lo:[0,1] neg_hi:[0,1]
	v_pk_add_f32 v[50:51], v[54:55], v[44:45]
	v_pk_add_f32 v[44:45], v[54:55], v[44:45] neg_lo:[0,1] neg_hi:[0,1]
	v_pk_add_f32 v[54:55], v[32:33], v[46:47] op_sel:[0,1] op_sel_hi:[1,0] neg_lo:[0,1]
	v_pk_add_f32 v[46:47], v[32:33], v[46:47] op_sel:[0,1] op_sel_hi:[1,0] neg_hi:[0,1]
	v_pk_add_f32 v[32:33], v[26:27], v[28:29]
	v_pk_add_f32 v[26:27], v[26:27], v[28:29] neg_lo:[0,1] neg_hi:[0,1]
	v_pk_add_f32 v[28:29], v[42:43], v[30:31]
	v_pk_add_f32 v[30:31], v[42:43], v[30:31] neg_lo:[0,1] neg_hi:[0,1]
	v_pk_add_f32 v[68:69], v[32:33], v[28:29]
	v_pk_add_f32 v[70:71], v[32:33], v[28:29] neg_lo:[0,1] neg_hi:[0,1]
	v_pk_add_f32 v[42:43], v[26:27], v[30:31] op_sel:[0,1] op_sel_hi:[1,0] neg_lo:[0,1]
	v_pk_add_f32 v[72:73], v[26:27], v[30:31] op_sel:[0,1] op_sel_hi:[1,0] neg_hi:[0,1]
	v_mov_b64_e32 v[32:33], s[62:63]
	v_pk_mul_f32 v[26:27], v[62:63], v[32:33] op_sel:[0,0] op_sel_hi:[0,1]
	v_mov_b64_e32 v[28:29], s[64:65]
	v_pk_fma_f32 v[62:63], v[62:63], v[32:33], v[26:27] op_sel:[1,1,0] op_sel_hi:[1,0,1] neg_lo:[0,1,0]
	v_pk_mul_f32 v[26:27], v[54:55], v[28:29] op_sel:[0,0] op_sel_hi:[0,1]
	v_pk_fma_f32 v[54:55], v[54:55], v[28:29], v[26:27] op_sel:[1,1,0] op_sel_hi:[1,0,1] neg_lo:[0,1,0]
	v_mov_b64_e32 v[26:27], s[66:67]
	v_pk_mul_f32 v[30:31], v[42:43], v[26:27] op_sel:[0,0] op_sel_hi:[0,1]
	v_pk_fma_f32 v[74:75], v[42:43], v[26:27], v[30:31] op_sel:[1,1,0] op_sel_hi:[1,0,1] neg_lo:[0,1,0]
	v_pk_mul_f32 v[30:31], v[52:53], v[28:29] op_sel:[0,0] op_sel_hi:[0,1]
	v_mov_b64_e32 v[42:43], s[68:69]
	v_pk_fma_f32 v[52:53], v[52:53], v[28:29], v[30:31] op_sel:[1,1,0] op_sel_hi:[1,0,1] neg_lo:[0,1,0]
	v_pk_mul_f32 v[30:31], v[44:45], v[42:43] op_sel:[0,0] op_sel_hi:[0,1]
	v_pk_fma_f32 v[76:77], v[44:45], v[42:43], v[30:31] op_sel:[1,1,0] op_sel_hi:[1,0,1] neg_lo:[0,1,0]
	v_mov_b64_e32 v[30:31], s[70:71]
	v_pk_mul_f32 v[44:45], v[70:71], v[30:31] op_sel:[0,0] op_sel_hi:[0,1]
	v_pk_fma_f32 v[70:71], v[70:71], v[30:31], v[44:45] op_sel:[1,1,0] op_sel_hi:[1,0,1] neg_lo:[0,1,0]
	v_pk_mul_f32 v[44:45], v[48:49], v[26:27] op_sel:[0,0] op_sel_hi:[0,1]
	v_pk_fma_f32 v[48:49], v[48:49], v[26:27], v[44:45] op_sel:[1,1,0] op_sel_hi:[1,0,1] neg_lo:[0,1,0]
	v_pk_mul_f32 v[44:45], v[46:47], v[30:31] op_sel:[0,0] op_sel_hi:[0,1]
	v_pk_fma_f32 v[46:47], v[46:47], v[30:31], v[44:45] op_sel:[1,1,0] op_sel_hi:[1,0,1] neg_lo:[0,1,0]
	v_mov_b64_e32 v[44:45], s[72:73]
	v_pk_mul_f32 v[78:79], v[72:73], v[44:45] op_sel:[0,0] op_sel_hi:[0,1]
	v_pk_fma_f32 v[72:73], v[72:73], v[44:45], v[78:79] op_sel:[1,1,0] op_sel_hi:[1,0,1] neg_lo:[0,1,0]
	v_pk_add_f32 v[78:79], v[64:65], v[50:51]
	v_pk_add_f32 v[50:51], v[64:65], v[50:51] neg_lo:[0,1] neg_hi:[0,1]
	v_pk_add_f32 v[64:65], v[58:59], v[68:69]
	v_pk_add_f32 v[58:59], v[58:59], v[68:69] neg_lo:[0,1] neg_hi:[0,1]
	v_pk_add_f32 v[68:69], v[78:79], v[64:65]
	v_pk_add_f32 v[64:65], v[78:79], v[64:65] neg_lo:[0,1] neg_hi:[0,1]
	v_pk_add_f32 v[78:79], v[50:51], v[58:59] op_sel:[0,1] op_sel_hi:[1,0] neg_lo:[0,1]
	v_pk_add_f32 v[50:51], v[50:51], v[58:59] op_sel:[0,1] op_sel_hi:[1,0] neg_hi:[0,1]
	v_pk_add_f32 v[58:59], v[66:67], v[54:55]
	v_pk_add_f32 v[54:55], v[66:67], v[54:55] neg_lo:[0,1] neg_hi:[0,1]
	v_pk_add_f32 v[66:67], v[62:63], v[74:75]
	v_pk_add_f32 v[62:63], v[62:63], v[74:75] neg_lo:[0,1] neg_hi:[0,1]
	v_pk_add_f32 v[74:75], v[58:59], v[66:67]
	v_pk_add_f32 v[58:59], v[58:59], v[66:67] neg_lo:[0,1] neg_hi:[0,1]
	v_pk_add_f32 v[66:67], v[54:55], v[62:63] op_sel:[0,1] op_sel_hi:[1,0] neg_lo:[0,1]
	v_pk_add_f32 v[54:55], v[54:55], v[62:63] op_sel:[0,1] op_sel_hi:[1,0] neg_hi:[0,1]
	v_pk_add_f32 v[62:63], v[60:61], v[76:77]
	v_pk_add_f32 v[60:61], v[60:61], v[76:77] neg_lo:[0,1] neg_hi:[0,1]
	v_pk_add_f32 v[76:77], v[52:53], v[70:71]
	v_pk_add_f32 v[52:53], v[52:53], v[70:71] neg_lo:[0,1] neg_hi:[0,1]
	v_pk_add_f32 v[70:71], v[62:63], v[76:77]
	v_pk_add_f32 v[62:63], v[62:63], v[76:77] neg_lo:[0,1] neg_hi:[0,1]
	v_pk_add_f32 v[76:77], v[60:61], v[52:53] op_sel:[0,1] op_sel_hi:[1,0] neg_lo:[0,1]
	v_pk_add_f32 v[52:53], v[60:61], v[52:53] op_sel:[0,1] op_sel_hi:[1,0] neg_hi:[0,1]
	v_pk_add_f32 v[60:61], v[56:57], v[46:47]
	v_pk_add_f32 v[46:47], v[56:57], v[46:47] neg_lo:[0,1] neg_hi:[0,1]
	v_pk_add_f32 v[56:57], v[48:49], v[72:73]
	v_pk_add_f32 v[48:49], v[48:49], v[72:73] neg_lo:[0,1] neg_hi:[0,1]
	v_pk_add_f32 v[72:73], v[60:61], v[56:57]
	v_pk_add_f32 v[56:57], v[60:61], v[56:57] neg_lo:[0,1] neg_hi:[0,1]
	v_pk_add_f32 v[60:61], v[46:47], v[48:49] op_sel:[0,1] op_sel_hi:[1,0] neg_lo:[0,1]
	v_pk_add_f32 v[46:47], v[46:47], v[48:49] op_sel:[0,1] op_sel_hi:[1,0] neg_hi:[0,1]
	ds_write2_b64 v147, v[68:69], v[74:75] offset1:1
	ds_write2_b64 v147, v[70:71], v[72:73] offset0:2 offset1:3
	ds_write2_b64 v147, v[78:79], v[66:67] offset0:4 offset1:5
	ds_write2_b64 v147, v[76:77], v[60:61] offset0:6 offset1:7
	ds_write2_b64 v147, v[64:65], v[58:59] offset0:8 offset1:9
	ds_write2_b64 v147, v[62:63], v[56:57] offset0:10 offset1:11
	ds_write2_b64 v147, v[50:51], v[54:55] offset0:12 offset1:13
	ds_write2_b64 v147, v[52:53], v[46:47] offset0:14 offset1:15
	s_waitcnt lgkmcnt(0)
	s_barrier
	ds_read2_b64 v[46:49], v146 offset1:17
	ds_read2_b64 v[50:53], v146 offset0:34 offset1:51
	s_waitcnt lgkmcnt(1)
	v_pk_mul_f32 v[54:55], v[48:49], v[40:41] op_sel:[0,0] op_sel_hi:[0,1] neg_hi:[0,1]
	v_pk_fma_f32 v[56:57], v[48:49], v[40:41], v[54:55] op_sel:[1,1,0] op_sel_hi:[1,0,1]
	v_pk_mul_f32 v[48:49], v[40:41], v[40:41] op_sel:[0,0] op_sel_hi:[0,1]
	v_pk_fma_f32 v[48:49], v[40:41], v[40:41], v[48:49] op_sel:[1,1,0] op_sel_hi:[1,0,1] neg_lo:[0,1,0]
	s_waitcnt lgkmcnt(0)
	v_pk_mul_f32 v[54:55], v[50:51], v[48:49] op_sel:[0,0] op_sel_hi:[0,1] neg_hi:[0,1]
	v_pk_fma_f32 v[58:59], v[50:51], v[48:49], v[54:55] op_sel:[1,1,0] op_sel_hi:[1,0,1]
	v_pk_mul_f32 v[50:51], v[48:49], v[40:41] op_sel:[0,0] op_sel_hi:[0,1]
	v_pk_fma_f32 v[54:55], v[48:49], v[40:41], v[50:51] op_sel:[1,1,0] op_sel_hi:[1,0,1] neg_lo:[0,1,0]
	ds_read2_b64 v[48:51], v146 offset0:68 offset1:85
	v_pk_mul_f32 v[60:61], v[52:53], v[54:55] op_sel:[0,0] op_sel_hi:[0,1] neg_hi:[0,1]
	v_pk_fma_f32 v[60:61], v[52:53], v[54:55], v[60:61] op_sel:[1,1,0] op_sel_hi:[1,0,1]
	v_pk_mul_f32 v[52:53], v[54:55], v[40:41] op_sel:[0,0] op_sel_hi:[0,1]
	v_pk_fma_f32 v[52:53], v[54:55], v[40:41], v[52:53] op_sel:[1,1,0] op_sel_hi:[1,0,1] neg_lo:[0,1,0]
	s_waitcnt lgkmcnt(0)
	v_pk_mul_f32 v[54:55], v[48:49], v[52:53] op_sel:[0,0] op_sel_hi:[0,1] neg_hi:[0,1]
	v_pk_fma_f32 v[62:63], v[48:49], v[52:53], v[54:55] op_sel:[1,1,0] op_sel_hi:[1,0,1]
	v_pk_mul_f32 v[48:49], v[52:53], v[40:41] op_sel:[0,0] op_sel_hi:[0,1]
	v_pk_fma_f32 v[48:49], v[52:53], v[40:41], v[48:49] op_sel:[1,1,0] op_sel_hi:[1,0,1] neg_lo:[0,1,0]
	ds_read2_b64 v[52:55], v146 offset0:102 offset1:119
	v_pk_mul_f32 v[64:65], v[50:51], v[48:49] op_sel:[0,0] op_sel_hi:[0,1] neg_hi:[0,1]
	v_pk_fma_f32 v[64:65], v[50:51], v[48:49], v[64:65] op_sel:[1,1,0] op_sel_hi:[1,0,1]
	v_pk_mul_f32 v[50:51], v[48:49], v[40:41] op_sel:[0,0] op_sel_hi:[0,1]
	v_pk_fma_f32 v[48:49], v[48:49], v[40:41], v[50:51] op_sel:[1,1,0] op_sel_hi:[1,0,1] neg_lo:[0,1,0]
	s_waitcnt lgkmcnt(0)
	v_pk_mul_f32 v[50:51], v[52:53], v[48:49] op_sel:[0,0] op_sel_hi:[0,1] neg_hi:[0,1]
	v_pk_fma_f32 v[66:67], v[52:53], v[48:49], v[50:51] op_sel:[1,1,0] op_sel_hi:[1,0,1]
	v_pk_mul_f32 v[50:51], v[48:49], v[40:41] op_sel:[0,0] op_sel_hi:[0,1]
	v_pk_fma_f32 v[52:53], v[48:49], v[40:41], v[50:51] op_sel:[1,1,0] op_sel_hi:[1,0,1] neg_lo:[0,1,0]
	ds_read2_b64 v[48:51], v146 offset0:136 offset1:153
	v_pk_mul_f32 v[68:69], v[54:55], v[52:53] op_sel:[0,0] op_sel_hi:[0,1] neg_hi:[0,1]
	v_pk_fma_f32 v[68:69], v[54:55], v[52:53], v[68:69] op_sel:[1,1,0] op_sel_hi:[1,0,1]
	v_pk_mul_f32 v[54:55], v[52:53], v[40:41] op_sel:[0,0] op_sel_hi:[0,1]
	v_pk_fma_f32 v[52:53], v[52:53], v[40:41], v[54:55] op_sel:[1,1,0] op_sel_hi:[1,0,1] neg_lo:[0,1,0]
	s_waitcnt lgkmcnt(0)
	v_pk_mul_f32 v[54:55], v[48:49], v[52:53] op_sel:[0,0] op_sel_hi:[0,1] neg_hi:[0,1]
	v_pk_fma_f32 v[70:71], v[48:49], v[52:53], v[54:55] op_sel:[1,1,0] op_sel_hi:[1,0,1]
	v_pk_mul_f32 v[48:49], v[52:53], v[40:41] op_sel:[0,0] op_sel_hi:[0,1]
	v_pk_fma_f32 v[48:49], v[52:53], v[40:41], v[48:49] op_sel:[1,1,0] op_sel_hi:[1,0,1] neg_lo:[0,1,0]
	ds_read2_b64 v[52:55], v146 offset0:170 offset1:187
	v_pk_mul_f32 v[72:73], v[50:51], v[48:49] op_sel:[0,0] op_sel_hi:[0,1] neg_hi:[0,1]
	v_pk_fma_f32 v[72:73], v[50:51], v[48:49], v[72:73] op_sel:[1,1,0] op_sel_hi:[1,0,1]
	v_pk_mul_f32 v[50:51], v[48:49], v[40:41] op_sel:[0,0] op_sel_hi:[0,1]
	v_pk_fma_f32 v[48:49], v[48:49], v[40:41], v[50:51] op_sel:[1,1,0] op_sel_hi:[1,0,1] neg_lo:[0,1,0]
	s_waitcnt lgkmcnt(0)
	v_pk_mul_f32 v[50:51], v[52:53], v[48:49] op_sel:[0,0] op_sel_hi:[0,1] neg_hi:[0,1]
	v_pk_fma_f32 v[74:75], v[52:53], v[48:49], v[50:51] op_sel:[1,1,0] op_sel_hi:[1,0,1]
	v_pk_mul_f32 v[50:51], v[48:49], v[40:41] op_sel:[0,0] op_sel_hi:[0,1]
	v_pk_fma_f32 v[52:53], v[48:49], v[40:41], v[50:51] op_sel:[1,1,0] op_sel_hi:[1,0,1] neg_lo:[0,1,0]
	ds_read2_b64 v[48:51], v146 offset0:204 offset1:221
	v_pk_mul_f32 v[76:77], v[54:55], v[52:53] op_sel:[0,0] op_sel_hi:[0,1] neg_hi:[0,1]
	v_pk_fma_f32 v[76:77], v[54:55], v[52:53], v[76:77] op_sel:[1,1,0] op_sel_hi:[1,0,1]
	v_pk_mul_f32 v[54:55], v[52:53], v[40:41] op_sel:[0,0] op_sel_hi:[0,1]
	v_pk_fma_f32 v[52:53], v[52:53], v[40:41], v[54:55] op_sel:[1,1,0] op_sel_hi:[1,0,1] neg_lo:[0,1,0]
	s_waitcnt lgkmcnt(0)
	v_pk_mul_f32 v[54:55], v[48:49], v[52:53] op_sel:[0,0] op_sel_hi:[0,1] neg_hi:[0,1]
	v_pk_fma_f32 v[48:49], v[48:49], v[52:53], v[54:55] op_sel:[1,1,0] op_sel_hi:[1,0,1]
	v_pk_mul_f32 v[54:55], v[52:53], v[40:41] op_sel:[0,0] op_sel_hi:[0,1]
	v_pk_fma_f32 v[78:79], v[52:53], v[40:41], v[54:55] op_sel:[1,1,0] op_sel_hi:[1,0,1] neg_lo:[0,1,0]
	ds_read2_b64 v[52:55], v146 offset0:238 offset1:255
	v_pk_mul_f32 v[80:81], v[50:51], v[78:79] op_sel:[0,0] op_sel_hi:[0,1] neg_hi:[0,1]
	v_pk_fma_f32 v[50:51], v[50:51], v[78:79], v[80:81] op_sel:[1,1,0] op_sel_hi:[1,0,1]
	v_pk_mul_f32 v[80:81], v[78:79], v[40:41] op_sel:[0,0] op_sel_hi:[0,1]
	v_pk_fma_f32 v[78:79], v[78:79], v[40:41], v[80:81] op_sel:[1,1,0] op_sel_hi:[1,0,1] neg_lo:[0,1,0]
	s_waitcnt lgkmcnt(0)
	v_pk_mul_f32 v[80:81], v[52:53], v[78:79] op_sel:[0,0] op_sel_hi:[0,1] neg_hi:[0,1]
	v_pk_fma_f32 v[52:53], v[52:53], v[78:79], v[80:81] op_sel:[1,1,0] op_sel_hi:[1,0,1]
	v_pk_mul_f32 v[80:81], v[78:79], v[40:41] op_sel:[0,0] op_sel_hi:[0,1]
	v_pk_fma_f32 v[40:41], v[78:79], v[40:41], v[80:81] op_sel:[1,1,0] op_sel_hi:[1,0,1] neg_lo:[0,1,0]
	v_pk_mul_f32 v[78:79], v[54:55], v[40:41] op_sel:[0,0] op_sel_hi:[0,1] neg_hi:[0,1]
	v_pk_fma_f32 v[40:41], v[54:55], v[40:41], v[78:79] op_sel:[1,1,0] op_sel_hi:[1,0,1]
	v_pk_add_f32 v[54:55], v[46:47], v[70:71]
	v_pk_add_f32 v[46:47], v[46:47], v[70:71] neg_lo:[0,1] neg_hi:[0,1]
	v_pk_add_f32 v[70:71], v[62:63], v[48:49]
	v_pk_add_f32 v[48:49], v[62:63], v[48:49] neg_lo:[0,1] neg_hi:[0,1]
	v_pk_add_f32 v[62:63], v[54:55], v[70:71]
	v_pk_add_f32 v[54:55], v[54:55], v[70:71] neg_lo:[0,1] neg_hi:[0,1]
	v_pk_add_f32 v[70:71], v[46:47], v[48:49] op_sel:[0,1] op_sel_hi:[1,0] neg_lo:[0,1]
	v_pk_add_f32 v[46:47], v[46:47], v[48:49] op_sel:[0,1] op_sel_hi:[1,0] neg_hi:[0,1]
	v_pk_add_f32 v[48:49], v[56:57], v[72:73]
	v_pk_add_f32 v[56:57], v[56:57], v[72:73] neg_lo:[0,1] neg_hi:[0,1]
	v_pk_add_f32 v[72:73], v[64:65], v[50:51]
	v_pk_add_f32 v[50:51], v[64:65], v[50:51] neg_lo:[0,1] neg_hi:[0,1]
	v_pk_add_f32 v[64:65], v[48:49], v[72:73]
	v_pk_add_f32 v[48:49], v[48:49], v[72:73] neg_lo:[0,1] neg_hi:[0,1]
	v_pk_add_f32 v[72:73], v[56:57], v[50:51] op_sel:[0,1] op_sel_hi:[1,0] neg_lo:[0,1]
	v_pk_add_f32 v[50:51], v[56:57], v[50:51] op_sel:[0,1] op_sel_hi:[1,0] neg_hi:[0,1]
	v_pk_add_f32 v[56:57], v[58:59], v[74:75]
	v_pk_add_f32 v[58:59], v[58:59], v[74:75] neg_lo:[0,1] neg_hi:[0,1]
	v_pk_add_f32 v[74:75], v[66:67], v[52:53]
	v_pk_add_f32 v[52:53], v[66:67], v[52:53] neg_lo:[0,1] neg_hi:[0,1]
	v_pk_add_f32 v[66:67], v[56:57], v[74:75]
	v_pk_add_f32 v[56:57], v[56:57], v[74:75] neg_lo:[0,1] neg_hi:[0,1]
	v_pk_add_f32 v[74:75], v[58:59], v[52:53] op_sel:[0,1] op_sel_hi:[1,0] neg_lo:[0,1]
	v_pk_add_f32 v[52:53], v[58:59], v[52:53] op_sel:[0,1] op_sel_hi:[1,0] neg_hi:[0,1]
	v_pk_add_f32 v[58:59], v[60:61], v[76:77]
	v_pk_add_f32 v[60:61], v[60:61], v[76:77] neg_lo:[0,1] neg_hi:[0,1]
	v_pk_add_f32 v[76:77], v[68:69], v[40:41]
	v_pk_add_f32 v[40:41], v[68:69], v[40:41] neg_lo:[0,1] neg_hi:[0,1]
	v_pk_add_f32 v[68:69], v[58:59], v[76:77]
	v_pk_add_f32 v[58:59], v[58:59], v[76:77] neg_lo:[0,1] neg_hi:[0,1]
	v_pk_add_f32 v[76:77], v[60:61], v[40:41] op_sel:[0,1] op_sel_hi:[1,0] neg_lo:[0,1]
	v_pk_add_f32 v[40:41], v[60:61], v[40:41] op_sel:[0,1] op_sel_hi:[1,0] neg_hi:[0,1]
	v_pk_mul_f32 v[60:61], v[72:73], v[32:33] op_sel:[0,0] op_sel_hi:[0,1]
	v_pk_fma_f32 v[60:61], v[72:73], v[32:33], v[60:61] op_sel:[1,1,0] op_sel_hi:[1,0,1] neg_lo:[0,1,0]
	v_pk_mul_f32 v[72:73], v[74:75], v[28:29] op_sel:[0,0] op_sel_hi:[0,1]
	v_pk_fma_f32 v[72:73], v[74:75], v[28:29], v[72:73] op_sel:[1,1,0] op_sel_hi:[1,0,1] neg_lo:[0,1,0]
	v_pk_mul_f32 v[74:75], v[76:77], v[26:27] op_sel:[0,0] op_sel_hi:[0,1]
	v_pk_fma_f32 v[74:75], v[76:77], v[26:27], v[74:75] op_sel:[1,1,0] op_sel_hi:[1,0,1] neg_lo:[0,1,0]
	v_pk_mul_f32 v[76:77], v[48:49], v[28:29] op_sel:[0,0] op_sel_hi:[0,1]
	v_pk_fma_f32 v[48:49], v[48:49], v[28:29], v[76:77] op_sel:[1,1,0] op_sel_hi:[1,0,1] neg_lo:[0,1,0]
	v_pk_mul_f32 v[76:77], v[56:57], v[42:43] op_sel:[0,0] op_sel_hi:[0,1]
	v_pk_fma_f32 v[56:57], v[56:57], v[42:43], v[76:77] op_sel:[1,1,0] op_sel_hi:[1,0,1] neg_lo:[0,1,0]
	v_pk_mul_f32 v[76:77], v[58:59], v[30:31] op_sel:[0,0] op_sel_hi:[0,1]
	v_pk_fma_f32 v[58:59], v[58:59], v[30:31], v[76:77] op_sel:[1,1,0] op_sel_hi:[1,0,1] neg_lo:[0,1,0]
	v_pk_mul_f32 v[76:77], v[50:51], v[26:27] op_sel:[0,0] op_sel_hi:[0,1]
	v_pk_fma_f32 v[50:51], v[50:51], v[26:27], v[76:77] op_sel:[1,1,0] op_sel_hi:[1,0,1] neg_lo:[0,1,0]
	v_pk_mul_f32 v[76:77], v[52:53], v[30:31] op_sel:[0,0] op_sel_hi:[0,1]
	v_pk_fma_f32 v[52:53], v[52:53], v[30:31], v[76:77] op_sel:[1,1,0] op_sel_hi:[1,0,1] neg_lo:[0,1,0]
	v_pk_mul_f32 v[76:77], v[40:41], v[44:45] op_sel:[0,0] op_sel_hi:[0,1]
	v_pk_fma_f32 v[40:41], v[40:41], v[44:45], v[76:77] op_sel:[1,1,0] op_sel_hi:[1,0,1] neg_lo:[0,1,0]
	v_pk_add_f32 v[76:77], v[62:63], v[66:67]
	v_pk_add_f32 v[62:63], v[62:63], v[66:67] neg_lo:[0,1] neg_hi:[0,1]
	v_pk_add_f32 v[66:67], v[64:65], v[68:69]
	v_pk_add_f32 v[64:65], v[64:65], v[68:69] neg_lo:[0,1] neg_hi:[0,1]
	v_pk_add_f32 v[68:69], v[76:77], v[66:67]
	v_pk_add_f32 v[66:67], v[76:77], v[66:67] neg_lo:[0,1] neg_hi:[0,1]
	v_pk_add_f32 v[76:77], v[62:63], v[64:65] op_sel:[0,1] op_sel_hi:[1,0] neg_lo:[0,1]
	v_pk_add_f32 v[62:63], v[62:63], v[64:65] op_sel:[0,1] op_sel_hi:[1,0] neg_hi:[0,1]
	v_pk_add_f32 v[64:65], v[70:71], v[72:73]
	v_pk_add_f32 v[70:71], v[70:71], v[72:73] neg_lo:[0,1] neg_hi:[0,1]
	v_pk_add_f32 v[72:73], v[60:61], v[74:75]
	v_pk_add_f32 v[60:61], v[60:61], v[74:75] neg_lo:[0,1] neg_hi:[0,1]
	v_pk_add_f32 v[74:75], v[64:65], v[72:73]
	v_pk_add_f32 v[64:65], v[64:65], v[72:73] neg_lo:[0,1] neg_hi:[0,1]
	v_pk_add_f32 v[72:73], v[70:71], v[60:61] op_sel:[0,1] op_sel_hi:[1,0] neg_lo:[0,1]
	v_pk_add_f32 v[60:61], v[70:71], v[60:61] op_sel:[0,1] op_sel_hi:[1,0] neg_hi:[0,1]
	v_pk_add_f32 v[70:71], v[54:55], v[56:57]
	v_pk_add_f32 v[54:55], v[54:55], v[56:57] neg_lo:[0,1] neg_hi:[0,1]
	v_pk_add_f32 v[56:57], v[48:49], v[58:59]
	v_pk_add_f32 v[48:49], v[48:49], v[58:59] neg_lo:[0,1] neg_hi:[0,1]
	v_pk_add_f32 v[58:59], v[70:71], v[56:57]
	v_pk_add_f32 v[56:57], v[70:71], v[56:57] neg_lo:[0,1] neg_hi:[0,1]
	v_pk_add_f32 v[70:71], v[54:55], v[48:49] op_sel:[0,1] op_sel_hi:[1,0] neg_lo:[0,1]
	v_pk_add_f32 v[48:49], v[54:55], v[48:49] op_sel:[0,1] op_sel_hi:[1,0] neg_hi:[0,1]
	v_pk_add_f32 v[54:55], v[46:47], v[52:53]
	v_pk_add_f32 v[46:47], v[46:47], v[52:53] neg_lo:[0,1] neg_hi:[0,1]
	v_pk_add_f32 v[52:53], v[50:51], v[40:41]
	v_pk_add_f32 v[40:41], v[50:51], v[40:41] neg_lo:[0,1] neg_hi:[0,1]
	v_pk_add_f32 v[50:51], v[54:55], v[52:53]
	v_pk_add_f32 v[52:53], v[54:55], v[52:53] neg_lo:[0,1] neg_hi:[0,1]
	v_pk_add_f32 v[54:55], v[46:47], v[40:41] op_sel:[0,1] op_sel_hi:[1,0] neg_lo:[0,1]
	v_pk_add_f32 v[40:41], v[46:47], v[40:41] op_sel:[0,1] op_sel_hi:[1,0] neg_hi:[0,1]
	ds_write2_b64 v146, v[68:69], v[74:75] offset1:17
	ds_write2_b64 v146, v[58:59], v[50:51] offset0:34 offset1:51
	ds_write2_b64 v146, v[76:77], v[72:73] offset0:68 offset1:85
	ds_write2_b64 v146, v[70:71], v[54:55] offset0:102 offset1:119
	ds_write2_b64 v146, v[66:67], v[64:65] offset0:136 offset1:153
	ds_write2_b64 v146, v[56:57], v[52:53] offset0:170 offset1:187
	ds_write2_b64 v146, v[62:63], v[60:61] offset0:204 offset1:221
	ds_write2_b64 v146, v[48:49], v[40:41] offset0:238 offset1:255
	s_waitcnt lgkmcnt(0)
	s_barrier
	ds_read_b64 v[40:41], v144 offset:2176
	ds_read_b64 v[46:47], v144 offset:4352
	ds_read_b64 v[48:49], v144 offset:6528
	ds_read_b64 v[50:51], v144
	s_waitcnt lgkmcnt(3)
	v_pk_mul_f32 v[52:53], v[40:41], v[38:39] op_sel:[0,0] op_sel_hi:[0,1] neg_hi:[0,1]
	v_pk_fma_f32 v[40:41], v[40:41], v[38:39], v[52:53] op_sel:[1,1,0] op_sel_hi:[1,0,1]
	v_pk_mul_f32 v[52:53], v[38:39], v[38:39] op_sel:[0,0] op_sel_hi:[0,1]
	ds_read_b64 v[56:57], v144 offset:8704
	v_pk_fma_f32 v[52:53], v[38:39], v[38:39], v[52:53] op_sel:[1,1,0] op_sel_hi:[1,0,1] neg_lo:[0,1,0]
	s_waitcnt lgkmcnt(3)
	v_pk_mul_f32 v[54:55], v[46:47], v[52:53] op_sel:[0,0] op_sel_hi:[0,1] neg_hi:[0,1]
	v_pk_fma_f32 v[46:47], v[46:47], v[52:53], v[54:55] op_sel:[1,1,0] op_sel_hi:[1,0,1]
	v_pk_mul_f32 v[54:55], v[52:53], v[38:39] op_sel:[0,0] op_sel_hi:[0,1]
	v_pk_fma_f32 v[52:53], v[52:53], v[38:39], v[54:55] op_sel:[1,1,0] op_sel_hi:[1,0,1] neg_lo:[0,1,0]
	s_waitcnt lgkmcnt(2)
	v_pk_mul_f32 v[54:55], v[48:49], v[52:53] op_sel:[0,0] op_sel_hi:[0,1] neg_hi:[0,1]
	v_pk_fma_f32 v[48:49], v[48:49], v[52:53], v[54:55] op_sel:[1,1,0] op_sel_hi:[1,0,1]
	v_pk_mul_f32 v[54:55], v[52:53], v[38:39] op_sel:[0,0] op_sel_hi:[0,1]
	v_pk_fma_f32 v[52:53], v[52:53], v[38:39], v[54:55] op_sel:[1,1,0] op_sel_hi:[1,0,1] neg_lo:[0,1,0]
	ds_read_b64 v[54:55], v144 offset:10880
	ds_read_b64 v[58:59], v144 offset:13056
	ds_read_b64 v[60:61], v144 offset:15232
	s_waitcnt lgkmcnt(3)
	v_pk_mul_f32 v[62:63], v[56:57], v[52:53] op_sel:[0,0] op_sel_hi:[0,1] neg_hi:[0,1]
	ds_read_b64 v[64:65], v144 offset:17408
	v_pk_fma_f32 v[56:57], v[56:57], v[52:53], v[62:63] op_sel:[1,1,0] op_sel_hi:[1,0,1]
	v_pk_mul_f32 v[62:63], v[52:53], v[38:39] op_sel:[0,0] op_sel_hi:[0,1]
	v_pk_fma_f32 v[52:53], v[52:53], v[38:39], v[62:63] op_sel:[1,1,0] op_sel_hi:[1,0,1] neg_lo:[0,1,0]
	s_waitcnt lgkmcnt(3)
	v_pk_mul_f32 v[62:63], v[54:55], v[52:53] op_sel:[0,0] op_sel_hi:[0,1] neg_hi:[0,1]
	v_pk_fma_f32 v[54:55], v[54:55], v[52:53], v[62:63] op_sel:[1,1,0] op_sel_hi:[1,0,1]
	v_pk_mul_f32 v[62:63], v[52:53], v[38:39] op_sel:[0,0] op_sel_hi:[0,1]
	v_pk_fma_f32 v[52:53], v[52:53], v[38:39], v[62:63] op_sel:[1,1,0] op_sel_hi:[1,0,1] neg_lo:[0,1,0]
	s_waitcnt lgkmcnt(2)
	v_pk_mul_f32 v[62:63], v[58:59], v[52:53] op_sel:[0,0] op_sel_hi:[0,1] neg_hi:[0,1]
	v_pk_fma_f32 v[58:59], v[58:59], v[52:53], v[62:63] op_sel:[1,1,0] op_sel_hi:[1,0,1]
	v_pk_mul_f32 v[62:63], v[52:53], v[38:39] op_sel:[0,0] op_sel_hi:[0,1]
	v_pk_fma_f32 v[52:53], v[52:53], v[38:39], v[62:63] op_sel:[1,1,0] op_sel_hi:[1,0,1] neg_lo:[0,1,0]
	s_waitcnt lgkmcnt(1)
	v_pk_mul_f32 v[62:63], v[60:61], v[52:53] op_sel:[0,0] op_sel_hi:[0,1] neg_hi:[0,1]
	v_pk_fma_f32 v[60:61], v[60:61], v[52:53], v[62:63] op_sel:[1,1,0] op_sel_hi:[1,0,1]
	v_pk_mul_f32 v[62:63], v[52:53], v[38:39] op_sel:[0,0] op_sel_hi:[0,1]
	v_pk_fma_f32 v[52:53], v[52:53], v[38:39], v[62:63] op_sel:[1,1,0] op_sel_hi:[1,0,1] neg_lo:[0,1,0]
	ds_read_b64 v[62:63], v144 offset:19584
	ds_read_b64 v[66:67], v144 offset:21760
	ds_read_b64 v[68:69], v144 offset:23936
	s_waitcnt lgkmcnt(3)
	v_pk_mul_f32 v[70:71], v[64:65], v[52:53] op_sel:[0,0] op_sel_hi:[0,1] neg_hi:[0,1]
	ds_read_b64 v[72:73], v144 offset:26112
	v_pk_fma_f32 v[64:65], v[64:65], v[52:53], v[70:71] op_sel:[1,1,0] op_sel_hi:[1,0,1]
	v_pk_mul_f32 v[70:71], v[52:53], v[38:39] op_sel:[0,0] op_sel_hi:[0,1]
	v_pk_fma_f32 v[52:53], v[52:53], v[38:39], v[70:71] op_sel:[1,1,0] op_sel_hi:[1,0,1] neg_lo:[0,1,0]
	s_waitcnt lgkmcnt(3)
	v_pk_mul_f32 v[70:71], v[62:63], v[52:53] op_sel:[0,0] op_sel_hi:[0,1] neg_hi:[0,1]
	v_pk_fma_f32 v[62:63], v[62:63], v[52:53], v[70:71] op_sel:[1,1,0] op_sel_hi:[1,0,1]
	v_pk_mul_f32 v[70:71], v[52:53], v[38:39] op_sel:[0,0] op_sel_hi:[0,1]
	v_pk_fma_f32 v[52:53], v[52:53], v[38:39], v[70:71] op_sel:[1,1,0] op_sel_hi:[1,0,1] neg_lo:[0,1,0]
	s_waitcnt lgkmcnt(2)
	v_pk_mul_f32 v[70:71], v[66:67], v[52:53] op_sel:[0,0] op_sel_hi:[0,1] neg_hi:[0,1]
	v_pk_fma_f32 v[66:67], v[66:67], v[52:53], v[70:71] op_sel:[1,1,0] op_sel_hi:[1,0,1]
	v_pk_mul_f32 v[70:71], v[52:53], v[38:39] op_sel:[0,0] op_sel_hi:[0,1]
	v_pk_fma_f32 v[52:53], v[52:53], v[38:39], v[70:71] op_sel:[1,1,0] op_sel_hi:[1,0,1] neg_lo:[0,1,0]
	s_waitcnt lgkmcnt(1)
	v_pk_mul_f32 v[70:71], v[68:69], v[52:53] op_sel:[0,0] op_sel_hi:[0,1] neg_hi:[0,1]
	v_pk_fma_f32 v[68:69], v[68:69], v[52:53], v[70:71] op_sel:[1,1,0] op_sel_hi:[1,0,1]
	v_pk_mul_f32 v[70:71], v[52:53], v[38:39] op_sel:[0,0] op_sel_hi:[0,1]
	v_pk_fma_f32 v[52:53], v[52:53], v[38:39], v[70:71] op_sel:[1,1,0] op_sel_hi:[1,0,1] neg_lo:[0,1,0]
	ds_read_b64 v[70:71], v144 offset:28288
	ds_read_b64 v[74:75], v144 offset:30464
	ds_read_b64 v[76:77], v144 offset:32640
	s_waitcnt lgkmcnt(3)
	v_pk_mul_f32 v[78:79], v[72:73], v[52:53] op_sel:[0,0] op_sel_hi:[0,1] neg_hi:[0,1]
	s_nop 0
	v_pk_fma_f32 v[72:73], v[72:73], v[52:53], v[78:79] op_sel:[1,1,0] op_sel_hi:[1,0,1]
	v_pk_mul_f32 v[78:79], v[52:53], v[38:39] op_sel:[0,0] op_sel_hi:[0,1]
	v_pk_fma_f32 v[52:53], v[52:53], v[38:39], v[78:79] op_sel:[1,1,0] op_sel_hi:[1,0,1] neg_lo:[0,1,0]
	s_waitcnt lgkmcnt(2)
	v_pk_mul_f32 v[78:79], v[70:71], v[52:53] op_sel:[0,0] op_sel_hi:[0,1] neg_hi:[0,1]
	v_pk_fma_f32 v[70:71], v[70:71], v[52:53], v[78:79] op_sel:[1,1,0] op_sel_hi:[1,0,1]
	v_pk_mul_f32 v[78:79], v[52:53], v[38:39] op_sel:[0,0] op_sel_hi:[0,1]
	v_pk_fma_f32 v[52:53], v[52:53], v[38:39], v[78:79] op_sel:[1,1,0] op_sel_hi:[1,0,1] neg_lo:[0,1,0]
	s_waitcnt lgkmcnt(1)
	v_pk_mul_f32 v[78:79], v[74:75], v[52:53] op_sel:[0,0] op_sel_hi:[0,1] neg_hi:[0,1]
	v_pk_fma_f32 v[74:75], v[74:75], v[52:53], v[78:79] op_sel:[1,1,0] op_sel_hi:[1,0,1]
	v_pk_mul_f32 v[78:79], v[52:53], v[38:39] op_sel:[0,0] op_sel_hi:[0,1]
	v_pk_fma_f32 v[38:39], v[52:53], v[38:39], v[78:79] op_sel:[1,1,0] op_sel_hi:[1,0,1] neg_lo:[0,1,0]
	s_waitcnt lgkmcnt(0)
	v_pk_mul_f32 v[52:53], v[76:77], v[38:39] op_sel:[0,0] op_sel_hi:[0,1] neg_hi:[0,1]
	v_pk_fma_f32 v[38:39], v[76:77], v[38:39], v[52:53] op_sel:[1,1,0] op_sel_hi:[1,0,1]
	v_pk_add_f32 v[52:53], v[50:51], v[64:65]
	v_pk_add_f32 v[50:51], v[50:51], v[64:65] neg_lo:[0,1] neg_hi:[0,1]
	v_pk_add_f32 v[64:65], v[56:57], v[72:73]
	v_pk_add_f32 v[56:57], v[56:57], v[72:73] neg_lo:[0,1] neg_hi:[0,1]
	v_pk_add_f32 v[72:73], v[52:53], v[64:65]
	v_pk_add_f32 v[76:77], v[50:51], v[56:57] op_sel:[0,1] op_sel_hi:[1,0] neg_lo:[0,1]
	v_pk_add_f32 v[78:79], v[50:51], v[56:57] op_sel:[0,1] op_sel_hi:[1,0] neg_hi:[0,1]
	v_pk_add_f32 v[50:51], v[40:41], v[62:63]
	v_pk_add_f32 v[40:41], v[40:41], v[62:63] neg_lo:[0,1] neg_hi:[0,1]
	v_pk_add_f32 v[56:57], v[54:55], v[70:71]
	v_pk_add_f32 v[54:55], v[54:55], v[70:71] neg_lo:[0,1] neg_hi:[0,1]
	v_pk_add_f32 v[52:53], v[52:53], v[64:65] neg_lo:[0,1] neg_hi:[0,1]
	v_pk_add_f32 v[62:63], v[50:51], v[56:57]
	v_pk_add_f32 v[50:51], v[50:51], v[56:57] neg_lo:[0,1] neg_hi:[0,1]
	v_pk_add_f32 v[56:57], v[40:41], v[54:55] op_sel:[0,1] op_sel_hi:[1,0] neg_lo:[0,1]
	v_pk_add_f32 v[40:41], v[40:41], v[54:55] op_sel:[0,1] op_sel_hi:[1,0] neg_hi:[0,1]
	v_pk_add_f32 v[54:55], v[46:47], v[66:67]
	v_pk_add_f32 v[46:47], v[46:47], v[66:67] neg_lo:[0,1] neg_hi:[0,1]
	v_pk_add_f32 v[64:65], v[58:59], v[74:75]
	v_pk_add_f32 v[58:59], v[58:59], v[74:75] neg_lo:[0,1] neg_hi:[0,1]
	v_pk_add_f32 v[66:67], v[54:55], v[64:65]
	v_pk_add_f32 v[54:55], v[54:55], v[64:65] neg_lo:[0,1] neg_hi:[0,1]
	v_pk_add_f32 v[64:65], v[46:47], v[58:59] op_sel:[0,1] op_sel_hi:[1,0] neg_lo:[0,1]
	v_pk_add_f32 v[46:47], v[46:47], v[58:59] op_sel:[0,1] op_sel_hi:[1,0] neg_hi:[0,1]
	v_pk_add_f32 v[58:59], v[48:49], v[68:69]
	v_pk_add_f32 v[48:49], v[48:49], v[68:69] neg_lo:[0,1] neg_hi:[0,1]
	v_pk_add_f32 v[68:69], v[60:61], v[38:39]
	v_pk_add_f32 v[38:39], v[60:61], v[38:39] neg_lo:[0,1] neg_hi:[0,1]
	v_pk_add_f32 v[60:61], v[58:59], v[68:69]
	v_pk_add_f32 v[58:59], v[58:59], v[68:69] neg_lo:[0,1] neg_hi:[0,1]
	v_pk_add_f32 v[68:69], v[48:49], v[38:39] op_sel:[0,1] op_sel_hi:[1,0] neg_lo:[0,1]
	v_pk_add_f32 v[38:39], v[48:49], v[38:39] op_sel:[0,1] op_sel_hi:[1,0] neg_hi:[0,1]
	v_pk_mul_f32 v[48:49], v[56:57], v[32:33] op_sel:[0,0] op_sel_hi:[0,1]
	v_pk_fma_f32 v[32:33], v[56:57], v[32:33], v[48:49] op_sel:[1,1,0] op_sel_hi:[1,0,1] neg_lo:[0,1,0]
	v_pk_mul_f32 v[48:49], v[64:65], v[28:29] op_sel:[0,0] op_sel_hi:[0,1]
	v_pk_mul_f32 v[56:57], v[68:69], v[26:27] op_sel:[0,0] op_sel_hi:[0,1]
	v_pk_fma_f32 v[48:49], v[64:65], v[28:29], v[48:49] op_sel:[1,1,0] op_sel_hi:[1,0,1] neg_lo:[0,1,0]
	v_pk_fma_f32 v[56:57], v[68:69], v[26:27], v[56:57] op_sel:[1,1,0] op_sel_hi:[1,0,1] neg_lo:[0,1,0]
	v_pk_mul_f32 v[64:65], v[50:51], v[28:29] op_sel:[0,0] op_sel_hi:[0,1]
	v_pk_fma_f32 v[68:69], v[50:51], v[28:29], v[64:65] op_sel:[1,1,0] op_sel_hi:[1,0,1] neg_lo:[0,1,0]
	v_pk_mul_f32 v[28:29], v[54:55], v[42:43] op_sel:[0,0] op_sel_hi:[0,1]
	v_pk_fma_f32 v[54:55], v[54:55], v[42:43], v[28:29] op_sel:[1,1,0] op_sel_hi:[1,0,1] neg_lo:[0,1,0]
	v_pk_mul_f32 v[28:29], v[58:59], v[30:31] op_sel:[0,0] op_sel_hi:[0,1]
	v_pk_add_f32 v[42:43], v[62:63], v[60:61]
	v_pk_fma_f32 v[58:59], v[58:59], v[30:31], v[28:29] op_sel:[1,1,0] op_sel_hi:[1,0,1] neg_lo:[0,1,0]
	v_pk_mul_f32 v[28:29], v[40:41], v[26:27] op_sel:[0,0] op_sel_hi:[0,1]
	v_pk_add_f32 v[50:51], v[52:53], v[54:55]
	v_pk_fma_f32 v[70:71], v[40:41], v[26:27], v[28:29] op_sel:[1,1,0] op_sel_hi:[1,0,1] neg_lo:[0,1,0]
	v_pk_mul_f32 v[26:27], v[46:47], v[30:31] op_sel:[0,0] op_sel_hi:[0,1]
	v_pk_add_f32 v[28:29], v[62:63], v[60:61] neg_lo:[0,1] neg_hi:[0,1]
	v_pk_fma_f32 v[74:75], v[46:47], v[30:31], v[26:27] op_sel:[1,1,0] op_sel_hi:[1,0,1] neg_lo:[0,1,0]
	v_pk_mul_f32 v[26:27], v[38:39], v[44:45] op_sel:[0,0] op_sel_hi:[0,1]
	v_pk_add_f32 v[30:31], v[32:33], v[56:57] neg_lo:[0,1] neg_hi:[0,1]
	v_pk_fma_f32 v[80:81], v[38:39], v[44:45], v[26:27] op_sel:[1,1,0] op_sel_hi:[1,0,1] neg_lo:[0,1,0]
	v_pk_add_f32 v[26:27], v[72:73], v[66:67] neg_lo:[0,1] neg_hi:[0,1]
	v_pk_add_f32 v[38:39], v[72:73], v[66:67]
	v_pk_add_f32 v[40:41], v[26:27], v[28:29] op_sel:[0,1] op_sel_hi:[1,0] neg_lo:[0,1]
	v_pk_add_f32 v[26:27], v[26:27], v[28:29] op_sel:[0,1] op_sel_hi:[1,0] neg_hi:[0,1]
	v_pk_add_f32 v[28:29], v[76:77], v[48:49] neg_lo:[0,1] neg_hi:[0,1]
	v_pk_add_f32 v[44:45], v[76:77], v[48:49]
	v_pk_add_f32 v[48:49], v[32:33], v[56:57]
	v_pk_add_f32 v[46:47], v[28:29], v[30:31] op_sel:[0,1] op_sel_hi:[1,0] neg_lo:[0,1]
	v_pk_add_f32 v[28:29], v[28:29], v[30:31] op_sel:[0,1] op_sel_hi:[1,0] neg_hi:[0,1]
	v_pk_add_f32 v[30:31], v[52:53], v[54:55] neg_lo:[0,1] neg_hi:[0,1]
	v_pk_add_f32 v[54:55], v[68:69], v[58:59]
	v_pk_add_f32 v[32:33], v[68:69], v[58:59] neg_lo:[0,1] neg_hi:[0,1]
	v_pk_add_f32 v[56:57], v[78:79], v[74:75]
	v_pk_add_f32 v[60:61], v[70:71], v[80:81]
	v_pk_add_f32 v[64:65], v[38:39], v[42:43]
	v_pk_add_f32 v[66:67], v[44:45], v[48:49]
	v_pk_add_f32 v[68:69], v[50:51], v[54:55]
	v_pk_add_f32 v[52:53], v[30:31], v[32:33] op_sel:[0,1] op_sel_hi:[1,0] neg_lo:[0,1]
	v_pk_add_f32 v[30:31], v[30:31], v[32:33] op_sel:[0,1] op_sel_hi:[1,0] neg_hi:[0,1]
	v_pk_add_f32 v[32:33], v[78:79], v[74:75] neg_lo:[0,1] neg_hi:[0,1]
	v_pk_add_f32 v[62:63], v[56:57], v[60:61]
	v_pk_add_f32 v[70:71], v[70:71], v[80:81] neg_lo:[0,1] neg_hi:[0,1]
	s_nop 0
	v_pk_add_f32 v[58:59], v[32:33], v[70:71] op_sel:[0,1] op_sel_hi:[1,0] neg_lo:[0,1]
	v_pk_add_f32 v[32:33], v[32:33], v[70:71] op_sel:[0,1] op_sel_hi:[1,0] neg_hi:[0,1]
	s_and_saveexec_b64 s[0:1], s[4:5]
	s_xor_b64 s[0:1], exec, s[0:1]
	s_cbranch_execz .LBB0_1415
	v_mov_b64_e32 v[70:71], s[16:17]
	v_pk_mul_f32 v[72:73], v[36:37], v[70:71] op_sel:[0,0] op_sel_hi:[0,1]
	v_pk_fma_f32 v[70:71], v[36:37], v[70:71], v[72:73] op_sel:[1,1,0] op_sel_hi:[1,0,1] neg_lo:[0,1,0]
	v_pk_mul_f32 v[72:73], v[64:65], v[70:71] op_sel:[0,0] op_sel_hi:[0,1] neg_hi:[0,1]
	v_pk_fma_f32 v[64:65], v[64:65], v[70:71], v[72:73] op_sel:[1,1,0] op_sel_hi:[1,0,1]
	v_mov_b64_e32 v[70:71], s[18:19]
	v_pk_mul_f32 v[72:73], v[36:37], v[70:71] op_sel:[0,0] op_sel_hi:[0,1]
	v_pk_fma_f32 v[70:71], v[36:37], v[70:71], v[72:73] op_sel:[1,1,0] op_sel_hi:[1,0,1] neg_lo:[0,1,0]
	v_pk_mul_f32 v[72:73], v[66:67], v[70:71] op_sel:[0,0] op_sel_hi:[0,1] neg_hi:[0,1]
	v_pk_fma_f32 v[66:67], v[66:67], v[70:71], v[72:73] op_sel:[1,1,0] op_sel_hi:[1,0,1]
	v_mov_b64_e32 v[70:71], s[20:21]
	v_pk_mul_f32 v[72:73], v[36:37], v[70:71] op_sel:[0,0] op_sel_hi:[0,1]
	v_pk_fma_f32 v[70:71], v[36:37], v[70:71], v[72:73] op_sel:[1,1,0] op_sel_hi:[1,0,1] neg_lo:[0,1,0]
	v_pk_mul_f32 v[72:73], v[68:69], v[70:71] op_sel:[0,0] op_sel_hi:[0,1] neg_hi:[0,1]
	v_pk_fma_f32 v[68:69], v[68:69], v[70:71], v[72:73] op_sel:[1,1,0] op_sel_hi:[1,0,1]
	v_mov_b64_e32 v[70:71], s[22:23]
	v_pk_mul_f32 v[72:73], v[36:37], v[70:71] op_sel:[0,0] op_sel_hi:[0,1]
	v_pk_fma_f32 v[70:71], v[36:37], v[70:71], v[72:73] op_sel:[1,1,0] op_sel_hi:[1,0,1] neg_lo:[0,1,0]
	v_pk_mul_f32 v[72:73], v[62:63], v[70:71] op_sel:[0,0] op_sel_hi:[0,1] neg_hi:[0,1]
	v_pk_fma_f32 v[62:63], v[62:63], v[70:71], v[72:73] op_sel:[1,1,0] op_sel_hi:[1,0,1]
	ds_write_b64 v144, v[64:65]
	ds_write_b64 v144, v[66:67] offset:2176
	ds_write_b64 v144, v[68:69] offset:4352
	ds_write_b64 v144, v[62:63] offset:6528
	v_mov_b64_e32 v[62:63], s[50:51]
	v_pk_mul_f32 v[64:65], v[36:37], v[62:63] op_sel:[0,0] op_sel_hi:[0,1]
	s_nop 0
	v_pk_fma_f32 v[62:63], v[36:37], v[62:63], v[64:65] op_sel:[1,1,0] op_sel_hi:[1,0,1] neg_lo:[0,1,0]
	v_pk_mul_f32 v[64:65], v[40:41], v[62:63] op_sel:[0,0] op_sel_hi:[0,1] neg_hi:[0,1]
	v_pk_fma_f32 v[40:41], v[40:41], v[62:63], v[64:65] op_sel:[1,1,0] op_sel_hi:[1,0,1]
	v_mov_b64_e32 v[62:63], s[52:53]
	v_pk_mul_f32 v[64:65], v[36:37], v[62:63] op_sel:[0,0] op_sel_hi:[0,1]
	v_pk_fma_f32 v[62:63], v[36:37], v[62:63], v[64:65] op_sel:[1,1,0] op_sel_hi:[1,0,1] neg_lo:[0,1,0]
	v_pk_mul_f32 v[64:65], v[46:47], v[62:63] op_sel:[0,0] op_sel_hi:[0,1] neg_hi:[0,1]
	v_pk_fma_f32 v[46:47], v[46:47], v[62:63], v[64:65] op_sel:[1,1,0] op_sel_hi:[1,0,1]
	v_mov_b64_e32 v[62:63], s[54:55]
	v_pk_mul_f32 v[64:65], v[36:37], v[62:63] op_sel:[0,0] op_sel_hi:[0,1]
	v_pk_fma_f32 v[62:63], v[36:37], v[62:63], v[64:65] op_sel:[1,1,0] op_sel_hi:[1,0,1] neg_lo:[0,1,0]
	v_pk_mul_f32 v[64:65], v[52:53], v[62:63] op_sel:[0,0] op_sel_hi:[0,1] neg_hi:[0,1]
	v_pk_fma_f32 v[52:53], v[52:53], v[62:63], v[64:65] op_sel:[1,1,0] op_sel_hi:[1,0,1]
	v_mov_b64_e32 v[62:63], s[56:57]
	v_pk_mul_f32 v[64:65], v[36:37], v[62:63] op_sel:[0,0] op_sel_hi:[0,1]
	v_pk_fma_f32 v[62:63], v[36:37], v[62:63], v[64:65] op_sel:[1,1,0] op_sel_hi:[1,0,1] neg_lo:[0,1,0]
	v_pk_mul_f32 v[64:65], v[58:59], v[62:63] op_sel:[0,0] op_sel_hi:[0,1] neg_hi:[0,1]
	s_nop 0
	v_pk_fma_f32 v[58:59], v[58:59], v[62:63], v[64:65] op_sel:[1,1,0] op_sel_hi:[1,0,1]

.LBB0_1417:
	s_or_b64 exec, exec, s[0:1]
	v_pk_add_f32 v[62:63], v[38:39], v[42:43] neg_lo:[0,1] neg_hi:[0,1]
	v_pk_add_f32 v[44:45], v[44:45], v[48:49] neg_lo:[0,1] neg_hi:[0,1]
	v_pk_add_f32 v[42:43], v[50:51], v[54:55] neg_lo:[0,1] neg_hi:[0,1]
	v_pk_add_f32 v[38:39], v[56:57], v[60:61] neg_lo:[0,1] neg_hi:[0,1]
	ds_write_b64 v144, v[40:41] offset:8704
	ds_write_b64 v144, v[46:47] offset:10880
	ds_write_b64 v144, v[52:53] offset:13056
	ds_write_b64 v144, v[58:59] offset:15232
	s_and_saveexec_b64 s[0:1], s[4:5]
	s_xor_b64 s[0:1], exec, s[0:1]
	s_cbranch_execz .LBB0_1419
	v_mov_b64_e32 v[40:41], s[14:15]
	v_pk_mul_f32 v[46:47], v[36:37], v[40:41] op_sel:[0,0] op_sel_hi:[0,1]
	s_mov_b32 s4, s19
	v_pk_fma_f32 v[40:41], v[36:37], v[40:41], v[46:47] op_sel:[1,1,0] op_sel_hi:[1,0,1] neg_lo:[0,1,0]
	s_mov_b32 s5, s57
	v_pk_mul_f32 v[46:47], v[62:63], v[40:41] op_sel:[0,0] op_sel_hi:[0,1] neg_hi:[0,1]
	v_pk_fma_f32 v[40:41], v[62:63], v[40:41], v[46:47] op_sel:[1,1,0] op_sel_hi:[1,0,1]
	v_mov_b64_e32 v[46:47], s[4:5]
	v_pk_mul_f32 v[48:49], v[36:37], v[46:47] op_sel:[0,0] op_sel_hi:[0,1]
	s_mov_b32 s4, s21
	v_pk_fma_f32 v[46:47], v[36:37], v[46:47], v[48:49] op_sel:[1,1,0] op_sel_hi:[1,0,1] neg_lo:[0,1,0]
	s_mov_b32 s5, s55
	v_pk_mul_f32 v[48:49], v[44:45], v[46:47] op_sel:[0,0] op_sel_hi:[0,1] neg_hi:[0,1]
	s_nop 0
	v_pk_fma_f32 v[44:45], v[44:45], v[46:47], v[48:49] op_sel:[1,1,0] op_sel_hi:[1,0,1]
	v_mov_b64_e32 v[46:47], s[4:5]
	v_pk_mul_f32 v[48:49], v[36:37], v[46:47] op_sel:[0,0] op_sel_hi:[0,1]
	s_mov_b32 s4, s23
	v_pk_fma_f32 v[46:47], v[36:37], v[46:47], v[48:49] op_sel:[1,1,0] op_sel_hi:[1,0,1] neg_lo:[0,1,0]
	s_mov_b32 s5, s53
	v_pk_mul_f32 v[48:49], v[42:43], v[46:47] op_sel:[0,0] op_sel_hi:[0,1] neg_hi:[0,1]
	v_pk_fma_f32 v[42:43], v[42:43], v[46:47], v[48:49] op_sel:[1,1,0] op_sel_hi:[1,0,1]
	v_mov_b64_e32 v[46:47], s[4:5]
	v_pk_mul_f32 v[48:49], v[36:37], v[46:47] op_sel:[0,0] op_sel_hi:[0,1]
	s_mov_b32 s4, s53
	v_pk_fma_f32 v[46:47], v[36:37], v[46:47], v[48:49] op_sel:[1,1,0] op_sel_hi:[1,0,1] neg_lo:[0,1,0]
	s_mov_b32 s5, s23
	v_pk_mul_f32 v[48:49], v[38:39], v[46:47] op_sel:[0,0] op_sel_hi:[0,1] neg_hi:[0,1]
	v_pk_fma_f32 v[38:39], v[38:39], v[46:47], v[48:49] op_sel:[1,1,0] op_sel_hi:[1,0,1]
	ds_write_b64 v144, v[40:41] offset:17408
	ds_write_b64 v144, v[44:45] offset:19584
	ds_write_b64 v144, v[42:43] offset:21760
	ds_write_b64 v144, v[38:39] offset:23936
	v_mov_b64_e32 v[38:39], s[58:59]
	v_pk_mul_f32 v[40:41], v[36:37], v[38:39] op_sel:[0,0] op_sel_hi:[0,1]
	s_nop 0
	v_pk_fma_f32 v[38:39], v[36:37], v[38:39], v[40:41] op_sel:[1,1,0] op_sel_hi:[1,0,1] neg_lo:[0,1,0]
	v_pk_mul_f32 v[40:41], v[26:27], v[38:39] op_sel:[0,0] op_sel_hi:[0,1] neg_hi:[0,1]
	v_pk_fma_f32 v[26:27], v[26:27], v[38:39], v[40:41] op_sel:[1,1,0] op_sel_hi:[1,0,1]
	v_mov_b64_e32 v[38:39], s[4:5]
	v_pk_mul_f32 v[40:41], v[36:37], v[38:39] op_sel:[0,0] op_sel_hi:[0,1]
	s_mov_b32 s4, s57
	v_pk_fma_f32 v[38:39], v[36:37], v[38:39], v[40:41] op_sel:[1,1,0] op_sel_hi:[1,0,1] neg_lo:[0,1,0]
	s_mov_b32 s5, s19
	v_pk_mul_f32 v[40:41], v[28:29], v[38:39] op_sel:[0,0] op_sel_hi:[0,1] neg_hi:[0,1]
	v_pk_fma_f32 v[28:29], v[28:29], v[38:39], v[40:41] op_sel:[1,1,0] op_sel_hi:[1,0,1]
	v_mov_b64_e32 v[38:39], s[72:73]
	v_pk_mul_f32 v[40:41], v[36:37], v[38:39] op_sel:[0,0] op_sel_hi:[0,1]
	v_pk_fma_f32 v[38:39], v[36:37], v[38:39], v[40:41] op_sel:[1,1,0] op_sel_hi:[1,0,1] neg_lo:[0,1,0]
	v_pk_mul_f32 v[40:41], v[30:31], v[38:39] op_sel:[0,0] op_sel_hi:[0,1] neg_hi:[0,1]
	v_pk_fma_f32 v[30:31], v[30:31], v[38:39], v[40:41] op_sel:[1,1,0] op_sel_hi:[1,0,1]
	v_mov_b64_e32 v[38:39], s[4:5]
	v_pk_mul_f32 v[40:41], v[36:37], v[38:39] op_sel:[0,0] op_sel_hi:[0,1]
	v_pk_fma_f32 v[36:37], v[36:37], v[38:39], v[40:41] op_sel:[1,1,0] op_sel_hi:[1,0,1] neg_lo:[0,1,0]
	v_pk_mul_f32 v[38:39], v[32:33], v[36:37] op_sel:[0,0] op_sel_hi:[0,1] neg_hi:[0,1]
	s_nop 0
	v_pk_fma_f32 v[32:33], v[32:33], v[36:37], v[38:39] op_sel:[1,1,0] op_sel_hi:[1,0,1]

.LBB0_1630:
	s_or_b64 exec, exec, s[12:13]
	v_lshlrev_b32_e32 v2, 2, v9
	v_add_u32_e32 v37, s31, v2
	v_add_u32_e32 v2, 0, v2
	v_add_u32_e32 v54, 0x1bc00, v2
	v_lshl_add_u32 v2, v26, 9, v37
	s_waitcnt lgkmcnt(0)
	s_barrier
	ds_read_b128 v[40:43], v2
	ds_read_b128 v[44:47], v54
	s_lshl_b64 s[12:13], s[8:9], 14
	s_add_u32 s0, s85, s12
	s_addc_u32 s1, s84, s13
	v_mov_b32_e32 v33, v3
	s_waitcnt lgkmcnt(1)
	v_mul_f32_e32 v15, 0x3fb8aa3b, v40
	v_lshl_add_u64 v[34:35], s[0:1], 0, v[32:33]
	v_add_u32_e32 v2, 0, v32
	v_exp_f32_e32 v32, v15
	s_waitcnt lgkmcnt(0)
	v_sub_f32_e32 v15, v40, v44
	v_mul_f32_e32 v15, 0x3fb8aa3b, v15
	v_exp_f32_e32 v48, v15
	v_sub_f32_e32 v15, v44, v40
	v_mul_f32_e32 v15, 0x3fb8aa3b, v15
	v_exp_f32_e32 v40, v15
	v_mul_f32_e32 v15, 0x3fb8aa3b, v41
	v_exp_f32_e32 v44, v15
	v_sub_f32_e32 v15, v41, v45
	v_mul_f32_e32 v15, 0x3fb8aa3b, v15
	v_exp_f32_e32 v50, v15
	v_sub_f32_e32 v15, v45, v41
	v_mul_f32_e32 v15, 0x3fb8aa3b, v15
	v_exp_f32_e32 v52, v15
	v_mul_f32_e32 v15, 0x3fb8aa3b, v42
	v_exp_f32_e32 v33, v15
	v_sub_f32_e32 v15, v42, v46
	v_mul_f32_e32 v15, 0x3fb8aa3b, v15
	v_exp_f32_e32 v49, v15
	v_sub_f32_e32 v15, v46, v42
	v_mul_f32_e32 v15, 0x3fb8aa3b, v15
	v_exp_f32_e32 v41, v15
	v_mul_f32_e32 v15, 0x3fb8aa3b, v43
	v_exp_f32_e32 v45, v15
	v_sub_f32_e32 v15, v43, v47
	v_mul_f32_e32 v15, 0x3fb8aa3b, v15
	v_exp_f32_e32 v51, v15
	v_sub_f32_e32 v15, v47, v43
	v_lshlrev_b32_e32 v43, 16, v31
	v_lshlrev_b32_e32 v42, 16, v30
	v_and_b32_e32 v31, 0xffff0000, v31
	v_and_b32_e32 v30, 0xffff0000, v30
	v_pk_mul_f32 v[30:31], v[30:31], s[6:7] op_sel_hi:[1,0]
	v_pk_mul_f32 v[42:43], v[42:43], s[6:7] op_sel_hi:[1,0]
	v_pk_mul_f32 v[44:45], v[30:31], v[44:45]
	v_mul_f32_e32 v15, 0x3fb8aa3b, v15
	v_pk_mul_f32 v[32:33], v[42:43], v[32:33]
	v_exp_f32_e32 v53, v15
	v_cvt_pk_bf16_f32 v33, v33, v45
	v_cvt_pk_bf16_f32 v32, v32, v44
	v_ashrrev_i32_e32 v27, 31, v26
	v_lshlrev_b64 v[44:45], 8, v[26:27]
	v_lshl_add_u64 v[44:45], v[34:35], 0, v[44:45]
	global_store_dwordx2 v[44:45], v[32:33], off
	v_pk_mul_f32 v[32:33], v[42:43], v[48:49]
	v_pk_mul_f32 v[30:31], v[30:31], v[50:51]
	v_cvt_pk_bf16_f32 v30, v32, v30
	v_cvt_pk_bf16_f32 v31, v33, v31
	v_lshlrev_b32_e32 v43, 16, v29
	v_lshlrev_b32_e32 v42, 16, v28
	v_and_b32_e32 v29, 0xffff0000, v29
	v_and_b32_e32 v28, 0xffff0000, v28
	v_mad_u64_u32 v[32:33], s[0:1], v26, s46, v[2:3]
	v_pk_mul_f32 v[40:41], v[40:41], v[42:43]
	v_pk_mul_f32 v[28:29], v[52:53], v[28:29]
	v_and_b32_sdwa v21, v40, v38 dst_sel:DWORD dst_unused:UNUSED_PAD src0_sel:WORD_1 src1_sel:DWORD
	v_and_b32_sdwa v27, v29, v38 dst_sel:DWORD dst_unused:UNUSED_PAD src0_sel:WORD_1 src1_sel:DWORD
	v_and_b32_sdwa v33, v28, v38 dst_sel:DWORD dst_unused:UNUSED_PAD src0_sel:WORD_1 src1_sel:DWORD
	v_and_b32_sdwa v15, v41, v38 dst_sel:DWORD dst_unused:UNUSED_PAD src0_sel:WORD_1 src1_sel:DWORD
	v_add3_u32 v21, v40, v21, s45
	v_add3_u32 v40, v29, v27, s45
	v_add3_u32 v33, v28, v33, s45
	v_add3_u32 v15, v41, v15, s45
	v_and_b32_e32 v27, 0xffff0000, v40
	v_and_b32_e32 v28, 0xffff0000, v33
	v_lshlrev_b32_e32 v26, 1, v26
	v_mul_u32_u24_e32 v48, 0x90, v9
	v_or_b32_sdwa v29, v27, v15 dst_sel:DWORD dst_unused:UNUSED_PAD src0_sel:DWORD src1_sel:WORD_1
	v_or_b32_sdwa v28, v28, v21 dst_sel:DWORD dst_unused:UNUSED_PAD src0_sel:DWORD src1_sel:WORD_1
	v_add3_u32 v9, s22, v26, v48
	ds_write2st64_b64 v32, v[30:31], v[28:29] offset1:66
	ds_write_b16_d16_hi v9, v21
	v_lshl_add_u32 v21, v20, 9, v37
	ds_read_b128 v[26:29], v21
	ds_write_b16_d16_hi v9, v33 offset:144
	ds_read_b128 v[30:33], v54
	ds_write_b16_d16_hi v9, v15 offset:288
	ds_write_b16_d16_hi v9, v40 offset:432
	v_ashrrev_i32_e32 v36, 6, v6
	s_waitcnt lgkmcnt(4)
	v_mul_f32_e32 v9, 0x3fb8aa3b, v26
	v_exp_f32_e32 v40, v9
	s_waitcnt lgkmcnt(2)
	v_sub_f32_e32 v9, v26, v30
	v_mul_f32_e32 v9, 0x3fb8aa3b, v9
	v_exp_f32_e32 v42, v9
	v_sub_f32_e32 v9, v30, v26
	v_mul_f32_e32 v9, 0x3fb8aa3b, v9
	v_exp_f32_e32 v26, v9
	v_mul_f32_e32 v9, 0x3fb8aa3b, v27
	v_exp_f32_e32 v30, v9
	v_sub_f32_e32 v9, v27, v31
	v_mul_f32_e32 v9, 0x3fb8aa3b, v9
	v_exp_f32_e32 v44, v9
	v_sub_f32_e32 v9, v31, v27
	v_mul_f32_e32 v9, 0x3fb8aa3b, v9
	v_exp_f32_e32 v46, v9
	v_mul_f32_e32 v9, 0x3fb8aa3b, v28
	v_exp_f32_e32 v41, v9
	v_sub_f32_e32 v9, v28, v32
	v_mul_f32_e32 v9, 0x3fb8aa3b, v9
	v_exp_f32_e32 v43, v9
	v_sub_f32_e32 v9, v32, v28
	v_mul_f32_e32 v9, 0x3fb8aa3b, v9
	v_exp_f32_e32 v27, v9
	v_mul_f32_e32 v9, 0x3fb8aa3b, v29
	v_exp_f32_e32 v31, v9
	v_sub_f32_e32 v9, v29, v33
	v_mul_f32_e32 v9, 0x3fb8aa3b, v9
	v_exp_f32_e32 v45, v9
	v_sub_f32_e32 v9, v33, v29
	v_lshlrev_b32_e32 v29, 16, v25
	v_lshlrev_b32_e32 v28, 16, v24
	v_and_b32_e32 v25, 0xffff0000, v25
	v_and_b32_e32 v24, 0xffff0000, v24
	v_pk_mul_f32 v[28:29], v[28:29], s[6:7] op_sel_hi:[1,0]
	v_pk_mul_f32 v[24:25], v[24:25], s[6:7] op_sel_hi:[1,0]
	v_pk_mul_f32 v[32:33], v[28:29], v[40:41]
	v_pk_mul_f32 v[30:31], v[24:25], v[30:31]
	v_mul_f32_e32 v9, 0x3fb8aa3b, v9
	v_exp_f32_e32 v47, v9
	v_cvt_pk_bf16_f32 v31, v33, v31
	v_cvt_pk_bf16_f32 v30, v32, v30
	v_ashrrev_i32_e32 v21, 31, v20
	v_pk_mul_f32 v[28:29], v[28:29], v[42:43]
	v_lshlrev_b64 v[32:33], 8, v[20:21]
	v_pk_mul_f32 v[24:25], v[24:25], v[44:45]
	v_lshl_add_u64 v[32:33], v[34:35], 0, v[32:33]
	v_cvt_pk_bf16_f32 v24, v28, v24
	global_store_dwordx2 v[32:33], v[30:31], off
	v_lshlrev_b32_e32 v31, 16, v23
	v_lshlrev_b32_e32 v30, 16, v22
	v_cvt_pk_bf16_f32 v25, v29, v25
	v_and_b32_e32 v23, 0xffff0000, v23
	v_and_b32_e32 v22, 0xffff0000, v22
	v_pk_mul_f32 v[26:27], v[26:27], v[30:31]
	v_pk_mul_f32 v[22:23], v[46:47], v[22:23]
	v_and_b32_sdwa v15, v26, v38 dst_sel:DWORD dst_unused:UNUSED_PAD src0_sel:WORD_1 src1_sel:DWORD
	s_nop 0
	v_mad_u64_u32 v[28:29], s[0:1], v20, s46, v[2:3]
	v_add3_u32 v15, v26, v15, s45
	v_and_b32_sdwa v21, v23, v38 dst_sel:DWORD dst_unused:UNUSED_PAD src0_sel:WORD_1 src1_sel:DWORD
	v_and_b32_sdwa v26, v22, v38 dst_sel:DWORD dst_unused:UNUSED_PAD src0_sel:WORD_1 src1_sel:DWORD
	v_and_b32_sdwa v9, v27, v38 dst_sel:DWORD dst_unused:UNUSED_PAD src0_sel:WORD_1 src1_sel:DWORD
	v_add3_u32 v29, v23, v21, s45
	v_add3_u32 v26, v22, v26, s45
	v_add3_u32 v9, v27, v9, s45
	v_and_b32_e32 v21, 0xffff0000, v29
	v_and_b32_e32 v22, 0xffff0000, v26
	v_or_b32_sdwa v23, v21, v9 dst_sel:DWORD dst_unused:UNUSED_PAD src0_sel:DWORD src1_sel:WORD_1
	v_or_b32_sdwa v22, v22, v15 dst_sel:DWORD dst_unused:UNUSED_PAD src0_sel:DWORD src1_sel:WORD_1
	v_lshlrev_b32_e32 v20, 1, v20
	ds_write2st64_b64 v28, v[24:25], v[22:23] offset1:66
	v_add3_u32 v28, s22, v20, v48
	ds_write_b16_d16_hi v28, v15
	v_lshl_add_u32 v15, v14, 9, v37
	ds_read_b128 v[20:23], v15
	ds_write_b16_d16_hi v28, v26 offset:144
	ds_read_b128 v[24:27], v54
	ds_write_b16_d16_hi v28, v9 offset:288
	ds_write_b16_d16_hi v28, v29 offset:432
	v_bfe_u32 v7, v6, 4, 2
	s_waitcnt lgkmcnt(4)
	v_mul_f32_e32 v9, 0x3fb8aa3b, v20
	v_exp_f32_e32 v28, v9
	s_waitcnt lgkmcnt(2)
	v_sub_f32_e32 v9, v20, v24
	v_mul_f32_e32 v9, 0x3fb8aa3b, v9
	v_exp_f32_e32 v30, v9
	v_sub_f32_e32 v9, v24, v20
	v_mul_f32_e32 v9, 0x3fb8aa3b, v9
	v_exp_f32_e32 v20, v9
	v_mul_f32_e32 v9, 0x3fb8aa3b, v21
	v_exp_f32_e32 v24, v9
	v_sub_f32_e32 v9, v21, v25
	v_mul_f32_e32 v9, 0x3fb8aa3b, v9
	v_exp_f32_e32 v32, v9
	v_sub_f32_e32 v9, v25, v21
	v_mul_f32_e32 v9, 0x3fb8aa3b, v9
	v_exp_f32_e32 v40, v9
	v_mul_f32_e32 v9, 0x3fb8aa3b, v22
	v_exp_f32_e32 v29, v9
	v_sub_f32_e32 v9, v22, v26
	v_mul_f32_e32 v9, 0x3fb8aa3b, v9
	v_exp_f32_e32 v31, v9
	v_sub_f32_e32 v9, v26, v22
	v_mul_f32_e32 v9, 0x3fb8aa3b, v9
	v_exp_f32_e32 v21, v9
	v_mul_f32_e32 v9, 0x3fb8aa3b, v23
	v_exp_f32_e32 v25, v9
	v_sub_f32_e32 v9, v23, v27
	v_mul_f32_e32 v9, 0x3fb8aa3b, v9
	v_exp_f32_e32 v33, v9
	v_sub_f32_e32 v9, v27, v23
	v_lshlrev_b32_e32 v23, 16, v19
	v_lshlrev_b32_e32 v22, 16, v18
	v_and_b32_e32 v19, 0xffff0000, v19
	v_and_b32_e32 v18, 0xffff0000, v18
	v_pk_mul_f32 v[22:23], v[22:23], s[6:7] op_sel_hi:[1,0]
	v_mul_f32_e32 v9, 0x3fb8aa3b, v9
	v_pk_mul_f32 v[18:19], v[18:19], s[6:7] op_sel_hi:[1,0]
	v_pk_mul_f32 v[26:27], v[22:23], v[28:29]
	v_exp_f32_e32 v41, v9
	v_pk_mul_f32 v[24:25], v[18:19], v[24:25]
	v_and_b32_sdwa v9, v27, v38 dst_sel:DWORD dst_unused:UNUSED_PAD src0_sel:WORD_1 src1_sel:DWORD
	v_add3_u32 v9, v27, v9, s45
	v_cvt_pk_bf16_f32 v24, v26, v24
	v_and_b32_sdwa v26, v25, v38 dst_sel:DWORD dst_unused:UNUSED_PAD src0_sel:WORD_1 src1_sel:DWORD
	v_add3_u32 v25, v25, v26, s45
	v_and_b32_e32 v25, 0xffff0000, v25
	v_ashrrev_i32_e32 v15, 31, v14
	v_pk_mul_f32 v[22:23], v[22:23], v[30:31]
	v_or_b32_sdwa v25, v25, v9 dst_sel:DWORD dst_unused:UNUSED_PAD src0_sel:DWORD src1_sel:WORD_1
	v_lshlrev_b64 v[26:27], 8, v[14:15]
	v_pk_mul_f32 v[18:19], v[18:19], v[32:33]
	v_and_b32_sdwa v15, v22, v38 dst_sel:DWORD dst_unused:UNUSED_PAD src0_sel:WORD_1 src1_sel:DWORD
	v_lshl_add_u64 v[26:27], v[34:35], 0, v[26:27]
	v_add3_u32 v15, v22, v15, s45
	v_cvt_pk_bf16_f32 v19, v23, v19
	v_and_b32_sdwa v23, v18, v38 dst_sel:DWORD dst_unused:UNUSED_PAD src0_sel:WORD_1 src1_sel:DWORD
	global_store_dwordx2 v[26:27], v[24:25], off
	s_nop 0
	v_add3_u32 v18, v18, v23, s45
	v_lshlrev_b32_e32 v25, 16, v17
	v_lshlrev_b32_e32 v24, 16, v16
	v_and_b32_e32 v18, 0xffff0000, v18
	v_and_b32_e32 v17, 0xffff0000, v17
	v_and_b32_e32 v16, 0xffff0000, v16
	v_pk_mul_f32 v[20:21], v[20:21], v[24:25]
	v_or_b32_sdwa v18, v18, v15 dst_sel:DWORD dst_unused:UNUSED_PAD src0_sel:DWORD src1_sel:WORD_1
	v_pk_mul_f32 v[16:17], v[40:41], v[16:17]
	v_and_b32_sdwa v9, v21, v38 dst_sel:DWORD dst_unused:UNUSED_PAD src0_sel:WORD_1 src1_sel:DWORD
	v_and_b32_sdwa v15, v20, v38 dst_sel:DWORD dst_unused:UNUSED_PAD src0_sel:WORD_1 src1_sel:DWORD
	v_mad_u64_u32 v[22:23], s[0:1], v14, s46, v[2:3]
	v_add3_u32 v15, v20, v15, s45
	v_add3_u32 v9, v21, v9, s45
	v_and_b32_sdwa v20, v17, v38 dst_sel:DWORD dst_unused:UNUSED_PAD src0_sel:WORD_1 src1_sel:DWORD
	v_and_b32_sdwa v21, v16, v38 dst_sel:DWORD dst_unused:UNUSED_PAD src0_sel:WORD_1 src1_sel:DWORD
	v_add3_u32 v23, v17, v20, s45
	v_add3_u32 v20, v16, v21, s45
	v_and_b32_e32 v16, 0xffff0000, v23
	v_and_b32_e32 v21, 0xffff0000, v20
	v_or_b32_sdwa v17, v16, v9 dst_sel:DWORD dst_unused:UNUSED_PAD src0_sel:DWORD src1_sel:WORD_1
	v_or_b32_sdwa v16, v21, v15 dst_sel:DWORD dst_unused:UNUSED_PAD src0_sel:DWORD src1_sel:WORD_1
	v_lshlrev_b32_e32 v14, 1, v14
	ds_write2st64_b64 v22, v[18:19], v[16:17] offset1:66
	v_add3_u32 v22, s22, v14, v48
	v_lshl_add_u32 v14, v8, 9, v37
	ds_write_b16_d16_hi v22, v15
	ds_read_b128 v[14:17], v14
	ds_write_b16_d16_hi v22, v20 offset:144
	ds_read_b128 v[18:21], v54
	ds_write_b16_d16_hi v22, v9 offset:288
	ds_write_b16_d16_hi v22, v23 offset:432
	s_waitcnt lgkmcnt(4)
	v_mul_f32_e32 v9, 0x3fb8aa3b, v14
	v_exp_f32_e32 v22, v9
	s_waitcnt lgkmcnt(2)
	v_sub_f32_e32 v9, v14, v18
	v_mul_f32_e32 v9, 0x3fb8aa3b, v9
	v_exp_f32_e32 v24, v9
	v_sub_f32_e32 v9, v18, v14
	v_mul_f32_e32 v9, 0x3fb8aa3b, v9
	v_exp_f32_e32 v14, v9
	v_mul_f32_e32 v9, 0x3fb8aa3b, v15
	v_exp_f32_e32 v18, v9
	v_sub_f32_e32 v9, v15, v19
	v_mul_f32_e32 v9, 0x3fb8aa3b, v9
	v_exp_f32_e32 v26, v9
	v_sub_f32_e32 v9, v19, v15
	v_mul_f32_e32 v9, 0x3fb8aa3b, v9
	v_exp_f32_e32 v28, v9
	v_mul_f32_e32 v9, 0x3fb8aa3b, v16
	v_exp_f32_e32 v23, v9
	v_sub_f32_e32 v9, v16, v20
	v_mul_f32_e32 v9, 0x3fb8aa3b, v9
	v_exp_f32_e32 v25, v9
	v_sub_f32_e32 v9, v20, v16
	v_mul_f32_e32 v9, 0x3fb8aa3b, v9
	v_exp_f32_e32 v15, v9
	v_mul_f32_e32 v9, 0x3fb8aa3b, v17
	v_exp_f32_e32 v19, v9
	v_sub_f32_e32 v9, v17, v21
	v_mul_f32_e32 v9, 0x3fb8aa3b, v9
	v_exp_f32_e32 v27, v9
	v_sub_f32_e32 v9, v21, v17
	v_lshlrev_b32_e32 v17, 16, v13
	v_lshlrev_b32_e32 v16, 16, v12
	v_and_b32_e32 v13, 0xffff0000, v13
	v_and_b32_e32 v12, 0xffff0000, v12
	v_pk_mul_f32 v[16:17], v[16:17], s[6:7] op_sel_hi:[1,0]
	v_mul_f32_e32 v9, 0x3fb8aa3b, v9
	v_pk_mul_f32 v[12:13], v[12:13], s[6:7] op_sel_hi:[1,0]
	v_pk_mul_f32 v[20:21], v[16:17], v[22:23]
	v_exp_f32_e32 v29, v9
	v_pk_mul_f32 v[18:19], v[12:13], v[18:19]
	v_and_b32_sdwa v22, v20, v38 dst_sel:DWORD dst_unused:UNUSED_PAD src0_sel:WORD_1 src1_sel:DWORD
	s_nop 0
	v_cvt_pk_bf16_f32 v19, v21, v19
	v_add3_u32 v20, v20, v22, s45
	v_and_b32_sdwa v22, v18, v38 dst_sel:DWORD dst_unused:UNUSED_PAD src0_sel:WORD_1 src1_sel:DWORD
	v_add3_u32 v18, v18, v22, s45
	v_and_b32_e32 v18, 0xffff0000, v18
	v_ashrrev_i32_e32 v9, 31, v8
	v_or_b32_sdwa v18, v18, v20 dst_sel:DWORD dst_unused:UNUSED_PAD src0_sel:DWORD src1_sel:WORD_1
	v_lshlrev_b64 v[20:21], 8, v[8:9]
	v_lshl_add_u64 v[20:21], v[34:35], 0, v[20:21]
	v_pk_mul_f32 v[16:17], v[16:17], v[24:25]
	global_store_dwordx2 v[20:21], v[18:19], off
	v_pk_mul_f32 v[12:13], v[12:13], v[26:27]
	v_and_b32_sdwa v18, v16, v38 dst_sel:DWORD dst_unused:UNUSED_PAD src0_sel:WORD_1 src1_sel:DWORD
	v_add3_u32 v16, v16, v18, s45
	v_cvt_pk_bf16_f32 v13, v17, v13
	v_and_b32_sdwa v18, v12, v38 dst_sel:DWORD dst_unused:UNUSED_PAD src0_sel:WORD_1 src1_sel:DWORD
	v_add3_u32 v12, v12, v18, s45
	v_lshlrev_b32_e32 v19, 16, v11
	v_lshlrev_b32_e32 v18, 16, v10
	v_and_b32_e32 v12, 0xffff0000, v12
	v_and_b32_e32 v11, 0xffff0000, v11
	v_and_b32_e32 v10, 0xffff0000, v10
	v_pk_mul_f32 v[14:15], v[14:15], v[18:19]
	v_or_b32_sdwa v12, v12, v16 dst_sel:DWORD dst_unused:UNUSED_PAD src0_sel:DWORD src1_sel:WORD_1
	v_mad_u64_u32 v[16:17], s[0:1], v8, s46, v[2:3]
	v_pk_mul_f32 v[10:11], v[28:29], v[10:11]
	v_and_b32_sdwa v2, v15, v38 dst_sel:DWORD dst_unused:UNUSED_PAD src0_sel:WORD_1 src1_sel:DWORD
	v_and_b32_sdwa v9, v14, v38 dst_sel:DWORD dst_unused:UNUSED_PAD src0_sel:WORD_1 src1_sel:DWORD
	v_add3_u32 v9, v14, v9, s45
	v_add3_u32 v2, v15, v2, s45
	v_and_b32_sdwa v14, v11, v38 dst_sel:DWORD dst_unused:UNUSED_PAD src0_sel:WORD_1 src1_sel:DWORD
	v_and_b32_sdwa v15, v10, v38 dst_sel:DWORD dst_unused:UNUSED_PAD src0_sel:WORD_1 src1_sel:DWORD
	v_add3_u32 v14, v11, v14, s45
	v_add3_u32 v15, v10, v15, s45
	v_and_b32_e32 v10, 0xffff0000, v14
	v_and_b32_e32 v17, 0xffff0000, v15
	v_lshlrev_b32_e32 v8, 1, v8
	v_or_b32_sdwa v11, v10, v2 dst_sel:DWORD dst_unused:UNUSED_PAD src0_sel:DWORD src1_sel:WORD_1
	v_or_b32_sdwa v10, v17, v9 dst_sel:DWORD dst_unused:UNUSED_PAD src0_sel:DWORD src1_sel:WORD_1
	v_add3_u32 v8, s22, v8, v48
	ds_write2st64_b64 v16, v[12:13], v[10:11] offset1:66
	ds_write_b16_d16_hi v8, v9
	ds_write_b16_d16_hi v8, v15 offset:144
	ds_write_b16_d16_hi v8, v2 offset:288
	ds_write_b16_d16_hi v8, v14 offset:432
	v_lshlrev_b32_e32 v2, 3, v36
	v_and_or_b32 v8, v2, s48, v39
	v_lshl_add_u32 v2, v7, 4, 0
	v_mad_u64_u32 v[28:29], s[0:1], v8, s46, v[2:3]
	s_waitcnt lgkmcnt(0)
	s_barrier
	ds_read_b128 v[8:11], v28
	v_lshlrev_b32_e32 v12, 5, v36
	v_and_or_b32 v36, v12, 32, v39
	v_mad_u32_u24 v2, v36, s46, v2
	ds_read_b128 v[12:15], v28 offset:64
	ds_read_b128 v[16:19], v2 offset:33792
	ds_read_b128 v[20:23], v2 offset:33856
	ds_read_b128 v[24:27], v28 offset:128
	s_waitcnt lgkmcnt(2)
	v_mfma_f32_16x16x32_bf16 v[16:19], v[8:11], v[16:19], 0
	s_waitcnt lgkmcnt(1)
	v_mfma_f32_16x16x32_bf16 v[16:19], v[12:15], v[20:23], v[16:19]
	ds_read_b128 v[20:23], v28 offset:192
	ds_read_b128 v[28:31], v2 offset:33920
	ds_read_b128 v[32:35], v2 offset:33984
	s_waitcnt lgkmcnt(1)
	v_mfma_f32_16x16x32_bf16 v[16:19], v[24:27], v[28:31], v[16:19]
	s_waitcnt lgkmcnt(0)
	v_mfma_f32_16x16x32_bf16 v[16:19], v[20:23], v[32:35], v[16:19]
	ds_read_b128 v[28:31], v2 offset:42240
	ds_read_b128 v[32:35], v2 offset:42304
	s_waitcnt lgkmcnt(1)
	v_mfma_f32_16x16x32_bf16 v[8:11], v[8:11], v[28:31], 0
	s_waitcnt lgkmcnt(0)
	v_mfma_f32_16x16x32_bf16 v[8:11], v[12:15], v[32:35], v[8:11]
	ds_read_b128 v[12:15], v2 offset:42368
	ds_read_b128 v[28:31], v2 offset:42432
	v_ashrrev_i32_e32 v2, 3, v6
	v_and_b32_e32 v2, -16, v2
	v_lshl_or_b32 v2, v7, 2, v2
	v_cmp_le_i32_e64 s[0:1], v36, v2
	s_waitcnt lgkmcnt(1)
	v_mfma_f32_16x16x32_bf16 v[8:11], v[24:27], v[12:15], v[8:11]
	v_lshl_add_u32 v6, v36, 1, s49
	v_cndmask_b32_e64 v7, 0, 1, s[0:1]
	v_cmp_ge_i32_e64 s[0:1], v36, v2
	s_waitcnt lgkmcnt(0)
	v_mfma_f32_16x16x32_bf16 v[8:11], v[20:23], v[28:31], v[8:11]
	v_cndmask_b32_e64 v12, 0, 1, s[0:1]
	v_cndmask_b32_e32 v7, v12, v7, vcc
	v_and_b32_e32 v7, 1, v7
	v_cmp_eq_u32_e64 s[0:1], 1, v7
	s_nop 1
	v_cndmask_b32_e64 v7, 0, v16, s[0:1]
	v_bfe_u32 v12, v7, 16, 1
	v_add3_u32 v7, v7, v12, s45
	v_mul_lo_u32 v12, v2, s47
	v_add_u32_e32 v13, v6, v12
	ds_write_b16_d16_hi v13, v7
	v_or_b32_e32 v7, 1, v2
	v_cmp_gt_i32_e64 s[0:1], v36, v2
	s_nop 1
	v_cndmask_b32_e64 v13, 0, 1, s[0:1]
	v_cmp_le_i32_e64 s[0:1], v36, v7
	s_nop 1
	v_cndmask_b32_e64 v14, 0, 1, s[0:1]
	v_cndmask_b32_e32 v13, v13, v14, vcc
	v_and_b32_e32 v13, 1, v13
	v_cmp_eq_u32_e64 s[0:1], 1, v13
	s_nop 1
	v_cndmask_b32_e64 v13, 0, v17, s[0:1]
	v_bfe_u32 v14, v13, 16, 1
	v_add3_u32 v13, v13, v14, s45
	v_add_u32_e32 v14, 0x90, v12
	v_add_u32_e32 v15, v6, v14
	ds_write_b16_d16_hi v15, v13
	v_or_b32_e32 v13, 2, v2
	v_cmp_le_i32_e64 s[0:1], v36, v13
	s_nop 1
	v_cndmask_b32_e64 v15, 0, 1, s[0:1]
	v_cmp_ge_i32_e64 s[0:1], v36, v13
	s_nop 1
	v_cndmask_b32_e64 v16, 0, 1, s[0:1]
	v_cndmask_b32_e32 v15, v16, v15, vcc
	v_and_b32_e32 v15, 1, v15
	v_cmp_eq_u32_e64 s[0:1], 1, v15
	s_nop 1
	v_cndmask_b32_e64 v15, 0, v18, s[0:1]
	v_bfe_u32 v16, v15, 16, 1
	v_add3_u32 v15, v15, v16, s45
	v_add_u32_e32 v16, 0x120, v12
	v_add_u32_e32 v17, v6, v16
	ds_write_b16_d16_hi v17, v15
	v_or_b32_e32 v15, 3, v2
	v_cmp_le_i32_e64 s[0:1], v36, v15
	s_nop 1
	v_cndmask_b32_e64 v17, 0, 1, s[0:1]
	v_cmp_ge_i32_e64 s[0:1], v36, v15
	s_nop 1
	v_cndmask_b32_e64 v18, 0, 1, s[0:1]
	v_cndmask_b32_e32 v17, v18, v17, vcc
	v_and_b32_e32 v17, 1, v17
	v_cmp_eq_u32_e64 s[0:1], 1, v17
	s_nop 1
	v_cndmask_b32_e64 v17, 0, v19, s[0:1]
	v_bfe_u32 v18, v17, 16, 1
	v_add3_u32 v17, v17, v18, s45
	v_add_u32_e32 v18, 0x1b0, v12
	v_add_u32_e32 v6, v6, v18
	ds_write_b16_d16_hi v6, v17
	v_or_b32_e32 v6, 16, v36
	v_cmp_le_i32_e64 s[0:1], v6, v2
	s_nop 1
	v_cndmask_b32_e64 v17, 0, 1, s[0:1]
	v_cmp_ge_i32_e64 s[0:1], v6, v2
	s_nop 1
	v_cndmask_b32_e64 v19, 0, 1, s[0:1]
	v_cndmask_b32_e32 v17, v19, v17, vcc
	v_and_b32_e32 v17, 1, v17
	v_cmp_eq_u32_e64 s[0:1], 1, v17
	s_nop 1
	v_cndmask_b32_e64 v8, 0, v8, s[0:1]
	v_cmp_le_i32_e64 s[0:1], v6, v7
	v_bfe_u32 v17, v8, 16, 1
	v_add3_u32 v8, v8, v17, s45
	v_cndmask_b32_e64 v7, 0, 1, s[0:1]
	v_cmp_gt_i32_e64 s[0:1], v6, v2
	v_lshlrev_b32_e32 v17, 1, v6
	v_add3_u32 v12, s49, v12, v17
	v_cndmask_b32_e64 v2, 0, 1, s[0:1]
	v_cndmask_b32_e32 v2, v2, v7, vcc
	v_and_b32_e32 v2, 1, v2
	v_cmp_eq_u32_e64 s[0:1], 1, v2
	ds_write_b16_d16_hi v12, v8
	s_nop 0
	v_cndmask_b32_e64 v2, 0, v9, s[0:1]
	v_bfe_u32 v7, v2, 16, 1
	v_add3_u32 v2, v2, v7, s45
	v_add3_u32 v7, s49, v14, v17
	v_cmp_le_i32_e64 s[0:1], v6, v13
	ds_write_b16_d16_hi v7, v2
	s_nop 0
	v_cndmask_b32_e64 v2, 0, 1, s[0:1]
	v_cmp_ge_i32_e64 s[0:1], v6, v13
	s_nop 1
	v_cndmask_b32_e64 v7, 0, 1, s[0:1]
	v_cndmask_b32_e32 v2, v7, v2, vcc
	v_and_b32_e32 v2, 1, v2
	v_cmp_eq_u32_e64 s[0:1], 1, v2
	s_nop 1
	v_cndmask_b32_e64 v2, 0, v10, s[0:1]
	v_bfe_u32 v7, v2, 16, 1
	v_add3_u32 v2, v2, v7, s45
	v_add3_u32 v7, s49, v16, v17
	v_cmp_le_i32_e64 s[0:1], v6, v15
	ds_write_b16_d16_hi v7, v2
	s_nop 0
	v_cndmask_b32_e64 v2, 0, 1, s[0:1]
	v_cmp_ge_i32_e64 s[0:1], v6, v15
	s_nop 1
	v_cndmask_b32_e64 v6, 0, 1, s[0:1]
	v_cndmask_b32_e32 v2, v6, v2, vcc
	v_and_b32_e32 v2, 1, v2
	v_cmp_eq_u32_e64 s[0:1], 1, v2
	s_nop 1
	v_cndmask_b32_e64 v2, 0, v11, s[0:1]
	v_bfe_u32 v6, v2, 16, 1
	v_add3_u32 v2, v2, v6, s45
	v_add3_u32 v6, s49, v18, v17
	ds_write_b16_d16_hi v6, v2
	v_mov_b32_e32 v6, v0
	s_waitcnt lgkmcnt(0)
	s_barrier
	s_nop 0
	v_cmp_gt_i32_e64 s[0:1], s19, v6
	s_and_saveexec_b64 s[14:15], s[0:1]
	s_cbranch_execz .LBB0_1633
	s_lshl_b64 s[0:1], s[8:9], 13
	v_readlane_b32 s8, v238, 9
	s_add_u32 s8, s8, s0
	v_readlane_b32 s0, v238, 7
	s_addc_u32 s9, s0, s1
	v_lshlrev_b32_e32 v7, 3, v6
	s_mov_b64 s[16:17], 0

.LBB0_1709:
	v_ashrrev_i32_e32 v37, 8, v18
	v_and_b32_e32 v34, 0xff, v18
	v_lshlrev_b32_e32 v19, 13, v37
	v_lshlrev_b32_e32 v20, 1, v34
	v_add3_u32 v38, s25, v19, v20
	v_add3_u32 v19, s54, v19, v20
	ds_read_u16 v20, v38
	ds_read_u16 v22, v38 offset:512
	ds_read_u16 v24, v38 offset:1024
	ds_read_u16 v26, v38 offset:1536
	ds_read_u16 v28, v38 offset:2048
	ds_read_u16 v39, v38 offset:2560
	ds_read_u16 v42, v38 offset:3072
	ds_read_u16 v44, v38 offset:3584
	ds_read_u16 v21, v19
	ds_read_u16 v23, v19 offset:512
	ds_read_u16 v25, v19 offset:1024
	ds_read_u16 v27, v19 offset:1536
	ds_read_u16 v29, v19 offset:2048
	ds_read_u16 v41, v19 offset:2560
	ds_read_u16 v43, v19 offset:3072
	ds_read_u16 v45, v19 offset:3584
	s_waitcnt lgkmcnt(7)
	v_lshlrev_b32_e32 v21, 16, v21
	v_lshlrev_b32_e32 v40, 16, v39
	s_waitcnt lgkmcnt(2)
	v_lshlrev_b32_e32 v39, 16, v41
	v_xor_b32_e32 v41, 0x80000000, v39
	s_waitcnt lgkmcnt(1)
	v_lshlrev_b32_e32 v39, 16, v43
	v_xor_b32_e32 v43, 0x80000000, v39
	s_waitcnt lgkmcnt(0)
	v_lshlrev_b32_e32 v39, 16, v45
	v_xor_b32_e32 v45, 0x80000000, v39
	ds_read_u16 v39, v38 offset:4096
	ds_read_u16 v48, v38 offset:4608
	ds_read_u16 v50, v38 offset:5120
	ds_read_u16 v52, v38 offset:5632
	ds_read_u16 v54, v38 offset:6144
	ds_read_u16 v56, v38 offset:6656
	ds_read_u16 v58, v38 offset:7168
	ds_read_u16 v38, v38 offset:7680
	s_waitcnt lgkmcnt(7)
	v_lshlrev_b32_e32 v46, 16, v39
	ds_read_u16 v39, v19 offset:4096
	ds_read_u16 v49, v19 offset:4608
	ds_read_u16 v51, v19 offset:5120
	ds_read_u16 v53, v19 offset:5632
	ds_read_u16 v55, v19 offset:6144
	ds_read_u16 v57, v19 offset:6656
	ds_read_u16 v59, v19 offset:7168
	ds_read_u16 v19, v19 offset:7680
	s_waitcnt lgkmcnt(7)
	v_lshlrev_b32_e32 v39, 16, v39
	v_xor_b32_e32 v47, 0x80000000, v39
	s_waitcnt lgkmcnt(6)
	v_lshlrev_b32_e32 v39, 16, v49
	v_xor_b32_e32 v49, 0x80000000, v39
	s_waitcnt lgkmcnt(5)
	v_lshlrev_b32_e32 v39, 16, v51
	v_xor_b32_e32 v51, 0x80000000, v39
	s_waitcnt lgkmcnt(4)
	v_lshlrev_b32_e32 v39, 16, v53
	v_lshlrev_b32_e32 v29, 16, v29
	v_xor_b32_e32 v53, 0x80000000, v39
	s_waitcnt lgkmcnt(3)
	v_lshlrev_b32_e32 v39, 16, v55
	v_lshlrev_b32_e32 v20, 16, v20
	v_xor_b32_e32 v21, 0x80000000, v21
	v_lshlrev_b32_e32 v23, 16, v23
	v_lshlrev_b32_e32 v28, 16, v28
	v_xor_b32_e32 v29, 0x80000000, v29
	v_lshlrev_b32_e32 v54, 16, v54
	v_xor_b32_e32 v55, 0x80000000, v39
	s_waitcnt lgkmcnt(2)
	v_lshlrev_b32_e32 v39, 16, v57
	s_waitcnt lgkmcnt(0)
	v_lshlrev_b32_e32 v19, 16, v19
	v_lshlrev_b32_e32 v22, 16, v22
	v_xor_b32_e32 v23, 0x80000000, v23
	v_lshlrev_b32_e32 v25, 16, v25
	v_lshlrev_b32_e32 v48, 16, v48
	v_lshlrev_b32_e32 v56, 16, v56
	v_xor_b32_e32 v57, 0x80000000, v39
	v_lshlrev_b32_e32 v39, 16, v59
	v_lshlrev_b32_e32 v60, 16, v38
	v_xor_b32_e32 v61, 0x80000000, v19
	v_bfe_u32 v38, v18, 4, 4
	v_pk_add_f32 v[18:19], v[20:21], v[46:47]
	v_pk_add_f32 v[20:21], v[20:21], v[46:47] neg_lo:[0,1] neg_hi:[0,1]
	v_pk_add_f32 v[46:47], v[28:29], v[54:55]
	v_pk_add_f32 v[28:29], v[28:29], v[54:55] neg_lo:[0,1] neg_hi:[0,1]
	v_lshlrev_b32_e32 v24, 16, v24
	v_xor_b32_e32 v25, 0x80000000, v25
	v_lshlrev_b32_e32 v27, 16, v27
	v_lshlrev_b32_e32 v42, 16, v42
	v_lshlrev_b32_e32 v50, 16, v50
	v_lshlrev_b32_e32 v58, 16, v58
	v_xor_b32_e32 v59, 0x80000000, v39
	v_pk_add_f32 v[54:55], v[18:19], v[46:47]
	v_pk_add_f32 v[46:47], v[18:19], v[46:47] neg_lo:[0,1] neg_hi:[0,1]
	v_pk_add_f32 v[62:63], v[20:21], v[28:29] op_sel:[0,1] op_sel_hi:[1,0] neg_hi:[0,1]
	v_pk_add_f32 v[64:65], v[20:21], v[28:29] op_sel:[0,1] op_sel_hi:[1,0] neg_lo:[0,1]
	v_pk_add_f32 v[18:19], v[22:23], v[48:49]
	v_pk_add_f32 v[20:21], v[22:23], v[48:49] neg_lo:[0,1] neg_hi:[0,1]
	v_pk_add_f32 v[22:23], v[40:41], v[56:57]
	v_pk_add_f32 v[28:29], v[40:41], v[56:57] neg_lo:[0,1] neg_hi:[0,1]
	v_lshlrev_b32_e32 v26, 16, v26
	v_xor_b32_e32 v27, 0x80000000, v27
	v_lshlrev_b32_e32 v44, 16, v44
	v_lshlrev_b32_e32 v52, 16, v52
	v_pk_add_f32 v[40:41], v[18:19], v[22:23]
	v_pk_add_f32 v[22:23], v[18:19], v[22:23] neg_lo:[0,1] neg_hi:[0,1]
	v_pk_add_f32 v[18:19], v[20:21], v[28:29] op_sel:[0,1] op_sel_hi:[1,0] neg_hi:[0,1]
	v_pk_add_f32 v[28:29], v[20:21], v[28:29] op_sel:[0,1] op_sel_hi:[1,0] neg_lo:[0,1]
	v_pk_add_f32 v[20:21], v[24:25], v[50:51]
	v_pk_add_f32 v[24:25], v[24:25], v[50:51] neg_lo:[0,1] neg_hi:[0,1]
	v_pk_add_f32 v[48:49], v[42:43], v[58:59]
	v_pk_add_f32 v[42:43], v[42:43], v[58:59] neg_lo:[0,1] neg_hi:[0,1]
	v_pk_add_f32 v[50:51], v[20:21], v[48:49]
	v_pk_add_f32 v[48:49], v[20:21], v[48:49] neg_lo:[0,1] neg_hi:[0,1]
	v_pk_add_f32 v[56:57], v[24:25], v[42:43] op_sel:[0,1] op_sel_hi:[1,0] neg_hi:[0,1]
	v_pk_add_f32 v[42:43], v[24:25], v[42:43] op_sel:[0,1] op_sel_hi:[1,0] neg_lo:[0,1]
	v_pk_add_f32 v[20:21], v[26:27], v[52:53]
	v_pk_add_f32 v[24:25], v[26:27], v[52:53] neg_lo:[0,1] neg_hi:[0,1]
	v_pk_add_f32 v[26:27], v[44:45], v[60:61]
	v_pk_add_f32 v[44:45], v[44:45], v[60:61] neg_lo:[0,1] neg_hi:[0,1]
	v_pk_add_f32 v[52:53], v[20:21], v[26:27]
	v_pk_add_f32 v[58:59], v[20:21], v[26:27] neg_lo:[0,1] neg_hi:[0,1]
	v_pk_add_f32 v[26:27], v[24:25], v[44:45] op_sel:[0,1] op_sel_hi:[1,0] neg_hi:[0,1]
	v_pk_add_f32 v[44:45], v[24:25], v[44:45] op_sel:[0,1] op_sel_hi:[1,0] neg_lo:[0,1]
	v_mov_b64_e32 v[24:25], s[38:39]
	v_pk_mul_f32 v[20:21], v[18:19], v[24:25] op_sel:[0,0] op_sel_hi:[0,1]
	v_mad_i32_i24 v35, v37, s3, 0
	v_pk_fma_f32 v[60:61], v[18:19], v[24:25], v[20:21] op_sel:[1,1,0] op_sel_hi:[1,0,1] neg_lo:[0,1,0]
	v_mov_b64_e32 v[20:21], s[40:41]
	v_pk_mul_f32 v[18:19], v[56:57], v[20:21] op_sel:[0,0] op_sel_hi:[0,1]
	v_lshlrev_b32_e32 v39, 3, v34
	v_pk_fma_f32 v[56:57], v[56:57], v[20:21], v[18:19] op_sel:[1,1,0] op_sel_hi:[1,0,1] neg_lo:[0,1,0]
	v_mov_b64_e32 v[18:19], s[44:45]
	v_pk_mul_f32 v[66:67], v[26:27], v[18:19] op_sel:[0,0] op_sel_hi:[0,1]
	v_lshlrev_b32_e32 v74, 3, v38
	v_pk_fma_f32 v[66:67], v[26:27], v[18:19], v[66:67] op_sel:[1,1,0] op_sel_hi:[1,0,1] neg_lo:[0,1,0]
	v_pk_mul_f32 v[26:27], v[22:23], v[20:21] op_sel:[0,0] op_sel_hi:[0,1]
	v_add3_u32 v74, v35, v39, v74
	v_pk_fma_f32 v[68:69], v[22:23], v[20:21], v[26:27] op_sel:[1,1,0] op_sel_hi:[1,0,1] neg_lo:[0,1,0]
	v_mov_b64_e32 v[26:27], s[36:37]
	v_pk_mul_f32 v[22:23], v[48:49], v[26:27] op_sel:[0,0] op_sel_hi:[0,1]
	v_lshl_add_u32 v78, v38, 11, v35
	v_pk_fma_f32 v[48:49], v[48:49], v[26:27], v[22:23] op_sel:[1,1,0] op_sel_hi:[1,0,1] neg_lo:[0,1,0]
	v_mov_b64_e32 v[22:23], s[46:47]
	v_pk_mul_f32 v[70:71], v[58:59], v[22:23] op_sel:[0,0] op_sel_hi:[0,1]
	v_add_u32_e32 v39, v78, v39
	v_pk_fma_f32 v[58:59], v[58:59], v[22:23], v[70:71] op_sel:[1,1,0] op_sel_hi:[1,0,1] neg_lo:[0,1,0]
	v_pk_mul_f32 v[70:71], v[28:29], v[18:19] op_sel:[0,0] op_sel_hi:[0,1]
	v_pk_fma_f32 v[70:71], v[28:29], v[18:19], v[70:71] op_sel:[1,1,0] op_sel_hi:[1,0,1] neg_lo:[0,1,0]
	v_pk_mul_f32 v[28:29], v[42:43], v[22:23] op_sel:[0,0] op_sel_hi:[0,1]
	v_pk_fma_f32 v[42:43], v[42:43], v[22:23], v[28:29] op_sel:[1,1,0] op_sel_hi:[1,0,1] neg_lo:[0,1,0]
	v_mov_b64_e32 v[28:29], s[48:49]
	v_pk_mul_f32 v[72:73], v[44:45], v[28:29] op_sel:[0,0] op_sel_hi:[0,1]
	v_pk_fma_f32 v[44:45], v[44:45], v[28:29], v[72:73] op_sel:[1,1,0] op_sel_hi:[1,0,1] neg_lo:[0,1,0]
	v_pk_add_f32 v[72:73], v[54:55], v[50:51]
	v_pk_add_f32 v[50:51], v[54:55], v[50:51] neg_lo:[0,1] neg_hi:[0,1]
	v_pk_add_f32 v[54:55], v[40:41], v[52:53]
	v_pk_add_f32 v[40:41], v[40:41], v[52:53] neg_lo:[0,1] neg_hi:[0,1]
	v_pk_add_f32 v[52:53], v[72:73], v[54:55]
	v_pk_add_f32 v[54:55], v[72:73], v[54:55] neg_lo:[0,1] neg_hi:[0,1]
	v_pk_add_f32 v[72:73], v[50:51], v[40:41] op_sel:[0,1] op_sel_hi:[1,0] neg_hi:[0,1]
	v_pk_add_f32 v[40:41], v[50:51], v[40:41] op_sel:[0,1] op_sel_hi:[1,0] neg_lo:[0,1]
	v_pk_add_f32 v[50:51], v[62:63], v[56:57]
	v_pk_add_f32 v[56:57], v[62:63], v[56:57] neg_lo:[0,1] neg_hi:[0,1]
	v_pk_add_f32 v[62:63], v[60:61], v[66:67]
	v_pk_add_f32 v[60:61], v[60:61], v[66:67] neg_lo:[0,1] neg_hi:[0,1]
	v_pk_add_f32 v[66:67], v[50:51], v[62:63]
	v_pk_add_f32 v[50:51], v[50:51], v[62:63] neg_lo:[0,1] neg_hi:[0,1]
	v_pk_add_f32 v[62:63], v[56:57], v[60:61] op_sel:[0,1] op_sel_hi:[1,0] neg_hi:[0,1]
	v_pk_add_f32 v[56:57], v[56:57], v[60:61] op_sel:[0,1] op_sel_hi:[1,0] neg_lo:[0,1]
	v_pk_add_f32 v[60:61], v[46:47], v[48:49]
	v_pk_add_f32 v[46:47], v[46:47], v[48:49] neg_lo:[0,1] neg_hi:[0,1]
	v_pk_add_f32 v[48:49], v[68:69], v[58:59]
	v_pk_add_f32 v[58:59], v[68:69], v[58:59] neg_lo:[0,1] neg_hi:[0,1]
	v_pk_add_f32 v[68:69], v[60:61], v[48:49]
	v_pk_add_f32 v[48:49], v[60:61], v[48:49] neg_lo:[0,1] neg_hi:[0,1]
	v_pk_add_f32 v[60:61], v[46:47], v[58:59] op_sel:[0,1] op_sel_hi:[1,0] neg_hi:[0,1]
	v_pk_add_f32 v[46:47], v[46:47], v[58:59] op_sel:[0,1] op_sel_hi:[1,0] neg_lo:[0,1]
	v_pk_add_f32 v[58:59], v[64:65], v[42:43]
	v_pk_add_f32 v[42:43], v[64:65], v[42:43] neg_lo:[0,1] neg_hi:[0,1]
	v_pk_add_f32 v[64:65], v[70:71], v[44:45]
	v_pk_add_f32 v[44:45], v[70:71], v[44:45] neg_lo:[0,1] neg_hi:[0,1]
	v_pk_add_f32 v[70:71], v[58:59], v[64:65]
	v_pk_add_f32 v[58:59], v[58:59], v[64:65] neg_lo:[0,1] neg_hi:[0,1]
	v_pk_add_f32 v[64:65], v[42:43], v[44:45] op_sel:[0,1] op_sel_hi:[1,0] neg_hi:[0,1]
	v_pk_add_f32 v[42:43], v[42:43], v[44:45] op_sel:[0,1] op_sel_hi:[1,0] neg_lo:[0,1]
	v_mov_b32_e32 v44, v1
	v_mov_b32_e32 v45, v31
	ds_write_b64 v74, v[52:53]
	v_pk_mul_f32 v[52:53], v[66:67], v[44:45] op_sel:[0,0] op_sel_hi:[0,1]
	v_pk_fma_f32 v[52:53], v[66:67], v[44:45], v[52:53] op_sel:[1,1,0] op_sel_hi:[1,0,1] neg_lo:[0,1,0]
	ds_write_b64 v74, v[52:53] offset:2176
	v_pk_mul_f32 v[52:53], v[44:45], v[44:45] op_sel:[0,0] op_sel_hi:[0,1]
	v_pk_fma_f32 v[52:53], v[44:45], v[44:45], v[52:53] op_sel:[1,1,0] op_sel_hi:[1,0,1] neg_lo:[0,1,0]
	v_pk_mul_f32 v[66:67], v[68:69], v[52:53] op_sel:[0,0] op_sel_hi:[0,1]
	v_pk_fma_f32 v[66:67], v[68:69], v[52:53], v[66:67] op_sel:[1,1,0] op_sel_hi:[1,0,1] neg_lo:[0,1,0]
	ds_write_b64 v74, v[66:67] offset:4352
	v_pk_mul_f32 v[66:67], v[52:53], v[44:45] op_sel:[0,0] op_sel_hi:[0,1]
	v_pk_fma_f32 v[52:53], v[52:53], v[44:45], v[66:67] op_sel:[1,1,0] op_sel_hi:[1,0,1] neg_lo:[0,1,0]
	v_pk_mul_f32 v[66:67], v[70:71], v[52:53] op_sel:[0,0] op_sel_hi:[0,1]
	v_pk_fma_f32 v[66:67], v[70:71], v[52:53], v[66:67] op_sel:[1,1,0] op_sel_hi:[1,0,1] neg_lo:[0,1,0]
	ds_write_b64 v74, v[66:67] offset:6528
	v_pk_mul_f32 v[66:67], v[52:53], v[44:45] op_sel:[0,0] op_sel_hi:[0,1]
	v_pk_fma_f32 v[52:53], v[52:53], v[44:45], v[66:67] op_sel:[1,1,0] op_sel_hi:[1,0,1] neg_lo:[0,1,0]
	v_pk_mul_f32 v[66:67], v[72:73], v[52:53] op_sel:[0,0] op_sel_hi:[0,1]
	v_pk_fma_f32 v[66:67], v[72:73], v[52:53], v[66:67] op_sel:[1,1,0] op_sel_hi:[1,0,1] neg_lo:[0,1,0]
	ds_write_b64 v74, v[66:67] offset:8704
	v_pk_mul_f32 v[66:67], v[52:53], v[44:45] op_sel:[0,0] op_sel_hi:[0,1]
	v_pk_fma_f32 v[52:53], v[52:53], v[44:45], v[66:67] op_sel:[1,1,0] op_sel_hi:[1,0,1] neg_lo:[0,1,0]
	v_pk_mul_f32 v[66:67], v[62:63], v[52:53] op_sel:[0,0] op_sel_hi:[0,1]
	v_pk_fma_f32 v[62:63], v[62:63], v[52:53], v[66:67] op_sel:[1,1,0] op_sel_hi:[1,0,1] neg_lo:[0,1,0]
	ds_write_b64 v74, v[62:63] offset:10880
	v_pk_mul_f32 v[62:63], v[52:53], v[44:45] op_sel:[0,0] op_sel_hi:[0,1]
	v_pk_fma_f32 v[52:53], v[52:53], v[44:45], v[62:63] op_sel:[1,1,0] op_sel_hi:[1,0,1] neg_lo:[0,1,0]
	v_pk_mul_f32 v[62:63], v[60:61], v[52:53] op_sel:[0,0] op_sel_hi:[0,1]
	v_pk_fma_f32 v[60:61], v[60:61], v[52:53], v[62:63] op_sel:[1,1,0] op_sel_hi:[1,0,1] neg_lo:[0,1,0]
	ds_write_b64 v74, v[60:61] offset:13056
	v_pk_mul_f32 v[60:61], v[52:53], v[44:45] op_sel:[0,0] op_sel_hi:[0,1]
	v_pk_fma_f32 v[52:53], v[52:53], v[44:45], v[60:61] op_sel:[1,1,0] op_sel_hi:[1,0,1] neg_lo:[0,1,0]
	v_pk_mul_f32 v[60:61], v[64:65], v[52:53] op_sel:[0,0] op_sel_hi:[0,1]
	v_pk_fma_f32 v[60:61], v[64:65], v[52:53], v[60:61] op_sel:[1,1,0] op_sel_hi:[1,0,1] neg_lo:[0,1,0]
	ds_write_b64 v74, v[60:61] offset:15232
	v_pk_mul_f32 v[60:61], v[52:53], v[44:45] op_sel:[0,0] op_sel_hi:[0,1]
	v_pk_fma_f32 v[52:53], v[52:53], v[44:45], v[60:61] op_sel:[1,1,0] op_sel_hi:[1,0,1] neg_lo:[0,1,0]
	v_pk_mul_f32 v[60:61], v[54:55], v[52:53] op_sel:[0,0] op_sel_hi:[0,1]
	v_pk_fma_f32 v[54:55], v[54:55], v[52:53], v[60:61] op_sel:[1,1,0] op_sel_hi:[1,0,1] neg_lo:[0,1,0]
	ds_write_b64 v74, v[54:55] offset:17408
	v_pk_mul_f32 v[54:55], v[52:53], v[44:45] op_sel:[0,0] op_sel_hi:[0,1]
	v_pk_fma_f32 v[52:53], v[52:53], v[44:45], v[54:55] op_sel:[1,1,0] op_sel_hi:[1,0,1] neg_lo:[0,1,0]
	v_pk_mul_f32 v[54:55], v[50:51], v[52:53] op_sel:[0,0] op_sel_hi:[0,1]
	v_pk_fma_f32 v[50:51], v[50:51], v[52:53], v[54:55] op_sel:[1,1,0] op_sel_hi:[1,0,1] neg_lo:[0,1,0]
	ds_write_b64 v74, v[50:51] offset:19584
	v_pk_mul_f32 v[50:51], v[52:53], v[44:45] op_sel:[0,0] op_sel_hi:[0,1]
	v_pk_fma_f32 v[50:51], v[52:53], v[44:45], v[50:51] op_sel:[1,1,0] op_sel_hi:[1,0,1] neg_lo:[0,1,0]
	v_pk_mul_f32 v[52:53], v[48:49], v[50:51] op_sel:[0,0] op_sel_hi:[0,1]
	v_pk_fma_f32 v[48:49], v[48:49], v[50:51], v[52:53] op_sel:[1,1,0] op_sel_hi:[1,0,1] neg_lo:[0,1,0]
	ds_write_b64 v74, v[48:49] offset:21760
	v_pk_mul_f32 v[48:49], v[50:51], v[44:45] op_sel:[0,0] op_sel_hi:[0,1]
	v_pk_fma_f32 v[48:49], v[50:51], v[44:45], v[48:49] op_sel:[1,1,0] op_sel_hi:[1,0,1] neg_lo:[0,1,0]
	v_pk_mul_f32 v[50:51], v[58:59], v[48:49] op_sel:[0,0] op_sel_hi:[0,1]
	v_pk_fma_f32 v[50:51], v[58:59], v[48:49], v[50:51] op_sel:[1,1,0] op_sel_hi:[1,0,1] neg_lo:[0,1,0]
	ds_write_b64 v74, v[50:51] offset:23936
	v_pk_mul_f32 v[50:51], v[48:49], v[44:45] op_sel:[0,0] op_sel_hi:[0,1]
	v_pk_fma_f32 v[48:49], v[48:49], v[44:45], v[50:51] op_sel:[1,1,0] op_sel_hi:[1,0,1] neg_lo:[0,1,0]
	v_pk_mul_f32 v[50:51], v[40:41], v[48:49] op_sel:[0,0] op_sel_hi:[0,1]
	v_pk_fma_f32 v[40:41], v[40:41], v[48:49], v[50:51] op_sel:[1,1,0] op_sel_hi:[1,0,1] neg_lo:[0,1,0]
	ds_write_b64 v74, v[40:41] offset:26112
	v_pk_mul_f32 v[40:41], v[48:49], v[44:45] op_sel:[0,0] op_sel_hi:[0,1]
	v_pk_fma_f32 v[40:41], v[48:49], v[44:45], v[40:41] op_sel:[1,1,0] op_sel_hi:[1,0,1] neg_lo:[0,1,0]
	v_pk_mul_f32 v[48:49], v[56:57], v[40:41] op_sel:[0,0] op_sel_hi:[0,1]
	v_pk_fma_f32 v[48:49], v[56:57], v[40:41], v[48:49] op_sel:[1,1,0] op_sel_hi:[1,0,1] neg_lo:[0,1,0]
	ds_write_b64 v74, v[48:49] offset:28288
	v_pk_mul_f32 v[48:49], v[40:41], v[44:45] op_sel:[0,0] op_sel_hi:[0,1]
	v_pk_fma_f32 v[40:41], v[40:41], v[44:45], v[48:49] op_sel:[1,1,0] op_sel_hi:[1,0,1] neg_lo:[0,1,0]
	v_pk_mul_f32 v[48:49], v[46:47], v[40:41] op_sel:[0,0] op_sel_hi:[0,1]
	v_pk_fma_f32 v[46:47], v[46:47], v[40:41], v[48:49] op_sel:[1,1,0] op_sel_hi:[1,0,1] neg_lo:[0,1,0]
	ds_write_b64 v74, v[46:47] offset:30464
	v_pk_mul_f32 v[46:47], v[40:41], v[44:45] op_sel:[0,0] op_sel_hi:[0,1]
	v_pk_fma_f32 v[40:41], v[40:41], v[44:45], v[46:47] op_sel:[1,1,0] op_sel_hi:[1,0,1] neg_lo:[0,1,0]
	v_pk_mul_f32 v[44:45], v[42:43], v[40:41] op_sel:[0,0] op_sel_hi:[0,1]
	v_pk_fma_f32 v[40:41], v[42:43], v[40:41], v[44:45] op_sel:[1,1,0] op_sel_hi:[1,0,1] neg_lo:[0,1,0]
	ds_write_b64 v74, v[40:41] offset:32640
	s_waitcnt lgkmcnt(0)
	s_barrier
	ds_read2_b64 v[40:43], v39 offset1:17
	ds_read2_b64 v[44:47], v39 offset0:34 offset1:51
	ds_read2_b64 v[48:51], v39 offset0:68 offset1:85
	ds_read2_b64 v[52:55], v39 offset0:136 offset1:153
	ds_read2_b64 v[56:59], v39 offset0:102 offset1:119
	ds_read2_b64 v[60:63], v39 offset0:204 offset1:221
	ds_read2_b64 v[64:67], v39 offset0:170 offset1:187
	ds_read2_b64 v[68:71], v39 offset0:238 offset1:255
	s_waitcnt lgkmcnt(4)
	v_pk_add_f32 v[72:73], v[40:41], v[52:53]
	v_pk_add_f32 v[40:41], v[40:41], v[52:53] neg_lo:[0,1] neg_hi:[0,1]
	s_waitcnt lgkmcnt(2)
	v_pk_add_f32 v[52:53], v[48:49], v[60:61]
	v_pk_add_f32 v[48:49], v[48:49], v[60:61] neg_lo:[0,1] neg_hi:[0,1]
	v_pk_add_f32 v[60:61], v[72:73], v[52:53]
	v_pk_add_f32 v[52:53], v[72:73], v[52:53] neg_lo:[0,1] neg_hi:[0,1]
	v_pk_add_f32 v[72:73], v[40:41], v[48:49] op_sel:[0,1] op_sel_hi:[1,0] neg_hi:[0,1]
	v_pk_add_f32 v[40:41], v[40:41], v[48:49] op_sel:[0,1] op_sel_hi:[1,0] neg_lo:[0,1]
	v_pk_add_f32 v[48:49], v[42:43], v[54:55]
	v_pk_add_f32 v[42:43], v[42:43], v[54:55] neg_lo:[0,1] neg_hi:[0,1]
	v_pk_add_f32 v[54:55], v[50:51], v[62:63]
	v_pk_add_f32 v[50:51], v[50:51], v[62:63] neg_lo:[0,1] neg_hi:[0,1]
	v_pk_add_f32 v[62:63], v[48:49], v[54:55]
	v_pk_add_f32 v[48:49], v[48:49], v[54:55] neg_lo:[0,1] neg_hi:[0,1]
	v_pk_add_f32 v[54:55], v[42:43], v[50:51] op_sel:[0,1] op_sel_hi:[1,0] neg_hi:[0,1]
	v_pk_add_f32 v[42:43], v[42:43], v[50:51] op_sel:[0,1] op_sel_hi:[1,0] neg_lo:[0,1]
	s_waitcnt lgkmcnt(1)
	v_pk_add_f32 v[50:51], v[44:45], v[64:65]
	v_pk_add_f32 v[44:45], v[44:45], v[64:65] neg_lo:[0,1] neg_hi:[0,1]
	s_waitcnt lgkmcnt(0)
	v_pk_add_f32 v[64:65], v[56:57], v[68:69]
	v_pk_add_f32 v[56:57], v[56:57], v[68:69] neg_lo:[0,1] neg_hi:[0,1]
	v_pk_add_f32 v[68:69], v[50:51], v[64:65]
	v_pk_add_f32 v[50:51], v[50:51], v[64:65] neg_lo:[0,1] neg_hi:[0,1]
	v_pk_add_f32 v[64:65], v[44:45], v[56:57] op_sel:[0,1] op_sel_hi:[1,0] neg_hi:[0,1]
	v_pk_add_f32 v[44:45], v[44:45], v[56:57] op_sel:[0,1] op_sel_hi:[1,0] neg_lo:[0,1]
	v_pk_add_f32 v[56:57], v[46:47], v[66:67]
	v_pk_add_f32 v[46:47], v[46:47], v[66:67] neg_lo:[0,1] neg_hi:[0,1]
	v_pk_add_f32 v[66:67], v[58:59], v[70:71]
	v_pk_add_f32 v[58:59], v[58:59], v[70:71] neg_lo:[0,1] neg_hi:[0,1]
	v_pk_add_f32 v[70:71], v[56:57], v[66:67]
	v_pk_add_f32 v[56:57], v[56:57], v[66:67] neg_lo:[0,1] neg_hi:[0,1]
	v_pk_add_f32 v[66:67], v[46:47], v[58:59] op_sel:[0,1] op_sel_hi:[1,0] neg_hi:[0,1]
	v_pk_add_f32 v[46:47], v[46:47], v[58:59] op_sel:[0,1] op_sel_hi:[1,0] neg_lo:[0,1]
	v_pk_mul_f32 v[58:59], v[54:55], v[24:25] op_sel:[0,0] op_sel_hi:[0,1]
	v_pk_fma_f32 v[54:55], v[54:55], v[24:25], v[58:59] op_sel:[1,1,0] op_sel_hi:[1,0,1] neg_lo:[0,1,0]
	v_pk_mul_f32 v[58:59], v[64:65], v[20:21] op_sel:[0,0] op_sel_hi:[0,1]
	v_pk_fma_f32 v[58:59], v[64:65], v[20:21], v[58:59] op_sel:[1,1,0] op_sel_hi:[1,0,1] neg_lo:[0,1,0]
	v_pk_mul_f32 v[64:65], v[66:67], v[18:19] op_sel:[0,0] op_sel_hi:[0,1]
	v_pk_fma_f32 v[64:65], v[66:67], v[18:19], v[64:65] op_sel:[1,1,0] op_sel_hi:[1,0,1] neg_lo:[0,1,0]
	v_pk_mul_f32 v[66:67], v[48:49], v[20:21] op_sel:[0,0] op_sel_hi:[0,1]
	v_pk_fma_f32 v[48:49], v[48:49], v[20:21], v[66:67] op_sel:[1,1,0] op_sel_hi:[1,0,1] neg_lo:[0,1,0]
	v_pk_mul_f32 v[66:67], v[50:51], v[26:27] op_sel:[0,0] op_sel_hi:[0,1]
	v_pk_fma_f32 v[50:51], v[50:51], v[26:27], v[66:67] op_sel:[1,1,0] op_sel_hi:[1,0,1] neg_lo:[0,1,0]
	v_pk_mul_f32 v[66:67], v[56:57], v[22:23] op_sel:[0,0] op_sel_hi:[0,1]
	v_pk_fma_f32 v[56:57], v[56:57], v[22:23], v[66:67] op_sel:[1,1,0] op_sel_hi:[1,0,1] neg_lo:[0,1,0]
	v_pk_mul_f32 v[66:67], v[42:43], v[18:19] op_sel:[0,0] op_sel_hi:[0,1]
	v_pk_fma_f32 v[42:43], v[42:43], v[18:19], v[66:67] op_sel:[1,1,0] op_sel_hi:[1,0,1] neg_lo:[0,1,0]
	v_pk_mul_f32 v[66:67], v[44:45], v[22:23] op_sel:[0,0] op_sel_hi:[0,1]
	v_pk_fma_f32 v[44:45], v[44:45], v[22:23], v[66:67] op_sel:[1,1,0] op_sel_hi:[1,0,1] neg_lo:[0,1,0]
	v_pk_mul_f32 v[66:67], v[46:47], v[28:29] op_sel:[0,0] op_sel_hi:[0,1]
	v_pk_fma_f32 v[46:47], v[46:47], v[28:29], v[66:67] op_sel:[1,1,0] op_sel_hi:[1,0,1] neg_lo:[0,1,0]
	v_pk_add_f32 v[66:67], v[60:61], v[68:69]
	v_pk_add_f32 v[60:61], v[60:61], v[68:69] neg_lo:[0,1] neg_hi:[0,1]
	v_pk_add_f32 v[68:69], v[62:63], v[70:71]
	v_pk_add_f32 v[62:63], v[62:63], v[70:71] neg_lo:[0,1] neg_hi:[0,1]
	v_pk_add_f32 v[70:71], v[66:67], v[68:69]
	v_pk_add_f32 v[66:67], v[66:67], v[68:69] neg_lo:[0,1] neg_hi:[0,1]
	v_pk_add_f32 v[68:69], v[60:61], v[62:63] op_sel:[0,1] op_sel_hi:[1,0] neg_hi:[0,1]
	v_pk_add_f32 v[60:61], v[60:61], v[62:63] op_sel:[0,1] op_sel_hi:[1,0] neg_lo:[0,1]
	v_pk_add_f32 v[62:63], v[72:73], v[58:59]
	v_pk_add_f32 v[58:59], v[72:73], v[58:59] neg_lo:[0,1] neg_hi:[0,1]
	v_pk_add_f32 v[72:73], v[54:55], v[64:65]
	v_pk_add_f32 v[54:55], v[54:55], v[64:65] neg_lo:[0,1] neg_hi:[0,1]
	v_pk_add_f32 v[64:65], v[62:63], v[72:73]
	v_pk_add_f32 v[62:63], v[62:63], v[72:73] neg_lo:[0,1] neg_hi:[0,1]
	v_pk_add_f32 v[72:73], v[58:59], v[54:55] op_sel:[0,1] op_sel_hi:[1,0] neg_hi:[0,1]
	v_pk_add_f32 v[54:55], v[58:59], v[54:55] op_sel:[0,1] op_sel_hi:[1,0] neg_lo:[0,1]
	v_pk_add_f32 v[58:59], v[52:53], v[50:51]
	v_pk_add_f32 v[50:51], v[52:53], v[50:51] neg_lo:[0,1] neg_hi:[0,1]
	v_pk_add_f32 v[52:53], v[48:49], v[56:57]
	v_pk_add_f32 v[48:49], v[48:49], v[56:57] neg_lo:[0,1] neg_hi:[0,1]
	v_pk_add_f32 v[56:57], v[58:59], v[52:53]
	v_pk_add_f32 v[52:53], v[58:59], v[52:53] neg_lo:[0,1] neg_hi:[0,1]
	v_pk_add_f32 v[58:59], v[50:51], v[48:49] op_sel:[0,1] op_sel_hi:[1,0] neg_hi:[0,1]
	v_pk_add_f32 v[48:49], v[50:51], v[48:49] op_sel:[0,1] op_sel_hi:[1,0] neg_lo:[0,1]
	v_pk_add_f32 v[50:51], v[40:41], v[44:45]
	v_pk_add_f32 v[40:41], v[40:41], v[44:45] neg_lo:[0,1] neg_hi:[0,1]
	v_pk_add_f32 v[44:45], v[42:43], v[46:47]
	v_pk_add_f32 v[42:43], v[42:43], v[46:47] neg_lo:[0,1] neg_hi:[0,1]
	v_pk_add_f32 v[46:47], v[50:51], v[44:45]
	v_pk_add_f32 v[44:45], v[50:51], v[44:45] neg_lo:[0,1] neg_hi:[0,1]
	v_pk_add_f32 v[50:51], v[40:41], v[42:43] op_sel:[0,1] op_sel_hi:[1,0] neg_hi:[0,1]
	v_pk_add_f32 v[40:41], v[40:41], v[42:43] op_sel:[0,1] op_sel_hi:[1,0] neg_lo:[0,1]
	v_mov_b32_e32 v42, v30
	v_mov_b32_e32 v43, v32
	s_nop 0
	v_pk_mul_f32 v[74:75], v[64:65], v[42:43] op_sel:[0,0] op_sel_hi:[0,1]
	v_pk_fma_f32 v[64:65], v[64:65], v[42:43], v[74:75] op_sel:[1,1,0] op_sel_hi:[1,0,1] neg_lo:[0,1,0]
	ds_write2_b64 v39, v[70:71], v[64:65] offset1:17
	v_pk_mul_f32 v[64:65], v[42:43], v[42:43] op_sel:[0,0] op_sel_hi:[0,1]
	v_pk_fma_f32 v[64:65], v[42:43], v[42:43], v[64:65] op_sel:[1,1,0] op_sel_hi:[1,0,1] neg_lo:[0,1,0]
	v_pk_mul_f32 v[70:71], v[56:57], v[64:65] op_sel:[0,0] op_sel_hi:[0,1]
	v_pk_fma_f32 v[56:57], v[56:57], v[64:65], v[70:71] op_sel:[1,1,0] op_sel_hi:[1,0,1] neg_lo:[0,1,0]
	v_pk_mul_f32 v[70:71], v[64:65], v[42:43] op_sel:[0,0] op_sel_hi:[0,1]
	v_pk_fma_f32 v[64:65], v[64:65], v[42:43], v[70:71] op_sel:[1,1,0] op_sel_hi:[1,0,1] neg_lo:[0,1,0]
	v_pk_mul_f32 v[70:71], v[46:47], v[64:65] op_sel:[0,0] op_sel_hi:[0,1]
	v_pk_fma_f32 v[46:47], v[46:47], v[64:65], v[70:71] op_sel:[1,1,0] op_sel_hi:[1,0,1] neg_lo:[0,1,0]
	ds_write2_b64 v39, v[56:57], v[46:47] offset0:34 offset1:51
	v_pk_mul_f32 v[46:47], v[64:65], v[42:43] op_sel:[0,0] op_sel_hi:[0,1]
	v_pk_fma_f32 v[46:47], v[64:65], v[42:43], v[46:47] op_sel:[1,1,0] op_sel_hi:[1,0,1] neg_lo:[0,1,0]
	v_pk_mul_f32 v[56:57], v[68:69], v[46:47] op_sel:[0,0] op_sel_hi:[0,1]
	v_pk_mul_f32 v[64:65], v[46:47], v[42:43] op_sel:[0,0] op_sel_hi:[0,1]
	v_pk_fma_f32 v[56:57], v[68:69], v[46:47], v[56:57] op_sel:[1,1,0] op_sel_hi:[1,0,1] neg_lo:[0,1,0]
	v_pk_fma_f32 v[46:47], v[46:47], v[42:43], v[64:65] op_sel:[1,1,0] op_sel_hi:[1,0,1] neg_lo:[0,1,0]
	v_pk_mul_f32 v[64:65], v[72:73], v[46:47] op_sel:[0,0] op_sel_hi:[0,1]
	v_pk_fma_f32 v[64:65], v[72:73], v[46:47], v[64:65] op_sel:[1,1,0] op_sel_hi:[1,0,1] neg_lo:[0,1,0]
	ds_write2_b64 v39, v[56:57], v[64:65] offset0:68 offset1:85
	v_pk_mul_f32 v[56:57], v[46:47], v[42:43] op_sel:[0,0] op_sel_hi:[0,1]
	v_pk_fma_f32 v[46:47], v[46:47], v[42:43], v[56:57] op_sel:[1,1,0] op_sel_hi:[1,0,1] neg_lo:[0,1,0]
	v_pk_mul_f32 v[56:57], v[58:59], v[46:47] op_sel:[0,0] op_sel_hi:[0,1]
	v_pk_fma_f32 v[56:57], v[58:59], v[46:47], v[56:57] op_sel:[1,1,0] op_sel_hi:[1,0,1] neg_lo:[0,1,0]
	v_pk_mul_f32 v[58:59], v[46:47], v[42:43] op_sel:[0,0] op_sel_hi:[0,1]
	v_pk_fma_f32 v[46:47], v[46:47], v[42:43], v[58:59] op_sel:[1,1,0] op_sel_hi:[1,0,1] neg_lo:[0,1,0]
	v_pk_mul_f32 v[58:59], v[50:51], v[46:47] op_sel:[0,0] op_sel_hi:[0,1]
	v_pk_fma_f32 v[50:51], v[50:51], v[46:47], v[58:59] op_sel:[1,1,0] op_sel_hi:[1,0,1] neg_lo:[0,1,0]
	ds_write2_b64 v39, v[56:57], v[50:51] offset0:102 offset1:119
	v_pk_mul_f32 v[50:51], v[46:47], v[42:43] op_sel:[0,0] op_sel_hi:[0,1]
	v_pk_fma_f32 v[46:47], v[46:47], v[42:43], v[50:51] op_sel:[1,1,0] op_sel_hi:[1,0,1] neg_lo:[0,1,0]
	v_pk_mul_f32 v[50:51], v[66:67], v[46:47] op_sel:[0,0] op_sel_hi:[0,1]
	v_pk_mul_f32 v[56:57], v[46:47], v[42:43] op_sel:[0,0] op_sel_hi:[0,1]
	v_pk_fma_f32 v[50:51], v[66:67], v[46:47], v[50:51] op_sel:[1,1,0] op_sel_hi:[1,0,1] neg_lo:[0,1,0]
	v_pk_fma_f32 v[46:47], v[46:47], v[42:43], v[56:57] op_sel:[1,1,0] op_sel_hi:[1,0,1] neg_lo:[0,1,0]
	v_pk_mul_f32 v[56:57], v[62:63], v[46:47] op_sel:[0,0] op_sel_hi:[0,1]
	v_pk_fma_f32 v[56:57], v[62:63], v[46:47], v[56:57] op_sel:[1,1,0] op_sel_hi:[1,0,1] neg_lo:[0,1,0]
	ds_write2_b64 v39, v[50:51], v[56:57] offset0:136 offset1:153
	v_pk_mul_f32 v[50:51], v[46:47], v[42:43] op_sel:[0,0] op_sel_hi:[0,1]
	v_pk_fma_f32 v[46:47], v[46:47], v[42:43], v[50:51] op_sel:[1,1,0] op_sel_hi:[1,0,1] neg_lo:[0,1,0]
	v_pk_mul_f32 v[50:51], v[52:53], v[46:47] op_sel:[0,0] op_sel_hi:[0,1]
	v_pk_fma_f32 v[50:51], v[52:53], v[46:47], v[50:51] op_sel:[1,1,0] op_sel_hi:[1,0,1] neg_lo:[0,1,0]
	v_pk_mul_f32 v[52:53], v[46:47], v[42:43] op_sel:[0,0] op_sel_hi:[0,1]
	v_pk_fma_f32 v[46:47], v[46:47], v[42:43], v[52:53] op_sel:[1,1,0] op_sel_hi:[1,0,1] neg_lo:[0,1,0]
	v_pk_mul_f32 v[52:53], v[44:45], v[46:47] op_sel:[0,0] op_sel_hi:[0,1]
	v_pk_fma_f32 v[44:45], v[44:45], v[46:47], v[52:53] op_sel:[1,1,0] op_sel_hi:[1,0,1] neg_lo:[0,1,0]
	ds_write2_b64 v39, v[50:51], v[44:45] offset0:170 offset1:187
	v_pk_mul_f32 v[44:45], v[46:47], v[42:43] op_sel:[0,0] op_sel_hi:[0,1]
	v_pk_fma_f32 v[44:45], v[46:47], v[42:43], v[44:45] op_sel:[1,1,0] op_sel_hi:[1,0,1] neg_lo:[0,1,0]
	v_pk_mul_f32 v[46:47], v[60:61], v[44:45] op_sel:[0,0] op_sel_hi:[0,1]
	v_pk_mul_f32 v[50:51], v[44:45], v[42:43] op_sel:[0,0] op_sel_hi:[0,1]
	v_pk_fma_f32 v[46:47], v[60:61], v[44:45], v[46:47] op_sel:[1,1,0] op_sel_hi:[1,0,1] neg_lo:[0,1,0]
	v_pk_fma_f32 v[44:45], v[44:45], v[42:43], v[50:51] op_sel:[1,1,0] op_sel_hi:[1,0,1] neg_lo:[0,1,0]
	v_pk_mul_f32 v[50:51], v[54:55], v[44:45] op_sel:[0,0] op_sel_hi:[0,1]
	v_pk_fma_f32 v[50:51], v[54:55], v[44:45], v[50:51] op_sel:[1,1,0] op_sel_hi:[1,0,1] neg_lo:[0,1,0]
	ds_write2_b64 v39, v[46:47], v[50:51] offset0:204 offset1:221
	v_pk_mul_f32 v[46:47], v[44:45], v[42:43] op_sel:[0,0] op_sel_hi:[0,1]
	v_pk_fma_f32 v[44:45], v[44:45], v[42:43], v[46:47] op_sel:[1,1,0] op_sel_hi:[1,0,1] neg_lo:[0,1,0]
	v_pk_mul_f32 v[46:47], v[48:49], v[44:45] op_sel:[0,0] op_sel_hi:[0,1]
	v_pk_fma_f32 v[46:47], v[48:49], v[44:45], v[46:47] op_sel:[1,1,0] op_sel_hi:[1,0,1] neg_lo:[0,1,0]
	v_pk_mul_f32 v[48:49], v[44:45], v[42:43] op_sel:[0,0] op_sel_hi:[0,1]
	v_pk_fma_f32 v[42:43], v[44:45], v[42:43], v[48:49] op_sel:[1,1,0] op_sel_hi:[1,0,1] neg_lo:[0,1,0]
	v_pk_mul_f32 v[44:45], v[40:41], v[42:43] op_sel:[0,0] op_sel_hi:[0,1]
	v_pk_fma_f32 v[40:41], v[40:41], v[42:43], v[44:45] op_sel:[1,1,0] op_sel_hi:[1,0,1] neg_lo:[0,1,0]
	ds_write2_b64 v39, v[46:47], v[40:41] offset0:238 offset1:255
	v_mad_u32_u24 v39, v34, s55, v35
	s_waitcnt lgkmcnt(0)
	s_barrier
	ds_read2_b64 v[40:43], v39 offset1:1
	ds_read2_b64 v[44:47], v39 offset0:2 offset1:3
	ds_read2_b64 v[48:51], v39 offset0:8 offset1:9
	ds_read2_b64 v[52:55], v39 offset0:4 offset1:5
	ds_read2_b64 v[56:59], v39 offset0:6 offset1:7
	ds_read2_b64 v[60:63], v39 offset0:12 offset1:13
	ds_read2_b64 v[64:67], v39 offset0:10 offset1:11
	ds_read2_b64 v[68:71], v39 offset0:14 offset1:15
	s_waitcnt lgkmcnt(5)
	v_pk_add_f32 v[72:73], v[40:41], v[48:49]
	v_pk_add_f32 v[40:41], v[40:41], v[48:49] neg_lo:[0,1] neg_hi:[0,1]
	s_waitcnt lgkmcnt(2)
	v_pk_add_f32 v[48:49], v[52:53], v[60:61]
	v_pk_add_f32 v[52:53], v[52:53], v[60:61] neg_lo:[0,1] neg_hi:[0,1]
	v_pk_add_f32 v[60:61], v[72:73], v[48:49]
	v_pk_add_f32 v[48:49], v[72:73], v[48:49] neg_lo:[0,1] neg_hi:[0,1]
	v_pk_add_f32 v[72:73], v[40:41], v[52:53] op_sel:[0,1] op_sel_hi:[1,0] neg_hi:[0,1]
	v_pk_add_f32 v[40:41], v[40:41], v[52:53] op_sel:[0,1] op_sel_hi:[1,0] neg_lo:[0,1]
	v_pk_add_f32 v[52:53], v[42:43], v[50:51]
	v_pk_add_f32 v[42:43], v[42:43], v[50:51] neg_lo:[0,1] neg_hi:[0,1]
	v_pk_add_f32 v[50:51], v[54:55], v[62:63]
	v_pk_add_f32 v[54:55], v[54:55], v[62:63] neg_lo:[0,1] neg_hi:[0,1]
	v_pk_add_f32 v[62:63], v[52:53], v[50:51]
	v_pk_add_f32 v[50:51], v[52:53], v[50:51] neg_lo:[0,1] neg_hi:[0,1]
	v_pk_add_f32 v[52:53], v[42:43], v[54:55] op_sel:[0,1] op_sel_hi:[1,0] neg_hi:[0,1]
	v_pk_add_f32 v[42:43], v[42:43], v[54:55] op_sel:[0,1] op_sel_hi:[1,0] neg_lo:[0,1]
	s_waitcnt lgkmcnt(1)
	v_pk_add_f32 v[54:55], v[44:45], v[64:65]
	v_pk_add_f32 v[44:45], v[44:45], v[64:65] neg_lo:[0,1] neg_hi:[0,1]
	s_waitcnt lgkmcnt(0)
	v_pk_add_f32 v[64:65], v[56:57], v[68:69]
	v_pk_add_f32 v[56:57], v[56:57], v[68:69] neg_lo:[0,1] neg_hi:[0,1]
	v_pk_add_f32 v[68:69], v[54:55], v[64:65]
	v_pk_add_f32 v[54:55], v[54:55], v[64:65] neg_lo:[0,1] neg_hi:[0,1]
	v_pk_add_f32 v[64:65], v[44:45], v[56:57] op_sel:[0,1] op_sel_hi:[1,0] neg_hi:[0,1]
	v_pk_add_f32 v[44:45], v[44:45], v[56:57] op_sel:[0,1] op_sel_hi:[1,0] neg_lo:[0,1]
	v_pk_add_f32 v[56:57], v[46:47], v[66:67]
	v_pk_add_f32 v[46:47], v[46:47], v[66:67] neg_lo:[0,1] neg_hi:[0,1]
	v_pk_add_f32 v[66:67], v[58:59], v[70:71]
	v_pk_add_f32 v[58:59], v[58:59], v[70:71] neg_lo:[0,1] neg_hi:[0,1]
	v_pk_add_f32 v[70:71], v[56:57], v[66:67]
	v_pk_add_f32 v[56:57], v[56:57], v[66:67] neg_lo:[0,1] neg_hi:[0,1]
	v_pk_add_f32 v[66:67], v[46:47], v[58:59] op_sel:[0,1] op_sel_hi:[1,0] neg_hi:[0,1]
	v_pk_add_f32 v[46:47], v[46:47], v[58:59] op_sel:[0,1] op_sel_hi:[1,0] neg_lo:[0,1]
	v_pk_mul_f32 v[58:59], v[52:53], v[24:25] op_sel:[0,0] op_sel_hi:[0,1]
	v_pk_fma_f32 v[24:25], v[52:53], v[24:25], v[58:59] op_sel:[1,1,0] op_sel_hi:[1,0,1] neg_lo:[0,1,0]
	v_pk_mul_f32 v[52:53], v[64:65], v[20:21] op_sel:[0,0] op_sel_hi:[0,1]
	v_pk_mul_f32 v[58:59], v[66:67], v[18:19] op_sel:[0,0] op_sel_hi:[0,1]
	s_barrier
	v_pk_fma_f32 v[52:53], v[64:65], v[20:21], v[52:53] op_sel:[1,1,0] op_sel_hi:[1,0,1] neg_lo:[0,1,0]
	v_pk_mul_f32 v[64:65], v[50:51], v[20:21] op_sel:[0,0] op_sel_hi:[0,1]
	v_pk_fma_f32 v[58:59], v[66:67], v[18:19], v[58:59] op_sel:[1,1,0] op_sel_hi:[1,0,1] neg_lo:[0,1,0]
	v_pk_fma_f32 v[20:21], v[50:51], v[20:21], v[64:65] op_sel:[1,1,0] op_sel_hi:[1,0,1] neg_lo:[0,1,0]
	v_pk_mul_f32 v[50:51], v[54:55], v[26:27] op_sel:[0,0] op_sel_hi:[0,1]
	v_pk_fma_f32 v[26:27], v[54:55], v[26:27], v[50:51] op_sel:[1,1,0] op_sel_hi:[1,0,1] neg_lo:[0,1,0]
	v_pk_mul_f32 v[50:51], v[56:57], v[22:23] op_sel:[0,0] op_sel_hi:[0,1]
	v_pk_mul_f32 v[54:55], v[42:43], v[18:19] op_sel:[0,0] op_sel_hi:[0,1]
	v_pk_fma_f32 v[18:19], v[42:43], v[18:19], v[54:55] op_sel:[1,1,0] op_sel_hi:[1,0,1] neg_lo:[0,1,0]
	v_pk_mul_f32 v[42:43], v[44:45], v[22:23] op_sel:[0,0] op_sel_hi:[0,1]
	v_pk_fma_f32 v[50:51], v[56:57], v[22:23], v[50:51] op_sel:[1,1,0] op_sel_hi:[1,0,1] neg_lo:[0,1,0]
	v_pk_add_f32 v[54:55], v[24:25], v[58:59] neg_lo:[0,1] neg_hi:[0,1]
	v_pk_fma_f32 v[22:23], v[44:45], v[22:23], v[42:43] op_sel:[1,1,0] op_sel_hi:[1,0,1] neg_lo:[0,1,0]
	v_pk_mul_f32 v[42:43], v[46:47], v[28:29] op_sel:[0,0] op_sel_hi:[0,1]
	v_pk_add_f32 v[44:45], v[62:63], v[70:71] neg_lo:[0,1] neg_hi:[0,1]
	v_pk_fma_f32 v[28:29], v[46:47], v[28:29], v[42:43] op_sel:[1,1,0] op_sel_hi:[1,0,1] neg_lo:[0,1,0]
	v_pk_add_f32 v[42:43], v[60:61], v[68:69] neg_lo:[0,1] neg_hi:[0,1]
	v_pk_add_f32 v[74:75], v[18:19], v[28:29] neg_lo:[0,1] neg_hi:[0,1]
	v_pk_add_f32 v[46:47], v[42:43], v[44:45] op_sel:[0,1] op_sel_hi:[1,0] neg_hi:[0,1]
	v_pk_add_f32 v[42:43], v[42:43], v[44:45] op_sel:[0,1] op_sel_hi:[1,0] neg_lo:[0,1]
	v_pk_add_f32 v[44:45], v[72:73], v[52:53] neg_lo:[0,1] neg_hi:[0,1]
	v_and_b32_e32 v19, 0xf0, v36
	v_pk_add_f32 v[56:57], v[44:45], v[54:55] op_sel:[0,1] op_sel_hi:[1,0] neg_hi:[0,1]
	v_pk_add_f32 v[44:45], v[44:45], v[54:55] op_sel:[0,1] op_sel_hi:[1,0] neg_lo:[0,1]
	v_pk_add_f32 v[54:55], v[48:49], v[26:27] neg_lo:[0,1] neg_hi:[0,1]
	v_pk_add_f32 v[64:65], v[20:21], v[50:51] neg_lo:[0,1] neg_hi:[0,1]
	v_mul_i32_i24_e32 v21, 0xfffff804, v38
	v_lshlrev_b32_e32 v19, 2, v19
	v_pk_add_f32 v[66:67], v[54:55], v[64:65] op_sel:[0,1] op_sel_hi:[1,0] neg_hi:[0,1]
	v_pk_add_f32 v[54:55], v[54:55], v[64:65] op_sel:[0,1] op_sel_hi:[1,0] neg_lo:[0,1]
	v_pk_add_f32 v[64:65], v[40:41], v[22:23] neg_lo:[0,1] neg_hi:[0,1]
	v_add3_u32 v19, v78, v21, v19
	v_add_f32_e32 v21, v62, v70
	v_add_f32_e32 v23, v60, v68
	v_add_f32_e32 v24, v24, v58
	v_add_f32_e32 v27, v72, v52
	v_add_f32_e32 v25, v23, v21
	v_add_f32_e32 v29, v27, v24
	v_mul_f32_e32 v25, 0x3a800000, v25
	v_mul_f32_e32 v29, 0x3a800000, v29
	ds_write2st64_b32 v19, v25, v29 offset1:4
	v_add_f32_e32 v20, v20, v50
	v_add_f32_e32 v25, v48, v26
	v_add_f32_e32 v18, v18, v28
	v_add_f32_e32 v22, v40, v22
	v_add_f32_e32 v26, v25, v20
	v_add_f32_e32 v28, v22, v18
	v_sub_f32_e32 v20, v25, v20
	v_sub_f32_e32 v18, v22, v18
	v_mul_f32_e32 v26, 0x3a800000, v26
	v_mul_f32_e32 v28, 0x3a800000, v28
	v_mul_f32_e32 v20, 0x3a800000, v20
	v_mul_f32_e32 v18, 0x3a800000, v18
	ds_write2st64_b32 v19, v26, v28 offset0:8 offset1:12
	v_mul_f32_e32 v26, 0x3a800000, v46
	v_mul_f32_e32 v28, 0x3a800000, v56
	v_sub_f32_e32 v21, v23, v21
	v_sub_f32_e32 v23, v27, v24
	ds_write2st64_b32 v19, v20, v18 offset0:40 offset1:44
	v_mul_f32_e32 v18, 0x3a800000, v42
	v_mul_f32_e32 v20, 0x3a800000, v44
	v_pk_add_f32 v[76:77], v[64:65], v[74:75] op_sel:[0,1] op_sel_hi:[1,0] neg_hi:[0,1]
	v_pk_add_f32 v[64:65], v[64:65], v[74:75] op_sel:[0,1] op_sel_hi:[1,0] neg_lo:[0,1]
	ds_write2st64_b32 v19, v26, v28 offset0:16 offset1:20
	v_mul_f32_e32 v26, 0x3a800000, v66
	v_mul_f32_e32 v28, 0x3a800000, v76
	v_mul_f32_e32 v21, 0x3a800000, v21
	v_mul_f32_e32 v23, 0x3a800000, v23
	ds_write2st64_b32 v19, v18, v20 offset0:48 offset1:52
	v_mul_f32_e32 v18, 0x3a800000, v54
	v_mul_f32_e32 v20, 0x3a800000, v64
	v_mov_b32_e32 v22, v34
	ds_write2st64_b32 v19, v26, v28 offset0:24 offset1:28
	ds_write2st64_b32 v19, v21, v23 offset0:32 offset1:36
	ds_write2st64_b32 v19, v18, v20 offset0:56 offset1:60
	s_waitcnt lgkmcnt(0)
	s_barrier
	v_lshlrev_b32_e32 v26, 12, v37
	v_lshl_add_u32 v23, v22, 5, v35
	ds_read_b128 v[18:21], v23
	v_lshlrev_b32_e32 v28, 3, v22
	ds_read_b128 v[22:25], v23 offset:16
	v_ashrrev_i32_e32 v27, 31, v26
	v_lshlrev_b64 v[26:27], 1, v[26:27]
	s_waitcnt lgkmcnt(1)
	v_bfe_u32 v29, v18, 16, 1
	v_add3_u32 v18, v18, v29, s56
	v_bfe_u32 v29, v19, 16, 1
	v_lshrrev_b32_e32 v18, 16, v18
	v_add3_u32 v19, v19, v29, s56
	v_and_or_b32 v18, v19, s57, v18
	v_cvt_pk_bf16_f32 v19, v20, v21
	s_waitcnt lgkmcnt(0)
	v_cvt_pk_bf16_f32 v20, v22, v23
	v_cvt_pk_bf16_f32 v21, v24, v25
	v_ashrrev_i32_e32 v29, 31, v28
	v_lshl_add_u64 v[22:23], v[28:29], 1, v[26:27]
	v_lshl_add_u64 v[22:23], s[26:27], 0, v[22:23]
	global_store_dwordx4 v[22:23], v[18:21], off
	s_nop 0
	v_lshl_add_u32 v22, v34, 5, v35
	ds_read_b128 v[18:21], v22 offset:8192
	ds_read_b128 v[22:25], v22 offset:8208
	v_lshl_add_u32 v28, v34, 3, v33
	s_waitcnt lgkmcnt(1)
	v_bfe_u32 v29, v18, 16, 1
	v_add3_u32 v18, v18, v29, s56
	v_bfe_u32 v29, v19, 16, 1
	v_lshrrev_b32_e32 v18, 16, v18
	v_add3_u32 v19, v19, v29, s56
	v_and_or_b32 v18, v19, s57, v18
	v_cvt_pk_bf16_f32 v19, v20, v21
	s_waitcnt lgkmcnt(0)
	v_cvt_pk_bf16_f32 v20, v22, v23
	v_cvt_pk_bf16_f32 v21, v24, v25
	v_ashrrev_i32_e32 v29, 31, v28
	v_lshl_add_u64 v[22:23], v[28:29], 1, v[26:27]
	v_lshl_add_u64 v[22:23], s[26:27], 0, v[22:23]
	s_add_u32 s26, s26, s34
	s_addc_u32 s27, s27, s35
	s_andn2_b64 vcc, exec, s[50:51]
	global_store_dwordx4 v[22:23], v[18:21], off
	s_barrier
	s_cbranch_vccz .LBB0_1712

.LBB0_1768:
	s_or_b64 exec, exec, s[52:53]
	s_lshl_b64 s[52:53], s[50:51], 15
	v_ashrrev_i32_e32 v91, 6, v38
	s_add_u32 s28, s65, s52
	v_lshlrev_b32_e32 v50, 3, v91
	v_lshlrev_b32_e32 v34, 1, v34
	s_addc_u32 s29, s64, s53
	v_add_u32_e32 v90, 0, v34
	v_lshl_add_u64 v[54:55], s[28:29], 0, v[34:35]
	v_add_u32_e32 v34, s91, v50
	v_and_b32_e32 v34, 0xfffffef8, v34
	v_cmp_eq_u32_e32 vcc, 0, v34
	s_waitcnt vmcnt(25)
	v_lshlrev_b32_e32 v96, 16, v66
	v_and_b32_e32 v94, 0xffff0000, v66
	v_lshlrev_b32_e32 v97, 16, v67
	v_and_b32_e32 v95, 0xffff0000, v67
	v_lshlrev_b32_e32 v67, 16, v59
	v_lshlrev_b32_e32 v66, 16, v58
	v_and_b32_e32 v101, 0xffff0000, v59
	v_and_b32_e32 v100, 0xffff0000, v58
	s_waitcnt vmcnt(3)
	v_mov_b32_e32 v58, v2
	v_mov_b32_e32 v59, v4
	v_mov_b32_e32 v4, v3
	v_mov_b32_e32 v2, v30
	v_mov_b32_e32 v3, v32
	v_cndmask_b32_e64 v34, 1.0, 0, vcc
	v_lshlrev_b32_e32 v87, 16, v65
	v_lshlrev_b32_e32 v86, 16, v64
	v_and_b32_e32 v105, 0xffff0000, v65
	v_and_b32_e32 v104, 0xffff0000, v64
	v_pk_mul_f32 v[64:65], v[2:3], v[66:67]
	v_pk_mul_f32 v[102:103], v[58:59], v[86:87]
	v_pk_mul_f32 v[66:67], v[64:65], v[34:35] op_sel_hi:[1,0]
	v_mov_b32_e32 v64, v26
	v_mov_b32_e32 v65, v28
	v_lshlrev_b32_e32 v89, 16, v69
	v_lshlrev_b32_e32 v88, 16, v68
	v_and_b32_e32 v87, 0xffff0000, v69
	v_and_b32_e32 v86, 0xffff0000, v68
	v_pk_fma_f32 v[68:69], v[64:65], v[96:97], v[66:67]
	v_mov_b32_e32 v66, v18
	v_mov_b32_e32 v67, v20
	v_mov_b32_e32 v32, v31
	v_pk_fma_f32 v[106:107], v[66:67], v[88:89], v[68:69]
	v_mov_b32_e32 v68, v22
	v_mov_b32_e32 v69, v24
	v_pk_mul_f32 v[30:31], v[32:33], v[100:101]
	v_pk_add_f32 v[106:107], v[68:69], v[106:107]
	v_pk_mul_f32 v[30:31], v[30:31], v[34:35] op_sel_hi:[1,0]
	v_mov_b32_e32 v28, v27
	v_mul_f32_e32 v18, 0xbfb8aa3b, v106
	v_pk_fma_f32 v[26:27], v[28:29], v[94:95], v[30:31]
	v_mov_b32_e32 v20, v19
	v_exp_f32_e32 v22, v18
	v_pk_fma_f32 v[18:19], v[20:21], v[86:87], v[26:27]
	v_mov_b32_e32 v24, v23
	v_pk_add_f32 v[18:19], v[24:25], v[18:19]
	v_mul_f32_e32 v26, 0xbfb8aa3b, v107
	v_mul_f32_e32 v23, 0xbfb8aa3b, v18
	v_exp_f32_e32 v23, v23
	v_exp_f32_e32 v27, v26
	v_mul_f32_e32 v26, 0xbfb8aa3b, v19
	v_exp_f32_e32 v51, v26
	v_add_f32_e32 v23, 1.0, v23
	v_add_f32_e32 v22, 1.0, v22
	v_rcp_f32_e32 v26, v23
	v_add_f32_e32 v23, 1.0, v27
	v_rcp_f32_e32 v22, v22
	v_rcp_f32_e32 v23, v23
	v_add_f32_e32 v27, 1.0, v51
	v_rcp_f32_e32 v27, v27
	v_lshlrev_b32_e32 v93, 16, v81
	v_lshlrev_b32_e32 v92, 16, v80
	v_and_b32_e32 v101, 0xffff0000, v81
	v_and_b32_e32 v100, 0xffff0000, v80
	v_pk_mul_f32 v[80:81], v[106:107], v[22:23]
	v_pk_mul_f32 v[30:31], v[4:5], v[104:105]
	v_pk_mul_f32 v[104:105], v[18:19], v[26:27]
	v_cvt_pk_bf16_f32 v107, v81, v105
	v_cvt_pk_bf16_f32 v106, v80, v104
	v_pk_mul_f32 v[22:23], v[34:35], v[102:103] op_sel_hi:[0,1]
	s_waitcnt vmcnt(2)
	v_mov_b32_e32 v18, v14
	v_mov_b32_e32 v19, v16
	v_lshlrev_b32_e32 v84, 16, v82
	v_lshlrev_b32_e32 v85, 16, v83
	v_pk_fma_f32 v[26:27], v[18:19], v[92:93], v[22:23]
	s_waitcnt vmcnt(1)
	v_mov_b32_e32 v22, v10
	v_mov_b32_e32 v23, v12
	v_pk_fma_f32 v[102:103], v[22:23], v[84:85], v[26:27]
	s_waitcnt vmcnt(0)
	v_mov_b32_e32 v26, v6
	v_mov_b32_e32 v27, v8
	v_pk_mul_f32 v[30:31], v[34:35], v[30:31] op_sel_hi:[0,1]
	v_mov_b32_e32 v16, v15
	v_and_b32_e32 v82, 0xffff0000, v82
	v_and_b32_e32 v83, 0xffff0000, v83
	v_pk_add_f32 v[102:103], v[26:27], v[102:103]
	v_pk_fma_f32 v[14:15], v[16:17], v[100:101], v[30:31]
	v_mov_b32_e32 v12, v11
	v_mul_f32_e32 v6, 0xbfb8aa3b, v102
	v_pk_fma_f32 v[10:11], v[12:13], v[82:83], v[14:15]
	v_mov_b32_e32 v8, v7
	v_exp_f32_e32 v108, v6
	v_pk_add_f32 v[6:7], v[8:9], v[10:11]
	v_mul_f32_e32 v14, 0xbfb8aa3b, v103
	v_mul_f32_e32 v10, 0xbfb8aa3b, v6
	v_exp_f32_e32 v11, v10
	v_exp_f32_e32 v15, v14
	v_mul_f32_e32 v14, 0xbfb8aa3b, v7
	v_exp_f32_e32 v30, v14
	v_add_f32_e32 v11, 1.0, v11
	v_add_f32_e32 v10, 1.0, v108
	v_rcp_f32_e32 v14, v11
	v_add_f32_e32 v11, 1.0, v15
	v_rcp_f32_e32 v10, v10
	v_rcp_f32_e32 v11, v11
	v_add_f32_e32 v15, 1.0, v30
	v_rcp_f32_e32 v15, v15
	s_movk_i32 s28, 0x1080
	v_pk_mul_f32 v[10:11], v[102:103], v[10:11]
	v_mad_u64_u32 v[30:31], s[28:29], v91, s28, v[90:91]
	v_pk_mul_f32 v[10:11], v[10:11], s[48:49] op_sel_hi:[1,0]
	v_pk_mul_f32 v[6:7], v[6:7], v[14:15]
	v_pk_mul_f32 v[6:7], v[6:7], s[48:49] op_sel_hi:[1,0]
	v_cvt_pk_bf16_f32 v15, v11, v7
	v_cvt_pk_bf16_f32 v14, v10, v6
	s_add_i32 s54, 0, 0x1be00
	v_lshlrev_b32_e32 v34, 5, v91
	s_waitcnt lgkmcnt(0)
	s_barrier
	ds_write2st64_b64 v30, v[106:107], v[14:15] offset1:66
	v_add_u32_e32 v14, s54, v34
	ds_read_b32 v14, v14
	s_add_i32 s55, 0, 0x1bf00
	v_add_u32_e32 v15, s55, v34
	ds_read_b32 v102, v15
	v_ashrrev_i32_e32 v51, 31, v50
	s_waitcnt lgkmcnt(1)
	v_pk_mul_f32 v[30:31], v[80:81], v[14:15] op_sel_hi:[1,0]
	v_pk_mul_f32 v[14:15], v[104:105], v[14:15] op_sel_hi:[1,0]
	v_and_b32_sdwa v80, v31, v98 dst_sel:DWORD dst_unused:UNUSED_PAD src0_sel:WORD_1 src1_sel:DWORD
	v_and_b32_sdwa v81, v30, v98 dst_sel:DWORD dst_unused:UNUSED_PAD src0_sel:WORD_1 src1_sel:DWORD
	v_add3_u32 v30, v30, v81, s49
	v_add3_u32 v31, v31, v80, s49
	v_and_b32_sdwa v80, v15, v98 dst_sel:DWORD dst_unused:UNUSED_PAD src0_sel:WORD_1 src1_sel:DWORD
	v_and_b32_sdwa v81, v14, v98 dst_sel:DWORD dst_unused:UNUSED_PAD src0_sel:WORD_1 src1_sel:DWORD
	v_add3_u32 v15, v15, v80, s49
	v_add3_u32 v14, v14, v81, s49
	v_and_b32_e32 v15, 0xffff0000, v15
	v_and_b32_e32 v14, 0xffff0000, v14
	v_or_b32_sdwa v15, v15, v31 dst_sel:DWORD dst_unused:UNUSED_PAD src0_sel:DWORD src1_sel:WORD_1
	v_or_b32_sdwa v14, v14, v30 dst_sel:DWORD dst_unused:UNUSED_PAD src0_sel:DWORD src1_sel:WORD_1
	v_lshlrev_b64 v[30:31], 9, v[50:51]
	v_lshl_add_u64 v[30:31], v[54:55], 0, v[30:31]
	s_waitcnt lgkmcnt(0)
	v_mul_f32_e32 v10, v10, v102
	global_store_dwordx2 v[30:31], v[14:15], off
	v_bfe_u32 v14, v10, 16, 1
	v_add3_u32 v10, v10, v14, s49
	v_mov_b32_e32 v14, s80
	s_movk_i32 s28, 0x240
	v_mad_u32_u24 v51, v99, s28, v14
	v_lshl_add_u32 v14, v91, 4, v51
	v_mul_f32_e32 v6, v6, v102
	ds_write_b16_d16_hi v14, v10
	v_bfe_u32 v10, v6, 16, 1
	v_add3_u32 v6, v6, v10, s49
	ds_write_b16_d16_hi v14, v6 offset:144
	v_mul_f32_e32 v6, v11, v102
	v_bfe_u32 v10, v6, 16, 1
	v_add3_u32 v6, v6, v10, s49
	ds_write_b16_d16_hi v14, v6 offset:288
	v_mul_f32_e32 v6, v7, v102
	v_bfe_u32 v7, v6, 16, 1
	v_add3_u32 v6, v6, v7, s49
	ds_write_b16_d16_hi v14, v6 offset:432
	v_pk_mul_f32 v[6:7], v[64:65], v[88:89]
	v_lshlrev_b32_e32 v81, 16, v79
	v_lshlrev_b32_e32 v80, 16, v78
	v_pk_fma_f32 v[6:7], v[2:3], v[96:97], v[6:7]
	v_pk_mul_f32 v[14:15], v[28:29], v[86:87]
	v_and_b32_e32 v79, 0xffff0000, v79
	v_and_b32_e32 v78, 0xffff0000, v78
	v_pk_fma_f32 v[6:7], v[66:67], v[80:81], v[6:7]
	v_pk_fma_f32 v[14:15], v[32:33], v[94:95], v[14:15]
	v_pk_add_f32 v[6:7], v[68:69], v[6:7]
	v_pk_fma_f32 v[14:15], v[20:21], v[78:79], v[14:15]
	v_mul_f32_e32 v11, 0xbfb8aa3b, v6
	v_pk_add_f32 v[94:95], v[24:25], v[14:15]
	v_exp_f32_e32 v11, v11
	v_mul_f32_e32 v14, 0xbfb8aa3b, v94
	v_exp_f32_e32 v15, v14
	v_mul_f32_e32 v31, 0xbfb8aa3b, v95
	v_add_f32_e32 v11, 1.0, v11
	v_rcp_f32_e32 v96, v11
	v_add_f32_e32 v11, 1.0, v15
	v_mul_f32_e32 v15, 0xbfb8aa3b, v7
	v_exp_f32_e32 v15, v15
	v_exp_f32_e32 v31, v31
	v_rcp_f32_e32 v102, v11
	v_lshlrev_b32_e32 v10, 16, v76
	v_add_f32_e32 v11, 1.0, v15
	v_rcp_f32_e32 v97, v11
	v_add_f32_e32 v11, 1.0, v31
	v_rcp_f32_e32 v103, v11
	v_and_b32_e32 v14, 0xffff0000, v76
	v_lshlrev_b32_e32 v11, 16, v77
	v_and_b32_e32 v15, 0xffff0000, v77
	v_pk_mul_f32 v[94:95], v[94:95], v[102:103]
	v_pk_mul_f32 v[76:77], v[6:7], v[96:97]
	v_cvt_pk_bf16_f32 v97, v77, v95
	v_cvt_pk_bf16_f32 v96, v76, v94
	v_pk_mul_f32 v[6:7], v[18:19], v[84:85]
	v_or_b32_e32 v30, 1, v50
	v_pk_fma_f32 v[6:7], v[58:59], v[92:93], v[6:7]
	v_and_b32_e32 v39, 15, v38
	v_pk_fma_f32 v[6:7], v[22:23], v[10:11], v[6:7]
	s_nop 0
	v_pk_add_f32 v[92:93], v[26:27], v[6:7]
	s_nop 0
	v_mul_f32_e32 v6, 0xbfb8aa3b, v92
	v_exp_f32_e32 v31, v6
	v_pk_mul_f32 v[6:7], v[16:17], v[82:83]
	s_nop 0
	v_pk_fma_f32 v[6:7], v[4:5], v[100:101], v[6:7]
	s_nop 0
	v_pk_fma_f32 v[6:7], v[12:13], v[14:15], v[6:7]
	s_nop 0
	v_pk_add_f32 v[100:101], v[8:9], v[6:7]
	s_nop 0
	v_mul_f32_e32 v6, 0xbfb8aa3b, v100
	v_exp_f32_e32 v91, v6
	s_nop 0
	v_mad_u64_u32 v[6:7], s[28:29], v30, s81, v[90:91]
	v_add_f32_e32 v7, 1.0, v31
	v_mul_f32_e32 v31, 0xbfb8aa3b, v93
	v_rcp_f32_e32 v90, v7
	v_add_f32_e32 v7, 1.0, v91
	v_exp_f32_e32 v31, v31
	v_mul_f32_e32 v91, 0xbfb8aa3b, v101
	v_exp_f32_e32 v103, v91
	v_rcp_f32_e32 v102, v7
	v_add_f32_e32 v7, 1.0, v31
	v_rcp_f32_e32 v91, v7
	v_add_f32_e32 v7, 1.0, v103
	v_rcp_f32_e32 v103, v7
	ds_write_b64 v6, v[96:97]
	v_pk_mul_f32 v[90:91], v[92:93], v[90:91]
	s_mov_b32 s28, 0xffffff0
	v_pk_mul_f32 v[92:93], v[100:101], v[102:103]
	v_pk_mul_f32 v[90:91], v[90:91], s[48:49] op_sel_hi:[1,0]
	v_pk_mul_f32 v[92:93], v[92:93], s[48:49] op_sel_hi:[1,0]
	v_cvt_pk_bf16_f32 v97, v91, v93
	v_cvt_pk_bf16_f32 v96, v90, v92
	ds_write_b64 v6, v[96:97] offset:33792
	v_lshlrev_b32_e32 v97, 2, v30
	v_add_u32_e32 v7, s54, v97
	ds_read_b32 v96, v7
	v_add_u32_e32 v97, s55, v97
	ds_read_b32 v100, v97
	v_ashrrev_i32_e32 v31, 31, v30
	v_mul_u32_u24_e32 v7, 0x240, v99
	s_waitcnt lgkmcnt(1)
	v_pk_mul_f32 v[76:77], v[76:77], v[96:97] op_sel_hi:[1,0]
	v_pk_mul_f32 v[94:95], v[94:95], v[96:97] op_sel_hi:[1,0]
	v_and_b32_sdwa v96, v77, v98 dst_sel:DWORD dst_unused:UNUSED_PAD src0_sel:WORD_1 src1_sel:DWORD
	v_and_b32_sdwa v97, v76, v98 dst_sel:DWORD dst_unused:UNUSED_PAD src0_sel:WORD_1 src1_sel:DWORD
	v_add3_u32 v76, v76, v97, s49
	v_add3_u32 v77, v77, v96, s49
	v_and_b32_sdwa v96, v95, v98 dst_sel:DWORD dst_unused:UNUSED_PAD src0_sel:WORD_1 src1_sel:DWORD
	v_and_b32_sdwa v97, v94, v98 dst_sel:DWORD dst_unused:UNUSED_PAD src0_sel:WORD_1 src1_sel:DWORD
	v_add3_u32 v95, v95, v96, s49
	v_add3_u32 v94, v94, v97, s49
	v_and_b32_e32 v95, 0xffff0000, v95
	v_and_b32_e32 v94, 0xffff0000, v94
	v_or_b32_sdwa v95, v95, v77 dst_sel:DWORD dst_unused:UNUSED_PAD src0_sel:DWORD src1_sel:WORD_1
	v_or_b32_sdwa v94, v94, v76 dst_sel:DWORD dst_unused:UNUSED_PAD src0_sel:DWORD src1_sel:WORD_1
	v_lshlrev_b64 v[76:77], 9, v[30:31]
	s_waitcnt lgkmcnt(0)
	v_mul_f32_e32 v31, v90, v100
	v_lshl_add_u64 v[96:97], v[54:55], 0, v[76:77]
	v_lshlrev_b32_e32 v30, 1, v30
	v_bfe_u32 v76, v31, 16, 1
	v_add3_u32 v31, v31, v76, s49
	v_add_u32_e32 v76, v51, v30
	ds_write_b16_d16_hi v76, v31
	v_mul_f32_e32 v31, v92, v100
	v_bfe_u32 v76, v31, 16, 1
	v_add3_u32 v31, v31, v76, s49
	v_add3_u32 v30, s80, v30, v7
	ds_write_b16_d16_hi v30, v31 offset:144
	v_mul_f32_e32 v31, v91, v100
	v_bfe_u32 v76, v31, 16, 1
	v_add3_u32 v31, v31, v76, s49
	ds_write_b16_d16_hi v30, v31 offset:288
	v_mul_f32_e32 v31, v93, v100
	v_pk_mul_f32 v[92:93], v[64:65], v[80:81]
	v_lshlrev_b32_e32 v91, 16, v75
	v_lshlrev_b32_e32 v90, 16, v74
	v_pk_fma_f32 v[88:89], v[2:3], v[88:89], v[92:93]
	v_pk_mul_f32 v[92:93], v[28:29], v[78:79]
	v_bfe_u32 v76, v31, 16, 1
	v_and_b32_e32 v75, 0xffff0000, v75
	v_and_b32_e32 v74, 0xffff0000, v74
	v_pk_fma_f32 v[88:89], v[66:67], v[90:91], v[88:89]
	v_pk_fma_f32 v[86:87], v[32:33], v[86:87], v[92:93]
	v_add3_u32 v31, v31, v76, s49
	v_pk_add_f32 v[88:89], v[68:69], v[88:89]
	v_pk_fma_f32 v[86:87], v[20:21], v[74:75], v[86:87]
	ds_write_b16_d16_hi v30, v31 offset:432
	v_mul_f32_e32 v31, 0xbfb8aa3b, v88
	v_pk_add_f32 v[86:87], v[24:25], v[86:87]
	v_exp_f32_e32 v31, v31
	v_mul_f32_e32 v77, 0xbfb8aa3b, v86
	v_exp_f32_e32 v77, v77
	v_mul_f32_e32 v93, 0xbfb8aa3b, v87
	v_add_f32_e32 v31, 1.0, v31
	v_rcp_f32_e32 v92, v31
	v_add_f32_e32 v31, 1.0, v77
	v_mul_f32_e32 v77, 0xbfb8aa3b, v89
	v_exp_f32_e32 v77, v77
	v_exp_f32_e32 v101, v93
	v_rcp_f32_e32 v100, v31
	v_lshlrev_b32_e32 v76, 16, v72
	v_add_f32_e32 v31, 1.0, v77
	v_rcp_f32_e32 v93, v31
	v_add_f32_e32 v31, 1.0, v101
	v_rcp_f32_e32 v101, v31
	v_lshlrev_b32_e32 v77, 16, v73
	v_pk_mul_f32 v[88:89], v[88:89], v[92:93]
	v_and_b32_e32 v72, 0xffff0000, v72
	v_pk_mul_f32 v[86:87], v[86:87], v[100:101]
	v_and_b32_e32 v73, 0xffff0000, v73
	v_pk_mul_f32 v[100:101], v[18:19], v[10:11]
	v_pk_fma_f32 v[84:85], v[58:59], v[84:85], v[100:101]
	v_pk_mul_f32 v[100:101], v[16:17], v[14:15]
	v_cvt_pk_bf16_f32 v93, v89, v87
	v_pk_fma_f32 v[84:85], v[22:23], v[76:77], v[84:85]
	v_pk_fma_f32 v[82:83], v[4:5], v[82:83], v[100:101]
	v_pk_add_f32 v[84:85], v[26:27], v[84:85]
	v_pk_fma_f32 v[82:83], v[12:13], v[72:73], v[82:83]
	v_mul_f32_e32 v31, 0xbfb8aa3b, v84
	v_pk_add_f32 v[82:83], v[8:9], v[82:83]
	v_exp_f32_e32 v31, v31
	v_mul_f32_e32 v100, 0xbfb8aa3b, v82
	v_exp_f32_e32 v101, v100
	v_cvt_pk_bf16_f32 v92, v88, v86
	v_add_f32_e32 v31, 1.0, v31
	v_rcp_f32_e32 v100, v31
	v_add_f32_e32 v31, 1.0, v101
	v_mul_f32_e32 v101, 0xbfb8aa3b, v85
	v_exp_f32_e32 v101, v101
	v_mul_f32_e32 v102, 0xbfb8aa3b, v83
	v_exp_f32_e32 v103, v102
	v_rcp_f32_e32 v102, v31
	v_add_f32_e32 v31, 1.0, v101
	v_rcp_f32_e32 v101, v31
	v_add_f32_e32 v31, 1.0, v103
	v_rcp_f32_e32 v103, v31
	ds_write_b64 v6, v[92:93] offset:528
	v_pk_mul_f32 v[84:85], v[84:85], v[100:101]
	v_or_b32_e32 v30, 2, v50
	v_pk_mul_f32 v[82:83], v[82:83], v[102:103]
	v_pk_mul_f32 v[84:85], v[84:85], s[48:49] op_sel_hi:[1,0]
	v_pk_mul_f32 v[82:83], v[82:83], s[48:49] op_sel_hi:[1,0]
	v_cvt_pk_bf16_f32 v93, v85, v83
	v_cvt_pk_bf16_f32 v92, v84, v82
	ds_write_b64 v6, v[92:93] offset:34320
	v_lshlrev_b32_e32 v93, 2, v30
	v_add_u32_e32 v31, s54, v93
	v_add_u32_e32 v93, s55, v93
	ds_read_b32 v92, v31
	ds_read_b32 v93, v93
	global_store_dwordx2 v[96:97], v[94:95], off
	v_ashrrev_i32_e32 v31, 31, v30
	s_waitcnt lgkmcnt(0)
	v_pk_mul_f32 v[88:89], v[88:89], v[92:93] op_sel_hi:[1,0]
	v_pk_mul_f32 v[86:87], v[86:87], v[92:93] op_sel_hi:[1,0]
	v_and_b32_sdwa v92, v89, v98 dst_sel:DWORD dst_unused:UNUSED_PAD src0_sel:WORD_1 src1_sel:DWORD
	v_and_b32_sdwa v94, v88, v98 dst_sel:DWORD dst_unused:UNUSED_PAD src0_sel:WORD_1 src1_sel:DWORD
	v_add3_u32 v88, v88, v94, s49
	v_add3_u32 v89, v89, v92, s49
	v_and_b32_sdwa v92, v87, v98 dst_sel:DWORD dst_unused:UNUSED_PAD src0_sel:WORD_1 src1_sel:DWORD
	v_and_b32_sdwa v94, v86, v98 dst_sel:DWORD dst_unused:UNUSED_PAD src0_sel:WORD_1 src1_sel:DWORD
	v_add3_u32 v87, v87, v92, s49
	v_add3_u32 v86, v86, v94, s49
	v_and_b32_e32 v87, 0xffff0000, v87
	v_and_b32_e32 v86, 0xffff0000, v86
	v_or_b32_sdwa v87, v87, v89 dst_sel:DWORD dst_unused:UNUSED_PAD src0_sel:DWORD src1_sel:WORD_1
	v_or_b32_sdwa v86, v86, v88 dst_sel:DWORD dst_unused:UNUSED_PAD src0_sel:DWORD src1_sel:WORD_1
	v_lshlrev_b64 v[88:89], 9, v[30:31]
	v_mul_f32_e32 v31, v84, v93
	v_lshlrev_b32_e32 v30, 1, v30
	v_bfe_u32 v84, v31, 16, 1
	v_add3_u32 v31, v31, v84, s49
	v_add_u32_e32 v84, v51, v30
	ds_write_b16_d16_hi v84, v31
	v_mul_f32_e32 v31, v82, v93
	v_bfe_u32 v82, v31, 16, 1
	v_add3_u32 v31, v31, v82, s49
	v_add3_u32 v30, s80, v30, v7
	ds_write_b16_d16_hi v30, v31 offset:144
	v_mul_f32_e32 v31, v85, v93
	v_bfe_u32 v82, v31, 16, 1
	v_add3_u32 v31, v31, v82, s49
	ds_write_b16_d16_hi v30, v31 offset:288
	v_mul_f32_e32 v31, v83, v93
	v_bfe_u32 v82, v31, 16, 1
	v_pk_mul_f32 v[92:93], v[64:65], v[90:91]
	v_add3_u32 v31, v31, v82, s49
	v_lshlrev_b32_e32 v83, 16, v71
	v_lshlrev_b32_e32 v82, 16, v70
	v_pk_fma_f32 v[80:81], v[2:3], v[80:81], v[92:93]
	v_pk_mul_f32 v[92:93], v[28:29], v[74:75]
	v_and_b32_e32 v71, 0xffff0000, v71
	v_and_b32_e32 v70, 0xffff0000, v70
	v_pk_fma_f32 v[80:81], v[66:67], v[82:83], v[80:81]
	v_pk_fma_f32 v[78:79], v[32:33], v[78:79], v[92:93]
	v_pk_add_f32 v[80:81], v[68:69], v[80:81]
	v_pk_fma_f32 v[78:79], v[20:21], v[70:71], v[78:79]
	ds_write_b16_d16_hi v30, v31 offset:432
	v_mul_f32_e32 v31, 0xbfb8aa3b, v80
	v_pk_add_f32 v[78:79], v[24:25], v[78:79]
	v_exp_f32_e32 v31, v31
	v_mul_f32_e32 v85, 0xbfb8aa3b, v78
	v_exp_f32_e32 v85, v85
	v_mul_f32_e32 v93, 0xbfb8aa3b, v79
	v_add_f32_e32 v31, 1.0, v31
	v_rcp_f32_e32 v92, v31
	v_add_f32_e32 v31, 1.0, v85
	v_mul_f32_e32 v85, 0xbfb8aa3b, v81
	v_exp_f32_e32 v85, v85
	v_exp_f32_e32 v95, v93
	v_rcp_f32_e32 v94, v31
	v_lshlrev_b32_e32 v30, 16, v62
	v_add_f32_e32 v31, 1.0, v85
	v_rcp_f32_e32 v93, v31
	v_add_f32_e32 v31, 1.0, v95
	v_rcp_f32_e32 v95, v31
	v_lshlrev_b32_e32 v31, 16, v63
	v_pk_mul_f32 v[80:81], v[80:81], v[92:93]
	v_and_b32_e32 v62, 0xffff0000, v62
	v_pk_mul_f32 v[78:79], v[78:79], v[94:95]
	v_and_b32_e32 v63, 0xffff0000, v63
	v_pk_mul_f32 v[94:95], v[18:19], v[76:77]
	v_pk_fma_f32 v[10:11], v[58:59], v[10:11], v[94:95]
	v_pk_mul_f32 v[94:95], v[16:17], v[72:73]
	v_cvt_pk_bf16_f32 v93, v81, v79
	v_pk_fma_f32 v[10:11], v[22:23], v[30:31], v[10:11]
	v_pk_fma_f32 v[14:15], v[4:5], v[14:15], v[94:95]
	v_pk_add_f32 v[10:11], v[26:27], v[10:11]
	v_pk_fma_f32 v[14:15], v[12:13], v[62:63], v[14:15]
	v_mul_f32_e32 v85, 0xbfb8aa3b, v10
	v_pk_add_f32 v[14:15], v[8:9], v[14:15]
	v_exp_f32_e32 v85, v85
	v_mul_f32_e32 v94, 0xbfb8aa3b, v14
	v_exp_f32_e32 v95, v94
	v_cvt_pk_bf16_f32 v92, v80, v78
	v_add_f32_e32 v85, 1.0, v85
	v_rcp_f32_e32 v94, v85
	v_add_f32_e32 v85, 1.0, v95
	v_mul_f32_e32 v95, 0xbfb8aa3b, v11
	v_exp_f32_e32 v95, v95
	v_mul_f32_e32 v96, 0xbfb8aa3b, v15
	v_exp_f32_e32 v97, v96
	v_rcp_f32_e32 v96, v85
	v_add_f32_e32 v85, 1.0, v95
	v_rcp_f32_e32 v95, v85
	v_add_f32_e32 v85, 1.0, v97
	v_rcp_f32_e32 v97, v85
	ds_write_b64 v6, v[92:93] offset:1056
	v_pk_mul_f32 v[10:11], v[10:11], v[94:95]
	v_or_b32_e32 v84, 3, v50
	v_pk_mul_f32 v[14:15], v[14:15], v[96:97]
	v_pk_mul_f32 v[10:11], v[10:11], s[48:49] op_sel_hi:[1,0]
	v_pk_mul_f32 v[14:15], v[14:15], s[48:49] op_sel_hi:[1,0]
	v_cvt_pk_bf16_f32 v93, v11, v15
	v_and_b32_sdwa v94, v14, v98 dst_sel:DWORD dst_unused:UNUSED_PAD src0_sel:WORD_1 src1_sel:DWORD
	v_and_b32_sdwa v92, v10, v98 dst_sel:DWORD dst_unused:UNUSED_PAD src0_sel:WORD_1 src1_sel:DWORD
	s_nop 0
	v_add3_u32 v94, v14, v94, s49
	v_add3_u32 v92, v10, v92, s49
	v_and_b32_e32 v94, 0xffff0000, v94
	v_or_b32_sdwa v92, v94, v92 dst_sel:DWORD dst_unused:UNUSED_PAD src0_sel:DWORD src1_sel:WORD_1
	ds_write_b64 v6, v[92:93] offset:34848
	v_lshlrev_b32_e32 v93, 2, v84
	v_add_u32_e32 v85, s54, v93
	ds_read_b32 v92, v85
	v_lshl_add_u64 v[88:89], v[54:55], 0, v[88:89]
	global_store_dwordx2 v[88:89], v[86:87], off
	v_add_u32_e32 v86, s55, v93
	ds_read_b32 v88, v86
	s_waitcnt lgkmcnt(1)
	v_pk_mul_f32 v[80:81], v[80:81], v[92:93] op_sel_hi:[1,0]
	v_pk_mul_f32 v[78:79], v[78:79], v[92:93] op_sel_hi:[1,0]
	v_and_b32_sdwa v86, v81, v98 dst_sel:DWORD dst_unused:UNUSED_PAD src0_sel:WORD_1 src1_sel:DWORD
	v_and_b32_sdwa v87, v80, v98 dst_sel:DWORD dst_unused:UNUSED_PAD src0_sel:WORD_1 src1_sel:DWORD
	v_add3_u32 v80, v80, v87, s49
	v_add3_u32 v81, v81, v86, s49
	v_and_b32_sdwa v86, v79, v98 dst_sel:DWORD dst_unused:UNUSED_PAD src0_sel:WORD_1 src1_sel:DWORD
	v_and_b32_sdwa v87, v78, v98 dst_sel:DWORD dst_unused:UNUSED_PAD src0_sel:WORD_1 src1_sel:DWORD
	v_add3_u32 v79, v79, v86, s49
	v_add3_u32 v78, v78, v87, s49
	v_ashrrev_i32_e32 v85, 31, v84
	v_and_b32_e32 v79, 0xffff0000, v79
	v_and_b32_e32 v78, 0xffff0000, v78
	v_or_b32_sdwa v81, v79, v81 dst_sel:DWORD dst_unused:UNUSED_PAD src0_sel:DWORD src1_sel:WORD_1
	v_or_b32_sdwa v80, v78, v80 dst_sel:DWORD dst_unused:UNUSED_PAD src0_sel:DWORD src1_sel:WORD_1
	v_lshlrev_b64 v[78:79], 9, v[84:85]
	s_waitcnt lgkmcnt(0)
	v_mul_f32_e32 v10, v10, v88
	v_lshl_add_u64 v[86:87], v[54:55], 0, v[78:79]
	v_lshlrev_b32_e32 v78, 1, v84
	v_bfe_u32 v79, v10, 16, 1
	v_add3_u32 v10, v10, v79, s49
	v_add_u32_e32 v79, v51, v78
	ds_write_b16_d16_hi v79, v10
	v_mul_f32_e32 v10, v14, v88
	v_bfe_u32 v14, v10, 16, 1
	v_add3_u32 v10, v10, v14, s49
	v_add3_u32 v14, s80, v78, v7
	ds_write_b16_d16_hi v14, v10 offset:144
	v_mul_f32_e32 v10, v11, v88
	v_bfe_u32 v11, v10, 16, 1
	v_add3_u32 v10, v10, v11, s49
	v_pk_mul_f32 v[84:85], v[64:65], v[82:83]
	ds_write_b16_d16_hi v14, v10 offset:288
	v_mul_f32_e32 v10, v15, v88
	v_lshlrev_b32_e32 v79, 16, v61
	v_lshlrev_b32_e32 v78, 16, v60
	v_pk_fma_f32 v[84:85], v[2:3], v[90:91], v[84:85]
	v_pk_mul_f32 v[88:89], v[28:29], v[70:71]
	v_and_b32_e32 v61, 0xffff0000, v61
	v_and_b32_e32 v60, 0xffff0000, v60
	v_pk_fma_f32 v[84:85], v[66:67], v[78:79], v[84:85]
	v_pk_fma_f32 v[74:75], v[32:33], v[74:75], v[88:89]
	v_bfe_u32 v11, v10, 16, 1
	v_pk_add_f32 v[84:85], v[68:69], v[84:85]
	v_pk_fma_f32 v[74:75], v[20:21], v[60:61], v[74:75]
	v_add3_u32 v10, v10, v11, s49
	v_mul_f32_e32 v11, 0xbfb8aa3b, v84
	v_pk_add_f32 v[74:75], v[24:25], v[74:75]
	v_exp_f32_e32 v11, v11
	v_mul_f32_e32 v15, 0xbfb8aa3b, v74
	v_exp_f32_e32 v15, v15
	v_mul_f32_e32 v89, 0xbfb8aa3b, v75
	v_add_f32_e32 v11, 1.0, v11
	v_rcp_f32_e32 v88, v11
	v_add_f32_e32 v11, 1.0, v15
	v_mul_f32_e32 v15, 0xbfb8aa3b, v85
	v_exp_f32_e32 v15, v15
	v_exp_f32_e32 v91, v89
	v_rcp_f32_e32 v90, v11
	ds_write_b16_d16_hi v14, v10 offset:432
	v_add_f32_e32 v11, 1.0, v15
	v_rcp_f32_e32 v89, v11
	v_add_f32_e32 v11, 1.0, v91
	v_rcp_f32_e32 v91, v11
	v_lshlrev_b32_e32 v14, 16, v56
	v_lshlrev_b32_e32 v15, 16, v57
	v_pk_mul_f32 v[84:85], v[84:85], v[88:89]
	v_pk_mul_f32 v[74:75], v[74:75], v[90:91]
	v_and_b32_e32 v56, 0xffff0000, v56
	v_pk_mul_f32 v[90:91], v[18:19], v[30:31]
	v_pk_fma_f32 v[76:77], v[58:59], v[76:77], v[90:91]
	v_pk_mul_f32 v[90:91], v[16:17], v[62:63]
	v_and_b32_e32 v57, 0xffff0000, v57
	v_cvt_pk_bf16_f32 v89, v85, v75
	v_pk_fma_f32 v[76:77], v[22:23], v[14:15], v[76:77]
	v_pk_fma_f32 v[72:73], v[4:5], v[72:73], v[90:91]
	v_pk_add_f32 v[76:77], v[26:27], v[76:77]
	v_pk_fma_f32 v[72:73], v[12:13], v[56:57], v[72:73]
	v_mul_f32_e32 v11, 0xbfb8aa3b, v76
	v_pk_add_f32 v[72:73], v[8:9], v[72:73]
	v_exp_f32_e32 v11, v11
	v_mul_f32_e32 v90, 0xbfb8aa3b, v72
	v_exp_f32_e32 v91, v90
	v_cvt_pk_bf16_f32 v88, v84, v74
	v_add_f32_e32 v11, 1.0, v11
	v_rcp_f32_e32 v90, v11
	v_add_f32_e32 v11, 1.0, v91
	v_mul_f32_e32 v91, 0xbfb8aa3b, v77
	v_exp_f32_e32 v91, v91
	v_mul_f32_e32 v92, 0xbfb8aa3b, v73
	v_exp_f32_e32 v93, v92
	v_rcp_f32_e32 v92, v11
	v_add_f32_e32 v11, 1.0, v91
	v_rcp_f32_e32 v91, v11
	v_add_f32_e32 v11, 1.0, v93
	v_rcp_f32_e32 v93, v11
	ds_write_b64 v6, v[88:89] offset:1584
	v_pk_mul_f32 v[76:77], v[76:77], v[90:91]
	v_or_b32_e32 v10, 4, v50
	v_pk_mul_f32 v[72:73], v[72:73], v[92:93]
	v_pk_mul_f32 v[76:77], v[76:77], s[48:49] op_sel_hi:[1,0]
	v_pk_mul_f32 v[72:73], v[72:73], s[48:49] op_sel_hi:[1,0]
	v_cvt_pk_bf16_f32 v89, v77, v73
	v_and_b32_sdwa v90, v72, v98 dst_sel:DWORD dst_unused:UNUSED_PAD src0_sel:WORD_1 src1_sel:DWORD
	v_and_b32_sdwa v88, v76, v98 dst_sel:DWORD dst_unused:UNUSED_PAD src0_sel:WORD_1 src1_sel:DWORD
	s_nop 0
	v_add3_u32 v90, v72, v90, s49
	v_add3_u32 v88, v76, v88, s49
	v_and_b32_e32 v90, 0xffff0000, v90
	v_or_b32_sdwa v88, v90, v88 dst_sel:DWORD dst_unused:UNUSED_PAD src0_sel:DWORD src1_sel:WORD_1
	ds_write_b64 v6, v[88:89] offset:35376
	v_lshlrev_b32_e32 v89, 2, v10
	v_add_u32_e32 v11, s54, v89
	ds_read_b32 v88, v11
	global_store_dwordx2 v[86:87], v[80:81], off
	v_add_u32_e32 v80, s55, v89
	ds_read_b32 v86, v80
	v_ashrrev_i32_e32 v11, 31, v10
	s_waitcnt lgkmcnt(1)
	v_pk_mul_f32 v[80:81], v[84:85], v[88:89] op_sel_hi:[1,0]
	v_pk_mul_f32 v[74:75], v[74:75], v[88:89] op_sel_hi:[1,0]
	v_and_b32_sdwa v84, v81, v98 dst_sel:DWORD dst_unused:UNUSED_PAD src0_sel:WORD_1 src1_sel:DWORD
	v_and_b32_sdwa v85, v80, v98 dst_sel:DWORD dst_unused:UNUSED_PAD src0_sel:WORD_1 src1_sel:DWORD
	v_add3_u32 v80, v80, v85, s49
	v_add3_u32 v81, v81, v84, s49
	v_and_b32_sdwa v84, v75, v98 dst_sel:DWORD dst_unused:UNUSED_PAD src0_sel:WORD_1 src1_sel:DWORD
	v_and_b32_sdwa v85, v74, v98 dst_sel:DWORD dst_unused:UNUSED_PAD src0_sel:WORD_1 src1_sel:DWORD
	v_add3_u32 v75, v75, v84, s49
	v_add3_u32 v74, v74, v85, s49
	v_and_b32_e32 v75, 0xffff0000, v75
	v_and_b32_e32 v74, 0xffff0000, v74
	v_or_b32_sdwa v75, v75, v81 dst_sel:DWORD dst_unused:UNUSED_PAD src0_sel:DWORD src1_sel:WORD_1
	v_or_b32_sdwa v74, v74, v80 dst_sel:DWORD dst_unused:UNUSED_PAD src0_sel:DWORD src1_sel:WORD_1
	v_lshlrev_b64 v[80:81], 9, v[10:11]
	s_waitcnt lgkmcnt(0)
	v_mul_f32_e32 v11, v76, v86
	v_lshlrev_b32_e32 v10, 1, v10
	v_bfe_u32 v76, v11, 16, 1
	v_add3_u32 v11, v11, v76, s49
	v_add_u32_e32 v76, v51, v10
	ds_write_b16_d16_hi v76, v11
	v_mul_f32_e32 v11, v72, v86
	v_bfe_u32 v72, v11, 16, 1
	v_add3_u32 v11, v11, v72, s49
	v_add3_u32 v10, s80, v10, v7
	ds_write_b16_d16_hi v10, v11 offset:144
	v_mul_f32_e32 v11, v77, v86
	v_bfe_u32 v72, v11, 16, 1
	v_add3_u32 v11, v11, v72, s49
	ds_write_b16_d16_hi v10, v11 offset:288
	v_mul_f32_e32 v11, v73, v86
	v_bfe_u32 v72, v11, 16, 1
	v_pk_mul_f32 v[84:85], v[64:65], v[78:79]
	v_add3_u32 v11, v11, v72, s49
	v_lshlrev_b32_e32 v73, 16, v53
	v_lshlrev_b32_e32 v72, 16, v52
	v_pk_fma_f32 v[82:83], v[2:3], v[82:83], v[84:85]
	v_pk_mul_f32 v[84:85], v[28:29], v[60:61]
	v_and_b32_e32 v53, 0xffff0000, v53
	v_and_b32_e32 v52, 0xffff0000, v52
	v_pk_fma_f32 v[82:83], v[66:67], v[72:73], v[82:83]
	v_pk_fma_f32 v[70:71], v[32:33], v[70:71], v[84:85]
	v_pk_add_f32 v[82:83], v[68:69], v[82:83]
	v_pk_fma_f32 v[70:71], v[20:21], v[52:53], v[70:71]
	ds_write_b16_d16_hi v10, v11 offset:432
	v_mul_f32_e32 v11, 0xbfb8aa3b, v82
	v_pk_add_f32 v[70:71], v[24:25], v[70:71]
	v_exp_f32_e32 v11, v11
	v_mul_f32_e32 v77, 0xbfb8aa3b, v70
	v_exp_f32_e32 v77, v77
	v_mul_f32_e32 v85, 0xbfb8aa3b, v71
	v_add_f32_e32 v11, 1.0, v11
	v_rcp_f32_e32 v84, v11
	v_add_f32_e32 v11, 1.0, v77
	v_mul_f32_e32 v77, 0xbfb8aa3b, v83
	v_exp_f32_e32 v77, v77
	v_exp_f32_e32 v87, v85
	v_rcp_f32_e32 v86, v11
	v_lshlrev_b32_e32 v10, 16, v48
	v_add_f32_e32 v11, 1.0, v77
	v_rcp_f32_e32 v85, v11
	v_add_f32_e32 v11, 1.0, v87
	v_rcp_f32_e32 v87, v11
	v_lshlrev_b32_e32 v11, 16, v49
	v_pk_mul_f32 v[82:83], v[82:83], v[84:85]
	v_and_b32_e32 v48, 0xffff0000, v48
	v_pk_mul_f32 v[70:71], v[70:71], v[86:87]
	v_and_b32_e32 v49, 0xffff0000, v49
	v_pk_mul_f32 v[86:87], v[18:19], v[14:15]
	v_pk_fma_f32 v[30:31], v[58:59], v[30:31], v[86:87]
	v_pk_mul_f32 v[86:87], v[16:17], v[56:57]
	v_cvt_pk_bf16_f32 v85, v83, v71
	v_pk_fma_f32 v[30:31], v[22:23], v[10:11], v[30:31]
	v_pk_fma_f32 v[62:63], v[4:5], v[62:63], v[86:87]
	v_pk_add_f32 v[30:31], v[26:27], v[30:31]
	v_pk_fma_f32 v[62:63], v[12:13], v[48:49], v[62:63]
	v_mul_f32_e32 v77, 0xbfb8aa3b, v30
	v_pk_add_f32 v[62:63], v[8:9], v[62:63]
	v_exp_f32_e32 v77, v77
	v_mul_f32_e32 v86, 0xbfb8aa3b, v62
	v_exp_f32_e32 v87, v86
	v_cvt_pk_bf16_f32 v84, v82, v70
	v_add_f32_e32 v77, 1.0, v77
	v_rcp_f32_e32 v86, v77
	v_add_f32_e32 v77, 1.0, v87
	v_mul_f32_e32 v87, 0xbfb8aa3b, v31
	v_exp_f32_e32 v87, v87
	v_mul_f32_e32 v88, 0xbfb8aa3b, v63
	v_exp_f32_e32 v89, v88
	v_rcp_f32_e32 v88, v77
	v_add_f32_e32 v77, 1.0, v87
	v_rcp_f32_e32 v87, v77
	v_add_f32_e32 v77, 1.0, v89
	v_rcp_f32_e32 v89, v77
	ds_write_b64 v6, v[84:85] offset:2112
	v_pk_mul_f32 v[30:31], v[30:31], v[86:87]
	v_or_b32_e32 v76, 5, v50
	v_pk_mul_f32 v[62:63], v[62:63], v[88:89]
	v_pk_mul_f32 v[30:31], v[30:31], s[48:49] op_sel_hi:[1,0]
	v_pk_mul_f32 v[62:63], v[62:63], s[48:49] op_sel_hi:[1,0]
	v_cvt_pk_bf16_f32 v85, v31, v63
	v_and_b32_sdwa v86, v62, v98 dst_sel:DWORD dst_unused:UNUSED_PAD src0_sel:WORD_1 src1_sel:DWORD
	v_and_b32_sdwa v84, v30, v98 dst_sel:DWORD dst_unused:UNUSED_PAD src0_sel:WORD_1 src1_sel:DWORD
	s_nop 0
	v_add3_u32 v86, v62, v86, s49
	v_add3_u32 v84, v30, v84, s49
	v_and_b32_e32 v86, 0xffff0000, v86
	v_or_b32_sdwa v84, v86, v84 dst_sel:DWORD dst_unused:UNUSED_PAD src0_sel:DWORD src1_sel:WORD_1
	ds_write_b64 v6, v[84:85] offset:35904
	v_lshlrev_b32_e32 v85, 2, v76
	v_add_u32_e32 v77, s54, v85
	ds_read_b32 v84, v77
	v_lshl_add_u64 v[80:81], v[54:55], 0, v[80:81]
	global_store_dwordx2 v[80:81], v[74:75], off
	v_add_u32_e32 v74, s55, v85
	ds_read_b32 v80, v74
	s_waitcnt lgkmcnt(1)
	v_pk_mul_f32 v[74:75], v[82:83], v[84:85] op_sel_hi:[1,0]
	v_pk_mul_f32 v[70:71], v[70:71], v[84:85] op_sel_hi:[1,0]
	v_and_b32_sdwa v81, v75, v98 dst_sel:DWORD dst_unused:UNUSED_PAD src0_sel:WORD_1 src1_sel:DWORD
	v_and_b32_sdwa v82, v74, v98 dst_sel:DWORD dst_unused:UNUSED_PAD src0_sel:WORD_1 src1_sel:DWORD
	v_add3_u32 v74, v74, v82, s49
	v_add3_u32 v75, v75, v81, s49
	v_and_b32_sdwa v81, v71, v98 dst_sel:DWORD dst_unused:UNUSED_PAD src0_sel:WORD_1 src1_sel:DWORD
	v_and_b32_sdwa v82, v70, v98 dst_sel:DWORD dst_unused:UNUSED_PAD src0_sel:WORD_1 src1_sel:DWORD
	v_add3_u32 v71, v71, v81, s49
	v_add3_u32 v70, v70, v82, s49
	v_ashrrev_i32_e32 v77, 31, v76
	v_and_b32_e32 v71, 0xffff0000, v71
	v_and_b32_e32 v70, 0xffff0000, v70
	s_waitcnt lgkmcnt(0)
	v_mul_f32_e32 v30, v30, v80
	v_or_b32_sdwa v71, v71, v75 dst_sel:DWORD dst_unused:UNUSED_PAD src0_sel:DWORD src1_sel:WORD_1
	v_or_b32_sdwa v70, v70, v74 dst_sel:DWORD dst_unused:UNUSED_PAD src0_sel:DWORD src1_sel:WORD_1
	v_lshlrev_b64 v[74:75], 9, v[76:77]
	v_lshlrev_b32_e32 v76, 1, v76
	v_bfe_u32 v77, v30, 16, 1
	v_add3_u32 v30, v30, v77, s49
	v_add_u32_e32 v77, v51, v76
	ds_write_b16_d16_hi v77, v30
	v_mul_f32_e32 v30, v62, v80
	v_bfe_u32 v62, v30, 16, 1
	v_add3_u32 v30, v30, v62, s49
	v_add3_u32 v62, s80, v76, v7
	ds_write_b16_d16_hi v62, v30 offset:144
	v_mul_f32_e32 v30, v31, v80
	v_bfe_u32 v31, v30, 16, 1
	v_add3_u32 v30, v30, v31, s49
	ds_write_b16_d16_hi v62, v30 offset:288
	v_mul_f32_e32 v30, v63, v80
	v_pk_mul_f32 v[80:81], v[64:65], v[72:73]
	v_lshlrev_b32_e32 v77, 16, v47
	v_lshlrev_b32_e32 v76, 16, v46
	v_pk_fma_f32 v[78:79], v[2:3], v[78:79], v[80:81]
	v_pk_mul_f32 v[80:81], v[28:29], v[52:53]
	v_and_b32_e32 v47, 0xffff0000, v47
	v_and_b32_e32 v46, 0xffff0000, v46
	v_pk_fma_f32 v[78:79], v[66:67], v[76:77], v[78:79]
	v_pk_fma_f32 v[60:61], v[32:33], v[60:61], v[80:81]
	v_bfe_u32 v31, v30, 16, 1
	v_pk_add_f32 v[78:79], v[68:69], v[78:79]
	v_pk_fma_f32 v[60:61], v[20:21], v[46:47], v[60:61]
	v_add3_u32 v30, v30, v31, s49
	v_mul_f32_e32 v31, 0xbfb8aa3b, v78
	v_pk_add_f32 v[60:61], v[24:25], v[60:61]
	v_exp_f32_e32 v31, v31
	v_mul_f32_e32 v63, 0xbfb8aa3b, v60
	v_exp_f32_e32 v63, v63
	v_mul_f32_e32 v81, 0xbfb8aa3b, v61
	v_add_f32_e32 v31, 1.0, v31
	v_rcp_f32_e32 v80, v31
	v_add_f32_e32 v31, 1.0, v63
	v_mul_f32_e32 v63, 0xbfb8aa3b, v79
	v_exp_f32_e32 v63, v63
	v_exp_f32_e32 v83, v81
	v_rcp_f32_e32 v82, v31
	ds_write_b16_d16_hi v62, v30 offset:432
	v_add_f32_e32 v31, 1.0, v63
	v_rcp_f32_e32 v81, v31
	v_add_f32_e32 v31, 1.0, v83
	v_rcp_f32_e32 v83, v31
	v_lshlrev_b32_e32 v62, 16, v44
	v_lshlrev_b32_e32 v63, 16, v45
	v_pk_mul_f32 v[78:79], v[78:79], v[80:81]
	v_pk_mul_f32 v[60:61], v[60:61], v[82:83]
	v_and_b32_e32 v44, 0xffff0000, v44
	v_pk_mul_f32 v[82:83], v[18:19], v[10:11]
	v_pk_fma_f32 v[14:15], v[58:59], v[14:15], v[82:83]
	v_pk_mul_f32 v[82:83], v[16:17], v[48:49]
	v_and_b32_e32 v45, 0xffff0000, v45
	v_cvt_pk_bf16_f32 v81, v79, v61
	v_pk_fma_f32 v[14:15], v[22:23], v[62:63], v[14:15]
	v_pk_fma_f32 v[56:57], v[4:5], v[56:57], v[82:83]
	v_pk_add_f32 v[14:15], v[26:27], v[14:15]
	v_pk_fma_f32 v[56:57], v[12:13], v[44:45], v[56:57]
	v_mul_f32_e32 v31, 0xbfb8aa3b, v14
	v_pk_add_f32 v[56:57], v[8:9], v[56:57]
	v_exp_f32_e32 v31, v31
	v_mul_f32_e32 v82, 0xbfb8aa3b, v56
	v_exp_f32_e32 v83, v82
	v_cvt_pk_bf16_f32 v80, v78, v60
	v_add_f32_e32 v31, 1.0, v31
	v_rcp_f32_e32 v82, v31
	v_add_f32_e32 v31, 1.0, v83
	v_mul_f32_e32 v83, 0xbfb8aa3b, v15
	v_exp_f32_e32 v83, v83
	v_mul_f32_e32 v84, 0xbfb8aa3b, v57
	v_exp_f32_e32 v85, v84
	v_rcp_f32_e32 v84, v31
	v_add_f32_e32 v31, 1.0, v83
	v_rcp_f32_e32 v83, v31
	v_add_f32_e32 v31, 1.0, v85
	v_rcp_f32_e32 v85, v31
	ds_write_b64 v6, v[80:81] offset:2640
	v_pk_mul_f32 v[14:15], v[14:15], v[82:83]
	v_or_b32_e32 v30, 6, v50
	v_pk_mul_f32 v[56:57], v[56:57], v[84:85]
	v_pk_mul_f32 v[14:15], v[14:15], s[48:49] op_sel_hi:[1,0]
	v_pk_mul_f32 v[56:57], v[56:57], s[48:49] op_sel_hi:[1,0]
	v_cvt_pk_bf16_f32 v81, v15, v57
	v_and_b32_sdwa v82, v56, v98 dst_sel:DWORD dst_unused:UNUSED_PAD src0_sel:WORD_1 src1_sel:DWORD
	v_and_b32_sdwa v80, v14, v98 dst_sel:DWORD dst_unused:UNUSED_PAD src0_sel:WORD_1 src1_sel:DWORD
	s_nop 0
	v_add3_u32 v82, v56, v82, s49
	v_add3_u32 v80, v14, v80, s49
	v_and_b32_e32 v82, 0xffff0000, v82
	v_or_b32_sdwa v80, v82, v80 dst_sel:DWORD dst_unused:UNUSED_PAD src0_sel:DWORD src1_sel:WORD_1
	ds_write_b64 v6, v[80:81] offset:36432
	v_lshlrev_b32_e32 v81, 2, v30
	v_add_u32_e32 v31, s54, v81
	ds_read_b32 v80, v31
	v_lshl_add_u64 v[74:75], v[54:55], 0, v[74:75]
	global_store_dwordx2 v[74:75], v[70:71], off
	v_add_u32_e32 v70, s55, v81
	ds_read_b32 v74, v70
	s_waitcnt lgkmcnt(1)
	v_pk_mul_f32 v[70:71], v[78:79], v[80:81] op_sel_hi:[1,0]
	v_pk_mul_f32 v[60:61], v[60:61], v[80:81] op_sel_hi:[1,0]
	v_and_b32_sdwa v75, v71, v98 dst_sel:DWORD dst_unused:UNUSED_PAD src0_sel:WORD_1 src1_sel:DWORD
	v_and_b32_sdwa v78, v70, v98 dst_sel:DWORD dst_unused:UNUSED_PAD src0_sel:WORD_1 src1_sel:DWORD
	v_add3_u32 v70, v70, v78, s49
	v_add3_u32 v71, v71, v75, s49
	v_and_b32_sdwa v75, v61, v98 dst_sel:DWORD dst_unused:UNUSED_PAD src0_sel:WORD_1 src1_sel:DWORD
	v_and_b32_sdwa v78, v60, v98 dst_sel:DWORD dst_unused:UNUSED_PAD src0_sel:WORD_1 src1_sel:DWORD
	v_add3_u32 v61, v61, v75, s49
	v_add3_u32 v60, v60, v78, s49
	v_ashrrev_i32_e32 v31, 31, v30
	v_and_b32_e32 v61, 0xffff0000, v61
	v_and_b32_e32 v60, 0xffff0000, v60
	s_waitcnt lgkmcnt(0)
	v_mul_f32_e32 v14, v14, v74
	v_or_b32_sdwa v61, v61, v71 dst_sel:DWORD dst_unused:UNUSED_PAD src0_sel:DWORD src1_sel:WORD_1
	v_or_b32_sdwa v60, v60, v70 dst_sel:DWORD dst_unused:UNUSED_PAD src0_sel:DWORD src1_sel:WORD_1
	v_lshlrev_b64 v[70:71], 9, v[30:31]
	v_lshlrev_b32_e32 v30, 1, v30
	v_bfe_u32 v31, v14, 16, 1
	v_add3_u32 v14, v14, v31, s49
	v_add_u32_e32 v31, v51, v30
	ds_write_b16_d16_hi v31, v14
	v_mul_f32_e32 v14, v56, v74
	v_bfe_u32 v31, v14, 16, 1
	v_add3_u32 v14, v14, v31, s49
	v_add3_u32 v30, s80, v30, v7
	ds_write_b16_d16_hi v30, v14 offset:144
	v_mul_f32_e32 v14, v15, v74
	v_bfe_u32 v15, v14, 16, 1
	v_add3_u32 v14, v14, v15, s49
	ds_write_b16_d16_hi v30, v14 offset:288
	v_mul_f32_e32 v14, v57, v74
	v_bfe_u32 v15, v14, 16, 1
	v_add3_u32 v14, v14, v15, s49
	ds_write_b16_d16_hi v30, v14 offset:432
	v_or_b32_e32 v14, 7, v50
	v_add_u32_e32 v15, s91, v14
	v_and_b32_e32 v15, 0xffffefff, v15
	v_cmp_eq_u32_e32 vcc, s82, v15
	v_lshlrev_b32_e32 v56, 16, v42
	v_lshlrev_b32_e32 v57, 16, v43
	v_pk_mul_f32 v[64:65], v[64:65], v[76:77]
	v_cndmask_b32_e64 v30, 1.0, 0, vcc
	v_and_b32_e32 v42, 0xffff0000, v42
	v_and_b32_e32 v43, 0xffff0000, v43
	v_pk_fma_f32 v[2:3], v[2:3], v[72:73], v[64:65]
	v_pk_mul_f32 v[56:57], v[66:67], v[56:57]
	v_pk_mul_f32 v[28:29], v[28:29], v[46:47]
	v_pk_fma_f32 v[2:3], v[56:57], v[30:31], v[2:3] op_sel_hi:[1,0,1]
	v_pk_fma_f32 v[28:29], v[32:33], v[52:53], v[28:29]
	v_pk_mul_f32 v[20:21], v[20:21], v[42:43]
	v_pk_add_f32 v[2:3], v[68:69], v[2:3]
	v_pk_fma_f32 v[20:21], v[20:21], v[30:31], v[28:29] op_sel_hi:[1,0,1]
	v_mul_f32_e32 v15, 0xbfb8aa3b, v2
	v_pk_add_f32 v[20:21], v[24:25], v[20:21]
	v_exp_f32_e32 v15, v15
	v_mul_f32_e32 v24, 0xbfb8aa3b, v20
	v_exp_f32_e32 v25, v24
	v_mul_f32_e32 v28, 0xbfb8aa3b, v21
	v_add_f32_e32 v15, 1.0, v15
	v_rcp_f32_e32 v24, v15
	v_add_f32_e32 v15, 1.0, v25
	v_mul_f32_e32 v25, 0xbfb8aa3b, v3
	v_exp_f32_e32 v25, v25
	v_exp_f32_e32 v29, v28
	v_rcp_f32_e32 v28, v15
	v_lshlrev_b32_e32 v75, 16, v41
	v_add_f32_e32 v15, 1.0, v25
	v_rcp_f32_e32 v25, v15
	v_add_f32_e32 v15, 1.0, v29
	v_rcp_f32_e32 v29, v15
	v_lshlrev_b32_e32 v74, 16, v40
	v_pk_mul_f32 v[18:19], v[18:19], v[62:63]
	v_pk_mul_f32 v[2:3], v[2:3], v[24:25]
	v_pk_mul_f32 v[20:21], v[20:21], v[28:29]
	v_pk_fma_f32 v[10:11], v[58:59], v[10:11], v[18:19]
	v_pk_mul_f32 v[18:19], v[22:23], v[74:75]
	v_and_b32_e32 v33, 0xffff0000, v41
	v_and_b32_e32 v32, 0xffff0000, v40
	v_cvt_pk_bf16_f32 v25, v3, v21
	v_pk_fma_f32 v[10:11], v[30:31], v[18:19], v[10:11] op_sel_hi:[0,1,1]
	v_pk_mul_f32 v[16:17], v[16:17], v[44:45]
	v_pk_add_f32 v[10:11], v[26:27], v[10:11]
	v_pk_fma_f32 v[4:5], v[4:5], v[48:49], v[16:17]
	v_pk_mul_f32 v[12:13], v[12:13], v[32:33]
	v_mul_f32_e32 v15, 0xbfb8aa3b, v10
	v_pk_fma_f32 v[4:5], v[30:31], v[12:13], v[4:5] op_sel_hi:[0,1,1]
	v_exp_f32_e32 v15, v15
	v_pk_add_f32 v[4:5], v[8:9], v[4:5]
	v_mul_f32_e32 v12, 0xbfb8aa3b, v11
	v_mul_f32_e32 v8, 0xbfb8aa3b, v4
	v_exp_f32_e32 v9, v8
	v_exp_f32_e32 v13, v12
	v_mul_f32_e32 v12, 0xbfb8aa3b, v5
	v_add_f32_e32 v8, 1.0, v15
	v_exp_f32_e32 v15, v12
	v_add_f32_e32 v9, 1.0, v9
	v_rcp_f32_e32 v12, v9
	v_add_f32_e32 v9, 1.0, v13
	v_rcp_f32_e32 v8, v8
	v_rcp_f32_e32 v9, v9
	v_add_f32_e32 v13, 1.0, v15
	v_rcp_f32_e32 v13, v13
	v_cvt_pk_bf16_f32 v24, v2, v20
	v_pk_mul_f32 v[8:9], v[10:11], v[8:9]
	v_pk_mul_f32 v[8:9], v[8:9], s[48:49] op_sel_hi:[1,0]
	v_pk_mul_f32 v[4:5], v[4:5], v[12:13]
	v_pk_mul_f32 v[4:5], v[4:5], s[48:49] op_sel_hi:[1,0]
	v_cvt_pk_bf16_f32 v11, v9, v5
	v_cvt_pk_bf16_f32 v10, v8, v4
	ds_write_b64 v6, v[10:11] offset:36960
	v_lshlrev_b32_e32 v10, 2, v14
	ds_write_b64 v6, v[24:25] offset:3168
	v_add_u32_e32 v6, s54, v10
	ds_read_b32 v6, v6
	v_add_u32_e32 v10, s55, v10
	ds_read_b32 v12, v10
	v_ashrrev_i32_e32 v15, 31, v14
	v_lshl_add_u64 v[70:71], v[54:55], 0, v[70:71]
	s_waitcnt lgkmcnt(1)
	v_pk_mul_f32 v[2:3], v[2:3], v[6:7] op_sel_hi:[1,0]
	v_pk_mul_f32 v[10:11], v[20:21], v[6:7] op_sel_hi:[1,0]
	v_and_b32_sdwa v13, v2, v98 dst_sel:DWORD dst_unused:UNUSED_PAD src0_sel:WORD_1 src1_sel:DWORD
	v_and_b32_sdwa v6, v3, v98 dst_sel:DWORD dst_unused:UNUSED_PAD src0_sel:WORD_1 src1_sel:DWORD
	v_add3_u32 v2, v2, v13, s49
	v_and_b32_sdwa v13, v10, v98 dst_sel:DWORD dst_unused:UNUSED_PAD src0_sel:WORD_1 src1_sel:DWORD
	v_add3_u32 v3, v3, v6, s49
	v_and_b32_sdwa v6, v11, v98 dst_sel:DWORD dst_unused:UNUSED_PAD src0_sel:WORD_1 src1_sel:DWORD
	v_add3_u32 v10, v10, v13, s49
	v_add3_u32 v6, v11, v6, s49
	v_and_b32_e32 v10, 0xffff0000, v10
	v_and_b32_e32 v6, 0xffff0000, v6
	v_or_b32_sdwa v2, v10, v2 dst_sel:DWORD dst_unused:UNUSED_PAD src0_sel:DWORD src1_sel:WORD_1
	v_lshlrev_b64 v[10:11], 9, v[14:15]
	v_or_b32_sdwa v3, v6, v3 dst_sel:DWORD dst_unused:UNUSED_PAD src0_sel:DWORD src1_sel:WORD_1
	v_lshl_add_u64 v[10:11], v[54:55], 0, v[10:11]
	global_store_dwordx2 v[10:11], v[2:3], off
	s_waitcnt lgkmcnt(0)
	v_mul_f32_e32 v3, v8, v12
	v_lshlrev_b32_e32 v2, 1, v14
	v_bfe_u32 v6, v3, 16, 1
	v_add3_u32 v3, v3, v6, s49
	v_add_u32_e32 v6, v51, v2
	ds_write_b16_d16_hi v6, v3
	v_mul_f32_e32 v3, v4, v12
	v_bfe_u32 v4, v3, 16, 1
	v_add3_u32 v3, v3, v4, s49
	v_add3_u32 v2, s80, v2, v7
	ds_write_b16_d16_hi v2, v3 offset:144
	v_mul_f32_e32 v3, v9, v12
	v_bfe_u32 v4, v3, 16, 1
	v_add3_u32 v3, v3, v4, s49
	ds_write_b16_d16_hi v2, v3 offset:288
	v_mul_f32_e32 v3, v5, v12
	v_bfe_u32 v4, v3, 16, 1
	v_add3_u32 v3, v3, v4, s49
	ds_write_b16_d16_hi v2, v3 offset:432
	v_and_b32_e32 v3, 48, v99
	v_and_or_b32 v2, v50, s28, v39
	v_add_u32_e32 v6, 0, v3
	v_mad_u64_u32 v[32:33], s[28:29], v2, s81, v[6:7]
	global_store_dwordx2 v[70:71], v[60:61], off
	s_waitcnt lgkmcnt(0)
	s_barrier
	ds_read_b128 v[2:5], v32
	v_and_or_b32 v10, v34, 32, v39
	v_mad_u32_u24 v11, v10, s81, v6
	ds_read_b128 v[12:15], v32 offset:64
	ds_read_b128 v[6:9], v11 offset:33792
	ds_read_b128 v[16:19], v11 offset:33856
	ds_read_b128 v[20:23], v32 offset:128
	s_waitcnt lgkmcnt(2)
	v_mfma_f32_16x16x32_bf16 v[6:9], v[2:5], v[6:9], 0
	s_add_i32 s28, 0, 0x1bd00
	s_waitcnt lgkmcnt(1)
	v_mfma_f32_16x16x32_bf16 v[6:9], v[12:15], v[16:19], v[6:9]
	ds_read_b128 v[16:19], v32 offset:192
	ds_read_b128 v[24:27], v11 offset:33920
	ds_read_b128 v[28:31], v11 offset:33984
	s_waitcnt lgkmcnt(1)
	v_mfma_f32_16x16x32_bf16 v[6:9], v[20:23], v[24:27], v[6:9]
	ds_read_b128 v[24:27], v32 offset:256
	s_waitcnt lgkmcnt(1)
	v_mfma_f32_16x16x32_bf16 v[6:9], v[16:19], v[28:31], v[6:9]
	ds_read_b128 v[28:31], v32 offset:320
	ds_read_b128 v[40:43], v11 offset:34048
	ds_read_b128 v[44:47], v11 offset:34112
	s_waitcnt lgkmcnt(1)
	v_mfma_f32_16x16x32_bf16 v[6:9], v[24:27], v[40:43], v[6:9]
	ds_read_b128 v[40:43], v32 offset:384
	s_waitcnt lgkmcnt(1)
	v_mfma_f32_16x16x32_bf16 v[6:9], v[28:31], v[44:47], v[6:9]
	ds_read_b128 v[44:47], v32 offset:448
	ds_read_b128 v[48:51], v11 offset:34176
	ds_read_b128 v[52:55], v11 offset:34240
	s_waitcnt lgkmcnt(1)
	v_mfma_f32_16x16x32_bf16 v[6:9], v[40:43], v[48:51], v[6:9]
	s_waitcnt lgkmcnt(0)
	v_mfma_f32_16x16x32_bf16 v[6:9], v[44:47], v[52:55], v[6:9]
	ds_read_b128 v[48:51], v11 offset:42240
	ds_read_b128 v[52:55], v11 offset:42304
	s_waitcnt lgkmcnt(1)
	v_mfma_f32_16x16x32_bf16 v[2:5], v[2:5], v[48:51], 0
	s_waitcnt lgkmcnt(0)
	v_mfma_f32_16x16x32_bf16 v[2:5], v[12:15], v[52:55], v[2:5]
	ds_read_b128 v[12:15], v11 offset:42368
	ds_read_b128 v[48:51], v11 offset:42432
	s_waitcnt lgkmcnt(1)
	v_mfma_f32_16x16x32_bf16 v[2:5], v[20:23], v[12:15], v[2:5]
	s_waitcnt lgkmcnt(0)
	v_mfma_f32_16x16x32_bf16 v[2:5], v[16:19], v[48:51], v[2:5]
	ds_read_b128 v[12:15], v11 offset:42496
	ds_read_b128 v[16:19], v11 offset:42560
	s_waitcnt lgkmcnt(1)
	v_mfma_f32_16x16x32_bf16 v[2:5], v[24:27], v[12:15], v[2:5]
	s_waitcnt lgkmcnt(0)
	v_mfma_f32_16x16x32_bf16 v[2:5], v[28:31], v[16:19], v[2:5]
	ds_read_b128 v[12:15], v11 offset:42624
	ds_read_b128 v[16:19], v11 offset:42688
	v_ashrrev_i32_e32 v11, 3, v38
	v_and_b32_e32 v11, -16, v11
	s_waitcnt lgkmcnt(1)
	v_mfma_f32_16x16x32_bf16 v[2:5], v[40:43], v[12:15], v[2:5]
	v_lshrrev_b32_e32 v12, 2, v99
	v_and_or_b32 v11, v12, 12, v11
	v_cmp_le_i32_e32 vcc, v10, v11
	s_waitcnt lgkmcnt(0)
	v_mfma_f32_16x16x32_bf16 v[2:5], v[44:47], v[16:19], v[2:5]
	v_mov_b32_e32 v15, 0
	v_cndmask_b32_e64 v12, 0, 1, vcc
	v_cmp_ge_i32_e32 vcc, v10, v11
	v_lshl_add_u32 v19, v10, 2, s28
	s_nop 0
	v_cndmask_b32_e64 v13, 0, 1, vcc
	v_cndmask_b32_e64 v12, v13, v12, s[6:7]
	v_and_b32_e32 v12, 1, v12
	v_cmp_eq_u32_e32 vcc, 1, v12
	v_lshl_add_u32 v12, v11, 2, 0
	v_mov_b32_e32 v13, 0
	s_and_saveexec_b64 s[54:55], vcc
	s_cbranch_execz .LBB0_1770
	v_add_u32_e32 v13, 0x1bc00, v12
	ds_read_b32 v13, v13
	ds_read_b32 v14, v19
	s_waitcnt lgkmcnt(0)
	v_add_f32_e32 v13, v13, v14
	v_mul_f32_e32 v13, 0x3fb8aa3b, v13
	v_exp_f32_e32 v13, v13
	s_nop 0
	v_mul_f32_e32 v13, v6, v13

.LBB0_1869:
	ds_read2_b32 v[20:21], v18 offset1:65
	ds_read2_b32 v[22:23], v18 offset0:130 offset1:195
	v_add_u32_e32 v19, 0x400, v18
	ds_read2_b32 v[26:27], v19 offset0:4 offset1:69
	ds_read2_b32 v[28:29], v19 offset0:134 offset1:199
	s_and_b32 s8, s46, 0xffffffc0
	s_waitcnt lgkmcnt(3)
	v_cvt_pk_bf16_f32 v20, v20, v21
	s_waitcnt lgkmcnt(2)
	v_cvt_pk_bf16_f32 v21, v22, v23
	s_waitcnt lgkmcnt(1)
	v_cvt_pk_bf16_f32 v22, v26, v27
	v_add_u32_e32 v24, s8, v15
	v_ashrrev_i32_e32 v25, 31, v24
	s_and_b32 s0, s0, 0x3c0
	s_waitcnt lgkmcnt(0)
	v_bfe_u32 v19, v28, 16, 1
	v_lshlrev_b64 v[24:25], 11, v[24:25]
	v_add3_u32 v19, v28, v19, s29
	v_bfe_u32 v23, v29, 16, 1
	v_lshl_add_u64 v[24:25], s[14:15], 0, v[24:25]
	s_lshl_b32 s0, s0, 1
	v_lshrrev_b32_e32 v19, 16, v19
	v_add3_u32 v23, v29, v23, s29
	v_lshl_add_u64 v[24:25], v[24:25], 0, s[0:1]
	v_and_or_b32 v23, v23, s28, v19
	v_lshl_add_u64 v[24:25], v[24:25], 0, v[10:11]
	global_store_dwordx4 v[24:25], v[20:23], off
	s_waitcnt lgkmcnt(0)
	s_barrier
	s_andn2_b64 vcc, exec, s[6:7]
	s_mov_b32 s0, s47
	s_mov_b32 s46, s45
	s_cbranch_vccz .LBB0_1874

.LBB0_1889:
	v_cvt_pk_bf16_f32 v90, v30, v31
	v_cvt_pk_bf16_f32 v91, v32, v33
	v_cvt_pk_bf16_f32 v92, v38, v39
	v_cvt_pk_bf16_f32 v93, v40, v41
	ds_write_b128 v78, v[90:93] offset:49664
	v_cvt_pk_bf16_f32 v90, v34, v35
	v_cvt_pk_bf16_f32 v91, v36, v37
	v_cvt_pk_bf16_f32 v92, v42, v43
	v_bfe_u32 v2, v44, 16, 1
	v_add3_u32 v2, v44, v2, s66
	v_bfe_u32 v4, v45, 16, 1
	v_lshrrev_b32_e32 v2, 16, v2
	v_add3_u32 v4, v45, v4, s66
	v_and_or_b32 v93, v4, s67, v2
	ds_write_b128 v78, v[90:93] offset:50688

.LBB0_1915:
	v_cvt_pk_bf16_f32 v154, v58, v59
	v_cvt_pk_bf16_f32 v155, v60, v61
	v_cvt_pk_bf16_f32 v156, v62, v63
	v_cvt_pk_bf16_f32 v157, v64, v65
	ds_write_b128 v141, v[154:157]
	v_cvt_pk_bf16_f32 v154, v54, v55
	v_cvt_pk_bf16_f32 v155, v56, v57
	v_cvt_pk_bf16_f32 v156, v74, v75
	v_cvt_pk_bf16_f32 v157, v76, v77
	ds_write_b128 v141, v[154:157] offset:1024
	v_cvt_pk_bf16_f32 v154, v50, v51
	v_cvt_pk_bf16_f32 v155, v52, v53
	v_cvt_pk_bf16_f32 v156, v90, v91
	v_cvt_pk_bf16_f32 v157, v92, v93
	ds_write_b128 v141, v[154:157] offset:2048
	v_cvt_pk_bf16_f32 v154, v66, v67
	v_cvt_pk_bf16_f32 v155, v68, v69
	v_cvt_pk_bf16_f32 v156, v82, v83
	v_cvt_pk_bf16_f32 v157, v84, v85
	ds_write_b128 v141, v[154:157] offset:3072
	v_cvt_pk_bf16_f32 v154, v70, v71
	v_cvt_pk_bf16_f32 v155, v72, v73
	v_cvt_pk_bf16_f32 v156, v86, v87
	v_cvt_pk_bf16_f32 v157, v88, v89
	ds_write_b128 v141, v[154:157] offset:4096
	v_cvt_pk_bf16_f32 v154, v78, v79
	v_cvt_pk_bf16_f32 v155, v80, v81
	v_cvt_pk_bf16_f32 v156, v94, v95
	v_bfe_u32 v2, v96, 16, 1
	v_add3_u32 v2, v96, v2, s66
	v_bfe_u32 v4, v97, 16, 1
	v_lshrrev_b32_e32 v2, 16, v2
	v_add3_u32 v4, v97, v4, s66
	v_and_or_b32 v157, v4, s67, v2
	ds_write_b128 v141, v[154:157] offset:5120

.LBB0_1933:
	ds_read2_b32 v[20:21], v18 offset1:65
	ds_read2_b32 v[22:23], v18 offset0:130 offset1:195
	v_add_u32_e32 v19, 0x400, v18
	ds_read2_b32 v[26:27], v19 offset0:4 offset1:69
	ds_read2_b32 v[28:29], v19 offset0:134 offset1:199
	s_and_b32 s0, s10, 0xffffffc0
	s_waitcnt lgkmcnt(3)
	v_cvt_pk_bf16_f32 v20, v20, v21
	s_waitcnt lgkmcnt(2)
	v_cvt_pk_bf16_f32 v21, v22, v23
	s_waitcnt lgkmcnt(1)
	v_cvt_pk_bf16_f32 v22, v26, v27
	v_add_u32_e32 v24, s0, v15
	v_ashrrev_i32_e32 v25, 31, v24
	s_and_b32 s3, s3, 0x3c0
	s_waitcnt lgkmcnt(0)
	v_bfe_u32 v19, v28, 16, 1
	v_lshlrev_b64 v[24:25], 11, v[24:25]
	v_add3_u32 v19, v28, v19, s9
	v_bfe_u32 v23, v29, 16, 1
	v_lshl_add_u64 v[24:25], s[14:15], 0, v[24:25]
	s_lshl_b32 s0, s3, 1
	v_lshrrev_b32_e32 v19, 16, v19
	v_add3_u32 v23, v29, v23, s9
	v_lshl_add_u64 v[24:25], v[24:25], 0, s[0:1]
	v_and_or_b32 v23, v23, s8, v19
	v_lshl_add_u64 v[24:25], v[24:25], 0, v[10:11]
	global_store_dwordx4 v[24:25], v[20:23], off
	s_waitcnt lgkmcnt(0)
	s_barrier
	s_andn2_b64 vcc, exec, s[4:5]
	s_mov_b32 s3, s19
	s_mov_b32 s10, s17
	s_cbranch_vccz .LBB0_1938

.LBB0_2009:
	v_pk_add_f32 v[28:29], v[28:29], v[32:33]
	v_pk_add_f32 v[30:31], v[30:31], v[34:35]
	v_pk_mul_f32 v[34:35], v[28:29], v[28:29]
	v_pk_mul_f32 v[32:33], v[30:31], v[30:31]
	v_add_f32_e32 v34, v34, v35
	v_add_f32_e32 v32, v32, v34
	v_add_f32_e32 v32, v33, v32
	ds_bpermute_b32 v33, v1, v32
	v_pk_add_f32 v[22:23], v[22:23], v[26:27]
	v_pk_add_f32 v[20:21], v[20:21], v[24:25]
	v_lshlrev_b32_e32 v25, 16, v60
	v_mul_f32_e32 v25, 0xbfb8aa3b, v25
	s_waitcnt lgkmcnt(0)
	v_add_f32_e32 v26, v32, v33
	ds_bpermute_b32 v27, v62, v26
	v_and_b32_e32 v32, 0xffff0000, v60
	v_exp_f32_e32 v25, v25
	v_lshlrev_b32_e32 v33, 16, v61
	v_and_b32_e32 v34, 0xffff0000, v61
	s_waitcnt lgkmcnt(0)
	v_add_f32_e32 v26, v26, v27
	ds_bpermute_b32 v27, v63, v26
	v_add_f32_e32 v25, 1.0, v25
	v_mul_f32_e32 v33, 0xbfb8aa3b, v33
	v_mul_f32_e32 v34, 0xbfb8aa3b, v34
	v_lshlrev_b32_e32 v24, 16, v52
	s_waitcnt lgkmcnt(0)
	v_add_f32_e32 v26, v26, v27
	ds_bpermute_b32 v27, v64, v26
	v_exp_f32_e32 v33, v33
	v_exp_f32_e32 v34, v34
	v_mul_f32_e32 v35, 0xbfb8aa3b, v24
	v_exp_f32_e32 v35, v35
	s_waitcnt lgkmcnt(0)
	v_add_f32_e32 v26, v26, v27
	ds_bpermute_b32 v27, v65, v26
	v_add_f32_e32 v33, 1.0, v33
	v_add_f32_e32 v34, 1.0, v34
	v_and_b32_e32 v52, 0xffff0000, v52
	v_add_f32_e32 v35, 1.0, v35
	s_waitcnt lgkmcnt(0)
	v_add_f32_e32 v27, v26, v27
	ds_bpermute_b32 v60, v66, v27
	v_rcp_f32_e32 v26, v25
	v_mov_b32_e32 v72, v20
	v_mul_f32_e32 v32, 0xbfb8aa3b, v32
	v_exp_f32_e32 v32, v32
	s_waitcnt lgkmcnt(0)
	v_add_f32_e32 v25, v27, v60
	v_fmamk_f32 v25, v25, 0x3b800000, v67
	v_mul_f32_e32 v27, 0x4b800000, v25
	v_cmp_gt_f32_e32 vcc, s3, v25
	v_mul_f32_e32 v60, 0xbfb8aa3b, v52
	v_exp_f32_e32 v61, v60
	v_cndmask_b32_e32 v25, v25, v27, vcc
	v_rsq_f32_e32 v25, v25
	v_rcp_f32_e32 v27, v33
	v_rcp_f32_e32 v33, v34
	v_rcp_f32_e32 v60, v35
	v_mul_f32_e32 v34, 0x45800000, v25
	v_cndmask_b32_e32 v34, v25, v34, vcc
	v_lshlrev_b32_e32 v25, 16, v53
	v_mul_f32_e32 v35, 0xbfb8aa3b, v25
	v_exp_f32_e32 v35, v35
	v_and_b32_e32 v53, 0xffff0000, v53
	v_add_f32_e32 v61, 1.0, v61
	v_rcp_f32_e32 v70, v61
	v_add_f32_e32 v20, 1.0, v35
	v_rcp_f32_e32 v61, v20
	v_mul_f32_e32 v20, 0xbfb8aa3b, v53
	v_exp_f32_e32 v20, v20
	v_add_f32_e32 v32, 1.0, v32
	v_rcp_f32_e32 v32, v32
	v_mov_b32_e32 v73, v22
	v_add_f32_e32 v20, 1.0, v20
	v_rcp_f32_e32 v71, v20
	v_pk_mul_f32 v[26:27], v[72:73], v[26:27]
	v_pk_mul_f32 v[24:25], v[60:61], v[24:25]
	v_mov_b32_e32 v22, v21
	v_pk_mul_f32 v[24:25], v[26:27], v[24:25]
	v_pk_mul_f32 v[20:21], v[22:23], v[32:33]
	v_pk_mul_f32 v[22:23], v[70:71], v[52:53]
	v_lshl_add_u64 v[42:43], v[42:43], 0, s[0:1]
	v_pk_mul_f32 v[20:21], v[20:21], v[22:23]
	v_and_b32_sdwa v23, v24, v68 dst_sel:DWORD dst_unused:UNUSED_PAD src0_sel:WORD_1 src1_sel:DWORD
	v_add3_u32 v23, v24, v23, s10
	v_cvt_pk_bf16_f32 v21, v25, v21
	v_and_b32_sdwa v25, v20, v68 dst_sel:DWORD dst_unused:UNUSED_PAD src0_sel:WORD_1 src1_sel:DWORD
	v_add3_u32 v20, v20, v25, s10
	v_and_b32_e32 v20, 0xffff0000, v20
	v_or_b32_sdwa v20, v20, v23 dst_sel:DWORD dst_unused:UNUSED_PAD src0_sel:DWORD src1_sel:WORD_1
	v_lshl_add_u64 v[22:23], v[50:51], 0, v[36:37]
	v_add_co_u32_e32 v22, vcc, s11, v22
	v_and_b32_e32 v24, 0xffff0000, v40
	s_nop 0
	v_addc_co_u32_e32 v23, vcc, 0, v23, vcc
	global_store_dwordx2 v[22:23], v[20:21], off
	v_lshlrev_b32_e32 v20, 16, v40
	v_mul_f32_e32 v25, 0xbfb8aa3b, v20
	v_exp_f32_e32 v26, v25
	v_mul_f32_e32 v25, 0xbfb8aa3b, v24
	v_exp_f32_e32 v27, v25
	v_lshlrev_b32_e32 v21, 16, v41
	v_and_b32_e32 v25, 0xffff0000, v41
	v_add_f32_e32 v26, 1.0, v26
	v_add_f32_e32 v27, 1.0, v27
	v_rcp_f32_e32 v32, v27
	v_mul_f32_e32 v27, 0xbfb8aa3b, v21
	v_exp_f32_e32 v27, v27
	v_mov_b32_e32 v40, v28
	v_mul_f32_e32 v28, 0xbfb8aa3b, v25
	v_rcp_f32_e32 v26, v26
	v_add_f32_e32 v27, 1.0, v27
	v_rcp_f32_e32 v27, v27
	v_exp_f32_e32 v28, v28
	v_mov_b32_e32 v41, v30
	v_pk_mul_f32 v[40:41], v[40:41], v[34:35] op_sel_hi:[1,0]
	v_pk_mul_f32 v[20:21], v[26:27], v[20:21]
	v_add_f32_e32 v26, 1.0, v28
	v_rcp_f32_e32 v33, v26
	v_mov_b32_e32 v30, v29
	v_pk_mul_f32 v[40:41], v[2:3], v[40:41]
	v_pk_mul_f32 v[26:27], v[30:31], v[34:35] op_sel_hi:[1,0]
	v_pk_mul_f32 v[20:21], v[20:21], v[40:41]
	v_pk_mul_f32 v[26:27], v[38:39], v[26:27]
	v_pk_mul_f32 v[24:25], v[32:33], v[24:25]
	s_waitcnt vmcnt(5)
	v_mov_b64_e32 v[30:31], v[14:15]
	v_pk_mul_f32 v[24:25], v[24:25], v[26:27]
	v_and_b32_sdwa v26, v21, v68 dst_sel:DWORD dst_unused:UNUSED_PAD src0_sel:WORD_1 src1_sel:DWORD
	v_and_b32_sdwa v27, v20, v68 dst_sel:DWORD dst_unused:UNUSED_PAD src0_sel:WORD_1 src1_sel:DWORD
	v_add3_u32 v20, v20, v27, s10
	v_add3_u32 v21, v21, v26, s10
	v_and_b32_sdwa v26, v25, v68 dst_sel:DWORD dst_unused:UNUSED_PAD src0_sel:WORD_1 src1_sel:DWORD
	v_and_b32_sdwa v27, v24, v68 dst_sel:DWORD dst_unused:UNUSED_PAD src0_sel:WORD_1 src1_sel:DWORD
	v_add3_u32 v25, v25, v26, s10
	v_add3_u32 v24, v24, v27, s10
	v_and_b32_e32 v25, 0xffff0000, v25
	v_and_b32_e32 v24, 0xffff0000, v24
	v_or_b32_sdwa v21, v25, v21 dst_sel:DWORD dst_unused:UNUSED_PAD src0_sel:DWORD src1_sel:WORD_1
	v_or_b32_sdwa v20, v24, v20 dst_sel:DWORD dst_unused:UNUSED_PAD src0_sel:DWORD src1_sel:WORD_1
	global_store_dwordx2 v[22:23], v[20:21], off offset:2048
	v_mov_b64_e32 v[22:23], v[6:7]
	v_mov_b64_e32 v[26:27], v[10:11]
	s_waitcnt vmcnt(5)
	v_mov_b64_e32 v[34:35], v[18:19]
	v_lshl_add_u64 v[46:47], v[46:47], 0, s[34:35]
	v_lshl_add_u64 v[48:49], v[48:49], 0, s[34:35]
	v_lshl_add_u64 v[50:51], v[50:51], 0, s[36:37]
	s_andn2_b64 vcc, exec, s[38:39]
	v_mov_b64_e32 v[20:21], v[4:5]
	v_mov_b64_e32 v[24:25], v[8:9]
	v_mov_b64_e32 v[28:29], v[12:13]
	v_mov_b64_e32 v[32:33], v[16:17]
	s_waitcnt vmcnt(4)
	v_mov_b64_e32 v[60:61], v[56:57]
	s_waitcnt vmcnt(3)
	v_mov_b64_e32 v[52:53], v[54:55]
	s_waitcnt vmcnt(2)
	v_mov_b64_e32 v[40:41], v[58:59]
	s_cbranch_vccz .LBB0_2012

.LBB0_2016:
	v_pk_add_f32 v[20:21], v[20:21], v[24:25]
	v_pk_add_f32 v[22:23], v[22:23], v[26:27]
	v_pk_mul_f32 v[26:27], v[20:21], v[20:21]
	v_pk_mul_f32 v[24:25], v[22:23], v[22:23]
	v_add_f32_e32 v26, v26, v27
	v_add_f32_e32 v24, v24, v26
	v_add_f32_e32 v26, v25, v24
	ds_bpermute_b32 v27, v1, v26
	v_pk_add_f32 v[24:25], v[30:31], v[34:35]
	v_and_b32_e32 v34, 0xffff0000, v61
	v_mul_f32_e32 v34, 0xbfb8aa3b, v34
	v_exp_f32_e32 v34, v34
	s_waitcnt lgkmcnt(0)
	v_add_f32_e32 v30, v26, v27
	ds_bpermute_b32 v31, v62, v30
	v_pk_add_f32 v[26:27], v[28:29], v[32:33]
	v_lshlrev_b32_e32 v29, 16, v60
	v_mul_f32_e32 v29, 0xbfb8aa3b, v29
	v_exp_f32_e32 v29, v29
	s_waitcnt lgkmcnt(0)
	v_add_f32_e32 v30, v30, v31
	ds_bpermute_b32 v31, v63, v30
	v_lshlrev_b32_e32 v33, 16, v61
	v_add_f32_e32 v29, 1.0, v29
	v_mul_f32_e32 v33, 0xbfb8aa3b, v33
	v_exp_f32_e32 v33, v33
	s_waitcnt lgkmcnt(0)
	v_add_f32_e32 v30, v30, v31
	ds_bpermute_b32 v31, v64, v30
	v_add_f32_e32 v34, 1.0, v34
	v_add_f32_e32 v33, 1.0, v33
	v_lshlrev_b32_e32 v28, 16, v58
	v_and_b32_e32 v58, 0xffff0000, v58
	s_waitcnt lgkmcnt(0)
	v_add_f32_e32 v30, v30, v31
	ds_bpermute_b32 v31, v65, v30
	v_and_b32_e32 v32, 0xffff0000, v60
	v_mul_f32_e32 v60, 0xbfb8aa3b, v58
	v_exp_f32_e32 v61, v60
	v_mov_b32_e32 v72, v26
	s_waitcnt lgkmcnt(0)
	v_add_f32_e32 v31, v30, v31
	ds_bpermute_b32 v35, v66, v31
	v_rcp_f32_e32 v30, v29
	v_add_f32_e32 v61, 1.0, v61
	v_mul_f32_e32 v32, 0xbfb8aa3b, v32
	v_rcp_f32_e32 v70, v61
	s_waitcnt lgkmcnt(0)
	v_add_f32_e32 v29, v31, v35
	v_fmamk_f32 v29, v29, 0x3b800000, v67
	v_mul_f32_e32 v31, 0x4b800000, v29
	v_cmp_gt_f32_e32 vcc, s1, v29
	v_exp_f32_e32 v32, v32
	v_mov_b32_e32 v73, v24
	v_cndmask_b32_e32 v29, v29, v31, vcc
	v_rsq_f32_e32 v29, v29
	v_rcp_f32_e32 v31, v33
	v_rcp_f32_e32 v33, v34
	v_add_f32_e32 v32, 1.0, v32
	v_mul_f32_e32 v34, 0x45800000, v29
	v_cndmask_b32_e32 v34, v29, v34, vcc
	v_mul_f32_e32 v29, 0xbfb8aa3b, v28
	v_exp_f32_e32 v35, v29
	v_lshlrev_b32_e32 v29, 16, v59
	v_and_b32_e32 v59, 0xffff0000, v59
	v_rcp_f32_e32 v32, v32
	v_add_f32_e32 v35, 1.0, v35
	v_rcp_f32_e32 v60, v35
	v_mul_f32_e32 v35, 0xbfb8aa3b, v29
	v_exp_f32_e32 v35, v35
	v_pk_mul_f32 v[30:31], v[72:73], v[30:31]
	s_addk_i32 s0, 0x88
	v_lshl_add_u64 v[42:43], v[42:43], 0, s[34:35]
	v_add_f32_e32 v26, 1.0, v35
	v_rcp_f32_e32 v61, v26
	v_mul_f32_e32 v26, 0xbfb8aa3b, v59
	v_exp_f32_e32 v26, v26
	v_lshl_add_u64 v[46:47], v[46:47], 0, s[36:37]
	v_pk_mul_f32 v[28:29], v[60:61], v[28:29]
	v_lshl_add_u64 v[48:49], v[48:49], 0, s[36:37]
	v_add_f32_e32 v24, 1.0, v26
	v_rcp_f32_e32 v71, v24
	v_mov_b32_e32 v24, v27
	v_pk_mul_f32 v[28:29], v[30:31], v[28:29]
	v_pk_mul_f32 v[24:25], v[24:25], v[32:33]
	v_pk_mul_f32 v[26:27], v[70:71], v[58:59]
	s_waitcnt vmcnt(2)
	v_mov_b64_e32 v[60:61], v[54:55]
	v_pk_mul_f32 v[24:25], v[24:25], v[26:27]
	v_and_b32_sdwa v27, v28, v68 dst_sel:DWORD dst_unused:UNUSED_PAD src0_sel:WORD_1 src1_sel:DWORD
	v_add3_u32 v27, v28, v27, s3
	v_cvt_pk_bf16_f32 v25, v29, v25
	v_and_b32_sdwa v29, v24, v68 dst_sel:DWORD dst_unused:UNUSED_PAD src0_sel:WORD_1 src1_sel:DWORD
	v_add3_u32 v24, v24, v29, s3
	v_and_b32_e32 v24, 0xffff0000, v24
	v_or_b32_sdwa v24, v24, v27 dst_sel:DWORD dst_unused:UNUSED_PAD src0_sel:DWORD src1_sel:WORD_1
	v_lshl_add_u64 v[26:27], v[50:51], 0, v[36:37]
	v_add_co_u32_e32 v26, vcc, s10, v26
	v_and_b32_e32 v28, 0xffff0000, v40
	s_nop 0
	v_addc_co_u32_e32 v27, vcc, 0, v27, vcc
	global_store_dwordx2 v[26:27], v[24:25], off
	v_lshlrev_b32_e32 v24, 16, v40
	v_mul_f32_e32 v29, 0xbfb8aa3b, v24
	v_exp_f32_e32 v30, v29
	v_mul_f32_e32 v29, 0xbfb8aa3b, v28
	v_exp_f32_e32 v31, v29
	v_lshlrev_b32_e32 v25, 16, v41
	v_and_b32_e32 v29, 0xffff0000, v41
	v_mov_b32_e32 v40, v20
	v_add_f32_e32 v31, 1.0, v31
	v_rcp_f32_e32 v32, v31
	v_mul_f32_e32 v31, 0xbfb8aa3b, v25
	v_exp_f32_e32 v31, v31
	v_add_f32_e32 v30, 1.0, v30
	v_rcp_f32_e32 v30, v30
	v_mov_b32_e32 v41, v22
	v_add_f32_e32 v20, 1.0, v31
	v_rcp_f32_e32 v31, v20
	v_mul_f32_e32 v20, 0xbfb8aa3b, v29
	v_exp_f32_e32 v20, v20
	v_pk_mul_f32 v[40:41], v[40:41], v[34:35] op_sel_hi:[1,0]
	v_mov_b32_e32 v22, v21
	v_pk_mul_f32 v[40:41], v[2:3], v[40:41]
	v_add_f32_e32 v20, 1.0, v20
	v_rcp_f32_e32 v33, v20
	v_pk_mul_f32 v[24:25], v[30:31], v[24:25]
	v_pk_mul_f32 v[20:21], v[22:23], v[34:35] op_sel_hi:[1,0]
	v_pk_mul_f32 v[24:25], v[24:25], v[40:41]
	v_pk_mul_f32 v[20:21], v[38:39], v[20:21]
	v_pk_mul_f32 v[22:23], v[32:33], v[28:29]
	v_mov_b64_e32 v[30:31], v[6:7]
	v_pk_mul_f32 v[20:21], v[22:23], v[20:21]
	v_and_b32_sdwa v23, v24, v68 dst_sel:DWORD dst_unused:UNUSED_PAD src0_sel:WORD_1 src1_sel:DWORD
	v_add3_u32 v23, v24, v23, s3
	v_cvt_pk_bf16_f32 v21, v25, v21
	v_and_b32_sdwa v25, v20, v68 dst_sel:DWORD dst_unused:UNUSED_PAD src0_sel:WORD_1 src1_sel:DWORD
	v_add3_u32 v20, v20, v25, s3
	v_and_b32_e32 v20, 0xffff0000, v20
	v_or_b32_sdwa v20, v20, v23 dst_sel:DWORD dst_unused:UNUSED_PAD src0_sel:DWORD src1_sel:WORD_1
	global_store_dwordx2 v[26:27], v[20:21], off offset:2048
	v_mov_b64_e32 v[34:35], v[10:11]
	v_mov_b64_e32 v[22:23], v[14:15]
	v_mov_b64_e32 v[26:27], v[18:19]
	v_lshl_add_u64 v[50:51], v[50:51], 0, s[38:39]
	s_and_b64 vcc, exec, s[40:41]
	v_mov_b64_e32 v[28:29], v[4:5]
	v_mov_b64_e32 v[32:33], v[8:9]
	v_mov_b64_e32 v[20:21], v[12:13]
	v_mov_b64_e32 v[24:25], v[16:17]
	s_waitcnt vmcnt(3)
	v_mov_b64_e32 v[58:59], v[52:53]
	s_waitcnt vmcnt(2)
	v_mov_b64_e32 v[40:41], v[56:57]
	s_cbranch_vccnz .LBB0_2019

.LBB0_2023:
	v_pk_add_f32 v[20:21], v[20:21], v[24:25]
	v_pk_add_f32 v[22:23], v[22:23], v[26:27]
	v_pk_mul_f32 v[26:27], v[20:21], v[20:21]
	v_pk_mul_f32 v[24:25], v[22:23], v[22:23]
	v_add_f32_e32 v26, v26, v27
	v_add_f32_e32 v24, v24, v26
	v_add_f32_e32 v26, v25, v24
	ds_bpermute_b32 v27, v1, v26
	v_pk_add_f32 v[24:25], v[30:31], v[34:35]
	v_and_b32_e32 v34, 0xffff0000, v61
	v_mul_f32_e32 v34, 0xbfb8aa3b, v34
	v_exp_f32_e32 v34, v34
	s_waitcnt lgkmcnt(0)
	v_add_f32_e32 v30, v26, v27
	ds_bpermute_b32 v31, v62, v30
	v_pk_add_f32 v[26:27], v[28:29], v[32:33]
	v_lshlrev_b32_e32 v29, 16, v60
	v_mul_f32_e32 v29, 0xbfb8aa3b, v29
	v_and_b32_e32 v32, 0xffff0000, v60
	s_waitcnt lgkmcnt(0)
	v_add_f32_e32 v30, v30, v31
	ds_bpermute_b32 v31, v63, v30
	v_exp_f32_e32 v29, v29
	v_lshlrev_b32_e32 v33, 16, v61
	v_mul_f32_e32 v33, 0xbfb8aa3b, v33
	v_lshlrev_b32_e32 v28, 16, v58
	s_waitcnt lgkmcnt(0)
	v_add_f32_e32 v30, v30, v31
	ds_bpermute_b32 v31, v64, v30
	v_add_f32_e32 v29, 1.0, v29
	v_exp_f32_e32 v33, v33
	v_mul_f32_e32 v35, 0xbfb8aa3b, v28
	v_exp_f32_e32 v35, v35
	s_waitcnt lgkmcnt(0)
	v_add_f32_e32 v30, v30, v31
	ds_bpermute_b32 v31, v65, v30
	v_add_f32_e32 v33, 1.0, v33
	v_add_f32_e32 v34, 1.0, v34
	v_and_b32_e32 v58, 0xffff0000, v58
	v_add_f32_e32 v35, 1.0, v35
	s_waitcnt lgkmcnt(0)
	v_add_f32_e32 v31, v30, v31
	ds_bpermute_b32 v60, v66, v31
	v_rcp_f32_e32 v30, v29
	v_mov_b32_e32 v72, v26
	v_mul_f32_e32 v32, 0xbfb8aa3b, v32
	v_exp_f32_e32 v32, v32
	s_waitcnt lgkmcnt(0)
	v_add_f32_e32 v29, v31, v60
	v_fmamk_f32 v29, v29, 0x3b800000, v67
	v_mul_f32_e32 v31, 0x4b800000, v29
	v_cmp_gt_f32_e32 vcc, s1, v29
	v_mul_f32_e32 v60, 0xbfb8aa3b, v58
	v_exp_f32_e32 v61, v60
	v_cndmask_b32_e32 v29, v29, v31, vcc
	v_rsq_f32_e32 v29, v29
	v_rcp_f32_e32 v31, v33
	v_rcp_f32_e32 v33, v34
	v_rcp_f32_e32 v60, v35
	v_mul_f32_e32 v34, 0x45800000, v29
	v_cndmask_b32_e32 v34, v29, v34, vcc
	v_lshlrev_b32_e32 v29, 16, v59
	v_mul_f32_e32 v35, 0xbfb8aa3b, v29
	v_exp_f32_e32 v35, v35
	v_and_b32_e32 v59, 0xffff0000, v59
	v_add_f32_e32 v61, 1.0, v61
	v_rcp_f32_e32 v70, v61
	v_add_f32_e32 v26, 1.0, v35
	v_rcp_f32_e32 v61, v26
	v_mul_f32_e32 v26, 0xbfb8aa3b, v59
	v_exp_f32_e32 v26, v26
	v_add_f32_e32 v32, 1.0, v32
	v_mov_b32_e32 v73, v24
	v_rcp_f32_e32 v32, v32
	v_add_f32_e32 v24, 1.0, v26
	v_rcp_f32_e32 v71, v24
	v_pk_mul_f32 v[30:31], v[72:73], v[30:31]
	v_pk_mul_f32 v[28:29], v[60:61], v[28:29]
	v_mov_b32_e32 v24, v27
	v_pk_mul_f32 v[28:29], v[30:31], v[28:29]
	v_pk_mul_f32 v[24:25], v[24:25], v[32:33]
	v_pk_mul_f32 v[26:27], v[70:71], v[58:59]
	s_add_i32 s0, s0, s34
	v_pk_mul_f32 v[24:25], v[24:25], v[26:27]
	v_and_b32_sdwa v27, v28, v68 dst_sel:DWORD dst_unused:UNUSED_PAD src0_sel:WORD_1 src1_sel:DWORD
	v_add3_u32 v27, v28, v27, s10
	v_cvt_pk_bf16_f32 v25, v29, v25
	v_and_b32_sdwa v29, v24, v68 dst_sel:DWORD dst_unused:UNUSED_PAD src0_sel:WORD_1 src1_sel:DWORD
	v_add3_u32 v24, v24, v29, s10
	v_and_b32_e32 v24, 0xffff0000, v24
	v_or_b32_sdwa v24, v24, v27 dst_sel:DWORD dst_unused:UNUSED_PAD src0_sel:DWORD src1_sel:WORD_1
	v_lshl_add_u64 v[26:27], v[50:51], 0, v[36:37]
	v_add_co_u32_e32 v26, vcc, s11, v26
	v_and_b32_e32 v28, 0xffff0000, v44
	s_nop 0
	v_addc_co_u32_e32 v27, vcc, 0, v27, vcc
	global_store_dwordx2 v[26:27], v[24:25], off
	v_lshlrev_b32_e32 v24, 16, v44
	v_mul_f32_e32 v29, 0xbfb8aa3b, v24
	v_exp_f32_e32 v30, v29
	v_mul_f32_e32 v29, 0xbfb8aa3b, v28
	v_exp_f32_e32 v31, v29
	v_lshlrev_b32_e32 v25, 16, v45
	v_and_b32_e32 v29, 0xffff0000, v45
	v_mov_b32_e32 v44, v20
	v_add_f32_e32 v31, 1.0, v31
	v_rcp_f32_e32 v32, v31
	v_mul_f32_e32 v31, 0xbfb8aa3b, v25
	v_exp_f32_e32 v31, v31
	v_add_f32_e32 v30, 1.0, v30
	v_rcp_f32_e32 v30, v30
	v_mov_b32_e32 v45, v22
	v_add_f32_e32 v20, 1.0, v31
	v_rcp_f32_e32 v31, v20
	v_mul_f32_e32 v20, 0xbfb8aa3b, v29
	v_exp_f32_e32 v20, v20
	v_pk_mul_f32 v[44:45], v[44:45], v[34:35] op_sel_hi:[1,0]
	v_mov_b32_e32 v22, v21
	v_pk_mul_f32 v[44:45], v[2:3], v[44:45]
	v_add_f32_e32 v20, 1.0, v20
	v_rcp_f32_e32 v33, v20
	v_pk_mul_f32 v[24:25], v[30:31], v[24:25]
	v_pk_mul_f32 v[20:21], v[22:23], v[34:35] op_sel_hi:[1,0]
	v_pk_mul_f32 v[24:25], v[24:25], v[44:45]
	v_pk_mul_f32 v[20:21], v[38:39], v[20:21]
	v_pk_mul_f32 v[22:23], v[32:33], v[28:29]
	s_waitcnt vmcnt(7)
	v_mov_b64_e32 v[30:31], v[6:7]
	v_pk_mul_f32 v[20:21], v[22:23], v[20:21]
	v_and_b32_sdwa v23, v24, v68 dst_sel:DWORD dst_unused:UNUSED_PAD src0_sel:WORD_1 src1_sel:DWORD
	v_add3_u32 v23, v24, v23, s10
	v_cvt_pk_bf16_f32 v21, v25, v21
	v_and_b32_sdwa v25, v20, v68 dst_sel:DWORD dst_unused:UNUSED_PAD src0_sel:WORD_1 src1_sel:DWORD
	v_add3_u32 v20, v20, v25, s10
	v_and_b32_e32 v20, 0xffff0000, v20
	v_or_b32_sdwa v20, v20, v23 dst_sel:DWORD dst_unused:UNUSED_PAD src0_sel:DWORD src1_sel:WORD_1
	global_store_dwordx2 v[26:27], v[20:21], off offset:2048
	s_waitcnt vmcnt(7)
	v_mov_b64_e32 v[34:35], v[10:11]
	s_waitcnt vmcnt(6)
	v_mov_b64_e32 v[22:23], v[14:15]
	s_waitcnt vmcnt(5)
	v_mov_b64_e32 v[26:27], v[18:19]
	v_lshl_add_u64 v[40:41], v[40:41], 0, s[4:5]
	v_lshl_add_u64 v[46:47], v[46:47], 0, s[18:19]
	v_lshl_add_u64 v[48:49], v[48:49], 0, s[18:19]
	v_lshl_add_u64 v[50:51], v[50:51], 0, s[16:17]
	s_cmp_ge_i32 s0, s3
	v_mov_b64_e32 v[28:29], v[4:5]
	v_mov_b64_e32 v[32:33], v[8:9]
	v_mov_b64_e32 v[20:21], v[12:13]
	v_mov_b64_e32 v[24:25], v[16:17]
	s_waitcnt vmcnt(4)
	v_mov_b64_e32 v[60:61], v[54:55]
	s_waitcnt vmcnt(3)
	v_mov_b64_e32 v[58:59], v[52:53]
	s_waitcnt vmcnt(2)
	v_mov_b64_e32 v[44:45], v[56:57]
	s_cbranch_scc1 .LBB0_2026

.LBB0_2289:
	ds_read2_b32 v[52:53], v89 offset1:65
	ds_read2_b32 v[78:79], v89 offset0:130 offset1:195
	s_mul_hi_i32 s6, s51, 0x8fb823ef
	s_add_i32 s6, s6, s51
	s_lshr_b32 s7, s6, 31
	s_waitcnt lgkmcnt(1)
	v_cvt_pk_bf16_f32 v106, v52, v53
	s_waitcnt lgkmcnt(0)
	v_cvt_pk_bf16_f32 v107, v78, v79
	ds_read2_b32 v[52:53], v102 offset0:4 offset1:69
	ds_read2_b32 v[78:79], v102 offset0:134 offset1:199
	s_waitcnt lgkmcnt(1)
	v_cvt_pk_bf16_f32 v108, v52, v53
	s_ashr_i32 s6, s6, 7
	s_add_i32 s6, s6, s7
	s_waitcnt lgkmcnt(0)
	v_cvt_pk_bf16_f32 v109, v78, v79
	s_mul_i32 s7, s6, 0xe4
	s_sub_i32 s7, s51, s7
	v_lshl_or_b32 v52, s7, 6, v88
	v_ashrrev_i32_e32 v53, 31, v52
	s_lshl_b32 s6, s6, 8
	v_lshlrev_b64 v[52:53], 13, v[52:53]
	v_lshl_add_u64 v[52:53], s[20:21], 0, v[52:53]
	ds_read2_b32 v[78:79], v90 offset1:65
	s_ashr_i32 s7, s6, 31
	v_lshl_add_u64 v[52:53], s[6:7], 1, v[52:53]
	v_lshl_add_u64 v[110:111], v[70:71], 1, v[52:53]
	global_store_dwordx4 v[110:111], v[106:109], off
	ds_read2_b32 v[108:109], v90 offset0:130 offset1:195
	s_waitcnt lgkmcnt(1)
	v_cvt_pk_bf16_f32 v106, v78, v79
	s_waitcnt lgkmcnt(0)
	ds_read2_b32 v[78:79], v103 offset0:4 offset1:69
	v_cvt_pk_bf16_f32 v107, v108, v109
	ds_read2_b32 v[102:103], v103 offset0:134 offset1:199
	s_waitcnt lgkmcnt(1)
	v_cvt_pk_bf16_f32 v108, v78, v79
	s_waitcnt lgkmcnt(0)
	ds_read2_b32 v[78:79], v91 offset1:65
	v_cvt_pk_bf16_f32 v109, v102, v103
	v_lshl_add_u64 v[102:103], v[72:73], 1, v[52:53]
	global_store_dwordx4 v[102:103], v[106:109], off
	ds_read2_b32 v[102:103], v91 offset0:130 offset1:195
	s_waitcnt lgkmcnt(1)
	v_cvt_pk_bf16_f32 v106, v78, v79
	ds_read2_b32 v[78:79], v104 offset0:4 offset1:69
	s_waitcnt lgkmcnt(1)
	v_cvt_pk_bf16_f32 v107, v102, v103
	ds_read2_b32 v[102:103], v104 offset0:134 offset1:199
	s_waitcnt lgkmcnt(1)
	v_cvt_pk_bf16_f32 v108, v78, v79
	ds_read2_b32 v[78:79], v92 offset1:65
	s_waitcnt lgkmcnt(1)
	v_cvt_pk_bf16_f32 v109, v102, v103
	v_lshl_add_u64 v[102:103], v[74:75], 1, v[52:53]
	global_store_dwordx4 v[102:103], v[106:109], off
	s_waitcnt lgkmcnt(0)
	v_cvt_pk_bf16_f32 v102, v78, v79
	ds_read2_b32 v[106:107], v92 offset0:130 offset1:195
	ds_read2_b32 v[78:79], v105 offset0:4 offset1:69
	s_waitcnt lgkmcnt(1)
	v_cvt_pk_bf16_f32 v103, v106, v107
	ds_read2_b32 v[106:107], v105 offset0:134 offset1:199
	s_waitcnt lgkmcnt(1)
	v_cvt_pk_bf16_f32 v104, v78, v79
	s_waitcnt lgkmcnt(0)
	v_bfe_u32 v51, v106, 16, 1
	v_add3_u32 v51, v106, v51, s47
	v_bfe_u32 v78, v107, 16, 1
	v_lshrrev_b32_e32 v51, 16, v51
	v_add3_u32 v78, v107, v78, s47
	v_and_or_b32 v105, v78, s48, v51
	v_lshl_add_u64 v[52:53], v[76:77], 1, v[52:53]
	global_store_dwordx4 v[52:53], v[102:105], off
	s_waitcnt lgkmcnt(0)
	s_barrier

.LBB0_2382:
	ds_read2_b32 v[52:53], v89 offset1:65
	ds_read2_b32 v[78:79], v89 offset0:130 offset1:195
	v_add_u32_e32 v102, 0x400, v89
	s_mul_hi_i32 s6, s50, 0x8fb823ef
	s_add_i32 s6, s6, s50
	s_waitcnt lgkmcnt(1)
	v_cvt_pk_bf16_f32 v104, v52, v53
	s_waitcnt lgkmcnt(0)
	v_cvt_pk_bf16_f32 v105, v78, v79
	ds_read2_b32 v[52:53], v102 offset0:4 offset1:69
	ds_read2_b32 v[78:79], v102 offset0:134 offset1:199
	s_waitcnt lgkmcnt(1)
	v_cvt_pk_bf16_f32 v106, v52, v53
	s_lshr_b32 s7, s6, 31
	s_ashr_i32 s6, s6, 7
	s_add_i32 s7, s6, s7
	s_waitcnt lgkmcnt(0)
	v_cvt_pk_bf16_f32 v107, v78, v79
	s_lshl_b32 s6, s7, 8
	s_mulk_i32 s7, 0xc700
	s_add_i32 s7, s7, s38
	v_add_u32_e32 v52, s7, v88
	v_ashrrev_i32_e32 v53, 31, v52
	ds_read2_b32 v[78:79], v90 offset1:65
	v_lshlrev_b64 v[52:53], 13, v[52:53]
	v_lshl_add_u64 v[52:53], s[20:21], 0, v[52:53]
	s_ashr_i32 s7, s6, 31
	v_lshl_add_u64 v[52:53], s[6:7], 1, v[52:53]
	v_lshl_add_u64 v[108:109], v[70:71], 1, v[52:53]
	global_store_dwordx4 v[108:109], v[104:107], off
	s_waitcnt lgkmcnt(0)
	s_nop 0
	ds_read2_b32 v[106:107], v90 offset0:130 offset1:195
	v_cvt_pk_bf16_f32 v104, v78, v79
	v_add_u32_e32 v103, 0x400, v90
	ds_read2_b32 v[78:79], v103 offset0:4 offset1:69
	s_waitcnt lgkmcnt(1)
	v_cvt_pk_bf16_f32 v105, v106, v107
	ds_read2_b32 v[108:109], v103 offset0:134 offset1:199
	s_waitcnt lgkmcnt(1)
	v_cvt_pk_bf16_f32 v106, v78, v79
	s_waitcnt lgkmcnt(0)
	v_cvt_pk_bf16_f32 v107, v108, v109
	ds_read2_b32 v[78:79], v91 offset1:65
	v_lshl_add_u64 v[108:109], v[72:73], 1, v[52:53]
	global_store_dwordx4 v[108:109], v[104:107], off
	ds_read2_b32 v[104:105], v91 offset0:130 offset1:195
	s_waitcnt lgkmcnt(1)
	v_cvt_pk_bf16_f32 v106, v78, v79
	s_waitcnt lgkmcnt(0)
	v_cvt_pk_bf16_f32 v107, v104, v105
	v_add_u32_e32 v104, 0x400, v91
	ds_read2_b32 v[78:79], v104 offset0:4 offset1:69
	ds_read2_b32 v[110:111], v104 offset0:134 offset1:199
	s_waitcnt lgkmcnt(1)
	v_cvt_pk_bf16_f32 v108, v78, v79
	ds_read2_b32 v[78:79], v92 offset1:65
	s_waitcnt lgkmcnt(1)
	v_cvt_pk_bf16_f32 v109, v110, v111
	v_lshl_add_u64 v[110:111], v[74:75], 1, v[52:53]
	global_store_dwordx4 v[110:111], v[106:109], off
	s_waitcnt lgkmcnt(0)
	v_cvt_pk_bf16_f32 v106, v78, v79
	ds_read2_b32 v[108:109], v92 offset0:130 offset1:195
	v_add_u32_e32 v105, 0x400, v92
	ds_read2_b32 v[78:79], v105 offset0:4 offset1:69
	s_waitcnt lgkmcnt(1)
	v_cvt_pk_bf16_f32 v107, v108, v109
	ds_read2_b32 v[110:111], v105 offset0:134 offset1:199
	s_waitcnt lgkmcnt(1)
	v_cvt_pk_bf16_f32 v108, v78, v79
	s_waitcnt lgkmcnt(0)
	v_bfe_u32 v51, v110, 16, 1
	v_add3_u32 v51, v110, v51, s47
	v_bfe_u32 v78, v111, 16, 1
	v_lshrrev_b32_e32 v51, 16, v51
	v_add3_u32 v78, v111, v78, s47
	v_and_or_b32 v109, v78, s48, v51
	v_lshl_add_u64 v[52:53], v[76:77], 1, v[52:53]
	global_store_dwordx4 v[52:53], v[106:109], off
	s_waitcnt lgkmcnt(0)
	s_barrier
	s_add_i32 s51, s24, s50
	s_cmpk_gt_i32 s51, 0xe3f
	s_cbranch_scc1 .LBB0_2290
	ds_write2_b32 v94, v22, v23 offset1:1
	ds_write2_b32 v94, v24, v25 offset0:2 offset1:3
	ds_write2_b32 v95, v30, v31 offset1:1
	ds_write2_b32 v95, v32, v33 offset0:2 offset1:3
	ds_write2_b32 v96, v38, v39 offset1:1
	ds_write2_b32 v96, v40, v41 offset0:2 offset1:3
	ds_write2_b32 v97, v46, v47 offset1:1
	ds_write2_b32 v97, v48, v49 offset0:2 offset1:3
	ds_write2_b32 v98, v54, v55 offset1:1
	ds_write2_b32 v98, v56, v57 offset0:2 offset1:3
	ds_write2_b32 v99, v58, v59 offset1:1
	ds_write2_b32 v99, v60, v61 offset0:2 offset1:3
	ds_write2_b32 v100, v62, v63 offset1:1
	ds_write2_b32 v100, v64, v65 offset0:2 offset1:3
	ds_write2_b32 v101, v66, v67 offset1:1
	ds_write2_b32 v101, v68, v69 offset0:2 offset1:3
	s_waitcnt lgkmcnt(0)
	s_barrier
	s_add_i32 s6, s40, s50
	s_cmpk_gt_i32 s6, 0xe3f
	s_cbranch_scc1 .LBB0_2289
	s_mul_hi_i32 s7, s6, 0x8fb823ef
	s_add_i32 s7, s7, s6
	s_lshr_b32 s28, s7, 31
	s_ashr_i32 s7, s7, 7
	s_add_i32 s28, s7, s28
	s_mul_i32 s7, s28, 0xe4
	s_sub_i32 s6, s6, s7
	s_lshl_b32 s50, s6, 6
	v_or_b32_e32 v78, s50, v1
	v_cmp_lt_i32_e64 s[6:7], s41, v78
	v_mov_b32_e32 v30, v78
	s_and_saveexec_b64 s[34:35], s[6:7]
	s_cbranch_execz .LBB0_2393
	s_cmpk_gt_u32 s50, 0x37ff
	s_mov_b64 s[36:37], -1
	s_cbranch_scc0 .LBB0_2391
	v_cmp_lt_u32_e32 vcc, s44, v78
	s_and_saveexec_b64 s[36:37], vcc
	s_xor_b64 s[36:37], exec, s[36:37]
	v_cmp_gt_u32_e32 vcc, s45, v78
	s_nop 1
	v_cndmask_b32_e32 v30, -1, v78, vcc
	s_andn2_saveexec_b64 s[36:37], s[36:37]
	v_add_u32_e32 v30, 0xfffff400, v78
	s_or_b64 exec, exec, s[36:37]
	s_mov_b64 s[36:37], 0

.LBB0_2704:
	ds_read2_b32 v[52:53], v89 offset1:65
	ds_read2_b32 v[78:79], v89 offset0:130 offset1:195
	s_mul_hi_i32 s4, s30, 0x8fb823ef
	s_add_i32 s4, s4, s30
	s_lshr_b32 s5, s4, 31
	s_waitcnt lgkmcnt(1)
	v_cvt_pk_bf16_f32 v106, v52, v53
	s_waitcnt lgkmcnt(0)
	v_cvt_pk_bf16_f32 v107, v78, v79
	ds_read2_b32 v[52:53], v102 offset0:4 offset1:69
	ds_read2_b32 v[78:79], v102 offset0:134 offset1:199
	s_waitcnt lgkmcnt(1)
	v_cvt_pk_bf16_f32 v108, v52, v53
	s_ashr_i32 s4, s4, 7
	s_add_i32 s4, s4, s5
	s_waitcnt lgkmcnt(0)
	v_cvt_pk_bf16_f32 v109, v78, v79
	s_mul_i32 s5, s4, 0xe4
	s_sub_i32 s5, s30, s5
	v_lshl_or_b32 v52, s5, 6, v88
	v_ashrrev_i32_e32 v53, 31, v52
	s_lshl_b32 s4, s4, 8
	v_lshlrev_b64 v[52:53], 13, v[52:53]
	v_lshl_add_u64 v[52:53], s[6:7], 0, v[52:53]
	ds_read2_b32 v[78:79], v90 offset1:65
	s_ashr_i32 s5, s4, 31
	v_lshl_add_u64 v[52:53], s[4:5], 1, v[52:53]
	v_lshl_add_u64 v[110:111], v[70:71], 1, v[52:53]
	global_store_dwordx4 v[110:111], v[106:109], off
	ds_read2_b32 v[108:109], v90 offset0:130 offset1:195
	s_waitcnt lgkmcnt(1)
	v_cvt_pk_bf16_f32 v106, v78, v79
	s_waitcnt lgkmcnt(0)
	ds_read2_b32 v[78:79], v103 offset0:4 offset1:69
	v_cvt_pk_bf16_f32 v107, v108, v109
	ds_read2_b32 v[102:103], v103 offset0:134 offset1:199
	s_waitcnt lgkmcnt(1)
	v_cvt_pk_bf16_f32 v108, v78, v79
	s_waitcnt lgkmcnt(0)
	ds_read2_b32 v[78:79], v91 offset1:65
	v_cvt_pk_bf16_f32 v109, v102, v103
	v_lshl_add_u64 v[102:103], v[72:73], 1, v[52:53]
	global_store_dwordx4 v[102:103], v[106:109], off
	ds_read2_b32 v[102:103], v91 offset0:130 offset1:195
	s_waitcnt lgkmcnt(1)
	v_cvt_pk_bf16_f32 v106, v78, v79
	ds_read2_b32 v[78:79], v104 offset0:4 offset1:69
	s_waitcnt lgkmcnt(1)
	v_cvt_pk_bf16_f32 v107, v102, v103
	ds_read2_b32 v[102:103], v104 offset0:134 offset1:199
	s_waitcnt lgkmcnt(1)
	v_cvt_pk_bf16_f32 v108, v78, v79
	ds_read2_b32 v[78:79], v92 offset1:65
	s_waitcnt lgkmcnt(1)
	v_cvt_pk_bf16_f32 v109, v102, v103
	v_lshl_add_u64 v[102:103], v[74:75], 1, v[52:53]
	global_store_dwordx4 v[102:103], v[106:109], off
	s_waitcnt lgkmcnt(0)
	v_cvt_pk_bf16_f32 v102, v78, v79
	ds_read2_b32 v[106:107], v92 offset0:130 offset1:195
	ds_read2_b32 v[78:79], v105 offset0:4 offset1:69
	s_waitcnt lgkmcnt(1)
	v_cvt_pk_bf16_f32 v103, v106, v107
	ds_read2_b32 v[106:107], v105 offset0:134 offset1:199
	s_waitcnt lgkmcnt(1)
	v_cvt_pk_bf16_f32 v104, v78, v79
	s_waitcnt lgkmcnt(0)
	v_bfe_u32 v51, v106, 16, 1
	v_add3_u32 v51, v106, v51, s23
	v_bfe_u32 v78, v107, 16, 1
	v_lshrrev_b32_e32 v51, 16, v51
	v_add3_u32 v78, v107, v78, s23
	v_and_or_b32 v105, v78, s25, v51
	v_lshl_add_u64 v[52:53], v[76:77], 1, v[52:53]
	global_store_dwordx4 v[52:53], v[102:105], off
	s_waitcnt lgkmcnt(0)
	s_barrier

.LBB0_2797:
	ds_read2_b32 v[52:53], v89 offset1:65
	ds_read2_b32 v[78:79], v89 offset0:130 offset1:195
	v_add_u32_e32 v102, 0x400, v89
	s_mul_hi_i32 s4, s27, 0x8fb823ef
	s_add_i32 s4, s4, s27
	s_waitcnt lgkmcnt(1)
	v_cvt_pk_bf16_f32 v104, v52, v53
	s_waitcnt lgkmcnt(0)
	v_cvt_pk_bf16_f32 v105, v78, v79
	ds_read2_b32 v[52:53], v102 offset0:4 offset1:69
	ds_read2_b32 v[78:79], v102 offset0:134 offset1:199
	s_waitcnt lgkmcnt(1)
	v_cvt_pk_bf16_f32 v106, v52, v53
	s_lshr_b32 s5, s4, 31
	s_ashr_i32 s4, s4, 7
	s_add_i32 s5, s4, s5
	s_waitcnt lgkmcnt(0)
	v_cvt_pk_bf16_f32 v107, v78, v79
	s_lshl_b32 s4, s5, 8
	s_mulk_i32 s5, 0xc700
	s_add_i32 s5, s5, s10
	v_add_u32_e32 v52, s5, v88
	v_ashrrev_i32_e32 v53, 31, v52
	ds_read2_b32 v[78:79], v90 offset1:65
	v_lshlrev_b64 v[52:53], 13, v[52:53]
	v_lshl_add_u64 v[52:53], s[6:7], 0, v[52:53]
	s_ashr_i32 s5, s4, 31
	v_lshl_add_u64 v[52:53], s[4:5], 1, v[52:53]
	v_lshl_add_u64 v[108:109], v[70:71], 1, v[52:53]
	global_store_dwordx4 v[108:109], v[104:107], off
	s_waitcnt lgkmcnt(0)
	s_nop 0
	ds_read2_b32 v[106:107], v90 offset0:130 offset1:195
	v_cvt_pk_bf16_f32 v104, v78, v79
	v_add_u32_e32 v103, 0x400, v90
	ds_read2_b32 v[78:79], v103 offset0:4 offset1:69
	s_waitcnt lgkmcnt(1)
	v_cvt_pk_bf16_f32 v105, v106, v107
	ds_read2_b32 v[108:109], v103 offset0:134 offset1:199
	s_waitcnt lgkmcnt(1)
	v_cvt_pk_bf16_f32 v106, v78, v79
	s_waitcnt lgkmcnt(0)
	v_cvt_pk_bf16_f32 v107, v108, v109
	ds_read2_b32 v[78:79], v91 offset1:65
	v_lshl_add_u64 v[108:109], v[72:73], 1, v[52:53]
	global_store_dwordx4 v[108:109], v[104:107], off
	ds_read2_b32 v[104:105], v91 offset0:130 offset1:195
	s_waitcnt lgkmcnt(1)
	v_cvt_pk_bf16_f32 v106, v78, v79
	s_waitcnt lgkmcnt(0)
	v_cvt_pk_bf16_f32 v107, v104, v105
	v_add_u32_e32 v104, 0x400, v91
	ds_read2_b32 v[78:79], v104 offset0:4 offset1:69
	ds_read2_b32 v[110:111], v104 offset0:134 offset1:199
	s_waitcnt lgkmcnt(1)
	v_cvt_pk_bf16_f32 v108, v78, v79
	ds_read2_b32 v[78:79], v92 offset1:65
	s_waitcnt lgkmcnt(1)
	v_cvt_pk_bf16_f32 v109, v110, v111
	v_lshl_add_u64 v[110:111], v[74:75], 1, v[52:53]
	global_store_dwordx4 v[110:111], v[106:109], off
	s_waitcnt lgkmcnt(0)
	v_cvt_pk_bf16_f32 v106, v78, v79
	ds_read2_b32 v[108:109], v92 offset0:130 offset1:195
	v_add_u32_e32 v105, 0x400, v92
	ds_read2_b32 v[78:79], v105 offset0:4 offset1:69
	s_waitcnt lgkmcnt(1)
	v_cvt_pk_bf16_f32 v107, v108, v109
	ds_read2_b32 v[110:111], v105 offset0:134 offset1:199
	s_waitcnt lgkmcnt(1)
	v_cvt_pk_bf16_f32 v108, v78, v79
	s_waitcnt lgkmcnt(0)
	v_bfe_u32 v51, v110, 16, 1
	v_add3_u32 v51, v110, v51, s23
	v_bfe_u32 v78, v111, 16, 1
	v_lshrrev_b32_e32 v51, 16, v51
	v_add3_u32 v78, v111, v78, s23
	v_and_or_b32 v109, v78, s25, v51
	v_lshl_add_u64 v[52:53], v[76:77], 1, v[52:53]
	global_store_dwordx4 v[52:53], v[106:109], off
	s_waitcnt lgkmcnt(0)
	s_barrier
	s_add_i32 s30, s24, s27
	s_cmpk_gt_i32 s30, 0xe3f
	s_cbranch_scc1 .LBB0_2705
	ds_write2_b32 v94, v22, v23 offset1:1
	ds_write2_b32 v94, v24, v25 offset0:2 offset1:3
	ds_write2_b32 v95, v30, v31 offset1:1
	ds_write2_b32 v95, v32, v33 offset0:2 offset1:3
	ds_write2_b32 v96, v38, v39 offset1:1
	ds_write2_b32 v96, v40, v41 offset0:2 offset1:3
	ds_write2_b32 v97, v46, v47 offset1:1
	ds_write2_b32 v97, v48, v49 offset0:2 offset1:3
	ds_write2_b32 v98, v54, v55 offset1:1
	ds_write2_b32 v98, v56, v57 offset0:2 offset1:3
	ds_write2_b32 v99, v58, v59 offset1:1
	ds_write2_b32 v99, v60, v61 offset0:2 offset1:3
	ds_write2_b32 v100, v62, v63 offset1:1
	ds_write2_b32 v100, v64, v65 offset0:2 offset1:3
	ds_write2_b32 v101, v66, v67 offset1:1
	ds_write2_b32 v101, v68, v69 offset0:2 offset1:3
	s_waitcnt lgkmcnt(0)
	s_barrier
	s_add_i32 s4, s18, s27
	s_cmpk_gt_i32 s4, 0xe3f
	s_cbranch_scc1 .LBB0_2704
	s_mul_hi_i32 s5, s4, 0x8fb823ef
	s_add_i32 s5, s5, s4
	s_lshr_b32 s14, s5, 31
	s_ashr_i32 s28, s5, 7
	s_add_i32 s28, s28, s14
	s_mul_i32 s5, s28, 0xe4
	s_sub_i32 s4, s4, s5
	s_lshl_b32 s27, s4, 6
	v_or_b32_e32 v78, s27, v1
	v_cmp_lt_i32_e64 s[4:5], s19, v78
	v_mov_b32_e32 v30, v78
	s_and_saveexec_b64 s[14:15], s[4:5]
	s_cbranch_execz .LBB0_2808
	s_cmpk_gt_u32 s27, 0x37ff
	s_mov_b64 s[16:17], -1
	s_cbranch_scc0 .LBB0_2806
	v_cmp_lt_u32_e32 vcc, s20, v78
	s_and_saveexec_b64 s[16:17], vcc
	s_xor_b64 s[16:17], exec, s[16:17]
	v_cmp_gt_u32_e32 vcc, s21, v78
	s_nop 1
	v_cndmask_b32_e32 v30, -1, v78, vcc
	s_andn2_saveexec_b64 s[16:17], s[16:17]
	v_add_u32_e32 v30, 0xfffff400, v78
	s_or_b64 exec, exec, s[16:17]
	s_mov_b64 s[16:17], 0

.LBB0_3100:
	s_or_b64 exec, exec, s[50:51]
	v_mov_b32_e32 v16, v6
	v_mov_b32_e32 v17, v2
	v_mov_b32_e32 v2, v7
	v_mov_b32_e32 v6, v8
	v_mov_b32_e32 v7, v4
	v_mov_b32_e32 v4, v9
	v_pk_add_f32 v[2:3], v[16:17], v[2:3]
	v_pk_add_f32 v[4:5], v[6:7], v[4:5]
	v_pk_add_f32 v[6:7], v[24:25], v[40:41]
	v_pk_add_f32 v[2:3], v[2:3], v[4:5]
	v_pk_add_f32 v[4:5], v[14:15], v[32:33] neg_lo:[0,1] neg_hi:[0,1]
	v_add_f32_e32 v10, v2, v3
	v_pk_add_f32 v[2:3], v[14:15], v[32:33]
	v_pk_add_f32 v[8:9], v[24:25], v[40:41] neg_lo:[0,1] neg_hi:[0,1]
	v_pk_add_f32 v[24:25], v[2:3], v[6:7]
	v_pk_add_f32 v[32:33], v[2:3], v[6:7] neg_lo:[0,1] neg_hi:[0,1]
	v_pk_add_f32 v[40:41], v[4:5], v[8:9] op_sel:[0,1] op_sel_hi:[1,0] neg_hi:[0,1]
	s_waitcnt lgkmcnt(1)
	v_pk_add_f32 v[48:49], v[4:5], v[8:9] op_sel:[0,1] op_sel_hi:[1,0] neg_lo:[0,1]
	v_pk_add_f32 v[2:3], v[18:19], v[34:35]
	v_pk_add_f32 v[4:5], v[18:19], v[34:35] neg_lo:[0,1] neg_hi:[0,1]
	v_pk_add_f32 v[6:7], v[26:27], v[42:43]
	v_pk_add_f32 v[8:9], v[26:27], v[42:43] neg_lo:[0,1] neg_hi:[0,1]
	v_pk_add_f32 v[18:19], v[2:3], v[6:7]
	v_pk_add_f32 v[6:7], v[2:3], v[6:7] neg_lo:[0,1] neg_hi:[0,1]
	v_pk_add_f32 v[2:3], v[4:5], v[8:9] op_sel:[0,1] op_sel_hi:[1,0] neg_hi:[0,1]
	v_pk_add_f32 v[16:17], v[4:5], v[8:9] op_sel:[0,1] op_sel_hi:[1,0] neg_lo:[0,1]
	v_pk_add_f32 v[4:5], v[20:21], v[36:37]
	v_pk_add_f32 v[8:9], v[20:21], v[36:37] neg_lo:[0,1] neg_hi:[0,1]
	v_pk_add_f32 v[14:15], v[28:29], v[44:45]
	v_pk_add_f32 v[20:21], v[28:29], v[44:45] neg_lo:[0,1] neg_hi:[0,1]
	v_pk_add_f32 v[26:27], v[4:5], v[14:15]
	v_pk_add_f32 v[28:29], v[4:5], v[14:15] neg_lo:[0,1] neg_hi:[0,1]
	v_pk_add_f32 v[14:15], v[8:9], v[20:21] op_sel:[0,1] op_sel_hi:[1,0] neg_hi:[0,1]
	v_pk_add_f32 v[20:21], v[8:9], v[20:21] op_sel:[0,1] op_sel_hi:[1,0] neg_lo:[0,1]
	v_pk_add_f32 v[4:5], v[22:23], v[38:39]
	v_pk_add_f32 v[8:9], v[22:23], v[38:39] neg_lo:[0,1] neg_hi:[0,1]
	v_pk_add_f32 v[22:23], v[30:31], v[46:47]
	v_pk_add_f32 v[30:31], v[30:31], v[46:47] neg_lo:[0,1] neg_hi:[0,1]
	v_pk_add_f32 v[34:35], v[4:5], v[22:23]
	v_pk_add_f32 v[22:23], v[4:5], v[22:23] neg_lo:[0,1] neg_hi:[0,1]
	v_pk_add_f32 v[36:37], v[8:9], v[30:31] op_sel:[0,1] op_sel_hi:[1,0] neg_hi:[0,1]
	v_pk_add_f32 v[30:31], v[8:9], v[30:31] op_sel:[0,1] op_sel_hi:[1,0] neg_lo:[0,1]
	v_mov_b64_e32 v[8:9], s[20:21]
	v_pk_mul_f32 v[4:5], v[2:3], v[8:9] op_sel:[0,0] op_sel_hi:[0,1]
	s_waitcnt lgkmcnt(0)
	v_pk_fma_f32 v[38:39], v[2:3], v[8:9], v[4:5] op_sel:[1,1,0] op_sel_hi:[1,0,1] neg_lo:[0,1,0]
	v_mov_b64_e32 v[4:5], s[26:27]
	v_pk_mul_f32 v[2:3], v[14:15], v[4:5] op_sel:[0,0] op_sel_hi:[0,1]
	s_barrier
	v_pk_fma_f32 v[42:43], v[14:15], v[4:5], v[2:3] op_sel:[1,1,0] op_sel_hi:[1,0,1] neg_lo:[0,1,0]
	v_mov_b64_e32 v[2:3], s[36:37]
	v_pk_mul_f32 v[14:15], v[36:37], v[2:3] op_sel:[0,0] op_sel_hi:[0,1]
	v_pk_fma_f32 v[36:37], v[36:37], v[2:3], v[14:15] op_sel:[1,1,0] op_sel_hi:[1,0,1] neg_lo:[0,1,0]
	v_pk_mul_f32 v[14:15], v[6:7], v[4:5] op_sel:[0,0] op_sel_hi:[0,1]
	s_lshl_b32 s12, s9, 13
	v_pk_fma_f32 v[44:45], v[6:7], v[4:5], v[14:15] op_sel:[1,1,0] op_sel_hi:[1,0,1] neg_lo:[0,1,0]
	v_mov_b64_e32 v[14:15], s[40:41]
	v_pk_mul_f32 v[6:7], v[28:29], v[14:15] op_sel:[0,0] op_sel_hi:[0,1]
	s_xor_b64 s[50:51], s[48:49], -1
	v_pk_fma_f32 v[28:29], v[28:29], v[14:15], v[6:7] op_sel:[1,1,0] op_sel_hi:[1,0,1] neg_lo:[0,1,0]
	v_mov_b64_e32 v[6:7], s[44:45]
	v_pk_mul_f32 v[46:47], v[22:23], v[6:7] op_sel:[0,0] op_sel_hi:[0,1]
	s_mov_b32 s9, 1
	v_pk_fma_f32 v[22:23], v[22:23], v[6:7], v[46:47] op_sel:[1,1,0] op_sel_hi:[1,0,1] neg_lo:[0,1,0]
	v_pk_mul_f32 v[46:47], v[16:17], v[2:3] op_sel:[0,0] op_sel_hi:[0,1]
	s_mov_b64 s[48:49], 0
	v_pk_fma_f32 v[46:47], v[16:17], v[2:3], v[46:47] op_sel:[1,1,0] op_sel_hi:[1,0,1] neg_lo:[0,1,0]
	v_pk_mul_f32 v[16:17], v[20:21], v[6:7] op_sel:[0,0] op_sel_hi:[0,1]
	v_pk_fma_f32 v[20:21], v[20:21], v[6:7], v[16:17] op_sel:[1,1,0] op_sel_hi:[1,0,1] neg_lo:[0,1,0]
	v_mov_b64_e32 v[16:17], s[46:47]
	v_pk_mul_f32 v[50:51], v[30:31], v[16:17] op_sel:[0,0] op_sel_hi:[0,1]
	v_pk_fma_f32 v[30:31], v[30:31], v[16:17], v[50:51] op_sel:[1,1,0] op_sel_hi:[1,0,1] neg_lo:[0,1,0]
	v_pk_add_f32 v[50:51], v[24:25], v[26:27]
	v_pk_add_f32 v[24:25], v[24:25], v[26:27] neg_lo:[0,1] neg_hi:[0,1]
	v_pk_add_f32 v[26:27], v[18:19], v[34:35]
	v_pk_add_f32 v[18:19], v[18:19], v[34:35] neg_lo:[0,1] neg_hi:[0,1]
	v_pk_add_f32 v[34:35], v[50:51], v[26:27]
	v_pk_add_f32 v[26:27], v[50:51], v[26:27] neg_lo:[0,1] neg_hi:[0,1]
	v_pk_add_f32 v[50:51], v[24:25], v[18:19] op_sel:[0,1] op_sel_hi:[1,0] neg_hi:[0,1]
	v_pk_add_f32 v[18:19], v[24:25], v[18:19] op_sel:[0,1] op_sel_hi:[1,0] neg_lo:[0,1]
	v_pk_add_f32 v[24:25], v[40:41], v[42:43]
	v_pk_add_f32 v[40:41], v[40:41], v[42:43] neg_lo:[0,1] neg_hi:[0,1]
	v_pk_add_f32 v[42:43], v[38:39], v[36:37]
	v_pk_add_f32 v[36:37], v[38:39], v[36:37] neg_lo:[0,1] neg_hi:[0,1]
	v_pk_add_f32 v[38:39], v[24:25], v[42:43]
	v_pk_add_f32 v[24:25], v[24:25], v[42:43] neg_lo:[0,1] neg_hi:[0,1]
	v_pk_add_f32 v[42:43], v[40:41], v[36:37] op_sel:[0,1] op_sel_hi:[1,0] neg_hi:[0,1]
	v_pk_add_f32 v[36:37], v[40:41], v[36:37] op_sel:[0,1] op_sel_hi:[1,0] neg_lo:[0,1]
	v_pk_add_f32 v[40:41], v[32:33], v[28:29]
	v_pk_add_f32 v[28:29], v[32:33], v[28:29] neg_lo:[0,1] neg_hi:[0,1]
	v_pk_add_f32 v[32:33], v[44:45], v[22:23]
	v_pk_add_f32 v[22:23], v[44:45], v[22:23] neg_lo:[0,1] neg_hi:[0,1]
	v_pk_add_f32 v[44:45], v[40:41], v[32:33]
	v_pk_add_f32 v[32:33], v[40:41], v[32:33] neg_lo:[0,1] neg_hi:[0,1]
	v_pk_add_f32 v[40:41], v[28:29], v[22:23] op_sel:[0,1] op_sel_hi:[1,0] neg_hi:[0,1]
	v_pk_add_f32 v[22:23], v[28:29], v[22:23] op_sel:[0,1] op_sel_hi:[1,0] neg_lo:[0,1]
	v_pk_add_f32 v[28:29], v[48:49], v[20:21]
	v_pk_add_f32 v[20:21], v[48:49], v[20:21] neg_lo:[0,1] neg_hi:[0,1]
	v_pk_add_f32 v[48:49], v[46:47], v[30:31]
	v_pk_add_f32 v[30:31], v[46:47], v[30:31] neg_lo:[0,1] neg_hi:[0,1]
	v_pk_add_f32 v[46:47], v[28:29], v[48:49]
	v_pk_add_f32 v[28:29], v[28:29], v[48:49] neg_lo:[0,1] neg_hi:[0,1]
	v_pk_add_f32 v[48:49], v[20:21], v[30:31] op_sel:[0,1] op_sel_hi:[1,0] neg_hi:[0,1]
	v_pk_add_f32 v[20:21], v[20:21], v[30:31] op_sel:[0,1] op_sel_hi:[1,0] neg_lo:[0,1]
	v_mov_b32_e32 v30, v53
	v_mov_b32_e32 v31, v62
	ds_write_b64 v59, v[34:35]
	v_pk_mul_f32 v[34:35], v[38:39], v[30:31] op_sel:[0,0] op_sel_hi:[0,1]
	v_pk_fma_f32 v[34:35], v[38:39], v[30:31], v[34:35] op_sel:[1,1,0] op_sel_hi:[1,0,1] neg_lo:[0,1,0]
	ds_write_b64 v59, v[34:35] offset:2176
	v_pk_mul_f32 v[34:35], v[30:31], v[30:31] op_sel:[0,0] op_sel_hi:[0,1]
	v_pk_fma_f32 v[34:35], v[30:31], v[30:31], v[34:35] op_sel:[1,1,0] op_sel_hi:[1,0,1] neg_lo:[0,1,0]
	v_pk_mul_f32 v[38:39], v[44:45], v[34:35] op_sel:[0,0] op_sel_hi:[0,1]
	v_pk_fma_f32 v[38:39], v[44:45], v[34:35], v[38:39] op_sel:[1,1,0] op_sel_hi:[1,0,1] neg_lo:[0,1,0]
	ds_write_b64 v59, v[38:39] offset:4352
	v_pk_mul_f32 v[38:39], v[34:35], v[30:31] op_sel:[0,0] op_sel_hi:[0,1]
	v_pk_fma_f32 v[34:35], v[34:35], v[30:31], v[38:39] op_sel:[1,1,0] op_sel_hi:[1,0,1] neg_lo:[0,1,0]
	v_pk_mul_f32 v[38:39], v[46:47], v[34:35] op_sel:[0,0] op_sel_hi:[0,1]
	v_pk_fma_f32 v[38:39], v[46:47], v[34:35], v[38:39] op_sel:[1,1,0] op_sel_hi:[1,0,1] neg_lo:[0,1,0]
	ds_write_b64 v59, v[38:39] offset:6528
	v_pk_mul_f32 v[38:39], v[34:35], v[30:31] op_sel:[0,0] op_sel_hi:[0,1]
	v_pk_fma_f32 v[34:35], v[34:35], v[30:31], v[38:39] op_sel:[1,1,0] op_sel_hi:[1,0,1] neg_lo:[0,1,0]
	v_pk_mul_f32 v[38:39], v[50:51], v[34:35] op_sel:[0,0] op_sel_hi:[0,1]
	v_pk_fma_f32 v[38:39], v[50:51], v[34:35], v[38:39] op_sel:[1,1,0] op_sel_hi:[1,0,1] neg_lo:[0,1,0]
	ds_write_b64 v59, v[38:39] offset:8704
	v_pk_mul_f32 v[38:39], v[34:35], v[30:31] op_sel:[0,0] op_sel_hi:[0,1]
	v_pk_fma_f32 v[34:35], v[34:35], v[30:31], v[38:39] op_sel:[1,1,0] op_sel_hi:[1,0,1] neg_lo:[0,1,0]
	v_pk_mul_f32 v[38:39], v[42:43], v[34:35] op_sel:[0,0] op_sel_hi:[0,1]
	v_pk_fma_f32 v[38:39], v[42:43], v[34:35], v[38:39] op_sel:[1,1,0] op_sel_hi:[1,0,1] neg_lo:[0,1,0]
	ds_write_b64 v59, v[38:39] offset:10880
	v_pk_mul_f32 v[38:39], v[34:35], v[30:31] op_sel:[0,0] op_sel_hi:[0,1]
	v_pk_fma_f32 v[34:35], v[34:35], v[30:31], v[38:39] op_sel:[1,1,0] op_sel_hi:[1,0,1] neg_lo:[0,1,0]
	v_pk_mul_f32 v[38:39], v[40:41], v[34:35] op_sel:[0,0] op_sel_hi:[0,1]
	v_pk_fma_f32 v[38:39], v[40:41], v[34:35], v[38:39] op_sel:[1,1,0] op_sel_hi:[1,0,1] neg_lo:[0,1,0]
	ds_write_b64 v59, v[38:39] offset:13056
	v_pk_mul_f32 v[38:39], v[34:35], v[30:31] op_sel:[0,0] op_sel_hi:[0,1]
	v_pk_fma_f32 v[34:35], v[34:35], v[30:31], v[38:39] op_sel:[1,1,0] op_sel_hi:[1,0,1] neg_lo:[0,1,0]
	v_pk_mul_f32 v[38:39], v[48:49], v[34:35] op_sel:[0,0] op_sel_hi:[0,1]
	v_pk_fma_f32 v[38:39], v[48:49], v[34:35], v[38:39] op_sel:[1,1,0] op_sel_hi:[1,0,1] neg_lo:[0,1,0]
	ds_write_b64 v59, v[38:39] offset:15232
	v_pk_mul_f32 v[38:39], v[34:35], v[30:31] op_sel:[0,0] op_sel_hi:[0,1]
	v_pk_fma_f32 v[34:35], v[34:35], v[30:31], v[38:39] op_sel:[1,1,0] op_sel_hi:[1,0,1] neg_lo:[0,1,0]
	v_pk_mul_f32 v[38:39], v[26:27], v[34:35] op_sel:[0,0] op_sel_hi:[0,1]
	v_pk_fma_f32 v[26:27], v[26:27], v[34:35], v[38:39] op_sel:[1,1,0] op_sel_hi:[1,0,1] neg_lo:[0,1,0]
	ds_write_b64 v59, v[26:27] offset:17408
	v_pk_mul_f32 v[26:27], v[34:35], v[30:31] op_sel:[0,0] op_sel_hi:[0,1]
	v_pk_fma_f32 v[26:27], v[34:35], v[30:31], v[26:27] op_sel:[1,1,0] op_sel_hi:[1,0,1] neg_lo:[0,1,0]
	v_pk_mul_f32 v[34:35], v[24:25], v[26:27] op_sel:[0,0] op_sel_hi:[0,1]
	v_pk_fma_f32 v[24:25], v[24:25], v[26:27], v[34:35] op_sel:[1,1,0] op_sel_hi:[1,0,1] neg_lo:[0,1,0]
	ds_write_b64 v59, v[24:25] offset:19584
	v_pk_mul_f32 v[24:25], v[26:27], v[30:31] op_sel:[0,0] op_sel_hi:[0,1]
	v_pk_fma_f32 v[24:25], v[26:27], v[30:31], v[24:25] op_sel:[1,1,0] op_sel_hi:[1,0,1] neg_lo:[0,1,0]
	v_pk_mul_f32 v[26:27], v[32:33], v[24:25] op_sel:[0,0] op_sel_hi:[0,1]
	v_pk_fma_f32 v[26:27], v[32:33], v[24:25], v[26:27] op_sel:[1,1,0] op_sel_hi:[1,0,1] neg_lo:[0,1,0]
	ds_write_b64 v59, v[26:27] offset:21760
	v_pk_mul_f32 v[26:27], v[24:25], v[30:31] op_sel:[0,0] op_sel_hi:[0,1]
	v_pk_fma_f32 v[24:25], v[24:25], v[30:31], v[26:27] op_sel:[1,1,0] op_sel_hi:[1,0,1] neg_lo:[0,1,0]
	v_pk_mul_f32 v[26:27], v[28:29], v[24:25] op_sel:[0,0] op_sel_hi:[0,1]
	v_pk_fma_f32 v[26:27], v[28:29], v[24:25], v[26:27] op_sel:[1,1,0] op_sel_hi:[1,0,1] neg_lo:[0,1,0]
	ds_write_b64 v59, v[26:27] offset:23936
	v_pk_mul_f32 v[26:27], v[24:25], v[30:31] op_sel:[0,0] op_sel_hi:[0,1]
	v_pk_fma_f32 v[24:25], v[24:25], v[30:31], v[26:27] op_sel:[1,1,0] op_sel_hi:[1,0,1] neg_lo:[0,1,0]
	v_pk_mul_f32 v[26:27], v[18:19], v[24:25] op_sel:[0,0] op_sel_hi:[0,1]
	v_pk_fma_f32 v[18:19], v[18:19], v[24:25], v[26:27] op_sel:[1,1,0] op_sel_hi:[1,0,1] neg_lo:[0,1,0]
	ds_write_b64 v59, v[18:19] offset:26112
	v_pk_mul_f32 v[18:19], v[24:25], v[30:31] op_sel:[0,0] op_sel_hi:[0,1]
	v_pk_fma_f32 v[18:19], v[24:25], v[30:31], v[18:19] op_sel:[1,1,0] op_sel_hi:[1,0,1] neg_lo:[0,1,0]
	v_pk_mul_f32 v[24:25], v[36:37], v[18:19] op_sel:[0,0] op_sel_hi:[0,1]
	v_pk_fma_f32 v[24:25], v[36:37], v[18:19], v[24:25] op_sel:[1,1,0] op_sel_hi:[1,0,1] neg_lo:[0,1,0]
	ds_write_b64 v59, v[24:25] offset:28288
	v_pk_mul_f32 v[24:25], v[18:19], v[30:31] op_sel:[0,0] op_sel_hi:[0,1]
	v_pk_fma_f32 v[18:19], v[18:19], v[30:31], v[24:25] op_sel:[1,1,0] op_sel_hi:[1,0,1] neg_lo:[0,1,0]
	v_pk_mul_f32 v[24:25], v[22:23], v[18:19] op_sel:[0,0] op_sel_hi:[0,1]
	v_pk_fma_f32 v[22:23], v[22:23], v[18:19], v[24:25] op_sel:[1,1,0] op_sel_hi:[1,0,1] neg_lo:[0,1,0]
	ds_write_b64 v59, v[22:23] offset:30464
	v_pk_mul_f32 v[22:23], v[18:19], v[30:31] op_sel:[0,0] op_sel_hi:[0,1]
	v_pk_fma_f32 v[18:19], v[18:19], v[30:31], v[22:23] op_sel:[1,1,0] op_sel_hi:[1,0,1] neg_lo:[0,1,0]
	v_pk_mul_f32 v[22:23], v[20:21], v[18:19] op_sel:[0,0] op_sel_hi:[0,1]
	v_pk_fma_f32 v[18:19], v[20:21], v[18:19], v[22:23] op_sel:[1,1,0] op_sel_hi:[1,0,1] neg_lo:[0,1,0]
	ds_write_b64 v59, v[18:19] offset:32640
	s_waitcnt lgkmcnt(0)
	s_barrier
	ds_read2_b64 v[18:21], v60 offset1:17
	ds_read2_b64 v[22:25], v60 offset0:34 offset1:51
	ds_read2_b64 v[26:29], v60 offset0:68 offset1:85
	ds_read2_b64 v[30:33], v60 offset0:136 offset1:153
	ds_read2_b64 v[34:37], v60 offset0:102 offset1:119
	ds_read2_b64 v[38:41], v60 offset0:204 offset1:221
	ds_read2_b64 v[42:45], v60 offset0:170 offset1:187
	ds_read2_b64 v[46:49], v60 offset0:238 offset1:255
	s_waitcnt lgkmcnt(4)
	v_pk_add_f32 v[50:51], v[18:19], v[30:31]
	v_pk_add_f32 v[18:19], v[18:19], v[30:31] neg_lo:[0,1] neg_hi:[0,1]
	s_waitcnt lgkmcnt(2)
	v_pk_add_f32 v[30:31], v[26:27], v[38:39]
	v_pk_add_f32 v[26:27], v[26:27], v[38:39] neg_lo:[0,1] neg_hi:[0,1]
	v_pk_add_f32 v[38:39], v[50:51], v[30:31]
	v_pk_add_f32 v[30:31], v[50:51], v[30:31] neg_lo:[0,1] neg_hi:[0,1]
	v_pk_add_f32 v[50:51], v[18:19], v[26:27] op_sel:[0,1] op_sel_hi:[1,0] neg_hi:[0,1]
	v_pk_add_f32 v[18:19], v[18:19], v[26:27] op_sel:[0,1] op_sel_hi:[1,0] neg_lo:[0,1]
	v_pk_add_f32 v[26:27], v[20:21], v[32:33]
	v_pk_add_f32 v[20:21], v[20:21], v[32:33] neg_lo:[0,1] neg_hi:[0,1]
	v_pk_add_f32 v[32:33], v[28:29], v[40:41]
	v_pk_add_f32 v[28:29], v[28:29], v[40:41] neg_lo:[0,1] neg_hi:[0,1]
	v_pk_add_f32 v[40:41], v[26:27], v[32:33]
	v_pk_add_f32 v[26:27], v[26:27], v[32:33] neg_lo:[0,1] neg_hi:[0,1]
	v_pk_add_f32 v[32:33], v[20:21], v[28:29] op_sel:[0,1] op_sel_hi:[1,0] neg_hi:[0,1]
	v_pk_add_f32 v[20:21], v[20:21], v[28:29] op_sel:[0,1] op_sel_hi:[1,0] neg_lo:[0,1]
	s_waitcnt lgkmcnt(1)
	v_pk_add_f32 v[28:29], v[22:23], v[42:43]
	v_pk_add_f32 v[22:23], v[22:23], v[42:43] neg_lo:[0,1] neg_hi:[0,1]
	s_waitcnt lgkmcnt(0)
	v_pk_add_f32 v[42:43], v[34:35], v[46:47]
	v_pk_add_f32 v[34:35], v[34:35], v[46:47] neg_lo:[0,1] neg_hi:[0,1]
	v_pk_add_f32 v[46:47], v[28:29], v[42:43]
	v_pk_add_f32 v[28:29], v[28:29], v[42:43] neg_lo:[0,1] neg_hi:[0,1]
	v_pk_add_f32 v[42:43], v[22:23], v[34:35] op_sel:[0,1] op_sel_hi:[1,0] neg_hi:[0,1]
	v_pk_add_f32 v[22:23], v[22:23], v[34:35] op_sel:[0,1] op_sel_hi:[1,0] neg_lo:[0,1]
	v_pk_add_f32 v[34:35], v[24:25], v[44:45]
	v_pk_add_f32 v[24:25], v[24:25], v[44:45] neg_lo:[0,1] neg_hi:[0,1]
	v_pk_add_f32 v[44:45], v[36:37], v[48:49]
	v_pk_add_f32 v[36:37], v[36:37], v[48:49] neg_lo:[0,1] neg_hi:[0,1]
	v_pk_add_f32 v[48:49], v[34:35], v[44:45]
	v_pk_add_f32 v[34:35], v[34:35], v[44:45] neg_lo:[0,1] neg_hi:[0,1]
	v_pk_add_f32 v[44:45], v[24:25], v[36:37] op_sel:[0,1] op_sel_hi:[1,0] neg_hi:[0,1]
	v_pk_add_f32 v[24:25], v[24:25], v[36:37] op_sel:[0,1] op_sel_hi:[1,0] neg_lo:[0,1]
	v_pk_mul_f32 v[36:37], v[32:33], v[8:9] op_sel:[0,0] op_sel_hi:[0,1]
	v_pk_fma_f32 v[32:33], v[32:33], v[8:9], v[36:37] op_sel:[1,1,0] op_sel_hi:[1,0,1] neg_lo:[0,1,0]
	v_pk_mul_f32 v[36:37], v[42:43], v[4:5] op_sel:[0,0] op_sel_hi:[0,1]
	v_pk_fma_f32 v[36:37], v[42:43], v[4:5], v[36:37] op_sel:[1,1,0] op_sel_hi:[1,0,1] neg_lo:[0,1,0]
	v_pk_mul_f32 v[42:43], v[44:45], v[2:3] op_sel:[0,0] op_sel_hi:[0,1]
	v_pk_fma_f32 v[42:43], v[44:45], v[2:3], v[42:43] op_sel:[1,1,0] op_sel_hi:[1,0,1] neg_lo:[0,1,0]
	v_pk_mul_f32 v[44:45], v[26:27], v[4:5] op_sel:[0,0] op_sel_hi:[0,1]
	v_pk_fma_f32 v[26:27], v[26:27], v[4:5], v[44:45] op_sel:[1,1,0] op_sel_hi:[1,0,1] neg_lo:[0,1,0]
	v_pk_mul_f32 v[44:45], v[28:29], v[14:15] op_sel:[0,0] op_sel_hi:[0,1]
	v_pk_fma_f32 v[28:29], v[28:29], v[14:15], v[44:45] op_sel:[1,1,0] op_sel_hi:[1,0,1] neg_lo:[0,1,0]
	v_pk_mul_f32 v[44:45], v[34:35], v[6:7] op_sel:[0,0] op_sel_hi:[0,1]
	v_pk_fma_f32 v[34:35], v[34:35], v[6:7], v[44:45] op_sel:[1,1,0] op_sel_hi:[1,0,1] neg_lo:[0,1,0]
	v_pk_mul_f32 v[44:45], v[20:21], v[2:3] op_sel:[0,0] op_sel_hi:[0,1]
	v_pk_fma_f32 v[20:21], v[20:21], v[2:3], v[44:45] op_sel:[1,1,0] op_sel_hi:[1,0,1] neg_lo:[0,1,0]
	v_pk_mul_f32 v[44:45], v[22:23], v[6:7] op_sel:[0,0] op_sel_hi:[0,1]
	v_pk_fma_f32 v[22:23], v[22:23], v[6:7], v[44:45] op_sel:[1,1,0] op_sel_hi:[1,0,1] neg_lo:[0,1,0]
	v_pk_mul_f32 v[44:45], v[24:25], v[16:17] op_sel:[0,0] op_sel_hi:[0,1]
	v_pk_fma_f32 v[24:25], v[24:25], v[16:17], v[44:45] op_sel:[1,1,0] op_sel_hi:[1,0,1] neg_lo:[0,1,0]
	v_pk_add_f32 v[44:45], v[38:39], v[46:47]
	v_pk_add_f32 v[38:39], v[38:39], v[46:47] neg_lo:[0,1] neg_hi:[0,1]
	v_pk_add_f32 v[46:47], v[40:41], v[48:49]
	v_pk_add_f32 v[40:41], v[40:41], v[48:49] neg_lo:[0,1] neg_hi:[0,1]
	v_pk_add_f32 v[48:49], v[44:45], v[46:47]
	v_pk_add_f32 v[44:45], v[44:45], v[46:47] neg_lo:[0,1] neg_hi:[0,1]
	v_pk_add_f32 v[46:47], v[38:39], v[40:41] op_sel:[0,1] op_sel_hi:[1,0] neg_hi:[0,1]
	v_pk_add_f32 v[38:39], v[38:39], v[40:41] op_sel:[0,1] op_sel_hi:[1,0] neg_lo:[0,1]
	v_pk_add_f32 v[40:41], v[50:51], v[36:37]
	v_pk_add_f32 v[36:37], v[50:51], v[36:37] neg_lo:[0,1] neg_hi:[0,1]
	v_pk_add_f32 v[50:51], v[32:33], v[42:43]
	v_pk_add_f32 v[32:33], v[32:33], v[42:43] neg_lo:[0,1] neg_hi:[0,1]
	v_pk_add_f32 v[42:43], v[40:41], v[50:51]
	v_pk_add_f32 v[40:41], v[40:41], v[50:51] neg_lo:[0,1] neg_hi:[0,1]
	v_pk_add_f32 v[50:51], v[36:37], v[32:33] op_sel:[0,1] op_sel_hi:[1,0] neg_hi:[0,1]
	v_pk_add_f32 v[32:33], v[36:37], v[32:33] op_sel:[0,1] op_sel_hi:[1,0] neg_lo:[0,1]
	v_pk_add_f32 v[36:37], v[30:31], v[28:29]
	v_pk_add_f32 v[28:29], v[30:31], v[28:29] neg_lo:[0,1] neg_hi:[0,1]
	v_pk_add_f32 v[30:31], v[26:27], v[34:35]
	v_pk_add_f32 v[26:27], v[26:27], v[34:35] neg_lo:[0,1] neg_hi:[0,1]
	v_pk_add_f32 v[34:35], v[36:37], v[30:31]
	v_pk_add_f32 v[30:31], v[36:37], v[30:31] neg_lo:[0,1] neg_hi:[0,1]
	v_pk_add_f32 v[36:37], v[28:29], v[26:27] op_sel:[0,1] op_sel_hi:[1,0] neg_hi:[0,1]
	v_pk_add_f32 v[26:27], v[28:29], v[26:27] op_sel:[0,1] op_sel_hi:[1,0] neg_lo:[0,1]
	v_pk_add_f32 v[28:29], v[18:19], v[22:23]
	v_pk_add_f32 v[18:19], v[18:19], v[22:23] neg_lo:[0,1] neg_hi:[0,1]
	v_pk_add_f32 v[22:23], v[20:21], v[24:25]
	v_pk_add_f32 v[20:21], v[20:21], v[24:25] neg_lo:[0,1] neg_hi:[0,1]
	v_pk_add_f32 v[24:25], v[28:29], v[22:23]
	v_pk_add_f32 v[22:23], v[28:29], v[22:23] neg_lo:[0,1] neg_hi:[0,1]
	v_pk_add_f32 v[28:29], v[18:19], v[20:21] op_sel:[0,1] op_sel_hi:[1,0] neg_hi:[0,1]
	v_pk_add_f32 v[18:19], v[18:19], v[20:21] op_sel:[0,1] op_sel_hi:[1,0] neg_lo:[0,1]
	v_mov_b32_e32 v21, v63
	v_mov_b32_e32 v20, v54
	s_nop 0
	v_pk_mul_f32 v[66:67], v[42:43], v[20:21] op_sel:[0,0] op_sel_hi:[0,1]
	v_pk_fma_f32 v[42:43], v[42:43], v[20:21], v[66:67] op_sel:[1,1,0] op_sel_hi:[1,0,1] neg_lo:[0,1,0]
	ds_write2_b64 v60, v[48:49], v[42:43] offset1:17
	v_pk_mul_f32 v[42:43], v[20:21], v[20:21] op_sel:[0,0] op_sel_hi:[0,1]
	v_pk_fma_f32 v[42:43], v[20:21], v[20:21], v[42:43] op_sel:[1,1,0] op_sel_hi:[1,0,1] neg_lo:[0,1,0]
	v_pk_mul_f32 v[48:49], v[34:35], v[42:43] op_sel:[0,0] op_sel_hi:[0,1]
	v_pk_fma_f32 v[34:35], v[34:35], v[42:43], v[48:49] op_sel:[1,1,0] op_sel_hi:[1,0,1] neg_lo:[0,1,0]
	v_pk_mul_f32 v[48:49], v[42:43], v[20:21] op_sel:[0,0] op_sel_hi:[0,1]
	v_pk_fma_f32 v[42:43], v[42:43], v[20:21], v[48:49] op_sel:[1,1,0] op_sel_hi:[1,0,1] neg_lo:[0,1,0]
	v_pk_mul_f32 v[48:49], v[24:25], v[42:43] op_sel:[0,0] op_sel_hi:[0,1]
	v_pk_fma_f32 v[24:25], v[24:25], v[42:43], v[48:49] op_sel:[1,1,0] op_sel_hi:[1,0,1] neg_lo:[0,1,0]
	ds_write2_b64 v60, v[34:35], v[24:25] offset0:34 offset1:51
	v_pk_mul_f32 v[24:25], v[42:43], v[20:21] op_sel:[0,0] op_sel_hi:[0,1]
	v_pk_fma_f32 v[24:25], v[42:43], v[20:21], v[24:25] op_sel:[1,1,0] op_sel_hi:[1,0,1] neg_lo:[0,1,0]
	v_pk_mul_f32 v[34:35], v[46:47], v[24:25] op_sel:[0,0] op_sel_hi:[0,1]
	v_pk_mul_f32 v[42:43], v[24:25], v[20:21] op_sel:[0,0] op_sel_hi:[0,1]
	v_pk_fma_f32 v[34:35], v[46:47], v[24:25], v[34:35] op_sel:[1,1,0] op_sel_hi:[1,0,1] neg_lo:[0,1,0]
	v_pk_fma_f32 v[24:25], v[24:25], v[20:21], v[42:43] op_sel:[1,1,0] op_sel_hi:[1,0,1] neg_lo:[0,1,0]
	v_pk_mul_f32 v[42:43], v[50:51], v[24:25] op_sel:[0,0] op_sel_hi:[0,1]
	v_pk_fma_f32 v[42:43], v[50:51], v[24:25], v[42:43] op_sel:[1,1,0] op_sel_hi:[1,0,1] neg_lo:[0,1,0]
	ds_write2_b64 v60, v[34:35], v[42:43] offset0:68 offset1:85
	v_pk_mul_f32 v[34:35], v[24:25], v[20:21] op_sel:[0,0] op_sel_hi:[0,1]
	v_pk_fma_f32 v[24:25], v[24:25], v[20:21], v[34:35] op_sel:[1,1,0] op_sel_hi:[1,0,1] neg_lo:[0,1,0]
	v_pk_mul_f32 v[34:35], v[36:37], v[24:25] op_sel:[0,0] op_sel_hi:[0,1]
	v_pk_fma_f32 v[34:35], v[36:37], v[24:25], v[34:35] op_sel:[1,1,0] op_sel_hi:[1,0,1] neg_lo:[0,1,0]
	v_pk_mul_f32 v[36:37], v[24:25], v[20:21] op_sel:[0,0] op_sel_hi:[0,1]
	v_pk_fma_f32 v[24:25], v[24:25], v[20:21], v[36:37] op_sel:[1,1,0] op_sel_hi:[1,0,1] neg_lo:[0,1,0]
	v_pk_mul_f32 v[36:37], v[28:29], v[24:25] op_sel:[0,0] op_sel_hi:[0,1]
	v_pk_fma_f32 v[28:29], v[28:29], v[24:25], v[36:37] op_sel:[1,1,0] op_sel_hi:[1,0,1] neg_lo:[0,1,0]
	ds_write2_b64 v60, v[34:35], v[28:29] offset0:102 offset1:119
	v_pk_mul_f32 v[28:29], v[24:25], v[20:21] op_sel:[0,0] op_sel_hi:[0,1]
	v_pk_fma_f32 v[24:25], v[24:25], v[20:21], v[28:29] op_sel:[1,1,0] op_sel_hi:[1,0,1] neg_lo:[0,1,0]
	v_pk_mul_f32 v[28:29], v[44:45], v[24:25] op_sel:[0,0] op_sel_hi:[0,1]
	v_pk_mul_f32 v[34:35], v[24:25], v[20:21] op_sel:[0,0] op_sel_hi:[0,1]
	v_pk_fma_f32 v[28:29], v[44:45], v[24:25], v[28:29] op_sel:[1,1,0] op_sel_hi:[1,0,1] neg_lo:[0,1,0]
	v_pk_fma_f32 v[24:25], v[24:25], v[20:21], v[34:35] op_sel:[1,1,0] op_sel_hi:[1,0,1] neg_lo:[0,1,0]
	v_pk_mul_f32 v[34:35], v[40:41], v[24:25] op_sel:[0,0] op_sel_hi:[0,1]
	v_pk_fma_f32 v[34:35], v[40:41], v[24:25], v[34:35] op_sel:[1,1,0] op_sel_hi:[1,0,1] neg_lo:[0,1,0]
	ds_write2_b64 v60, v[28:29], v[34:35] offset0:136 offset1:153
	v_pk_mul_f32 v[28:29], v[24:25], v[20:21] op_sel:[0,0] op_sel_hi:[0,1]
	v_pk_fma_f32 v[24:25], v[24:25], v[20:21], v[28:29] op_sel:[1,1,0] op_sel_hi:[1,0,1] neg_lo:[0,1,0]
	v_pk_mul_f32 v[28:29], v[30:31], v[24:25] op_sel:[0,0] op_sel_hi:[0,1]
	v_pk_fma_f32 v[28:29], v[30:31], v[24:25], v[28:29] op_sel:[1,1,0] op_sel_hi:[1,0,1] neg_lo:[0,1,0]
	v_pk_mul_f32 v[30:31], v[24:25], v[20:21] op_sel:[0,0] op_sel_hi:[0,1]
	v_pk_fma_f32 v[24:25], v[24:25], v[20:21], v[30:31] op_sel:[1,1,0] op_sel_hi:[1,0,1] neg_lo:[0,1,0]
	v_pk_mul_f32 v[30:31], v[22:23], v[24:25] op_sel:[0,0] op_sel_hi:[0,1]
	v_pk_fma_f32 v[22:23], v[22:23], v[24:25], v[30:31] op_sel:[1,1,0] op_sel_hi:[1,0,1] neg_lo:[0,1,0]
	ds_write2_b64 v60, v[28:29], v[22:23] offset0:170 offset1:187
	v_pk_mul_f32 v[22:23], v[24:25], v[20:21] op_sel:[0,0] op_sel_hi:[0,1]
	v_pk_fma_f32 v[22:23], v[24:25], v[20:21], v[22:23] op_sel:[1,1,0] op_sel_hi:[1,0,1] neg_lo:[0,1,0]
	v_pk_mul_f32 v[24:25], v[38:39], v[22:23] op_sel:[0,0] op_sel_hi:[0,1]
	v_pk_mul_f32 v[28:29], v[22:23], v[20:21] op_sel:[0,0] op_sel_hi:[0,1]
	v_pk_fma_f32 v[24:25], v[38:39], v[22:23], v[24:25] op_sel:[1,1,0] op_sel_hi:[1,0,1] neg_lo:[0,1,0]
	v_pk_fma_f32 v[22:23], v[22:23], v[20:21], v[28:29] op_sel:[1,1,0] op_sel_hi:[1,0,1] neg_lo:[0,1,0]
	v_pk_mul_f32 v[28:29], v[32:33], v[22:23] op_sel:[0,0] op_sel_hi:[0,1]
	v_pk_fma_f32 v[28:29], v[32:33], v[22:23], v[28:29] op_sel:[1,1,0] op_sel_hi:[1,0,1] neg_lo:[0,1,0]
	ds_write2_b64 v60, v[24:25], v[28:29] offset0:204 offset1:221
	v_pk_mul_f32 v[24:25], v[22:23], v[20:21] op_sel:[0,0] op_sel_hi:[0,1]
	v_pk_fma_f32 v[22:23], v[22:23], v[20:21], v[24:25] op_sel:[1,1,0] op_sel_hi:[1,0,1] neg_lo:[0,1,0]
	v_pk_mul_f32 v[24:25], v[26:27], v[22:23] op_sel:[0,0] op_sel_hi:[0,1]
	v_pk_fma_f32 v[24:25], v[26:27], v[22:23], v[24:25] op_sel:[1,1,0] op_sel_hi:[1,0,1] neg_lo:[0,1,0]
	v_pk_mul_f32 v[26:27], v[22:23], v[20:21] op_sel:[0,0] op_sel_hi:[0,1]
	v_pk_fma_f32 v[20:21], v[22:23], v[20:21], v[26:27] op_sel:[1,1,0] op_sel_hi:[1,0,1] neg_lo:[0,1,0]
	v_pk_mul_f32 v[22:23], v[18:19], v[20:21] op_sel:[0,0] op_sel_hi:[0,1]
	v_pk_fma_f32 v[18:19], v[18:19], v[20:21], v[22:23] op_sel:[1,1,0] op_sel_hi:[1,0,1] neg_lo:[0,1,0]
	ds_write2_b64 v60, v[24:25], v[18:19] offset0:238 offset1:255
	s_waitcnt lgkmcnt(0)
	s_barrier
	ds_read2_b64 v[18:21], v64 offset1:1
	ds_read2_b64 v[22:25], v64 offset0:2 offset1:3
	ds_read2_b64 v[26:29], v64 offset0:8 offset1:9
	ds_read2_b64 v[30:33], v64 offset0:4 offset1:5
	ds_read2_b64 v[34:37], v64 offset0:6 offset1:7
	ds_read2_b64 v[38:41], v64 offset0:12 offset1:13
	ds_read2_b64 v[42:45], v64 offset0:10 offset1:11
	ds_read2_b64 v[46:49], v64 offset0:14 offset1:15
	s_waitcnt lgkmcnt(5)
	v_pk_add_f32 v[50:51], v[18:19], v[26:27]
	v_pk_add_f32 v[18:19], v[18:19], v[26:27] neg_lo:[0,1] neg_hi:[0,1]
	s_waitcnt lgkmcnt(2)
	v_pk_add_f32 v[26:27], v[30:31], v[38:39]
	v_pk_add_f32 v[30:31], v[30:31], v[38:39] neg_lo:[0,1] neg_hi:[0,1]
	v_pk_add_f32 v[38:39], v[50:51], v[26:27]
	v_pk_add_f32 v[26:27], v[50:51], v[26:27] neg_lo:[0,1] neg_hi:[0,1]
	v_pk_add_f32 v[50:51], v[18:19], v[30:31] op_sel:[0,1] op_sel_hi:[1,0] neg_hi:[0,1]
	v_pk_add_f32 v[18:19], v[18:19], v[30:31] op_sel:[0,1] op_sel_hi:[1,0] neg_lo:[0,1]
	v_pk_add_f32 v[30:31], v[20:21], v[28:29]
	v_pk_add_f32 v[20:21], v[20:21], v[28:29] neg_lo:[0,1] neg_hi:[0,1]
	v_pk_add_f32 v[28:29], v[32:33], v[40:41]
	v_pk_add_f32 v[32:33], v[32:33], v[40:41] neg_lo:[0,1] neg_hi:[0,1]
	v_pk_add_f32 v[40:41], v[30:31], v[28:29]
	v_pk_add_f32 v[28:29], v[30:31], v[28:29] neg_lo:[0,1] neg_hi:[0,1]
	v_pk_add_f32 v[30:31], v[20:21], v[32:33] op_sel:[0,1] op_sel_hi:[1,0] neg_hi:[0,1]
	v_pk_add_f32 v[20:21], v[20:21], v[32:33] op_sel:[0,1] op_sel_hi:[1,0] neg_lo:[0,1]
	s_waitcnt lgkmcnt(1)
	v_pk_add_f32 v[32:33], v[22:23], v[42:43]
	v_pk_add_f32 v[22:23], v[22:23], v[42:43] neg_lo:[0,1] neg_hi:[0,1]
	s_waitcnt lgkmcnt(0)
	v_pk_add_f32 v[42:43], v[34:35], v[46:47]
	v_pk_add_f32 v[34:35], v[34:35], v[46:47] neg_lo:[0,1] neg_hi:[0,1]
	v_pk_add_f32 v[46:47], v[32:33], v[42:43]
	v_pk_add_f32 v[32:33], v[32:33], v[42:43] neg_lo:[0,1] neg_hi:[0,1]
	v_pk_add_f32 v[42:43], v[22:23], v[34:35] op_sel:[0,1] op_sel_hi:[1,0] neg_hi:[0,1]
	v_pk_add_f32 v[22:23], v[22:23], v[34:35] op_sel:[0,1] op_sel_hi:[1,0] neg_lo:[0,1]
	v_pk_add_f32 v[34:35], v[24:25], v[44:45]
	v_pk_add_f32 v[24:25], v[24:25], v[44:45] neg_lo:[0,1] neg_hi:[0,1]
	v_pk_add_f32 v[44:45], v[36:37], v[48:49]
	v_pk_add_f32 v[36:37], v[36:37], v[48:49] neg_lo:[0,1] neg_hi:[0,1]
	v_pk_add_f32 v[48:49], v[34:35], v[44:45]
	v_pk_add_f32 v[34:35], v[34:35], v[44:45] neg_lo:[0,1] neg_hi:[0,1]
	v_pk_add_f32 v[44:45], v[24:25], v[36:37] op_sel:[0,1] op_sel_hi:[1,0] neg_hi:[0,1]
	v_pk_add_f32 v[24:25], v[24:25], v[36:37] op_sel:[0,1] op_sel_hi:[1,0] neg_lo:[0,1]
	v_pk_mul_f32 v[36:37], v[30:31], v[8:9] op_sel:[0,0] op_sel_hi:[0,1]
	v_pk_fma_f32 v[8:9], v[30:31], v[8:9], v[36:37] op_sel:[1,1,0] op_sel_hi:[1,0,1] neg_lo:[0,1,0]
	v_pk_mul_f32 v[30:31], v[42:43], v[4:5] op_sel:[0,0] op_sel_hi:[0,1]
	v_pk_mul_f32 v[36:37], v[44:45], v[2:3] op_sel:[0,0] op_sel_hi:[0,1]
	s_barrier
	v_pk_fma_f32 v[30:31], v[42:43], v[4:5], v[30:31] op_sel:[1,1,0] op_sel_hi:[1,0,1] neg_lo:[0,1,0]
	v_pk_mul_f32 v[42:43], v[28:29], v[4:5] op_sel:[0,0] op_sel_hi:[0,1]
	v_pk_fma_f32 v[36:37], v[44:45], v[2:3], v[36:37] op_sel:[1,1,0] op_sel_hi:[1,0,1] neg_lo:[0,1,0]
	v_pk_fma_f32 v[4:5], v[28:29], v[4:5], v[42:43] op_sel:[1,1,0] op_sel_hi:[1,0,1] neg_lo:[0,1,0]
	v_pk_mul_f32 v[28:29], v[32:33], v[14:15] op_sel:[0,0] op_sel_hi:[0,1]
	v_pk_fma_f32 v[14:15], v[32:33], v[14:15], v[28:29] op_sel:[1,1,0] op_sel_hi:[1,0,1] neg_lo:[0,1,0]
	v_pk_mul_f32 v[28:29], v[34:35], v[6:7] op_sel:[0,0] op_sel_hi:[0,1]
	v_pk_mul_f32 v[32:33], v[20:21], v[2:3] op_sel:[0,0] op_sel_hi:[0,1]
	v_pk_fma_f32 v[2:3], v[20:21], v[2:3], v[32:33] op_sel:[1,1,0] op_sel_hi:[1,0,1] neg_lo:[0,1,0]
	v_pk_mul_f32 v[20:21], v[22:23], v[6:7] op_sel:[0,0] op_sel_hi:[0,1]
	v_pk_fma_f32 v[28:29], v[34:35], v[6:7], v[28:29] op_sel:[1,1,0] op_sel_hi:[1,0,1] neg_lo:[0,1,0]
	v_pk_add_f32 v[32:33], v[40:41], v[48:49] neg_lo:[0,1] neg_hi:[0,1]
	v_pk_fma_f32 v[6:7], v[22:23], v[6:7], v[20:21] op_sel:[1,1,0] op_sel_hi:[1,0,1] neg_lo:[0,1,0]
	v_pk_mul_f32 v[20:21], v[24:25], v[16:17] op_sel:[0,0] op_sel_hi:[0,1]
	v_pk_add_f32 v[22:23], v[38:39], v[46:47] neg_lo:[0,1] neg_hi:[0,1]
	v_pk_fma_f32 v[16:17], v[24:25], v[16:17], v[20:21] op_sel:[1,1,0] op_sel_hi:[1,0,1] neg_lo:[0,1,0]
	v_pk_add_f32 v[20:21], v[38:39], v[46:47]
	v_pk_add_f32 v[24:25], v[40:41], v[48:49]
	v_pk_add_f32 v[38:39], v[8:9], v[36:37]
	v_pk_add_f32 v[34:35], v[20:21], v[24:25]
	v_pk_add_f32 v[20:21], v[20:21], v[24:25] neg_lo:[0,1] neg_hi:[0,1]
	v_pk_add_f32 v[24:25], v[22:23], v[32:33] op_sel:[0,1] op_sel_hi:[1,0] neg_hi:[0,1]
	v_pk_add_f32 v[22:23], v[22:23], v[32:33] op_sel:[0,1] op_sel_hi:[1,0] neg_lo:[0,1]
	v_pk_add_f32 v[32:33], v[50:51], v[30:31]
	v_pk_add_f32 v[30:31], v[50:51], v[30:31] neg_lo:[0,1] neg_hi:[0,1]
	v_pk_add_f32 v[8:9], v[8:9], v[36:37] neg_lo:[0,1] neg_hi:[0,1]
	v_pk_add_f32 v[36:37], v[32:33], v[38:39]
	v_pk_add_f32 v[32:33], v[32:33], v[38:39] neg_lo:[0,1] neg_hi:[0,1]
	v_pk_add_f32 v[38:39], v[30:31], v[8:9] op_sel:[0,1] op_sel_hi:[1,0] neg_hi:[0,1]
	v_pk_add_f32 v[8:9], v[30:31], v[8:9] op_sel:[0,1] op_sel_hi:[1,0] neg_lo:[0,1]
	v_pk_add_f32 v[30:31], v[26:27], v[14:15]
	v_pk_add_f32 v[14:15], v[26:27], v[14:15] neg_lo:[0,1] neg_hi:[0,1]
	v_pk_add_f32 v[26:27], v[4:5], v[28:29]
	v_pk_add_f32 v[4:5], v[4:5], v[28:29] neg_lo:[0,1] neg_hi:[0,1]
	v_pk_add_f32 v[28:29], v[30:31], v[26:27]
	v_pk_add_f32 v[26:27], v[30:31], v[26:27] neg_lo:[0,1] neg_hi:[0,1]
	v_pk_add_f32 v[30:31], v[14:15], v[4:5] op_sel:[0,1] op_sel_hi:[1,0] neg_hi:[0,1]
	v_pk_add_f32 v[4:5], v[14:15], v[4:5] op_sel:[0,1] op_sel_hi:[1,0] neg_lo:[0,1]
	v_pk_add_f32 v[14:15], v[18:19], v[6:7]
	v_pk_add_f32 v[6:7], v[18:19], v[6:7] neg_lo:[0,1] neg_hi:[0,1]
	v_pk_add_f32 v[18:19], v[2:3], v[16:17]
	v_pk_add_f32 v[2:3], v[2:3], v[16:17] neg_lo:[0,1] neg_hi:[0,1]
	v_pk_add_f32 v[16:17], v[14:15], v[18:19]
	v_pk_add_f32 v[14:15], v[14:15], v[18:19] neg_lo:[0,1] neg_hi:[0,1]
	v_pk_add_f32 v[18:19], v[6:7], v[2:3] op_sel:[0,1] op_sel_hi:[1,0] neg_hi:[0,1]
	v_pk_add_f32 v[2:3], v[6:7], v[2:3] op_sel:[0,1] op_sel_hi:[1,0] neg_lo:[0,1]
	v_add_f32_e32 v6, 0x358637bd, v10
	v_mul_f32_e32 v6, 0x46000000, v6
	v_div_scale_f32 v7, s[28:29], v6, v6, 1.0
	v_rcp_f32_e32 v10, v7
	s_nop 0
	v_fma_f32 v40, -v7, v10, 1.0
	v_fmac_f32_e32 v10, v40, v10
	v_div_scale_f32 v40, vcc, 1.0, v6, 1.0
	v_mul_f32_e32 v41, v40, v10
	v_fma_f32 v42, -v7, v41, v40
	v_fmac_f32_e32 v41, v42, v10
	v_fma_f32 v7, -v7, v41, v40
	v_div_fmas_f32 v7, v7, v10, v41
	v_div_fixup_f32 v6, v7, v6, 1.0
	v_pk_mul_f32 v[34:35], v[6:7], v[34:35] op_sel_hi:[0,1]
	v_pk_mul_f32 v[24:25], v[6:7], v[24:25] op_sel_hi:[0,1]
	v_pk_mul_f32 v[20:21], v[6:7], v[20:21] op_sel_hi:[0,1]
	v_pk_mul_f32 v[22:23], v[6:7], v[22:23] op_sel_hi:[0,1]
	v_pk_mul_f32 v[36:37], v[6:7], v[36:37] op_sel_hi:[0,1]
	v_pk_mul_f32 v[38:39], v[6:7], v[38:39] op_sel_hi:[0,1]
	v_pk_mul_f32 v[32:33], v[6:7], v[32:33] op_sel_hi:[0,1]
	v_pk_mul_f32 v[8:9], v[6:7], v[8:9] op_sel_hi:[0,1]
	v_pk_mul_f32 v[28:29], v[6:7], v[28:29] op_sel_hi:[0,1]
	v_pk_mul_f32 v[30:31], v[6:7], v[30:31] op_sel_hi:[0,1]
	v_pk_mul_f32 v[26:27], v[6:7], v[26:27] op_sel_hi:[0,1]
	v_pk_mul_f32 v[4:5], v[6:7], v[4:5] op_sel_hi:[0,1]
	v_pk_mul_f32 v[16:17], v[6:7], v[16:17] op_sel_hi:[0,1]
	v_pk_mul_f32 v[18:19], v[6:7], v[18:19] op_sel_hi:[0,1]
	v_pk_mul_f32 v[14:15], v[6:7], v[14:15] op_sel_hi:[0,1]
	v_pk_mul_f32 v[2:3], v[6:7], v[2:3] op_sel_hi:[0,1]
	v_lshl_add_u64 v[6:7], s[12:13], 3, v[12:13]
	global_store_dwordx2 v[6:7], v[34:35], off
	v_add_co_u32_e32 v34, vcc, s57, v6
	s_nop 1
	v_addc_co_u32_e32 v35, vcc, 0, v7, vcc
	global_store_dwordx2 v[34:35], v[24:25], off offset:-4096
	global_store_dwordx2 v[34:35], v[20:21], off
	v_add_co_u32_e32 v20, vcc, s58, v6
	s_nop 1
	v_addc_co_u32_e32 v21, vcc, 0, v7, vcc
	global_store_dwordx2 v[20:21], v[22:23], off offset:-4096
	global_store_dwordx2 v[20:21], v[36:37], off
	v_add_co_u32_e32 v20, vcc, s59, v6
	s_nop 1
	v_addc_co_u32_e32 v21, vcc, 0, v7, vcc
	global_store_dwordx2 v[20:21], v[38:39], off offset:-4096
	global_store_dwordx2 v[20:21], v[32:33], off
	v_add_co_u32_e32 v20, vcc, s60, v6
	s_nop 1
	v_addc_co_u32_e32 v21, vcc, 0, v7, vcc
	global_store_dwordx2 v[20:21], v[8:9], off offset:-4096
	global_store_dwordx2 v[20:21], v[28:29], off
	v_add_co_u32_e32 v8, vcc, s61, v6
	s_nop 1
	v_addc_co_u32_e32 v9, vcc, 0, v7, vcc
	global_store_dwordx2 v[8:9], v[30:31], off offset:-4096
	global_store_dwordx2 v[8:9], v[26:27], off
	v_add_co_u32_e32 v8, vcc, s62, v6
	s_nop 1
	v_addc_co_u32_e32 v9, vcc, 0, v7, vcc
	global_store_dwordx2 v[8:9], v[4:5], off offset:-4096
	global_store_dwordx2 v[8:9], v[16:17], off
	v_add_co_u32_e32 v4, vcc, s63, v6
	s_nop 1
	v_addc_co_u32_e32 v5, vcc, 0, v7, vcc
	global_store_dwordx2 v[4:5], v[18:19], off
	v_add_co_u32_e32 v4, vcc, 0xe000, v6
	s_nop 1
	v_addc_co_u32_e32 v5, vcc, 0, v7, vcc
	global_store_dwordx2 v[4:5], v[14:15], off
	v_add_co_u32_e32 v4, vcc, 0xf000, v6
	s_nop 1
	v_addc_co_u32_e32 v5, vcc, 0, v7, vcc
	s_and_b64 vcc, exec, s[50:51]
	global_store_dwordx2 v[4:5], v[2:3], off
	s_barrier
	s_cbranch_vccnz .LBB0_3098

.LBB0_3363:
	s_or_b64 exec, exec, s[0:1]
	v_pk_add_f32 v[44:45], v[42:43], v[60:61]
	v_pk_add_f32 v[42:43], v[42:43], v[60:61] neg_lo:[0,1] neg_hi:[0,1]
	v_pk_add_f32 v[60:61], v[52:53], v[68:69]
	v_pk_add_f32 v[52:53], v[52:53], v[68:69] neg_lo:[0,1] neg_hi:[0,1]
	v_pk_add_f32 v[68:69], v[44:45], v[60:61]
	v_pk_add_f32 v[60:61], v[44:45], v[60:61] neg_lo:[0,1] neg_hi:[0,1]
	s_waitcnt lgkmcnt(1)
	v_pk_add_f32 v[76:77], v[42:43], v[52:53] op_sel:[0,1] op_sel_hi:[1,0] neg_hi:[0,1]
	s_waitcnt lgkmcnt(0)
	v_pk_add_f32 v[78:79], v[42:43], v[52:53] op_sel:[0,1] op_sel_hi:[1,0] neg_lo:[0,1]
	v_pk_add_f32 v[42:43], v[46:47], v[62:63]
	v_pk_add_f32 v[44:45], v[46:47], v[62:63] neg_lo:[0,1] neg_hi:[0,1]
	v_pk_add_f32 v[46:47], v[54:55], v[70:71]
	v_pk_add_f32 v[52:53], v[54:55], v[70:71] neg_lo:[0,1] neg_hi:[0,1]
	v_pk_add_f32 v[54:55], v[42:43], v[46:47]
	v_pk_add_f32 v[46:47], v[42:43], v[46:47] neg_lo:[0,1] neg_hi:[0,1]
	v_pk_add_f32 v[42:43], v[44:45], v[52:53] op_sel:[0,1] op_sel_hi:[1,0] neg_hi:[0,1]
	v_pk_add_f32 v[52:53], v[44:45], v[52:53] op_sel:[0,1] op_sel_hi:[1,0] neg_lo:[0,1]
	v_pk_add_f32 v[44:45], v[48:49], v[64:65]
	v_pk_add_f32 v[48:49], v[48:49], v[64:65] neg_lo:[0,1] neg_hi:[0,1]
	v_pk_add_f32 v[62:63], v[56:57], v[72:73]
	v_pk_add_f32 v[56:57], v[56:57], v[72:73] neg_lo:[0,1] neg_hi:[0,1]
	v_pk_add_f32 v[64:65], v[44:45], v[62:63]
	v_pk_add_f32 v[62:63], v[44:45], v[62:63] neg_lo:[0,1] neg_hi:[0,1]
	v_pk_add_f32 v[70:71], v[48:49], v[56:57] op_sel:[0,1] op_sel_hi:[1,0] neg_hi:[0,1]
	v_pk_add_f32 v[56:57], v[48:49], v[56:57] op_sel:[0,1] op_sel_hi:[1,0] neg_lo:[0,1]
	v_pk_add_f32 v[44:45], v[50:51], v[66:67]
	v_pk_add_f32 v[48:49], v[50:51], v[66:67] neg_lo:[0,1] neg_hi:[0,1]
	v_pk_add_f32 v[50:51], v[58:59], v[74:75]
	v_pk_add_f32 v[58:59], v[58:59], v[74:75] neg_lo:[0,1] neg_hi:[0,1]
	v_pk_add_f32 v[66:67], v[44:45], v[50:51]
	v_pk_add_f32 v[72:73], v[44:45], v[50:51] neg_lo:[0,1] neg_hi:[0,1]
	v_pk_add_f32 v[50:51], v[48:49], v[58:59] op_sel:[0,1] op_sel_hi:[1,0] neg_hi:[0,1]
	v_pk_add_f32 v[58:59], v[48:49], v[58:59] op_sel:[0,1] op_sel_hi:[1,0] neg_lo:[0,1]
	v_mov_b64_e32 v[48:49], s[20:21]
	v_pk_mul_f32 v[44:45], v[42:43], v[48:49] op_sel:[0,0] op_sel_hi:[0,1]
	v_pk_fma_f32 v[74:75], v[42:43], v[48:49], v[44:45] op_sel:[1,1,0] op_sel_hi:[1,0,1] neg_lo:[0,1,0]
	v_mov_b64_e32 v[44:45], s[46:47]
	v_pk_mul_f32 v[42:43], v[70:71], v[44:45] op_sel:[0,0] op_sel_hi:[0,1]
	s_barrier
	v_pk_fma_f32 v[70:71], v[70:71], v[44:45], v[42:43] op_sel:[1,1,0] op_sel_hi:[1,0,1] neg_lo:[0,1,0]
	v_mov_b64_e32 v[42:43], s[50:51]
	s_waitcnt vmcnt(5)
	v_pk_mul_f32 v[80:81], v[50:51], v[42:43] op_sel:[0,0] op_sel_hi:[0,1]
	v_pk_fma_f32 v[80:81], v[50:51], v[42:43], v[80:81] op_sel:[1,1,0] op_sel_hi:[1,0,1] neg_lo:[0,1,0]
	v_pk_mul_f32 v[50:51], v[46:47], v[44:45] op_sel:[0,0] op_sel_hi:[0,1]
	s_lshl_b64 s[0:1], s[70:71], 14
	v_pk_fma_f32 v[82:83], v[46:47], v[44:45], v[50:51] op_sel:[1,1,0] op_sel_hi:[1,0,1] neg_lo:[0,1,0]
	v_mov_b64_e32 v[50:51], s[8:9]
	v_pk_mul_f32 v[46:47], v[62:63], v[50:51] op_sel:[0,0] op_sel_hi:[0,1]
	s_add_u32 s0, s96, s0
	v_pk_fma_f32 v[62:63], v[62:63], v[50:51], v[46:47] op_sel:[1,1,0] op_sel_hi:[1,0,1] neg_lo:[0,1,0]
	v_mov_b64_e32 v[46:47], s[54:55]
	s_waitcnt vmcnt(4)
	v_pk_mul_f32 v[84:85], v[72:73], v[46:47] op_sel:[0,0] op_sel_hi:[0,1]
	v_lshlrev_b32_e32 v34, 14, v133
	v_pk_fma_f32 v[72:73], v[72:73], v[46:47], v[84:85] op_sel:[1,1,0] op_sel_hi:[1,0,1] neg_lo:[0,1,0]
	v_pk_mul_f32 v[84:85], v[52:53], v[42:43] op_sel:[0,0] op_sel_hi:[0,1]
	s_addc_u32 s1, s97, s1
	v_pk_fma_f32 v[84:85], v[52:53], v[42:43], v[84:85] op_sel:[1,1,0] op_sel_hi:[1,0,1] neg_lo:[0,1,0]
	v_pk_mul_f32 v[52:53], v[56:57], v[46:47] op_sel:[0,0] op_sel_hi:[0,1]
	v_and_b32_e32 v139, 0xffc00000, v34
	v_pk_fma_f32 v[56:57], v[56:57], v[46:47], v[52:53] op_sel:[1,1,0] op_sel_hi:[1,0,1] neg_lo:[0,1,0]
	v_mov_b64_e32 v[52:53], s[56:57]
	v_pk_mul_f32 v[86:87], v[58:59], v[52:53] op_sel:[0,0] op_sel_hi:[0,1]
	s_add_u32 s0, s0, 0x2000000
	v_pk_fma_f32 v[58:59], v[58:59], v[52:53], v[86:87] op_sel:[1,1,0] op_sel_hi:[1,0,1] neg_lo:[0,1,0]
	v_pk_add_f32 v[86:87], v[68:69], v[64:65]
	v_pk_add_f32 v[64:65], v[68:69], v[64:65] neg_lo:[0,1] neg_hi:[0,1]
	v_pk_add_f32 v[68:69], v[54:55], v[66:67]
	v_pk_add_f32 v[54:55], v[54:55], v[66:67] neg_lo:[0,1] neg_hi:[0,1]
	v_pk_add_f32 v[66:67], v[86:87], v[68:69]
	v_pk_add_f32 v[68:69], v[86:87], v[68:69] neg_lo:[0,1] neg_hi:[0,1]
	v_pk_add_f32 v[86:87], v[64:65], v[54:55] op_sel:[0,1] op_sel_hi:[1,0] neg_hi:[0,1]
	v_pk_add_f32 v[54:55], v[64:65], v[54:55] op_sel:[0,1] op_sel_hi:[1,0] neg_lo:[0,1]
	v_pk_add_f32 v[64:65], v[76:77], v[70:71]
	v_pk_add_f32 v[70:71], v[76:77], v[70:71] neg_lo:[0,1] neg_hi:[0,1]
	v_pk_add_f32 v[76:77], v[74:75], v[80:81]
	v_pk_add_f32 v[74:75], v[74:75], v[80:81] neg_lo:[0,1] neg_hi:[0,1]
	v_pk_add_f32 v[80:81], v[64:65], v[76:77]
	v_pk_add_f32 v[64:65], v[64:65], v[76:77] neg_lo:[0,1] neg_hi:[0,1]
	v_pk_add_f32 v[76:77], v[70:71], v[74:75] op_sel:[0,1] op_sel_hi:[1,0] neg_hi:[0,1]
	v_pk_add_f32 v[70:71], v[70:71], v[74:75] op_sel:[0,1] op_sel_hi:[1,0] neg_lo:[0,1]
	v_pk_add_f32 v[74:75], v[60:61], v[62:63]
	v_pk_add_f32 v[60:61], v[60:61], v[62:63] neg_lo:[0,1] neg_hi:[0,1]
	v_pk_add_f32 v[62:63], v[82:83], v[72:73]
	v_pk_add_f32 v[72:73], v[82:83], v[72:73] neg_lo:[0,1] neg_hi:[0,1]
	v_pk_add_f32 v[82:83], v[74:75], v[62:63]
	v_pk_add_f32 v[62:63], v[74:75], v[62:63] neg_lo:[0,1] neg_hi:[0,1]
	v_pk_add_f32 v[74:75], v[60:61], v[72:73] op_sel:[0,1] op_sel_hi:[1,0] neg_hi:[0,1]
	v_pk_add_f32 v[60:61], v[60:61], v[72:73] op_sel:[0,1] op_sel_hi:[1,0] neg_lo:[0,1]
	v_pk_add_f32 v[72:73], v[78:79], v[56:57]
	v_pk_add_f32 v[56:57], v[78:79], v[56:57] neg_lo:[0,1] neg_hi:[0,1]
	v_pk_add_f32 v[78:79], v[84:85], v[58:59]
	v_pk_add_f32 v[58:59], v[84:85], v[58:59] neg_lo:[0,1] neg_hi:[0,1]
	v_pk_add_f32 v[84:85], v[72:73], v[78:79]
	v_pk_add_f32 v[72:73], v[72:73], v[78:79] neg_lo:[0,1] neg_hi:[0,1]
	v_pk_add_f32 v[78:79], v[56:57], v[58:59] op_sel:[0,1] op_sel_hi:[1,0] neg_hi:[0,1]
	v_pk_add_f32 v[56:57], v[56:57], v[58:59] op_sel:[0,1] op_sel_hi:[1,0] neg_lo:[0,1]
	v_xor_b32_e32 v59, 0x80000000, v39
	v_mov_b32_e32 v58, v38
	ds_write_b64 v132, v[66:67]
	v_pk_mul_f32 v[66:67], v[80:81], v[58:59] op_sel:[0,0] op_sel_hi:[0,1]
	s_addc_u32 s1, s1, 0
	v_pk_fma_f32 v[66:67], v[80:81], v[58:59], v[66:67] op_sel:[1,1,0] op_sel_hi:[1,0,1] neg_lo:[0,1,0]
	ds_write_b64 v132, v[66:67] offset:2176
	v_pk_mul_f32 v[66:67], v[58:59], v[58:59] op_sel:[0,0] op_sel_hi:[0,1]
	v_pk_fma_f32 v[66:67], v[58:59], v[58:59], v[66:67] op_sel:[1,1,0] op_sel_hi:[1,0,1] neg_lo:[0,1,0]
	v_pk_mul_f32 v[80:81], v[82:83], v[66:67] op_sel:[0,0] op_sel_hi:[0,1]
	v_pk_fma_f32 v[80:81], v[82:83], v[66:67], v[80:81] op_sel:[1,1,0] op_sel_hi:[1,0,1] neg_lo:[0,1,0]
	ds_write_b64 v132, v[80:81] offset:4352
	v_pk_mul_f32 v[80:81], v[66:67], v[58:59] op_sel:[0,0] op_sel_hi:[0,1]
	v_pk_fma_f32 v[66:67], v[66:67], v[58:59], v[80:81] op_sel:[1,1,0] op_sel_hi:[1,0,1] neg_lo:[0,1,0]
	v_pk_mul_f32 v[80:81], v[84:85], v[66:67] op_sel:[0,0] op_sel_hi:[0,1]
	v_pk_fma_f32 v[80:81], v[84:85], v[66:67], v[80:81] op_sel:[1,1,0] op_sel_hi:[1,0,1] neg_lo:[0,1,0]
	ds_write_b64 v132, v[80:81] offset:6528
	v_pk_mul_f32 v[80:81], v[66:67], v[58:59] op_sel:[0,0] op_sel_hi:[0,1]
	v_pk_fma_f32 v[66:67], v[66:67], v[58:59], v[80:81] op_sel:[1,1,0] op_sel_hi:[1,0,1] neg_lo:[0,1,0]
	v_pk_mul_f32 v[80:81], v[86:87], v[66:67] op_sel:[0,0] op_sel_hi:[0,1]
	v_pk_fma_f32 v[80:81], v[86:87], v[66:67], v[80:81] op_sel:[1,1,0] op_sel_hi:[1,0,1] neg_lo:[0,1,0]
	ds_write_b64 v132, v[80:81] offset:8704
	v_pk_mul_f32 v[80:81], v[66:67], v[58:59] op_sel:[0,0] op_sel_hi:[0,1]
	v_pk_fma_f32 v[66:67], v[66:67], v[58:59], v[80:81] op_sel:[1,1,0] op_sel_hi:[1,0,1] neg_lo:[0,1,0]
	v_pk_mul_f32 v[80:81], v[76:77], v[66:67] op_sel:[0,0] op_sel_hi:[0,1]
	v_pk_fma_f32 v[76:77], v[76:77], v[66:67], v[80:81] op_sel:[1,1,0] op_sel_hi:[1,0,1] neg_lo:[0,1,0]
	ds_write_b64 v132, v[76:77] offset:10880
	v_pk_mul_f32 v[76:77], v[66:67], v[58:59] op_sel:[0,0] op_sel_hi:[0,1]
	v_pk_fma_f32 v[66:67], v[66:67], v[58:59], v[76:77] op_sel:[1,1,0] op_sel_hi:[1,0,1] neg_lo:[0,1,0]
	v_pk_mul_f32 v[76:77], v[74:75], v[66:67] op_sel:[0,0] op_sel_hi:[0,1]
	v_pk_fma_f32 v[74:75], v[74:75], v[66:67], v[76:77] op_sel:[1,1,0] op_sel_hi:[1,0,1] neg_lo:[0,1,0]
	ds_write_b64 v132, v[74:75] offset:13056
	v_pk_mul_f32 v[74:75], v[66:67], v[58:59] op_sel:[0,0] op_sel_hi:[0,1]
	v_pk_fma_f32 v[66:67], v[66:67], v[58:59], v[74:75] op_sel:[1,1,0] op_sel_hi:[1,0,1] neg_lo:[0,1,0]
	v_pk_mul_f32 v[74:75], v[78:79], v[66:67] op_sel:[0,0] op_sel_hi:[0,1]
	v_pk_fma_f32 v[74:75], v[78:79], v[66:67], v[74:75] op_sel:[1,1,0] op_sel_hi:[1,0,1] neg_lo:[0,1,0]
	ds_write_b64 v132, v[74:75] offset:15232
	v_pk_mul_f32 v[74:75], v[66:67], v[58:59] op_sel:[0,0] op_sel_hi:[0,1]
	v_pk_fma_f32 v[66:67], v[66:67], v[58:59], v[74:75] op_sel:[1,1,0] op_sel_hi:[1,0,1] neg_lo:[0,1,0]
	v_pk_mul_f32 v[74:75], v[68:69], v[66:67] op_sel:[0,0] op_sel_hi:[0,1]
	v_pk_fma_f32 v[68:69], v[68:69], v[66:67], v[74:75] op_sel:[1,1,0] op_sel_hi:[1,0,1] neg_lo:[0,1,0]
	ds_write_b64 v132, v[68:69] offset:17408
	v_pk_mul_f32 v[68:69], v[66:67], v[58:59] op_sel:[0,0] op_sel_hi:[0,1]
	v_pk_fma_f32 v[66:67], v[66:67], v[58:59], v[68:69] op_sel:[1,1,0] op_sel_hi:[1,0,1] neg_lo:[0,1,0]
	v_pk_mul_f32 v[68:69], v[64:65], v[66:67] op_sel:[0,0] op_sel_hi:[0,1]
	v_pk_fma_f32 v[64:65], v[64:65], v[66:67], v[68:69] op_sel:[1,1,0] op_sel_hi:[1,0,1] neg_lo:[0,1,0]
	ds_write_b64 v132, v[64:65] offset:19584
	v_pk_mul_f32 v[64:65], v[66:67], v[58:59] op_sel:[0,0] op_sel_hi:[0,1]
	v_pk_fma_f32 v[64:65], v[66:67], v[58:59], v[64:65] op_sel:[1,1,0] op_sel_hi:[1,0,1] neg_lo:[0,1,0]
	v_pk_mul_f32 v[66:67], v[62:63], v[64:65] op_sel:[0,0] op_sel_hi:[0,1]
	v_pk_fma_f32 v[62:63], v[62:63], v[64:65], v[66:67] op_sel:[1,1,0] op_sel_hi:[1,0,1] neg_lo:[0,1,0]
	ds_write_b64 v132, v[62:63] offset:21760
	v_pk_mul_f32 v[62:63], v[64:65], v[58:59] op_sel:[0,0] op_sel_hi:[0,1]
	v_pk_fma_f32 v[62:63], v[64:65], v[58:59], v[62:63] op_sel:[1,1,0] op_sel_hi:[1,0,1] neg_lo:[0,1,0]
	v_pk_mul_f32 v[64:65], v[72:73], v[62:63] op_sel:[0,0] op_sel_hi:[0,1]
	v_pk_fma_f32 v[64:65], v[72:73], v[62:63], v[64:65] op_sel:[1,1,0] op_sel_hi:[1,0,1] neg_lo:[0,1,0]
	ds_write_b64 v132, v[64:65] offset:23936
	v_pk_mul_f32 v[64:65], v[62:63], v[58:59] op_sel:[0,0] op_sel_hi:[0,1]
	v_pk_fma_f32 v[62:63], v[62:63], v[58:59], v[64:65] op_sel:[1,1,0] op_sel_hi:[1,0,1] neg_lo:[0,1,0]
	v_pk_mul_f32 v[64:65], v[54:55], v[62:63] op_sel:[0,0] op_sel_hi:[0,1]
	v_pk_fma_f32 v[54:55], v[54:55], v[62:63], v[64:65] op_sel:[1,1,0] op_sel_hi:[1,0,1] neg_lo:[0,1,0]
	ds_write_b64 v132, v[54:55] offset:26112
	v_pk_mul_f32 v[54:55], v[62:63], v[58:59] op_sel:[0,0] op_sel_hi:[0,1]
	v_pk_fma_f32 v[54:55], v[62:63], v[58:59], v[54:55] op_sel:[1,1,0] op_sel_hi:[1,0,1] neg_lo:[0,1,0]
	v_pk_mul_f32 v[62:63], v[70:71], v[54:55] op_sel:[0,0] op_sel_hi:[0,1]
	v_pk_fma_f32 v[62:63], v[70:71], v[54:55], v[62:63] op_sel:[1,1,0] op_sel_hi:[1,0,1] neg_lo:[0,1,0]
	ds_write_b64 v132, v[62:63] offset:28288
	v_pk_mul_f32 v[62:63], v[54:55], v[58:59] op_sel:[0,0] op_sel_hi:[0,1]
	v_pk_fma_f32 v[54:55], v[54:55], v[58:59], v[62:63] op_sel:[1,1,0] op_sel_hi:[1,0,1] neg_lo:[0,1,0]
	v_pk_mul_f32 v[62:63], v[60:61], v[54:55] op_sel:[0,0] op_sel_hi:[0,1]
	v_pk_fma_f32 v[60:61], v[60:61], v[54:55], v[62:63] op_sel:[1,1,0] op_sel_hi:[1,0,1] neg_lo:[0,1,0]
	ds_write_b64 v132, v[60:61] offset:30464
	v_pk_mul_f32 v[60:61], v[54:55], v[58:59] op_sel:[0,0] op_sel_hi:[0,1]
	v_pk_fma_f32 v[54:55], v[54:55], v[58:59], v[60:61] op_sel:[1,1,0] op_sel_hi:[1,0,1] neg_lo:[0,1,0]
	v_pk_mul_f32 v[58:59], v[56:57], v[54:55] op_sel:[0,0] op_sel_hi:[0,1]
	v_pk_fma_f32 v[54:55], v[56:57], v[54:55], v[58:59] op_sel:[1,1,0] op_sel_hi:[1,0,1] neg_lo:[0,1,0]
	ds_write_b64 v132, v[54:55] offset:32640
	s_waitcnt lgkmcnt(0)
	s_barrier
	ds_read2_b64 v[54:57], v134 offset1:17
	ds_read2_b64 v[58:61], v134 offset0:34 offset1:51
	ds_read2_b64 v[62:65], v134 offset0:68 offset1:85
	ds_read2_b64 v[66:69], v134 offset0:136 offset1:153
	ds_read2_b64 v[70:73], v134 offset0:102 offset1:119
	ds_read2_b64 v[74:77], v134 offset0:204 offset1:221
	ds_read2_b64 v[78:81], v134 offset0:170 offset1:187
	ds_read2_b64 v[82:85], v134 offset0:238 offset1:255
	s_waitcnt lgkmcnt(4)
	v_pk_add_f32 v[86:87], v[54:55], v[66:67]
	v_pk_add_f32 v[54:55], v[54:55], v[66:67] neg_lo:[0,1] neg_hi:[0,1]
	s_waitcnt lgkmcnt(2)
	v_pk_add_f32 v[66:67], v[62:63], v[74:75]
	v_pk_add_f32 v[62:63], v[62:63], v[74:75] neg_lo:[0,1] neg_hi:[0,1]
	v_pk_add_f32 v[74:75], v[86:87], v[66:67]
	v_pk_add_f32 v[66:67], v[86:87], v[66:67] neg_lo:[0,1] neg_hi:[0,1]
	v_pk_add_f32 v[86:87], v[54:55], v[62:63] op_sel:[0,1] op_sel_hi:[1,0] neg_hi:[0,1]
	v_pk_add_f32 v[54:55], v[54:55], v[62:63] op_sel:[0,1] op_sel_hi:[1,0] neg_lo:[0,1]
	v_pk_add_f32 v[62:63], v[56:57], v[68:69]
	v_pk_add_f32 v[56:57], v[56:57], v[68:69] neg_lo:[0,1] neg_hi:[0,1]
	v_pk_add_f32 v[68:69], v[64:65], v[76:77]
	v_pk_add_f32 v[64:65], v[64:65], v[76:77] neg_lo:[0,1] neg_hi:[0,1]
	v_pk_add_f32 v[76:77], v[62:63], v[68:69]
	v_pk_add_f32 v[62:63], v[62:63], v[68:69] neg_lo:[0,1] neg_hi:[0,1]
	v_pk_add_f32 v[68:69], v[56:57], v[64:65] op_sel:[0,1] op_sel_hi:[1,0] neg_hi:[0,1]
	v_pk_add_f32 v[56:57], v[56:57], v[64:65] op_sel:[0,1] op_sel_hi:[1,0] neg_lo:[0,1]
	s_waitcnt lgkmcnt(1)
	v_pk_add_f32 v[64:65], v[58:59], v[78:79]
	v_pk_add_f32 v[58:59], v[58:59], v[78:79] neg_lo:[0,1] neg_hi:[0,1]
	s_waitcnt lgkmcnt(0)
	v_pk_add_f32 v[78:79], v[70:71], v[82:83]
	v_pk_add_f32 v[70:71], v[70:71], v[82:83] neg_lo:[0,1] neg_hi:[0,1]
	v_pk_add_f32 v[82:83], v[64:65], v[78:79]
	v_pk_add_f32 v[64:65], v[64:65], v[78:79] neg_lo:[0,1] neg_hi:[0,1]
	v_pk_add_f32 v[78:79], v[58:59], v[70:71] op_sel:[0,1] op_sel_hi:[1,0] neg_hi:[0,1]
	v_pk_add_f32 v[58:59], v[58:59], v[70:71] op_sel:[0,1] op_sel_hi:[1,0] neg_lo:[0,1]
	v_pk_add_f32 v[70:71], v[60:61], v[80:81]
	v_pk_add_f32 v[60:61], v[60:61], v[80:81] neg_lo:[0,1] neg_hi:[0,1]
	v_pk_add_f32 v[80:81], v[72:73], v[84:85]
	v_pk_add_f32 v[72:73], v[72:73], v[84:85] neg_lo:[0,1] neg_hi:[0,1]
	v_pk_add_f32 v[84:85], v[70:71], v[80:81]
	v_pk_add_f32 v[70:71], v[70:71], v[80:81] neg_lo:[0,1] neg_hi:[0,1]
	v_pk_add_f32 v[80:81], v[60:61], v[72:73] op_sel:[0,1] op_sel_hi:[1,0] neg_hi:[0,1]
	v_pk_add_f32 v[60:61], v[60:61], v[72:73] op_sel:[0,1] op_sel_hi:[1,0] neg_lo:[0,1]
	v_pk_mul_f32 v[72:73], v[68:69], v[48:49] op_sel:[0,0] op_sel_hi:[0,1]
	v_pk_fma_f32 v[68:69], v[68:69], v[48:49], v[72:73] op_sel:[1,1,0] op_sel_hi:[1,0,1] neg_lo:[0,1,0]
	v_pk_mul_f32 v[72:73], v[78:79], v[44:45] op_sel:[0,0] op_sel_hi:[0,1]
	v_pk_fma_f32 v[72:73], v[78:79], v[44:45], v[72:73] op_sel:[1,1,0] op_sel_hi:[1,0,1] neg_lo:[0,1,0]
	v_pk_mul_f32 v[78:79], v[80:81], v[42:43] op_sel:[0,0] op_sel_hi:[0,1]
	v_pk_fma_f32 v[78:79], v[80:81], v[42:43], v[78:79] op_sel:[1,1,0] op_sel_hi:[1,0,1] neg_lo:[0,1,0]
	v_pk_mul_f32 v[80:81], v[62:63], v[44:45] op_sel:[0,0] op_sel_hi:[0,1]
	v_pk_fma_f32 v[62:63], v[62:63], v[44:45], v[80:81] op_sel:[1,1,0] op_sel_hi:[1,0,1] neg_lo:[0,1,0]
	v_pk_mul_f32 v[80:81], v[64:65], v[50:51] op_sel:[0,0] op_sel_hi:[0,1]
	v_pk_fma_f32 v[64:65], v[64:65], v[50:51], v[80:81] op_sel:[1,1,0] op_sel_hi:[1,0,1] neg_lo:[0,1,0]
	v_pk_mul_f32 v[80:81], v[70:71], v[46:47] op_sel:[0,0] op_sel_hi:[0,1]
	v_pk_fma_f32 v[70:71], v[70:71], v[46:47], v[80:81] op_sel:[1,1,0] op_sel_hi:[1,0,1] neg_lo:[0,1,0]
	v_pk_mul_f32 v[80:81], v[56:57], v[42:43] op_sel:[0,0] op_sel_hi:[0,1]
	v_pk_fma_f32 v[56:57], v[56:57], v[42:43], v[80:81] op_sel:[1,1,0] op_sel_hi:[1,0,1] neg_lo:[0,1,0]
	v_pk_mul_f32 v[80:81], v[58:59], v[46:47] op_sel:[0,0] op_sel_hi:[0,1]
	v_pk_fma_f32 v[58:59], v[58:59], v[46:47], v[80:81] op_sel:[1,1,0] op_sel_hi:[1,0,1] neg_lo:[0,1,0]
	v_pk_mul_f32 v[80:81], v[60:61], v[52:53] op_sel:[0,0] op_sel_hi:[0,1]
	v_pk_fma_f32 v[60:61], v[60:61], v[52:53], v[80:81] op_sel:[1,1,0] op_sel_hi:[1,0,1] neg_lo:[0,1,0]
	v_pk_add_f32 v[80:81], v[74:75], v[82:83]
	v_pk_add_f32 v[74:75], v[74:75], v[82:83] neg_lo:[0,1] neg_hi:[0,1]
	v_pk_add_f32 v[82:83], v[76:77], v[84:85]
	v_pk_add_f32 v[76:77], v[76:77], v[84:85] neg_lo:[0,1] neg_hi:[0,1]
	v_pk_add_f32 v[84:85], v[80:81], v[82:83]
	v_pk_add_f32 v[80:81], v[80:81], v[82:83] neg_lo:[0,1] neg_hi:[0,1]
	v_pk_add_f32 v[82:83], v[74:75], v[76:77] op_sel:[0,1] op_sel_hi:[1,0] neg_hi:[0,1]
	v_pk_add_f32 v[74:75], v[74:75], v[76:77] op_sel:[0,1] op_sel_hi:[1,0] neg_lo:[0,1]
	v_pk_add_f32 v[76:77], v[86:87], v[72:73]
	v_pk_add_f32 v[72:73], v[86:87], v[72:73] neg_lo:[0,1] neg_hi:[0,1]
	v_pk_add_f32 v[86:87], v[68:69], v[78:79]
	v_pk_add_f32 v[68:69], v[68:69], v[78:79] neg_lo:[0,1] neg_hi:[0,1]
	v_pk_add_f32 v[78:79], v[76:77], v[86:87]
	v_pk_add_f32 v[76:77], v[76:77], v[86:87] neg_lo:[0,1] neg_hi:[0,1]
	v_pk_add_f32 v[86:87], v[72:73], v[68:69] op_sel:[0,1] op_sel_hi:[1,0] neg_hi:[0,1]
	v_pk_add_f32 v[68:69], v[72:73], v[68:69] op_sel:[0,1] op_sel_hi:[1,0] neg_lo:[0,1]
	v_pk_add_f32 v[72:73], v[66:67], v[64:65]
	v_pk_add_f32 v[64:65], v[66:67], v[64:65] neg_lo:[0,1] neg_hi:[0,1]
	v_pk_add_f32 v[66:67], v[62:63], v[70:71]
	v_pk_add_f32 v[62:63], v[62:63], v[70:71] neg_lo:[0,1] neg_hi:[0,1]
	v_pk_add_f32 v[70:71], v[72:73], v[66:67]
	v_pk_add_f32 v[66:67], v[72:73], v[66:67] neg_lo:[0,1] neg_hi:[0,1]
	v_pk_add_f32 v[72:73], v[64:65], v[62:63] op_sel:[0,1] op_sel_hi:[1,0] neg_hi:[0,1]
	v_pk_add_f32 v[62:63], v[64:65], v[62:63] op_sel:[0,1] op_sel_hi:[1,0] neg_lo:[0,1]
	v_pk_add_f32 v[64:65], v[54:55], v[58:59]
	v_pk_add_f32 v[54:55], v[54:55], v[58:59] neg_lo:[0,1] neg_hi:[0,1]
	v_pk_add_f32 v[58:59], v[56:57], v[60:61]
	v_pk_add_f32 v[56:57], v[56:57], v[60:61] neg_lo:[0,1] neg_hi:[0,1]
	v_pk_add_f32 v[60:61], v[64:65], v[58:59]
	v_pk_add_f32 v[58:59], v[64:65], v[58:59] neg_lo:[0,1] neg_hi:[0,1]
	v_pk_add_f32 v[64:65], v[54:55], v[56:57] op_sel:[0,1] op_sel_hi:[1,0] neg_hi:[0,1]
	v_pk_add_f32 v[54:55], v[54:55], v[56:57] op_sel:[0,1] op_sel_hi:[1,0] neg_lo:[0,1]
	v_xor_b32_e32 v57, 0x80000000, v41
	v_mov_b32_e32 v56, v40
	s_waitcnt vmcnt(1)
	v_pk_mul_f32 v[88:89], v[78:79], v[56:57] op_sel:[0,0] op_sel_hi:[0,1]
	v_pk_fma_f32 v[78:79], v[78:79], v[56:57], v[88:89] op_sel:[1,1,0] op_sel_hi:[1,0,1] neg_lo:[0,1,0]
	ds_write2_b64 v134, v[84:85], v[78:79] offset1:17
	v_pk_mul_f32 v[78:79], v[56:57], v[56:57] op_sel:[0,0] op_sel_hi:[0,1]
	v_pk_fma_f32 v[78:79], v[56:57], v[56:57], v[78:79] op_sel:[1,1,0] op_sel_hi:[1,0,1] neg_lo:[0,1,0]
	v_pk_mul_f32 v[84:85], v[70:71], v[78:79] op_sel:[0,0] op_sel_hi:[0,1]
	v_pk_fma_f32 v[70:71], v[70:71], v[78:79], v[84:85] op_sel:[1,1,0] op_sel_hi:[1,0,1] neg_lo:[0,1,0]
	v_pk_mul_f32 v[84:85], v[78:79], v[56:57] op_sel:[0,0] op_sel_hi:[0,1]
	v_pk_fma_f32 v[78:79], v[78:79], v[56:57], v[84:85] op_sel:[1,1,0] op_sel_hi:[1,0,1] neg_lo:[0,1,0]
	v_pk_mul_f32 v[84:85], v[60:61], v[78:79] op_sel:[0,0] op_sel_hi:[0,1]
	v_pk_fma_f32 v[60:61], v[60:61], v[78:79], v[84:85] op_sel:[1,1,0] op_sel_hi:[1,0,1] neg_lo:[0,1,0]
	ds_write2_b64 v134, v[70:71], v[60:61] offset0:34 offset1:51
	v_pk_mul_f32 v[60:61], v[78:79], v[56:57] op_sel:[0,0] op_sel_hi:[0,1]
	v_pk_fma_f32 v[60:61], v[78:79], v[56:57], v[60:61] op_sel:[1,1,0] op_sel_hi:[1,0,1] neg_lo:[0,1,0]
	v_pk_mul_f32 v[70:71], v[82:83], v[60:61] op_sel:[0,0] op_sel_hi:[0,1]
	v_pk_mul_f32 v[78:79], v[60:61], v[56:57] op_sel:[0,0] op_sel_hi:[0,1]
	v_pk_fma_f32 v[70:71], v[82:83], v[60:61], v[70:71] op_sel:[1,1,0] op_sel_hi:[1,0,1] neg_lo:[0,1,0]
	v_pk_fma_f32 v[60:61], v[60:61], v[56:57], v[78:79] op_sel:[1,1,0] op_sel_hi:[1,0,1] neg_lo:[0,1,0]
	v_pk_mul_f32 v[78:79], v[86:87], v[60:61] op_sel:[0,0] op_sel_hi:[0,1]
	v_pk_fma_f32 v[78:79], v[86:87], v[60:61], v[78:79] op_sel:[1,1,0] op_sel_hi:[1,0,1] neg_lo:[0,1,0]
	ds_write2_b64 v134, v[70:71], v[78:79] offset0:68 offset1:85
	v_pk_mul_f32 v[70:71], v[60:61], v[56:57] op_sel:[0,0] op_sel_hi:[0,1]
	v_pk_fma_f32 v[60:61], v[60:61], v[56:57], v[70:71] op_sel:[1,1,0] op_sel_hi:[1,0,1] neg_lo:[0,1,0]
	v_pk_mul_f32 v[70:71], v[72:73], v[60:61] op_sel:[0,0] op_sel_hi:[0,1]
	v_pk_fma_f32 v[70:71], v[72:73], v[60:61], v[70:71] op_sel:[1,1,0] op_sel_hi:[1,0,1] neg_lo:[0,1,0]
	v_pk_mul_f32 v[72:73], v[60:61], v[56:57] op_sel:[0,0] op_sel_hi:[0,1]
	v_pk_fma_f32 v[60:61], v[60:61], v[56:57], v[72:73] op_sel:[1,1,0] op_sel_hi:[1,0,1] neg_lo:[0,1,0]
	v_pk_mul_f32 v[72:73], v[64:65], v[60:61] op_sel:[0,0] op_sel_hi:[0,1]
	v_pk_fma_f32 v[64:65], v[64:65], v[60:61], v[72:73] op_sel:[1,1,0] op_sel_hi:[1,0,1] neg_lo:[0,1,0]
	ds_write2_b64 v134, v[70:71], v[64:65] offset0:102 offset1:119
	v_pk_mul_f32 v[64:65], v[60:61], v[56:57] op_sel:[0,0] op_sel_hi:[0,1]
	v_pk_fma_f32 v[60:61], v[60:61], v[56:57], v[64:65] op_sel:[1,1,0] op_sel_hi:[1,0,1] neg_lo:[0,1,0]
	v_pk_mul_f32 v[64:65], v[80:81], v[60:61] op_sel:[0,0] op_sel_hi:[0,1]
	v_pk_mul_f32 v[70:71], v[60:61], v[56:57] op_sel:[0,0] op_sel_hi:[0,1]
	v_pk_fma_f32 v[64:65], v[80:81], v[60:61], v[64:65] op_sel:[1,1,0] op_sel_hi:[1,0,1] neg_lo:[0,1,0]
	v_pk_fma_f32 v[60:61], v[60:61], v[56:57], v[70:71] op_sel:[1,1,0] op_sel_hi:[1,0,1] neg_lo:[0,1,0]
	v_pk_mul_f32 v[70:71], v[76:77], v[60:61] op_sel:[0,0] op_sel_hi:[0,1]
	v_pk_fma_f32 v[70:71], v[76:77], v[60:61], v[70:71] op_sel:[1,1,0] op_sel_hi:[1,0,1] neg_lo:[0,1,0]
	ds_write2_b64 v134, v[64:65], v[70:71] offset0:136 offset1:153
	v_pk_mul_f32 v[64:65], v[60:61], v[56:57] op_sel:[0,0] op_sel_hi:[0,1]
	v_pk_fma_f32 v[60:61], v[60:61], v[56:57], v[64:65] op_sel:[1,1,0] op_sel_hi:[1,0,1] neg_lo:[0,1,0]
	v_pk_mul_f32 v[64:65], v[66:67], v[60:61] op_sel:[0,0] op_sel_hi:[0,1]
	v_pk_fma_f32 v[64:65], v[66:67], v[60:61], v[64:65] op_sel:[1,1,0] op_sel_hi:[1,0,1] neg_lo:[0,1,0]
	v_pk_mul_f32 v[66:67], v[60:61], v[56:57] op_sel:[0,0] op_sel_hi:[0,1]
	v_pk_fma_f32 v[60:61], v[60:61], v[56:57], v[66:67] op_sel:[1,1,0] op_sel_hi:[1,0,1] neg_lo:[0,1,0]
	v_pk_mul_f32 v[66:67], v[58:59], v[60:61] op_sel:[0,0] op_sel_hi:[0,1]
	v_pk_fma_f32 v[58:59], v[58:59], v[60:61], v[66:67] op_sel:[1,1,0] op_sel_hi:[1,0,1] neg_lo:[0,1,0]
	ds_write2_b64 v134, v[64:65], v[58:59] offset0:170 offset1:187
	v_pk_mul_f32 v[58:59], v[60:61], v[56:57] op_sel:[0,0] op_sel_hi:[0,1]
	v_pk_fma_f32 v[58:59], v[60:61], v[56:57], v[58:59] op_sel:[1,1,0] op_sel_hi:[1,0,1] neg_lo:[0,1,0]
	v_pk_mul_f32 v[60:61], v[74:75], v[58:59] op_sel:[0,0] op_sel_hi:[0,1]
	v_pk_mul_f32 v[64:65], v[58:59], v[56:57] op_sel:[0,0] op_sel_hi:[0,1]
	v_pk_fma_f32 v[60:61], v[74:75], v[58:59], v[60:61] op_sel:[1,1,0] op_sel_hi:[1,0,1] neg_lo:[0,1,0]
	v_pk_fma_f32 v[58:59], v[58:59], v[56:57], v[64:65] op_sel:[1,1,0] op_sel_hi:[1,0,1] neg_lo:[0,1,0]
	v_pk_mul_f32 v[64:65], v[68:69], v[58:59] op_sel:[0,0] op_sel_hi:[0,1]
	v_pk_fma_f32 v[64:65], v[68:69], v[58:59], v[64:65] op_sel:[1,1,0] op_sel_hi:[1,0,1] neg_lo:[0,1,0]
	ds_write2_b64 v134, v[60:61], v[64:65] offset0:204 offset1:221
	v_pk_mul_f32 v[60:61], v[58:59], v[56:57] op_sel:[0,0] op_sel_hi:[0,1]
	v_pk_fma_f32 v[58:59], v[58:59], v[56:57], v[60:61] op_sel:[1,1,0] op_sel_hi:[1,0,1] neg_lo:[0,1,0]
	v_pk_mul_f32 v[60:61], v[62:63], v[58:59] op_sel:[0,0] op_sel_hi:[0,1]
	v_pk_fma_f32 v[60:61], v[62:63], v[58:59], v[60:61] op_sel:[1,1,0] op_sel_hi:[1,0,1] neg_lo:[0,1,0]
	v_pk_mul_f32 v[62:63], v[58:59], v[56:57] op_sel:[0,0] op_sel_hi:[0,1]
	v_pk_fma_f32 v[56:57], v[58:59], v[56:57], v[62:63] op_sel:[1,1,0] op_sel_hi:[1,0,1] neg_lo:[0,1,0]
	v_pk_mul_f32 v[58:59], v[54:55], v[56:57] op_sel:[0,0] op_sel_hi:[0,1]
	v_pk_fma_f32 v[54:55], v[54:55], v[56:57], v[58:59] op_sel:[1,1,0] op_sel_hi:[1,0,1] neg_lo:[0,1,0]
	ds_write2_b64 v134, v[60:61], v[54:55] offset0:238 offset1:255
	s_waitcnt lgkmcnt(0)
	s_barrier
	ds_read2_b64 v[54:57], v135 offset1:1
	ds_read2_b64 v[58:61], v135 offset0:2 offset1:3
	ds_read2_b64 v[62:65], v135 offset0:8 offset1:9
	ds_read2_b64 v[66:69], v135 offset0:4 offset1:5
	ds_read2_b64 v[80:83], v135 offset0:6 offset1:7
	ds_read2_b64 v[76:79], v135 offset0:12 offset1:13
	ds_read2_b64 v[84:87], v135 offset0:10 offset1:11
	ds_read2_b64 v[88:91], v135 offset0:14 offset1:15
	s_waitcnt lgkmcnt(5)
	v_pk_add_f32 v[70:71], v[54:55], v[62:63]
	v_pk_add_f32 v[54:55], v[54:55], v[62:63] neg_lo:[0,1] neg_hi:[0,1]
	s_waitcnt lgkmcnt(2)
	v_pk_add_f32 v[62:63], v[66:67], v[76:77]
	v_pk_add_f32 v[66:67], v[66:67], v[76:77] neg_lo:[0,1] neg_hi:[0,1]
	v_pk_add_f32 v[76:77], v[70:71], v[62:63]
	v_pk_add_f32 v[70:71], v[70:71], v[62:63] neg_lo:[0,1] neg_hi:[0,1]
	v_pk_add_f32 v[74:75], v[54:55], v[66:67] op_sel:[0,1] op_sel_hi:[1,0] neg_hi:[0,1]
	v_pk_add_f32 v[72:73], v[54:55], v[66:67] op_sel:[0,1] op_sel_hi:[1,0] neg_lo:[0,1]
	v_pk_add_f32 v[54:55], v[56:57], v[64:65]
	v_pk_add_f32 v[56:57], v[56:57], v[64:65] neg_lo:[0,1] neg_hi:[0,1]
	v_pk_add_f32 v[62:63], v[68:69], v[78:79]
	v_pk_add_f32 v[64:65], v[68:69], v[78:79] neg_lo:[0,1] neg_hi:[0,1]
	v_pk_add_f32 v[78:79], v[54:55], v[62:63]
	v_pk_add_f32 v[54:55], v[54:55], v[62:63] neg_lo:[0,1] neg_hi:[0,1]
	v_pk_add_f32 v[62:63], v[56:57], v[64:65] op_sel:[0,1] op_sel_hi:[1,0] neg_hi:[0,1]
	v_pk_add_f32 v[56:57], v[56:57], v[64:65] op_sel:[0,1] op_sel_hi:[1,0] neg_lo:[0,1]
	s_waitcnt lgkmcnt(1)
	v_pk_add_f32 v[64:65], v[58:59], v[84:85]
	v_pk_add_f32 v[58:59], v[58:59], v[84:85] neg_lo:[0,1] neg_hi:[0,1]
	s_waitcnt lgkmcnt(0)
	v_pk_add_f32 v[66:67], v[80:81], v[88:89]
	v_pk_add_f32 v[68:69], v[80:81], v[88:89] neg_lo:[0,1] neg_hi:[0,1]
	v_pk_add_f32 v[80:81], v[64:65], v[66:67]
	v_pk_add_f32 v[64:65], v[64:65], v[66:67] neg_lo:[0,1] neg_hi:[0,1]
	v_pk_add_f32 v[66:67], v[58:59], v[68:69] op_sel:[0,1] op_sel_hi:[1,0] neg_hi:[0,1]
	v_pk_add_f32 v[58:59], v[58:59], v[68:69] op_sel:[0,1] op_sel_hi:[1,0] neg_lo:[0,1]
	v_pk_add_f32 v[68:69], v[60:61], v[86:87]
	v_pk_add_f32 v[84:85], v[82:83], v[90:91]
	v_pk_add_f32 v[60:61], v[60:61], v[86:87] neg_lo:[0,1] neg_hi:[0,1]
	v_pk_add_f32 v[86:87], v[82:83], v[90:91] neg_lo:[0,1] neg_hi:[0,1]
	v_pk_add_f32 v[82:83], v[68:69], v[84:85]
	v_pk_add_f32 v[68:69], v[68:69], v[84:85] neg_lo:[0,1] neg_hi:[0,1]
	v_pk_mul_f32 v[84:85], v[62:63], v[48:49] op_sel:[0,0] op_sel_hi:[0,1]
	v_pk_add_f32 v[88:89], v[60:61], v[86:87] op_sel:[0,1] op_sel_hi:[1,0] neg_hi:[0,1]
	v_pk_add_f32 v[60:61], v[60:61], v[86:87] op_sel:[0,1] op_sel_hi:[1,0] neg_lo:[0,1]
	v_pk_fma_f32 v[84:85], v[62:63], v[48:49], v[84:85] op_sel:[1,1,0] op_sel_hi:[1,0,1] neg_lo:[0,1,0]
	v_pk_mul_f32 v[48:49], v[66:67], v[44:45] op_sel:[0,0] op_sel_hi:[0,1]
	s_barrier
	v_pk_fma_f32 v[86:87], v[66:67], v[44:45], v[48:49] op_sel:[1,1,0] op_sel_hi:[1,0,1] neg_lo:[0,1,0]
	v_pk_mul_f32 v[48:49], v[88:89], v[42:43] op_sel:[0,0] op_sel_hi:[0,1]
	v_pk_fma_f32 v[90:91], v[88:89], v[42:43], v[48:49] op_sel:[1,1,0] op_sel_hi:[1,0,1] neg_lo:[0,1,0]
	v_pk_mul_f32 v[48:49], v[54:55], v[44:45] op_sel:[0,0] op_sel_hi:[0,1]
	v_pk_fma_f32 v[88:89], v[54:55], v[44:45], v[48:49] op_sel:[1,1,0] op_sel_hi:[1,0,1] neg_lo:[0,1,0]
	v_pk_mul_f32 v[44:45], v[64:65], v[50:51] op_sel:[0,0] op_sel_hi:[0,1]
	s_waitcnt vmcnt(0)
	v_pk_fma_f32 v[92:93], v[64:65], v[50:51], v[44:45] op_sel:[1,1,0] op_sel_hi:[1,0,1] neg_lo:[0,1,0]
	v_pk_mul_f32 v[44:45], v[68:69], v[46:47] op_sel:[0,0] op_sel_hi:[0,1]
	v_pk_fma_f32 v[96:97], v[68:69], v[46:47], v[44:45] op_sel:[1,1,0] op_sel_hi:[1,0,1] neg_lo:[0,1,0]
	v_pk_mul_f32 v[44:45], v[56:57], v[42:43] op_sel:[0,0] op_sel_hi:[0,1]
	v_pk_fma_f32 v[94:95], v[56:57], v[42:43], v[44:45] op_sel:[1,1,0] op_sel_hi:[1,0,1] neg_lo:[0,1,0]
	v_pk_mul_f32 v[42:43], v[58:59], v[46:47] op_sel:[0,0] op_sel_hi:[0,1]
	v_pk_add_f32 v[44:45], v[78:79], v[82:83] neg_lo:[0,1] neg_hi:[0,1]
	v_pk_fma_f32 v[100:101], v[58:59], v[46:47], v[42:43] op_sel:[1,1,0] op_sel_hi:[1,0,1] neg_lo:[0,1,0]
	v_pk_mul_f32 v[42:43], v[60:61], v[52:53] op_sel:[0,0] op_sel_hi:[0,1]
	v_pk_fma_f32 v[106:107], v[60:61], v[52:53], v[42:43] op_sel:[1,1,0] op_sel_hi:[1,0,1] neg_lo:[0,1,0]
	v_pk_add_f32 v[42:43], v[76:77], v[80:81] neg_lo:[0,1] neg_hi:[0,1]
	s_nop 0
	v_pk_add_f32 v[98:99], v[42:43], v[44:45] op_sel:[0,1] op_sel_hi:[1,0] neg_hi:[0,1]
	v_pk_add_f32 v[102:103], v[42:43], v[44:45] op_sel:[0,1] op_sel_hi:[1,0] neg_lo:[0,1]
	v_pk_add_f32 v[42:43], v[74:75], v[86:87] neg_lo:[0,1] neg_hi:[0,1]
	v_pk_add_f32 v[44:45], v[84:85], v[90:91] neg_lo:[0,1] neg_hi:[0,1]
	s_nop 0
	v_pk_add_f32 v[104:105], v[42:43], v[44:45] op_sel:[0,1] op_sel_hi:[1,0] neg_hi:[0,1]
	v_pk_add_f32 v[108:109], v[42:43], v[44:45] op_sel:[0,1] op_sel_hi:[1,0] neg_lo:[0,1]
	v_pk_add_f32 v[42:43], v[70:71], v[92:93] neg_lo:[0,1] neg_hi:[0,1]
	v_pk_add_f32 v[44:45], v[88:89], v[96:97] neg_lo:[0,1] neg_hi:[0,1]
	s_nop 0
	v_pk_add_f32 v[110:111], v[42:43], v[44:45] op_sel:[0,1] op_sel_hi:[1,0] neg_hi:[0,1]
	v_pk_add_f32 v[112:113], v[42:43], v[44:45] op_sel:[0,1] op_sel_hi:[1,0] neg_lo:[0,1]
	v_pk_add_f32 v[42:43], v[72:73], v[100:101] neg_lo:[0,1] neg_hi:[0,1]
	v_pk_add_f32 v[44:45], v[94:95], v[106:107] neg_lo:[0,1] neg_hi:[0,1]
	s_nop 0
	v_pk_add_f32 v[114:115], v[42:43], v[44:45] op_sel:[0,1] op_sel_hi:[1,0] neg_hi:[0,1]
	v_pk_add_f32 v[116:117], v[42:43], v[44:45] op_sel:[0,1] op_sel_hi:[1,0] neg_lo:[0,1]
	v_mov_b32_e32 v43, v126
	v_mov_b32_e32 v44, 0
	v_sub_u32_e32 v34, 0x1000, v43
	v_cndmask_b32_e64 v42, v34, v43, s[6:7]
	v_cmp_gt_i32_e32 vcc, s86, v42
	v_mov_b32_e32 v34, 0
	s_and_saveexec_b64 s[82:83], vcc
	s_cbranch_execz .LBB0_3365
	v_add_u32_e32 v46, v42, v139
	v_ashrrev_i32_e32 v47, 31, v46
	v_lshl_add_u64 v[46:47], v[46:47], 2, s[0:1]
	global_load_dword v34, v[46:47], off

.LBB0_3397:
	s_or_b64 exec, exec, s[0:1]
	s_addk_i32 s6, 0x800
	s_waitcnt lgkmcnt(0)
	ds_write_b64 v27, v[98:99]
	s_cmpk_lg_u32 s6, 0x8000
	v_add_u32_e32 v27, 0x880, v27
	v_mov_b64_e32 v[98:99], s[16:17]
	v_pk_mul_f32 v[100:101], v[96:97], v[98:99] op_sel:[0,0] op_sel_hi:[0,1]
	v_pk_fma_f32 v[96:97], v[96:97], v[98:99], v[100:101] op_sel:[1,1,0] op_sel_hi:[1,0,1] neg_lo:[0,1,0]
	s_cbranch_scc0 .LBB0_3400
.LBB0_3398:
	v_add_u32_e32 v43, s6, v109
	ds_read_b64 v[98:99], v43
	s_and_saveexec_b64 s[0:1], s[4:5]
	s_cbranch_execz .LBB0_3397
	s_waitcnt lgkmcnt(0)
	v_pk_mul_f32 v[100:101], v[98:99], v[96:97] op_sel:[0,0] op_sel_hi:[0,1]
	v_pk_fma_f32 v[98:99], v[98:99], v[96:97], v[100:101] op_sel:[1,1,0] op_sel_hi:[1,0,1] neg_lo:[0,1,0]
	s_branch .LBB0_3397
.LBB0_3400:
	ds_read_b64 v[96:97], v132
	ds_read_b64 v[98:99], v132 offset:2176
	ds_read_b64 v[100:101], v132 offset:4352
	ds_read_b64 v[102:103], v132 offset:6528
	ds_read_b64 v[104:105], v132 offset:8704
	ds_read_b64 v[106:107], v132 offset:10880
	ds_read_b64 v[110:111], v132 offset:13056
	ds_read_b64 v[112:113], v132 offset:15232
	ds_read_b64 v[114:115], v132 offset:17408
	ds_read_b64 v[116:117], v132 offset:19584
	ds_read_b64 v[140:141], v132 offset:21760
	ds_read_b64 v[142:143], v132 offset:23936
	ds_read_b64 v[144:145], v132 offset:26112
	ds_read_b64 v[146:147], v132 offset:28288
	ds_read_b64 v[148:149], v132 offset:30464
	ds_read_b64 v[150:151], v132 offset:32640
	s_waitcnt lgkmcnt(7)
	v_pk_add_f32 v[152:153], v[96:97], v[114:115]
	v_pk_add_f32 v[96:97], v[96:97], v[114:115] neg_lo:[0,1] neg_hi:[0,1]
	s_waitcnt lgkmcnt(3)
	v_pk_add_f32 v[114:115], v[104:105], v[144:145]
	v_pk_add_f32 v[104:105], v[104:105], v[144:145] neg_lo:[0,1] neg_hi:[0,1]
	v_pk_add_f32 v[144:145], v[152:153], v[114:115]
	v_pk_add_f32 v[114:115], v[152:153], v[114:115] neg_lo:[0,1] neg_hi:[0,1]
	v_pk_add_f32 v[152:153], v[96:97], v[104:105] op_sel:[0,1] op_sel_hi:[1,0] neg_hi:[0,1]
	v_pk_add_f32 v[154:155], v[96:97], v[104:105] op_sel:[0,1] op_sel_hi:[1,0] neg_lo:[0,1]
	v_pk_add_f32 v[96:97], v[98:99], v[116:117]
	v_pk_add_f32 v[98:99], v[98:99], v[116:117] neg_lo:[0,1] neg_hi:[0,1]
	s_waitcnt lgkmcnt(2)
	v_pk_add_f32 v[104:105], v[106:107], v[146:147]
	v_pk_add_f32 v[106:107], v[106:107], v[146:147] neg_lo:[0,1] neg_hi:[0,1]
	v_pk_add_f32 v[116:117], v[96:97], v[104:105]
	v_pk_add_f32 v[104:105], v[96:97], v[104:105] neg_lo:[0,1] neg_hi:[0,1]
	v_pk_add_f32 v[96:97], v[98:99], v[106:107] op_sel:[0,1] op_sel_hi:[1,0] neg_hi:[0,1]
	v_pk_add_f32 v[106:107], v[98:99], v[106:107] op_sel:[0,1] op_sel_hi:[1,0] neg_lo:[0,1]
	v_pk_add_f32 v[98:99], v[100:101], v[140:141]
	v_pk_add_f32 v[100:101], v[100:101], v[140:141] neg_lo:[0,1] neg_hi:[0,1]
	s_waitcnt lgkmcnt(1)
	v_pk_add_f32 v[140:141], v[110:111], v[148:149]
	v_pk_add_f32 v[110:111], v[110:111], v[148:149] neg_lo:[0,1] neg_hi:[0,1]
	v_pk_add_f32 v[146:147], v[98:99], v[140:141]
	v_pk_add_f32 v[140:141], v[98:99], v[140:141] neg_lo:[0,1] neg_hi:[0,1]
	v_pk_add_f32 v[148:149], v[100:101], v[110:111] op_sel:[0,1] op_sel_hi:[1,0] neg_hi:[0,1]
	v_pk_add_f32 v[110:111], v[100:101], v[110:111] op_sel:[0,1] op_sel_hi:[1,0] neg_lo:[0,1]
	v_pk_add_f32 v[98:99], v[102:103], v[142:143]
	v_pk_add_f32 v[100:101], v[102:103], v[142:143] neg_lo:[0,1] neg_hi:[0,1]
	s_waitcnt lgkmcnt(0)
	v_pk_add_f32 v[102:103], v[112:113], v[150:151]
	v_pk_add_f32 v[112:113], v[112:113], v[150:151] neg_lo:[0,1] neg_hi:[0,1]
	v_pk_add_f32 v[142:143], v[98:99], v[102:103]
	v_pk_add_f32 v[150:151], v[98:99], v[102:103] neg_lo:[0,1] neg_hi:[0,1]
	v_mov_b64_e32 v[102:103], s[20:21]
	v_pk_mul_f32 v[98:99], v[96:97], v[102:103] op_sel:[0,0] op_sel_hi:[0,1]
	v_pk_add_f32 v[156:157], v[100:101], v[112:113] op_sel:[0,1] op_sel_hi:[1,0] neg_hi:[0,1]
	v_pk_add_f32 v[112:113], v[100:101], v[112:113] op_sel:[0,1] op_sel_hi:[1,0] neg_lo:[0,1]
	v_xor_b32_e32 v39, 0x80000000, v39
	v_pk_fma_f32 v[158:159], v[96:97], v[102:103], v[98:99] op_sel:[1,1,0] op_sel_hi:[1,0,1] neg_lo:[0,1,0]
	v_mov_b64_e32 v[98:99], s[46:47]
	v_pk_mul_f32 v[96:97], v[148:149], v[98:99] op_sel:[0,0] op_sel_hi:[0,1]
	v_xor_b32_e32 v41, 0x80000000, v41
	v_pk_fma_f32 v[148:149], v[148:149], v[98:99], v[96:97] op_sel:[1,1,0] op_sel_hi:[1,0,1] neg_lo:[0,1,0]
	v_mov_b64_e32 v[96:97], s[50:51]
	v_pk_mul_f32 v[100:101], v[156:157], v[96:97] op_sel:[0,0] op_sel_hi:[0,1]
	v_pk_fma_f32 v[156:157], v[156:157], v[96:97], v[100:101] op_sel:[1,1,0] op_sel_hi:[1,0,1] neg_lo:[0,1,0]
	v_pk_mul_f32 v[100:101], v[104:105], v[98:99] op_sel:[0,0] op_sel_hi:[0,1]
	v_pk_fma_f32 v[160:161], v[104:105], v[98:99], v[100:101] op_sel:[1,1,0] op_sel_hi:[1,0,1] neg_lo:[0,1,0]
	v_mov_b64_e32 v[104:105], s[8:9]
	v_pk_mul_f32 v[100:101], v[140:141], v[104:105] op_sel:[0,0] op_sel_hi:[0,1]
	v_pk_fma_f32 v[140:141], v[140:141], v[104:105], v[100:101] op_sel:[1,1,0] op_sel_hi:[1,0,1] neg_lo:[0,1,0]
	v_mov_b64_e32 v[100:101], s[54:55]
	v_pk_mul_f32 v[162:163], v[150:151], v[100:101] op_sel:[0,0] op_sel_hi:[0,1]
	v_pk_fma_f32 v[150:151], v[150:151], v[100:101], v[162:163] op_sel:[1,1,0] op_sel_hi:[1,0,1] neg_lo:[0,1,0]
	v_pk_mul_f32 v[162:163], v[106:107], v[96:97] op_sel:[0,0] op_sel_hi:[0,1]
	v_pk_fma_f32 v[162:163], v[106:107], v[96:97], v[162:163] op_sel:[1,1,0] op_sel_hi:[1,0,1] neg_lo:[0,1,0]
	v_pk_mul_f32 v[106:107], v[110:111], v[100:101] op_sel:[0,0] op_sel_hi:[0,1]
	v_pk_fma_f32 v[110:111], v[110:111], v[100:101], v[106:107] op_sel:[1,1,0] op_sel_hi:[1,0,1] neg_lo:[0,1,0]
	v_mov_b64_e32 v[106:107], s[56:57]
	v_pk_mul_f32 v[164:165], v[112:113], v[106:107] op_sel:[0,0] op_sel_hi:[0,1]
	v_pk_fma_f32 v[112:113], v[112:113], v[106:107], v[164:165] op_sel:[1,1,0] op_sel_hi:[1,0,1] neg_lo:[0,1,0]
	v_pk_add_f32 v[164:165], v[144:145], v[146:147]
	v_pk_add_f32 v[144:145], v[144:145], v[146:147] neg_lo:[0,1] neg_hi:[0,1]
	v_pk_add_f32 v[146:147], v[116:117], v[142:143]
	v_pk_add_f32 v[116:117], v[116:117], v[142:143] neg_lo:[0,1] neg_hi:[0,1]
	v_pk_add_f32 v[142:143], v[164:165], v[146:147]
	v_pk_add_f32 v[146:147], v[164:165], v[146:147] neg_lo:[0,1] neg_hi:[0,1]
	v_pk_add_f32 v[164:165], v[144:145], v[116:117] op_sel:[0,1] op_sel_hi:[1,0] neg_hi:[0,1]
	v_pk_add_f32 v[116:117], v[144:145], v[116:117] op_sel:[0,1] op_sel_hi:[1,0] neg_lo:[0,1]
	v_pk_add_f32 v[144:145], v[152:153], v[148:149]
	v_pk_add_f32 v[148:149], v[152:153], v[148:149] neg_lo:[0,1] neg_hi:[0,1]
	v_pk_add_f32 v[152:153], v[158:159], v[156:157]
	v_pk_add_f32 v[156:157], v[158:159], v[156:157] neg_lo:[0,1] neg_hi:[0,1]
	v_pk_add_f32 v[158:159], v[144:145], v[152:153]
	v_pk_add_f32 v[144:145], v[144:145], v[152:153] neg_lo:[0,1] neg_hi:[0,1]
	v_pk_add_f32 v[152:153], v[148:149], v[156:157] op_sel:[0,1] op_sel_hi:[1,0] neg_hi:[0,1]
	v_pk_add_f32 v[148:149], v[148:149], v[156:157] op_sel:[0,1] op_sel_hi:[1,0] neg_lo:[0,1]
	v_pk_add_f32 v[156:157], v[114:115], v[140:141]
	v_pk_add_f32 v[114:115], v[114:115], v[140:141] neg_lo:[0,1] neg_hi:[0,1]
	v_pk_add_f32 v[140:141], v[160:161], v[150:151]
	v_pk_add_f32 v[150:151], v[160:161], v[150:151] neg_lo:[0,1] neg_hi:[0,1]
	v_pk_add_f32 v[160:161], v[156:157], v[140:141]
	v_pk_add_f32 v[140:141], v[156:157], v[140:141] neg_lo:[0,1] neg_hi:[0,1]
	v_pk_add_f32 v[156:157], v[114:115], v[150:151] op_sel:[0,1] op_sel_hi:[1,0] neg_hi:[0,1]
	v_pk_add_f32 v[114:115], v[114:115], v[150:151] op_sel:[0,1] op_sel_hi:[1,0] neg_lo:[0,1]
	v_pk_add_f32 v[150:151], v[154:155], v[110:111]
	v_pk_add_f32 v[110:111], v[154:155], v[110:111] neg_lo:[0,1] neg_hi:[0,1]
	v_pk_add_f32 v[154:155], v[162:163], v[112:113]
	v_pk_add_f32 v[112:113], v[162:163], v[112:113] neg_lo:[0,1] neg_hi:[0,1]
	v_pk_add_f32 v[162:163], v[150:151], v[154:155]
	v_pk_add_f32 v[150:151], v[150:151], v[154:155] neg_lo:[0,1] neg_hi:[0,1]
	v_pk_add_f32 v[154:155], v[110:111], v[112:113] op_sel:[0,1] op_sel_hi:[1,0] neg_hi:[0,1]
	v_pk_add_f32 v[110:111], v[110:111], v[112:113] op_sel:[0,1] op_sel_hi:[1,0] neg_lo:[0,1]
	v_mov_b32_e32 v113, v39
	v_mov_b32_e32 v112, v38
	ds_write_b64 v132, v[142:143]
	v_pk_mul_f32 v[142:143], v[158:159], v[112:113] op_sel:[0,0] op_sel_hi:[0,1]
	v_pk_fma_f32 v[142:143], v[158:159], v[112:113], v[142:143] op_sel:[1,1,0] op_sel_hi:[1,0,1] neg_lo:[0,1,0]
	ds_write_b64 v132, v[142:143] offset:2176
	v_pk_mul_f32 v[142:143], v[112:113], v[112:113] op_sel:[0,0] op_sel_hi:[0,1]
	v_pk_fma_f32 v[142:143], v[112:113], v[112:113], v[142:143] op_sel:[1,1,0] op_sel_hi:[1,0,1] neg_lo:[0,1,0]
	v_pk_mul_f32 v[158:159], v[160:161], v[142:143] op_sel:[0,0] op_sel_hi:[0,1]
	v_pk_fma_f32 v[158:159], v[160:161], v[142:143], v[158:159] op_sel:[1,1,0] op_sel_hi:[1,0,1] neg_lo:[0,1,0]
	ds_write_b64 v132, v[158:159] offset:4352
	v_pk_mul_f32 v[158:159], v[142:143], v[112:113] op_sel:[0,0] op_sel_hi:[0,1]
	v_pk_fma_f32 v[142:143], v[142:143], v[112:113], v[158:159] op_sel:[1,1,0] op_sel_hi:[1,0,1] neg_lo:[0,1,0]
	v_pk_mul_f32 v[158:159], v[162:163], v[142:143] op_sel:[0,0] op_sel_hi:[0,1]
	v_pk_fma_f32 v[158:159], v[162:163], v[142:143], v[158:159] op_sel:[1,1,0] op_sel_hi:[1,0,1] neg_lo:[0,1,0]
	ds_write_b64 v132, v[158:159] offset:6528
	v_pk_mul_f32 v[158:159], v[142:143], v[112:113] op_sel:[0,0] op_sel_hi:[0,1]
	v_pk_fma_f32 v[142:143], v[142:143], v[112:113], v[158:159] op_sel:[1,1,0] op_sel_hi:[1,0,1] neg_lo:[0,1,0]
	v_pk_mul_f32 v[158:159], v[164:165], v[142:143] op_sel:[0,0] op_sel_hi:[0,1]
	v_pk_fma_f32 v[158:159], v[164:165], v[142:143], v[158:159] op_sel:[1,1,0] op_sel_hi:[1,0,1] neg_lo:[0,1,0]
	ds_write_b64 v132, v[158:159] offset:8704
	v_pk_mul_f32 v[158:159], v[142:143], v[112:113] op_sel:[0,0] op_sel_hi:[0,1]
	v_pk_fma_f32 v[142:143], v[142:143], v[112:113], v[158:159] op_sel:[1,1,0] op_sel_hi:[1,0,1] neg_lo:[0,1,0]
	v_pk_mul_f32 v[158:159], v[152:153], v[142:143] op_sel:[0,0] op_sel_hi:[0,1]
	v_pk_fma_f32 v[152:153], v[152:153], v[142:143], v[158:159] op_sel:[1,1,0] op_sel_hi:[1,0,1] neg_lo:[0,1,0]
	ds_write_b64 v132, v[152:153] offset:10880
	v_pk_mul_f32 v[152:153], v[142:143], v[112:113] op_sel:[0,0] op_sel_hi:[0,1]
	v_pk_fma_f32 v[142:143], v[142:143], v[112:113], v[152:153] op_sel:[1,1,0] op_sel_hi:[1,0,1] neg_lo:[0,1,0]
	v_pk_mul_f32 v[152:153], v[156:157], v[142:143] op_sel:[0,0] op_sel_hi:[0,1]
	v_pk_fma_f32 v[152:153], v[156:157], v[142:143], v[152:153] op_sel:[1,1,0] op_sel_hi:[1,0,1] neg_lo:[0,1,0]
	ds_write_b64 v132, v[152:153] offset:13056
	v_pk_mul_f32 v[152:153], v[142:143], v[112:113] op_sel:[0,0] op_sel_hi:[0,1]
	v_pk_fma_f32 v[142:143], v[142:143], v[112:113], v[152:153] op_sel:[1,1,0] op_sel_hi:[1,0,1] neg_lo:[0,1,0]
	v_pk_mul_f32 v[152:153], v[154:155], v[142:143] op_sel:[0,0] op_sel_hi:[0,1]
	v_pk_fma_f32 v[152:153], v[154:155], v[142:143], v[152:153] op_sel:[1,1,0] op_sel_hi:[1,0,1] neg_lo:[0,1,0]
	ds_write_b64 v132, v[152:153] offset:15232
	v_pk_mul_f32 v[152:153], v[142:143], v[112:113] op_sel:[0,0] op_sel_hi:[0,1]
	v_pk_fma_f32 v[142:143], v[142:143], v[112:113], v[152:153] op_sel:[1,1,0] op_sel_hi:[1,0,1] neg_lo:[0,1,0]
	v_pk_mul_f32 v[152:153], v[146:147], v[142:143] op_sel:[0,0] op_sel_hi:[0,1]
	v_pk_fma_f32 v[146:147], v[146:147], v[142:143], v[152:153] op_sel:[1,1,0] op_sel_hi:[1,0,1] neg_lo:[0,1,0]
	ds_write_b64 v132, v[146:147] offset:17408
	v_pk_mul_f32 v[146:147], v[142:143], v[112:113] op_sel:[0,0] op_sel_hi:[0,1]
	v_pk_fma_f32 v[142:143], v[142:143], v[112:113], v[146:147] op_sel:[1,1,0] op_sel_hi:[1,0,1] neg_lo:[0,1,0]
	v_pk_mul_f32 v[146:147], v[144:145], v[142:143] op_sel:[0,0] op_sel_hi:[0,1]
	v_pk_fma_f32 v[144:145], v[144:145], v[142:143], v[146:147] op_sel:[1,1,0] op_sel_hi:[1,0,1] neg_lo:[0,1,0]
	ds_write_b64 v132, v[144:145] offset:19584
	v_pk_mul_f32 v[144:145], v[142:143], v[112:113] op_sel:[0,0] op_sel_hi:[0,1]
	v_pk_fma_f32 v[142:143], v[142:143], v[112:113], v[144:145] op_sel:[1,1,0] op_sel_hi:[1,0,1] neg_lo:[0,1,0]
	v_pk_mul_f32 v[144:145], v[140:141], v[142:143] op_sel:[0,0] op_sel_hi:[0,1]
	v_pk_fma_f32 v[140:141], v[140:141], v[142:143], v[144:145] op_sel:[1,1,0] op_sel_hi:[1,0,1] neg_lo:[0,1,0]
	ds_write_b64 v132, v[140:141] offset:21760
	v_pk_mul_f32 v[140:141], v[142:143], v[112:113] op_sel:[0,0] op_sel_hi:[0,1]
	v_pk_fma_f32 v[140:141], v[142:143], v[112:113], v[140:141] op_sel:[1,1,0] op_sel_hi:[1,0,1] neg_lo:[0,1,0]
	v_pk_mul_f32 v[142:143], v[150:151], v[140:141] op_sel:[0,0] op_sel_hi:[0,1]
	v_pk_fma_f32 v[142:143], v[150:151], v[140:141], v[142:143] op_sel:[1,1,0] op_sel_hi:[1,0,1] neg_lo:[0,1,0]
	ds_write_b64 v132, v[142:143] offset:23936
	v_pk_mul_f32 v[142:143], v[140:141], v[112:113] op_sel:[0,0] op_sel_hi:[0,1]
	v_pk_fma_f32 v[140:141], v[140:141], v[112:113], v[142:143] op_sel:[1,1,0] op_sel_hi:[1,0,1] neg_lo:[0,1,0]
	v_pk_mul_f32 v[142:143], v[116:117], v[140:141] op_sel:[0,0] op_sel_hi:[0,1]
	v_pk_fma_f32 v[116:117], v[116:117], v[140:141], v[142:143] op_sel:[1,1,0] op_sel_hi:[1,0,1] neg_lo:[0,1,0]
	ds_write_b64 v132, v[116:117] offset:26112
	v_pk_mul_f32 v[116:117], v[140:141], v[112:113] op_sel:[0,0] op_sel_hi:[0,1]
	v_pk_fma_f32 v[116:117], v[140:141], v[112:113], v[116:117] op_sel:[1,1,0] op_sel_hi:[1,0,1] neg_lo:[0,1,0]
	v_pk_mul_f32 v[140:141], v[148:149], v[116:117] op_sel:[0,0] op_sel_hi:[0,1]
	v_pk_fma_f32 v[140:141], v[148:149], v[116:117], v[140:141] op_sel:[1,1,0] op_sel_hi:[1,0,1] neg_lo:[0,1,0]
	ds_write_b64 v132, v[140:141] offset:28288
	v_pk_mul_f32 v[140:141], v[116:117], v[112:113] op_sel:[0,0] op_sel_hi:[0,1]
	v_pk_fma_f32 v[116:117], v[116:117], v[112:113], v[140:141] op_sel:[1,1,0] op_sel_hi:[1,0,1] neg_lo:[0,1,0]
	v_pk_mul_f32 v[140:141], v[114:115], v[116:117] op_sel:[0,0] op_sel_hi:[0,1]
	v_pk_fma_f32 v[114:115], v[114:115], v[116:117], v[140:141] op_sel:[1,1,0] op_sel_hi:[1,0,1] neg_lo:[0,1,0]
	ds_write_b64 v132, v[114:115] offset:30464
	v_pk_mul_f32 v[114:115], v[116:117], v[112:113] op_sel:[0,0] op_sel_hi:[0,1]
	v_pk_fma_f32 v[112:113], v[116:117], v[112:113], v[114:115] op_sel:[1,1,0] op_sel_hi:[1,0,1] neg_lo:[0,1,0]
	v_pk_mul_f32 v[114:115], v[110:111], v[112:113] op_sel:[0,0] op_sel_hi:[0,1]
	v_pk_fma_f32 v[110:111], v[110:111], v[112:113], v[114:115] op_sel:[1,1,0] op_sel_hi:[1,0,1] neg_lo:[0,1,0]
	ds_write_b64 v132, v[110:111] offset:32640
	s_waitcnt lgkmcnt(0)
	s_barrier
	ds_read2_b64 v[110:113], v134 offset1:17
	ds_read2_b64 v[114:117], v134 offset0:34 offset1:51
	ds_read2_b64 v[140:143], v134 offset0:68 offset1:85
	ds_read2_b64 v[144:147], v134 offset0:136 offset1:153
	ds_read2_b64 v[148:151], v134 offset0:102 offset1:119
	ds_read2_b64 v[152:155], v134 offset0:204 offset1:221
	ds_read2_b64 v[156:159], v134 offset0:170 offset1:187
	ds_read2_b64 v[160:163], v134 offset0:238 offset1:255
	s_waitcnt lgkmcnt(4)
	v_pk_add_f32 v[164:165], v[110:111], v[144:145]
	v_pk_add_f32 v[110:111], v[110:111], v[144:145] neg_lo:[0,1] neg_hi:[0,1]
	s_waitcnt lgkmcnt(2)
	v_pk_add_f32 v[144:145], v[140:141], v[152:153]
	v_pk_add_f32 v[140:141], v[140:141], v[152:153] neg_lo:[0,1] neg_hi:[0,1]
	v_pk_add_f32 v[152:153], v[164:165], v[144:145]
	v_pk_add_f32 v[144:145], v[164:165], v[144:145] neg_lo:[0,1] neg_hi:[0,1]
	v_pk_add_f32 v[164:165], v[110:111], v[140:141] op_sel:[0,1] op_sel_hi:[1,0] neg_hi:[0,1]
	v_pk_add_f32 v[110:111], v[110:111], v[140:141] op_sel:[0,1] op_sel_hi:[1,0] neg_lo:[0,1]
	v_pk_add_f32 v[140:141], v[112:113], v[146:147]
	v_pk_add_f32 v[112:113], v[112:113], v[146:147] neg_lo:[0,1] neg_hi:[0,1]
	v_pk_add_f32 v[146:147], v[142:143], v[154:155]
	v_pk_add_f32 v[142:143], v[142:143], v[154:155] neg_lo:[0,1] neg_hi:[0,1]
	v_pk_add_f32 v[154:155], v[140:141], v[146:147]
	v_pk_add_f32 v[140:141], v[140:141], v[146:147] neg_lo:[0,1] neg_hi:[0,1]
	v_pk_add_f32 v[146:147], v[112:113], v[142:143] op_sel:[0,1] op_sel_hi:[1,0] neg_hi:[0,1]
	v_pk_add_f32 v[112:113], v[112:113], v[142:143] op_sel:[0,1] op_sel_hi:[1,0] neg_lo:[0,1]
	s_waitcnt lgkmcnt(1)
	v_pk_add_f32 v[142:143], v[114:115], v[156:157]
	v_pk_add_f32 v[114:115], v[114:115], v[156:157] neg_lo:[0,1] neg_hi:[0,1]
	s_waitcnt lgkmcnt(0)
	v_pk_add_f32 v[156:157], v[148:149], v[160:161]
	v_pk_add_f32 v[148:149], v[148:149], v[160:161] neg_lo:[0,1] neg_hi:[0,1]
	v_pk_add_f32 v[160:161], v[142:143], v[156:157]
	v_pk_add_f32 v[142:143], v[142:143], v[156:157] neg_lo:[0,1] neg_hi:[0,1]
	v_pk_add_f32 v[156:157], v[114:115], v[148:149] op_sel:[0,1] op_sel_hi:[1,0] neg_hi:[0,1]
	v_pk_add_f32 v[114:115], v[114:115], v[148:149] op_sel:[0,1] op_sel_hi:[1,0] neg_lo:[0,1]
	v_pk_add_f32 v[148:149], v[116:117], v[158:159]
	v_pk_add_f32 v[116:117], v[116:117], v[158:159] neg_lo:[0,1] neg_hi:[0,1]
	v_pk_add_f32 v[158:159], v[150:151], v[162:163]
	v_pk_add_f32 v[150:151], v[150:151], v[162:163] neg_lo:[0,1] neg_hi:[0,1]
	v_pk_add_f32 v[162:163], v[148:149], v[158:159]
	v_pk_add_f32 v[148:149], v[148:149], v[158:159] neg_lo:[0,1] neg_hi:[0,1]
	v_pk_add_f32 v[158:159], v[116:117], v[150:151] op_sel:[0,1] op_sel_hi:[1,0] neg_hi:[0,1]
	v_pk_add_f32 v[116:117], v[116:117], v[150:151] op_sel:[0,1] op_sel_hi:[1,0] neg_lo:[0,1]
	v_pk_mul_f32 v[150:151], v[146:147], v[102:103] op_sel:[0,0] op_sel_hi:[0,1]
	v_pk_fma_f32 v[146:147], v[146:147], v[102:103], v[150:151] op_sel:[1,1,0] op_sel_hi:[1,0,1] neg_lo:[0,1,0]
	v_pk_mul_f32 v[150:151], v[156:157], v[98:99] op_sel:[0,0] op_sel_hi:[0,1]
	v_pk_fma_f32 v[150:151], v[156:157], v[98:99], v[150:151] op_sel:[1,1,0] op_sel_hi:[1,0,1] neg_lo:[0,1,0]
	v_pk_mul_f32 v[156:157], v[158:159], v[96:97] op_sel:[0,0] op_sel_hi:[0,1]
	v_pk_fma_f32 v[156:157], v[158:159], v[96:97], v[156:157] op_sel:[1,1,0] op_sel_hi:[1,0,1] neg_lo:[0,1,0]
	v_pk_mul_f32 v[158:159], v[140:141], v[98:99] op_sel:[0,0] op_sel_hi:[0,1]
	v_pk_fma_f32 v[140:141], v[140:141], v[98:99], v[158:159] op_sel:[1,1,0] op_sel_hi:[1,0,1] neg_lo:[0,1,0]
	v_pk_mul_f32 v[158:159], v[142:143], v[104:105] op_sel:[0,0] op_sel_hi:[0,1]
	v_pk_fma_f32 v[142:143], v[142:143], v[104:105], v[158:159] op_sel:[1,1,0] op_sel_hi:[1,0,1] neg_lo:[0,1,0]
	v_pk_mul_f32 v[158:159], v[148:149], v[100:101] op_sel:[0,0] op_sel_hi:[0,1]
	v_pk_fma_f32 v[148:149], v[148:149], v[100:101], v[158:159] op_sel:[1,1,0] op_sel_hi:[1,0,1] neg_lo:[0,1,0]
	v_pk_mul_f32 v[158:159], v[112:113], v[96:97] op_sel:[0,0] op_sel_hi:[0,1]
	v_pk_fma_f32 v[112:113], v[112:113], v[96:97], v[158:159] op_sel:[1,1,0] op_sel_hi:[1,0,1] neg_lo:[0,1,0]
	v_pk_mul_f32 v[158:159], v[114:115], v[100:101] op_sel:[0,0] op_sel_hi:[0,1]
	v_pk_fma_f32 v[114:115], v[114:115], v[100:101], v[158:159] op_sel:[1,1,0] op_sel_hi:[1,0,1] neg_lo:[0,1,0]
	v_pk_mul_f32 v[158:159], v[116:117], v[106:107] op_sel:[0,0] op_sel_hi:[0,1]
	v_pk_fma_f32 v[116:117], v[116:117], v[106:107], v[158:159] op_sel:[1,1,0] op_sel_hi:[1,0,1] neg_lo:[0,1,0]
	v_pk_add_f32 v[158:159], v[152:153], v[160:161]
	v_pk_add_f32 v[152:153], v[152:153], v[160:161] neg_lo:[0,1] neg_hi:[0,1]
	v_pk_add_f32 v[160:161], v[154:155], v[162:163]
	v_pk_add_f32 v[154:155], v[154:155], v[162:163] neg_lo:[0,1] neg_hi:[0,1]
	v_pk_add_f32 v[162:163], v[158:159], v[160:161]
	v_pk_add_f32 v[158:159], v[158:159], v[160:161] neg_lo:[0,1] neg_hi:[0,1]
	v_pk_add_f32 v[160:161], v[152:153], v[154:155] op_sel:[0,1] op_sel_hi:[1,0] neg_hi:[0,1]
	v_pk_add_f32 v[152:153], v[152:153], v[154:155] op_sel:[0,1] op_sel_hi:[1,0] neg_lo:[0,1]
	v_pk_add_f32 v[154:155], v[164:165], v[150:151]
	v_pk_add_f32 v[150:151], v[164:165], v[150:151] neg_lo:[0,1] neg_hi:[0,1]
	v_pk_add_f32 v[164:165], v[146:147], v[156:157]
	v_pk_add_f32 v[146:147], v[146:147], v[156:157] neg_lo:[0,1] neg_hi:[0,1]
	v_pk_add_f32 v[156:157], v[154:155], v[164:165]
	v_pk_add_f32 v[154:155], v[154:155], v[164:165] neg_lo:[0,1] neg_hi:[0,1]
	v_pk_add_f32 v[164:165], v[150:151], v[146:147] op_sel:[0,1] op_sel_hi:[1,0] neg_hi:[0,1]
	v_pk_add_f32 v[146:147], v[150:151], v[146:147] op_sel:[0,1] op_sel_hi:[1,0] neg_lo:[0,1]
	v_pk_add_f32 v[150:151], v[144:145], v[142:143]
	v_pk_add_f32 v[142:143], v[144:145], v[142:143] neg_lo:[0,1] neg_hi:[0,1]
	v_pk_add_f32 v[144:145], v[140:141], v[148:149]
	v_pk_add_f32 v[140:141], v[140:141], v[148:149] neg_lo:[0,1] neg_hi:[0,1]
	v_pk_add_f32 v[148:149], v[150:151], v[144:145]
	v_pk_add_f32 v[144:145], v[150:151], v[144:145] neg_lo:[0,1] neg_hi:[0,1]
	v_pk_add_f32 v[150:151], v[142:143], v[140:141] op_sel:[0,1] op_sel_hi:[1,0] neg_hi:[0,1]
	v_pk_add_f32 v[140:141], v[142:143], v[140:141] op_sel:[0,1] op_sel_hi:[1,0] neg_lo:[0,1]
	v_pk_add_f32 v[142:143], v[110:111], v[114:115]
	v_pk_add_f32 v[110:111], v[110:111], v[114:115] neg_lo:[0,1] neg_hi:[0,1]
	v_pk_add_f32 v[114:115], v[112:113], v[116:117]
	v_pk_add_f32 v[112:113], v[112:113], v[116:117] neg_lo:[0,1] neg_hi:[0,1]
	v_pk_add_f32 v[116:117], v[142:143], v[114:115]
	v_pk_add_f32 v[114:115], v[142:143], v[114:115] neg_lo:[0,1] neg_hi:[0,1]
	v_pk_add_f32 v[142:143], v[110:111], v[112:113] op_sel:[0,1] op_sel_hi:[1,0] neg_hi:[0,1]
	v_pk_add_f32 v[110:111], v[110:111], v[112:113] op_sel:[0,1] op_sel_hi:[1,0] neg_lo:[0,1]
	v_mov_b32_e32 v112, v40
	v_mov_b32_e32 v113, v41
	s_nop 0
	v_pk_mul_f32 v[166:167], v[156:157], v[112:113] op_sel:[0,0] op_sel_hi:[0,1]
	v_pk_fma_f32 v[156:157], v[156:157], v[112:113], v[166:167] op_sel:[1,1,0] op_sel_hi:[1,0,1] neg_lo:[0,1,0]
	ds_write2_b64 v134, v[162:163], v[156:157] offset1:17
	v_pk_mul_f32 v[156:157], v[112:113], v[112:113] op_sel:[0,0] op_sel_hi:[0,1]
	v_pk_fma_f32 v[156:157], v[112:113], v[112:113], v[156:157] op_sel:[1,1,0] op_sel_hi:[1,0,1] neg_lo:[0,1,0]
	v_pk_mul_f32 v[162:163], v[148:149], v[156:157] op_sel:[0,0] op_sel_hi:[0,1]
	v_pk_fma_f32 v[148:149], v[148:149], v[156:157], v[162:163] op_sel:[1,1,0] op_sel_hi:[1,0,1] neg_lo:[0,1,0]
	v_pk_mul_f32 v[162:163], v[156:157], v[112:113] op_sel:[0,0] op_sel_hi:[0,1]
	v_pk_fma_f32 v[156:157], v[156:157], v[112:113], v[162:163] op_sel:[1,1,0] op_sel_hi:[1,0,1] neg_lo:[0,1,0]
	v_pk_mul_f32 v[162:163], v[116:117], v[156:157] op_sel:[0,0] op_sel_hi:[0,1]
	v_pk_fma_f32 v[116:117], v[116:117], v[156:157], v[162:163] op_sel:[1,1,0] op_sel_hi:[1,0,1] neg_lo:[0,1,0]
	ds_write2_b64 v134, v[148:149], v[116:117] offset0:34 offset1:51
	v_pk_mul_f32 v[116:117], v[156:157], v[112:113] op_sel:[0,0] op_sel_hi:[0,1]
	v_pk_fma_f32 v[116:117], v[156:157], v[112:113], v[116:117] op_sel:[1,1,0] op_sel_hi:[1,0,1] neg_lo:[0,1,0]
	v_pk_mul_f32 v[148:149], v[160:161], v[116:117] op_sel:[0,0] op_sel_hi:[0,1]
	v_pk_mul_f32 v[156:157], v[116:117], v[112:113] op_sel:[0,0] op_sel_hi:[0,1]
	v_pk_fma_f32 v[148:149], v[160:161], v[116:117], v[148:149] op_sel:[1,1,0] op_sel_hi:[1,0,1] neg_lo:[0,1,0]
	v_pk_fma_f32 v[116:117], v[116:117], v[112:113], v[156:157] op_sel:[1,1,0] op_sel_hi:[1,0,1] neg_lo:[0,1,0]
	v_pk_mul_f32 v[156:157], v[164:165], v[116:117] op_sel:[0,0] op_sel_hi:[0,1]
	v_pk_fma_f32 v[156:157], v[164:165], v[116:117], v[156:157] op_sel:[1,1,0] op_sel_hi:[1,0,1] neg_lo:[0,1,0]
	ds_write2_b64 v134, v[148:149], v[156:157] offset0:68 offset1:85
	v_pk_mul_f32 v[148:149], v[116:117], v[112:113] op_sel:[0,0] op_sel_hi:[0,1]
	v_pk_fma_f32 v[116:117], v[116:117], v[112:113], v[148:149] op_sel:[1,1,0] op_sel_hi:[1,0,1] neg_lo:[0,1,0]
	v_pk_mul_f32 v[148:149], v[150:151], v[116:117] op_sel:[0,0] op_sel_hi:[0,1]
	v_pk_fma_f32 v[148:149], v[150:151], v[116:117], v[148:149] op_sel:[1,1,0] op_sel_hi:[1,0,1] neg_lo:[0,1,0]
	v_pk_mul_f32 v[150:151], v[116:117], v[112:113] op_sel:[0,0] op_sel_hi:[0,1]
	v_pk_fma_f32 v[116:117], v[116:117], v[112:113], v[150:151] op_sel:[1,1,0] op_sel_hi:[1,0,1] neg_lo:[0,1,0]
	v_pk_mul_f32 v[150:151], v[142:143], v[116:117] op_sel:[0,0] op_sel_hi:[0,1]
	v_pk_fma_f32 v[142:143], v[142:143], v[116:117], v[150:151] op_sel:[1,1,0] op_sel_hi:[1,0,1] neg_lo:[0,1,0]
	ds_write2_b64 v134, v[148:149], v[142:143] offset0:102 offset1:119
	v_pk_mul_f32 v[142:143], v[116:117], v[112:113] op_sel:[0,0] op_sel_hi:[0,1]
	v_pk_fma_f32 v[116:117], v[116:117], v[112:113], v[142:143] op_sel:[1,1,0] op_sel_hi:[1,0,1] neg_lo:[0,1,0]
	v_pk_mul_f32 v[142:143], v[158:159], v[116:117] op_sel:[0,0] op_sel_hi:[0,1]
	v_pk_mul_f32 v[148:149], v[116:117], v[112:113] op_sel:[0,0] op_sel_hi:[0,1]
	v_pk_fma_f32 v[142:143], v[158:159], v[116:117], v[142:143] op_sel:[1,1,0] op_sel_hi:[1,0,1] neg_lo:[0,1,0]
	v_pk_fma_f32 v[116:117], v[116:117], v[112:113], v[148:149] op_sel:[1,1,0] op_sel_hi:[1,0,1] neg_lo:[0,1,0]
	v_pk_mul_f32 v[148:149], v[154:155], v[116:117] op_sel:[0,0] op_sel_hi:[0,1]
	v_pk_fma_f32 v[148:149], v[154:155], v[116:117], v[148:149] op_sel:[1,1,0] op_sel_hi:[1,0,1] neg_lo:[0,1,0]
	ds_write2_b64 v134, v[142:143], v[148:149] offset0:136 offset1:153
	v_pk_mul_f32 v[142:143], v[116:117], v[112:113] op_sel:[0,0] op_sel_hi:[0,1]
	v_pk_fma_f32 v[116:117], v[116:117], v[112:113], v[142:143] op_sel:[1,1,0] op_sel_hi:[1,0,1] neg_lo:[0,1,0]
	v_pk_mul_f32 v[142:143], v[144:145], v[116:117] op_sel:[0,0] op_sel_hi:[0,1]
	v_pk_fma_f32 v[142:143], v[144:145], v[116:117], v[142:143] op_sel:[1,1,0] op_sel_hi:[1,0,1] neg_lo:[0,1,0]
	v_pk_mul_f32 v[144:145], v[116:117], v[112:113] op_sel:[0,0] op_sel_hi:[0,1]
	v_pk_fma_f32 v[116:117], v[116:117], v[112:113], v[144:145] op_sel:[1,1,0] op_sel_hi:[1,0,1] neg_lo:[0,1,0]
	v_pk_mul_f32 v[144:145], v[114:115], v[116:117] op_sel:[0,0] op_sel_hi:[0,1]
	v_pk_fma_f32 v[114:115], v[114:115], v[116:117], v[144:145] op_sel:[1,1,0] op_sel_hi:[1,0,1] neg_lo:[0,1,0]
	ds_write2_b64 v134, v[142:143], v[114:115] offset0:170 offset1:187
	v_pk_mul_f32 v[114:115], v[116:117], v[112:113] op_sel:[0,0] op_sel_hi:[0,1]
	v_pk_fma_f32 v[114:115], v[116:117], v[112:113], v[114:115] op_sel:[1,1,0] op_sel_hi:[1,0,1] neg_lo:[0,1,0]
	v_pk_mul_f32 v[116:117], v[152:153], v[114:115] op_sel:[0,0] op_sel_hi:[0,1]
	v_pk_mul_f32 v[142:143], v[114:115], v[112:113] op_sel:[0,0] op_sel_hi:[0,1]
	v_pk_fma_f32 v[116:117], v[152:153], v[114:115], v[116:117] op_sel:[1,1,0] op_sel_hi:[1,0,1] neg_lo:[0,1,0]
	v_pk_fma_f32 v[114:115], v[114:115], v[112:113], v[142:143] op_sel:[1,1,0] op_sel_hi:[1,0,1] neg_lo:[0,1,0]
	v_pk_mul_f32 v[142:143], v[146:147], v[114:115] op_sel:[0,0] op_sel_hi:[0,1]
	v_pk_fma_f32 v[142:143], v[146:147], v[114:115], v[142:143] op_sel:[1,1,0] op_sel_hi:[1,0,1] neg_lo:[0,1,0]
	ds_write2_b64 v134, v[116:117], v[142:143] offset0:204 offset1:221
	v_pk_mul_f32 v[116:117], v[114:115], v[112:113] op_sel:[0,0] op_sel_hi:[0,1]
	v_pk_fma_f32 v[114:115], v[114:115], v[112:113], v[116:117] op_sel:[1,1,0] op_sel_hi:[1,0,1] neg_lo:[0,1,0]
	v_pk_mul_f32 v[116:117], v[140:141], v[114:115] op_sel:[0,0] op_sel_hi:[0,1]
	v_pk_fma_f32 v[116:117], v[140:141], v[114:115], v[116:117] op_sel:[1,1,0] op_sel_hi:[1,0,1] neg_lo:[0,1,0]
	v_pk_mul_f32 v[140:141], v[114:115], v[112:113] op_sel:[0,0] op_sel_hi:[0,1]
	v_pk_fma_f32 v[112:113], v[114:115], v[112:113], v[140:141] op_sel:[1,1,0] op_sel_hi:[1,0,1] neg_lo:[0,1,0]
	v_pk_mul_f32 v[114:115], v[110:111], v[112:113] op_sel:[0,0] op_sel_hi:[0,1]
	v_pk_fma_f32 v[110:111], v[110:111], v[112:113], v[114:115] op_sel:[1,1,0] op_sel_hi:[1,0,1] neg_lo:[0,1,0]
	ds_write2_b64 v134, v[116:117], v[110:111] offset0:238 offset1:255
	s_waitcnt lgkmcnt(0)
	s_barrier
	ds_read2_b64 v[110:113], v135 offset1:1
	ds_read2_b64 v[114:117], v135 offset0:2 offset1:3
	ds_read2_b64 v[140:143], v135 offset0:8 offset1:9
	ds_read2_b64 v[144:147], v135 offset0:4 offset1:5
	ds_read2_b64 v[148:151], v135 offset0:6 offset1:7
	ds_read2_b64 v[152:155], v135 offset0:12 offset1:13
	ds_read2_b64 v[156:159], v135 offset0:10 offset1:11
	ds_read2_b64 v[160:163], v135 offset0:14 offset1:15
	s_waitcnt lgkmcnt(5)
	v_pk_add_f32 v[164:165], v[110:111], v[140:141]
	v_pk_add_f32 v[110:111], v[110:111], v[140:141] neg_lo:[0,1] neg_hi:[0,1]
	s_waitcnt lgkmcnt(2)
	v_pk_add_f32 v[140:141], v[144:145], v[152:153]
	v_pk_add_f32 v[144:145], v[144:145], v[152:153] neg_lo:[0,1] neg_hi:[0,1]
	v_pk_add_f32 v[152:153], v[164:165], v[140:141]
	v_pk_add_f32 v[140:141], v[164:165], v[140:141] neg_lo:[0,1] neg_hi:[0,1]
	v_pk_add_f32 v[164:165], v[110:111], v[144:145] op_sel:[0,1] op_sel_hi:[1,0] neg_hi:[0,1]
	v_pk_add_f32 v[110:111], v[110:111], v[144:145] op_sel:[0,1] op_sel_hi:[1,0] neg_lo:[0,1]
	v_pk_add_f32 v[144:145], v[112:113], v[142:143]
	v_pk_add_f32 v[112:113], v[112:113], v[142:143] neg_lo:[0,1] neg_hi:[0,1]
	v_pk_add_f32 v[142:143], v[146:147], v[154:155]
	v_pk_add_f32 v[146:147], v[146:147], v[154:155] neg_lo:[0,1] neg_hi:[0,1]
	v_pk_add_f32 v[154:155], v[144:145], v[142:143]
	v_pk_add_f32 v[142:143], v[144:145], v[142:143] neg_lo:[0,1] neg_hi:[0,1]
	v_pk_add_f32 v[144:145], v[112:113], v[146:147] op_sel:[0,1] op_sel_hi:[1,0] neg_hi:[0,1]
	v_pk_add_f32 v[112:113], v[112:113], v[146:147] op_sel:[0,1] op_sel_hi:[1,0] neg_lo:[0,1]
	s_waitcnt lgkmcnt(1)
	v_pk_add_f32 v[146:147], v[114:115], v[156:157]
	v_pk_add_f32 v[114:115], v[114:115], v[156:157] neg_lo:[0,1] neg_hi:[0,1]
	s_waitcnt lgkmcnt(0)
	v_pk_add_f32 v[156:157], v[148:149], v[160:161]
	v_pk_add_f32 v[148:149], v[148:149], v[160:161] neg_lo:[0,1] neg_hi:[0,1]
	v_pk_add_f32 v[160:161], v[146:147], v[156:157]
	v_pk_add_f32 v[146:147], v[146:147], v[156:157] neg_lo:[0,1] neg_hi:[0,1]
	v_pk_add_f32 v[156:157], v[114:115], v[148:149] op_sel:[0,1] op_sel_hi:[1,0] neg_hi:[0,1]
	v_pk_add_f32 v[114:115], v[114:115], v[148:149] op_sel:[0,1] op_sel_hi:[1,0] neg_lo:[0,1]
	v_pk_add_f32 v[148:149], v[116:117], v[158:159]
	v_pk_add_f32 v[116:117], v[116:117], v[158:159] neg_lo:[0,1] neg_hi:[0,1]
	v_pk_add_f32 v[158:159], v[150:151], v[162:163]
	v_pk_add_f32 v[150:151], v[150:151], v[162:163] neg_lo:[0,1] neg_hi:[0,1]
	v_pk_add_f32 v[162:163], v[148:149], v[158:159]
	v_pk_add_f32 v[148:149], v[148:149], v[158:159] neg_lo:[0,1] neg_hi:[0,1]
	v_pk_add_f32 v[158:159], v[116:117], v[150:151] op_sel:[0,1] op_sel_hi:[1,0] neg_hi:[0,1]
	v_pk_add_f32 v[116:117], v[116:117], v[150:151] op_sel:[0,1] op_sel_hi:[1,0] neg_lo:[0,1]
	v_pk_mul_f32 v[150:151], v[144:145], v[102:103] op_sel:[0,0] op_sel_hi:[0,1]
	v_pk_fma_f32 v[102:103], v[144:145], v[102:103], v[150:151] op_sel:[1,1,0] op_sel_hi:[1,0,1] neg_lo:[0,1,0]
	v_pk_mul_f32 v[144:145], v[156:157], v[98:99] op_sel:[0,0] op_sel_hi:[0,1]
	v_pk_mul_f32 v[150:151], v[158:159], v[96:97] op_sel:[0,0] op_sel_hi:[0,1]
	v_pk_fma_f32 v[144:145], v[156:157], v[98:99], v[144:145] op_sel:[1,1,0] op_sel_hi:[1,0,1] neg_lo:[0,1,0]
	v_pk_mul_f32 v[156:157], v[142:143], v[98:99] op_sel:[0,0] op_sel_hi:[0,1]
	v_pk_fma_f32 v[150:151], v[158:159], v[96:97], v[150:151] op_sel:[1,1,0] op_sel_hi:[1,0,1] neg_lo:[0,1,0]
	v_pk_fma_f32 v[98:99], v[142:143], v[98:99], v[156:157] op_sel:[1,1,0] op_sel_hi:[1,0,1] neg_lo:[0,1,0]
	v_pk_mul_f32 v[142:143], v[146:147], v[104:105] op_sel:[0,0] op_sel_hi:[0,1]
	v_pk_fma_f32 v[104:105], v[146:147], v[104:105], v[142:143] op_sel:[1,1,0] op_sel_hi:[1,0,1] neg_lo:[0,1,0]
	v_pk_mul_f32 v[142:143], v[148:149], v[100:101] op_sel:[0,0] op_sel_hi:[0,1]
	v_pk_mul_f32 v[146:147], v[112:113], v[96:97] op_sel:[0,0] op_sel_hi:[0,1]
	v_pk_fma_f32 v[96:97], v[112:113], v[96:97], v[146:147] op_sel:[1,1,0] op_sel_hi:[1,0,1] neg_lo:[0,1,0]
	v_pk_mul_f32 v[112:113], v[114:115], v[100:101] op_sel:[0,0] op_sel_hi:[0,1]
	v_pk_fma_f32 v[142:143], v[148:149], v[100:101], v[142:143] op_sel:[1,1,0] op_sel_hi:[1,0,1] neg_lo:[0,1,0]
	v_pk_add_f32 v[146:147], v[154:155], v[162:163] neg_lo:[0,1] neg_hi:[0,1]
	v_pk_fma_f32 v[100:101], v[114:115], v[100:101], v[112:113] op_sel:[1,1,0] op_sel_hi:[1,0,1] neg_lo:[0,1,0]
	v_pk_mul_f32 v[112:113], v[116:117], v[106:107] op_sel:[0,0] op_sel_hi:[0,1]
	v_pk_add_f32 v[114:115], v[152:153], v[160:161] neg_lo:[0,1] neg_hi:[0,1]
	v_pk_fma_f32 v[106:107], v[116:117], v[106:107], v[112:113] op_sel:[1,1,0] op_sel_hi:[1,0,1] neg_lo:[0,1,0]
	v_pk_add_f32 v[112:113], v[152:153], v[160:161]
	v_pk_add_f32 v[116:117], v[154:155], v[162:163]
	v_pk_add_f32 v[152:153], v[102:103], v[150:151]
	v_pk_add_f32 v[148:149], v[112:113], v[116:117]
	v_pk_add_f32 v[112:113], v[112:113], v[116:117] neg_lo:[0,1] neg_hi:[0,1]
	v_pk_add_f32 v[116:117], v[114:115], v[146:147] op_sel:[0,1] op_sel_hi:[1,0] neg_hi:[0,1]
	v_pk_add_f32 v[114:115], v[114:115], v[146:147] op_sel:[0,1] op_sel_hi:[1,0] neg_lo:[0,1]
	v_pk_add_f32 v[146:147], v[164:165], v[144:145]
	v_pk_add_f32 v[144:145], v[164:165], v[144:145] neg_lo:[0,1] neg_hi:[0,1]
	v_pk_add_f32 v[102:103], v[102:103], v[150:151] neg_lo:[0,1] neg_hi:[0,1]
	v_pk_add_f32 v[150:151], v[146:147], v[152:153]
	v_pk_add_f32 v[146:147], v[146:147], v[152:153] neg_lo:[0,1] neg_hi:[0,1]
	v_pk_add_f32 v[152:153], v[144:145], v[102:103] op_sel:[0,1] op_sel_hi:[1,0] neg_hi:[0,1]
	v_pk_add_f32 v[102:103], v[144:145], v[102:103] op_sel:[0,1] op_sel_hi:[1,0] neg_lo:[0,1]
	v_pk_add_f32 v[144:145], v[140:141], v[104:105]
	v_pk_add_f32 v[104:105], v[140:141], v[104:105] neg_lo:[0,1] neg_hi:[0,1]
	v_pk_add_f32 v[140:141], v[98:99], v[142:143]
	v_pk_add_f32 v[98:99], v[98:99], v[142:143] neg_lo:[0,1] neg_hi:[0,1]
	v_pk_add_f32 v[142:143], v[144:145], v[140:141]
	v_pk_add_f32 v[140:141], v[144:145], v[140:141] neg_lo:[0,1] neg_hi:[0,1]
	v_pk_add_f32 v[144:145], v[104:105], v[98:99] op_sel:[0,1] op_sel_hi:[1,0] neg_hi:[0,1]
	v_pk_add_f32 v[98:99], v[104:105], v[98:99] op_sel:[0,1] op_sel_hi:[1,0] neg_lo:[0,1]
	v_pk_add_f32 v[104:105], v[110:111], v[100:101]
	v_pk_add_f32 v[100:101], v[110:111], v[100:101] neg_lo:[0,1] neg_hi:[0,1]
	v_pk_add_f32 v[110:111], v[96:97], v[106:107]
	v_pk_add_f32 v[96:97], v[96:97], v[106:107] neg_lo:[0,1] neg_hi:[0,1]
	v_pk_add_f32 v[106:107], v[104:105], v[110:111]
	v_pk_add_f32 v[104:105], v[104:105], v[110:111] neg_lo:[0,1] neg_hi:[0,1]
	v_pk_add_f32 v[110:111], v[100:101], v[96:97] op_sel:[0,1] op_sel_hi:[1,0] neg_hi:[0,1]
	v_pk_add_f32 v[96:97], v[100:101], v[96:97] op_sel:[0,1] op_sel_hi:[1,0] neg_lo:[0,1]
	s_waitcnt vmcnt(15)
	v_pk_mul_f32 v[100:101], v[148:149], v[70:71] op_sel:[0,0] op_sel_hi:[0,1]
	v_pk_fma_f32 v[70:71], v[148:149], v[70:71], v[100:101] op_sel:[1,1,0] op_sel_hi:[1,0,1] neg_lo:[0,1,0]
	s_waitcnt vmcnt(14)
	v_pk_mul_f32 v[100:101], v[116:117], v[30:31] op_sel:[0,0] op_sel_hi:[0,1]
	v_pk_fma_f32 v[30:31], v[116:117], v[30:31], v[100:101] op_sel:[1,1,0] op_sel_hi:[1,0,1] neg_lo:[0,1,0]
	s_waitcnt vmcnt(13)
	v_pk_mul_f32 v[100:101], v[112:113], v[28:29] op_sel:[0,0] op_sel_hi:[0,1]
	v_pk_fma_f32 v[28:29], v[112:113], v[28:29], v[100:101] op_sel:[1,1,0] op_sel_hi:[1,0,1] neg_lo:[0,1,0]
	s_waitcnt vmcnt(12)
	v_pk_mul_f32 v[100:101], v[114:115], v[32:33] op_sel:[0,0] op_sel_hi:[0,1]
	v_pk_fma_f32 v[32:33], v[114:115], v[32:33], v[100:101] op_sel:[1,1,0] op_sel_hi:[1,0,1] neg_lo:[0,1,0]
	s_waitcnt vmcnt(11)
	v_pk_mul_f32 v[100:101], v[150:151], v[78:79] op_sel:[0,0] op_sel_hi:[0,1]
	v_pk_fma_f32 v[78:79], v[150:151], v[78:79], v[100:101] op_sel:[1,1,0] op_sel_hi:[1,0,1] neg_lo:[0,1,0]
	s_waitcnt vmcnt(10)
	v_pk_mul_f32 v[100:101], v[152:153], v[74:75] op_sel:[0,0] op_sel_hi:[0,1]
	v_pk_fma_f32 v[74:75], v[152:153], v[74:75], v[100:101] op_sel:[1,1,0] op_sel_hi:[1,0,1] neg_lo:[0,1,0]
	s_waitcnt vmcnt(9)
	v_pk_mul_f32 v[100:101], v[146:147], v[72:73] op_sel:[0,0] op_sel_hi:[0,1]
	v_pk_fma_f32 v[72:73], v[146:147], v[72:73], v[100:101] op_sel:[1,1,0] op_sel_hi:[1,0,1] neg_lo:[0,1,0]
	s_waitcnt vmcnt(8)
	v_pk_mul_f32 v[100:101], v[102:103], v[76:77] op_sel:[0,0] op_sel_hi:[0,1]
	v_pk_fma_f32 v[76:77], v[102:103], v[76:77], v[100:101] op_sel:[1,1,0] op_sel_hi:[1,0,1] neg_lo:[0,1,0]
	s_waitcnt vmcnt(7)
	v_pk_mul_f32 v[100:101], v[142:143], v[86:87] op_sel:[0,0] op_sel_hi:[0,1]
	v_pk_fma_f32 v[86:87], v[142:143], v[86:87], v[100:101] op_sel:[1,1,0] op_sel_hi:[1,0,1] neg_lo:[0,1,0]
	s_waitcnt vmcnt(6)
	v_pk_mul_f32 v[100:101], v[144:145], v[82:83] op_sel:[0,0] op_sel_hi:[0,1]
	v_pk_fma_f32 v[82:83], v[144:145], v[82:83], v[100:101] op_sel:[1,1,0] op_sel_hi:[1,0,1] neg_lo:[0,1,0]
	s_waitcnt vmcnt(5)
	v_pk_mul_f32 v[100:101], v[140:141], v[80:81] op_sel:[0,0] op_sel_hi:[0,1]
	v_pk_fma_f32 v[80:81], v[140:141], v[80:81], v[100:101] op_sel:[1,1,0] op_sel_hi:[1,0,1] neg_lo:[0,1,0]
	s_waitcnt vmcnt(4)
	v_pk_mul_f32 v[100:101], v[98:99], v[84:85] op_sel:[0,0] op_sel_hi:[0,1]
	v_pk_fma_f32 v[84:85], v[98:99], v[84:85], v[100:101] op_sel:[1,1,0] op_sel_hi:[1,0,1] neg_lo:[0,1,0]
	s_waitcnt vmcnt(3)
	v_pk_mul_f32 v[98:99], v[106:107], v[94:95] op_sel:[0,0] op_sel_hi:[0,1]
	v_pk_fma_f32 v[94:95], v[106:107], v[94:95], v[98:99] op_sel:[1,1,0] op_sel_hi:[1,0,1] neg_lo:[0,1,0]
	s_waitcnt vmcnt(2)
	v_pk_mul_f32 v[98:99], v[110:111], v[90:91] op_sel:[0,0] op_sel_hi:[0,1]
	v_pk_fma_f32 v[90:91], v[110:111], v[90:91], v[98:99] op_sel:[1,1,0] op_sel_hi:[1,0,1] neg_lo:[0,1,0]
	s_waitcnt vmcnt(1)
	v_pk_mul_f32 v[98:99], v[104:105], v[88:89] op_sel:[0,0] op_sel_hi:[0,1]
	v_pk_fma_f32 v[88:89], v[104:105], v[88:89], v[98:99] op_sel:[1,1,0] op_sel_hi:[1,0,1] neg_lo:[0,1,0]
	s_waitcnt vmcnt(0)
	v_pk_mul_f32 v[98:99], v[96:97], v[92:93] op_sel:[0,0] op_sel_hi:[0,1]
	v_pk_fma_f32 v[92:93], v[96:97], v[92:93], v[98:99] op_sel:[1,1,0] op_sel_hi:[1,0,1] neg_lo:[0,1,0]
	v_pk_add_f32 v[96:97], v[70:71], v[28:29]
	v_pk_add_f32 v[28:29], v[70:71], v[28:29] neg_lo:[0,1] neg_hi:[0,1]
	v_pk_add_f32 v[70:71], v[30:31], v[32:33]
	v_pk_add_f32 v[30:31], v[30:31], v[32:33] neg_lo:[0,1] neg_hi:[0,1]
	v_pk_add_f32 v[98:99], v[96:97], v[70:71]
	v_pk_add_f32 v[96:97], v[96:97], v[70:71] neg_lo:[0,1] neg_hi:[0,1]
	v_pk_add_f32 v[100:101], v[28:29], v[30:31] op_sel:[0,1] op_sel_hi:[1,0] neg_lo:[0,1]
	v_pk_add_f32 v[102:103], v[28:29], v[30:31] op_sel:[0,1] op_sel_hi:[1,0] neg_hi:[0,1]
	v_pk_add_f32 v[28:29], v[78:79], v[72:73]
	v_pk_add_f32 v[30:31], v[78:79], v[72:73] neg_lo:[0,1] neg_hi:[0,1]
	v_pk_add_f32 v[32:33], v[74:75], v[76:77]
	v_pk_add_f32 v[70:71], v[74:75], v[76:77] neg_lo:[0,1] neg_hi:[0,1]
	v_pk_add_f32 v[76:77], v[28:29], v[32:33]
	v_pk_add_f32 v[32:33], v[28:29], v[32:33] neg_lo:[0,1] neg_hi:[0,1]
	v_pk_add_f32 v[28:29], v[30:31], v[70:71] op_sel:[0,1] op_sel_hi:[1,0] neg_lo:[0,1]
	v_pk_add_f32 v[74:75], v[30:31], v[70:71] op_sel:[0,1] op_sel_hi:[1,0] neg_hi:[0,1]
	v_pk_add_f32 v[30:31], v[86:87], v[80:81]
	v_pk_add_f32 v[70:71], v[86:87], v[80:81] neg_lo:[0,1] neg_hi:[0,1]
	v_pk_add_f32 v[72:73], v[82:83], v[84:85]
	v_pk_add_f32 v[78:79], v[82:83], v[84:85] neg_lo:[0,1] neg_hi:[0,1]
	v_pk_add_f32 v[80:81], v[30:31], v[72:73]
	v_pk_add_f32 v[82:83], v[30:31], v[72:73] neg_lo:[0,1] neg_hi:[0,1]
	v_pk_add_f32 v[72:73], v[70:71], v[78:79] op_sel:[0,1] op_sel_hi:[1,0] neg_lo:[0,1]
	v_pk_add_f32 v[78:79], v[70:71], v[78:79] op_sel:[0,1] op_sel_hi:[1,0] neg_hi:[0,1]
	v_pk_add_f32 v[30:31], v[94:95], v[88:89]
	v_pk_add_f32 v[70:71], v[94:95], v[88:89] neg_lo:[0,1] neg_hi:[0,1]
	v_pk_add_f32 v[84:85], v[90:91], v[92:93]
	v_pk_add_f32 v[86:87], v[90:91], v[92:93] neg_lo:[0,1] neg_hi:[0,1]
	v_pk_add_f32 v[88:89], v[30:31], v[84:85]
	v_pk_add_f32 v[84:85], v[30:31], v[84:85] neg_lo:[0,1] neg_hi:[0,1]
	v_pk_add_f32 v[90:91], v[70:71], v[86:87] op_sel:[0,1] op_sel_hi:[1,0] neg_lo:[0,1]
	v_pk_add_f32 v[86:87], v[70:71], v[86:87] op_sel:[0,1] op_sel_hi:[1,0] neg_hi:[0,1]
	v_mov_b64_e32 v[70:71], s[58:59]
	v_pk_mul_f32 v[30:31], v[28:29], v[70:71] op_sel:[0,0] op_sel_hi:[0,1]
	v_pk_fma_f32 v[92:93], v[28:29], v[70:71], v[30:31] op_sel:[1,1,0] op_sel_hi:[1,0,1] neg_lo:[0,1,0]
	v_mov_b64_e32 v[30:31], s[60:61]
	v_pk_mul_f32 v[28:29], v[72:73], v[30:31] op_sel:[0,0] op_sel_hi:[0,1]
	v_pk_fma_f32 v[94:95], v[72:73], v[30:31], v[28:29] op_sel:[1,1,0] op_sel_hi:[1,0,1] neg_lo:[0,1,0]
	v_mov_b64_e32 v[28:29], s[62:63]
	v_pk_mul_f32 v[72:73], v[90:91], v[28:29] op_sel:[0,0] op_sel_hi:[0,1]
	v_pk_fma_f32 v[90:91], v[90:91], v[28:29], v[72:73] op_sel:[1,1,0] op_sel_hi:[1,0,1] neg_lo:[0,1,0]
	v_pk_mul_f32 v[72:73], v[32:33], v[30:31] op_sel:[0,0] op_sel_hi:[0,1]
	v_pk_fma_f32 v[104:105], v[32:33], v[30:31], v[72:73] op_sel:[1,1,0] op_sel_hi:[1,0,1] neg_lo:[0,1,0]
	v_mov_b64_e32 v[72:73], s[64:65]
	v_pk_mul_f32 v[32:33], v[82:83], v[72:73] op_sel:[0,0] op_sel_hi:[0,1]
	v_pk_fma_f32 v[82:83], v[82:83], v[72:73], v[32:33] op_sel:[1,1,0] op_sel_hi:[1,0,1] neg_lo:[0,1,0]
	v_mov_b64_e32 v[32:33], s[66:67]
	v_pk_mul_f32 v[106:107], v[84:85], v[32:33] op_sel:[0,0] op_sel_hi:[0,1]
	v_pk_fma_f32 v[84:85], v[84:85], v[32:33], v[106:107] op_sel:[1,1,0] op_sel_hi:[1,0,1] neg_lo:[0,1,0]
	v_pk_mul_f32 v[106:107], v[74:75], v[28:29] op_sel:[0,0] op_sel_hi:[0,1]
	v_pk_fma_f32 v[106:107], v[74:75], v[28:29], v[106:107] op_sel:[1,1,0] op_sel_hi:[1,0,1] neg_lo:[0,1,0]
	v_pk_mul_f32 v[74:75], v[78:79], v[32:33] op_sel:[0,0] op_sel_hi:[0,1]
	v_pk_fma_f32 v[78:79], v[78:79], v[32:33], v[74:75] op_sel:[1,1,0] op_sel_hi:[1,0,1] neg_lo:[0,1,0]
	v_mov_b64_e32 v[74:75], s[68:69]
	v_pk_mul_f32 v[110:111], v[86:87], v[74:75] op_sel:[0,0] op_sel_hi:[0,1]
	v_pk_fma_f32 v[86:87], v[86:87], v[74:75], v[110:111] op_sel:[1,1,0] op_sel_hi:[1,0,1] neg_lo:[0,1,0]
	v_pk_add_f32 v[110:111], v[98:99], v[80:81]
	v_pk_add_f32 v[80:81], v[98:99], v[80:81] neg_lo:[0,1] neg_hi:[0,1]
	v_pk_add_f32 v[98:99], v[76:77], v[88:89]
	v_pk_add_f32 v[76:77], v[76:77], v[88:89] neg_lo:[0,1] neg_hi:[0,1]
	v_pk_add_f32 v[88:89], v[110:111], v[98:99]
	v_pk_add_f32 v[98:99], v[110:111], v[98:99] neg_lo:[0,1] neg_hi:[0,1]
	v_pk_add_f32 v[110:111], v[80:81], v[76:77] op_sel:[0,1] op_sel_hi:[1,0] neg_lo:[0,1]
	v_pk_add_f32 v[76:77], v[80:81], v[76:77] op_sel:[0,1] op_sel_hi:[1,0] neg_hi:[0,1]
	v_pk_add_f32 v[80:81], v[100:101], v[94:95]
	v_pk_add_f32 v[94:95], v[100:101], v[94:95] neg_lo:[0,1] neg_hi:[0,1]
	v_pk_add_f32 v[100:101], v[92:93], v[90:91]
	v_pk_add_f32 v[90:91], v[92:93], v[90:91] neg_lo:[0,1] neg_hi:[0,1]
	v_pk_add_f32 v[92:93], v[80:81], v[100:101]
	v_pk_add_f32 v[80:81], v[80:81], v[100:101] neg_lo:[0,1] neg_hi:[0,1]
	v_pk_add_f32 v[100:101], v[94:95], v[90:91] op_sel:[0,1] op_sel_hi:[1,0] neg_lo:[0,1]
	v_pk_add_f32 v[90:91], v[94:95], v[90:91] op_sel:[0,1] op_sel_hi:[1,0] neg_hi:[0,1]
	v_pk_add_f32 v[94:95], v[96:97], v[82:83]
	v_pk_add_f32 v[82:83], v[96:97], v[82:83] neg_lo:[0,1] neg_hi:[0,1]
	v_pk_add_f32 v[96:97], v[104:105], v[84:85]
	v_pk_add_f32 v[84:85], v[104:105], v[84:85] neg_lo:[0,1] neg_hi:[0,1]
	v_pk_add_f32 v[104:105], v[94:95], v[96:97]
	v_pk_add_f32 v[94:95], v[94:95], v[96:97] neg_lo:[0,1] neg_hi:[0,1]
	v_pk_add_f32 v[96:97], v[82:83], v[84:85] op_sel:[0,1] op_sel_hi:[1,0] neg_lo:[0,1]
	v_pk_add_f32 v[82:83], v[82:83], v[84:85] op_sel:[0,1] op_sel_hi:[1,0] neg_hi:[0,1]
	v_pk_add_f32 v[84:85], v[102:103], v[78:79]
	v_pk_add_f32 v[78:79], v[102:103], v[78:79] neg_lo:[0,1] neg_hi:[0,1]
	v_pk_add_f32 v[102:103], v[106:107], v[86:87]
	v_pk_add_f32 v[86:87], v[106:107], v[86:87] neg_lo:[0,1] neg_hi:[0,1]
	v_pk_add_f32 v[106:107], v[84:85], v[102:103]
	v_pk_add_f32 v[84:85], v[84:85], v[102:103] neg_lo:[0,1] neg_hi:[0,1]
	v_pk_add_f32 v[102:103], v[78:79], v[86:87] op_sel:[0,1] op_sel_hi:[1,0] neg_lo:[0,1]
	v_pk_add_f32 v[78:79], v[78:79], v[86:87] op_sel:[0,1] op_sel_hi:[1,0] neg_hi:[0,1]
	v_mov_b32_e32 v86, v40
	v_mov_b32_e32 v87, v41
	ds_write2_b64 v135, v[88:89], v[92:93] offset1:1
	ds_write2_b64 v135, v[104:105], v[106:107] offset0:2 offset1:3
	ds_write2_b64 v135, v[110:111], v[100:101] offset0:4 offset1:5
	ds_write2_b64 v135, v[96:97], v[102:103] offset0:6 offset1:7
	ds_write2_b64 v135, v[98:99], v[80:81] offset0:8 offset1:9
	ds_write2_b64 v135, v[94:95], v[84:85] offset0:10 offset1:11
	ds_write2_b64 v135, v[76:77], v[90:91] offset0:12 offset1:13
	ds_write2_b64 v135, v[82:83], v[78:79] offset0:14 offset1:15
	s_waitcnt lgkmcnt(0)
	s_barrier
	ds_read2_b64 v[76:79], v134 offset1:17
	ds_read2_b64 v[80:83], v134 offset0:34 offset1:51
	s_waitcnt lgkmcnt(1)
	v_pk_mul_f32 v[84:85], v[78:79], v[86:87] op_sel:[0,0] op_sel_hi:[0,1] neg_hi:[0,1]
	v_pk_fma_f32 v[88:89], v[78:79], v[86:87], v[84:85] op_sel:[1,1,0] op_sel_hi:[1,0,1]
	v_pk_mul_f32 v[78:79], v[86:87], v[86:87] op_sel:[0,0] op_sel_hi:[0,1]
	v_pk_fma_f32 v[78:79], v[86:87], v[86:87], v[78:79] op_sel:[1,1,0] op_sel_hi:[1,0,1] neg_lo:[0,1,0]
	s_waitcnt lgkmcnt(0)
	v_pk_mul_f32 v[84:85], v[80:81], v[78:79] op_sel:[0,0] op_sel_hi:[0,1] neg_hi:[0,1]
	v_pk_fma_f32 v[90:91], v[80:81], v[78:79], v[84:85] op_sel:[1,1,0] op_sel_hi:[1,0,1]
	v_pk_mul_f32 v[80:81], v[78:79], v[86:87] op_sel:[0,0] op_sel_hi:[0,1]
	v_pk_fma_f32 v[84:85], v[78:79], v[86:87], v[80:81] op_sel:[1,1,0] op_sel_hi:[1,0,1] neg_lo:[0,1,0]
	ds_read2_b64 v[78:81], v134 offset0:68 offset1:85
	v_pk_mul_f32 v[92:93], v[82:83], v[84:85] op_sel:[0,0] op_sel_hi:[0,1] neg_hi:[0,1]
	v_pk_fma_f32 v[92:93], v[82:83], v[84:85], v[92:93] op_sel:[1,1,0] op_sel_hi:[1,0,1]
	v_pk_mul_f32 v[82:83], v[84:85], v[86:87] op_sel:[0,0] op_sel_hi:[0,1]
	v_pk_fma_f32 v[82:83], v[84:85], v[86:87], v[82:83] op_sel:[1,1,0] op_sel_hi:[1,0,1] neg_lo:[0,1,0]
	s_waitcnt lgkmcnt(0)
	v_pk_mul_f32 v[84:85], v[78:79], v[82:83] op_sel:[0,0] op_sel_hi:[0,1] neg_hi:[0,1]
	v_pk_fma_f32 v[94:95], v[78:79], v[82:83], v[84:85] op_sel:[1,1,0] op_sel_hi:[1,0,1]
	v_pk_mul_f32 v[78:79], v[82:83], v[86:87] op_sel:[0,0] op_sel_hi:[0,1]
	v_pk_fma_f32 v[78:79], v[82:83], v[86:87], v[78:79] op_sel:[1,1,0] op_sel_hi:[1,0,1] neg_lo:[0,1,0]
	ds_read2_b64 v[82:85], v134 offset0:102 offset1:119
	v_pk_mul_f32 v[96:97], v[80:81], v[78:79] op_sel:[0,0] op_sel_hi:[0,1] neg_hi:[0,1]
	v_pk_fma_f32 v[96:97], v[80:81], v[78:79], v[96:97] op_sel:[1,1,0] op_sel_hi:[1,0,1]
	v_pk_mul_f32 v[80:81], v[78:79], v[86:87] op_sel:[0,0] op_sel_hi:[0,1]
	v_pk_fma_f32 v[78:79], v[78:79], v[86:87], v[80:81] op_sel:[1,1,0] op_sel_hi:[1,0,1] neg_lo:[0,1,0]
	s_waitcnt lgkmcnt(0)
	v_pk_mul_f32 v[80:81], v[82:83], v[78:79] op_sel:[0,0] op_sel_hi:[0,1] neg_hi:[0,1]
	v_pk_fma_f32 v[98:99], v[82:83], v[78:79], v[80:81] op_sel:[1,1,0] op_sel_hi:[1,0,1]
	v_pk_mul_f32 v[80:81], v[78:79], v[86:87] op_sel:[0,0] op_sel_hi:[0,1]
	v_pk_fma_f32 v[82:83], v[78:79], v[86:87], v[80:81] op_sel:[1,1,0] op_sel_hi:[1,0,1] neg_lo:[0,1,0]
	ds_read2_b64 v[78:81], v134 offset0:136 offset1:153
	v_pk_mul_f32 v[100:101], v[84:85], v[82:83] op_sel:[0,0] op_sel_hi:[0,1] neg_hi:[0,1]
	v_pk_fma_f32 v[100:101], v[84:85], v[82:83], v[100:101] op_sel:[1,1,0] op_sel_hi:[1,0,1]
	v_pk_mul_f32 v[84:85], v[82:83], v[86:87] op_sel:[0,0] op_sel_hi:[0,1]
	v_pk_fma_f32 v[82:83], v[82:83], v[86:87], v[84:85] op_sel:[1,1,0] op_sel_hi:[1,0,1] neg_lo:[0,1,0]
	s_waitcnt lgkmcnt(0)
	v_pk_mul_f32 v[84:85], v[78:79], v[82:83] op_sel:[0,0] op_sel_hi:[0,1] neg_hi:[0,1]
	v_pk_fma_f32 v[102:103], v[78:79], v[82:83], v[84:85] op_sel:[1,1,0] op_sel_hi:[1,0,1]
	v_pk_mul_f32 v[78:79], v[82:83], v[86:87] op_sel:[0,0] op_sel_hi:[0,1]
	v_pk_fma_f32 v[78:79], v[82:83], v[86:87], v[78:79] op_sel:[1,1,0] op_sel_hi:[1,0,1] neg_lo:[0,1,0]
	ds_read2_b64 v[82:85], v134 offset0:170 offset1:187
	v_pk_mul_f32 v[104:105], v[80:81], v[78:79] op_sel:[0,0] op_sel_hi:[0,1] neg_hi:[0,1]
	v_pk_fma_f32 v[104:105], v[80:81], v[78:79], v[104:105] op_sel:[1,1,0] op_sel_hi:[1,0,1]
	v_pk_mul_f32 v[80:81], v[78:79], v[86:87] op_sel:[0,0] op_sel_hi:[0,1]
	v_pk_fma_f32 v[78:79], v[78:79], v[86:87], v[80:81] op_sel:[1,1,0] op_sel_hi:[1,0,1] neg_lo:[0,1,0]
	s_waitcnt lgkmcnt(0)
	v_pk_mul_f32 v[80:81], v[82:83], v[78:79] op_sel:[0,0] op_sel_hi:[0,1] neg_hi:[0,1]
	v_pk_fma_f32 v[106:107], v[82:83], v[78:79], v[80:81] op_sel:[1,1,0] op_sel_hi:[1,0,1]
	v_pk_mul_f32 v[80:81], v[78:79], v[86:87] op_sel:[0,0] op_sel_hi:[0,1]
	v_pk_fma_f32 v[82:83], v[78:79], v[86:87], v[80:81] op_sel:[1,1,0] op_sel_hi:[1,0,1] neg_lo:[0,1,0]
	ds_read2_b64 v[78:81], v134 offset0:204 offset1:221
	v_pk_mul_f32 v[110:111], v[84:85], v[82:83] op_sel:[0,0] op_sel_hi:[0,1] neg_hi:[0,1]
	v_pk_fma_f32 v[110:111], v[84:85], v[82:83], v[110:111] op_sel:[1,1,0] op_sel_hi:[1,0,1]
	v_pk_mul_f32 v[84:85], v[82:83], v[86:87] op_sel:[0,0] op_sel_hi:[0,1]
	v_pk_fma_f32 v[82:83], v[82:83], v[86:87], v[84:85] op_sel:[1,1,0] op_sel_hi:[1,0,1] neg_lo:[0,1,0]
	s_waitcnt lgkmcnt(0)
	v_pk_mul_f32 v[84:85], v[78:79], v[82:83] op_sel:[0,0] op_sel_hi:[0,1] neg_hi:[0,1]
	v_pk_fma_f32 v[78:79], v[78:79], v[82:83], v[84:85] op_sel:[1,1,0] op_sel_hi:[1,0,1]
	v_pk_mul_f32 v[84:85], v[82:83], v[86:87] op_sel:[0,0] op_sel_hi:[0,1]
	v_pk_fma_f32 v[112:113], v[82:83], v[86:87], v[84:85] op_sel:[1,1,0] op_sel_hi:[1,0,1] neg_lo:[0,1,0]
	ds_read2_b64 v[82:85], v134 offset0:238 offset1:255
	v_pk_mul_f32 v[114:115], v[80:81], v[112:113] op_sel:[0,0] op_sel_hi:[0,1] neg_hi:[0,1]
	v_pk_fma_f32 v[80:81], v[80:81], v[112:113], v[114:115] op_sel:[1,1,0] op_sel_hi:[1,0,1]
	v_pk_mul_f32 v[114:115], v[112:113], v[86:87] op_sel:[0,0] op_sel_hi:[0,1]
	v_pk_fma_f32 v[112:113], v[112:113], v[86:87], v[114:115] op_sel:[1,1,0] op_sel_hi:[1,0,1] neg_lo:[0,1,0]
	s_waitcnt lgkmcnt(0)
	v_pk_mul_f32 v[114:115], v[82:83], v[112:113] op_sel:[0,0] op_sel_hi:[0,1] neg_hi:[0,1]
	v_pk_fma_f32 v[82:83], v[82:83], v[112:113], v[114:115] op_sel:[1,1,0] op_sel_hi:[1,0,1]
	v_pk_mul_f32 v[114:115], v[112:113], v[86:87] op_sel:[0,0] op_sel_hi:[0,1]
	v_pk_fma_f32 v[86:87], v[112:113], v[86:87], v[114:115] op_sel:[1,1,0] op_sel_hi:[1,0,1] neg_lo:[0,1,0]
	v_pk_mul_f32 v[112:113], v[84:85], v[86:87] op_sel:[0,0] op_sel_hi:[0,1] neg_hi:[0,1]
	v_pk_fma_f32 v[84:85], v[84:85], v[86:87], v[112:113] op_sel:[1,1,0] op_sel_hi:[1,0,1]
	v_pk_add_f32 v[86:87], v[76:77], v[102:103]
	v_pk_add_f32 v[76:77], v[76:77], v[102:103] neg_lo:[0,1] neg_hi:[0,1]
	v_pk_add_f32 v[102:103], v[94:95], v[78:79]
	v_pk_add_f32 v[78:79], v[94:95], v[78:79] neg_lo:[0,1] neg_hi:[0,1]
	v_pk_add_f32 v[94:95], v[86:87], v[102:103]
	v_pk_add_f32 v[86:87], v[86:87], v[102:103] neg_lo:[0,1] neg_hi:[0,1]
	v_pk_add_f32 v[102:103], v[76:77], v[78:79] op_sel:[0,1] op_sel_hi:[1,0] neg_lo:[0,1]
	v_pk_add_f32 v[76:77], v[76:77], v[78:79] op_sel:[0,1] op_sel_hi:[1,0] neg_hi:[0,1]
	v_pk_add_f32 v[78:79], v[88:89], v[104:105]
	v_pk_add_f32 v[88:89], v[88:89], v[104:105] neg_lo:[0,1] neg_hi:[0,1]
	v_pk_add_f32 v[104:105], v[96:97], v[80:81]
	v_pk_add_f32 v[80:81], v[96:97], v[80:81] neg_lo:[0,1] neg_hi:[0,1]
	v_pk_add_f32 v[96:97], v[78:79], v[104:105]
	v_pk_add_f32 v[78:79], v[78:79], v[104:105] neg_lo:[0,1] neg_hi:[0,1]
	v_pk_add_f32 v[104:105], v[88:89], v[80:81] op_sel:[0,1] op_sel_hi:[1,0] neg_lo:[0,1]
	v_pk_add_f32 v[80:81], v[88:89], v[80:81] op_sel:[0,1] op_sel_hi:[1,0] neg_hi:[0,1]
	v_pk_add_f32 v[88:89], v[90:91], v[106:107]
	v_pk_add_f32 v[90:91], v[90:91], v[106:107] neg_lo:[0,1] neg_hi:[0,1]
	v_pk_add_f32 v[106:107], v[98:99], v[82:83]
	v_pk_add_f32 v[82:83], v[98:99], v[82:83] neg_lo:[0,1] neg_hi:[0,1]
	v_pk_add_f32 v[98:99], v[88:89], v[106:107]
	v_pk_add_f32 v[88:89], v[88:89], v[106:107] neg_lo:[0,1] neg_hi:[0,1]
	v_pk_add_f32 v[106:107], v[90:91], v[82:83] op_sel:[0,1] op_sel_hi:[1,0] neg_lo:[0,1]
	v_pk_add_f32 v[82:83], v[90:91], v[82:83] op_sel:[0,1] op_sel_hi:[1,0] neg_hi:[0,1]
	v_pk_add_f32 v[90:91], v[92:93], v[110:111]
	v_pk_add_f32 v[92:93], v[92:93], v[110:111] neg_lo:[0,1] neg_hi:[0,1]
	v_pk_add_f32 v[110:111], v[100:101], v[84:85]
	v_pk_add_f32 v[84:85], v[100:101], v[84:85] neg_lo:[0,1] neg_hi:[0,1]
	v_pk_add_f32 v[100:101], v[90:91], v[110:111]
	v_pk_add_f32 v[90:91], v[90:91], v[110:111] neg_lo:[0,1] neg_hi:[0,1]
	v_pk_add_f32 v[110:111], v[92:93], v[84:85] op_sel:[0,1] op_sel_hi:[1,0] neg_lo:[0,1]
	v_pk_add_f32 v[84:85], v[92:93], v[84:85] op_sel:[0,1] op_sel_hi:[1,0] neg_hi:[0,1]
	v_pk_mul_f32 v[92:93], v[104:105], v[70:71] op_sel:[0,0] op_sel_hi:[0,1]
	v_pk_fma_f32 v[92:93], v[104:105], v[70:71], v[92:93] op_sel:[1,1,0] op_sel_hi:[1,0,1] neg_lo:[0,1,0]
	v_pk_mul_f32 v[104:105], v[106:107], v[30:31] op_sel:[0,0] op_sel_hi:[0,1]
	v_pk_fma_f32 v[104:105], v[106:107], v[30:31], v[104:105] op_sel:[1,1,0] op_sel_hi:[1,0,1] neg_lo:[0,1,0]
	v_pk_mul_f32 v[106:107], v[110:111], v[28:29] op_sel:[0,0] op_sel_hi:[0,1]
	v_pk_fma_f32 v[106:107], v[110:111], v[28:29], v[106:107] op_sel:[1,1,0] op_sel_hi:[1,0,1] neg_lo:[0,1,0]
	v_pk_mul_f32 v[110:111], v[78:79], v[30:31] op_sel:[0,0] op_sel_hi:[0,1]
	v_pk_fma_f32 v[78:79], v[78:79], v[30:31], v[110:111] op_sel:[1,1,0] op_sel_hi:[1,0,1] neg_lo:[0,1,0]
	v_pk_mul_f32 v[110:111], v[88:89], v[72:73] op_sel:[0,0] op_sel_hi:[0,1]
	v_pk_fma_f32 v[88:89], v[88:89], v[72:73], v[110:111] op_sel:[1,1,0] op_sel_hi:[1,0,1] neg_lo:[0,1,0]
	v_pk_mul_f32 v[110:111], v[90:91], v[32:33] op_sel:[0,0] op_sel_hi:[0,1]
	v_pk_fma_f32 v[90:91], v[90:91], v[32:33], v[110:111] op_sel:[1,1,0] op_sel_hi:[1,0,1] neg_lo:[0,1,0]
	v_pk_mul_f32 v[110:111], v[80:81], v[28:29] op_sel:[0,0] op_sel_hi:[0,1]
	v_pk_fma_f32 v[80:81], v[80:81], v[28:29], v[110:111] op_sel:[1,1,0] op_sel_hi:[1,0,1] neg_lo:[0,1,0]
	v_pk_mul_f32 v[110:111], v[82:83], v[32:33] op_sel:[0,0] op_sel_hi:[0,1]
	v_pk_fma_f32 v[82:83], v[82:83], v[32:33], v[110:111] op_sel:[1,1,0] op_sel_hi:[1,0,1] neg_lo:[0,1,0]
	v_pk_mul_f32 v[110:111], v[84:85], v[74:75] op_sel:[0,0] op_sel_hi:[0,1]
	v_pk_fma_f32 v[84:85], v[84:85], v[74:75], v[110:111] op_sel:[1,1,0] op_sel_hi:[1,0,1] neg_lo:[0,1,0]
	v_pk_add_f32 v[110:111], v[94:95], v[98:99]
	v_pk_add_f32 v[94:95], v[94:95], v[98:99] neg_lo:[0,1] neg_hi:[0,1]
	v_pk_add_f32 v[98:99], v[96:97], v[100:101]
	v_pk_add_f32 v[96:97], v[96:97], v[100:101] neg_lo:[0,1] neg_hi:[0,1]
	v_pk_add_f32 v[100:101], v[110:111], v[98:99]
	v_pk_add_f32 v[98:99], v[110:111], v[98:99] neg_lo:[0,1] neg_hi:[0,1]
	v_pk_add_f32 v[110:111], v[94:95], v[96:97] op_sel:[0,1] op_sel_hi:[1,0] neg_lo:[0,1]
	v_pk_add_f32 v[94:95], v[94:95], v[96:97] op_sel:[0,1] op_sel_hi:[1,0] neg_hi:[0,1]
	v_pk_add_f32 v[96:97], v[102:103], v[104:105]
	v_pk_add_f32 v[102:103], v[102:103], v[104:105] neg_lo:[0,1] neg_hi:[0,1]
	v_pk_add_f32 v[104:105], v[92:93], v[106:107]
	v_pk_add_f32 v[92:93], v[92:93], v[106:107] neg_lo:[0,1] neg_hi:[0,1]
	v_pk_add_f32 v[106:107], v[96:97], v[104:105]
	v_pk_add_f32 v[96:97], v[96:97], v[104:105] neg_lo:[0,1] neg_hi:[0,1]
	v_pk_add_f32 v[104:105], v[102:103], v[92:93] op_sel:[0,1] op_sel_hi:[1,0] neg_lo:[0,1]
	v_pk_add_f32 v[92:93], v[102:103], v[92:93] op_sel:[0,1] op_sel_hi:[1,0] neg_hi:[0,1]
	v_pk_add_f32 v[102:103], v[86:87], v[88:89]
	v_pk_add_f32 v[86:87], v[86:87], v[88:89] neg_lo:[0,1] neg_hi:[0,1]
	v_pk_add_f32 v[88:89], v[78:79], v[90:91]
	v_pk_add_f32 v[78:79], v[78:79], v[90:91] neg_lo:[0,1] neg_hi:[0,1]
	v_pk_add_f32 v[90:91], v[102:103], v[88:89]
	v_pk_add_f32 v[88:89], v[102:103], v[88:89] neg_lo:[0,1] neg_hi:[0,1]
	v_pk_add_f32 v[102:103], v[86:87], v[78:79] op_sel:[0,1] op_sel_hi:[1,0] neg_lo:[0,1]
	v_pk_add_f32 v[78:79], v[86:87], v[78:79] op_sel:[0,1] op_sel_hi:[1,0] neg_hi:[0,1]
	v_pk_add_f32 v[86:87], v[76:77], v[82:83]
	v_pk_add_f32 v[76:77], v[76:77], v[82:83] neg_lo:[0,1] neg_hi:[0,1]
	v_pk_add_f32 v[82:83], v[80:81], v[84:85]
	v_pk_add_f32 v[80:81], v[80:81], v[84:85] neg_lo:[0,1] neg_hi:[0,1]
	v_pk_add_f32 v[84:85], v[86:87], v[82:83]
	v_pk_add_f32 v[82:83], v[86:87], v[82:83] neg_lo:[0,1] neg_hi:[0,1]
	v_pk_add_f32 v[86:87], v[76:77], v[80:81] op_sel:[0,1] op_sel_hi:[1,0] neg_lo:[0,1]
	v_pk_add_f32 v[76:77], v[76:77], v[80:81] op_sel:[0,1] op_sel_hi:[1,0] neg_hi:[0,1]
	ds_write2_b64 v134, v[100:101], v[106:107] offset1:17
	ds_write2_b64 v134, v[90:91], v[84:85] offset0:34 offset1:51
	ds_write2_b64 v134, v[110:111], v[104:105] offset0:68 offset1:85
	ds_write2_b64 v134, v[102:103], v[86:87] offset0:102 offset1:119
	ds_write2_b64 v134, v[98:99], v[96:97] offset0:136 offset1:153
	ds_write2_b64 v134, v[88:89], v[82:83] offset0:170 offset1:187
	ds_write2_b64 v134, v[94:95], v[92:93] offset0:204 offset1:221
	ds_write2_b64 v134, v[78:79], v[76:77] offset0:238 offset1:255
	v_mov_b32_e32 v77, v39
	v_mov_b32_e32 v76, v38
	s_waitcnt lgkmcnt(0)
	s_barrier
	ds_read_b64 v[78:79], v132 offset:2176
	ds_read_b64 v[80:81], v132 offset:4352
	ds_read_b64 v[82:83], v132 offset:6528
	ds_read_b64 v[84:85], v132
	s_waitcnt lgkmcnt(3)
	v_pk_mul_f32 v[86:87], v[78:79], v[76:77] op_sel:[0,0] op_sel_hi:[0,1] neg_hi:[0,1]
	v_pk_fma_f32 v[78:79], v[78:79], v[76:77], v[86:87] op_sel:[1,1,0] op_sel_hi:[1,0,1]
	v_pk_mul_f32 v[86:87], v[76:77], v[76:77] op_sel:[0,0] op_sel_hi:[0,1]
	ds_read_b64 v[90:91], v132 offset:8704
	v_pk_fma_f32 v[86:87], v[76:77], v[76:77], v[86:87] op_sel:[1,1,0] op_sel_hi:[1,0,1] neg_lo:[0,1,0]
	s_waitcnt lgkmcnt(3)
	v_pk_mul_f32 v[88:89], v[80:81], v[86:87] op_sel:[0,0] op_sel_hi:[0,1] neg_hi:[0,1]
	v_pk_fma_f32 v[80:81], v[80:81], v[86:87], v[88:89] op_sel:[1,1,0] op_sel_hi:[1,0,1]
	v_pk_mul_f32 v[88:89], v[86:87], v[76:77] op_sel:[0,0] op_sel_hi:[0,1]
	v_pk_fma_f32 v[86:87], v[86:87], v[76:77], v[88:89] op_sel:[1,1,0] op_sel_hi:[1,0,1] neg_lo:[0,1,0]
	s_waitcnt lgkmcnt(2)
	v_pk_mul_f32 v[88:89], v[82:83], v[86:87] op_sel:[0,0] op_sel_hi:[0,1] neg_hi:[0,1]
	v_pk_fma_f32 v[82:83], v[82:83], v[86:87], v[88:89] op_sel:[1,1,0] op_sel_hi:[1,0,1]
	v_pk_mul_f32 v[88:89], v[86:87], v[76:77] op_sel:[0,0] op_sel_hi:[0,1]
	v_pk_fma_f32 v[86:87], v[86:87], v[76:77], v[88:89] op_sel:[1,1,0] op_sel_hi:[1,0,1] neg_lo:[0,1,0]
	ds_read_b64 v[88:89], v132 offset:10880
	ds_read_b64 v[92:93], v132 offset:13056
	ds_read_b64 v[94:95], v132 offset:15232
	s_waitcnt lgkmcnt(3)
	v_pk_mul_f32 v[96:97], v[90:91], v[86:87] op_sel:[0,0] op_sel_hi:[0,1] neg_hi:[0,1]
	ds_read_b64 v[98:99], v132 offset:17408
	v_pk_fma_f32 v[90:91], v[90:91], v[86:87], v[96:97] op_sel:[1,1,0] op_sel_hi:[1,0,1]
	v_pk_mul_f32 v[96:97], v[86:87], v[76:77] op_sel:[0,0] op_sel_hi:[0,1]
	v_pk_fma_f32 v[86:87], v[86:87], v[76:77], v[96:97] op_sel:[1,1,0] op_sel_hi:[1,0,1] neg_lo:[0,1,0]
	s_waitcnt lgkmcnt(3)
	v_pk_mul_f32 v[96:97], v[88:89], v[86:87] op_sel:[0,0] op_sel_hi:[0,1] neg_hi:[0,1]
	v_pk_fma_f32 v[88:89], v[88:89], v[86:87], v[96:97] op_sel:[1,1,0] op_sel_hi:[1,0,1]
	v_pk_mul_f32 v[96:97], v[86:87], v[76:77] op_sel:[0,0] op_sel_hi:[0,1]
	v_pk_fma_f32 v[86:87], v[86:87], v[76:77], v[96:97] op_sel:[1,1,0] op_sel_hi:[1,0,1] neg_lo:[0,1,0]
	s_waitcnt lgkmcnt(2)
	v_pk_mul_f32 v[96:97], v[92:93], v[86:87] op_sel:[0,0] op_sel_hi:[0,1] neg_hi:[0,1]
	v_pk_fma_f32 v[92:93], v[92:93], v[86:87], v[96:97] op_sel:[1,1,0] op_sel_hi:[1,0,1]
	v_pk_mul_f32 v[96:97], v[86:87], v[76:77] op_sel:[0,0] op_sel_hi:[0,1]
	v_pk_fma_f32 v[86:87], v[86:87], v[76:77], v[96:97] op_sel:[1,1,0] op_sel_hi:[1,0,1] neg_lo:[0,1,0]
	s_waitcnt lgkmcnt(1)
	v_pk_mul_f32 v[96:97], v[94:95], v[86:87] op_sel:[0,0] op_sel_hi:[0,1] neg_hi:[0,1]
	v_pk_fma_f32 v[94:95], v[94:95], v[86:87], v[96:97] op_sel:[1,1,0] op_sel_hi:[1,0,1]
	v_pk_mul_f32 v[96:97], v[86:87], v[76:77] op_sel:[0,0] op_sel_hi:[0,1]
	v_pk_fma_f32 v[86:87], v[86:87], v[76:77], v[96:97] op_sel:[1,1,0] op_sel_hi:[1,0,1] neg_lo:[0,1,0]
	ds_read_b64 v[96:97], v132 offset:19584
	ds_read_b64 v[100:101], v132 offset:21760
	ds_read_b64 v[102:103], v132 offset:23936
	s_waitcnt lgkmcnt(3)
	v_pk_mul_f32 v[104:105], v[98:99], v[86:87] op_sel:[0,0] op_sel_hi:[0,1] neg_hi:[0,1]
	ds_read_b64 v[106:107], v132 offset:26112
	v_pk_fma_f32 v[98:99], v[98:99], v[86:87], v[104:105] op_sel:[1,1,0] op_sel_hi:[1,0,1]
	v_pk_mul_f32 v[104:105], v[86:87], v[76:77] op_sel:[0,0] op_sel_hi:[0,1]
	v_pk_fma_f32 v[86:87], v[86:87], v[76:77], v[104:105] op_sel:[1,1,0] op_sel_hi:[1,0,1] neg_lo:[0,1,0]
	s_waitcnt lgkmcnt(3)
	v_pk_mul_f32 v[104:105], v[96:97], v[86:87] op_sel:[0,0] op_sel_hi:[0,1] neg_hi:[0,1]
	v_pk_fma_f32 v[96:97], v[96:97], v[86:87], v[104:105] op_sel:[1,1,0] op_sel_hi:[1,0,1]
	v_pk_mul_f32 v[104:105], v[86:87], v[76:77] op_sel:[0,0] op_sel_hi:[0,1]
	v_pk_fma_f32 v[86:87], v[86:87], v[76:77], v[104:105] op_sel:[1,1,0] op_sel_hi:[1,0,1] neg_lo:[0,1,0]
	s_waitcnt lgkmcnt(2)
	v_pk_mul_f32 v[104:105], v[100:101], v[86:87] op_sel:[0,0] op_sel_hi:[0,1] neg_hi:[0,1]
	v_pk_fma_f32 v[100:101], v[100:101], v[86:87], v[104:105] op_sel:[1,1,0] op_sel_hi:[1,0,1]
	v_pk_mul_f32 v[104:105], v[86:87], v[76:77] op_sel:[0,0] op_sel_hi:[0,1]
	v_pk_fma_f32 v[86:87], v[86:87], v[76:77], v[104:105] op_sel:[1,1,0] op_sel_hi:[1,0,1] neg_lo:[0,1,0]
	s_waitcnt lgkmcnt(1)
	v_pk_mul_f32 v[104:105], v[102:103], v[86:87] op_sel:[0,0] op_sel_hi:[0,1] neg_hi:[0,1]
	v_pk_fma_f32 v[102:103], v[102:103], v[86:87], v[104:105] op_sel:[1,1,0] op_sel_hi:[1,0,1]
	v_pk_mul_f32 v[104:105], v[86:87], v[76:77] op_sel:[0,0] op_sel_hi:[0,1]
	v_pk_fma_f32 v[86:87], v[86:87], v[76:77], v[104:105] op_sel:[1,1,0] op_sel_hi:[1,0,1] neg_lo:[0,1,0]
	ds_read_b64 v[104:105], v132 offset:28288
	ds_read_b64 v[110:111], v132 offset:30464
	ds_read_b64 v[112:113], v132 offset:32640
	s_waitcnt lgkmcnt(3)
	v_pk_mul_f32 v[114:115], v[106:107], v[86:87] op_sel:[0,0] op_sel_hi:[0,1] neg_hi:[0,1]
	v_pk_fma_f32 v[106:107], v[106:107], v[86:87], v[114:115] op_sel:[1,1,0] op_sel_hi:[1,0,1]
	v_pk_mul_f32 v[114:115], v[86:87], v[76:77] op_sel:[0,0] op_sel_hi:[0,1]
	v_pk_fma_f32 v[86:87], v[86:87], v[76:77], v[114:115] op_sel:[1,1,0] op_sel_hi:[1,0,1] neg_lo:[0,1,0]
	s_waitcnt lgkmcnt(2)
	v_pk_mul_f32 v[114:115], v[104:105], v[86:87] op_sel:[0,0] op_sel_hi:[0,1] neg_hi:[0,1]
	v_pk_fma_f32 v[104:105], v[104:105], v[86:87], v[114:115] op_sel:[1,1,0] op_sel_hi:[1,0,1]
	v_pk_mul_f32 v[114:115], v[86:87], v[76:77] op_sel:[0,0] op_sel_hi:[0,1]
	v_pk_fma_f32 v[86:87], v[86:87], v[76:77], v[114:115] op_sel:[1,1,0] op_sel_hi:[1,0,1] neg_lo:[0,1,0]
	s_waitcnt lgkmcnt(1)
	v_pk_mul_f32 v[114:115], v[110:111], v[86:87] op_sel:[0,0] op_sel_hi:[0,1] neg_hi:[0,1]
	v_pk_fma_f32 v[110:111], v[110:111], v[86:87], v[114:115] op_sel:[1,1,0] op_sel_hi:[1,0,1]
	v_pk_mul_f32 v[114:115], v[86:87], v[76:77] op_sel:[0,0] op_sel_hi:[0,1]
	v_pk_fma_f32 v[76:77], v[86:87], v[76:77], v[114:115] op_sel:[1,1,0] op_sel_hi:[1,0,1] neg_lo:[0,1,0]
	s_waitcnt lgkmcnt(0)
	v_pk_mul_f32 v[86:87], v[112:113], v[76:77] op_sel:[0,0] op_sel_hi:[0,1] neg_hi:[0,1]
	v_pk_fma_f32 v[76:77], v[112:113], v[76:77], v[86:87] op_sel:[1,1,0] op_sel_hi:[1,0,1]
	v_pk_add_f32 v[86:87], v[84:85], v[98:99]
	v_pk_add_f32 v[84:85], v[84:85], v[98:99] neg_lo:[0,1] neg_hi:[0,1]
	v_pk_add_f32 v[98:99], v[90:91], v[106:107]
	v_pk_add_f32 v[90:91], v[90:91], v[106:107] neg_lo:[0,1] neg_hi:[0,1]
	v_pk_add_f32 v[106:107], v[86:87], v[98:99]
	v_pk_add_f32 v[98:99], v[86:87], v[98:99] neg_lo:[0,1] neg_hi:[0,1]
	v_pk_add_f32 v[86:87], v[84:85], v[90:91] op_sel:[0,1] op_sel_hi:[1,0] neg_lo:[0,1]
	v_pk_add_f32 v[112:113], v[84:85], v[90:91] op_sel:[0,1] op_sel_hi:[1,0] neg_hi:[0,1]
	v_pk_add_f32 v[84:85], v[78:79], v[96:97]
	v_pk_add_f32 v[78:79], v[78:79], v[96:97] neg_lo:[0,1] neg_hi:[0,1]
	v_pk_add_f32 v[90:91], v[88:89], v[104:105]
	v_pk_add_f32 v[88:89], v[88:89], v[104:105] neg_lo:[0,1] neg_hi:[0,1]
	v_pk_add_f32 v[96:97], v[84:85], v[90:91]
	v_pk_add_f32 v[84:85], v[84:85], v[90:91] neg_lo:[0,1] neg_hi:[0,1]
	v_pk_add_f32 v[90:91], v[78:79], v[88:89] op_sel:[0,1] op_sel_hi:[1,0] neg_lo:[0,1]
	v_pk_add_f32 v[78:79], v[78:79], v[88:89] op_sel:[0,1] op_sel_hi:[1,0] neg_hi:[0,1]
	v_pk_add_f32 v[88:89], v[80:81], v[100:101]
	v_pk_add_f32 v[80:81], v[80:81], v[100:101] neg_lo:[0,1] neg_hi:[0,1]
	v_pk_add_f32 v[100:101], v[92:93], v[110:111]
	v_pk_add_f32 v[92:93], v[92:93], v[110:111] neg_lo:[0,1] neg_hi:[0,1]
	v_pk_add_f32 v[104:105], v[88:89], v[100:101]
	v_pk_add_f32 v[88:89], v[88:89], v[100:101] neg_lo:[0,1] neg_hi:[0,1]
	v_pk_add_f32 v[100:101], v[80:81], v[92:93] op_sel:[0,1] op_sel_hi:[1,0] neg_lo:[0,1]
	v_pk_add_f32 v[80:81], v[80:81], v[92:93] op_sel:[0,1] op_sel_hi:[1,0] neg_hi:[0,1]
	v_pk_add_f32 v[92:93], v[82:83], v[102:103]
	v_pk_add_f32 v[82:83], v[82:83], v[102:103] neg_lo:[0,1] neg_hi:[0,1]
	v_pk_add_f32 v[102:103], v[94:95], v[76:77]
	v_pk_add_f32 v[76:77], v[94:95], v[76:77] neg_lo:[0,1] neg_hi:[0,1]
	v_pk_add_f32 v[94:95], v[92:93], v[102:103]
	v_pk_add_f32 v[92:93], v[92:93], v[102:103] neg_lo:[0,1] neg_hi:[0,1]
	v_pk_add_f32 v[102:103], v[82:83], v[76:77] op_sel:[0,1] op_sel_hi:[1,0] neg_lo:[0,1]
	v_pk_add_f32 v[76:77], v[82:83], v[76:77] op_sel:[0,1] op_sel_hi:[1,0] neg_hi:[0,1]
	v_pk_mul_f32 v[82:83], v[90:91], v[70:71] op_sel:[0,0] op_sel_hi:[0,1]
	v_pk_fma_f32 v[70:71], v[90:91], v[70:71], v[82:83] op_sel:[1,1,0] op_sel_hi:[1,0,1] neg_lo:[0,1,0]
	v_pk_mul_f32 v[82:83], v[100:101], v[30:31] op_sel:[0,0] op_sel_hi:[0,1]
	v_pk_mul_f32 v[90:91], v[102:103], v[28:29] op_sel:[0,0] op_sel_hi:[0,1]
	v_pk_fma_f32 v[82:83], v[100:101], v[30:31], v[82:83] op_sel:[1,1,0] op_sel_hi:[1,0,1] neg_lo:[0,1,0]
	v_pk_mul_f32 v[100:101], v[84:85], v[30:31] op_sel:[0,0] op_sel_hi:[0,1]
	v_pk_fma_f32 v[90:91], v[102:103], v[28:29], v[90:91] op_sel:[1,1,0] op_sel_hi:[1,0,1] neg_lo:[0,1,0]
	v_pk_fma_f32 v[110:111], v[84:85], v[30:31], v[100:101] op_sel:[1,1,0] op_sel_hi:[1,0,1] neg_lo:[0,1,0]
	v_pk_mul_f32 v[30:31], v[88:89], v[72:73] op_sel:[0,0] op_sel_hi:[0,1]
	v_pk_add_f32 v[84:85], v[70:71], v[90:91]
	v_pk_fma_f32 v[72:73], v[88:89], v[72:73], v[30:31] op_sel:[1,1,0] op_sel_hi:[1,0,1] neg_lo:[0,1,0]
	v_pk_mul_f32 v[30:31], v[92:93], v[32:33] op_sel:[0,0] op_sel_hi:[0,1]
	v_pk_fma_f32 v[88:89], v[92:93], v[32:33], v[30:31] op_sel:[1,1,0] op_sel_hi:[1,0,1] neg_lo:[0,1,0]
	v_pk_mul_f32 v[30:31], v[78:79], v[28:29] op_sel:[0,0] op_sel_hi:[0,1]
	v_pk_fma_f32 v[114:115], v[78:79], v[28:29], v[30:31] op_sel:[1,1,0] op_sel_hi:[1,0,1] neg_lo:[0,1,0]
	v_pk_mul_f32 v[28:29], v[80:81], v[32:33] op_sel:[0,0] op_sel_hi:[0,1]
	v_pk_add_f32 v[30:31], v[96:97], v[94:95] neg_lo:[0,1] neg_hi:[0,1]
	v_pk_fma_f32 v[116:117], v[80:81], v[32:33], v[28:29] op_sel:[1,1,0] op_sel_hi:[1,0,1] neg_lo:[0,1,0]
	v_pk_mul_f32 v[28:29], v[76:77], v[74:75] op_sel:[0,0] op_sel_hi:[0,1]
	v_pk_add_f32 v[32:33], v[70:71], v[90:91] neg_lo:[0,1] neg_hi:[0,1]
	v_pk_fma_f32 v[140:141], v[76:77], v[74:75], v[28:29] op_sel:[1,1,0] op_sel_hi:[1,0,1] neg_lo:[0,1,0]
	v_pk_add_f32 v[28:29], v[106:107], v[104:105] neg_lo:[0,1] neg_hi:[0,1]
	v_pk_add_f32 v[80:81], v[86:87], v[82:83]
	v_pk_add_f32 v[76:77], v[28:29], v[30:31] op_sel:[0,1] op_sel_hi:[1,0] neg_lo:[0,1]
	v_pk_add_f32 v[28:29], v[28:29], v[30:31] op_sel:[0,1] op_sel_hi:[1,0] neg_hi:[0,1]
	v_pk_add_f32 v[30:31], v[86:87], v[82:83] neg_lo:[0,1] neg_hi:[0,1]
	v_pk_add_f32 v[70:71], v[110:111], v[88:89] neg_lo:[0,1] neg_hi:[0,1]
	v_pk_add_f32 v[82:83], v[30:31], v[32:33] op_sel:[0,1] op_sel_hi:[1,0] neg_lo:[0,1]
	v_pk_add_f32 v[30:31], v[30:31], v[32:33] op_sel:[0,1] op_sel_hi:[1,0] neg_hi:[0,1]
	v_pk_add_f32 v[32:33], v[98:99], v[72:73] neg_lo:[0,1] neg_hi:[0,1]
	v_pk_add_f32 v[74:75], v[106:107], v[104:105]
	v_pk_add_f32 v[78:79], v[96:97], v[94:95]
	v_pk_add_f32 v[86:87], v[98:99], v[72:73]
	v_pk_add_f32 v[90:91], v[110:111], v[88:89]
	v_pk_add_f32 v[88:89], v[32:33], v[70:71] op_sel:[0,1] op_sel_hi:[1,0] neg_lo:[0,1]
	v_pk_add_f32 v[32:33], v[32:33], v[70:71] op_sel:[0,1] op_sel_hi:[1,0] neg_hi:[0,1]
	v_pk_add_f32 v[92:93], v[112:113], v[116:117]
	v_pk_add_f32 v[70:71], v[112:113], v[116:117] neg_lo:[0,1] neg_hi:[0,1]
	v_pk_add_f32 v[96:97], v[114:115], v[140:141]
	v_pk_add_f32 v[72:73], v[114:115], v[140:141] neg_lo:[0,1] neg_hi:[0,1]
	v_pk_add_f32 v[100:101], v[74:75], v[78:79]
	v_pk_add_f32 v[102:103], v[80:81], v[84:85]
	v_pk_add_f32 v[104:105], v[86:87], v[90:91]
	v_pk_add_f32 v[98:99], v[92:93], v[96:97]
	v_pk_add_f32 v[94:95], v[70:71], v[72:73] op_sel:[0,1] op_sel_hi:[1,0] neg_lo:[0,1]
	v_pk_add_f32 v[70:71], v[70:71], v[72:73] op_sel:[0,1] op_sel_hi:[1,0] neg_hi:[0,1]
	v_mov_b32_e32 v73, v37
	v_mov_b32_e32 v72, v36
	s_and_saveexec_b64 s[0:1], s[4:5]
	s_xor_b64 s[0:1], exec, s[0:1]
	s_cbranch_execz .LBB0_3402
	v_mov_b64_e32 v[106:107], s[12:13]
	v_pk_mul_f32 v[110:111], v[72:73], v[106:107] op_sel:[0,0] op_sel_hi:[0,1]
	v_pk_fma_f32 v[106:107], v[72:73], v[106:107], v[110:111] op_sel:[1,1,0] op_sel_hi:[1,0,1] neg_lo:[0,1,0]
	v_pk_mul_f32 v[110:111], v[100:101], v[106:107] op_sel:[0,0] op_sel_hi:[0,1] neg_hi:[0,1]
	v_pk_fma_f32 v[100:101], v[100:101], v[106:107], v[110:111] op_sel:[1,1,0] op_sel_hi:[1,0,1]
	v_mov_b64_e32 v[106:107], s[16:17]
	v_pk_mul_f32 v[110:111], v[72:73], v[106:107] op_sel:[0,0] op_sel_hi:[0,1]
	v_pk_fma_f32 v[106:107], v[72:73], v[106:107], v[110:111] op_sel:[1,1,0] op_sel_hi:[1,0,1] neg_lo:[0,1,0]
	v_pk_mul_f32 v[110:111], v[102:103], v[106:107] op_sel:[0,0] op_sel_hi:[0,1] neg_hi:[0,1]
	v_pk_fma_f32 v[102:103], v[102:103], v[106:107], v[110:111] op_sel:[1,1,0] op_sel_hi:[1,0,1]
	v_mov_b64_e32 v[106:107], s[20:21]
	v_pk_mul_f32 v[110:111], v[72:73], v[106:107] op_sel:[0,0] op_sel_hi:[0,1]
	v_pk_fma_f32 v[106:107], v[72:73], v[106:107], v[110:111] op_sel:[1,1,0] op_sel_hi:[1,0,1] neg_lo:[0,1,0]
	v_pk_mul_f32 v[110:111], v[104:105], v[106:107] op_sel:[0,0] op_sel_hi:[0,1] neg_hi:[0,1]
	v_pk_fma_f32 v[104:105], v[104:105], v[106:107], v[110:111] op_sel:[1,1,0] op_sel_hi:[1,0,1]
	v_mov_b64_e32 v[106:107], s[22:23]
	v_pk_mul_f32 v[110:111], v[72:73], v[106:107] op_sel:[0,0] op_sel_hi:[0,1]
	v_pk_fma_f32 v[106:107], v[72:73], v[106:107], v[110:111] op_sel:[1,1,0] op_sel_hi:[1,0,1] neg_lo:[0,1,0]
	v_pk_mul_f32 v[110:111], v[98:99], v[106:107] op_sel:[0,0] op_sel_hi:[0,1] neg_hi:[0,1]
	v_pk_fma_f32 v[98:99], v[98:99], v[106:107], v[110:111] op_sel:[1,1,0] op_sel_hi:[1,0,1]
	ds_write_b64 v132, v[100:101]
	ds_write_b64 v132, v[102:103] offset:2176
	ds_write_b64 v132, v[104:105] offset:4352
	ds_write_b64 v132, v[98:99] offset:6528
	v_mov_b64_e32 v[98:99], s[46:47]
	v_pk_mul_f32 v[100:101], v[72:73], v[98:99] op_sel:[0,0] op_sel_hi:[0,1]
	s_nop 0
	v_pk_fma_f32 v[98:99], v[72:73], v[98:99], v[100:101] op_sel:[1,1,0] op_sel_hi:[1,0,1] neg_lo:[0,1,0]
	v_pk_mul_f32 v[100:101], v[76:77], v[98:99] op_sel:[0,0] op_sel_hi:[0,1] neg_hi:[0,1]
	v_pk_fma_f32 v[76:77], v[76:77], v[98:99], v[100:101] op_sel:[1,1,0] op_sel_hi:[1,0,1]
	v_mov_b64_e32 v[98:99], s[48:49]
	v_pk_mul_f32 v[100:101], v[72:73], v[98:99] op_sel:[0,0] op_sel_hi:[0,1]
	v_pk_fma_f32 v[98:99], v[72:73], v[98:99], v[100:101] op_sel:[1,1,0] op_sel_hi:[1,0,1] neg_lo:[0,1,0]
	v_pk_mul_f32 v[100:101], v[82:83], v[98:99] op_sel:[0,0] op_sel_hi:[0,1] neg_hi:[0,1]
	v_pk_fma_f32 v[82:83], v[82:83], v[98:99], v[100:101] op_sel:[1,1,0] op_sel_hi:[1,0,1]
	v_mov_b64_e32 v[98:99], s[50:51]
	v_pk_mul_f32 v[100:101], v[72:73], v[98:99] op_sel:[0,0] op_sel_hi:[0,1]
	v_pk_fma_f32 v[98:99], v[72:73], v[98:99], v[100:101] op_sel:[1,1,0] op_sel_hi:[1,0,1] neg_lo:[0,1,0]
	v_pk_mul_f32 v[100:101], v[88:89], v[98:99] op_sel:[0,0] op_sel_hi:[0,1] neg_hi:[0,1]
	v_pk_fma_f32 v[88:89], v[88:89], v[98:99], v[100:101] op_sel:[1,1,0] op_sel_hi:[1,0,1]
	v_mov_b64_e32 v[98:99], s[52:53]
	v_pk_mul_f32 v[100:101], v[72:73], v[98:99] op_sel:[0,0] op_sel_hi:[0,1]
	v_pk_fma_f32 v[98:99], v[72:73], v[98:99], v[100:101] op_sel:[1,1,0] op_sel_hi:[1,0,1] neg_lo:[0,1,0]
	v_pk_mul_f32 v[100:101], v[94:95], v[98:99] op_sel:[0,0] op_sel_hi:[0,1] neg_hi:[0,1]
	s_nop 0
	v_pk_fma_f32 v[94:95], v[94:95], v[98:99], v[100:101] op_sel:[1,1,0] op_sel_hi:[1,0,1]

.LBB0_3404:
	s_or_b64 exec, exec, s[0:1]
	v_pk_add_f32 v[98:99], v[74:75], v[78:79] neg_lo:[0,1] neg_hi:[0,1]
	v_pk_add_f32 v[80:81], v[80:81], v[84:85] neg_lo:[0,1] neg_hi:[0,1]
	v_pk_add_f32 v[78:79], v[86:87], v[90:91] neg_lo:[0,1] neg_hi:[0,1]
	v_pk_add_f32 v[74:75], v[92:93], v[96:97] neg_lo:[0,1] neg_hi:[0,1]
	ds_write_b64 v132, v[76:77] offset:8704
	ds_write_b64 v132, v[82:83] offset:10880
	ds_write_b64 v132, v[88:89] offset:13056
	ds_write_b64 v132, v[94:95] offset:15232
	s_and_saveexec_b64 s[0:1], s[4:5]
	s_xor_b64 s[0:1], exec, s[0:1]
	s_cbranch_execz .LBB0_3406
	v_mov_b64_e32 v[76:77], s[8:9]
	v_pk_mul_f32 v[82:83], v[72:73], v[76:77] op_sel:[0,0] op_sel_hi:[0,1]
	s_mov_b32 s15, s53
	v_pk_fma_f32 v[76:77], v[72:73], v[76:77], v[82:83] op_sel:[1,1,0] op_sel_hi:[1,0,1] neg_lo:[0,1,0]
	s_mov_b32 s6, s23
	v_pk_mul_f32 v[82:83], v[98:99], v[76:77] op_sel:[0,0] op_sel_hi:[0,1] neg_hi:[0,1]
	s_mov_b32 s7, s49
	v_pk_fma_f32 v[76:77], v[98:99], v[76:77], v[82:83] op_sel:[1,1,0] op_sel_hi:[1,0,1]
	v_mov_b64_e32 v[82:83], s[14:15]
	v_pk_mul_f32 v[84:85], v[72:73], v[82:83] op_sel:[0,0] op_sel_hi:[0,1]
	s_nop 0
	v_pk_fma_f32 v[82:83], v[72:73], v[82:83], v[84:85] op_sel:[1,1,0] op_sel_hi:[1,0,1] neg_lo:[0,1,0]
	v_pk_mul_f32 v[84:85], v[80:81], v[82:83] op_sel:[0,0] op_sel_hi:[0,1] neg_hi:[0,1]
	v_pk_fma_f32 v[80:81], v[80:81], v[82:83], v[84:85] op_sel:[1,1,0] op_sel_hi:[1,0,1]
	v_mov_b64_e32 v[82:83], s[18:19]
	v_pk_mul_f32 v[84:85], v[72:73], v[82:83] op_sel:[0,0] op_sel_hi:[0,1]
	v_pk_fma_f32 v[82:83], v[72:73], v[82:83], v[84:85] op_sel:[1,1,0] op_sel_hi:[1,0,1] neg_lo:[0,1,0]
	v_pk_mul_f32 v[84:85], v[78:79], v[82:83] op_sel:[0,0] op_sel_hi:[0,1] neg_hi:[0,1]
	v_pk_fma_f32 v[78:79], v[78:79], v[82:83], v[84:85] op_sel:[1,1,0] op_sel_hi:[1,0,1]
	v_mov_b64_e32 v[82:83], s[6:7]
	v_pk_mul_f32 v[84:85], v[72:73], v[82:83] op_sel:[0,0] op_sel_hi:[0,1]
	s_mov_b32 s6, s49
	v_pk_fma_f32 v[82:83], v[72:73], v[82:83], v[84:85] op_sel:[1,1,0] op_sel_hi:[1,0,1] neg_lo:[0,1,0]
	s_mov_b32 s7, s23
	v_pk_mul_f32 v[84:85], v[74:75], v[82:83] op_sel:[0,0] op_sel_hi:[0,1] neg_hi:[0,1]
	v_pk_fma_f32 v[74:75], v[74:75], v[82:83], v[84:85] op_sel:[1,1,0] op_sel_hi:[1,0,1]
	ds_write_b64 v132, v[76:77] offset:17408
	ds_write_b64 v132, v[80:81] offset:19584
	ds_write_b64 v132, v[78:79] offset:21760
	ds_write_b64 v132, v[74:75] offset:23936
	v_mov_b64_e32 v[74:75], s[54:55]
	v_pk_mul_f32 v[76:77], v[72:73], v[74:75] op_sel:[0,0] op_sel_hi:[0,1]
	s_nop 0
	v_pk_fma_f32 v[74:75], v[72:73], v[74:75], v[76:77] op_sel:[1,1,0] op_sel_hi:[1,0,1] neg_lo:[0,1,0]
	v_pk_mul_f32 v[76:77], v[28:29], v[74:75] op_sel:[0,0] op_sel_hi:[0,1] neg_hi:[0,1]
	v_pk_fma_f32 v[28:29], v[28:29], v[74:75], v[76:77] op_sel:[1,1,0] op_sel_hi:[1,0,1]
	v_mov_b64_e32 v[74:75], s[6:7]
	v_pk_mul_f32 v[76:77], v[72:73], v[74:75] op_sel:[0,0] op_sel_hi:[0,1]
	s_mov_b32 s6, s53
	v_pk_fma_f32 v[74:75], v[72:73], v[74:75], v[76:77] op_sel:[1,1,0] op_sel_hi:[1,0,1] neg_lo:[0,1,0]
	s_mov_b32 s7, s14
	v_pk_mul_f32 v[76:77], v[30:31], v[74:75] op_sel:[0,0] op_sel_hi:[0,1] neg_hi:[0,1]
	v_pk_fma_f32 v[30:31], v[30:31], v[74:75], v[76:77] op_sel:[1,1,0] op_sel_hi:[1,0,1]
	v_mov_b64_e32 v[74:75], s[68:69]
	v_pk_mul_f32 v[76:77], v[72:73], v[74:75] op_sel:[0,0] op_sel_hi:[0,1]
	v_pk_fma_f32 v[74:75], v[72:73], v[74:75], v[76:77] op_sel:[1,1,0] op_sel_hi:[1,0,1] neg_lo:[0,1,0]
	v_pk_mul_f32 v[76:77], v[32:33], v[74:75] op_sel:[0,0] op_sel_hi:[0,1] neg_hi:[0,1]
	v_pk_fma_f32 v[32:33], v[32:33], v[74:75], v[76:77] op_sel:[1,1,0] op_sel_hi:[1,0,1]
	v_mov_b64_e32 v[74:75], s[6:7]
	v_pk_mul_f32 v[76:77], v[72:73], v[74:75] op_sel:[0,0] op_sel_hi:[0,1]
	v_pk_fma_f32 v[72:73], v[72:73], v[74:75], v[76:77] op_sel:[1,1,0] op_sel_hi:[1,0,1] neg_lo:[0,1,0]
	v_pk_mul_f32 v[74:75], v[70:71], v[72:73] op_sel:[0,0] op_sel_hi:[0,1] neg_hi:[0,1]
	s_nop 0
	v_pk_fma_f32 v[70:71], v[70:71], v[72:73], v[74:75] op_sel:[1,1,0] op_sel_hi:[1,0,1]

.LBB0_3479:
	s_or_b64 exec, exec, s[0:1]
	v_mov_b32_e32 v44, v30
	v_mov_b32_e32 v45, v26
	v_mov_b32_e32 v26, v31
	v_mov_b32_e32 v30, v32
	v_mov_b32_e32 v31, v28
	v_mov_b32_e32 v28, v33
	v_pk_add_f32 v[26:27], v[44:45], v[26:27]
	v_pk_add_f32 v[28:29], v[30:31], v[28:29]
	v_pk_add_f32 v[30:31], v[52:53], v[68:69]
	v_pk_add_f32 v[26:27], v[26:27], v[28:29]
	v_pk_add_f32 v[28:29], v[42:43], v[60:61] neg_lo:[0,1] neg_hi:[0,1]
	v_add_f32_e32 v34, v26, v27
	v_pk_add_f32 v[26:27], v[42:43], v[60:61]
	v_pk_add_f32 v[32:33], v[52:53], v[68:69] neg_lo:[0,1] neg_hi:[0,1]
	v_pk_add_f32 v[52:53], v[26:27], v[30:31]
	v_pk_add_f32 v[60:61], v[26:27], v[30:31] neg_lo:[0,1] neg_hi:[0,1]
	v_pk_add_f32 v[68:69], v[28:29], v[32:33] op_sel:[0,1] op_sel_hi:[1,0] neg_hi:[0,1]
	s_waitcnt lgkmcnt(1)
	v_pk_add_f32 v[76:77], v[28:29], v[32:33] op_sel:[0,1] op_sel_hi:[1,0] neg_lo:[0,1]
	v_pk_add_f32 v[26:27], v[46:47], v[62:63]
	v_pk_add_f32 v[28:29], v[46:47], v[62:63] neg_lo:[0,1] neg_hi:[0,1]
	v_pk_add_f32 v[30:31], v[54:55], v[70:71]
	v_pk_add_f32 v[32:33], v[54:55], v[70:71] neg_lo:[0,1] neg_hi:[0,1]
	v_pk_add_f32 v[46:47], v[26:27], v[30:31]
	v_pk_add_f32 v[30:31], v[26:27], v[30:31] neg_lo:[0,1] neg_hi:[0,1]
	v_pk_add_f32 v[26:27], v[28:29], v[32:33] op_sel:[0,1] op_sel_hi:[1,0] neg_hi:[0,1]
	v_pk_add_f32 v[44:45], v[28:29], v[32:33] op_sel:[0,1] op_sel_hi:[1,0] neg_lo:[0,1]
	v_pk_add_f32 v[28:29], v[48:49], v[64:65]
	v_pk_add_f32 v[32:33], v[48:49], v[64:65] neg_lo:[0,1] neg_hi:[0,1]
	v_pk_add_f32 v[42:43], v[56:57], v[72:73]
	v_pk_add_f32 v[48:49], v[56:57], v[72:73] neg_lo:[0,1] neg_hi:[0,1]
	v_pk_add_f32 v[54:55], v[28:29], v[42:43]
	v_pk_add_f32 v[56:57], v[28:29], v[42:43] neg_lo:[0,1] neg_hi:[0,1]
	v_pk_add_f32 v[42:43], v[32:33], v[48:49] op_sel:[0,1] op_sel_hi:[1,0] neg_hi:[0,1]
	v_pk_add_f32 v[48:49], v[32:33], v[48:49] op_sel:[0,1] op_sel_hi:[1,0] neg_lo:[0,1]
	v_pk_add_f32 v[28:29], v[50:51], v[66:67]
	v_pk_add_f32 v[32:33], v[50:51], v[66:67] neg_lo:[0,1] neg_hi:[0,1]
	v_pk_add_f32 v[50:51], v[58:59], v[74:75]
	v_pk_add_f32 v[58:59], v[58:59], v[74:75] neg_lo:[0,1] neg_hi:[0,1]
	v_pk_add_f32 v[62:63], v[28:29], v[50:51]
	v_pk_add_f32 v[50:51], v[28:29], v[50:51] neg_lo:[0,1] neg_hi:[0,1]
	v_pk_add_f32 v[64:65], v[32:33], v[58:59] op_sel:[0,1] op_sel_hi:[1,0] neg_hi:[0,1]
	v_pk_add_f32 v[58:59], v[32:33], v[58:59] op_sel:[0,1] op_sel_hi:[1,0] neg_lo:[0,1]
	v_mov_b64_e32 v[32:33], s[20:21]
	v_pk_mul_f32 v[28:29], v[26:27], v[32:33] op_sel:[0,0] op_sel_hi:[0,1]
	s_waitcnt lgkmcnt(0)
	v_pk_fma_f32 v[66:67], v[26:27], v[32:33], v[28:29] op_sel:[1,1,0] op_sel_hi:[1,0,1] neg_lo:[0,1,0]
	v_mov_b64_e32 v[28:29], s[46:47]
	v_pk_mul_f32 v[26:27], v[42:43], v[28:29] op_sel:[0,0] op_sel_hi:[0,1]
	s_barrier
	v_pk_fma_f32 v[70:71], v[42:43], v[28:29], v[26:27] op_sel:[1,1,0] op_sel_hi:[1,0,1] neg_lo:[0,1,0]
	v_mov_b64_e32 v[26:27], s[50:51]
	v_pk_mul_f32 v[42:43], v[64:65], v[26:27] op_sel:[0,0] op_sel_hi:[0,1]
	v_pk_fma_f32 v[64:65], v[64:65], v[26:27], v[42:43] op_sel:[1,1,0] op_sel_hi:[1,0,1] neg_lo:[0,1,0]
	v_pk_mul_f32 v[42:43], v[30:31], v[28:29] op_sel:[0,0] op_sel_hi:[0,1]
	v_pk_fma_f32 v[72:73], v[30:31], v[28:29], v[42:43] op_sel:[1,1,0] op_sel_hi:[1,0,1] neg_lo:[0,1,0]
	v_mov_b64_e32 v[42:43], s[8:9]
	v_pk_mul_f32 v[30:31], v[56:57], v[42:43] op_sel:[0,0] op_sel_hi:[0,1]
	v_pk_fma_f32 v[56:57], v[56:57], v[42:43], v[30:31] op_sel:[1,1,0] op_sel_hi:[1,0,1] neg_lo:[0,1,0]
	v_mov_b64_e32 v[30:31], s[54:55]
	v_pk_mul_f32 v[74:75], v[50:51], v[30:31] op_sel:[0,0] op_sel_hi:[0,1]
	v_pk_fma_f32 v[50:51], v[50:51], v[30:31], v[74:75] op_sel:[1,1,0] op_sel_hi:[1,0,1] neg_lo:[0,1,0]
	v_pk_mul_f32 v[74:75], v[44:45], v[26:27] op_sel:[0,0] op_sel_hi:[0,1]
	v_pk_fma_f32 v[74:75], v[44:45], v[26:27], v[74:75] op_sel:[1,1,0] op_sel_hi:[1,0,1] neg_lo:[0,1,0]
	v_pk_mul_f32 v[44:45], v[48:49], v[30:31] op_sel:[0,0] op_sel_hi:[0,1]
	v_pk_fma_f32 v[48:49], v[48:49], v[30:31], v[44:45] op_sel:[1,1,0] op_sel_hi:[1,0,1] neg_lo:[0,1,0]
	v_mov_b64_e32 v[44:45], s[56:57]
	v_pk_mul_f32 v[78:79], v[58:59], v[44:45] op_sel:[0,0] op_sel_hi:[0,1]
	v_pk_fma_f32 v[58:59], v[58:59], v[44:45], v[78:79] op_sel:[1,1,0] op_sel_hi:[1,0,1] neg_lo:[0,1,0]
	v_pk_add_f32 v[78:79], v[52:53], v[54:55]
	v_pk_add_f32 v[52:53], v[52:53], v[54:55] neg_lo:[0,1] neg_hi:[0,1]
	v_pk_add_f32 v[54:55], v[46:47], v[62:63]
	v_pk_add_f32 v[46:47], v[46:47], v[62:63] neg_lo:[0,1] neg_hi:[0,1]
	v_pk_add_f32 v[62:63], v[78:79], v[54:55]
	v_pk_add_f32 v[54:55], v[78:79], v[54:55] neg_lo:[0,1] neg_hi:[0,1]
	v_pk_add_f32 v[78:79], v[52:53], v[46:47] op_sel:[0,1] op_sel_hi:[1,0] neg_hi:[0,1]
	v_pk_add_f32 v[46:47], v[52:53], v[46:47] op_sel:[0,1] op_sel_hi:[1,0] neg_lo:[0,1]
	v_pk_add_f32 v[52:53], v[68:69], v[70:71]
	v_pk_add_f32 v[68:69], v[68:69], v[70:71] neg_lo:[0,1] neg_hi:[0,1]
	v_pk_add_f32 v[70:71], v[66:67], v[64:65]
	v_pk_add_f32 v[64:65], v[66:67], v[64:65] neg_lo:[0,1] neg_hi:[0,1]
	v_pk_add_f32 v[66:67], v[52:53], v[70:71]
	v_pk_add_f32 v[52:53], v[52:53], v[70:71] neg_lo:[0,1] neg_hi:[0,1]
	v_pk_add_f32 v[70:71], v[68:69], v[64:65] op_sel:[0,1] op_sel_hi:[1,0] neg_hi:[0,1]
	v_pk_add_f32 v[64:65], v[68:69], v[64:65] op_sel:[0,1] op_sel_hi:[1,0] neg_lo:[0,1]
	v_pk_add_f32 v[68:69], v[60:61], v[56:57]
	v_pk_add_f32 v[56:57], v[60:61], v[56:57] neg_lo:[0,1] neg_hi:[0,1]
	v_pk_add_f32 v[60:61], v[72:73], v[50:51]
	v_pk_add_f32 v[50:51], v[72:73], v[50:51] neg_lo:[0,1] neg_hi:[0,1]
	v_pk_add_f32 v[72:73], v[68:69], v[60:61]
	v_pk_add_f32 v[60:61], v[68:69], v[60:61] neg_lo:[0,1] neg_hi:[0,1]
	v_pk_add_f32 v[68:69], v[56:57], v[50:51] op_sel:[0,1] op_sel_hi:[1,0] neg_hi:[0,1]
	v_pk_add_f32 v[50:51], v[56:57], v[50:51] op_sel:[0,1] op_sel_hi:[1,0] neg_lo:[0,1]
	v_pk_add_f32 v[56:57], v[76:77], v[48:49]
	v_pk_add_f32 v[48:49], v[76:77], v[48:49] neg_lo:[0,1] neg_hi:[0,1]
	v_pk_add_f32 v[76:77], v[74:75], v[58:59]
	v_pk_add_f32 v[58:59], v[74:75], v[58:59] neg_lo:[0,1] neg_hi:[0,1]
	v_pk_add_f32 v[74:75], v[56:57], v[76:77]
	v_pk_add_f32 v[56:57], v[56:57], v[76:77] neg_lo:[0,1] neg_hi:[0,1]
	v_pk_add_f32 v[76:77], v[48:49], v[58:59] op_sel:[0,1] op_sel_hi:[1,0] neg_hi:[0,1]
	v_pk_add_f32 v[48:49], v[48:49], v[58:59] op_sel:[0,1] op_sel_hi:[1,0] neg_lo:[0,1]
	v_mov_b32_e32 v58, v38
	v_mov_b32_e32 v59, v39
	ds_write_b64 v132, v[62:63]
	v_pk_mul_f32 v[62:63], v[66:67], v[58:59] op_sel:[0,0] op_sel_hi:[0,1]
	v_pk_fma_f32 v[62:63], v[66:67], v[58:59], v[62:63] op_sel:[1,1,0] op_sel_hi:[1,0,1] neg_lo:[0,1,0]
	ds_write_b64 v132, v[62:63] offset:2176
	v_pk_mul_f32 v[62:63], v[58:59], v[58:59] op_sel:[0,0] op_sel_hi:[0,1]
	v_pk_fma_f32 v[62:63], v[58:59], v[58:59], v[62:63] op_sel:[1,1,0] op_sel_hi:[1,0,1] neg_lo:[0,1,0]
	v_pk_mul_f32 v[66:67], v[72:73], v[62:63] op_sel:[0,0] op_sel_hi:[0,1]
	v_pk_fma_f32 v[66:67], v[72:73], v[62:63], v[66:67] op_sel:[1,1,0] op_sel_hi:[1,0,1] neg_lo:[0,1,0]
	ds_write_b64 v132, v[66:67] offset:4352
	v_pk_mul_f32 v[66:67], v[62:63], v[58:59] op_sel:[0,0] op_sel_hi:[0,1]
	v_pk_fma_f32 v[62:63], v[62:63], v[58:59], v[66:67] op_sel:[1,1,0] op_sel_hi:[1,0,1] neg_lo:[0,1,0]
	v_pk_mul_f32 v[66:67], v[74:75], v[62:63] op_sel:[0,0] op_sel_hi:[0,1]
	v_pk_fma_f32 v[66:67], v[74:75], v[62:63], v[66:67] op_sel:[1,1,0] op_sel_hi:[1,0,1] neg_lo:[0,1,0]
	ds_write_b64 v132, v[66:67] offset:6528
	v_pk_mul_f32 v[66:67], v[62:63], v[58:59] op_sel:[0,0] op_sel_hi:[0,1]
	v_pk_fma_f32 v[62:63], v[62:63], v[58:59], v[66:67] op_sel:[1,1,0] op_sel_hi:[1,0,1] neg_lo:[0,1,0]
	v_pk_mul_f32 v[66:67], v[78:79], v[62:63] op_sel:[0,0] op_sel_hi:[0,1]
	v_pk_fma_f32 v[66:67], v[78:79], v[62:63], v[66:67] op_sel:[1,1,0] op_sel_hi:[1,0,1] neg_lo:[0,1,0]
	ds_write_b64 v132, v[66:67] offset:8704
	v_pk_mul_f32 v[66:67], v[62:63], v[58:59] op_sel:[0,0] op_sel_hi:[0,1]
	v_pk_fma_f32 v[62:63], v[62:63], v[58:59], v[66:67] op_sel:[1,1,0] op_sel_hi:[1,0,1] neg_lo:[0,1,0]
	v_pk_mul_f32 v[66:67], v[70:71], v[62:63] op_sel:[0,0] op_sel_hi:[0,1]
	v_pk_fma_f32 v[66:67], v[70:71], v[62:63], v[66:67] op_sel:[1,1,0] op_sel_hi:[1,0,1] neg_lo:[0,1,0]
	ds_write_b64 v132, v[66:67] offset:10880
	v_pk_mul_f32 v[66:67], v[62:63], v[58:59] op_sel:[0,0] op_sel_hi:[0,1]
	v_pk_fma_f32 v[62:63], v[62:63], v[58:59], v[66:67] op_sel:[1,1,0] op_sel_hi:[1,0,1] neg_lo:[0,1,0]
	v_pk_mul_f32 v[66:67], v[68:69], v[62:63] op_sel:[0,0] op_sel_hi:[0,1]
	v_pk_fma_f32 v[66:67], v[68:69], v[62:63], v[66:67] op_sel:[1,1,0] op_sel_hi:[1,0,1] neg_lo:[0,1,0]
	ds_write_b64 v132, v[66:67] offset:13056
	v_pk_mul_f32 v[66:67], v[62:63], v[58:59] op_sel:[0,0] op_sel_hi:[0,1]
	v_pk_fma_f32 v[62:63], v[62:63], v[58:59], v[66:67] op_sel:[1,1,0] op_sel_hi:[1,0,1] neg_lo:[0,1,0]
	v_pk_mul_f32 v[66:67], v[76:77], v[62:63] op_sel:[0,0] op_sel_hi:[0,1]
	v_pk_fma_f32 v[66:67], v[76:77], v[62:63], v[66:67] op_sel:[1,1,0] op_sel_hi:[1,0,1] neg_lo:[0,1,0]
	ds_write_b64 v132, v[66:67] offset:15232
	v_pk_mul_f32 v[66:67], v[62:63], v[58:59] op_sel:[0,0] op_sel_hi:[0,1]
	v_pk_fma_f32 v[62:63], v[62:63], v[58:59], v[66:67] op_sel:[1,1,0] op_sel_hi:[1,0,1] neg_lo:[0,1,0]
	v_pk_mul_f32 v[66:67], v[54:55], v[62:63] op_sel:[0,0] op_sel_hi:[0,1]
	v_pk_fma_f32 v[54:55], v[54:55], v[62:63], v[66:67] op_sel:[1,1,0] op_sel_hi:[1,0,1] neg_lo:[0,1,0]
	ds_write_b64 v132, v[54:55] offset:17408
	v_pk_mul_f32 v[54:55], v[62:63], v[58:59] op_sel:[0,0] op_sel_hi:[0,1]
	v_pk_fma_f32 v[54:55], v[62:63], v[58:59], v[54:55] op_sel:[1,1,0] op_sel_hi:[1,0,1] neg_lo:[0,1,0]
	v_pk_mul_f32 v[62:63], v[52:53], v[54:55] op_sel:[0,0] op_sel_hi:[0,1]
	v_pk_fma_f32 v[52:53], v[52:53], v[54:55], v[62:63] op_sel:[1,1,0] op_sel_hi:[1,0,1] neg_lo:[0,1,0]
	ds_write_b64 v132, v[52:53] offset:19584
	v_pk_mul_f32 v[52:53], v[54:55], v[58:59] op_sel:[0,0] op_sel_hi:[0,1]
	v_pk_fma_f32 v[52:53], v[54:55], v[58:59], v[52:53] op_sel:[1,1,0] op_sel_hi:[1,0,1] neg_lo:[0,1,0]
	v_pk_mul_f32 v[54:55], v[60:61], v[52:53] op_sel:[0,0] op_sel_hi:[0,1]
	v_pk_fma_f32 v[54:55], v[60:61], v[52:53], v[54:55] op_sel:[1,1,0] op_sel_hi:[1,0,1] neg_lo:[0,1,0]
	ds_write_b64 v132, v[54:55] offset:21760
	v_pk_mul_f32 v[54:55], v[52:53], v[58:59] op_sel:[0,0] op_sel_hi:[0,1]
	v_pk_fma_f32 v[52:53], v[52:53], v[58:59], v[54:55] op_sel:[1,1,0] op_sel_hi:[1,0,1] neg_lo:[0,1,0]
	v_pk_mul_f32 v[54:55], v[56:57], v[52:53] op_sel:[0,0] op_sel_hi:[0,1]
	v_pk_fma_f32 v[54:55], v[56:57], v[52:53], v[54:55] op_sel:[1,1,0] op_sel_hi:[1,0,1] neg_lo:[0,1,0]
	ds_write_b64 v132, v[54:55] offset:23936
	v_pk_mul_f32 v[54:55], v[52:53], v[58:59] op_sel:[0,0] op_sel_hi:[0,1]
	v_pk_fma_f32 v[52:53], v[52:53], v[58:59], v[54:55] op_sel:[1,1,0] op_sel_hi:[1,0,1] neg_lo:[0,1,0]
	v_pk_mul_f32 v[54:55], v[46:47], v[52:53] op_sel:[0,0] op_sel_hi:[0,1]
	v_pk_fma_f32 v[46:47], v[46:47], v[52:53], v[54:55] op_sel:[1,1,0] op_sel_hi:[1,0,1] neg_lo:[0,1,0]
	ds_write_b64 v132, v[46:47] offset:26112
	v_pk_mul_f32 v[46:47], v[52:53], v[58:59] op_sel:[0,0] op_sel_hi:[0,1]
	v_pk_fma_f32 v[46:47], v[52:53], v[58:59], v[46:47] op_sel:[1,1,0] op_sel_hi:[1,0,1] neg_lo:[0,1,0]
	v_pk_mul_f32 v[52:53], v[64:65], v[46:47] op_sel:[0,0] op_sel_hi:[0,1]
	v_pk_fma_f32 v[52:53], v[64:65], v[46:47], v[52:53] op_sel:[1,1,0] op_sel_hi:[1,0,1] neg_lo:[0,1,0]
	ds_write_b64 v132, v[52:53] offset:28288
	v_pk_mul_f32 v[52:53], v[46:47], v[58:59] op_sel:[0,0] op_sel_hi:[0,1]
	v_pk_fma_f32 v[46:47], v[46:47], v[58:59], v[52:53] op_sel:[1,1,0] op_sel_hi:[1,0,1] neg_lo:[0,1,0]
	v_pk_mul_f32 v[52:53], v[50:51], v[46:47] op_sel:[0,0] op_sel_hi:[0,1]
	v_pk_fma_f32 v[50:51], v[50:51], v[46:47], v[52:53] op_sel:[1,1,0] op_sel_hi:[1,0,1] neg_lo:[0,1,0]
	ds_write_b64 v132, v[50:51] offset:30464
	v_pk_mul_f32 v[50:51], v[46:47], v[58:59] op_sel:[0,0] op_sel_hi:[0,1]
	v_pk_fma_f32 v[46:47], v[46:47], v[58:59], v[50:51] op_sel:[1,1,0] op_sel_hi:[1,0,1] neg_lo:[0,1,0]
	v_pk_mul_f32 v[50:51], v[48:49], v[46:47] op_sel:[0,0] op_sel_hi:[0,1]
	v_pk_fma_f32 v[46:47], v[48:49], v[46:47], v[50:51] op_sel:[1,1,0] op_sel_hi:[1,0,1] neg_lo:[0,1,0]
	ds_write_b64 v132, v[46:47] offset:32640
	s_waitcnt lgkmcnt(0)
	s_barrier
	ds_read2_b64 v[46:49], v134 offset1:17
	ds_read2_b64 v[50:53], v134 offset0:34 offset1:51
	ds_read2_b64 v[54:57], v134 offset0:68 offset1:85
	ds_read2_b64 v[58:61], v134 offset0:136 offset1:153
	ds_read2_b64 v[62:65], v134 offset0:102 offset1:119
	ds_read2_b64 v[66:69], v134 offset0:204 offset1:221
	ds_read2_b64 v[70:73], v134 offset0:170 offset1:187
	ds_read2_b64 v[74:77], v134 offset0:238 offset1:255
	s_waitcnt lgkmcnt(4)
	v_pk_add_f32 v[78:79], v[46:47], v[58:59]
	v_pk_add_f32 v[46:47], v[46:47], v[58:59] neg_lo:[0,1] neg_hi:[0,1]
	s_waitcnt lgkmcnt(2)
	v_pk_add_f32 v[58:59], v[54:55], v[66:67]
	v_pk_add_f32 v[54:55], v[54:55], v[66:67] neg_lo:[0,1] neg_hi:[0,1]
	v_pk_add_f32 v[66:67], v[78:79], v[58:59]
	v_pk_add_f32 v[58:59], v[78:79], v[58:59] neg_lo:[0,1] neg_hi:[0,1]
	v_pk_add_f32 v[78:79], v[46:47], v[54:55] op_sel:[0,1] op_sel_hi:[1,0] neg_hi:[0,1]
	v_pk_add_f32 v[46:47], v[46:47], v[54:55] op_sel:[0,1] op_sel_hi:[1,0] neg_lo:[0,1]
	v_pk_add_f32 v[54:55], v[48:49], v[60:61]
	v_pk_add_f32 v[48:49], v[48:49], v[60:61] neg_lo:[0,1] neg_hi:[0,1]
	v_pk_add_f32 v[60:61], v[56:57], v[68:69]
	v_pk_add_f32 v[56:57], v[56:57], v[68:69] neg_lo:[0,1] neg_hi:[0,1]
	v_pk_add_f32 v[68:69], v[54:55], v[60:61]
	v_pk_add_f32 v[54:55], v[54:55], v[60:61] neg_lo:[0,1] neg_hi:[0,1]
	v_pk_add_f32 v[60:61], v[48:49], v[56:57] op_sel:[0,1] op_sel_hi:[1,0] neg_hi:[0,1]
	v_pk_add_f32 v[48:49], v[48:49], v[56:57] op_sel:[0,1] op_sel_hi:[1,0] neg_lo:[0,1]
	s_waitcnt lgkmcnt(1)
	v_pk_add_f32 v[56:57], v[50:51], v[70:71]
	v_pk_add_f32 v[50:51], v[50:51], v[70:71] neg_lo:[0,1] neg_hi:[0,1]
	s_waitcnt lgkmcnt(0)
	v_pk_add_f32 v[70:71], v[62:63], v[74:75]
	v_pk_add_f32 v[62:63], v[62:63], v[74:75] neg_lo:[0,1] neg_hi:[0,1]
	v_pk_add_f32 v[74:75], v[56:57], v[70:71]
	v_pk_add_f32 v[56:57], v[56:57], v[70:71] neg_lo:[0,1] neg_hi:[0,1]
	v_pk_add_f32 v[70:71], v[50:51], v[62:63] op_sel:[0,1] op_sel_hi:[1,0] neg_hi:[0,1]
	v_pk_add_f32 v[50:51], v[50:51], v[62:63] op_sel:[0,1] op_sel_hi:[1,0] neg_lo:[0,1]
	v_pk_add_f32 v[62:63], v[52:53], v[72:73]
	v_pk_add_f32 v[52:53], v[52:53], v[72:73] neg_lo:[0,1] neg_hi:[0,1]
	v_pk_add_f32 v[72:73], v[64:65], v[76:77]
	v_pk_add_f32 v[64:65], v[64:65], v[76:77] neg_lo:[0,1] neg_hi:[0,1]
	v_pk_add_f32 v[76:77], v[62:63], v[72:73]
	v_pk_add_f32 v[62:63], v[62:63], v[72:73] neg_lo:[0,1] neg_hi:[0,1]
	v_pk_add_f32 v[72:73], v[52:53], v[64:65] op_sel:[0,1] op_sel_hi:[1,0] neg_hi:[0,1]
	v_pk_add_f32 v[52:53], v[52:53], v[64:65] op_sel:[0,1] op_sel_hi:[1,0] neg_lo:[0,1]
	v_pk_mul_f32 v[64:65], v[60:61], v[32:33] op_sel:[0,0] op_sel_hi:[0,1]
	v_pk_fma_f32 v[60:61], v[60:61], v[32:33], v[64:65] op_sel:[1,1,0] op_sel_hi:[1,0,1] neg_lo:[0,1,0]
	v_pk_mul_f32 v[64:65], v[70:71], v[28:29] op_sel:[0,0] op_sel_hi:[0,1]
	v_pk_fma_f32 v[64:65], v[70:71], v[28:29], v[64:65] op_sel:[1,1,0] op_sel_hi:[1,0,1] neg_lo:[0,1,0]
	v_pk_mul_f32 v[70:71], v[72:73], v[26:27] op_sel:[0,0] op_sel_hi:[0,1]
	v_pk_fma_f32 v[70:71], v[72:73], v[26:27], v[70:71] op_sel:[1,1,0] op_sel_hi:[1,0,1] neg_lo:[0,1,0]
	v_pk_mul_f32 v[72:73], v[54:55], v[28:29] op_sel:[0,0] op_sel_hi:[0,1]
	v_pk_fma_f32 v[54:55], v[54:55], v[28:29], v[72:73] op_sel:[1,1,0] op_sel_hi:[1,0,1] neg_lo:[0,1,0]
	v_pk_mul_f32 v[72:73], v[56:57], v[42:43] op_sel:[0,0] op_sel_hi:[0,1]
	v_pk_fma_f32 v[56:57], v[56:57], v[42:43], v[72:73] op_sel:[1,1,0] op_sel_hi:[1,0,1] neg_lo:[0,1,0]
	v_pk_mul_f32 v[72:73], v[62:63], v[30:31] op_sel:[0,0] op_sel_hi:[0,1]
	v_pk_fma_f32 v[62:63], v[62:63], v[30:31], v[72:73] op_sel:[1,1,0] op_sel_hi:[1,0,1] neg_lo:[0,1,0]
	v_pk_mul_f32 v[72:73], v[48:49], v[26:27] op_sel:[0,0] op_sel_hi:[0,1]
	v_pk_fma_f32 v[48:49], v[48:49], v[26:27], v[72:73] op_sel:[1,1,0] op_sel_hi:[1,0,1] neg_lo:[0,1,0]
	v_pk_mul_f32 v[72:73], v[50:51], v[30:31] op_sel:[0,0] op_sel_hi:[0,1]
	v_pk_fma_f32 v[50:51], v[50:51], v[30:31], v[72:73] op_sel:[1,1,0] op_sel_hi:[1,0,1] neg_lo:[0,1,0]
	v_pk_mul_f32 v[72:73], v[52:53], v[44:45] op_sel:[0,0] op_sel_hi:[0,1]
	v_pk_fma_f32 v[52:53], v[52:53], v[44:45], v[72:73] op_sel:[1,1,0] op_sel_hi:[1,0,1] neg_lo:[0,1,0]
	v_pk_add_f32 v[72:73], v[66:67], v[74:75]
	v_pk_add_f32 v[66:67], v[66:67], v[74:75] neg_lo:[0,1] neg_hi:[0,1]
	v_pk_add_f32 v[74:75], v[68:69], v[76:77]
	v_pk_add_f32 v[68:69], v[68:69], v[76:77] neg_lo:[0,1] neg_hi:[0,1]
	v_pk_add_f32 v[76:77], v[72:73], v[74:75]
	v_pk_add_f32 v[72:73], v[72:73], v[74:75] neg_lo:[0,1] neg_hi:[0,1]
	v_pk_add_f32 v[74:75], v[66:67], v[68:69] op_sel:[0,1] op_sel_hi:[1,0] neg_hi:[0,1]
	v_pk_add_f32 v[66:67], v[66:67], v[68:69] op_sel:[0,1] op_sel_hi:[1,0] neg_lo:[0,1]
	v_pk_add_f32 v[68:69], v[78:79], v[64:65]
	v_pk_add_f32 v[64:65], v[78:79], v[64:65] neg_lo:[0,1] neg_hi:[0,1]
	v_pk_add_f32 v[78:79], v[60:61], v[70:71]
	v_pk_add_f32 v[60:61], v[60:61], v[70:71] neg_lo:[0,1] neg_hi:[0,1]
	v_pk_add_f32 v[70:71], v[68:69], v[78:79]
	v_pk_add_f32 v[68:69], v[68:69], v[78:79] neg_lo:[0,1] neg_hi:[0,1]
	v_pk_add_f32 v[78:79], v[64:65], v[60:61] op_sel:[0,1] op_sel_hi:[1,0] neg_hi:[0,1]
	v_pk_add_f32 v[60:61], v[64:65], v[60:61] op_sel:[0,1] op_sel_hi:[1,0] neg_lo:[0,1]
	v_pk_add_f32 v[64:65], v[58:59], v[56:57]
	v_pk_add_f32 v[56:57], v[58:59], v[56:57] neg_lo:[0,1] neg_hi:[0,1]
	v_pk_add_f32 v[58:59], v[54:55], v[62:63]
	v_pk_add_f32 v[54:55], v[54:55], v[62:63] neg_lo:[0,1] neg_hi:[0,1]
	v_pk_add_f32 v[62:63], v[64:65], v[58:59]
	v_pk_add_f32 v[58:59], v[64:65], v[58:59] neg_lo:[0,1] neg_hi:[0,1]
	v_pk_add_f32 v[64:65], v[56:57], v[54:55] op_sel:[0,1] op_sel_hi:[1,0] neg_hi:[0,1]
	v_pk_add_f32 v[54:55], v[56:57], v[54:55] op_sel:[0,1] op_sel_hi:[1,0] neg_lo:[0,1]
	v_pk_add_f32 v[56:57], v[46:47], v[50:51]
	v_pk_add_f32 v[46:47], v[46:47], v[50:51] neg_lo:[0,1] neg_hi:[0,1]
	v_pk_add_f32 v[50:51], v[48:49], v[52:53]
	v_pk_add_f32 v[48:49], v[48:49], v[52:53] neg_lo:[0,1] neg_hi:[0,1]
	v_pk_add_f32 v[52:53], v[56:57], v[50:51]
	v_pk_add_f32 v[50:51], v[56:57], v[50:51] neg_lo:[0,1] neg_hi:[0,1]
	v_pk_add_f32 v[56:57], v[46:47], v[48:49] op_sel:[0,1] op_sel_hi:[1,0] neg_hi:[0,1]
	v_pk_add_f32 v[46:47], v[46:47], v[48:49] op_sel:[0,1] op_sel_hi:[1,0] neg_lo:[0,1]
	v_mov_b32_e32 v48, v40
	v_mov_b32_e32 v49, v41
	s_waitcnt vmcnt(5)
	v_pk_mul_f32 v[80:81], v[70:71], v[48:49] op_sel:[0,0] op_sel_hi:[0,1]
	v_pk_fma_f32 v[70:71], v[70:71], v[48:49], v[80:81] op_sel:[1,1,0] op_sel_hi:[1,0,1] neg_lo:[0,1,0]
	ds_write2_b64 v134, v[76:77], v[70:71] offset1:17
	v_pk_mul_f32 v[70:71], v[48:49], v[48:49] op_sel:[0,0] op_sel_hi:[0,1]
	v_pk_fma_f32 v[70:71], v[48:49], v[48:49], v[70:71] op_sel:[1,1,0] op_sel_hi:[1,0,1] neg_lo:[0,1,0]
	v_pk_mul_f32 v[76:77], v[62:63], v[70:71] op_sel:[0,0] op_sel_hi:[0,1]
	v_pk_fma_f32 v[62:63], v[62:63], v[70:71], v[76:77] op_sel:[1,1,0] op_sel_hi:[1,0,1] neg_lo:[0,1,0]
	v_pk_mul_f32 v[76:77], v[70:71], v[48:49] op_sel:[0,0] op_sel_hi:[0,1]
	v_pk_fma_f32 v[70:71], v[70:71], v[48:49], v[76:77] op_sel:[1,1,0] op_sel_hi:[1,0,1] neg_lo:[0,1,0]
	v_pk_mul_f32 v[76:77], v[52:53], v[70:71] op_sel:[0,0] op_sel_hi:[0,1]
	v_pk_fma_f32 v[52:53], v[52:53], v[70:71], v[76:77] op_sel:[1,1,0] op_sel_hi:[1,0,1] neg_lo:[0,1,0]
	ds_write2_b64 v134, v[62:63], v[52:53] offset0:34 offset1:51
	v_pk_mul_f32 v[52:53], v[70:71], v[48:49] op_sel:[0,0] op_sel_hi:[0,1]
	v_pk_fma_f32 v[52:53], v[70:71], v[48:49], v[52:53] op_sel:[1,1,0] op_sel_hi:[1,0,1] neg_lo:[0,1,0]
	v_pk_mul_f32 v[62:63], v[74:75], v[52:53] op_sel:[0,0] op_sel_hi:[0,1]
	v_pk_mul_f32 v[70:71], v[52:53], v[48:49] op_sel:[0,0] op_sel_hi:[0,1]
	v_pk_fma_f32 v[62:63], v[74:75], v[52:53], v[62:63] op_sel:[1,1,0] op_sel_hi:[1,0,1] neg_lo:[0,1,0]
	v_pk_fma_f32 v[52:53], v[52:53], v[48:49], v[70:71] op_sel:[1,1,0] op_sel_hi:[1,0,1] neg_lo:[0,1,0]
	v_pk_mul_f32 v[70:71], v[78:79], v[52:53] op_sel:[0,0] op_sel_hi:[0,1]
	v_pk_fma_f32 v[70:71], v[78:79], v[52:53], v[70:71] op_sel:[1,1,0] op_sel_hi:[1,0,1] neg_lo:[0,1,0]
	ds_write2_b64 v134, v[62:63], v[70:71] offset0:68 offset1:85
	v_pk_mul_f32 v[62:63], v[52:53], v[48:49] op_sel:[0,0] op_sel_hi:[0,1]
	v_pk_fma_f32 v[52:53], v[52:53], v[48:49], v[62:63] op_sel:[1,1,0] op_sel_hi:[1,0,1] neg_lo:[0,1,0]
	v_pk_mul_f32 v[62:63], v[64:65], v[52:53] op_sel:[0,0] op_sel_hi:[0,1]
	v_pk_fma_f32 v[62:63], v[64:65], v[52:53], v[62:63] op_sel:[1,1,0] op_sel_hi:[1,0,1] neg_lo:[0,1,0]
	v_pk_mul_f32 v[64:65], v[52:53], v[48:49] op_sel:[0,0] op_sel_hi:[0,1]
	v_pk_fma_f32 v[52:53], v[52:53], v[48:49], v[64:65] op_sel:[1,1,0] op_sel_hi:[1,0,1] neg_lo:[0,1,0]
	v_pk_mul_f32 v[64:65], v[56:57], v[52:53] op_sel:[0,0] op_sel_hi:[0,1]
	v_pk_fma_f32 v[56:57], v[56:57], v[52:53], v[64:65] op_sel:[1,1,0] op_sel_hi:[1,0,1] neg_lo:[0,1,0]
	ds_write2_b64 v134, v[62:63], v[56:57] offset0:102 offset1:119
	v_pk_mul_f32 v[56:57], v[52:53], v[48:49] op_sel:[0,0] op_sel_hi:[0,1]
	v_pk_fma_f32 v[52:53], v[52:53], v[48:49], v[56:57] op_sel:[1,1,0] op_sel_hi:[1,0,1] neg_lo:[0,1,0]
	v_pk_mul_f32 v[56:57], v[72:73], v[52:53] op_sel:[0,0] op_sel_hi:[0,1]
	v_pk_mul_f32 v[62:63], v[52:53], v[48:49] op_sel:[0,0] op_sel_hi:[0,1]
	v_pk_fma_f32 v[56:57], v[72:73], v[52:53], v[56:57] op_sel:[1,1,0] op_sel_hi:[1,0,1] neg_lo:[0,1,0]
	v_pk_fma_f32 v[52:53], v[52:53], v[48:49], v[62:63] op_sel:[1,1,0] op_sel_hi:[1,0,1] neg_lo:[0,1,0]
	v_pk_mul_f32 v[62:63], v[68:69], v[52:53] op_sel:[0,0] op_sel_hi:[0,1]
	v_pk_fma_f32 v[62:63], v[68:69], v[52:53], v[62:63] op_sel:[1,1,0] op_sel_hi:[1,0,1] neg_lo:[0,1,0]
	ds_write2_b64 v134, v[56:57], v[62:63] offset0:136 offset1:153
	v_pk_mul_f32 v[56:57], v[52:53], v[48:49] op_sel:[0,0] op_sel_hi:[0,1]
	v_pk_fma_f32 v[52:53], v[52:53], v[48:49], v[56:57] op_sel:[1,1,0] op_sel_hi:[1,0,1] neg_lo:[0,1,0]
	v_pk_mul_f32 v[56:57], v[58:59], v[52:53] op_sel:[0,0] op_sel_hi:[0,1]
	v_pk_fma_f32 v[56:57], v[58:59], v[52:53], v[56:57] op_sel:[1,1,0] op_sel_hi:[1,0,1] neg_lo:[0,1,0]
	v_pk_mul_f32 v[58:59], v[52:53], v[48:49] op_sel:[0,0] op_sel_hi:[0,1]
	v_pk_fma_f32 v[52:53], v[52:53], v[48:49], v[58:59] op_sel:[1,1,0] op_sel_hi:[1,0,1] neg_lo:[0,1,0]
	v_pk_mul_f32 v[58:59], v[50:51], v[52:53] op_sel:[0,0] op_sel_hi:[0,1]
	v_pk_fma_f32 v[50:51], v[50:51], v[52:53], v[58:59] op_sel:[1,1,0] op_sel_hi:[1,0,1] neg_lo:[0,1,0]
	ds_write2_b64 v134, v[56:57], v[50:51] offset0:170 offset1:187
	v_pk_mul_f32 v[50:51], v[52:53], v[48:49] op_sel:[0,0] op_sel_hi:[0,1]
	v_pk_fma_f32 v[50:51], v[52:53], v[48:49], v[50:51] op_sel:[1,1,0] op_sel_hi:[1,0,1] neg_lo:[0,1,0]
	v_pk_mul_f32 v[52:53], v[66:67], v[50:51] op_sel:[0,0] op_sel_hi:[0,1]
	v_pk_mul_f32 v[56:57], v[50:51], v[48:49] op_sel:[0,0] op_sel_hi:[0,1]
	v_pk_fma_f32 v[52:53], v[66:67], v[50:51], v[52:53] op_sel:[1,1,0] op_sel_hi:[1,0,1] neg_lo:[0,1,0]
	v_pk_fma_f32 v[50:51], v[50:51], v[48:49], v[56:57] op_sel:[1,1,0] op_sel_hi:[1,0,1] neg_lo:[0,1,0]
	v_pk_mul_f32 v[56:57], v[60:61], v[50:51] op_sel:[0,0] op_sel_hi:[0,1]
	v_pk_fma_f32 v[56:57], v[60:61], v[50:51], v[56:57] op_sel:[1,1,0] op_sel_hi:[1,0,1] neg_lo:[0,1,0]
	ds_write2_b64 v134, v[52:53], v[56:57] offset0:204 offset1:221
	v_pk_mul_f32 v[52:53], v[50:51], v[48:49] op_sel:[0,0] op_sel_hi:[0,1]
	v_pk_fma_f32 v[50:51], v[50:51], v[48:49], v[52:53] op_sel:[1,1,0] op_sel_hi:[1,0,1] neg_lo:[0,1,0]
	v_pk_mul_f32 v[52:53], v[54:55], v[50:51] op_sel:[0,0] op_sel_hi:[0,1]
	v_pk_fma_f32 v[52:53], v[54:55], v[50:51], v[52:53] op_sel:[1,1,0] op_sel_hi:[1,0,1] neg_lo:[0,1,0]
	v_pk_mul_f32 v[54:55], v[50:51], v[48:49] op_sel:[0,0] op_sel_hi:[0,1]
	v_pk_fma_f32 v[48:49], v[50:51], v[48:49], v[54:55] op_sel:[1,1,0] op_sel_hi:[1,0,1] neg_lo:[0,1,0]
	v_pk_mul_f32 v[50:51], v[46:47], v[48:49] op_sel:[0,0] op_sel_hi:[0,1]
	v_pk_fma_f32 v[46:47], v[46:47], v[48:49], v[50:51] op_sel:[1,1,0] op_sel_hi:[1,0,1] neg_lo:[0,1,0]
	ds_write2_b64 v134, v[52:53], v[46:47] offset0:238 offset1:255
	s_waitcnt lgkmcnt(0)
	s_barrier
	ds_read2_b64 v[46:49], v135 offset1:1
	ds_read2_b64 v[50:53], v135 offset0:2 offset1:3
	ds_read2_b64 v[54:57], v135 offset0:8 offset1:9
	ds_read2_b64 v[58:61], v135 offset0:4 offset1:5
	ds_read2_b64 v[62:65], v135 offset0:6 offset1:7
	ds_read2_b64 v[66:69], v135 offset0:12 offset1:13
	ds_read2_b64 v[70:73], v135 offset0:10 offset1:11
	ds_read2_b64 v[74:77], v135 offset0:14 offset1:15
	s_waitcnt lgkmcnt(5)
	v_pk_add_f32 v[78:79], v[46:47], v[54:55]
	v_pk_add_f32 v[46:47], v[46:47], v[54:55] neg_lo:[0,1] neg_hi:[0,1]
	s_waitcnt lgkmcnt(2)
	v_pk_add_f32 v[54:55], v[58:59], v[66:67]
	v_pk_add_f32 v[58:59], v[58:59], v[66:67] neg_lo:[0,1] neg_hi:[0,1]
	v_pk_add_f32 v[66:67], v[78:79], v[54:55]
	v_pk_add_f32 v[54:55], v[78:79], v[54:55] neg_lo:[0,1] neg_hi:[0,1]
	v_pk_add_f32 v[78:79], v[46:47], v[58:59] op_sel:[0,1] op_sel_hi:[1,0] neg_hi:[0,1]
	v_pk_add_f32 v[46:47], v[46:47], v[58:59] op_sel:[0,1] op_sel_hi:[1,0] neg_lo:[0,1]
	v_pk_add_f32 v[58:59], v[48:49], v[56:57]
	v_pk_add_f32 v[48:49], v[48:49], v[56:57] neg_lo:[0,1] neg_hi:[0,1]
	v_pk_add_f32 v[56:57], v[60:61], v[68:69]
	v_pk_add_f32 v[60:61], v[60:61], v[68:69] neg_lo:[0,1] neg_hi:[0,1]
	v_pk_add_f32 v[68:69], v[58:59], v[56:57]
	v_pk_add_f32 v[56:57], v[58:59], v[56:57] neg_lo:[0,1] neg_hi:[0,1]
	v_pk_add_f32 v[58:59], v[48:49], v[60:61] op_sel:[0,1] op_sel_hi:[1,0] neg_hi:[0,1]
	v_pk_add_f32 v[48:49], v[48:49], v[60:61] op_sel:[0,1] op_sel_hi:[1,0] neg_lo:[0,1]
	s_waitcnt lgkmcnt(1)
	v_pk_add_f32 v[60:61], v[50:51], v[70:71]
	v_pk_add_f32 v[50:51], v[50:51], v[70:71] neg_lo:[0,1] neg_hi:[0,1]
	s_waitcnt lgkmcnt(0)
	v_pk_add_f32 v[70:71], v[62:63], v[74:75]
	v_pk_add_f32 v[62:63], v[62:63], v[74:75] neg_lo:[0,1] neg_hi:[0,1]
	v_pk_add_f32 v[74:75], v[60:61], v[70:71]
	v_pk_add_f32 v[60:61], v[60:61], v[70:71] neg_lo:[0,1] neg_hi:[0,1]
	v_pk_add_f32 v[70:71], v[50:51], v[62:63] op_sel:[0,1] op_sel_hi:[1,0] neg_hi:[0,1]
	v_pk_add_f32 v[50:51], v[50:51], v[62:63] op_sel:[0,1] op_sel_hi:[1,0] neg_lo:[0,1]
	v_pk_add_f32 v[62:63], v[52:53], v[72:73]
	v_pk_add_f32 v[52:53], v[52:53], v[72:73] neg_lo:[0,1] neg_hi:[0,1]
	v_pk_add_f32 v[72:73], v[64:65], v[76:77]
	v_pk_add_f32 v[64:65], v[64:65], v[76:77] neg_lo:[0,1] neg_hi:[0,1]
	v_pk_add_f32 v[76:77], v[62:63], v[72:73]
	v_pk_add_f32 v[62:63], v[62:63], v[72:73] neg_lo:[0,1] neg_hi:[0,1]
	v_pk_add_f32 v[72:73], v[52:53], v[64:65] op_sel:[0,1] op_sel_hi:[1,0] neg_hi:[0,1]
	v_pk_add_f32 v[52:53], v[52:53], v[64:65] op_sel:[0,1] op_sel_hi:[1,0] neg_lo:[0,1]
	v_pk_mul_f32 v[64:65], v[58:59], v[32:33] op_sel:[0,0] op_sel_hi:[0,1]
	v_pk_fma_f32 v[32:33], v[58:59], v[32:33], v[64:65] op_sel:[1,1,0] op_sel_hi:[1,0,1] neg_lo:[0,1,0]
	v_pk_mul_f32 v[58:59], v[70:71], v[28:29] op_sel:[0,0] op_sel_hi:[0,1]
	v_pk_mul_f32 v[64:65], v[72:73], v[26:27] op_sel:[0,0] op_sel_hi:[0,1]
	s_barrier
	v_pk_fma_f32 v[58:59], v[70:71], v[28:29], v[58:59] op_sel:[1,1,0] op_sel_hi:[1,0,1] neg_lo:[0,1,0]
	v_pk_mul_f32 v[70:71], v[56:57], v[28:29] op_sel:[0,0] op_sel_hi:[0,1]
	v_pk_fma_f32 v[64:65], v[72:73], v[26:27], v[64:65] op_sel:[1,1,0] op_sel_hi:[1,0,1] neg_lo:[0,1,0]
	v_pk_fma_f32 v[28:29], v[56:57], v[28:29], v[70:71] op_sel:[1,1,0] op_sel_hi:[1,0,1] neg_lo:[0,1,0]
	v_pk_mul_f32 v[56:57], v[60:61], v[42:43] op_sel:[0,0] op_sel_hi:[0,1]
	v_pk_fma_f32 v[42:43], v[60:61], v[42:43], v[56:57] op_sel:[1,1,0] op_sel_hi:[1,0,1] neg_lo:[0,1,0]
	v_pk_mul_f32 v[56:57], v[62:63], v[30:31] op_sel:[0,0] op_sel_hi:[0,1]
	v_pk_mul_f32 v[60:61], v[48:49], v[26:27] op_sel:[0,0] op_sel_hi:[0,1]
	v_pk_fma_f32 v[26:27], v[48:49], v[26:27], v[60:61] op_sel:[1,1,0] op_sel_hi:[1,0,1] neg_lo:[0,1,0]
	v_pk_mul_f32 v[48:49], v[50:51], v[30:31] op_sel:[0,0] op_sel_hi:[0,1]
	v_pk_fma_f32 v[56:57], v[62:63], v[30:31], v[56:57] op_sel:[1,1,0] op_sel_hi:[1,0,1] neg_lo:[0,1,0]
	v_pk_add_f32 v[60:61], v[68:69], v[76:77] neg_lo:[0,1] neg_hi:[0,1]
	v_pk_fma_f32 v[30:31], v[50:51], v[30:31], v[48:49] op_sel:[1,1,0] op_sel_hi:[1,0,1] neg_lo:[0,1,0]
	v_pk_mul_f32 v[48:49], v[52:53], v[44:45] op_sel:[0,0] op_sel_hi:[0,1]
	v_pk_add_f32 v[50:51], v[66:67], v[74:75] neg_lo:[0,1] neg_hi:[0,1]
	v_pk_fma_f32 v[44:45], v[52:53], v[44:45], v[48:49] op_sel:[1,1,0] op_sel_hi:[1,0,1] neg_lo:[0,1,0]
	v_pk_add_f32 v[48:49], v[66:67], v[74:75]
	v_pk_add_f32 v[52:53], v[68:69], v[76:77]
	v_pk_add_f32 v[66:67], v[32:33], v[64:65]
	v_pk_add_f32 v[62:63], v[48:49], v[52:53]
	v_pk_add_f32 v[48:49], v[48:49], v[52:53] neg_lo:[0,1] neg_hi:[0,1]
	v_pk_add_f32 v[52:53], v[50:51], v[60:61] op_sel:[0,1] op_sel_hi:[1,0] neg_hi:[0,1]
	v_pk_add_f32 v[50:51], v[50:51], v[60:61] op_sel:[0,1] op_sel_hi:[1,0] neg_lo:[0,1]
	v_pk_add_f32 v[60:61], v[78:79], v[58:59]
	v_pk_add_f32 v[58:59], v[78:79], v[58:59] neg_lo:[0,1] neg_hi:[0,1]
	v_pk_add_f32 v[32:33], v[32:33], v[64:65] neg_lo:[0,1] neg_hi:[0,1]
	v_pk_add_f32 v[64:65], v[60:61], v[66:67]
	v_pk_add_f32 v[60:61], v[60:61], v[66:67] neg_lo:[0,1] neg_hi:[0,1]
	v_pk_add_f32 v[66:67], v[58:59], v[32:33] op_sel:[0,1] op_sel_hi:[1,0] neg_hi:[0,1]
	v_pk_add_f32 v[58:59], v[58:59], v[32:33] op_sel:[0,1] op_sel_hi:[1,0] neg_lo:[0,1]
	v_pk_add_f32 v[32:33], v[54:55], v[42:43]
	v_pk_add_f32 v[42:43], v[54:55], v[42:43] neg_lo:[0,1] neg_hi:[0,1]
	v_pk_add_f32 v[54:55], v[28:29], v[56:57]
	v_pk_add_f32 v[28:29], v[28:29], v[56:57] neg_lo:[0,1] neg_hi:[0,1]
	v_pk_add_f32 v[56:57], v[32:33], v[54:55]
	v_pk_add_f32 v[54:55], v[32:33], v[54:55] neg_lo:[0,1] neg_hi:[0,1]
	v_pk_add_f32 v[68:69], v[42:43], v[28:29] op_sel:[0,1] op_sel_hi:[1,0] neg_hi:[0,1]
	v_pk_add_f32 v[42:43], v[42:43], v[28:29] op_sel:[0,1] op_sel_hi:[1,0] neg_lo:[0,1]
	v_pk_add_f32 v[28:29], v[46:47], v[30:31]
	v_pk_add_f32 v[32:33], v[26:27], v[44:45]
	v_pk_add_f32 v[30:31], v[46:47], v[30:31] neg_lo:[0,1] neg_hi:[0,1]
	v_pk_add_f32 v[26:27], v[26:27], v[44:45] neg_lo:[0,1] neg_hi:[0,1]
	v_pk_add_f32 v[44:45], v[28:29], v[32:33]
	v_pk_add_f32 v[46:47], v[28:29], v[32:33] neg_lo:[0,1] neg_hi:[0,1]
	v_add_f32_e32 v28, 0x358637bd, v34
	v_mul_f32_e32 v28, 0x46000000, v28
	v_div_scale_f32 v29, s[0:1], v28, v28, 1.0
	s_waitcnt vmcnt(1)
	v_pk_add_f32 v[88:89], v[30:31], v[26:27] op_sel:[0,1] op_sel_hi:[1,0] neg_hi:[0,1]
	v_pk_add_f32 v[26:27], v[30:31], v[26:27] op_sel:[0,1] op_sel_hi:[1,0] neg_lo:[0,1]
	v_rcp_f32_e32 v30, v29
	s_nop 0
	v_fma_f32 v31, -v29, v30, 1.0
	v_fmac_f32_e32 v30, v31, v30
	v_div_scale_f32 v31, vcc, 1.0, v28, 1.0
	v_mul_f32_e32 v32, v31, v30
	v_fma_f32 v33, -v29, v32, v31
	v_fmac_f32_e32 v32, v33, v30
	v_fma_f32 v29, -v29, v32, v31
	v_div_fmas_f32 v29, v29, v30, v32
	v_div_fixup_f32 v34, v29, v28, 1.0
	v_pk_mul_f32 v[70:71], v[34:35], v[62:63] op_sel_hi:[0,1]
	v_pk_mul_f32 v[30:31], v[34:35], v[52:53] op_sel_hi:[0,1]
	v_pk_mul_f32 v[28:29], v[34:35], v[48:49] op_sel_hi:[0,1]
	v_pk_mul_f32 v[32:33], v[34:35], v[50:51] op_sel_hi:[0,1]
	v_pk_mul_f32 v[78:79], v[34:35], v[64:65] op_sel_hi:[0,1]
	v_pk_mul_f32 v[74:75], v[34:35], v[66:67] op_sel_hi:[0,1]
	v_pk_mul_f32 v[72:73], v[34:35], v[60:61] op_sel_hi:[0,1]
	v_pk_mul_f32 v[76:77], v[34:35], v[58:59] op_sel_hi:[0,1]
	v_pk_mul_f32 v[86:87], v[34:35], v[56:57] op_sel_hi:[0,1]
	v_pk_mul_f32 v[82:83], v[34:35], v[68:69] op_sel_hi:[0,1]
	v_pk_mul_f32 v[80:81], v[34:35], v[54:55] op_sel_hi:[0,1]
	v_pk_mul_f32 v[84:85], v[34:35], v[42:43] op_sel_hi:[0,1]
	v_pk_mul_f32 v[94:95], v[34:35], v[44:45] op_sel_hi:[0,1]
	v_pk_mul_f32 v[90:91], v[34:35], v[88:89] op_sel_hi:[0,1]
	v_pk_mul_f32 v[88:89], v[34:35], v[46:47] op_sel_hi:[0,1]
	s_waitcnt vmcnt(0)
	v_pk_mul_f32 v[92:93], v[34:35], v[26:27] op_sel_hi:[0,1]

.LBB0_3481:
	s_or_b64 exec, exec, s[0:1]
	s_addk_i32 s15, 0x800
	s_waitcnt lgkmcnt(0)
	ds_write_b64 v34, v[42:43]
	s_cmpk_lg_u32 s15, 0x8000
	v_add_u32_e32 v34, 0x880, v34
	v_mov_b64_e32 v[42:43], s[16:17]
	v_pk_mul_f32 v[44:45], v[26:27], v[42:43] op_sel:[0,0] op_sel_hi:[0,1]
	v_pk_fma_f32 v[26:27], v[26:27], v[42:43], v[44:45] op_sel:[1,1,0] op_sel_hi:[1,0,1] neg_lo:[0,1,0]
	s_cbranch_scc0 .LBB0_3484
.LBB0_3482:
	v_add_u32_e32 v42, s15, v109
	ds_read_b64 v[42:43], v42
	s_and_saveexec_b64 s[0:1], s[4:5]
	s_cbranch_execz .LBB0_3481
	s_waitcnt lgkmcnt(0)
	v_pk_mul_f32 v[44:45], v[42:43], v[26:27] op_sel:[0,0] op_sel_hi:[0,1]
	v_pk_fma_f32 v[42:43], v[42:43], v[26:27], v[44:45] op_sel:[1,1,0] op_sel_hi:[1,0,1] neg_lo:[0,1,0]
	s_branch .LBB0_3481
.LBB0_3484:
	ds_read_b64 v[26:27], v132
	ds_read_b64 v[42:43], v132 offset:2176
	ds_read_b64 v[44:45], v132 offset:4352
	ds_read_b64 v[46:47], v132 offset:6528
	ds_read_b64 v[48:49], v132 offset:8704
	ds_read_b64 v[50:51], v132 offset:10880
	ds_read_b64 v[52:53], v132 offset:13056
	ds_read_b64 v[54:55], v132 offset:15232
	ds_read_b64 v[56:57], v132 offset:17408
	ds_read_b64 v[58:59], v132 offset:19584
	ds_read_b64 v[60:61], v132 offset:21760
	ds_read_b64 v[62:63], v132 offset:23936
	ds_read_b64 v[64:65], v132 offset:26112
	ds_read_b64 v[66:67], v132 offset:28288
	ds_read_b64 v[68:69], v132 offset:30464
	ds_read_b64 v[98:99], v132 offset:32640
	s_waitcnt lgkmcnt(7)
	v_pk_add_f32 v[100:101], v[26:27], v[56:57]
	v_pk_add_f32 v[26:27], v[26:27], v[56:57] neg_lo:[0,1] neg_hi:[0,1]
	s_waitcnt lgkmcnt(3)
	v_pk_add_f32 v[56:57], v[48:49], v[64:65]
	v_pk_add_f32 v[48:49], v[48:49], v[64:65] neg_lo:[0,1] neg_hi:[0,1]
	v_pk_add_f32 v[64:65], v[100:101], v[56:57]
	v_pk_add_f32 v[56:57], v[100:101], v[56:57] neg_lo:[0,1] neg_hi:[0,1]
	v_pk_add_f32 v[100:101], v[26:27], v[48:49] op_sel:[0,1] op_sel_hi:[1,0] neg_hi:[0,1]
	v_pk_add_f32 v[102:103], v[26:27], v[48:49] op_sel:[0,1] op_sel_hi:[1,0] neg_lo:[0,1]
	v_pk_add_f32 v[26:27], v[42:43], v[58:59]
	v_pk_add_f32 v[42:43], v[42:43], v[58:59] neg_lo:[0,1] neg_hi:[0,1]
	s_waitcnt lgkmcnt(2)
	v_pk_add_f32 v[48:49], v[50:51], v[66:67]
	v_pk_add_f32 v[50:51], v[50:51], v[66:67] neg_lo:[0,1] neg_hi:[0,1]
	v_pk_add_f32 v[58:59], v[26:27], v[48:49]
	v_pk_add_f32 v[48:49], v[26:27], v[48:49] neg_lo:[0,1] neg_hi:[0,1]
	v_pk_add_f32 v[26:27], v[42:43], v[50:51] op_sel:[0,1] op_sel_hi:[1,0] neg_hi:[0,1]
	v_pk_add_f32 v[50:51], v[42:43], v[50:51] op_sel:[0,1] op_sel_hi:[1,0] neg_lo:[0,1]
	v_pk_add_f32 v[42:43], v[44:45], v[60:61]
	v_pk_add_f32 v[44:45], v[44:45], v[60:61] neg_lo:[0,1] neg_hi:[0,1]
	s_waitcnt lgkmcnt(1)
	v_pk_add_f32 v[60:61], v[52:53], v[68:69]
	v_pk_add_f32 v[52:53], v[52:53], v[68:69] neg_lo:[0,1] neg_hi:[0,1]
	v_pk_add_f32 v[66:67], v[42:43], v[60:61]
	v_pk_add_f32 v[60:61], v[42:43], v[60:61] neg_lo:[0,1] neg_hi:[0,1]
	v_pk_add_f32 v[68:69], v[44:45], v[52:53] op_sel:[0,1] op_sel_hi:[1,0] neg_hi:[0,1]
	v_pk_add_f32 v[52:53], v[44:45], v[52:53] op_sel:[0,1] op_sel_hi:[1,0] neg_lo:[0,1]
	v_pk_add_f32 v[42:43], v[46:47], v[62:63]
	v_pk_add_f32 v[44:45], v[46:47], v[62:63] neg_lo:[0,1] neg_hi:[0,1]
	s_waitcnt lgkmcnt(0)
	v_pk_add_f32 v[46:47], v[54:55], v[98:99]
	v_pk_add_f32 v[54:55], v[54:55], v[98:99] neg_lo:[0,1] neg_hi:[0,1]
	v_pk_add_f32 v[62:63], v[42:43], v[46:47]
	v_pk_add_f32 v[98:99], v[42:43], v[46:47] neg_lo:[0,1] neg_hi:[0,1]
	v_mov_b64_e32 v[46:47], s[20:21]
	v_pk_mul_f32 v[42:43], v[26:27], v[46:47] op_sel:[0,0] op_sel_hi:[0,1]
	v_pk_add_f32 v[104:105], v[44:45], v[54:55] op_sel:[0,1] op_sel_hi:[1,0] neg_hi:[0,1]
	v_pk_add_f32 v[54:55], v[44:45], v[54:55] op_sel:[0,1] op_sel_hi:[1,0] neg_lo:[0,1]
	s_add_i32 s78, s70, s24
	v_pk_fma_f32 v[106:107], v[26:27], v[46:47], v[42:43] op_sel:[1,1,0] op_sel_hi:[1,0,1] neg_lo:[0,1,0]
	v_mov_b64_e32 v[42:43], s[46:47]
	v_pk_mul_f32 v[26:27], v[68:69], v[42:43] op_sel:[0,0] op_sel_hi:[0,1]
	s_cmpk_gt_i32 s78, 0x3ff
	v_pk_fma_f32 v[68:69], v[68:69], v[42:43], v[26:27] op_sel:[1,1,0] op_sel_hi:[1,0,1] neg_lo:[0,1,0]
	v_mov_b64_e32 v[26:27], s[50:51]
	v_pk_mul_f32 v[44:45], v[104:105], v[26:27] op_sel:[0,0] op_sel_hi:[0,1]
	s_cselect_b64 s[76:77], -1, 0
	v_pk_fma_f32 v[104:105], v[104:105], v[26:27], v[44:45] op_sel:[1,1,0] op_sel_hi:[1,0,1] neg_lo:[0,1,0]
	v_pk_mul_f32 v[44:45], v[48:49], v[42:43] op_sel:[0,0] op_sel_hi:[0,1]
	s_cmpk_lt_i32 s78, 0x400
	v_pk_fma_f32 v[110:111], v[48:49], v[42:43], v[44:45] op_sel:[1,1,0] op_sel_hi:[1,0,1] neg_lo:[0,1,0]
	v_mov_b64_e32 v[48:49], s[8:9]
	v_pk_mul_f32 v[44:45], v[60:61], v[48:49] op_sel:[0,0] op_sel_hi:[0,1]
	s_cselect_b32 s0, s78, -1
	v_pk_fma_f32 v[60:61], v[60:61], v[48:49], v[44:45] op_sel:[1,1,0] op_sel_hi:[1,0,1] neg_lo:[0,1,0]
	v_mov_b64_e32 v[44:45], s[54:55]
	v_pk_mul_f32 v[112:113], v[98:99], v[44:45] op_sel:[0,0] op_sel_hi:[0,1]
	s_cmp_lt_i32 s0, 0
	v_pk_fma_f32 v[98:99], v[98:99], v[44:45], v[112:113] op_sel:[1,1,0] op_sel_hi:[1,0,1] neg_lo:[0,1,0]
	v_pk_mul_f32 v[112:113], v[50:51], v[26:27] op_sel:[0,0] op_sel_hi:[0,1]
	v_pk_fma_f32 v[112:113], v[50:51], v[26:27], v[112:113] op_sel:[1,1,0] op_sel_hi:[1,0,1] neg_lo:[0,1,0]
	v_pk_mul_f32 v[50:51], v[52:53], v[44:45] op_sel:[0,0] op_sel_hi:[0,1]
	v_pk_fma_f32 v[52:53], v[52:53], v[44:45], v[50:51] op_sel:[1,1,0] op_sel_hi:[1,0,1] neg_lo:[0,1,0]
	v_mov_b64_e32 v[50:51], s[56:57]
	v_pk_mul_f32 v[114:115], v[54:55], v[50:51] op_sel:[0,0] op_sel_hi:[0,1]
	v_pk_fma_f32 v[54:55], v[54:55], v[50:51], v[114:115] op_sel:[1,1,0] op_sel_hi:[1,0,1] neg_lo:[0,1,0]
	v_pk_add_f32 v[114:115], v[64:65], v[66:67]
	v_pk_add_f32 v[64:65], v[64:65], v[66:67] neg_lo:[0,1] neg_hi:[0,1]
	v_pk_add_f32 v[66:67], v[58:59], v[62:63]
	v_pk_add_f32 v[58:59], v[58:59], v[62:63] neg_lo:[0,1] neg_hi:[0,1]
	v_pk_add_f32 v[62:63], v[114:115], v[66:67]
	v_pk_add_f32 v[66:67], v[114:115], v[66:67] neg_lo:[0,1] neg_hi:[0,1]
	v_pk_add_f32 v[114:115], v[64:65], v[58:59] op_sel:[0,1] op_sel_hi:[1,0] neg_hi:[0,1]
	v_pk_add_f32 v[58:59], v[64:65], v[58:59] op_sel:[0,1] op_sel_hi:[1,0] neg_lo:[0,1]
	v_pk_add_f32 v[64:65], v[100:101], v[68:69]
	v_pk_add_f32 v[68:69], v[100:101], v[68:69] neg_lo:[0,1] neg_hi:[0,1]
	v_pk_add_f32 v[100:101], v[106:107], v[104:105]
	v_pk_add_f32 v[104:105], v[106:107], v[104:105] neg_lo:[0,1] neg_hi:[0,1]
	v_pk_add_f32 v[106:107], v[64:65], v[100:101]
	v_pk_add_f32 v[64:65], v[64:65], v[100:101] neg_lo:[0,1] neg_hi:[0,1]
	v_pk_add_f32 v[100:101], v[68:69], v[104:105] op_sel:[0,1] op_sel_hi:[1,0] neg_hi:[0,1]
	v_pk_add_f32 v[68:69], v[68:69], v[104:105] op_sel:[0,1] op_sel_hi:[1,0] neg_lo:[0,1]
	v_pk_add_f32 v[104:105], v[56:57], v[60:61]
	v_pk_add_f32 v[56:57], v[56:57], v[60:61] neg_lo:[0,1] neg_hi:[0,1]
	v_pk_add_f32 v[60:61], v[110:111], v[98:99]
	v_pk_add_f32 v[98:99], v[110:111], v[98:99] neg_lo:[0,1] neg_hi:[0,1]
	v_pk_add_f32 v[110:111], v[104:105], v[60:61]
	v_pk_add_f32 v[60:61], v[104:105], v[60:61] neg_lo:[0,1] neg_hi:[0,1]
	v_pk_add_f32 v[104:105], v[56:57], v[98:99] op_sel:[0,1] op_sel_hi:[1,0] neg_hi:[0,1]
	v_pk_add_f32 v[56:57], v[56:57], v[98:99] op_sel:[0,1] op_sel_hi:[1,0] neg_lo:[0,1]
	v_pk_add_f32 v[98:99], v[102:103], v[52:53]
	v_pk_add_f32 v[52:53], v[102:103], v[52:53] neg_lo:[0,1] neg_hi:[0,1]
	v_pk_add_f32 v[102:103], v[112:113], v[54:55]
	v_pk_add_f32 v[54:55], v[112:113], v[54:55] neg_lo:[0,1] neg_hi:[0,1]
	v_pk_add_f32 v[112:113], v[98:99], v[102:103]
	v_pk_add_f32 v[98:99], v[98:99], v[102:103] neg_lo:[0,1] neg_hi:[0,1]
	v_pk_add_f32 v[102:103], v[52:53], v[54:55] op_sel:[0,1] op_sel_hi:[1,0] neg_hi:[0,1]
	v_pk_add_f32 v[52:53], v[52:53], v[54:55] op_sel:[0,1] op_sel_hi:[1,0] neg_lo:[0,1]
	v_mov_b32_e32 v55, v39
	v_mov_b32_e32 v54, v38
	ds_write_b64 v132, v[62:63]
	v_pk_mul_f32 v[62:63], v[106:107], v[54:55] op_sel:[0,0] op_sel_hi:[0,1]
	v_pk_fma_f32 v[62:63], v[106:107], v[54:55], v[62:63] op_sel:[1,1,0] op_sel_hi:[1,0,1] neg_lo:[0,1,0]
	ds_write_b64 v132, v[62:63] offset:2176
	v_pk_mul_f32 v[62:63], v[54:55], v[54:55] op_sel:[0,0] op_sel_hi:[0,1]
	v_pk_fma_f32 v[62:63], v[54:55], v[54:55], v[62:63] op_sel:[1,1,0] op_sel_hi:[1,0,1] neg_lo:[0,1,0]
	v_pk_mul_f32 v[106:107], v[110:111], v[62:63] op_sel:[0,0] op_sel_hi:[0,1]
	v_pk_fma_f32 v[106:107], v[110:111], v[62:63], v[106:107] op_sel:[1,1,0] op_sel_hi:[1,0,1] neg_lo:[0,1,0]
	ds_write_b64 v132, v[106:107] offset:4352
	v_pk_mul_f32 v[106:107], v[62:63], v[54:55] op_sel:[0,0] op_sel_hi:[0,1]
	v_pk_fma_f32 v[62:63], v[62:63], v[54:55], v[106:107] op_sel:[1,1,0] op_sel_hi:[1,0,1] neg_lo:[0,1,0]
	v_pk_mul_f32 v[106:107], v[112:113], v[62:63] op_sel:[0,0] op_sel_hi:[0,1]
	v_pk_fma_f32 v[106:107], v[112:113], v[62:63], v[106:107] op_sel:[1,1,0] op_sel_hi:[1,0,1] neg_lo:[0,1,0]
	ds_write_b64 v132, v[106:107] offset:6528
	v_pk_mul_f32 v[106:107], v[62:63], v[54:55] op_sel:[0,0] op_sel_hi:[0,1]
	v_pk_fma_f32 v[62:63], v[62:63], v[54:55], v[106:107] op_sel:[1,1,0] op_sel_hi:[1,0,1] neg_lo:[0,1,0]
	v_pk_mul_f32 v[106:107], v[114:115], v[62:63] op_sel:[0,0] op_sel_hi:[0,1]
	v_pk_fma_f32 v[106:107], v[114:115], v[62:63], v[106:107] op_sel:[1,1,0] op_sel_hi:[1,0,1] neg_lo:[0,1,0]
	ds_write_b64 v132, v[106:107] offset:8704
	v_pk_mul_f32 v[106:107], v[62:63], v[54:55] op_sel:[0,0] op_sel_hi:[0,1]
	v_pk_fma_f32 v[62:63], v[62:63], v[54:55], v[106:107] op_sel:[1,1,0] op_sel_hi:[1,0,1] neg_lo:[0,1,0]
	v_pk_mul_f32 v[106:107], v[100:101], v[62:63] op_sel:[0,0] op_sel_hi:[0,1]
	v_pk_fma_f32 v[100:101], v[100:101], v[62:63], v[106:107] op_sel:[1,1,0] op_sel_hi:[1,0,1] neg_lo:[0,1,0]
	ds_write_b64 v132, v[100:101] offset:10880
	v_pk_mul_f32 v[100:101], v[62:63], v[54:55] op_sel:[0,0] op_sel_hi:[0,1]
	v_pk_fma_f32 v[62:63], v[62:63], v[54:55], v[100:101] op_sel:[1,1,0] op_sel_hi:[1,0,1] neg_lo:[0,1,0]
	v_pk_mul_f32 v[100:101], v[104:105], v[62:63] op_sel:[0,0] op_sel_hi:[0,1]
	v_pk_fma_f32 v[100:101], v[104:105], v[62:63], v[100:101] op_sel:[1,1,0] op_sel_hi:[1,0,1] neg_lo:[0,1,0]
	ds_write_b64 v132, v[100:101] offset:13056
	v_pk_mul_f32 v[100:101], v[62:63], v[54:55] op_sel:[0,0] op_sel_hi:[0,1]
	v_pk_fma_f32 v[62:63], v[62:63], v[54:55], v[100:101] op_sel:[1,1,0] op_sel_hi:[1,0,1] neg_lo:[0,1,0]
	v_pk_mul_f32 v[100:101], v[102:103], v[62:63] op_sel:[0,0] op_sel_hi:[0,1]
	v_pk_fma_f32 v[100:101], v[102:103], v[62:63], v[100:101] op_sel:[1,1,0] op_sel_hi:[1,0,1] neg_lo:[0,1,0]
	ds_write_b64 v132, v[100:101] offset:15232
	v_pk_mul_f32 v[100:101], v[62:63], v[54:55] op_sel:[0,0] op_sel_hi:[0,1]
	v_pk_fma_f32 v[62:63], v[62:63], v[54:55], v[100:101] op_sel:[1,1,0] op_sel_hi:[1,0,1] neg_lo:[0,1,0]
	v_pk_mul_f32 v[100:101], v[66:67], v[62:63] op_sel:[0,0] op_sel_hi:[0,1]
	v_pk_fma_f32 v[66:67], v[66:67], v[62:63], v[100:101] op_sel:[1,1,0] op_sel_hi:[1,0,1] neg_lo:[0,1,0]
	ds_write_b64 v132, v[66:67] offset:17408
	v_pk_mul_f32 v[66:67], v[62:63], v[54:55] op_sel:[0,0] op_sel_hi:[0,1]
	v_pk_fma_f32 v[62:63], v[62:63], v[54:55], v[66:67] op_sel:[1,1,0] op_sel_hi:[1,0,1] neg_lo:[0,1,0]
	v_pk_mul_f32 v[66:67], v[64:65], v[62:63] op_sel:[0,0] op_sel_hi:[0,1]
	v_pk_fma_f32 v[64:65], v[64:65], v[62:63], v[66:67] op_sel:[1,1,0] op_sel_hi:[1,0,1] neg_lo:[0,1,0]
	ds_write_b64 v132, v[64:65] offset:19584
	v_pk_mul_f32 v[64:65], v[62:63], v[54:55] op_sel:[0,0] op_sel_hi:[0,1]
	v_pk_fma_f32 v[62:63], v[62:63], v[54:55], v[64:65] op_sel:[1,1,0] op_sel_hi:[1,0,1] neg_lo:[0,1,0]
	v_pk_mul_f32 v[64:65], v[60:61], v[62:63] op_sel:[0,0] op_sel_hi:[0,1]
	v_pk_fma_f32 v[60:61], v[60:61], v[62:63], v[64:65] op_sel:[1,1,0] op_sel_hi:[1,0,1] neg_lo:[0,1,0]
	ds_write_b64 v132, v[60:61] offset:21760
	v_pk_mul_f32 v[60:61], v[62:63], v[54:55] op_sel:[0,0] op_sel_hi:[0,1]
	v_pk_fma_f32 v[60:61], v[62:63], v[54:55], v[60:61] op_sel:[1,1,0] op_sel_hi:[1,0,1] neg_lo:[0,1,0]
	v_pk_mul_f32 v[62:63], v[98:99], v[60:61] op_sel:[0,0] op_sel_hi:[0,1]
	v_pk_fma_f32 v[62:63], v[98:99], v[60:61], v[62:63] op_sel:[1,1,0] op_sel_hi:[1,0,1] neg_lo:[0,1,0]
	ds_write_b64 v132, v[62:63] offset:23936
	v_pk_mul_f32 v[62:63], v[60:61], v[54:55] op_sel:[0,0] op_sel_hi:[0,1]
	v_pk_fma_f32 v[60:61], v[60:61], v[54:55], v[62:63] op_sel:[1,1,0] op_sel_hi:[1,0,1] neg_lo:[0,1,0]
	v_pk_mul_f32 v[62:63], v[58:59], v[60:61] op_sel:[0,0] op_sel_hi:[0,1]
	v_pk_fma_f32 v[58:59], v[58:59], v[60:61], v[62:63] op_sel:[1,1,0] op_sel_hi:[1,0,1] neg_lo:[0,1,0]
	ds_write_b64 v132, v[58:59] offset:26112
	v_pk_mul_f32 v[58:59], v[60:61], v[54:55] op_sel:[0,0] op_sel_hi:[0,1]
	v_pk_fma_f32 v[58:59], v[60:61], v[54:55], v[58:59] op_sel:[1,1,0] op_sel_hi:[1,0,1] neg_lo:[0,1,0]
	v_pk_mul_f32 v[60:61], v[68:69], v[58:59] op_sel:[0,0] op_sel_hi:[0,1]
	v_pk_fma_f32 v[60:61], v[68:69], v[58:59], v[60:61] op_sel:[1,1,0] op_sel_hi:[1,0,1] neg_lo:[0,1,0]
	ds_write_b64 v132, v[60:61] offset:28288
	v_pk_mul_f32 v[60:61], v[58:59], v[54:55] op_sel:[0,0] op_sel_hi:[0,1]
	v_pk_fma_f32 v[58:59], v[58:59], v[54:55], v[60:61] op_sel:[1,1,0] op_sel_hi:[1,0,1] neg_lo:[0,1,0]
	v_pk_mul_f32 v[60:61], v[56:57], v[58:59] op_sel:[0,0] op_sel_hi:[0,1]
	v_pk_fma_f32 v[56:57], v[56:57], v[58:59], v[60:61] op_sel:[1,1,0] op_sel_hi:[1,0,1] neg_lo:[0,1,0]
	ds_write_b64 v132, v[56:57] offset:30464
	v_pk_mul_f32 v[56:57], v[58:59], v[54:55] op_sel:[0,0] op_sel_hi:[0,1]
	v_pk_fma_f32 v[54:55], v[58:59], v[54:55], v[56:57] op_sel:[1,1,0] op_sel_hi:[1,0,1] neg_lo:[0,1,0]
	v_pk_mul_f32 v[56:57], v[52:53], v[54:55] op_sel:[0,0] op_sel_hi:[0,1]
	v_pk_fma_f32 v[52:53], v[52:53], v[54:55], v[56:57] op_sel:[1,1,0] op_sel_hi:[1,0,1] neg_lo:[0,1,0]
	ds_write_b64 v132, v[52:53] offset:32640
	s_waitcnt lgkmcnt(0)
	s_barrier
	ds_read2_b64 v[52:55], v134 offset1:17
	ds_read2_b64 v[56:59], v134 offset0:34 offset1:51
	ds_read2_b64 v[60:63], v134 offset0:68 offset1:85
	ds_read2_b64 v[64:67], v134 offset0:136 offset1:153
	ds_read2_b64 v[98:101], v134 offset0:102 offset1:119
	ds_read2_b64 v[102:105], v134 offset0:204 offset1:221
	ds_read2_b64 v[110:113], v134 offset0:170 offset1:187
	ds_read2_b64 v[114:117], v134 offset0:238 offset1:255
	s_waitcnt lgkmcnt(4)
	v_pk_add_f32 v[68:69], v[52:53], v[64:65]
	v_pk_add_f32 v[52:53], v[52:53], v[64:65] neg_lo:[0,1] neg_hi:[0,1]
	s_waitcnt lgkmcnt(2)
	v_pk_add_f32 v[64:65], v[60:61], v[102:103]
	v_pk_add_f32 v[60:61], v[60:61], v[102:103] neg_lo:[0,1] neg_hi:[0,1]
	v_pk_add_f32 v[102:103], v[68:69], v[64:65]
	v_pk_add_f32 v[64:65], v[68:69], v[64:65] neg_lo:[0,1] neg_hi:[0,1]
	v_pk_add_f32 v[68:69], v[52:53], v[60:61] op_sel:[0,1] op_sel_hi:[1,0] neg_hi:[0,1]
	v_pk_add_f32 v[52:53], v[52:53], v[60:61] op_sel:[0,1] op_sel_hi:[1,0] neg_lo:[0,1]
	v_pk_add_f32 v[60:61], v[54:55], v[66:67]
	v_pk_add_f32 v[54:55], v[54:55], v[66:67] neg_lo:[0,1] neg_hi:[0,1]
	v_pk_add_f32 v[66:67], v[62:63], v[104:105]
	v_pk_add_f32 v[62:63], v[62:63], v[104:105] neg_lo:[0,1] neg_hi:[0,1]
	v_pk_add_f32 v[104:105], v[60:61], v[66:67]
	v_pk_add_f32 v[60:61], v[60:61], v[66:67] neg_lo:[0,1] neg_hi:[0,1]
	v_pk_add_f32 v[66:67], v[54:55], v[62:63] op_sel:[0,1] op_sel_hi:[1,0] neg_hi:[0,1]
	v_pk_add_f32 v[54:55], v[54:55], v[62:63] op_sel:[0,1] op_sel_hi:[1,0] neg_lo:[0,1]
	s_waitcnt lgkmcnt(1)
	v_pk_add_f32 v[62:63], v[56:57], v[110:111]
	v_pk_add_f32 v[56:57], v[56:57], v[110:111] neg_lo:[0,1] neg_hi:[0,1]
	s_waitcnt lgkmcnt(0)
	v_pk_add_f32 v[106:107], v[98:99], v[114:115]
	v_pk_add_f32 v[98:99], v[98:99], v[114:115] neg_lo:[0,1] neg_hi:[0,1]
	v_pk_add_f32 v[110:111], v[62:63], v[106:107]
	v_pk_add_f32 v[62:63], v[62:63], v[106:107] neg_lo:[0,1] neg_hi:[0,1]
	v_pk_add_f32 v[106:107], v[56:57], v[98:99] op_sel:[0,1] op_sel_hi:[1,0] neg_hi:[0,1]
	v_pk_add_f32 v[56:57], v[56:57], v[98:99] op_sel:[0,1] op_sel_hi:[1,0] neg_lo:[0,1]
	v_pk_add_f32 v[98:99], v[58:59], v[112:113]
	v_pk_add_f32 v[58:59], v[58:59], v[112:113] neg_lo:[0,1] neg_hi:[0,1]
	v_pk_add_f32 v[112:113], v[100:101], v[116:117]
	v_pk_add_f32 v[100:101], v[100:101], v[116:117] neg_lo:[0,1] neg_hi:[0,1]
	v_pk_add_f32 v[114:115], v[98:99], v[112:113]
	v_pk_add_f32 v[98:99], v[98:99], v[112:113] neg_lo:[0,1] neg_hi:[0,1]
	v_pk_add_f32 v[112:113], v[58:59], v[100:101] op_sel:[0,1] op_sel_hi:[1,0] neg_hi:[0,1]
	v_pk_add_f32 v[58:59], v[58:59], v[100:101] op_sel:[0,1] op_sel_hi:[1,0] neg_lo:[0,1]
	v_pk_mul_f32 v[100:101], v[66:67], v[46:47] op_sel:[0,0] op_sel_hi:[0,1]
	v_pk_fma_f32 v[66:67], v[66:67], v[46:47], v[100:101] op_sel:[1,1,0] op_sel_hi:[1,0,1] neg_lo:[0,1,0]
	v_pk_mul_f32 v[100:101], v[106:107], v[42:43] op_sel:[0,0] op_sel_hi:[0,1]
	v_pk_fma_f32 v[100:101], v[106:107], v[42:43], v[100:101] op_sel:[1,1,0] op_sel_hi:[1,0,1] neg_lo:[0,1,0]
	v_pk_mul_f32 v[106:107], v[112:113], v[26:27] op_sel:[0,0] op_sel_hi:[0,1]
	v_pk_fma_f32 v[106:107], v[112:113], v[26:27], v[106:107] op_sel:[1,1,0] op_sel_hi:[1,0,1] neg_lo:[0,1,0]
	v_pk_mul_f32 v[112:113], v[60:61], v[42:43] op_sel:[0,0] op_sel_hi:[0,1]
	v_pk_fma_f32 v[60:61], v[60:61], v[42:43], v[112:113] op_sel:[1,1,0] op_sel_hi:[1,0,1] neg_lo:[0,1,0]
	v_pk_mul_f32 v[112:113], v[62:63], v[48:49] op_sel:[0,0] op_sel_hi:[0,1]
	v_pk_fma_f32 v[62:63], v[62:63], v[48:49], v[112:113] op_sel:[1,1,0] op_sel_hi:[1,0,1] neg_lo:[0,1,0]
	v_pk_mul_f32 v[112:113], v[98:99], v[44:45] op_sel:[0,0] op_sel_hi:[0,1]
	v_pk_fma_f32 v[98:99], v[98:99], v[44:45], v[112:113] op_sel:[1,1,0] op_sel_hi:[1,0,1] neg_lo:[0,1,0]
	v_pk_mul_f32 v[112:113], v[54:55], v[26:27] op_sel:[0,0] op_sel_hi:[0,1]
	v_pk_fma_f32 v[54:55], v[54:55], v[26:27], v[112:113] op_sel:[1,1,0] op_sel_hi:[1,0,1] neg_lo:[0,1,0]
	v_pk_mul_f32 v[112:113], v[56:57], v[44:45] op_sel:[0,0] op_sel_hi:[0,1]
	v_pk_fma_f32 v[56:57], v[56:57], v[44:45], v[112:113] op_sel:[1,1,0] op_sel_hi:[1,0,1] neg_lo:[0,1,0]
	v_pk_mul_f32 v[112:113], v[58:59], v[50:51] op_sel:[0,0] op_sel_hi:[0,1]
	v_pk_fma_f32 v[58:59], v[58:59], v[50:51], v[112:113] op_sel:[1,1,0] op_sel_hi:[1,0,1] neg_lo:[0,1,0]
	v_pk_add_f32 v[112:113], v[102:103], v[110:111]
	v_pk_add_f32 v[102:103], v[102:103], v[110:111] neg_lo:[0,1] neg_hi:[0,1]
	v_pk_add_f32 v[110:111], v[104:105], v[114:115]
	v_pk_add_f32 v[104:105], v[104:105], v[114:115] neg_lo:[0,1] neg_hi:[0,1]
	v_pk_add_f32 v[114:115], v[112:113], v[110:111]
	v_pk_add_f32 v[110:111], v[112:113], v[110:111] neg_lo:[0,1] neg_hi:[0,1]
	v_pk_add_f32 v[112:113], v[102:103], v[104:105] op_sel:[0,1] op_sel_hi:[1,0] neg_hi:[0,1]
	v_pk_add_f32 v[102:103], v[102:103], v[104:105] op_sel:[0,1] op_sel_hi:[1,0] neg_lo:[0,1]
	v_pk_add_f32 v[104:105], v[68:69], v[100:101]
	v_pk_add_f32 v[68:69], v[68:69], v[100:101] neg_lo:[0,1] neg_hi:[0,1]
	v_pk_add_f32 v[100:101], v[66:67], v[106:107]
	v_pk_add_f32 v[66:67], v[66:67], v[106:107] neg_lo:[0,1] neg_hi:[0,1]
	v_pk_add_f32 v[106:107], v[104:105], v[100:101]
	v_pk_add_f32 v[100:101], v[104:105], v[100:101] neg_lo:[0,1] neg_hi:[0,1]
	v_pk_add_f32 v[104:105], v[68:69], v[66:67] op_sel:[0,1] op_sel_hi:[1,0] neg_hi:[0,1]
	v_pk_add_f32 v[66:67], v[68:69], v[66:67] op_sel:[0,1] op_sel_hi:[1,0] neg_lo:[0,1]
	v_pk_add_f32 v[68:69], v[64:65], v[62:63]
	v_pk_add_f32 v[62:63], v[64:65], v[62:63] neg_lo:[0,1] neg_hi:[0,1]
	v_pk_add_f32 v[64:65], v[60:61], v[98:99]
	v_pk_add_f32 v[60:61], v[60:61], v[98:99] neg_lo:[0,1] neg_hi:[0,1]
	v_pk_add_f32 v[98:99], v[68:69], v[64:65]
	v_pk_add_f32 v[64:65], v[68:69], v[64:65] neg_lo:[0,1] neg_hi:[0,1]
	v_pk_add_f32 v[68:69], v[62:63], v[60:61] op_sel:[0,1] op_sel_hi:[1,0] neg_hi:[0,1]
	v_pk_add_f32 v[60:61], v[62:63], v[60:61] op_sel:[0,1] op_sel_hi:[1,0] neg_lo:[0,1]
	v_pk_add_f32 v[62:63], v[52:53], v[56:57]
	v_pk_add_f32 v[52:53], v[52:53], v[56:57] neg_lo:[0,1] neg_hi:[0,1]
	v_pk_add_f32 v[56:57], v[54:55], v[58:59]
	v_pk_add_f32 v[54:55], v[54:55], v[58:59] neg_lo:[0,1] neg_hi:[0,1]
	v_pk_add_f32 v[58:59], v[62:63], v[56:57]
	v_pk_add_f32 v[56:57], v[62:63], v[56:57] neg_lo:[0,1] neg_hi:[0,1]
	v_pk_add_f32 v[62:63], v[52:53], v[54:55] op_sel:[0,1] op_sel_hi:[1,0] neg_hi:[0,1]
	v_pk_add_f32 v[52:53], v[52:53], v[54:55] op_sel:[0,1] op_sel_hi:[1,0] neg_lo:[0,1]
	v_mov_b32_e32 v55, v41
	v_mov_b32_e32 v54, v40
	s_nop 0
	v_pk_mul_f32 v[116:117], v[106:107], v[54:55] op_sel:[0,0] op_sel_hi:[0,1]
	v_pk_fma_f32 v[106:107], v[106:107], v[54:55], v[116:117] op_sel:[1,1,0] op_sel_hi:[1,0,1] neg_lo:[0,1,0]
	ds_write2_b64 v134, v[114:115], v[106:107] offset1:17
	v_pk_mul_f32 v[106:107], v[54:55], v[54:55] op_sel:[0,0] op_sel_hi:[0,1]
	v_pk_fma_f32 v[106:107], v[54:55], v[54:55], v[106:107] op_sel:[1,1,0] op_sel_hi:[1,0,1] neg_lo:[0,1,0]
	v_pk_mul_f32 v[114:115], v[98:99], v[106:107] op_sel:[0,0] op_sel_hi:[0,1]
	v_pk_fma_f32 v[98:99], v[98:99], v[106:107], v[114:115] op_sel:[1,1,0] op_sel_hi:[1,0,1] neg_lo:[0,1,0]
	v_pk_mul_f32 v[114:115], v[106:107], v[54:55] op_sel:[0,0] op_sel_hi:[0,1]
	v_pk_fma_f32 v[106:107], v[106:107], v[54:55], v[114:115] op_sel:[1,1,0] op_sel_hi:[1,0,1] neg_lo:[0,1,0]
	v_pk_mul_f32 v[114:115], v[58:59], v[106:107] op_sel:[0,0] op_sel_hi:[0,1]
	v_pk_fma_f32 v[58:59], v[58:59], v[106:107], v[114:115] op_sel:[1,1,0] op_sel_hi:[1,0,1] neg_lo:[0,1,0]
	ds_write2_b64 v134, v[98:99], v[58:59] offset0:34 offset1:51
	v_pk_mul_f32 v[58:59], v[106:107], v[54:55] op_sel:[0,0] op_sel_hi:[0,1]
	v_pk_fma_f32 v[58:59], v[106:107], v[54:55], v[58:59] op_sel:[1,1,0] op_sel_hi:[1,0,1] neg_lo:[0,1,0]
	v_pk_mul_f32 v[98:99], v[112:113], v[58:59] op_sel:[0,0] op_sel_hi:[0,1]
	v_pk_mul_f32 v[106:107], v[58:59], v[54:55] op_sel:[0,0] op_sel_hi:[0,1]
	v_pk_fma_f32 v[98:99], v[112:113], v[58:59], v[98:99] op_sel:[1,1,0] op_sel_hi:[1,0,1] neg_lo:[0,1,0]
	v_pk_fma_f32 v[58:59], v[58:59], v[54:55], v[106:107] op_sel:[1,1,0] op_sel_hi:[1,0,1] neg_lo:[0,1,0]
	v_pk_mul_f32 v[106:107], v[104:105], v[58:59] op_sel:[0,0] op_sel_hi:[0,1]
	v_pk_fma_f32 v[104:105], v[104:105], v[58:59], v[106:107] op_sel:[1,1,0] op_sel_hi:[1,0,1] neg_lo:[0,1,0]
	ds_write2_b64 v134, v[98:99], v[104:105] offset0:68 offset1:85
	v_pk_mul_f32 v[98:99], v[58:59], v[54:55] op_sel:[0,0] op_sel_hi:[0,1]
	v_pk_fma_f32 v[58:59], v[58:59], v[54:55], v[98:99] op_sel:[1,1,0] op_sel_hi:[1,0,1] neg_lo:[0,1,0]
	v_pk_mul_f32 v[98:99], v[68:69], v[58:59] op_sel:[0,0] op_sel_hi:[0,1]
	v_pk_fma_f32 v[68:69], v[68:69], v[58:59], v[98:99] op_sel:[1,1,0] op_sel_hi:[1,0,1] neg_lo:[0,1,0]
	v_pk_mul_f32 v[98:99], v[58:59], v[54:55] op_sel:[0,0] op_sel_hi:[0,1]
	v_pk_fma_f32 v[58:59], v[58:59], v[54:55], v[98:99] op_sel:[1,1,0] op_sel_hi:[1,0,1] neg_lo:[0,1,0]
	v_pk_mul_f32 v[98:99], v[62:63], v[58:59] op_sel:[0,0] op_sel_hi:[0,1]
	v_pk_fma_f32 v[62:63], v[62:63], v[58:59], v[98:99] op_sel:[1,1,0] op_sel_hi:[1,0,1] neg_lo:[0,1,0]
	ds_write2_b64 v134, v[68:69], v[62:63] offset0:102 offset1:119
	v_pk_mul_f32 v[62:63], v[58:59], v[54:55] op_sel:[0,0] op_sel_hi:[0,1]
	v_pk_fma_f32 v[58:59], v[58:59], v[54:55], v[62:63] op_sel:[1,1,0] op_sel_hi:[1,0,1] neg_lo:[0,1,0]
	v_pk_mul_f32 v[62:63], v[110:111], v[58:59] op_sel:[0,0] op_sel_hi:[0,1]
	v_pk_mul_f32 v[68:69], v[58:59], v[54:55] op_sel:[0,0] op_sel_hi:[0,1]
	v_pk_fma_f32 v[62:63], v[110:111], v[58:59], v[62:63] op_sel:[1,1,0] op_sel_hi:[1,0,1] neg_lo:[0,1,0]
	v_pk_fma_f32 v[58:59], v[58:59], v[54:55], v[68:69] op_sel:[1,1,0] op_sel_hi:[1,0,1] neg_lo:[0,1,0]
	v_pk_mul_f32 v[68:69], v[100:101], v[58:59] op_sel:[0,0] op_sel_hi:[0,1]
	v_pk_fma_f32 v[68:69], v[100:101], v[58:59], v[68:69] op_sel:[1,1,0] op_sel_hi:[1,0,1] neg_lo:[0,1,0]
	ds_write2_b64 v134, v[62:63], v[68:69] offset0:136 offset1:153
	v_pk_mul_f32 v[62:63], v[58:59], v[54:55] op_sel:[0,0] op_sel_hi:[0,1]
	v_pk_fma_f32 v[58:59], v[58:59], v[54:55], v[62:63] op_sel:[1,1,0] op_sel_hi:[1,0,1] neg_lo:[0,1,0]
	v_pk_mul_f32 v[62:63], v[64:65], v[58:59] op_sel:[0,0] op_sel_hi:[0,1]
	v_pk_fma_f32 v[62:63], v[64:65], v[58:59], v[62:63] op_sel:[1,1,0] op_sel_hi:[1,0,1] neg_lo:[0,1,0]
	v_pk_mul_f32 v[64:65], v[58:59], v[54:55] op_sel:[0,0] op_sel_hi:[0,1]
	v_pk_fma_f32 v[58:59], v[58:59], v[54:55], v[64:65] op_sel:[1,1,0] op_sel_hi:[1,0,1] neg_lo:[0,1,0]
	v_pk_mul_f32 v[64:65], v[56:57], v[58:59] op_sel:[0,0] op_sel_hi:[0,1]
	v_pk_fma_f32 v[56:57], v[56:57], v[58:59], v[64:65] op_sel:[1,1,0] op_sel_hi:[1,0,1] neg_lo:[0,1,0]
	ds_write2_b64 v134, v[62:63], v[56:57] offset0:170 offset1:187
	v_pk_mul_f32 v[56:57], v[58:59], v[54:55] op_sel:[0,0] op_sel_hi:[0,1]
	v_pk_fma_f32 v[56:57], v[58:59], v[54:55], v[56:57] op_sel:[1,1,0] op_sel_hi:[1,0,1] neg_lo:[0,1,0]
	v_pk_mul_f32 v[58:59], v[102:103], v[56:57] op_sel:[0,0] op_sel_hi:[0,1]
	v_pk_mul_f32 v[62:63], v[56:57], v[54:55] op_sel:[0,0] op_sel_hi:[0,1]
	v_pk_fma_f32 v[58:59], v[102:103], v[56:57], v[58:59] op_sel:[1,1,0] op_sel_hi:[1,0,1] neg_lo:[0,1,0]
	v_pk_fma_f32 v[56:57], v[56:57], v[54:55], v[62:63] op_sel:[1,1,0] op_sel_hi:[1,0,1] neg_lo:[0,1,0]
	v_pk_mul_f32 v[62:63], v[66:67], v[56:57] op_sel:[0,0] op_sel_hi:[0,1]
	v_pk_fma_f32 v[62:63], v[66:67], v[56:57], v[62:63] op_sel:[1,1,0] op_sel_hi:[1,0,1] neg_lo:[0,1,0]
	ds_write2_b64 v134, v[58:59], v[62:63] offset0:204 offset1:221
	v_pk_mul_f32 v[58:59], v[56:57], v[54:55] op_sel:[0,0] op_sel_hi:[0,1]
	v_pk_fma_f32 v[56:57], v[56:57], v[54:55], v[58:59] op_sel:[1,1,0] op_sel_hi:[1,0,1] neg_lo:[0,1,0]
	v_pk_mul_f32 v[58:59], v[60:61], v[56:57] op_sel:[0,0] op_sel_hi:[0,1]
	v_pk_fma_f32 v[58:59], v[60:61], v[56:57], v[58:59] op_sel:[1,1,0] op_sel_hi:[1,0,1] neg_lo:[0,1,0]
	v_pk_mul_f32 v[60:61], v[56:57], v[54:55] op_sel:[0,0] op_sel_hi:[0,1]
	v_pk_fma_f32 v[54:55], v[56:57], v[54:55], v[60:61] op_sel:[1,1,0] op_sel_hi:[1,0,1] neg_lo:[0,1,0]
	v_pk_mul_f32 v[56:57], v[52:53], v[54:55] op_sel:[0,0] op_sel_hi:[0,1]
	v_pk_fma_f32 v[52:53], v[52:53], v[54:55], v[56:57] op_sel:[1,1,0] op_sel_hi:[1,0,1] neg_lo:[0,1,0]
	ds_write2_b64 v134, v[58:59], v[52:53] offset0:238 offset1:255
	s_waitcnt lgkmcnt(0)
	s_barrier
	ds_read2_b64 v[52:55], v135 offset1:1
	ds_read2_b64 v[56:59], v135 offset0:2 offset1:3
	ds_read2_b64 v[60:63], v135 offset0:8 offset1:9
	ds_read2_b64 v[64:67], v135 offset0:4 offset1:5
	ds_read2_b64 v[98:101], v135 offset0:6 offset1:7
	ds_read2_b64 v[102:105], v135 offset0:12 offset1:13
	ds_read2_b64 v[110:113], v135 offset0:10 offset1:11
	ds_read2_b64 v[114:117], v135 offset0:14 offset1:15
	s_waitcnt lgkmcnt(5)
	v_pk_add_f32 v[68:69], v[52:53], v[60:61]
	v_pk_add_f32 v[52:53], v[52:53], v[60:61] neg_lo:[0,1] neg_hi:[0,1]
	s_waitcnt lgkmcnt(2)
	v_pk_add_f32 v[60:61], v[64:65], v[102:103]
	v_pk_add_f32 v[64:65], v[64:65], v[102:103] neg_lo:[0,1] neg_hi:[0,1]
	v_pk_add_f32 v[102:103], v[68:69], v[60:61]
	v_pk_add_f32 v[60:61], v[68:69], v[60:61] neg_lo:[0,1] neg_hi:[0,1]
	v_pk_add_f32 v[68:69], v[52:53], v[64:65] op_sel:[0,1] op_sel_hi:[1,0] neg_hi:[0,1]
	v_pk_add_f32 v[52:53], v[52:53], v[64:65] op_sel:[0,1] op_sel_hi:[1,0] neg_lo:[0,1]
	v_pk_add_f32 v[64:65], v[54:55], v[62:63]
	v_pk_add_f32 v[54:55], v[54:55], v[62:63] neg_lo:[0,1] neg_hi:[0,1]
	v_pk_add_f32 v[62:63], v[66:67], v[104:105]
	v_pk_add_f32 v[66:67], v[66:67], v[104:105] neg_lo:[0,1] neg_hi:[0,1]
	v_pk_add_f32 v[104:105], v[64:65], v[62:63]
	v_pk_add_f32 v[62:63], v[64:65], v[62:63] neg_lo:[0,1] neg_hi:[0,1]
	v_pk_add_f32 v[64:65], v[54:55], v[66:67] op_sel:[0,1] op_sel_hi:[1,0] neg_hi:[0,1]
	v_pk_add_f32 v[54:55], v[54:55], v[66:67] op_sel:[0,1] op_sel_hi:[1,0] neg_lo:[0,1]
	s_waitcnt lgkmcnt(1)
	v_pk_add_f32 v[66:67], v[56:57], v[110:111]
	v_pk_add_f32 v[56:57], v[56:57], v[110:111] neg_lo:[0,1] neg_hi:[0,1]
	s_waitcnt lgkmcnt(0)
	v_pk_add_f32 v[106:107], v[98:99], v[114:115]
	v_pk_add_f32 v[98:99], v[98:99], v[114:115] neg_lo:[0,1] neg_hi:[0,1]
	v_pk_add_f32 v[110:111], v[66:67], v[106:107]
	v_pk_add_f32 v[66:67], v[66:67], v[106:107] neg_lo:[0,1] neg_hi:[0,1]
	v_pk_add_f32 v[106:107], v[56:57], v[98:99] op_sel:[0,1] op_sel_hi:[1,0] neg_hi:[0,1]
	v_pk_add_f32 v[56:57], v[56:57], v[98:99] op_sel:[0,1] op_sel_hi:[1,0] neg_lo:[0,1]
	v_pk_add_f32 v[98:99], v[58:59], v[112:113]
	v_pk_add_f32 v[58:59], v[58:59], v[112:113] neg_lo:[0,1] neg_hi:[0,1]
	v_pk_add_f32 v[112:113], v[100:101], v[116:117]
	v_pk_add_f32 v[100:101], v[100:101], v[116:117] neg_lo:[0,1] neg_hi:[0,1]
	v_pk_add_f32 v[114:115], v[98:99], v[112:113]
	v_pk_add_f32 v[98:99], v[98:99], v[112:113] neg_lo:[0,1] neg_hi:[0,1]
	v_pk_add_f32 v[112:113], v[58:59], v[100:101] op_sel:[0,1] op_sel_hi:[1,0] neg_hi:[0,1]
	v_pk_add_f32 v[58:59], v[58:59], v[100:101] op_sel:[0,1] op_sel_hi:[1,0] neg_lo:[0,1]
	v_pk_mul_f32 v[100:101], v[64:65], v[46:47] op_sel:[0,0] op_sel_hi:[0,1]
	v_pk_fma_f32 v[46:47], v[64:65], v[46:47], v[100:101] op_sel:[1,1,0] op_sel_hi:[1,0,1] neg_lo:[0,1,0]
	v_pk_mul_f32 v[64:65], v[106:107], v[42:43] op_sel:[0,0] op_sel_hi:[0,1]
	v_pk_mul_f32 v[100:101], v[112:113], v[26:27] op_sel:[0,0] op_sel_hi:[0,1]
	v_pk_fma_f32 v[64:65], v[106:107], v[42:43], v[64:65] op_sel:[1,1,0] op_sel_hi:[1,0,1] neg_lo:[0,1,0]
	v_pk_mul_f32 v[106:107], v[62:63], v[42:43] op_sel:[0,0] op_sel_hi:[0,1]
	v_pk_fma_f32 v[100:101], v[112:113], v[26:27], v[100:101] op_sel:[1,1,0] op_sel_hi:[1,0,1] neg_lo:[0,1,0]
	v_pk_fma_f32 v[42:43], v[62:63], v[42:43], v[106:107] op_sel:[1,1,0] op_sel_hi:[1,0,1] neg_lo:[0,1,0]
	v_pk_mul_f32 v[62:63], v[66:67], v[48:49] op_sel:[0,0] op_sel_hi:[0,1]
	v_pk_fma_f32 v[48:49], v[66:67], v[48:49], v[62:63] op_sel:[1,1,0] op_sel_hi:[1,0,1] neg_lo:[0,1,0]
	v_pk_mul_f32 v[62:63], v[98:99], v[44:45] op_sel:[0,0] op_sel_hi:[0,1]
	v_pk_mul_f32 v[66:67], v[54:55], v[26:27] op_sel:[0,0] op_sel_hi:[0,1]
	v_pk_fma_f32 v[26:27], v[54:55], v[26:27], v[66:67] op_sel:[1,1,0] op_sel_hi:[1,0,1] neg_lo:[0,1,0]
	v_pk_mul_f32 v[54:55], v[56:57], v[44:45] op_sel:[0,0] op_sel_hi:[0,1]
	v_pk_fma_f32 v[62:63], v[98:99], v[44:45], v[62:63] op_sel:[1,1,0] op_sel_hi:[1,0,1] neg_lo:[0,1,0]
	v_pk_add_f32 v[66:67], v[104:105], v[114:115] neg_lo:[0,1] neg_hi:[0,1]
	v_pk_fma_f32 v[44:45], v[56:57], v[44:45], v[54:55] op_sel:[1,1,0] op_sel_hi:[1,0,1] neg_lo:[0,1,0]
	v_pk_mul_f32 v[54:55], v[58:59], v[50:51] op_sel:[0,0] op_sel_hi:[0,1]
	v_pk_add_f32 v[56:57], v[102:103], v[110:111] neg_lo:[0,1] neg_hi:[0,1]
	v_pk_fma_f32 v[50:51], v[58:59], v[50:51], v[54:55] op_sel:[1,1,0] op_sel_hi:[1,0,1] neg_lo:[0,1,0]
	v_pk_add_f32 v[54:55], v[102:103], v[110:111]
	v_pk_add_f32 v[58:59], v[104:105], v[114:115]
	s_nop 0
	v_pk_add_f32 v[98:99], v[54:55], v[58:59]
	v_pk_add_f32 v[54:55], v[54:55], v[58:59] neg_lo:[0,1] neg_hi:[0,1]
	v_pk_add_f32 v[58:59], v[56:57], v[66:67] op_sel:[0,1] op_sel_hi:[1,0] neg_hi:[0,1]
	v_pk_add_f32 v[56:57], v[56:57], v[66:67] op_sel:[0,1] op_sel_hi:[1,0] neg_lo:[0,1]
	v_pk_add_f32 v[66:67], v[68:69], v[64:65]
	v_pk_add_f32 v[64:65], v[68:69], v[64:65] neg_lo:[0,1] neg_hi:[0,1]
	v_pk_add_f32 v[68:69], v[46:47], v[100:101]
	v_pk_add_f32 v[46:47], v[46:47], v[100:101] neg_lo:[0,1] neg_hi:[0,1]
	v_pk_add_f32 v[100:101], v[66:67], v[68:69]
	v_pk_add_f32 v[66:67], v[66:67], v[68:69] neg_lo:[0,1] neg_hi:[0,1]
	v_pk_add_f32 v[68:69], v[64:65], v[46:47] op_sel:[0,1] op_sel_hi:[1,0] neg_hi:[0,1]
	v_pk_add_f32 v[46:47], v[64:65], v[46:47] op_sel:[0,1] op_sel_hi:[1,0] neg_lo:[0,1]
	v_pk_add_f32 v[64:65], v[60:61], v[48:49]
	v_pk_add_f32 v[48:49], v[60:61], v[48:49] neg_lo:[0,1] neg_hi:[0,1]
	v_pk_add_f32 v[60:61], v[42:43], v[62:63]
	v_pk_add_f32 v[42:43], v[42:43], v[62:63] neg_lo:[0,1] neg_hi:[0,1]
	v_pk_add_f32 v[62:63], v[64:65], v[60:61]
	v_pk_add_f32 v[60:61], v[64:65], v[60:61] neg_lo:[0,1] neg_hi:[0,1]
	v_pk_add_f32 v[64:65], v[48:49], v[42:43] op_sel:[0,1] op_sel_hi:[1,0] neg_hi:[0,1]
	v_pk_add_f32 v[102:103], v[48:49], v[42:43] op_sel:[0,1] op_sel_hi:[1,0] neg_lo:[0,1]
	v_pk_add_f32 v[42:43], v[52:53], v[44:45]
	v_pk_add_f32 v[48:49], v[26:27], v[50:51]
	v_pk_add_f32 v[44:45], v[52:53], v[44:45] neg_lo:[0,1] neg_hi:[0,1]
	v_pk_add_f32 v[104:105], v[42:43], v[48:49]
	v_pk_add_f32 v[106:107], v[42:43], v[48:49] neg_lo:[0,1] neg_hi:[0,1]
	s_waitcnt vmcnt(14)
	v_pk_mul_f32 v[42:43], v[58:59], v[30:31] op_sel:[0,0] op_sel_hi:[0,1]
	v_pk_add_f32 v[26:27], v[26:27], v[50:51] neg_lo:[0,1] neg_hi:[0,1]
	v_pk_fma_f32 v[30:31], v[58:59], v[30:31], v[42:43] op_sel:[1,1,0] op_sel_hi:[1,0,1] neg_lo:[0,1,0]
	s_waitcnt vmcnt(13)
	v_pk_mul_f32 v[42:43], v[54:55], v[28:29] op_sel:[0,0] op_sel_hi:[0,1]
	s_waitcnt vmcnt(8)
	v_pk_mul_f32 v[50:51], v[46:47], v[76:77] op_sel:[0,0] op_sel_hi:[0,1]
	v_pk_mul_f32 v[48:49], v[66:67], v[72:73] op_sel:[0,0] op_sel_hi:[0,1]
	v_pk_fma_f32 v[42:43], v[54:55], v[28:29], v[42:43] op_sel:[1,1,0] op_sel_hi:[1,0,1] neg_lo:[0,1,0]
	s_waitcnt vmcnt(5)
	v_pk_mul_f32 v[54:55], v[60:61], v[80:81] op_sel:[0,0] op_sel_hi:[0,1]
	v_pk_add_f32 v[110:111], v[44:45], v[26:27] op_sel:[0,1] op_sel_hi:[1,0] neg_hi:[0,1]
	v_pk_add_f32 v[112:113], v[44:45], v[26:27] op_sel:[0,1] op_sel_hi:[1,0] neg_lo:[0,1]
	v_pk_mul_f32 v[28:29], v[56:57], v[32:33] op_sel:[0,0] op_sel_hi:[0,1]
	v_pk_fma_f32 v[52:53], v[46:47], v[76:77], v[50:51] op_sel:[1,1,0] op_sel_hi:[1,0,1] neg_lo:[0,1,0]
	v_pk_mul_f32 v[46:47], v[62:63], v[86:87] op_sel:[0,0] op_sel_hi:[0,1]
	v_pk_mul_f32 v[50:51], v[64:65], v[82:83] op_sel:[0,0] op_sel_hi:[0,1]
	v_pk_mul_f32 v[26:27], v[98:99], v[70:71] op_sel:[0,0] op_sel_hi:[0,1]
	s_waitcnt vmcnt(2)
	v_pk_mul_f32 v[58:59], v[110:111], v[90:91] op_sel:[0,0] op_sel_hi:[0,1]
	v_pk_fma_f32 v[44:45], v[56:57], v[32:33], v[28:29] op_sel:[1,1,0] op_sel_hi:[1,0,1] neg_lo:[0,1,0]
	v_pk_fma_f32 v[56:57], v[60:61], v[80:81], v[54:55] op_sel:[1,1,0] op_sel_hi:[1,0,1] neg_lo:[0,1,0]
	v_pk_mul_f32 v[54:55], v[102:103], v[84:85] op_sel:[0,0] op_sel_hi:[0,1]
	v_pk_mul_f32 v[28:29], v[100:101], v[78:79] op_sel:[0,0] op_sel_hi:[0,1]
	v_pk_mul_f32 v[32:33], v[68:69], v[74:75] op_sel:[0,0] op_sel_hi:[0,1]
	v_pk_fma_f32 v[46:47], v[62:63], v[86:87], v[46:47] op_sel:[1,1,0] op_sel_hi:[1,0,1] neg_lo:[0,1,0]
	v_pk_fma_f32 v[50:51], v[64:65], v[82:83], v[50:51] op_sel:[1,1,0] op_sel_hi:[1,0,1] neg_lo:[0,1,0]
	s_waitcnt vmcnt(1)
	v_pk_mul_f32 v[62:63], v[106:107], v[88:89] op_sel:[0,0] op_sel_hi:[0,1]
	v_pk_fma_f32 v[60:61], v[102:103], v[84:85], v[54:55] op_sel:[1,1,0] op_sel_hi:[1,0,1] neg_lo:[0,1,0]
	v_pk_mul_f32 v[54:55], v[104:105], v[94:95] op_sel:[0,0] op_sel_hi:[0,1]
	s_waitcnt vmcnt(0)
	v_pk_mul_f32 v[64:65], v[112:113], v[92:93] op_sel:[0,0] op_sel_hi:[0,1]
	v_pk_fma_f32 v[26:27], v[98:99], v[70:71], v[26:27] op_sel:[1,1,0] op_sel_hi:[1,0,1] neg_lo:[0,1,0]
	v_pk_fma_f32 v[28:29], v[100:101], v[78:79], v[28:29] op_sel:[1,1,0] op_sel_hi:[1,0,1] neg_lo:[0,1,0]
	v_pk_fma_f32 v[32:33], v[68:69], v[74:75], v[32:33] op_sel:[1,1,0] op_sel_hi:[1,0,1] neg_lo:[0,1,0]
	v_pk_fma_f32 v[48:49], v[66:67], v[72:73], v[48:49] op_sel:[1,1,0] op_sel_hi:[1,0,1] neg_lo:[0,1,0]
	v_pk_fma_f32 v[54:55], v[104:105], v[94:95], v[54:55] op_sel:[1,1,0] op_sel_hi:[1,0,1] neg_lo:[0,1,0]
	v_pk_fma_f32 v[58:59], v[110:111], v[90:91], v[58:59] op_sel:[1,1,0] op_sel_hi:[1,0,1] neg_lo:[0,1,0]
	v_pk_fma_f32 v[62:63], v[106:107], v[88:89], v[62:63] op_sel:[1,1,0] op_sel_hi:[1,0,1] neg_lo:[0,1,0]
	v_pk_fma_f32 v[64:65], v[112:113], v[92:93], v[64:65] op_sel:[1,1,0] op_sel_hi:[1,0,1] neg_lo:[0,1,0]
	s_cbranch_scc1 .LBB0_3486
	s_mul_i32 s15, s0, 0x4400
	s_mul_hi_u32 s1, s0, 0x4400
	s_add_u32 s28, s11, s15
	s_addc_u32 s29, s10, s1
	s_add_i32 s1, s0, 0x400
	s_add_i32 s79, s15, 0x1100000
	s_mul_hi_u32 s1, s1, 0x4400
	v_lshlrev_b32_e32 v2, 3, v133
	s_add_u32 s80, s11, s79
	v_ashrrev_i32_e32 v3, 31, v2
	s_addc_u32 s81, s10, s1
	s_addk_i32 s0, 0x800
	s_add_i32 s15, s15, 0x2200000
	v_lshlrev_b64 v[18:19], 1, v[2:3]
	v_add_u32_e32 v2, 0x1000, v2
	s_mul_hi_u32 s1, s0, 0x4400
	s_add_u32 s0, s11, s15
	v_ashrrev_i32_e32 v3, 31, v2
	s_addc_u32 s1, s10, s1
	v_lshlrev_b64 v[20:21], 1, v[2:3]
	v_lshl_add_u64 v[4:5], s[28:29], 0, v[18:19]
	v_lshl_add_u64 v[6:7], s[28:29], 0, v[20:21]
	v_lshl_add_u64 v[10:11], s[80:81], 0, v[18:19]
	v_lshl_add_u64 v[14:15], s[80:81], 0, v[20:21]
	v_lshl_add_u64 v[18:19], s[0:1], 0, v[18:19]
	v_lshl_add_u64 v[22:23], s[0:1], 0, v[20:21]
	global_load_dwordx4 v[2:5], v[4:5], off
	s_nop 0
	global_load_dwordx4 v[6:9], v[6:7], off
	s_nop 0
	global_load_dwordx4 v[10:13], v[10:11], off
	s_nop 0
	global_load_dwordx4 v[14:17], v[14:15], off
	s_nop 0
	global_load_dwordx4 v[18:21], v[18:19], off
	s_nop 0
	global_load_dwordx4 v[22:25], v[22:23], off
.LBB0_3486:
	v_pk_add_f32 v[66:67], v[26:27], v[42:43]
	v_pk_add_f32 v[26:27], v[26:27], v[42:43] neg_lo:[0,1] neg_hi:[0,1]
	v_pk_add_f32 v[42:43], v[30:31], v[44:45]
	v_pk_add_f32 v[30:31], v[30:31], v[44:45] neg_lo:[0,1] neg_hi:[0,1]
	v_pk_add_f32 v[68:69], v[66:67], v[42:43]
	v_pk_add_f32 v[70:71], v[26:27], v[30:31] op_sel:[0,1] op_sel_hi:[1,0] neg_lo:[0,1]
	v_pk_add_f32 v[72:73], v[26:27], v[30:31] op_sel:[0,1] op_sel_hi:[1,0] neg_hi:[0,1]
	v_pk_add_f32 v[26:27], v[28:29], v[48:49]
	v_pk_add_f32 v[28:29], v[28:29], v[48:49] neg_lo:[0,1] neg_hi:[0,1]
	v_pk_add_f32 v[30:31], v[32:33], v[52:53]
	v_pk_add_f32 v[32:33], v[32:33], v[52:53] neg_lo:[0,1] neg_hi:[0,1]
	v_pk_add_f32 v[66:67], v[66:67], v[42:43] neg_lo:[0,1] neg_hi:[0,1]
	v_pk_add_f32 v[48:49], v[26:27], v[30:31]
	v_pk_add_f32 v[30:31], v[26:27], v[30:31] neg_lo:[0,1] neg_hi:[0,1]
	v_pk_add_f32 v[26:27], v[28:29], v[32:33] op_sel:[0,1] op_sel_hi:[1,0] neg_lo:[0,1]
	v_pk_add_f32 v[44:45], v[28:29], v[32:33] op_sel:[0,1] op_sel_hi:[1,0] neg_hi:[0,1]
	v_pk_add_f32 v[28:29], v[46:47], v[56:57]
	v_pk_add_f32 v[32:33], v[46:47], v[56:57] neg_lo:[0,1] neg_hi:[0,1]
	v_pk_add_f32 v[42:43], v[50:51], v[60:61]
	v_pk_add_f32 v[46:47], v[50:51], v[60:61] neg_lo:[0,1] neg_hi:[0,1]
	v_pk_add_f32 v[50:51], v[28:29], v[42:43]
	v_pk_add_f32 v[52:53], v[28:29], v[42:43] neg_lo:[0,1] neg_hi:[0,1]
	v_pk_add_f32 v[42:43], v[32:33], v[46:47] op_sel:[0,1] op_sel_hi:[1,0] neg_lo:[0,1]
	v_pk_add_f32 v[46:47], v[32:33], v[46:47] op_sel:[0,1] op_sel_hi:[1,0] neg_hi:[0,1]
	v_pk_add_f32 v[28:29], v[54:55], v[62:63]
	v_pk_add_f32 v[32:33], v[54:55], v[62:63] neg_lo:[0,1] neg_hi:[0,1]
	v_pk_add_f32 v[54:55], v[58:59], v[64:65]
	v_pk_add_f32 v[56:57], v[58:59], v[64:65] neg_lo:[0,1] neg_hi:[0,1]
	v_pk_add_f32 v[58:59], v[28:29], v[54:55]
	v_pk_add_f32 v[54:55], v[28:29], v[54:55] neg_lo:[0,1] neg_hi:[0,1]
	v_pk_add_f32 v[60:61], v[32:33], v[56:57] op_sel:[0,1] op_sel_hi:[1,0] neg_lo:[0,1]
	v_pk_add_f32 v[56:57], v[32:33], v[56:57] op_sel:[0,1] op_sel_hi:[1,0] neg_hi:[0,1]
	v_mov_b64_e32 v[32:33], s[58:59]
	v_pk_mul_f32 v[28:29], v[26:27], v[32:33] op_sel:[0,0] op_sel_hi:[0,1]
	v_pk_fma_f32 v[62:63], v[26:27], v[32:33], v[28:29] op_sel:[1,1,0] op_sel_hi:[1,0,1] neg_lo:[0,1,0]
	v_mov_b64_e32 v[28:29], s[60:61]
	v_pk_mul_f32 v[26:27], v[42:43], v[28:29] op_sel:[0,0] op_sel_hi:[0,1]
	v_pk_fma_f32 v[64:65], v[42:43], v[28:29], v[26:27] op_sel:[1,1,0] op_sel_hi:[1,0,1] neg_lo:[0,1,0]
	v_mov_b64_e32 v[26:27], s[62:63]
	v_pk_mul_f32 v[42:43], v[60:61], v[26:27] op_sel:[0,0] op_sel_hi:[0,1]
	v_pk_fma_f32 v[60:61], v[60:61], v[26:27], v[42:43] op_sel:[1,1,0] op_sel_hi:[1,0,1] neg_lo:[0,1,0]
	v_pk_mul_f32 v[42:43], v[30:31], v[28:29] op_sel:[0,0] op_sel_hi:[0,1]
	v_pk_fma_f32 v[74:75], v[30:31], v[28:29], v[42:43] op_sel:[1,1,0] op_sel_hi:[1,0,1] neg_lo:[0,1,0]
	v_mov_b64_e32 v[42:43], s[64:65]
	v_pk_mul_f32 v[30:31], v[52:53], v[42:43] op_sel:[0,0] op_sel_hi:[0,1]
	v_pk_fma_f32 v[52:53], v[52:53], v[42:43], v[30:31] op_sel:[1,1,0] op_sel_hi:[1,0,1] neg_lo:[0,1,0]
	v_mov_b64_e32 v[30:31], s[66:67]
	v_pk_mul_f32 v[76:77], v[54:55], v[30:31] op_sel:[0,0] op_sel_hi:[0,1]
	v_pk_fma_f32 v[54:55], v[54:55], v[30:31], v[76:77] op_sel:[1,1,0] op_sel_hi:[1,0,1] neg_lo:[0,1,0]
	v_pk_mul_f32 v[76:77], v[44:45], v[26:27] op_sel:[0,0] op_sel_hi:[0,1]
	v_pk_fma_f32 v[76:77], v[44:45], v[26:27], v[76:77] op_sel:[1,1,0] op_sel_hi:[1,0,1] neg_lo:[0,1,0]
	v_pk_mul_f32 v[44:45], v[46:47], v[30:31] op_sel:[0,0] op_sel_hi:[0,1]
	v_pk_fma_f32 v[46:47], v[46:47], v[30:31], v[44:45] op_sel:[1,1,0] op_sel_hi:[1,0,1] neg_lo:[0,1,0]
	v_mov_b64_e32 v[44:45], s[68:69]
	v_pk_mul_f32 v[78:79], v[56:57], v[44:45] op_sel:[0,0] op_sel_hi:[0,1]
	v_pk_fma_f32 v[56:57], v[56:57], v[44:45], v[78:79] op_sel:[1,1,0] op_sel_hi:[1,0,1] neg_lo:[0,1,0]
	v_pk_add_f32 v[78:79], v[68:69], v[50:51]
	v_pk_add_f32 v[50:51], v[68:69], v[50:51] neg_lo:[0,1] neg_hi:[0,1]
	v_pk_add_f32 v[68:69], v[48:49], v[58:59]
	v_pk_add_f32 v[48:49], v[48:49], v[58:59] neg_lo:[0,1] neg_hi:[0,1]
	v_pk_add_f32 v[58:59], v[78:79], v[68:69]
	v_pk_add_f32 v[68:69], v[78:79], v[68:69] neg_lo:[0,1] neg_hi:[0,1]
	v_pk_add_f32 v[78:79], v[50:51], v[48:49] op_sel:[0,1] op_sel_hi:[1,0] neg_lo:[0,1]
	v_pk_add_f32 v[48:49], v[50:51], v[48:49] op_sel:[0,1] op_sel_hi:[1,0] neg_hi:[0,1]
	v_pk_add_f32 v[50:51], v[70:71], v[64:65]
	v_pk_add_f32 v[64:65], v[70:71], v[64:65] neg_lo:[0,1] neg_hi:[0,1]
	v_pk_add_f32 v[70:71], v[62:63], v[60:61]
	v_pk_add_f32 v[60:61], v[62:63], v[60:61] neg_lo:[0,1] neg_hi:[0,1]
	v_pk_add_f32 v[62:63], v[50:51], v[70:71]
	v_pk_add_f32 v[50:51], v[50:51], v[70:71] neg_lo:[0,1] neg_hi:[0,1]
	v_pk_add_f32 v[70:71], v[64:65], v[60:61] op_sel:[0,1] op_sel_hi:[1,0] neg_lo:[0,1]
	v_pk_add_f32 v[60:61], v[64:65], v[60:61] op_sel:[0,1] op_sel_hi:[1,0] neg_hi:[0,1]
	v_pk_add_f32 v[64:65], v[66:67], v[52:53]
	v_pk_add_f32 v[52:53], v[66:67], v[52:53] neg_lo:[0,1] neg_hi:[0,1]
	v_pk_add_f32 v[66:67], v[74:75], v[54:55]
	v_pk_add_f32 v[54:55], v[74:75], v[54:55] neg_lo:[0,1] neg_hi:[0,1]
	v_pk_add_f32 v[74:75], v[64:65], v[66:67]
	v_pk_add_f32 v[64:65], v[64:65], v[66:67] neg_lo:[0,1] neg_hi:[0,1]
	v_pk_add_f32 v[66:67], v[52:53], v[54:55] op_sel:[0,1] op_sel_hi:[1,0] neg_lo:[0,1]
	v_pk_add_f32 v[52:53], v[52:53], v[54:55] op_sel:[0,1] op_sel_hi:[1,0] neg_hi:[0,1]
	v_pk_add_f32 v[54:55], v[72:73], v[46:47]
	v_pk_add_f32 v[46:47], v[72:73], v[46:47] neg_lo:[0,1] neg_hi:[0,1]
	v_pk_add_f32 v[72:73], v[76:77], v[56:57]
	v_pk_add_f32 v[56:57], v[76:77], v[56:57] neg_lo:[0,1] neg_hi:[0,1]
	v_pk_add_f32 v[76:77], v[54:55], v[72:73]
	v_pk_add_f32 v[54:55], v[54:55], v[72:73] neg_lo:[0,1] neg_hi:[0,1]
	v_pk_add_f32 v[72:73], v[46:47], v[56:57] op_sel:[0,1] op_sel_hi:[1,0] neg_lo:[0,1]
	v_pk_add_f32 v[46:47], v[46:47], v[56:57] op_sel:[0,1] op_sel_hi:[1,0] neg_hi:[0,1]
	ds_write2_b64 v135, v[58:59], v[62:63] offset1:1
	ds_write2_b64 v135, v[74:75], v[76:77] offset0:2 offset1:3
	ds_write2_b64 v135, v[78:79], v[70:71] offset0:4 offset1:5
	ds_write2_b64 v135, v[66:67], v[72:73] offset0:6 offset1:7
	ds_write2_b64 v135, v[68:69], v[50:51] offset0:8 offset1:9
	ds_write2_b64 v135, v[64:65], v[54:55] offset0:10 offset1:11
	ds_write2_b64 v135, v[48:49], v[60:61] offset0:12 offset1:13
	ds_write2_b64 v135, v[52:53], v[46:47] offset0:14 offset1:15
	s_waitcnt lgkmcnt(0)
	s_barrier
	ds_read2_b64 v[46:49], v134 offset1:17
	ds_read2_b64 v[50:53], v134 offset0:34 offset1:51
	s_waitcnt lgkmcnt(1)
	v_pk_mul_f32 v[54:55], v[48:49], v[40:41] op_sel:[0,0] op_sel_hi:[0,1] neg_hi:[0,1]
	v_pk_fma_f32 v[56:57], v[48:49], v[40:41], v[54:55] op_sel:[1,1,0] op_sel_hi:[1,0,1]
	v_pk_mul_f32 v[48:49], v[40:41], v[40:41] op_sel:[0,0] op_sel_hi:[0,1]
	v_pk_fma_f32 v[48:49], v[40:41], v[40:41], v[48:49] op_sel:[1,1,0] op_sel_hi:[1,0,1] neg_lo:[0,1,0]
	s_waitcnt lgkmcnt(0)
	v_pk_mul_f32 v[54:55], v[50:51], v[48:49] op_sel:[0,0] op_sel_hi:[0,1] neg_hi:[0,1]
	v_pk_fma_f32 v[58:59], v[50:51], v[48:49], v[54:55] op_sel:[1,1,0] op_sel_hi:[1,0,1]
	v_pk_mul_f32 v[50:51], v[48:49], v[40:41] op_sel:[0,0] op_sel_hi:[0,1]
	v_pk_fma_f32 v[54:55], v[48:49], v[40:41], v[50:51] op_sel:[1,1,0] op_sel_hi:[1,0,1] neg_lo:[0,1,0]
	ds_read2_b64 v[48:51], v134 offset0:68 offset1:85
	v_pk_mul_f32 v[60:61], v[52:53], v[54:55] op_sel:[0,0] op_sel_hi:[0,1] neg_hi:[0,1]
	v_pk_fma_f32 v[60:61], v[52:53], v[54:55], v[60:61] op_sel:[1,1,0] op_sel_hi:[1,0,1]
	v_pk_mul_f32 v[52:53], v[54:55], v[40:41] op_sel:[0,0] op_sel_hi:[0,1]
	v_pk_fma_f32 v[52:53], v[54:55], v[40:41], v[52:53] op_sel:[1,1,0] op_sel_hi:[1,0,1] neg_lo:[0,1,0]
	s_waitcnt lgkmcnt(0)
	v_pk_mul_f32 v[54:55], v[48:49], v[52:53] op_sel:[0,0] op_sel_hi:[0,1] neg_hi:[0,1]
	v_pk_fma_f32 v[62:63], v[48:49], v[52:53], v[54:55] op_sel:[1,1,0] op_sel_hi:[1,0,1]
	v_pk_mul_f32 v[48:49], v[52:53], v[40:41] op_sel:[0,0] op_sel_hi:[0,1]
	v_pk_fma_f32 v[48:49], v[52:53], v[40:41], v[48:49] op_sel:[1,1,0] op_sel_hi:[1,0,1] neg_lo:[0,1,0]
	ds_read2_b64 v[52:55], v134 offset0:102 offset1:119
	v_pk_mul_f32 v[64:65], v[50:51], v[48:49] op_sel:[0,0] op_sel_hi:[0,1] neg_hi:[0,1]
	v_pk_fma_f32 v[64:65], v[50:51], v[48:49], v[64:65] op_sel:[1,1,0] op_sel_hi:[1,0,1]
	v_pk_mul_f32 v[50:51], v[48:49], v[40:41] op_sel:[0,0] op_sel_hi:[0,1]
	v_pk_fma_f32 v[48:49], v[48:49], v[40:41], v[50:51] op_sel:[1,1,0] op_sel_hi:[1,0,1] neg_lo:[0,1,0]
	s_waitcnt lgkmcnt(0)
	v_pk_mul_f32 v[50:51], v[52:53], v[48:49] op_sel:[0,0] op_sel_hi:[0,1] neg_hi:[0,1]
	v_pk_fma_f32 v[66:67], v[52:53], v[48:49], v[50:51] op_sel:[1,1,0] op_sel_hi:[1,0,1]
	v_pk_mul_f32 v[50:51], v[48:49], v[40:41] op_sel:[0,0] op_sel_hi:[0,1]
	v_pk_fma_f32 v[52:53], v[48:49], v[40:41], v[50:51] op_sel:[1,1,0] op_sel_hi:[1,0,1] neg_lo:[0,1,0]
	ds_read2_b64 v[48:51], v134 offset0:136 offset1:153
	v_pk_mul_f32 v[68:69], v[54:55], v[52:53] op_sel:[0,0] op_sel_hi:[0,1] neg_hi:[0,1]
	v_pk_fma_f32 v[68:69], v[54:55], v[52:53], v[68:69] op_sel:[1,1,0] op_sel_hi:[1,0,1]
	v_pk_mul_f32 v[54:55], v[52:53], v[40:41] op_sel:[0,0] op_sel_hi:[0,1]
	v_pk_fma_f32 v[52:53], v[52:53], v[40:41], v[54:55] op_sel:[1,1,0] op_sel_hi:[1,0,1] neg_lo:[0,1,0]
	s_waitcnt lgkmcnt(0)
	v_pk_mul_f32 v[54:55], v[48:49], v[52:53] op_sel:[0,0] op_sel_hi:[0,1] neg_hi:[0,1]
	v_pk_fma_f32 v[70:71], v[48:49], v[52:53], v[54:55] op_sel:[1,1,0] op_sel_hi:[1,0,1]
	v_pk_mul_f32 v[48:49], v[52:53], v[40:41] op_sel:[0,0] op_sel_hi:[0,1]
	v_pk_fma_f32 v[48:49], v[52:53], v[40:41], v[48:49] op_sel:[1,1,0] op_sel_hi:[1,0,1] neg_lo:[0,1,0]
	ds_read2_b64 v[52:55], v134 offset0:170 offset1:187
	v_pk_mul_f32 v[72:73], v[50:51], v[48:49] op_sel:[0,0] op_sel_hi:[0,1] neg_hi:[0,1]
	v_pk_fma_f32 v[72:73], v[50:51], v[48:49], v[72:73] op_sel:[1,1,0] op_sel_hi:[1,0,1]
	v_pk_mul_f32 v[50:51], v[48:49], v[40:41] op_sel:[0,0] op_sel_hi:[0,1]
	v_pk_fma_f32 v[48:49], v[48:49], v[40:41], v[50:51] op_sel:[1,1,0] op_sel_hi:[1,0,1] neg_lo:[0,1,0]
	s_waitcnt lgkmcnt(0)
	v_pk_mul_f32 v[50:51], v[52:53], v[48:49] op_sel:[0,0] op_sel_hi:[0,1] neg_hi:[0,1]
	v_pk_fma_f32 v[74:75], v[52:53], v[48:49], v[50:51] op_sel:[1,1,0] op_sel_hi:[1,0,1]
	v_pk_mul_f32 v[50:51], v[48:49], v[40:41] op_sel:[0,0] op_sel_hi:[0,1]
	v_pk_fma_f32 v[52:53], v[48:49], v[40:41], v[50:51] op_sel:[1,1,0] op_sel_hi:[1,0,1] neg_lo:[0,1,0]
	ds_read2_b64 v[48:51], v134 offset0:204 offset1:221
	v_pk_mul_f32 v[76:77], v[54:55], v[52:53] op_sel:[0,0] op_sel_hi:[0,1] neg_hi:[0,1]
	v_pk_fma_f32 v[76:77], v[54:55], v[52:53], v[76:77] op_sel:[1,1,0] op_sel_hi:[1,0,1]
	v_pk_mul_f32 v[54:55], v[52:53], v[40:41] op_sel:[0,0] op_sel_hi:[0,1]
	v_pk_fma_f32 v[52:53], v[52:53], v[40:41], v[54:55] op_sel:[1,1,0] op_sel_hi:[1,0,1] neg_lo:[0,1,0]
	s_waitcnt lgkmcnt(0)
	v_pk_mul_f32 v[54:55], v[48:49], v[52:53] op_sel:[0,0] op_sel_hi:[0,1] neg_hi:[0,1]
	v_pk_fma_f32 v[48:49], v[48:49], v[52:53], v[54:55] op_sel:[1,1,0] op_sel_hi:[1,0,1]
	v_pk_mul_f32 v[54:55], v[52:53], v[40:41] op_sel:[0,0] op_sel_hi:[0,1]
	v_pk_fma_f32 v[78:79], v[52:53], v[40:41], v[54:55] op_sel:[1,1,0] op_sel_hi:[1,0,1] neg_lo:[0,1,0]
	ds_read2_b64 v[52:55], v134 offset0:238 offset1:255
	v_pk_mul_f32 v[80:81], v[50:51], v[78:79] op_sel:[0,0] op_sel_hi:[0,1] neg_hi:[0,1]
	v_pk_fma_f32 v[50:51], v[50:51], v[78:79], v[80:81] op_sel:[1,1,0] op_sel_hi:[1,0,1]
	v_pk_mul_f32 v[80:81], v[78:79], v[40:41] op_sel:[0,0] op_sel_hi:[0,1]
	v_pk_fma_f32 v[78:79], v[78:79], v[40:41], v[80:81] op_sel:[1,1,0] op_sel_hi:[1,0,1] neg_lo:[0,1,0]
	s_waitcnt lgkmcnt(0)
	v_pk_mul_f32 v[80:81], v[52:53], v[78:79] op_sel:[0,0] op_sel_hi:[0,1] neg_hi:[0,1]
	v_pk_fma_f32 v[52:53], v[52:53], v[78:79], v[80:81] op_sel:[1,1,0] op_sel_hi:[1,0,1]
	v_pk_mul_f32 v[80:81], v[78:79], v[40:41] op_sel:[0,0] op_sel_hi:[0,1]
	v_pk_fma_f32 v[40:41], v[78:79], v[40:41], v[80:81] op_sel:[1,1,0] op_sel_hi:[1,0,1] neg_lo:[0,1,0]
	v_pk_mul_f32 v[78:79], v[54:55], v[40:41] op_sel:[0,0] op_sel_hi:[0,1] neg_hi:[0,1]
	v_pk_fma_f32 v[40:41], v[54:55], v[40:41], v[78:79] op_sel:[1,1,0] op_sel_hi:[1,0,1]
	v_pk_add_f32 v[54:55], v[46:47], v[70:71]
	v_pk_add_f32 v[46:47], v[46:47], v[70:71] neg_lo:[0,1] neg_hi:[0,1]
	v_pk_add_f32 v[70:71], v[62:63], v[48:49]
	v_pk_add_f32 v[48:49], v[62:63], v[48:49] neg_lo:[0,1] neg_hi:[0,1]
	v_pk_add_f32 v[62:63], v[54:55], v[70:71]
	v_pk_add_f32 v[54:55], v[54:55], v[70:71] neg_lo:[0,1] neg_hi:[0,1]
	v_pk_add_f32 v[70:71], v[46:47], v[48:49] op_sel:[0,1] op_sel_hi:[1,0] neg_lo:[0,1]
	v_pk_add_f32 v[46:47], v[46:47], v[48:49] op_sel:[0,1] op_sel_hi:[1,0] neg_hi:[0,1]
	v_pk_add_f32 v[48:49], v[56:57], v[72:73]
	v_pk_add_f32 v[56:57], v[56:57], v[72:73] neg_lo:[0,1] neg_hi:[0,1]
	v_pk_add_f32 v[72:73], v[64:65], v[50:51]
	v_pk_add_f32 v[50:51], v[64:65], v[50:51] neg_lo:[0,1] neg_hi:[0,1]
	v_pk_add_f32 v[64:65], v[48:49], v[72:73]
	v_pk_add_f32 v[48:49], v[48:49], v[72:73] neg_lo:[0,1] neg_hi:[0,1]
	v_pk_add_f32 v[72:73], v[56:57], v[50:51] op_sel:[0,1] op_sel_hi:[1,0] neg_lo:[0,1]
	v_pk_add_f32 v[50:51], v[56:57], v[50:51] op_sel:[0,1] op_sel_hi:[1,0] neg_hi:[0,1]
	v_pk_add_f32 v[56:57], v[58:59], v[74:75]
	v_pk_add_f32 v[58:59], v[58:59], v[74:75] neg_lo:[0,1] neg_hi:[0,1]
	v_pk_add_f32 v[74:75], v[66:67], v[52:53]
	v_pk_add_f32 v[52:53], v[66:67], v[52:53] neg_lo:[0,1] neg_hi:[0,1]
	v_pk_add_f32 v[66:67], v[56:57], v[74:75]
	v_pk_add_f32 v[56:57], v[56:57], v[74:75] neg_lo:[0,1] neg_hi:[0,1]
	v_pk_add_f32 v[74:75], v[58:59], v[52:53] op_sel:[0,1] op_sel_hi:[1,0] neg_lo:[0,1]
	v_pk_add_f32 v[52:53], v[58:59], v[52:53] op_sel:[0,1] op_sel_hi:[1,0] neg_hi:[0,1]
	v_pk_add_f32 v[58:59], v[60:61], v[76:77]
	v_pk_add_f32 v[60:61], v[60:61], v[76:77] neg_lo:[0,1] neg_hi:[0,1]
	v_pk_add_f32 v[76:77], v[68:69], v[40:41]
	v_pk_add_f32 v[40:41], v[68:69], v[40:41] neg_lo:[0,1] neg_hi:[0,1]
	v_pk_add_f32 v[68:69], v[58:59], v[76:77]
	v_pk_add_f32 v[58:59], v[58:59], v[76:77] neg_lo:[0,1] neg_hi:[0,1]
	v_pk_add_f32 v[76:77], v[60:61], v[40:41] op_sel:[0,1] op_sel_hi:[1,0] neg_lo:[0,1]
	v_pk_add_f32 v[40:41], v[60:61], v[40:41] op_sel:[0,1] op_sel_hi:[1,0] neg_hi:[0,1]
	v_pk_mul_f32 v[60:61], v[72:73], v[32:33] op_sel:[0,0] op_sel_hi:[0,1]
	v_pk_fma_f32 v[60:61], v[72:73], v[32:33], v[60:61] op_sel:[1,1,0] op_sel_hi:[1,0,1] neg_lo:[0,1,0]
	v_pk_mul_f32 v[72:73], v[74:75], v[28:29] op_sel:[0,0] op_sel_hi:[0,1]
	v_pk_fma_f32 v[72:73], v[74:75], v[28:29], v[72:73] op_sel:[1,1,0] op_sel_hi:[1,0,1] neg_lo:[0,1,0]
	v_pk_mul_f32 v[74:75], v[76:77], v[26:27] op_sel:[0,0] op_sel_hi:[0,1]
	v_pk_fma_f32 v[74:75], v[76:77], v[26:27], v[74:75] op_sel:[1,1,0] op_sel_hi:[1,0,1] neg_lo:[0,1,0]
	v_pk_mul_f32 v[76:77], v[48:49], v[28:29] op_sel:[0,0] op_sel_hi:[0,1]
	v_pk_fma_f32 v[48:49], v[48:49], v[28:29], v[76:77] op_sel:[1,1,0] op_sel_hi:[1,0,1] neg_lo:[0,1,0]
	v_pk_mul_f32 v[76:77], v[56:57], v[42:43] op_sel:[0,0] op_sel_hi:[0,1]
	v_pk_fma_f32 v[56:57], v[56:57], v[42:43], v[76:77] op_sel:[1,1,0] op_sel_hi:[1,0,1] neg_lo:[0,1,0]
	v_pk_mul_f32 v[76:77], v[58:59], v[30:31] op_sel:[0,0] op_sel_hi:[0,1]
	v_pk_fma_f32 v[58:59], v[58:59], v[30:31], v[76:77] op_sel:[1,1,0] op_sel_hi:[1,0,1] neg_lo:[0,1,0]
	v_pk_mul_f32 v[76:77], v[50:51], v[26:27] op_sel:[0,0] op_sel_hi:[0,1]
	v_pk_fma_f32 v[50:51], v[50:51], v[26:27], v[76:77] op_sel:[1,1,0] op_sel_hi:[1,0,1] neg_lo:[0,1,0]
	v_pk_mul_f32 v[76:77], v[52:53], v[30:31] op_sel:[0,0] op_sel_hi:[0,1]
	v_pk_fma_f32 v[52:53], v[52:53], v[30:31], v[76:77] op_sel:[1,1,0] op_sel_hi:[1,0,1] neg_lo:[0,1,0]
	v_pk_mul_f32 v[76:77], v[40:41], v[44:45] op_sel:[0,0] op_sel_hi:[0,1]
	v_pk_fma_f32 v[40:41], v[40:41], v[44:45], v[76:77] op_sel:[1,1,0] op_sel_hi:[1,0,1] neg_lo:[0,1,0]
	v_pk_add_f32 v[76:77], v[62:63], v[66:67]
	v_pk_add_f32 v[62:63], v[62:63], v[66:67] neg_lo:[0,1] neg_hi:[0,1]
	v_pk_add_f32 v[66:67], v[64:65], v[68:69]
	v_pk_add_f32 v[64:65], v[64:65], v[68:69] neg_lo:[0,1] neg_hi:[0,1]
	v_pk_add_f32 v[68:69], v[76:77], v[66:67]
	v_pk_add_f32 v[66:67], v[76:77], v[66:67] neg_lo:[0,1] neg_hi:[0,1]
	v_pk_add_f32 v[76:77], v[62:63], v[64:65] op_sel:[0,1] op_sel_hi:[1,0] neg_lo:[0,1]
	v_pk_add_f32 v[62:63], v[62:63], v[64:65] op_sel:[0,1] op_sel_hi:[1,0] neg_hi:[0,1]
	v_pk_add_f32 v[64:65], v[70:71], v[72:73]
	v_pk_add_f32 v[70:71], v[70:71], v[72:73] neg_lo:[0,1] neg_hi:[0,1]
	v_pk_add_f32 v[72:73], v[60:61], v[74:75]
	v_pk_add_f32 v[60:61], v[60:61], v[74:75] neg_lo:[0,1] neg_hi:[0,1]
	v_pk_add_f32 v[74:75], v[64:65], v[72:73]
	v_pk_add_f32 v[64:65], v[64:65], v[72:73] neg_lo:[0,1] neg_hi:[0,1]
	v_pk_add_f32 v[72:73], v[70:71], v[60:61] op_sel:[0,1] op_sel_hi:[1,0] neg_lo:[0,1]
	v_pk_add_f32 v[60:61], v[70:71], v[60:61] op_sel:[0,1] op_sel_hi:[1,0] neg_hi:[0,1]
	v_pk_add_f32 v[70:71], v[54:55], v[56:57]
	v_pk_add_f32 v[54:55], v[54:55], v[56:57] neg_lo:[0,1] neg_hi:[0,1]
	v_pk_add_f32 v[56:57], v[48:49], v[58:59]
	v_pk_add_f32 v[48:49], v[48:49], v[58:59] neg_lo:[0,1] neg_hi:[0,1]
	v_pk_add_f32 v[58:59], v[70:71], v[56:57]
	v_pk_add_f32 v[56:57], v[70:71], v[56:57] neg_lo:[0,1] neg_hi:[0,1]
	v_pk_add_f32 v[70:71], v[54:55], v[48:49] op_sel:[0,1] op_sel_hi:[1,0] neg_lo:[0,1]
	v_pk_add_f32 v[48:49], v[54:55], v[48:49] op_sel:[0,1] op_sel_hi:[1,0] neg_hi:[0,1]
	v_pk_add_f32 v[54:55], v[46:47], v[52:53]
	v_pk_add_f32 v[46:47], v[46:47], v[52:53] neg_lo:[0,1] neg_hi:[0,1]
	v_pk_add_f32 v[52:53], v[50:51], v[40:41]
	v_pk_add_f32 v[40:41], v[50:51], v[40:41] neg_lo:[0,1] neg_hi:[0,1]
	v_pk_add_f32 v[50:51], v[54:55], v[52:53]
	v_pk_add_f32 v[52:53], v[54:55], v[52:53] neg_lo:[0,1] neg_hi:[0,1]
	v_pk_add_f32 v[54:55], v[46:47], v[40:41] op_sel:[0,1] op_sel_hi:[1,0] neg_lo:[0,1]
	v_pk_add_f32 v[40:41], v[46:47], v[40:41] op_sel:[0,1] op_sel_hi:[1,0] neg_hi:[0,1]
	ds_write2_b64 v134, v[68:69], v[74:75] offset1:17
	ds_write2_b64 v134, v[58:59], v[50:51] offset0:34 offset1:51
	ds_write2_b64 v134, v[76:77], v[72:73] offset0:68 offset1:85
	ds_write2_b64 v134, v[70:71], v[54:55] offset0:102 offset1:119
	ds_write2_b64 v134, v[66:67], v[64:65] offset0:136 offset1:153
	ds_write2_b64 v134, v[56:57], v[52:53] offset0:170 offset1:187
	ds_write2_b64 v134, v[62:63], v[60:61] offset0:204 offset1:221
	ds_write2_b64 v134, v[48:49], v[40:41] offset0:238 offset1:255
	s_waitcnt lgkmcnt(0)
	s_barrier
	ds_read_b64 v[40:41], v132 offset:2176
	ds_read_b64 v[46:47], v132 offset:4352
	ds_read_b64 v[48:49], v132 offset:6528
	ds_read_b64 v[50:51], v132
	s_waitcnt lgkmcnt(3)
	v_pk_mul_f32 v[52:53], v[40:41], v[38:39] op_sel:[0,0] op_sel_hi:[0,1] neg_hi:[0,1]
	v_pk_fma_f32 v[40:41], v[40:41], v[38:39], v[52:53] op_sel:[1,1,0] op_sel_hi:[1,0,1]
	v_pk_mul_f32 v[52:53], v[38:39], v[38:39] op_sel:[0,0] op_sel_hi:[0,1]
	ds_read_b64 v[56:57], v132 offset:8704
	v_pk_fma_f32 v[52:53], v[38:39], v[38:39], v[52:53] op_sel:[1,1,0] op_sel_hi:[1,0,1] neg_lo:[0,1,0]
	s_waitcnt lgkmcnt(3)
	v_pk_mul_f32 v[54:55], v[46:47], v[52:53] op_sel:[0,0] op_sel_hi:[0,1] neg_hi:[0,1]
	v_pk_fma_f32 v[46:47], v[46:47], v[52:53], v[54:55] op_sel:[1,1,0] op_sel_hi:[1,0,1]
	v_pk_mul_f32 v[54:55], v[52:53], v[38:39] op_sel:[0,0] op_sel_hi:[0,1]
	v_pk_fma_f32 v[52:53], v[52:53], v[38:39], v[54:55] op_sel:[1,1,0] op_sel_hi:[1,0,1] neg_lo:[0,1,0]
	s_waitcnt lgkmcnt(2)
	v_pk_mul_f32 v[54:55], v[48:49], v[52:53] op_sel:[0,0] op_sel_hi:[0,1] neg_hi:[0,1]
	v_pk_fma_f32 v[48:49], v[48:49], v[52:53], v[54:55] op_sel:[1,1,0] op_sel_hi:[1,0,1]
	v_pk_mul_f32 v[54:55], v[52:53], v[38:39] op_sel:[0,0] op_sel_hi:[0,1]
	v_pk_fma_f32 v[52:53], v[52:53], v[38:39], v[54:55] op_sel:[1,1,0] op_sel_hi:[1,0,1] neg_lo:[0,1,0]
	ds_read_b64 v[54:55], v132 offset:10880
	ds_read_b64 v[58:59], v132 offset:13056
	ds_read_b64 v[60:61], v132 offset:15232
	s_waitcnt lgkmcnt(3)
	v_pk_mul_f32 v[62:63], v[56:57], v[52:53] op_sel:[0,0] op_sel_hi:[0,1] neg_hi:[0,1]
	ds_read_b64 v[64:65], v132 offset:17408
	v_pk_fma_f32 v[56:57], v[56:57], v[52:53], v[62:63] op_sel:[1,1,0] op_sel_hi:[1,0,1]
	v_pk_mul_f32 v[62:63], v[52:53], v[38:39] op_sel:[0,0] op_sel_hi:[0,1]
	v_pk_fma_f32 v[52:53], v[52:53], v[38:39], v[62:63] op_sel:[1,1,0] op_sel_hi:[1,0,1] neg_lo:[0,1,0]
	s_waitcnt lgkmcnt(3)
	v_pk_mul_f32 v[62:63], v[54:55], v[52:53] op_sel:[0,0] op_sel_hi:[0,1] neg_hi:[0,1]
	v_pk_fma_f32 v[54:55], v[54:55], v[52:53], v[62:63] op_sel:[1,1,0] op_sel_hi:[1,0,1]
	v_pk_mul_f32 v[62:63], v[52:53], v[38:39] op_sel:[0,0] op_sel_hi:[0,1]
	v_pk_fma_f32 v[52:53], v[52:53], v[38:39], v[62:63] op_sel:[1,1,0] op_sel_hi:[1,0,1] neg_lo:[0,1,0]
	s_waitcnt lgkmcnt(2)
	v_pk_mul_f32 v[62:63], v[58:59], v[52:53] op_sel:[0,0] op_sel_hi:[0,1] neg_hi:[0,1]
	v_pk_fma_f32 v[58:59], v[58:59], v[52:53], v[62:63] op_sel:[1,1,0] op_sel_hi:[1,0,1]
	v_pk_mul_f32 v[62:63], v[52:53], v[38:39] op_sel:[0,0] op_sel_hi:[0,1]
	v_pk_fma_f32 v[52:53], v[52:53], v[38:39], v[62:63] op_sel:[1,1,0] op_sel_hi:[1,0,1] neg_lo:[0,1,0]
	s_waitcnt lgkmcnt(1)
	v_pk_mul_f32 v[62:63], v[60:61], v[52:53] op_sel:[0,0] op_sel_hi:[0,1] neg_hi:[0,1]
	v_pk_fma_f32 v[60:61], v[60:61], v[52:53], v[62:63] op_sel:[1,1,0] op_sel_hi:[1,0,1]
	v_pk_mul_f32 v[62:63], v[52:53], v[38:39] op_sel:[0,0] op_sel_hi:[0,1]
	v_pk_fma_f32 v[52:53], v[52:53], v[38:39], v[62:63] op_sel:[1,1,0] op_sel_hi:[1,0,1] neg_lo:[0,1,0]
	ds_read_b64 v[62:63], v132 offset:19584
	ds_read_b64 v[66:67], v132 offset:21760
	ds_read_b64 v[68:69], v132 offset:23936
	s_waitcnt lgkmcnt(3)
	v_pk_mul_f32 v[70:71], v[64:65], v[52:53] op_sel:[0,0] op_sel_hi:[0,1] neg_hi:[0,1]
	ds_read_b64 v[72:73], v132 offset:26112
	v_pk_fma_f32 v[64:65], v[64:65], v[52:53], v[70:71] op_sel:[1,1,0] op_sel_hi:[1,0,1]
	v_pk_mul_f32 v[70:71], v[52:53], v[38:39] op_sel:[0,0] op_sel_hi:[0,1]
	v_pk_fma_f32 v[52:53], v[52:53], v[38:39], v[70:71] op_sel:[1,1,0] op_sel_hi:[1,0,1] neg_lo:[0,1,0]
	s_waitcnt lgkmcnt(3)
	v_pk_mul_f32 v[70:71], v[62:63], v[52:53] op_sel:[0,0] op_sel_hi:[0,1] neg_hi:[0,1]
	v_pk_fma_f32 v[62:63], v[62:63], v[52:53], v[70:71] op_sel:[1,1,0] op_sel_hi:[1,0,1]
	v_pk_mul_f32 v[70:71], v[52:53], v[38:39] op_sel:[0,0] op_sel_hi:[0,1]
	v_pk_fma_f32 v[52:53], v[52:53], v[38:39], v[70:71] op_sel:[1,1,0] op_sel_hi:[1,0,1] neg_lo:[0,1,0]
	s_waitcnt lgkmcnt(2)
	v_pk_mul_f32 v[70:71], v[66:67], v[52:53] op_sel:[0,0] op_sel_hi:[0,1] neg_hi:[0,1]
	v_pk_fma_f32 v[66:67], v[66:67], v[52:53], v[70:71] op_sel:[1,1,0] op_sel_hi:[1,0,1]
	v_pk_mul_f32 v[70:71], v[52:53], v[38:39] op_sel:[0,0] op_sel_hi:[0,1]
	v_pk_fma_f32 v[52:53], v[52:53], v[38:39], v[70:71] op_sel:[1,1,0] op_sel_hi:[1,0,1] neg_lo:[0,1,0]
	s_waitcnt lgkmcnt(1)
	v_pk_mul_f32 v[70:71], v[68:69], v[52:53] op_sel:[0,0] op_sel_hi:[0,1] neg_hi:[0,1]
	v_pk_fma_f32 v[68:69], v[68:69], v[52:53], v[70:71] op_sel:[1,1,0] op_sel_hi:[1,0,1]
	v_pk_mul_f32 v[70:71], v[52:53], v[38:39] op_sel:[0,0] op_sel_hi:[0,1]
	v_pk_fma_f32 v[52:53], v[52:53], v[38:39], v[70:71] op_sel:[1,1,0] op_sel_hi:[1,0,1] neg_lo:[0,1,0]
	ds_read_b64 v[70:71], v132 offset:28288
	ds_read_b64 v[74:75], v132 offset:30464
	ds_read_b64 v[76:77], v132 offset:32640
	s_waitcnt lgkmcnt(3)
	v_pk_mul_f32 v[78:79], v[72:73], v[52:53] op_sel:[0,0] op_sel_hi:[0,1] neg_hi:[0,1]
	s_nop 0
	v_pk_fma_f32 v[72:73], v[72:73], v[52:53], v[78:79] op_sel:[1,1,0] op_sel_hi:[1,0,1]
	v_pk_mul_f32 v[78:79], v[52:53], v[38:39] op_sel:[0,0] op_sel_hi:[0,1]
	v_pk_fma_f32 v[52:53], v[52:53], v[38:39], v[78:79] op_sel:[1,1,0] op_sel_hi:[1,0,1] neg_lo:[0,1,0]
	s_waitcnt lgkmcnt(2)
	v_pk_mul_f32 v[78:79], v[70:71], v[52:53] op_sel:[0,0] op_sel_hi:[0,1] neg_hi:[0,1]
	v_pk_fma_f32 v[70:71], v[70:71], v[52:53], v[78:79] op_sel:[1,1,0] op_sel_hi:[1,0,1]
	v_pk_mul_f32 v[78:79], v[52:53], v[38:39] op_sel:[0,0] op_sel_hi:[0,1]
	v_pk_fma_f32 v[52:53], v[52:53], v[38:39], v[78:79] op_sel:[1,1,0] op_sel_hi:[1,0,1] neg_lo:[0,1,0]
	s_waitcnt lgkmcnt(1)
	v_pk_mul_f32 v[78:79], v[74:75], v[52:53] op_sel:[0,0] op_sel_hi:[0,1] neg_hi:[0,1]
	v_pk_fma_f32 v[74:75], v[74:75], v[52:53], v[78:79] op_sel:[1,1,0] op_sel_hi:[1,0,1]
	v_pk_mul_f32 v[78:79], v[52:53], v[38:39] op_sel:[0,0] op_sel_hi:[0,1]
	v_pk_fma_f32 v[38:39], v[52:53], v[38:39], v[78:79] op_sel:[1,1,0] op_sel_hi:[1,0,1] neg_lo:[0,1,0]
	s_waitcnt lgkmcnt(0)
	v_pk_mul_f32 v[52:53], v[76:77], v[38:39] op_sel:[0,0] op_sel_hi:[0,1] neg_hi:[0,1]
	v_pk_fma_f32 v[38:39], v[76:77], v[38:39], v[52:53] op_sel:[1,1,0] op_sel_hi:[1,0,1]
	v_pk_add_f32 v[52:53], v[50:51], v[64:65]
	v_pk_add_f32 v[50:51], v[50:51], v[64:65] neg_lo:[0,1] neg_hi:[0,1]
	v_pk_add_f32 v[64:65], v[56:57], v[72:73]
	v_pk_add_f32 v[56:57], v[56:57], v[72:73] neg_lo:[0,1] neg_hi:[0,1]
	v_pk_add_f32 v[72:73], v[52:53], v[64:65]
	v_pk_add_f32 v[76:77], v[50:51], v[56:57] op_sel:[0,1] op_sel_hi:[1,0] neg_lo:[0,1]
	v_pk_add_f32 v[78:79], v[50:51], v[56:57] op_sel:[0,1] op_sel_hi:[1,0] neg_hi:[0,1]
	v_pk_add_f32 v[50:51], v[40:41], v[62:63]
	v_pk_add_f32 v[40:41], v[40:41], v[62:63] neg_lo:[0,1] neg_hi:[0,1]
	v_pk_add_f32 v[56:57], v[54:55], v[70:71]
	v_pk_add_f32 v[54:55], v[54:55], v[70:71] neg_lo:[0,1] neg_hi:[0,1]
	v_pk_add_f32 v[52:53], v[52:53], v[64:65] neg_lo:[0,1] neg_hi:[0,1]
	v_pk_add_f32 v[62:63], v[50:51], v[56:57]
	v_pk_add_f32 v[50:51], v[50:51], v[56:57] neg_lo:[0,1] neg_hi:[0,1]
	v_pk_add_f32 v[56:57], v[40:41], v[54:55] op_sel:[0,1] op_sel_hi:[1,0] neg_lo:[0,1]
	v_pk_add_f32 v[40:41], v[40:41], v[54:55] op_sel:[0,1] op_sel_hi:[1,0] neg_hi:[0,1]
	v_pk_add_f32 v[54:55], v[46:47], v[66:67]
	v_pk_add_f32 v[46:47], v[46:47], v[66:67] neg_lo:[0,1] neg_hi:[0,1]
	v_pk_add_f32 v[64:65], v[58:59], v[74:75]
	v_pk_add_f32 v[58:59], v[58:59], v[74:75] neg_lo:[0,1] neg_hi:[0,1]
	v_pk_add_f32 v[66:67], v[54:55], v[64:65]
	v_pk_add_f32 v[54:55], v[54:55], v[64:65] neg_lo:[0,1] neg_hi:[0,1]
	v_pk_add_f32 v[64:65], v[46:47], v[58:59] op_sel:[0,1] op_sel_hi:[1,0] neg_lo:[0,1]
	v_pk_add_f32 v[46:47], v[46:47], v[58:59] op_sel:[0,1] op_sel_hi:[1,0] neg_hi:[0,1]
	v_pk_add_f32 v[58:59], v[48:49], v[68:69]
	v_pk_add_f32 v[48:49], v[48:49], v[68:69] neg_lo:[0,1] neg_hi:[0,1]
	v_pk_add_f32 v[68:69], v[60:61], v[38:39]
	v_pk_add_f32 v[38:39], v[60:61], v[38:39] neg_lo:[0,1] neg_hi:[0,1]
	v_pk_add_f32 v[60:61], v[58:59], v[68:69]
	v_pk_add_f32 v[58:59], v[58:59], v[68:69] neg_lo:[0,1] neg_hi:[0,1]
	v_pk_add_f32 v[68:69], v[48:49], v[38:39] op_sel:[0,1] op_sel_hi:[1,0] neg_lo:[0,1]
	v_pk_add_f32 v[38:39], v[48:49], v[38:39] op_sel:[0,1] op_sel_hi:[1,0] neg_hi:[0,1]
	v_pk_mul_f32 v[48:49], v[56:57], v[32:33] op_sel:[0,0] op_sel_hi:[0,1]
	v_pk_fma_f32 v[32:33], v[56:57], v[32:33], v[48:49] op_sel:[1,1,0] op_sel_hi:[1,0,1] neg_lo:[0,1,0]
	v_pk_mul_f32 v[48:49], v[64:65], v[28:29] op_sel:[0,0] op_sel_hi:[0,1]
	v_pk_mul_f32 v[56:57], v[68:69], v[26:27] op_sel:[0,0] op_sel_hi:[0,1]
	v_pk_fma_f32 v[48:49], v[64:65], v[28:29], v[48:49] op_sel:[1,1,0] op_sel_hi:[1,0,1] neg_lo:[0,1,0]
	v_pk_fma_f32 v[56:57], v[68:69], v[26:27], v[56:57] op_sel:[1,1,0] op_sel_hi:[1,0,1] neg_lo:[0,1,0]
	v_pk_mul_f32 v[64:65], v[50:51], v[28:29] op_sel:[0,0] op_sel_hi:[0,1]
	v_pk_fma_f32 v[68:69], v[50:51], v[28:29], v[64:65] op_sel:[1,1,0] op_sel_hi:[1,0,1] neg_lo:[0,1,0]
	v_pk_mul_f32 v[28:29], v[54:55], v[42:43] op_sel:[0,0] op_sel_hi:[0,1]
	v_pk_fma_f32 v[54:55], v[54:55], v[42:43], v[28:29] op_sel:[1,1,0] op_sel_hi:[1,0,1] neg_lo:[0,1,0]
	v_pk_mul_f32 v[28:29], v[58:59], v[30:31] op_sel:[0,0] op_sel_hi:[0,1]
	v_pk_add_f32 v[42:43], v[62:63], v[60:61]
	v_pk_fma_f32 v[58:59], v[58:59], v[30:31], v[28:29] op_sel:[1,1,0] op_sel_hi:[1,0,1] neg_lo:[0,1,0]
	v_pk_mul_f32 v[28:29], v[40:41], v[26:27] op_sel:[0,0] op_sel_hi:[0,1]
	v_pk_add_f32 v[50:51], v[52:53], v[54:55]
	v_pk_fma_f32 v[70:71], v[40:41], v[26:27], v[28:29] op_sel:[1,1,0] op_sel_hi:[1,0,1] neg_lo:[0,1,0]
	v_pk_mul_f32 v[26:27], v[46:47], v[30:31] op_sel:[0,0] op_sel_hi:[0,1]
	v_pk_add_f32 v[28:29], v[62:63], v[60:61] neg_lo:[0,1] neg_hi:[0,1]
	v_pk_fma_f32 v[74:75], v[46:47], v[30:31], v[26:27] op_sel:[1,1,0] op_sel_hi:[1,0,1] neg_lo:[0,1,0]
	v_pk_mul_f32 v[26:27], v[38:39], v[44:45] op_sel:[0,0] op_sel_hi:[0,1]
	v_pk_add_f32 v[30:31], v[32:33], v[56:57] neg_lo:[0,1] neg_hi:[0,1]
	v_pk_fma_f32 v[80:81], v[38:39], v[44:45], v[26:27] op_sel:[1,1,0] op_sel_hi:[1,0,1] neg_lo:[0,1,0]
	v_pk_add_f32 v[26:27], v[72:73], v[66:67] neg_lo:[0,1] neg_hi:[0,1]
	v_pk_add_f32 v[38:39], v[72:73], v[66:67]
	v_pk_add_f32 v[40:41], v[26:27], v[28:29] op_sel:[0,1] op_sel_hi:[1,0] neg_lo:[0,1]
	v_pk_add_f32 v[26:27], v[26:27], v[28:29] op_sel:[0,1] op_sel_hi:[1,0] neg_hi:[0,1]
	v_pk_add_f32 v[28:29], v[76:77], v[48:49] neg_lo:[0,1] neg_hi:[0,1]
	v_pk_add_f32 v[44:45], v[76:77], v[48:49]
	v_pk_add_f32 v[48:49], v[32:33], v[56:57]
	v_pk_add_f32 v[46:47], v[28:29], v[30:31] op_sel:[0,1] op_sel_hi:[1,0] neg_lo:[0,1]
	v_pk_add_f32 v[28:29], v[28:29], v[30:31] op_sel:[0,1] op_sel_hi:[1,0] neg_hi:[0,1]
	v_pk_add_f32 v[30:31], v[52:53], v[54:55] neg_lo:[0,1] neg_hi:[0,1]
	v_pk_add_f32 v[54:55], v[68:69], v[58:59]
	v_pk_add_f32 v[32:33], v[68:69], v[58:59] neg_lo:[0,1] neg_hi:[0,1]
	v_pk_add_f32 v[56:57], v[78:79], v[74:75]
	v_pk_add_f32 v[60:61], v[70:71], v[80:81]
	v_pk_add_f32 v[64:65], v[38:39], v[42:43]
	v_pk_add_f32 v[66:67], v[44:45], v[48:49]
	v_pk_add_f32 v[68:69], v[50:51], v[54:55]
	v_pk_add_f32 v[52:53], v[30:31], v[32:33] op_sel:[0,1] op_sel_hi:[1,0] neg_lo:[0,1]
	v_pk_add_f32 v[30:31], v[30:31], v[32:33] op_sel:[0,1] op_sel_hi:[1,0] neg_hi:[0,1]
	v_pk_add_f32 v[32:33], v[78:79], v[74:75] neg_lo:[0,1] neg_hi:[0,1]
	v_pk_add_f32 v[62:63], v[56:57], v[60:61]
	v_pk_add_f32 v[70:71], v[70:71], v[80:81] neg_lo:[0,1] neg_hi:[0,1]
	s_nop 0
	v_pk_add_f32 v[58:59], v[32:33], v[70:71] op_sel:[0,1] op_sel_hi:[1,0] neg_lo:[0,1]
	v_pk_add_f32 v[32:33], v[32:33], v[70:71] op_sel:[0,1] op_sel_hi:[1,0] neg_hi:[0,1]
	s_and_saveexec_b64 s[0:1], s[4:5]
	s_xor_b64 s[0:1], exec, s[0:1]
	s_cbranch_execz .LBB0_3488
	v_mov_b64_e32 v[70:71], s[12:13]
	v_pk_mul_f32 v[72:73], v[36:37], v[70:71] op_sel:[0,0] op_sel_hi:[0,1]
	v_pk_fma_f32 v[70:71], v[36:37], v[70:71], v[72:73] op_sel:[1,1,0] op_sel_hi:[1,0,1] neg_lo:[0,1,0]
	v_pk_mul_f32 v[72:73], v[64:65], v[70:71] op_sel:[0,0] op_sel_hi:[0,1] neg_hi:[0,1]
	v_pk_fma_f32 v[64:65], v[64:65], v[70:71], v[72:73] op_sel:[1,1,0] op_sel_hi:[1,0,1]
	v_mov_b64_e32 v[70:71], s[16:17]
	v_pk_mul_f32 v[72:73], v[36:37], v[70:71] op_sel:[0,0] op_sel_hi:[0,1]
	v_pk_fma_f32 v[70:71], v[36:37], v[70:71], v[72:73] op_sel:[1,1,0] op_sel_hi:[1,0,1] neg_lo:[0,1,0]
	v_pk_mul_f32 v[72:73], v[66:67], v[70:71] op_sel:[0,0] op_sel_hi:[0,1] neg_hi:[0,1]
	v_pk_fma_f32 v[66:67], v[66:67], v[70:71], v[72:73] op_sel:[1,1,0] op_sel_hi:[1,0,1]
	v_mov_b64_e32 v[70:71], s[20:21]
	v_pk_mul_f32 v[72:73], v[36:37], v[70:71] op_sel:[0,0] op_sel_hi:[0,1]
	v_pk_fma_f32 v[70:71], v[36:37], v[70:71], v[72:73] op_sel:[1,1,0] op_sel_hi:[1,0,1] neg_lo:[0,1,0]
	v_pk_mul_f32 v[72:73], v[68:69], v[70:71] op_sel:[0,0] op_sel_hi:[0,1] neg_hi:[0,1]
	v_pk_fma_f32 v[68:69], v[68:69], v[70:71], v[72:73] op_sel:[1,1,0] op_sel_hi:[1,0,1]
	v_mov_b64_e32 v[70:71], s[22:23]
	v_pk_mul_f32 v[72:73], v[36:37], v[70:71] op_sel:[0,0] op_sel_hi:[0,1]
	v_pk_fma_f32 v[70:71], v[36:37], v[70:71], v[72:73] op_sel:[1,1,0] op_sel_hi:[1,0,1] neg_lo:[0,1,0]
	v_pk_mul_f32 v[72:73], v[62:63], v[70:71] op_sel:[0,0] op_sel_hi:[0,1] neg_hi:[0,1]
	v_pk_fma_f32 v[62:63], v[62:63], v[70:71], v[72:73] op_sel:[1,1,0] op_sel_hi:[1,0,1]
	ds_write_b64 v132, v[64:65]
	ds_write_b64 v132, v[66:67] offset:2176
	ds_write_b64 v132, v[68:69] offset:4352
	ds_write_b64 v132, v[62:63] offset:6528
	v_mov_b64_e32 v[62:63], s[46:47]
	v_pk_mul_f32 v[64:65], v[36:37], v[62:63] op_sel:[0,0] op_sel_hi:[0,1]
	s_nop 0
	v_pk_fma_f32 v[62:63], v[36:37], v[62:63], v[64:65] op_sel:[1,1,0] op_sel_hi:[1,0,1] neg_lo:[0,1,0]
	v_pk_mul_f32 v[64:65], v[40:41], v[62:63] op_sel:[0,0] op_sel_hi:[0,1] neg_hi:[0,1]
	v_pk_fma_f32 v[40:41], v[40:41], v[62:63], v[64:65] op_sel:[1,1,0] op_sel_hi:[1,0,1]
	v_mov_b64_e32 v[62:63], s[48:49]
	v_pk_mul_f32 v[64:65], v[36:37], v[62:63] op_sel:[0,0] op_sel_hi:[0,1]
	v_pk_fma_f32 v[62:63], v[36:37], v[62:63], v[64:65] op_sel:[1,1,0] op_sel_hi:[1,0,1] neg_lo:[0,1,0]
	v_pk_mul_f32 v[64:65], v[46:47], v[62:63] op_sel:[0,0] op_sel_hi:[0,1] neg_hi:[0,1]
	v_pk_fma_f32 v[46:47], v[46:47], v[62:63], v[64:65] op_sel:[1,1,0] op_sel_hi:[1,0,1]
	v_mov_b64_e32 v[62:63], s[50:51]
	v_pk_mul_f32 v[64:65], v[36:37], v[62:63] op_sel:[0,0] op_sel_hi:[0,1]
	v_pk_fma_f32 v[62:63], v[36:37], v[62:63], v[64:65] op_sel:[1,1,0] op_sel_hi:[1,0,1] neg_lo:[0,1,0]
	v_pk_mul_f32 v[64:65], v[52:53], v[62:63] op_sel:[0,0] op_sel_hi:[0,1] neg_hi:[0,1]
	v_pk_fma_f32 v[52:53], v[52:53], v[62:63], v[64:65] op_sel:[1,1,0] op_sel_hi:[1,0,1]
	v_mov_b64_e32 v[62:63], s[52:53]
	v_pk_mul_f32 v[64:65], v[36:37], v[62:63] op_sel:[0,0] op_sel_hi:[0,1]
	v_pk_fma_f32 v[62:63], v[36:37], v[62:63], v[64:65] op_sel:[1,1,0] op_sel_hi:[1,0,1] neg_lo:[0,1,0]
	v_pk_mul_f32 v[64:65], v[58:59], v[62:63] op_sel:[0,0] op_sel_hi:[0,1] neg_hi:[0,1]
	s_nop 0
	v_pk_fma_f32 v[58:59], v[58:59], v[62:63], v[64:65] op_sel:[1,1,0] op_sel_hi:[1,0,1]

.LBB0_3490:
	s_or_b64 exec, exec, s[0:1]
	v_pk_add_f32 v[62:63], v[38:39], v[42:43] neg_lo:[0,1] neg_hi:[0,1]
	v_pk_add_f32 v[44:45], v[44:45], v[48:49] neg_lo:[0,1] neg_hi:[0,1]
	v_pk_add_f32 v[42:43], v[50:51], v[54:55] neg_lo:[0,1] neg_hi:[0,1]
	v_pk_add_f32 v[38:39], v[56:57], v[60:61] neg_lo:[0,1] neg_hi:[0,1]
	ds_write_b64 v132, v[40:41] offset:8704
	ds_write_b64 v132, v[46:47] offset:10880
	ds_write_b64 v132, v[52:53] offset:13056
	ds_write_b64 v132, v[58:59] offset:15232
	s_and_saveexec_b64 s[0:1], s[4:5]
	s_xor_b64 s[0:1], exec, s[0:1]
	s_cbranch_execz .LBB0_3492
	v_mov_b64_e32 v[40:41], s[8:9]
	v_pk_mul_f32 v[46:47], v[36:37], v[40:41] op_sel:[0,0] op_sel_hi:[0,1]
	s_mov_b32 s15, s53
	v_pk_fma_f32 v[40:41], v[36:37], v[40:41], v[46:47] op_sel:[1,1,0] op_sel_hi:[1,0,1] neg_lo:[0,1,0]
	s_mov_b32 s4, s23
	v_pk_mul_f32 v[46:47], v[62:63], v[40:41] op_sel:[0,0] op_sel_hi:[0,1] neg_hi:[0,1]
	s_mov_b32 s5, s49
	v_pk_fma_f32 v[40:41], v[62:63], v[40:41], v[46:47] op_sel:[1,1,0] op_sel_hi:[1,0,1]
	v_mov_b64_e32 v[46:47], s[14:15]
	v_pk_mul_f32 v[48:49], v[36:37], v[46:47] op_sel:[0,0] op_sel_hi:[0,1]
	s_nop 0
	v_pk_fma_f32 v[46:47], v[36:37], v[46:47], v[48:49] op_sel:[1,1,0] op_sel_hi:[1,0,1] neg_lo:[0,1,0]
	v_pk_mul_f32 v[48:49], v[44:45], v[46:47] op_sel:[0,0] op_sel_hi:[0,1] neg_hi:[0,1]
	v_pk_fma_f32 v[44:45], v[44:45], v[46:47], v[48:49] op_sel:[1,1,0] op_sel_hi:[1,0,1]
	v_mov_b64_e32 v[46:47], s[18:19]
	v_pk_mul_f32 v[48:49], v[36:37], v[46:47] op_sel:[0,0] op_sel_hi:[0,1]
	v_pk_fma_f32 v[46:47], v[36:37], v[46:47], v[48:49] op_sel:[1,1,0] op_sel_hi:[1,0,1] neg_lo:[0,1,0]
	v_pk_mul_f32 v[48:49], v[42:43], v[46:47] op_sel:[0,0] op_sel_hi:[0,1] neg_hi:[0,1]
	v_pk_fma_f32 v[42:43], v[42:43], v[46:47], v[48:49] op_sel:[1,1,0] op_sel_hi:[1,0,1]
	v_mov_b64_e32 v[46:47], s[4:5]
	v_pk_mul_f32 v[48:49], v[36:37], v[46:47] op_sel:[0,0] op_sel_hi:[0,1]
	s_mov_b32 s4, s49
	v_pk_fma_f32 v[46:47], v[36:37], v[46:47], v[48:49] op_sel:[1,1,0] op_sel_hi:[1,0,1] neg_lo:[0,1,0]
	s_mov_b32 s5, s23
	v_pk_mul_f32 v[48:49], v[38:39], v[46:47] op_sel:[0,0] op_sel_hi:[0,1] neg_hi:[0,1]
	v_pk_fma_f32 v[38:39], v[38:39], v[46:47], v[48:49] op_sel:[1,1,0] op_sel_hi:[1,0,1]
	ds_write_b64 v132, v[40:41] offset:17408
	ds_write_b64 v132, v[44:45] offset:19584
	ds_write_b64 v132, v[42:43] offset:21760
	ds_write_b64 v132, v[38:39] offset:23936
	v_mov_b64_e32 v[38:39], s[54:55]
	v_pk_mul_f32 v[40:41], v[36:37], v[38:39] op_sel:[0,0] op_sel_hi:[0,1]
	s_nop 0
	v_pk_fma_f32 v[38:39], v[36:37], v[38:39], v[40:41] op_sel:[1,1,0] op_sel_hi:[1,0,1] neg_lo:[0,1,0]
	v_pk_mul_f32 v[40:41], v[26:27], v[38:39] op_sel:[0,0] op_sel_hi:[0,1] neg_hi:[0,1]
	v_pk_fma_f32 v[26:27], v[26:27], v[38:39], v[40:41] op_sel:[1,1,0] op_sel_hi:[1,0,1]
	v_mov_b64_e32 v[38:39], s[4:5]
	v_pk_mul_f32 v[40:41], v[36:37], v[38:39] op_sel:[0,0] op_sel_hi:[0,1]
	s_mov_b32 s4, s53
	v_pk_fma_f32 v[38:39], v[36:37], v[38:39], v[40:41] op_sel:[1,1,0] op_sel_hi:[1,0,1] neg_lo:[0,1,0]
	s_mov_b32 s5, s14
	v_pk_mul_f32 v[40:41], v[28:29], v[38:39] op_sel:[0,0] op_sel_hi:[0,1] neg_hi:[0,1]
	v_pk_fma_f32 v[28:29], v[28:29], v[38:39], v[40:41] op_sel:[1,1,0] op_sel_hi:[1,0,1]
	v_mov_b64_e32 v[38:39], s[68:69]
	v_pk_mul_f32 v[40:41], v[36:37], v[38:39] op_sel:[0,0] op_sel_hi:[0,1]
	v_pk_fma_f32 v[38:39], v[36:37], v[38:39], v[40:41] op_sel:[1,1,0] op_sel_hi:[1,0,1] neg_lo:[0,1,0]
	v_pk_mul_f32 v[40:41], v[30:31], v[38:39] op_sel:[0,0] op_sel_hi:[0,1] neg_hi:[0,1]
	v_pk_fma_f32 v[30:31], v[30:31], v[38:39], v[40:41] op_sel:[1,1,0] op_sel_hi:[1,0,1]
	v_mov_b64_e32 v[38:39], s[4:5]
	v_pk_mul_f32 v[40:41], v[36:37], v[38:39] op_sel:[0,0] op_sel_hi:[0,1]
	v_pk_fma_f32 v[36:37], v[36:37], v[38:39], v[40:41] op_sel:[1,1,0] op_sel_hi:[1,0,1] neg_lo:[0,1,0]
	v_pk_mul_f32 v[38:39], v[32:33], v[36:37] op_sel:[0,0] op_sel_hi:[0,1] neg_hi:[0,1]
	s_nop 0
	v_pk_fma_f32 v[32:33], v[32:33], v[36:37], v[38:39] op_sel:[1,1,0] op_sel_hi:[1,0,1]

.LBB0_3673:
	s_or_b64 exec, exec, s[16:17]
	v_lshlrev_b32_e32 v2, 2, v9
	v_add_u32_e32 v37, s38, v2
	v_add_u32_e32 v2, 0, v2
	v_add_u32_e32 v54, 0x1bc00, v2
	v_lshl_add_u32 v2, v26, 9, v37
	s_waitcnt lgkmcnt(0)
	s_barrier
	ds_read_b128 v[40:43], v2
	ds_read_b128 v[44:47], v54
	s_lshl_b64 s[16:17], s[14:15], 14
	s_add_u32 s0, s85, s16
	s_addc_u32 s1, s84, s17
	v_mov_b32_e32 v33, v3
	s_waitcnt lgkmcnt(1)
	v_mul_f32_e32 v15, 0x3fb8aa3b, v40
	v_lshl_add_u64 v[34:35], s[0:1], 0, v[32:33]
	v_add_u32_e32 v2, 0, v32
	v_exp_f32_e32 v32, v15
	s_waitcnt lgkmcnt(0)
	v_sub_f32_e32 v15, v40, v44
	v_mul_f32_e32 v15, 0x3fb8aa3b, v15
	v_exp_f32_e32 v48, v15
	v_sub_f32_e32 v15, v44, v40
	v_mul_f32_e32 v15, 0x3fb8aa3b, v15
	v_exp_f32_e32 v40, v15
	v_mul_f32_e32 v15, 0x3fb8aa3b, v41
	v_exp_f32_e32 v44, v15
	v_sub_f32_e32 v15, v41, v45
	v_mul_f32_e32 v15, 0x3fb8aa3b, v15
	v_exp_f32_e32 v50, v15
	v_sub_f32_e32 v15, v45, v41
	v_mul_f32_e32 v15, 0x3fb8aa3b, v15
	v_exp_f32_e32 v52, v15
	v_mul_f32_e32 v15, 0x3fb8aa3b, v42
	v_exp_f32_e32 v33, v15
	v_sub_f32_e32 v15, v42, v46
	v_mul_f32_e32 v15, 0x3fb8aa3b, v15
	v_exp_f32_e32 v49, v15
	v_sub_f32_e32 v15, v46, v42
	v_mul_f32_e32 v15, 0x3fb8aa3b, v15
	v_exp_f32_e32 v41, v15
	v_mul_f32_e32 v15, 0x3fb8aa3b, v43
	v_exp_f32_e32 v45, v15
	v_sub_f32_e32 v15, v43, v47
	v_mul_f32_e32 v15, 0x3fb8aa3b, v15
	v_exp_f32_e32 v51, v15
	v_sub_f32_e32 v15, v47, v43
	v_lshlrev_b32_e32 v43, 16, v31
	v_lshlrev_b32_e32 v42, 16, v30
	v_and_b32_e32 v31, 0xffff0000, v31
	v_and_b32_e32 v30, 0xffff0000, v30
	v_pk_mul_f32 v[30:31], v[30:31], s[12:13] op_sel_hi:[1,0]
	v_pk_mul_f32 v[42:43], v[42:43], s[12:13] op_sel_hi:[1,0]
	v_pk_mul_f32 v[44:45], v[30:31], v[44:45]
	v_mul_f32_e32 v15, 0x3fb8aa3b, v15
	v_pk_mul_f32 v[32:33], v[42:43], v[32:33]
	v_exp_f32_e32 v53, v15
	v_cvt_pk_bf16_f32 v33, v33, v45
	v_cvt_pk_bf16_f32 v32, v32, v44
	v_ashrrev_i32_e32 v27, 31, v26
	v_lshlrev_b64 v[44:45], 8, v[26:27]
	v_lshl_add_u64 v[44:45], v[34:35], 0, v[44:45]
	global_store_dwordx2 v[44:45], v[32:33], off
	v_pk_mul_f32 v[32:33], v[42:43], v[48:49]
	v_pk_mul_f32 v[30:31], v[30:31], v[50:51]
	v_cvt_pk_bf16_f32 v30, v32, v30
	v_cvt_pk_bf16_f32 v31, v33, v31
	v_lshlrev_b32_e32 v43, 16, v29
	v_lshlrev_b32_e32 v42, 16, v28
	v_and_b32_e32 v29, 0xffff0000, v29
	v_and_b32_e32 v28, 0xffff0000, v28
	v_mad_u64_u32 v[32:33], s[0:1], v26, s46, v[2:3]
	v_pk_mul_f32 v[40:41], v[40:41], v[42:43]
	v_pk_mul_f32 v[28:29], v[52:53], v[28:29]
	v_and_b32_sdwa v21, v40, v38 dst_sel:DWORD dst_unused:UNUSED_PAD src0_sel:WORD_1 src1_sel:DWORD
	v_and_b32_sdwa v27, v29, v38 dst_sel:DWORD dst_unused:UNUSED_PAD src0_sel:WORD_1 src1_sel:DWORD
	v_and_b32_sdwa v33, v28, v38 dst_sel:DWORD dst_unused:UNUSED_PAD src0_sel:WORD_1 src1_sel:DWORD
	v_and_b32_sdwa v15, v41, v38 dst_sel:DWORD dst_unused:UNUSED_PAD src0_sel:WORD_1 src1_sel:DWORD
	v_add3_u32 v21, v40, v21, s45
	v_add3_u32 v40, v29, v27, s45
	v_add3_u32 v33, v28, v33, s45
	v_add3_u32 v15, v41, v15, s45
	v_and_b32_e32 v27, 0xffff0000, v40
	v_and_b32_e32 v28, 0xffff0000, v33
	v_lshlrev_b32_e32 v26, 1, v26
	v_mul_u32_u24_e32 v48, 0x90, v9
	v_or_b32_sdwa v29, v27, v15 dst_sel:DWORD dst_unused:UNUSED_PAD src0_sel:DWORD src1_sel:WORD_1
	v_or_b32_sdwa v28, v28, v21 dst_sel:DWORD dst_unused:UNUSED_PAD src0_sel:DWORD src1_sel:WORD_1
	v_add3_u32 v9, s27, v26, v48
	ds_write2st64_b64 v32, v[30:31], v[28:29] offset1:66
	ds_write_b16_d16_hi v9, v21
	v_lshl_add_u32 v21, v20, 9, v37
	ds_read_b128 v[26:29], v21
	ds_write_b16_d16_hi v9, v33 offset:144
	ds_read_b128 v[30:33], v54
	ds_write_b16_d16_hi v9, v15 offset:288
	ds_write_b16_d16_hi v9, v40 offset:432
	v_ashrrev_i32_e32 v36, 6, v6
	s_waitcnt lgkmcnt(4)
	v_mul_f32_e32 v9, 0x3fb8aa3b, v26
	v_exp_f32_e32 v40, v9
	s_waitcnt lgkmcnt(2)
	v_sub_f32_e32 v9, v26, v30
	v_mul_f32_e32 v9, 0x3fb8aa3b, v9
	v_exp_f32_e32 v42, v9
	v_sub_f32_e32 v9, v30, v26
	v_mul_f32_e32 v9, 0x3fb8aa3b, v9
	v_exp_f32_e32 v26, v9
	v_mul_f32_e32 v9, 0x3fb8aa3b, v27
	v_exp_f32_e32 v30, v9
	v_sub_f32_e32 v9, v27, v31
	v_mul_f32_e32 v9, 0x3fb8aa3b, v9
	v_exp_f32_e32 v44, v9
	v_sub_f32_e32 v9, v31, v27
	v_mul_f32_e32 v9, 0x3fb8aa3b, v9
	v_exp_f32_e32 v46, v9
	v_mul_f32_e32 v9, 0x3fb8aa3b, v28
	v_exp_f32_e32 v41, v9
	v_sub_f32_e32 v9, v28, v32
	v_mul_f32_e32 v9, 0x3fb8aa3b, v9
	v_exp_f32_e32 v43, v9
	v_sub_f32_e32 v9, v32, v28
	v_mul_f32_e32 v9, 0x3fb8aa3b, v9
	v_exp_f32_e32 v27, v9
	v_mul_f32_e32 v9, 0x3fb8aa3b, v29
	v_exp_f32_e32 v31, v9
	v_sub_f32_e32 v9, v29, v33
	v_mul_f32_e32 v9, 0x3fb8aa3b, v9
	v_exp_f32_e32 v45, v9
	v_sub_f32_e32 v9, v33, v29
	v_lshlrev_b32_e32 v29, 16, v25
	v_lshlrev_b32_e32 v28, 16, v24
	v_and_b32_e32 v25, 0xffff0000, v25
	v_and_b32_e32 v24, 0xffff0000, v24
	v_pk_mul_f32 v[28:29], v[28:29], s[12:13] op_sel_hi:[1,0]
	v_pk_mul_f32 v[24:25], v[24:25], s[12:13] op_sel_hi:[1,0]
	v_pk_mul_f32 v[32:33], v[28:29], v[40:41]
	v_pk_mul_f32 v[30:31], v[24:25], v[30:31]
	v_mul_f32_e32 v9, 0x3fb8aa3b, v9
	v_exp_f32_e32 v47, v9
	v_cvt_pk_bf16_f32 v31, v33, v31
	v_cvt_pk_bf16_f32 v30, v32, v30
	v_ashrrev_i32_e32 v21, 31, v20
	v_pk_mul_f32 v[28:29], v[28:29], v[42:43]
	v_lshlrev_b64 v[32:33], 8, v[20:21]
	v_pk_mul_f32 v[24:25], v[24:25], v[44:45]
	v_lshl_add_u64 v[32:33], v[34:35], 0, v[32:33]
	v_cvt_pk_bf16_f32 v24, v28, v24
	global_store_dwordx2 v[32:33], v[30:31], off
	v_lshlrev_b32_e32 v31, 16, v23
	v_lshlrev_b32_e32 v30, 16, v22
	v_cvt_pk_bf16_f32 v25, v29, v25
	v_and_b32_e32 v23, 0xffff0000, v23
	v_and_b32_e32 v22, 0xffff0000, v22
	v_pk_mul_f32 v[26:27], v[26:27], v[30:31]
	v_pk_mul_f32 v[22:23], v[46:47], v[22:23]
	v_and_b32_sdwa v15, v26, v38 dst_sel:DWORD dst_unused:UNUSED_PAD src0_sel:WORD_1 src1_sel:DWORD
	s_nop 0
	v_mad_u64_u32 v[28:29], s[0:1], v20, s46, v[2:3]
	v_add3_u32 v15, v26, v15, s45
	v_and_b32_sdwa v21, v23, v38 dst_sel:DWORD dst_unused:UNUSED_PAD src0_sel:WORD_1 src1_sel:DWORD
	v_and_b32_sdwa v26, v22, v38 dst_sel:DWORD dst_unused:UNUSED_PAD src0_sel:WORD_1 src1_sel:DWORD
	v_and_b32_sdwa v9, v27, v38 dst_sel:DWORD dst_unused:UNUSED_PAD src0_sel:WORD_1 src1_sel:DWORD
	v_add3_u32 v29, v23, v21, s45
	v_add3_u32 v26, v22, v26, s45
	v_add3_u32 v9, v27, v9, s45
	v_and_b32_e32 v21, 0xffff0000, v29
	v_and_b32_e32 v22, 0xffff0000, v26
	v_or_b32_sdwa v23, v21, v9 dst_sel:DWORD dst_unused:UNUSED_PAD src0_sel:DWORD src1_sel:WORD_1
	v_or_b32_sdwa v22, v22, v15 dst_sel:DWORD dst_unused:UNUSED_PAD src0_sel:DWORD src1_sel:WORD_1
	v_lshlrev_b32_e32 v20, 1, v20
	ds_write2st64_b64 v28, v[24:25], v[22:23] offset1:66
	v_add3_u32 v28, s27, v20, v48
	ds_write_b16_d16_hi v28, v15
	v_lshl_add_u32 v15, v14, 9, v37
	ds_read_b128 v[20:23], v15
	ds_write_b16_d16_hi v28, v26 offset:144
	ds_read_b128 v[24:27], v54
	ds_write_b16_d16_hi v28, v9 offset:288
	ds_write_b16_d16_hi v28, v29 offset:432
	v_bfe_u32 v7, v6, 4, 2
	s_waitcnt lgkmcnt(4)
	v_mul_f32_e32 v9, 0x3fb8aa3b, v20
	v_exp_f32_e32 v28, v9
	s_waitcnt lgkmcnt(2)
	v_sub_f32_e32 v9, v20, v24
	v_mul_f32_e32 v9, 0x3fb8aa3b, v9
	v_exp_f32_e32 v30, v9
	v_sub_f32_e32 v9, v24, v20
	v_mul_f32_e32 v9, 0x3fb8aa3b, v9
	v_exp_f32_e32 v20, v9
	v_mul_f32_e32 v9, 0x3fb8aa3b, v21
	v_exp_f32_e32 v24, v9
	v_sub_f32_e32 v9, v21, v25
	v_mul_f32_e32 v9, 0x3fb8aa3b, v9
	v_exp_f32_e32 v32, v9
	v_sub_f32_e32 v9, v25, v21
	v_mul_f32_e32 v9, 0x3fb8aa3b, v9
	v_exp_f32_e32 v40, v9
	v_mul_f32_e32 v9, 0x3fb8aa3b, v22
	v_exp_f32_e32 v29, v9
	v_sub_f32_e32 v9, v22, v26
	v_mul_f32_e32 v9, 0x3fb8aa3b, v9
	v_exp_f32_e32 v31, v9
	v_sub_f32_e32 v9, v26, v22
	v_mul_f32_e32 v9, 0x3fb8aa3b, v9
	v_exp_f32_e32 v21, v9
	v_mul_f32_e32 v9, 0x3fb8aa3b, v23
	v_exp_f32_e32 v25, v9
	v_sub_f32_e32 v9, v23, v27
	v_mul_f32_e32 v9, 0x3fb8aa3b, v9
	v_exp_f32_e32 v33, v9
	v_sub_f32_e32 v9, v27, v23
	v_lshlrev_b32_e32 v23, 16, v19
	v_lshlrev_b32_e32 v22, 16, v18
	v_and_b32_e32 v19, 0xffff0000, v19
	v_and_b32_e32 v18, 0xffff0000, v18
	v_pk_mul_f32 v[22:23], v[22:23], s[12:13] op_sel_hi:[1,0]
	v_mul_f32_e32 v9, 0x3fb8aa3b, v9
	v_pk_mul_f32 v[18:19], v[18:19], s[12:13] op_sel_hi:[1,0]
	v_pk_mul_f32 v[26:27], v[22:23], v[28:29]
	v_exp_f32_e32 v41, v9
	v_pk_mul_f32 v[24:25], v[18:19], v[24:25]
	v_and_b32_sdwa v9, v27, v38 dst_sel:DWORD dst_unused:UNUSED_PAD src0_sel:WORD_1 src1_sel:DWORD
	v_add3_u32 v9, v27, v9, s45
	v_cvt_pk_bf16_f32 v24, v26, v24
	v_and_b32_sdwa v26, v25, v38 dst_sel:DWORD dst_unused:UNUSED_PAD src0_sel:WORD_1 src1_sel:DWORD
	v_add3_u32 v25, v25, v26, s45
	v_and_b32_e32 v25, 0xffff0000, v25
	v_ashrrev_i32_e32 v15, 31, v14
	v_pk_mul_f32 v[22:23], v[22:23], v[30:31]
	v_or_b32_sdwa v25, v25, v9 dst_sel:DWORD dst_unused:UNUSED_PAD src0_sel:DWORD src1_sel:WORD_1
	v_lshlrev_b64 v[26:27], 8, v[14:15]
	v_pk_mul_f32 v[18:19], v[18:19], v[32:33]
	v_and_b32_sdwa v15, v22, v38 dst_sel:DWORD dst_unused:UNUSED_PAD src0_sel:WORD_1 src1_sel:DWORD
	v_lshl_add_u64 v[26:27], v[34:35], 0, v[26:27]
	v_add3_u32 v15, v22, v15, s45
	v_cvt_pk_bf16_f32 v19, v23, v19
	v_and_b32_sdwa v23, v18, v38 dst_sel:DWORD dst_unused:UNUSED_PAD src0_sel:WORD_1 src1_sel:DWORD
	global_store_dwordx2 v[26:27], v[24:25], off
	s_nop 0
	v_add3_u32 v18, v18, v23, s45
	v_lshlrev_b32_e32 v25, 16, v17
	v_lshlrev_b32_e32 v24, 16, v16
	v_and_b32_e32 v18, 0xffff0000, v18
	v_and_b32_e32 v17, 0xffff0000, v17
	v_and_b32_e32 v16, 0xffff0000, v16
	v_pk_mul_f32 v[20:21], v[20:21], v[24:25]
	v_or_b32_sdwa v18, v18, v15 dst_sel:DWORD dst_unused:UNUSED_PAD src0_sel:DWORD src1_sel:WORD_1
	v_pk_mul_f32 v[16:17], v[40:41], v[16:17]
	v_and_b32_sdwa v9, v21, v38 dst_sel:DWORD dst_unused:UNUSED_PAD src0_sel:WORD_1 src1_sel:DWORD
	v_and_b32_sdwa v15, v20, v38 dst_sel:DWORD dst_unused:UNUSED_PAD src0_sel:WORD_1 src1_sel:DWORD
	v_mad_u64_u32 v[22:23], s[0:1], v14, s46, v[2:3]
	v_add3_u32 v15, v20, v15, s45
	v_add3_u32 v9, v21, v9, s45
	v_and_b32_sdwa v20, v17, v38 dst_sel:DWORD dst_unused:UNUSED_PAD src0_sel:WORD_1 src1_sel:DWORD
	v_and_b32_sdwa v21, v16, v38 dst_sel:DWORD dst_unused:UNUSED_PAD src0_sel:WORD_1 src1_sel:DWORD
	v_add3_u32 v23, v17, v20, s45
	v_add3_u32 v20, v16, v21, s45
	v_and_b32_e32 v16, 0xffff0000, v23
	v_and_b32_e32 v21, 0xffff0000, v20
	v_or_b32_sdwa v17, v16, v9 dst_sel:DWORD dst_unused:UNUSED_PAD src0_sel:DWORD src1_sel:WORD_1
	v_or_b32_sdwa v16, v21, v15 dst_sel:DWORD dst_unused:UNUSED_PAD src0_sel:DWORD src1_sel:WORD_1
	v_lshlrev_b32_e32 v14, 1, v14
	ds_write2st64_b64 v22, v[18:19], v[16:17] offset1:66
	v_add3_u32 v22, s27, v14, v48
	v_lshl_add_u32 v14, v8, 9, v37
	ds_write_b16_d16_hi v22, v15
	ds_read_b128 v[14:17], v14
	ds_write_b16_d16_hi v22, v20 offset:144
	ds_read_b128 v[18:21], v54
	ds_write_b16_d16_hi v22, v9 offset:288
	ds_write_b16_d16_hi v22, v23 offset:432
	s_waitcnt lgkmcnt(4)
	v_mul_f32_e32 v9, 0x3fb8aa3b, v14
	v_exp_f32_e32 v22, v9
	s_waitcnt lgkmcnt(2)
	v_sub_f32_e32 v9, v14, v18
	v_mul_f32_e32 v9, 0x3fb8aa3b, v9
	v_exp_f32_e32 v24, v9
	v_sub_f32_e32 v9, v18, v14
	v_mul_f32_e32 v9, 0x3fb8aa3b, v9
	v_exp_f32_e32 v14, v9
	v_mul_f32_e32 v9, 0x3fb8aa3b, v15
	v_exp_f32_e32 v18, v9
	v_sub_f32_e32 v9, v15, v19
	v_mul_f32_e32 v9, 0x3fb8aa3b, v9
	v_exp_f32_e32 v26, v9
	v_sub_f32_e32 v9, v19, v15
	v_mul_f32_e32 v9, 0x3fb8aa3b, v9
	v_exp_f32_e32 v28, v9
	v_mul_f32_e32 v9, 0x3fb8aa3b, v16
	v_exp_f32_e32 v23, v9
	v_sub_f32_e32 v9, v16, v20
	v_mul_f32_e32 v9, 0x3fb8aa3b, v9
	v_exp_f32_e32 v25, v9
	v_sub_f32_e32 v9, v20, v16
	v_mul_f32_e32 v9, 0x3fb8aa3b, v9
	v_exp_f32_e32 v15, v9
	v_mul_f32_e32 v9, 0x3fb8aa3b, v17
	v_exp_f32_e32 v19, v9
	v_sub_f32_e32 v9, v17, v21
	v_mul_f32_e32 v9, 0x3fb8aa3b, v9
	v_exp_f32_e32 v27, v9
	v_sub_f32_e32 v9, v21, v17
	v_lshlrev_b32_e32 v17, 16, v13
	v_lshlrev_b32_e32 v16, 16, v12
	v_and_b32_e32 v13, 0xffff0000, v13
	v_and_b32_e32 v12, 0xffff0000, v12
	v_pk_mul_f32 v[16:17], v[16:17], s[12:13] op_sel_hi:[1,0]
	v_mul_f32_e32 v9, 0x3fb8aa3b, v9
	v_pk_mul_f32 v[12:13], v[12:13], s[12:13] op_sel_hi:[1,0]
	v_pk_mul_f32 v[20:21], v[16:17], v[22:23]
	v_exp_f32_e32 v29, v9
	v_pk_mul_f32 v[18:19], v[12:13], v[18:19]
	v_and_b32_sdwa v22, v20, v38 dst_sel:DWORD dst_unused:UNUSED_PAD src0_sel:WORD_1 src1_sel:DWORD
	s_nop 0
	v_cvt_pk_bf16_f32 v19, v21, v19
	v_add3_u32 v20, v20, v22, s45
	v_and_b32_sdwa v22, v18, v38 dst_sel:DWORD dst_unused:UNUSED_PAD src0_sel:WORD_1 src1_sel:DWORD
	v_add3_u32 v18, v18, v22, s45
	v_and_b32_e32 v18, 0xffff0000, v18
	v_ashrrev_i32_e32 v9, 31, v8
	v_or_b32_sdwa v18, v18, v20 dst_sel:DWORD dst_unused:UNUSED_PAD src0_sel:DWORD src1_sel:WORD_1
	v_lshlrev_b64 v[20:21], 8, v[8:9]
	v_lshl_add_u64 v[20:21], v[34:35], 0, v[20:21]
	v_pk_mul_f32 v[16:17], v[16:17], v[24:25]
	global_store_dwordx2 v[20:21], v[18:19], off
	v_pk_mul_f32 v[12:13], v[12:13], v[26:27]
	v_and_b32_sdwa v18, v16, v38 dst_sel:DWORD dst_unused:UNUSED_PAD src0_sel:WORD_1 src1_sel:DWORD
	v_add3_u32 v16, v16, v18, s45
	v_cvt_pk_bf16_f32 v13, v17, v13
	v_and_b32_sdwa v18, v12, v38 dst_sel:DWORD dst_unused:UNUSED_PAD src0_sel:WORD_1 src1_sel:DWORD
	v_add3_u32 v12, v12, v18, s45
	v_lshlrev_b32_e32 v19, 16, v11
	v_lshlrev_b32_e32 v18, 16, v10
	v_and_b32_e32 v12, 0xffff0000, v12
	v_and_b32_e32 v11, 0xffff0000, v11
	v_and_b32_e32 v10, 0xffff0000, v10
	v_pk_mul_f32 v[14:15], v[14:15], v[18:19]
	v_or_b32_sdwa v12, v12, v16 dst_sel:DWORD dst_unused:UNUSED_PAD src0_sel:DWORD src1_sel:WORD_1
	v_mad_u64_u32 v[16:17], s[0:1], v8, s46, v[2:3]
	v_pk_mul_f32 v[10:11], v[28:29], v[10:11]
	v_and_b32_sdwa v2, v15, v38 dst_sel:DWORD dst_unused:UNUSED_PAD src0_sel:WORD_1 src1_sel:DWORD
	v_and_b32_sdwa v9, v14, v38 dst_sel:DWORD dst_unused:UNUSED_PAD src0_sel:WORD_1 src1_sel:DWORD
	v_add3_u32 v9, v14, v9, s45
	v_add3_u32 v2, v15, v2, s45
	v_and_b32_sdwa v14, v11, v38 dst_sel:DWORD dst_unused:UNUSED_PAD src0_sel:WORD_1 src1_sel:DWORD
	v_and_b32_sdwa v15, v10, v38 dst_sel:DWORD dst_unused:UNUSED_PAD src0_sel:WORD_1 src1_sel:DWORD
	v_add3_u32 v14, v11, v14, s45
	v_add3_u32 v15, v10, v15, s45
	v_and_b32_e32 v10, 0xffff0000, v14
	v_and_b32_e32 v17, 0xffff0000, v15
	v_lshlrev_b32_e32 v8, 1, v8
	v_or_b32_sdwa v11, v10, v2 dst_sel:DWORD dst_unused:UNUSED_PAD src0_sel:DWORD src1_sel:WORD_1
	v_or_b32_sdwa v10, v17, v9 dst_sel:DWORD dst_unused:UNUSED_PAD src0_sel:DWORD src1_sel:WORD_1
	v_add3_u32 v8, s27, v8, v48
	ds_write2st64_b64 v16, v[12:13], v[10:11] offset1:66
	ds_write_b16_d16_hi v8, v9
	ds_write_b16_d16_hi v8, v15 offset:144
	ds_write_b16_d16_hi v8, v2 offset:288
	ds_write_b16_d16_hi v8, v14 offset:432
	v_lshlrev_b32_e32 v2, 3, v36
	v_and_or_b32 v8, v2, s48, v39
	v_lshl_add_u32 v2, v7, 4, 0
	v_mad_u64_u32 v[28:29], s[0:1], v8, s46, v[2:3]
	s_waitcnt lgkmcnt(0)
	s_barrier
	ds_read_b128 v[8:11], v28
	v_lshlrev_b32_e32 v12, 5, v36
	v_and_or_b32 v36, v12, 32, v39
	v_mad_u32_u24 v2, v36, s46, v2
	ds_read_b128 v[12:15], v28 offset:64
	ds_read_b128 v[16:19], v2 offset:33792
	ds_read_b128 v[20:23], v2 offset:33856
	ds_read_b128 v[24:27], v28 offset:128
	s_waitcnt lgkmcnt(2)
	v_mfma_f32_16x16x32_bf16 v[16:19], v[8:11], v[16:19], 0
	s_waitcnt lgkmcnt(1)
	v_mfma_f32_16x16x32_bf16 v[16:19], v[12:15], v[20:23], v[16:19]
	ds_read_b128 v[20:23], v28 offset:192
	ds_read_b128 v[28:31], v2 offset:33920
	ds_read_b128 v[32:35], v2 offset:33984
	s_waitcnt lgkmcnt(1)
	v_mfma_f32_16x16x32_bf16 v[16:19], v[24:27], v[28:31], v[16:19]
	s_waitcnt lgkmcnt(0)
	v_mfma_f32_16x16x32_bf16 v[16:19], v[20:23], v[32:35], v[16:19]
	ds_read_b128 v[28:31], v2 offset:42240
	ds_read_b128 v[32:35], v2 offset:42304
	s_waitcnt lgkmcnt(1)
	v_mfma_f32_16x16x32_bf16 v[8:11], v[8:11], v[28:31], 0
	s_waitcnt lgkmcnt(0)
	v_mfma_f32_16x16x32_bf16 v[8:11], v[12:15], v[32:35], v[8:11]
	ds_read_b128 v[12:15], v2 offset:42368
	ds_read_b128 v[28:31], v2 offset:42432
	v_ashrrev_i32_e32 v2, 3, v6
	v_and_b32_e32 v2, -16, v2
	v_lshl_or_b32 v2, v7, 2, v2
	v_cmp_le_i32_e64 s[0:1], v36, v2
	s_waitcnt lgkmcnt(1)
	v_mfma_f32_16x16x32_bf16 v[8:11], v[24:27], v[12:15], v[8:11]
	v_lshl_add_u32 v6, v36, 1, s49
	v_cndmask_b32_e64 v7, 0, 1, s[0:1]
	v_cmp_ge_i32_e64 s[0:1], v36, v2
	s_waitcnt lgkmcnt(0)
	v_mfma_f32_16x16x32_bf16 v[8:11], v[20:23], v[28:31], v[8:11]
	v_cndmask_b32_e64 v12, 0, 1, s[0:1]
	v_cndmask_b32_e32 v7, v12, v7, vcc
	v_and_b32_e32 v7, 1, v7
	v_cmp_eq_u32_e64 s[0:1], 1, v7
	s_nop 1
	v_cndmask_b32_e64 v7, 0, v16, s[0:1]
	v_bfe_u32 v12, v7, 16, 1
	v_add3_u32 v7, v7, v12, s45
	v_mul_lo_u32 v12, v2, s47
	v_add_u32_e32 v13, v6, v12
	ds_write_b16_d16_hi v13, v7
	v_or_b32_e32 v7, 1, v2
	v_cmp_gt_i32_e64 s[0:1], v36, v2
	s_nop 1
	v_cndmask_b32_e64 v13, 0, 1, s[0:1]
	v_cmp_le_i32_e64 s[0:1], v36, v7
	s_nop 1
	v_cndmask_b32_e64 v14, 0, 1, s[0:1]
	v_cndmask_b32_e32 v13, v13, v14, vcc
	v_and_b32_e32 v13, 1, v13
	v_cmp_eq_u32_e64 s[0:1], 1, v13
	s_nop 1
	v_cndmask_b32_e64 v13, 0, v17, s[0:1]
	v_bfe_u32 v14, v13, 16, 1
	v_add3_u32 v13, v13, v14, s45
	v_add_u32_e32 v14, 0x90, v12
	v_add_u32_e32 v15, v6, v14
	ds_write_b16_d16_hi v15, v13
	v_or_b32_e32 v13, 2, v2
	v_cmp_le_i32_e64 s[0:1], v36, v13
	s_nop 1
	v_cndmask_b32_e64 v15, 0, 1, s[0:1]
	v_cmp_ge_i32_e64 s[0:1], v36, v13
	s_nop 1
	v_cndmask_b32_e64 v16, 0, 1, s[0:1]
	v_cndmask_b32_e32 v15, v16, v15, vcc
	v_and_b32_e32 v15, 1, v15
	v_cmp_eq_u32_e64 s[0:1], 1, v15
	s_nop 1
	v_cndmask_b32_e64 v15, 0, v18, s[0:1]
	v_bfe_u32 v16, v15, 16, 1
	v_add3_u32 v15, v15, v16, s45
	v_add_u32_e32 v16, 0x120, v12
	v_add_u32_e32 v17, v6, v16
	ds_write_b16_d16_hi v17, v15
	v_or_b32_e32 v15, 3, v2
	v_cmp_le_i32_e64 s[0:1], v36, v15
	s_nop 1
	v_cndmask_b32_e64 v17, 0, 1, s[0:1]
	v_cmp_ge_i32_e64 s[0:1], v36, v15
	s_nop 1
	v_cndmask_b32_e64 v18, 0, 1, s[0:1]
	v_cndmask_b32_e32 v17, v18, v17, vcc
	v_and_b32_e32 v17, 1, v17
	v_cmp_eq_u32_e64 s[0:1], 1, v17
	s_nop 1
	v_cndmask_b32_e64 v17, 0, v19, s[0:1]
	v_bfe_u32 v18, v17, 16, 1
	v_add3_u32 v17, v17, v18, s45
	v_add_u32_e32 v18, 0x1b0, v12
	v_add_u32_e32 v6, v6, v18
	ds_write_b16_d16_hi v6, v17
	v_or_b32_e32 v6, 16, v36
	v_cmp_le_i32_e64 s[0:1], v6, v2
	s_nop 1
	v_cndmask_b32_e64 v17, 0, 1, s[0:1]
	v_cmp_ge_i32_e64 s[0:1], v6, v2
	s_nop 1
	v_cndmask_b32_e64 v19, 0, 1, s[0:1]
	v_cndmask_b32_e32 v17, v19, v17, vcc
	v_and_b32_e32 v17, 1, v17
	v_cmp_eq_u32_e64 s[0:1], 1, v17
	s_nop 1
	v_cndmask_b32_e64 v8, 0, v8, s[0:1]
	v_cmp_le_i32_e64 s[0:1], v6, v7
	v_bfe_u32 v17, v8, 16, 1
	v_add3_u32 v8, v8, v17, s45
	v_cndmask_b32_e64 v7, 0, 1, s[0:1]
	v_cmp_gt_i32_e64 s[0:1], v6, v2
	v_lshlrev_b32_e32 v17, 1, v6
	v_add3_u32 v12, s49, v12, v17
	v_cndmask_b32_e64 v2, 0, 1, s[0:1]
	v_cndmask_b32_e32 v2, v2, v7, vcc
	v_and_b32_e32 v2, 1, v2
	v_cmp_eq_u32_e64 s[0:1], 1, v2
	ds_write_b16_d16_hi v12, v8
	s_nop 0
	v_cndmask_b32_e64 v2, 0, v9, s[0:1]
	v_bfe_u32 v7, v2, 16, 1
	v_add3_u32 v2, v2, v7, s45
	v_add3_u32 v7, s49, v14, v17
	v_cmp_le_i32_e64 s[0:1], v6, v13
	ds_write_b16_d16_hi v7, v2
	s_nop 0
	v_cndmask_b32_e64 v2, 0, 1, s[0:1]
	v_cmp_ge_i32_e64 s[0:1], v6, v13
	s_nop 1
	v_cndmask_b32_e64 v7, 0, 1, s[0:1]
	v_cndmask_b32_e32 v2, v7, v2, vcc
	v_and_b32_e32 v2, 1, v2
	v_cmp_eq_u32_e64 s[0:1], 1, v2
	s_nop 1
	v_cndmask_b32_e64 v2, 0, v10, s[0:1]
	v_bfe_u32 v7, v2, 16, 1
	v_add3_u32 v2, v2, v7, s45
	v_add3_u32 v7, s49, v16, v17
	v_cmp_le_i32_e64 s[0:1], v6, v15
	ds_write_b16_d16_hi v7, v2
	s_nop 0
	v_cndmask_b32_e64 v2, 0, 1, s[0:1]
	v_cmp_ge_i32_e64 s[0:1], v6, v15
	s_nop 1
	v_cndmask_b32_e64 v6, 0, 1, s[0:1]
	v_cndmask_b32_e32 v2, v6, v2, vcc
	v_and_b32_e32 v2, 1, v2
	v_cmp_eq_u32_e64 s[0:1], 1, v2
	s_nop 1
	v_cndmask_b32_e64 v2, 0, v11, s[0:1]
	v_bfe_u32 v6, v2, 16, 1
	v_add3_u32 v2, v2, v6, s45
	v_add3_u32 v6, s49, v18, v17
	ds_write_b16_d16_hi v6, v2
	v_mov_b32_e32 v6, v0
	s_waitcnt lgkmcnt(0)
	s_barrier
	s_nop 0
	v_cmp_gt_i32_e64 s[0:1], s23, v6
	s_and_saveexec_b64 s[18:19], s[0:1]
	s_cbranch_execz .LBB0_3676
	s_lshl_b64 s[0:1], s[14:15], 13
	s_add_u32 s14, s64, s0
	s_addc_u32 s15, s61, s1
	v_lshlrev_b32_e32 v7, 3, v6
	s_mov_b64 s[20:21], 0

.LBB0_3752:
	v_ashrrev_i32_e32 v37, 8, v18
	v_and_b32_e32 v34, 0xff, v18
	v_lshlrev_b32_e32 v19, 13, v37
	v_lshlrev_b32_e32 v20, 1, v34
	v_add3_u32 v38, s25, v19, v20
	v_add3_u32 v19, s53, v19, v20
	ds_read_u16 v20, v38
	ds_read_u16 v22, v38 offset:512
	ds_read_u16 v24, v38 offset:1024
	ds_read_u16 v26, v38 offset:1536
	ds_read_u16 v28, v38 offset:2048
	ds_read_u16 v39, v38 offset:2560
	ds_read_u16 v42, v38 offset:3072
	ds_read_u16 v44, v38 offset:3584
	ds_read_u16 v21, v19
	ds_read_u16 v23, v19 offset:512
	ds_read_u16 v25, v19 offset:1024
	ds_read_u16 v27, v19 offset:1536
	ds_read_u16 v29, v19 offset:2048
	ds_read_u16 v41, v19 offset:2560
	ds_read_u16 v43, v19 offset:3072
	ds_read_u16 v45, v19 offset:3584
	s_waitcnt lgkmcnt(7)
	v_lshlrev_b32_e32 v21, 16, v21
	v_lshlrev_b32_e32 v40, 16, v39
	s_waitcnt lgkmcnt(2)
	v_lshlrev_b32_e32 v39, 16, v41
	v_xor_b32_e32 v41, 0x80000000, v39
	s_waitcnt lgkmcnt(1)
	v_lshlrev_b32_e32 v39, 16, v43
	v_xor_b32_e32 v43, 0x80000000, v39
	s_waitcnt lgkmcnt(0)
	v_lshlrev_b32_e32 v39, 16, v45
	v_xor_b32_e32 v45, 0x80000000, v39
	ds_read_u16 v39, v38 offset:4096
	ds_read_u16 v48, v38 offset:4608
	ds_read_u16 v50, v38 offset:5120
	ds_read_u16 v52, v38 offset:5632
	ds_read_u16 v54, v38 offset:6144
	ds_read_u16 v56, v38 offset:6656
	ds_read_u16 v58, v38 offset:7168
	ds_read_u16 v38, v38 offset:7680
	s_waitcnt lgkmcnt(7)
	v_lshlrev_b32_e32 v46, 16, v39
	ds_read_u16 v39, v19 offset:4096
	ds_read_u16 v49, v19 offset:4608
	ds_read_u16 v51, v19 offset:5120
	ds_read_u16 v53, v19 offset:5632
	ds_read_u16 v55, v19 offset:6144
	ds_read_u16 v57, v19 offset:6656
	ds_read_u16 v59, v19 offset:7168
	ds_read_u16 v19, v19 offset:7680
	s_waitcnt lgkmcnt(7)
	v_lshlrev_b32_e32 v39, 16, v39
	v_xor_b32_e32 v47, 0x80000000, v39
	s_waitcnt lgkmcnt(6)
	v_lshlrev_b32_e32 v39, 16, v49
	v_xor_b32_e32 v49, 0x80000000, v39
	s_waitcnt lgkmcnt(5)
	v_lshlrev_b32_e32 v39, 16, v51
	v_xor_b32_e32 v51, 0x80000000, v39
	s_waitcnt lgkmcnt(4)
	v_lshlrev_b32_e32 v39, 16, v53
	v_lshlrev_b32_e32 v29, 16, v29
	v_xor_b32_e32 v53, 0x80000000, v39
	s_waitcnt lgkmcnt(3)
	v_lshlrev_b32_e32 v39, 16, v55
	v_lshlrev_b32_e32 v20, 16, v20
	v_xor_b32_e32 v21, 0x80000000, v21
	v_lshlrev_b32_e32 v23, 16, v23
	v_lshlrev_b32_e32 v28, 16, v28
	v_xor_b32_e32 v29, 0x80000000, v29
	v_lshlrev_b32_e32 v54, 16, v54
	v_xor_b32_e32 v55, 0x80000000, v39
	s_waitcnt lgkmcnt(2)
	v_lshlrev_b32_e32 v39, 16, v57
	s_waitcnt lgkmcnt(0)
	v_lshlrev_b32_e32 v19, 16, v19
	v_lshlrev_b32_e32 v22, 16, v22
	v_xor_b32_e32 v23, 0x80000000, v23
	v_lshlrev_b32_e32 v25, 16, v25
	v_lshlrev_b32_e32 v48, 16, v48
	v_lshlrev_b32_e32 v56, 16, v56
	v_xor_b32_e32 v57, 0x80000000, v39
	v_lshlrev_b32_e32 v39, 16, v59
	v_lshlrev_b32_e32 v60, 16, v38
	v_xor_b32_e32 v61, 0x80000000, v19
	v_bfe_u32 v38, v18, 4, 4
	v_pk_add_f32 v[18:19], v[20:21], v[46:47]
	v_pk_add_f32 v[20:21], v[20:21], v[46:47] neg_lo:[0,1] neg_hi:[0,1]
	v_pk_add_f32 v[46:47], v[28:29], v[54:55]
	v_pk_add_f32 v[28:29], v[28:29], v[54:55] neg_lo:[0,1] neg_hi:[0,1]
	v_lshlrev_b32_e32 v24, 16, v24
	v_xor_b32_e32 v25, 0x80000000, v25
	v_lshlrev_b32_e32 v27, 16, v27
	v_lshlrev_b32_e32 v42, 16, v42
	v_lshlrev_b32_e32 v50, 16, v50
	v_lshlrev_b32_e32 v58, 16, v58
	v_xor_b32_e32 v59, 0x80000000, v39
	v_pk_add_f32 v[54:55], v[18:19], v[46:47]
	v_pk_add_f32 v[46:47], v[18:19], v[46:47] neg_lo:[0,1] neg_hi:[0,1]
	v_pk_add_f32 v[62:63], v[20:21], v[28:29] op_sel:[0,1] op_sel_hi:[1,0] neg_hi:[0,1]
	v_pk_add_f32 v[64:65], v[20:21], v[28:29] op_sel:[0,1] op_sel_hi:[1,0] neg_lo:[0,1]
	v_pk_add_f32 v[18:19], v[22:23], v[48:49]
	v_pk_add_f32 v[20:21], v[22:23], v[48:49] neg_lo:[0,1] neg_hi:[0,1]
	v_pk_add_f32 v[22:23], v[40:41], v[56:57]
	v_pk_add_f32 v[28:29], v[40:41], v[56:57] neg_lo:[0,1] neg_hi:[0,1]
	v_lshlrev_b32_e32 v26, 16, v26
	v_xor_b32_e32 v27, 0x80000000, v27
	v_lshlrev_b32_e32 v44, 16, v44
	v_lshlrev_b32_e32 v52, 16, v52
	v_pk_add_f32 v[40:41], v[18:19], v[22:23]
	v_pk_add_f32 v[22:23], v[18:19], v[22:23] neg_lo:[0,1] neg_hi:[0,1]
	v_pk_add_f32 v[18:19], v[20:21], v[28:29] op_sel:[0,1] op_sel_hi:[1,0] neg_hi:[0,1]
	v_pk_add_f32 v[28:29], v[20:21], v[28:29] op_sel:[0,1] op_sel_hi:[1,0] neg_lo:[0,1]
	v_pk_add_f32 v[20:21], v[24:25], v[50:51]
	v_pk_add_f32 v[24:25], v[24:25], v[50:51] neg_lo:[0,1] neg_hi:[0,1]
	v_pk_add_f32 v[48:49], v[42:43], v[58:59]
	v_pk_add_f32 v[42:43], v[42:43], v[58:59] neg_lo:[0,1] neg_hi:[0,1]
	v_pk_add_f32 v[50:51], v[20:21], v[48:49]
	v_pk_add_f32 v[48:49], v[20:21], v[48:49] neg_lo:[0,1] neg_hi:[0,1]
	v_pk_add_f32 v[56:57], v[24:25], v[42:43] op_sel:[0,1] op_sel_hi:[1,0] neg_hi:[0,1]
	v_pk_add_f32 v[42:43], v[24:25], v[42:43] op_sel:[0,1] op_sel_hi:[1,0] neg_lo:[0,1]
	v_pk_add_f32 v[20:21], v[26:27], v[52:53]
	v_pk_add_f32 v[24:25], v[26:27], v[52:53] neg_lo:[0,1] neg_hi:[0,1]
	v_pk_add_f32 v[26:27], v[44:45], v[60:61]
	v_pk_add_f32 v[44:45], v[44:45], v[60:61] neg_lo:[0,1] neg_hi:[0,1]
	v_pk_add_f32 v[52:53], v[20:21], v[26:27]
	v_pk_add_f32 v[58:59], v[20:21], v[26:27] neg_lo:[0,1] neg_hi:[0,1]
	v_pk_add_f32 v[26:27], v[24:25], v[44:45] op_sel:[0,1] op_sel_hi:[1,0] neg_hi:[0,1]
	v_pk_add_f32 v[44:45], v[24:25], v[44:45] op_sel:[0,1] op_sel_hi:[1,0] neg_lo:[0,1]
	v_mov_b64_e32 v[24:25], s[26:27]
	v_pk_mul_f32 v[20:21], v[18:19], v[24:25] op_sel:[0,0] op_sel_hi:[0,1]
	v_mad_i32_i24 v35, v37, s3, 0
	v_pk_fma_f32 v[60:61], v[18:19], v[24:25], v[20:21] op_sel:[1,1,0] op_sel_hi:[1,0,1] neg_lo:[0,1,0]
	v_mov_b64_e32 v[20:21], s[34:35]
	v_pk_mul_f32 v[18:19], v[56:57], v[20:21] op_sel:[0,0] op_sel_hi:[0,1]
	v_lshlrev_b32_e32 v39, 3, v34
	v_pk_fma_f32 v[56:57], v[56:57], v[20:21], v[18:19] op_sel:[1,1,0] op_sel_hi:[1,0,1] neg_lo:[0,1,0]
	v_mov_b64_e32 v[18:19], s[36:37]
	v_pk_mul_f32 v[66:67], v[26:27], v[18:19] op_sel:[0,0] op_sel_hi:[0,1]
	v_lshlrev_b32_e32 v74, 3, v38
	v_pk_fma_f32 v[66:67], v[26:27], v[18:19], v[66:67] op_sel:[1,1,0] op_sel_hi:[1,0,1] neg_lo:[0,1,0]
	v_pk_mul_f32 v[26:27], v[22:23], v[20:21] op_sel:[0,0] op_sel_hi:[0,1]
	v_add3_u32 v74, v35, v39, v74
	v_pk_fma_f32 v[68:69], v[22:23], v[20:21], v[26:27] op_sel:[1,1,0] op_sel_hi:[1,0,1] neg_lo:[0,1,0]
	v_mov_b64_e32 v[26:27], s[22:23]
	v_pk_mul_f32 v[22:23], v[48:49], v[26:27] op_sel:[0,0] op_sel_hi:[0,1]
	v_lshl_add_u32 v78, v38, 11, v35
	v_pk_fma_f32 v[48:49], v[48:49], v[26:27], v[22:23] op_sel:[1,1,0] op_sel_hi:[1,0,1] neg_lo:[0,1,0]
	v_mov_b64_e32 v[22:23], s[38:39]
	v_pk_mul_f32 v[70:71], v[58:59], v[22:23] op_sel:[0,0] op_sel_hi:[0,1]
	v_add_u32_e32 v39, v78, v39
	v_pk_fma_f32 v[58:59], v[58:59], v[22:23], v[70:71] op_sel:[1,1,0] op_sel_hi:[1,0,1] neg_lo:[0,1,0]
	v_pk_mul_f32 v[70:71], v[28:29], v[18:19] op_sel:[0,0] op_sel_hi:[0,1]
	v_pk_fma_f32 v[70:71], v[28:29], v[18:19], v[70:71] op_sel:[1,1,0] op_sel_hi:[1,0,1] neg_lo:[0,1,0]
	v_pk_mul_f32 v[28:29], v[42:43], v[22:23] op_sel:[0,0] op_sel_hi:[0,1]
	v_pk_fma_f32 v[42:43], v[42:43], v[22:23], v[28:29] op_sel:[1,1,0] op_sel_hi:[1,0,1] neg_lo:[0,1,0]
	v_mov_b64_e32 v[28:29], s[40:41]
	v_pk_mul_f32 v[72:73], v[44:45], v[28:29] op_sel:[0,0] op_sel_hi:[0,1]
	v_pk_fma_f32 v[44:45], v[44:45], v[28:29], v[72:73] op_sel:[1,1,0] op_sel_hi:[1,0,1] neg_lo:[0,1,0]
	v_pk_add_f32 v[72:73], v[54:55], v[50:51]
	v_pk_add_f32 v[50:51], v[54:55], v[50:51] neg_lo:[0,1] neg_hi:[0,1]
	v_pk_add_f32 v[54:55], v[40:41], v[52:53]
	v_pk_add_f32 v[40:41], v[40:41], v[52:53] neg_lo:[0,1] neg_hi:[0,1]
	v_pk_add_f32 v[52:53], v[72:73], v[54:55]
	v_pk_add_f32 v[54:55], v[72:73], v[54:55] neg_lo:[0,1] neg_hi:[0,1]
	v_pk_add_f32 v[72:73], v[50:51], v[40:41] op_sel:[0,1] op_sel_hi:[1,0] neg_hi:[0,1]
	v_pk_add_f32 v[40:41], v[50:51], v[40:41] op_sel:[0,1] op_sel_hi:[1,0] neg_lo:[0,1]
	v_pk_add_f32 v[50:51], v[62:63], v[56:57]
	v_pk_add_f32 v[56:57], v[62:63], v[56:57] neg_lo:[0,1] neg_hi:[0,1]
	v_pk_add_f32 v[62:63], v[60:61], v[66:67]
	v_pk_add_f32 v[60:61], v[60:61], v[66:67] neg_lo:[0,1] neg_hi:[0,1]
	v_pk_add_f32 v[66:67], v[50:51], v[62:63]
	v_pk_add_f32 v[50:51], v[50:51], v[62:63] neg_lo:[0,1] neg_hi:[0,1]
	v_pk_add_f32 v[62:63], v[56:57], v[60:61] op_sel:[0,1] op_sel_hi:[1,0] neg_hi:[0,1]
	v_pk_add_f32 v[56:57], v[56:57], v[60:61] op_sel:[0,1] op_sel_hi:[1,0] neg_lo:[0,1]
	v_pk_add_f32 v[60:61], v[46:47], v[48:49]
	v_pk_add_f32 v[46:47], v[46:47], v[48:49] neg_lo:[0,1] neg_hi:[0,1]
	v_pk_add_f32 v[48:49], v[68:69], v[58:59]
	v_pk_add_f32 v[58:59], v[68:69], v[58:59] neg_lo:[0,1] neg_hi:[0,1]
	v_pk_add_f32 v[68:69], v[60:61], v[48:49]
	v_pk_add_f32 v[48:49], v[60:61], v[48:49] neg_lo:[0,1] neg_hi:[0,1]
	v_pk_add_f32 v[60:61], v[46:47], v[58:59] op_sel:[0,1] op_sel_hi:[1,0] neg_hi:[0,1]
	v_pk_add_f32 v[46:47], v[46:47], v[58:59] op_sel:[0,1] op_sel_hi:[1,0] neg_lo:[0,1]
	v_pk_add_f32 v[58:59], v[64:65], v[42:43]
	v_pk_add_f32 v[42:43], v[64:65], v[42:43] neg_lo:[0,1] neg_hi:[0,1]
	v_pk_add_f32 v[64:65], v[70:71], v[44:45]
	v_pk_add_f32 v[44:45], v[70:71], v[44:45] neg_lo:[0,1] neg_hi:[0,1]
	v_pk_add_f32 v[70:71], v[58:59], v[64:65]
	v_pk_add_f32 v[58:59], v[58:59], v[64:65] neg_lo:[0,1] neg_hi:[0,1]
	v_pk_add_f32 v[64:65], v[42:43], v[44:45] op_sel:[0,1] op_sel_hi:[1,0] neg_hi:[0,1]
	v_pk_add_f32 v[42:43], v[42:43], v[44:45] op_sel:[0,1] op_sel_hi:[1,0] neg_lo:[0,1]
	v_mov_b32_e32 v45, v31
	v_mov_b32_e32 v44, v1
	ds_write_b64 v74, v[52:53]
	v_pk_mul_f32 v[52:53], v[66:67], v[44:45] op_sel:[0,0] op_sel_hi:[0,1]
	v_pk_fma_f32 v[52:53], v[66:67], v[44:45], v[52:53] op_sel:[1,1,0] op_sel_hi:[1,0,1] neg_lo:[0,1,0]
	ds_write_b64 v74, v[52:53] offset:2176
	v_pk_mul_f32 v[52:53], v[44:45], v[44:45] op_sel:[0,0] op_sel_hi:[0,1]
	v_pk_fma_f32 v[52:53], v[44:45], v[44:45], v[52:53] op_sel:[1,1,0] op_sel_hi:[1,0,1] neg_lo:[0,1,0]
	v_pk_mul_f32 v[66:67], v[68:69], v[52:53] op_sel:[0,0] op_sel_hi:[0,1]
	v_pk_fma_f32 v[66:67], v[68:69], v[52:53], v[66:67] op_sel:[1,1,0] op_sel_hi:[1,0,1] neg_lo:[0,1,0]
	ds_write_b64 v74, v[66:67] offset:4352
	v_pk_mul_f32 v[66:67], v[52:53], v[44:45] op_sel:[0,0] op_sel_hi:[0,1]
	v_pk_fma_f32 v[52:53], v[52:53], v[44:45], v[66:67] op_sel:[1,1,0] op_sel_hi:[1,0,1] neg_lo:[0,1,0]
	v_pk_mul_f32 v[66:67], v[70:71], v[52:53] op_sel:[0,0] op_sel_hi:[0,1]
	v_pk_fma_f32 v[66:67], v[70:71], v[52:53], v[66:67] op_sel:[1,1,0] op_sel_hi:[1,0,1] neg_lo:[0,1,0]
	ds_write_b64 v74, v[66:67] offset:6528
	v_pk_mul_f32 v[66:67], v[52:53], v[44:45] op_sel:[0,0] op_sel_hi:[0,1]
	v_pk_fma_f32 v[52:53], v[52:53], v[44:45], v[66:67] op_sel:[1,1,0] op_sel_hi:[1,0,1] neg_lo:[0,1,0]
	v_pk_mul_f32 v[66:67], v[72:73], v[52:53] op_sel:[0,0] op_sel_hi:[0,1]
	v_pk_fma_f32 v[66:67], v[72:73], v[52:53], v[66:67] op_sel:[1,1,0] op_sel_hi:[1,0,1] neg_lo:[0,1,0]
	ds_write_b64 v74, v[66:67] offset:8704
	v_pk_mul_f32 v[66:67], v[52:53], v[44:45] op_sel:[0,0] op_sel_hi:[0,1]
	v_pk_fma_f32 v[52:53], v[52:53], v[44:45], v[66:67] op_sel:[1,1,0] op_sel_hi:[1,0,1] neg_lo:[0,1,0]
	v_pk_mul_f32 v[66:67], v[62:63], v[52:53] op_sel:[0,0] op_sel_hi:[0,1]
	v_pk_fma_f32 v[62:63], v[62:63], v[52:53], v[66:67] op_sel:[1,1,0] op_sel_hi:[1,0,1] neg_lo:[0,1,0]
	ds_write_b64 v74, v[62:63] offset:10880
	v_pk_mul_f32 v[62:63], v[52:53], v[44:45] op_sel:[0,0] op_sel_hi:[0,1]
	v_pk_fma_f32 v[52:53], v[52:53], v[44:45], v[62:63] op_sel:[1,1,0] op_sel_hi:[1,0,1] neg_lo:[0,1,0]
	v_pk_mul_f32 v[62:63], v[60:61], v[52:53] op_sel:[0,0] op_sel_hi:[0,1]
	v_pk_fma_f32 v[60:61], v[60:61], v[52:53], v[62:63] op_sel:[1,1,0] op_sel_hi:[1,0,1] neg_lo:[0,1,0]
	ds_write_b64 v74, v[60:61] offset:13056
	v_pk_mul_f32 v[60:61], v[52:53], v[44:45] op_sel:[0,0] op_sel_hi:[0,1]
	v_pk_fma_f32 v[52:53], v[52:53], v[44:45], v[60:61] op_sel:[1,1,0] op_sel_hi:[1,0,1] neg_lo:[0,1,0]
	v_pk_mul_f32 v[60:61], v[64:65], v[52:53] op_sel:[0,0] op_sel_hi:[0,1]
	v_pk_fma_f32 v[60:61], v[64:65], v[52:53], v[60:61] op_sel:[1,1,0] op_sel_hi:[1,0,1] neg_lo:[0,1,0]
	ds_write_b64 v74, v[60:61] offset:15232
	v_pk_mul_f32 v[60:61], v[52:53], v[44:45] op_sel:[0,0] op_sel_hi:[0,1]
	v_pk_fma_f32 v[52:53], v[52:53], v[44:45], v[60:61] op_sel:[1,1,0] op_sel_hi:[1,0,1] neg_lo:[0,1,0]
	v_pk_mul_f32 v[60:61], v[54:55], v[52:53] op_sel:[0,0] op_sel_hi:[0,1]
	v_pk_fma_f32 v[54:55], v[54:55], v[52:53], v[60:61] op_sel:[1,1,0] op_sel_hi:[1,0,1] neg_lo:[0,1,0]
	ds_write_b64 v74, v[54:55] offset:17408
	v_pk_mul_f32 v[54:55], v[52:53], v[44:45] op_sel:[0,0] op_sel_hi:[0,1]
	v_pk_fma_f32 v[52:53], v[52:53], v[44:45], v[54:55] op_sel:[1,1,0] op_sel_hi:[1,0,1] neg_lo:[0,1,0]
	v_pk_mul_f32 v[54:55], v[50:51], v[52:53] op_sel:[0,0] op_sel_hi:[0,1]
	v_pk_fma_f32 v[50:51], v[50:51], v[52:53], v[54:55] op_sel:[1,1,0] op_sel_hi:[1,0,1] neg_lo:[0,1,0]
	ds_write_b64 v74, v[50:51] offset:19584
	v_pk_mul_f32 v[50:51], v[52:53], v[44:45] op_sel:[0,0] op_sel_hi:[0,1]
	v_pk_fma_f32 v[50:51], v[52:53], v[44:45], v[50:51] op_sel:[1,1,0] op_sel_hi:[1,0,1] neg_lo:[0,1,0]
	v_pk_mul_f32 v[52:53], v[48:49], v[50:51] op_sel:[0,0] op_sel_hi:[0,1]
	v_pk_fma_f32 v[48:49], v[48:49], v[50:51], v[52:53] op_sel:[1,1,0] op_sel_hi:[1,0,1] neg_lo:[0,1,0]
	ds_write_b64 v74, v[48:49] offset:21760
	v_pk_mul_f32 v[48:49], v[50:51], v[44:45] op_sel:[0,0] op_sel_hi:[0,1]
	v_pk_fma_f32 v[48:49], v[50:51], v[44:45], v[48:49] op_sel:[1,1,0] op_sel_hi:[1,0,1] neg_lo:[0,1,0]
	v_pk_mul_f32 v[50:51], v[58:59], v[48:49] op_sel:[0,0] op_sel_hi:[0,1]
	v_pk_fma_f32 v[50:51], v[58:59], v[48:49], v[50:51] op_sel:[1,1,0] op_sel_hi:[1,0,1] neg_lo:[0,1,0]
	ds_write_b64 v74, v[50:51] offset:23936
	v_pk_mul_f32 v[50:51], v[48:49], v[44:45] op_sel:[0,0] op_sel_hi:[0,1]
	v_pk_fma_f32 v[48:49], v[48:49], v[44:45], v[50:51] op_sel:[1,1,0] op_sel_hi:[1,0,1] neg_lo:[0,1,0]
	v_pk_mul_f32 v[50:51], v[40:41], v[48:49] op_sel:[0,0] op_sel_hi:[0,1]
	v_pk_fma_f32 v[40:41], v[40:41], v[48:49], v[50:51] op_sel:[1,1,0] op_sel_hi:[1,0,1] neg_lo:[0,1,0]
	ds_write_b64 v74, v[40:41] offset:26112
	v_pk_mul_f32 v[40:41], v[48:49], v[44:45] op_sel:[0,0] op_sel_hi:[0,1]
	v_pk_fma_f32 v[40:41], v[48:49], v[44:45], v[40:41] op_sel:[1,1,0] op_sel_hi:[1,0,1] neg_lo:[0,1,0]
	v_pk_mul_f32 v[48:49], v[56:57], v[40:41] op_sel:[0,0] op_sel_hi:[0,1]
	v_pk_fma_f32 v[48:49], v[56:57], v[40:41], v[48:49] op_sel:[1,1,0] op_sel_hi:[1,0,1] neg_lo:[0,1,0]
	ds_write_b64 v74, v[48:49] offset:28288
	v_pk_mul_f32 v[48:49], v[40:41], v[44:45] op_sel:[0,0] op_sel_hi:[0,1]
	v_pk_fma_f32 v[40:41], v[40:41], v[44:45], v[48:49] op_sel:[1,1,0] op_sel_hi:[1,0,1] neg_lo:[0,1,0]
	v_pk_mul_f32 v[48:49], v[46:47], v[40:41] op_sel:[0,0] op_sel_hi:[0,1]
	v_pk_fma_f32 v[46:47], v[46:47], v[40:41], v[48:49] op_sel:[1,1,0] op_sel_hi:[1,0,1] neg_lo:[0,1,0]
	ds_write_b64 v74, v[46:47] offset:30464
	v_pk_mul_f32 v[46:47], v[40:41], v[44:45] op_sel:[0,0] op_sel_hi:[0,1]
	v_pk_fma_f32 v[40:41], v[40:41], v[44:45], v[46:47] op_sel:[1,1,0] op_sel_hi:[1,0,1] neg_lo:[0,1,0]
	v_pk_mul_f32 v[44:45], v[42:43], v[40:41] op_sel:[0,0] op_sel_hi:[0,1]
	v_pk_fma_f32 v[40:41], v[42:43], v[40:41], v[44:45] op_sel:[1,1,0] op_sel_hi:[1,0,1] neg_lo:[0,1,0]
	ds_write_b64 v74, v[40:41] offset:32640
	s_waitcnt lgkmcnt(0)
	s_barrier
	ds_read2_b64 v[40:43], v39 offset1:17
	ds_read2_b64 v[44:47], v39 offset0:34 offset1:51
	ds_read2_b64 v[48:51], v39 offset0:68 offset1:85
	ds_read2_b64 v[52:55], v39 offset0:136 offset1:153
	ds_read2_b64 v[56:59], v39 offset0:102 offset1:119
	ds_read2_b64 v[60:63], v39 offset0:204 offset1:221
	ds_read2_b64 v[64:67], v39 offset0:170 offset1:187
	ds_read2_b64 v[68:71], v39 offset0:238 offset1:255
	s_waitcnt lgkmcnt(4)
	v_pk_add_f32 v[72:73], v[40:41], v[52:53]
	v_pk_add_f32 v[40:41], v[40:41], v[52:53] neg_lo:[0,1] neg_hi:[0,1]
	s_waitcnt lgkmcnt(2)
	v_pk_add_f32 v[52:53], v[48:49], v[60:61]
	v_pk_add_f32 v[48:49], v[48:49], v[60:61] neg_lo:[0,1] neg_hi:[0,1]
	v_pk_add_f32 v[60:61], v[72:73], v[52:53]
	v_pk_add_f32 v[52:53], v[72:73], v[52:53] neg_lo:[0,1] neg_hi:[0,1]
	v_pk_add_f32 v[72:73], v[40:41], v[48:49] op_sel:[0,1] op_sel_hi:[1,0] neg_hi:[0,1]
	v_pk_add_f32 v[40:41], v[40:41], v[48:49] op_sel:[0,1] op_sel_hi:[1,0] neg_lo:[0,1]
	v_pk_add_f32 v[48:49], v[42:43], v[54:55]
	v_pk_add_f32 v[42:43], v[42:43], v[54:55] neg_lo:[0,1] neg_hi:[0,1]
	v_pk_add_f32 v[54:55], v[50:51], v[62:63]
	v_pk_add_f32 v[50:51], v[50:51], v[62:63] neg_lo:[0,1] neg_hi:[0,1]
	v_pk_add_f32 v[62:63], v[48:49], v[54:55]
	v_pk_add_f32 v[48:49], v[48:49], v[54:55] neg_lo:[0,1] neg_hi:[0,1]
	v_pk_add_f32 v[54:55], v[42:43], v[50:51] op_sel:[0,1] op_sel_hi:[1,0] neg_hi:[0,1]
	v_pk_add_f32 v[42:43], v[42:43], v[50:51] op_sel:[0,1] op_sel_hi:[1,0] neg_lo:[0,1]
	s_waitcnt lgkmcnt(1)
	v_pk_add_f32 v[50:51], v[44:45], v[64:65]
	v_pk_add_f32 v[44:45], v[44:45], v[64:65] neg_lo:[0,1] neg_hi:[0,1]
	s_waitcnt lgkmcnt(0)
	v_pk_add_f32 v[64:65], v[56:57], v[68:69]
	v_pk_add_f32 v[56:57], v[56:57], v[68:69] neg_lo:[0,1] neg_hi:[0,1]
	v_pk_add_f32 v[68:69], v[50:51], v[64:65]
	v_pk_add_f32 v[50:51], v[50:51], v[64:65] neg_lo:[0,1] neg_hi:[0,1]
	v_pk_add_f32 v[64:65], v[44:45], v[56:57] op_sel:[0,1] op_sel_hi:[1,0] neg_hi:[0,1]
	v_pk_add_f32 v[44:45], v[44:45], v[56:57] op_sel:[0,1] op_sel_hi:[1,0] neg_lo:[0,1]
	v_pk_add_f32 v[56:57], v[46:47], v[66:67]
	v_pk_add_f32 v[46:47], v[46:47], v[66:67] neg_lo:[0,1] neg_hi:[0,1]
	v_pk_add_f32 v[66:67], v[58:59], v[70:71]
	v_pk_add_f32 v[58:59], v[58:59], v[70:71] neg_lo:[0,1] neg_hi:[0,1]
	v_pk_add_f32 v[70:71], v[56:57], v[66:67]
	v_pk_add_f32 v[56:57], v[56:57], v[66:67] neg_lo:[0,1] neg_hi:[0,1]
	v_pk_add_f32 v[66:67], v[46:47], v[58:59] op_sel:[0,1] op_sel_hi:[1,0] neg_hi:[0,1]
	v_pk_add_f32 v[46:47], v[46:47], v[58:59] op_sel:[0,1] op_sel_hi:[1,0] neg_lo:[0,1]
	v_pk_mul_f32 v[58:59], v[54:55], v[24:25] op_sel:[0,0] op_sel_hi:[0,1]
	v_pk_fma_f32 v[54:55], v[54:55], v[24:25], v[58:59] op_sel:[1,1,0] op_sel_hi:[1,0,1] neg_lo:[0,1,0]
	v_pk_mul_f32 v[58:59], v[64:65], v[20:21] op_sel:[0,0] op_sel_hi:[0,1]
	v_pk_fma_f32 v[58:59], v[64:65], v[20:21], v[58:59] op_sel:[1,1,0] op_sel_hi:[1,0,1] neg_lo:[0,1,0]
	v_pk_mul_f32 v[64:65], v[66:67], v[18:19] op_sel:[0,0] op_sel_hi:[0,1]
	v_pk_fma_f32 v[64:65], v[66:67], v[18:19], v[64:65] op_sel:[1,1,0] op_sel_hi:[1,0,1] neg_lo:[0,1,0]
	v_pk_mul_f32 v[66:67], v[48:49], v[20:21] op_sel:[0,0] op_sel_hi:[0,1]
	v_pk_fma_f32 v[48:49], v[48:49], v[20:21], v[66:67] op_sel:[1,1,0] op_sel_hi:[1,0,1] neg_lo:[0,1,0]
	v_pk_mul_f32 v[66:67], v[50:51], v[26:27] op_sel:[0,0] op_sel_hi:[0,1]
	v_pk_fma_f32 v[50:51], v[50:51], v[26:27], v[66:67] op_sel:[1,1,0] op_sel_hi:[1,0,1] neg_lo:[0,1,0]
	v_pk_mul_f32 v[66:67], v[56:57], v[22:23] op_sel:[0,0] op_sel_hi:[0,1]
	v_pk_fma_f32 v[56:57], v[56:57], v[22:23], v[66:67] op_sel:[1,1,0] op_sel_hi:[1,0,1] neg_lo:[0,1,0]
	v_pk_mul_f32 v[66:67], v[42:43], v[18:19] op_sel:[0,0] op_sel_hi:[0,1]
	v_pk_fma_f32 v[42:43], v[42:43], v[18:19], v[66:67] op_sel:[1,1,0] op_sel_hi:[1,0,1] neg_lo:[0,1,0]
	v_pk_mul_f32 v[66:67], v[44:45], v[22:23] op_sel:[0,0] op_sel_hi:[0,1]
	v_pk_fma_f32 v[44:45], v[44:45], v[22:23], v[66:67] op_sel:[1,1,0] op_sel_hi:[1,0,1] neg_lo:[0,1,0]
	v_pk_mul_f32 v[66:67], v[46:47], v[28:29] op_sel:[0,0] op_sel_hi:[0,1]
	v_pk_fma_f32 v[46:47], v[46:47], v[28:29], v[66:67] op_sel:[1,1,0] op_sel_hi:[1,0,1] neg_lo:[0,1,0]
	v_pk_add_f32 v[66:67], v[60:61], v[68:69]
	v_pk_add_f32 v[60:61], v[60:61], v[68:69] neg_lo:[0,1] neg_hi:[0,1]
	v_pk_add_f32 v[68:69], v[62:63], v[70:71]
	v_pk_add_f32 v[62:63], v[62:63], v[70:71] neg_lo:[0,1] neg_hi:[0,1]
	v_pk_add_f32 v[70:71], v[66:67], v[68:69]
	v_pk_add_f32 v[66:67], v[66:67], v[68:69] neg_lo:[0,1] neg_hi:[0,1]
	v_pk_add_f32 v[68:69], v[60:61], v[62:63] op_sel:[0,1] op_sel_hi:[1,0] neg_hi:[0,1]
	v_pk_add_f32 v[60:61], v[60:61], v[62:63] op_sel:[0,1] op_sel_hi:[1,0] neg_lo:[0,1]
	v_pk_add_f32 v[62:63], v[72:73], v[58:59]
	v_pk_add_f32 v[58:59], v[72:73], v[58:59] neg_lo:[0,1] neg_hi:[0,1]
	v_pk_add_f32 v[72:73], v[54:55], v[64:65]
	v_pk_add_f32 v[54:55], v[54:55], v[64:65] neg_lo:[0,1] neg_hi:[0,1]
	v_pk_add_f32 v[64:65], v[62:63], v[72:73]
	v_pk_add_f32 v[62:63], v[62:63], v[72:73] neg_lo:[0,1] neg_hi:[0,1]
	v_pk_add_f32 v[72:73], v[58:59], v[54:55] op_sel:[0,1] op_sel_hi:[1,0] neg_hi:[0,1]
	v_pk_add_f32 v[54:55], v[58:59], v[54:55] op_sel:[0,1] op_sel_hi:[1,0] neg_lo:[0,1]
	v_pk_add_f32 v[58:59], v[52:53], v[50:51]
	v_pk_add_f32 v[50:51], v[52:53], v[50:51] neg_lo:[0,1] neg_hi:[0,1]
	v_pk_add_f32 v[52:53], v[48:49], v[56:57]
	v_pk_add_f32 v[48:49], v[48:49], v[56:57] neg_lo:[0,1] neg_hi:[0,1]
	v_pk_add_f32 v[56:57], v[58:59], v[52:53]
	v_pk_add_f32 v[52:53], v[58:59], v[52:53] neg_lo:[0,1] neg_hi:[0,1]
	v_pk_add_f32 v[58:59], v[50:51], v[48:49] op_sel:[0,1] op_sel_hi:[1,0] neg_hi:[0,1]
	v_pk_add_f32 v[48:49], v[50:51], v[48:49] op_sel:[0,1] op_sel_hi:[1,0] neg_lo:[0,1]
	v_pk_add_f32 v[50:51], v[40:41], v[44:45]
	v_pk_add_f32 v[40:41], v[40:41], v[44:45] neg_lo:[0,1] neg_hi:[0,1]
	v_pk_add_f32 v[44:45], v[42:43], v[46:47]
	v_pk_add_f32 v[42:43], v[42:43], v[46:47] neg_lo:[0,1] neg_hi:[0,1]
	v_pk_add_f32 v[46:47], v[50:51], v[44:45]
	v_pk_add_f32 v[44:45], v[50:51], v[44:45] neg_lo:[0,1] neg_hi:[0,1]
	v_pk_add_f32 v[50:51], v[40:41], v[42:43] op_sel:[0,1] op_sel_hi:[1,0] neg_hi:[0,1]
	v_pk_add_f32 v[40:41], v[40:41], v[42:43] op_sel:[0,1] op_sel_hi:[1,0] neg_lo:[0,1]
	v_mov_b32_e32 v42, v30
	v_mov_b32_e32 v43, v32
	s_nop 0
	v_pk_mul_f32 v[74:75], v[64:65], v[42:43] op_sel:[0,0] op_sel_hi:[0,1]
	v_pk_fma_f32 v[64:65], v[64:65], v[42:43], v[74:75] op_sel:[1,1,0] op_sel_hi:[1,0,1] neg_lo:[0,1,0]
	ds_write2_b64 v39, v[70:71], v[64:65] offset1:17
	v_pk_mul_f32 v[64:65], v[42:43], v[42:43] op_sel:[0,0] op_sel_hi:[0,1]
	v_pk_fma_f32 v[64:65], v[42:43], v[42:43], v[64:65] op_sel:[1,1,0] op_sel_hi:[1,0,1] neg_lo:[0,1,0]
	v_pk_mul_f32 v[70:71], v[56:57], v[64:65] op_sel:[0,0] op_sel_hi:[0,1]
	v_pk_fma_f32 v[56:57], v[56:57], v[64:65], v[70:71] op_sel:[1,1,0] op_sel_hi:[1,0,1] neg_lo:[0,1,0]
	v_pk_mul_f32 v[70:71], v[64:65], v[42:43] op_sel:[0,0] op_sel_hi:[0,1]
	v_pk_fma_f32 v[64:65], v[64:65], v[42:43], v[70:71] op_sel:[1,1,0] op_sel_hi:[1,0,1] neg_lo:[0,1,0]
	v_pk_mul_f32 v[70:71], v[46:47], v[64:65] op_sel:[0,0] op_sel_hi:[0,1]
	v_pk_fma_f32 v[46:47], v[46:47], v[64:65], v[70:71] op_sel:[1,1,0] op_sel_hi:[1,0,1] neg_lo:[0,1,0]
	ds_write2_b64 v39, v[56:57], v[46:47] offset0:34 offset1:51
	v_pk_mul_f32 v[46:47], v[64:65], v[42:43] op_sel:[0,0] op_sel_hi:[0,1]
	v_pk_fma_f32 v[46:47], v[64:65], v[42:43], v[46:47] op_sel:[1,1,0] op_sel_hi:[1,0,1] neg_lo:[0,1,0]
	v_pk_mul_f32 v[56:57], v[68:69], v[46:47] op_sel:[0,0] op_sel_hi:[0,1]
	v_pk_mul_f32 v[64:65], v[46:47], v[42:43] op_sel:[0,0] op_sel_hi:[0,1]
	v_pk_fma_f32 v[56:57], v[68:69], v[46:47], v[56:57] op_sel:[1,1,0] op_sel_hi:[1,0,1] neg_lo:[0,1,0]
	v_pk_fma_f32 v[46:47], v[46:47], v[42:43], v[64:65] op_sel:[1,1,0] op_sel_hi:[1,0,1] neg_lo:[0,1,0]
	v_pk_mul_f32 v[64:65], v[72:73], v[46:47] op_sel:[0,0] op_sel_hi:[0,1]
	v_pk_fma_f32 v[64:65], v[72:73], v[46:47], v[64:65] op_sel:[1,1,0] op_sel_hi:[1,0,1] neg_lo:[0,1,0]
	ds_write2_b64 v39, v[56:57], v[64:65] offset0:68 offset1:85
	v_pk_mul_f32 v[56:57], v[46:47], v[42:43] op_sel:[0,0] op_sel_hi:[0,1]
	v_pk_fma_f32 v[46:47], v[46:47], v[42:43], v[56:57] op_sel:[1,1,0] op_sel_hi:[1,0,1] neg_lo:[0,1,0]
	v_pk_mul_f32 v[56:57], v[58:59], v[46:47] op_sel:[0,0] op_sel_hi:[0,1]
	v_pk_fma_f32 v[56:57], v[58:59], v[46:47], v[56:57] op_sel:[1,1,0] op_sel_hi:[1,0,1] neg_lo:[0,1,0]
	v_pk_mul_f32 v[58:59], v[46:47], v[42:43] op_sel:[0,0] op_sel_hi:[0,1]
	v_pk_fma_f32 v[46:47], v[46:47], v[42:43], v[58:59] op_sel:[1,1,0] op_sel_hi:[1,0,1] neg_lo:[0,1,0]
	v_pk_mul_f32 v[58:59], v[50:51], v[46:47] op_sel:[0,0] op_sel_hi:[0,1]
	v_pk_fma_f32 v[50:51], v[50:51], v[46:47], v[58:59] op_sel:[1,1,0] op_sel_hi:[1,0,1] neg_lo:[0,1,0]
	ds_write2_b64 v39, v[56:57], v[50:51] offset0:102 offset1:119
	v_pk_mul_f32 v[50:51], v[46:47], v[42:43] op_sel:[0,0] op_sel_hi:[0,1]
	v_pk_fma_f32 v[46:47], v[46:47], v[42:43], v[50:51] op_sel:[1,1,0] op_sel_hi:[1,0,1] neg_lo:[0,1,0]
	v_pk_mul_f32 v[50:51], v[66:67], v[46:47] op_sel:[0,0] op_sel_hi:[0,1]
	v_pk_mul_f32 v[56:57], v[46:47], v[42:43] op_sel:[0,0] op_sel_hi:[0,1]
	v_pk_fma_f32 v[50:51], v[66:67], v[46:47], v[50:51] op_sel:[1,1,0] op_sel_hi:[1,0,1] neg_lo:[0,1,0]
	v_pk_fma_f32 v[46:47], v[46:47], v[42:43], v[56:57] op_sel:[1,1,0] op_sel_hi:[1,0,1] neg_lo:[0,1,0]
	v_pk_mul_f32 v[56:57], v[62:63], v[46:47] op_sel:[0,0] op_sel_hi:[0,1]
	v_pk_fma_f32 v[56:57], v[62:63], v[46:47], v[56:57] op_sel:[1,1,0] op_sel_hi:[1,0,1] neg_lo:[0,1,0]
	ds_write2_b64 v39, v[50:51], v[56:57] offset0:136 offset1:153
	v_pk_mul_f32 v[50:51], v[46:47], v[42:43] op_sel:[0,0] op_sel_hi:[0,1]
	v_pk_fma_f32 v[46:47], v[46:47], v[42:43], v[50:51] op_sel:[1,1,0] op_sel_hi:[1,0,1] neg_lo:[0,1,0]
	v_pk_mul_f32 v[50:51], v[52:53], v[46:47] op_sel:[0,0] op_sel_hi:[0,1]
	v_pk_fma_f32 v[50:51], v[52:53], v[46:47], v[50:51] op_sel:[1,1,0] op_sel_hi:[1,0,1] neg_lo:[0,1,0]
	v_pk_mul_f32 v[52:53], v[46:47], v[42:43] op_sel:[0,0] op_sel_hi:[0,1]
	v_pk_fma_f32 v[46:47], v[46:47], v[42:43], v[52:53] op_sel:[1,1,0] op_sel_hi:[1,0,1] neg_lo:[0,1,0]
	v_pk_mul_f32 v[52:53], v[44:45], v[46:47] op_sel:[0,0] op_sel_hi:[0,1]
	v_pk_fma_f32 v[44:45], v[44:45], v[46:47], v[52:53] op_sel:[1,1,0] op_sel_hi:[1,0,1] neg_lo:[0,1,0]
	ds_write2_b64 v39, v[50:51], v[44:45] offset0:170 offset1:187
	v_pk_mul_f32 v[44:45], v[46:47], v[42:43] op_sel:[0,0] op_sel_hi:[0,1]
	v_pk_fma_f32 v[44:45], v[46:47], v[42:43], v[44:45] op_sel:[1,1,0] op_sel_hi:[1,0,1] neg_lo:[0,1,0]
	v_pk_mul_f32 v[46:47], v[60:61], v[44:45] op_sel:[0,0] op_sel_hi:[0,1]
	v_pk_mul_f32 v[50:51], v[44:45], v[42:43] op_sel:[0,0] op_sel_hi:[0,1]
	v_pk_fma_f32 v[46:47], v[60:61], v[44:45], v[46:47] op_sel:[1,1,0] op_sel_hi:[1,0,1] neg_lo:[0,1,0]
	v_pk_fma_f32 v[44:45], v[44:45], v[42:43], v[50:51] op_sel:[1,1,0] op_sel_hi:[1,0,1] neg_lo:[0,1,0]
	v_pk_mul_f32 v[50:51], v[54:55], v[44:45] op_sel:[0,0] op_sel_hi:[0,1]
	v_pk_fma_f32 v[50:51], v[54:55], v[44:45], v[50:51] op_sel:[1,1,0] op_sel_hi:[1,0,1] neg_lo:[0,1,0]
	ds_write2_b64 v39, v[46:47], v[50:51] offset0:204 offset1:221
	v_pk_mul_f32 v[46:47], v[44:45], v[42:43] op_sel:[0,0] op_sel_hi:[0,1]
	v_pk_fma_f32 v[44:45], v[44:45], v[42:43], v[46:47] op_sel:[1,1,0] op_sel_hi:[1,0,1] neg_lo:[0,1,0]
	v_pk_mul_f32 v[46:47], v[48:49], v[44:45] op_sel:[0,0] op_sel_hi:[0,1]
	v_pk_fma_f32 v[46:47], v[48:49], v[44:45], v[46:47] op_sel:[1,1,0] op_sel_hi:[1,0,1] neg_lo:[0,1,0]
	v_pk_mul_f32 v[48:49], v[44:45], v[42:43] op_sel:[0,0] op_sel_hi:[0,1]
	v_pk_fma_f32 v[42:43], v[44:45], v[42:43], v[48:49] op_sel:[1,1,0] op_sel_hi:[1,0,1] neg_lo:[0,1,0]
	v_pk_mul_f32 v[44:45], v[40:41], v[42:43] op_sel:[0,0] op_sel_hi:[0,1]
	v_pk_fma_f32 v[40:41], v[40:41], v[42:43], v[44:45] op_sel:[1,1,0] op_sel_hi:[1,0,1] neg_lo:[0,1,0]
	ds_write2_b64 v39, v[46:47], v[40:41] offset0:238 offset1:255
	v_mad_u32_u24 v39, v34, s54, v35
	s_waitcnt lgkmcnt(0)
	s_barrier
	ds_read2_b64 v[40:43], v39 offset1:1
	ds_read2_b64 v[44:47], v39 offset0:2 offset1:3
	ds_read2_b64 v[48:51], v39 offset0:8 offset1:9
	ds_read2_b64 v[52:55], v39 offset0:4 offset1:5
	ds_read2_b64 v[56:59], v39 offset0:6 offset1:7
	ds_read2_b64 v[60:63], v39 offset0:12 offset1:13
	ds_read2_b64 v[64:67], v39 offset0:10 offset1:11
	ds_read2_b64 v[68:71], v39 offset0:14 offset1:15
	s_waitcnt lgkmcnt(5)
	v_pk_add_f32 v[72:73], v[40:41], v[48:49]
	v_pk_add_f32 v[40:41], v[40:41], v[48:49] neg_lo:[0,1] neg_hi:[0,1]
	s_waitcnt lgkmcnt(2)
	v_pk_add_f32 v[48:49], v[52:53], v[60:61]
	v_pk_add_f32 v[52:53], v[52:53], v[60:61] neg_lo:[0,1] neg_hi:[0,1]
	v_pk_add_f32 v[60:61], v[72:73], v[48:49]
	v_pk_add_f32 v[48:49], v[72:73], v[48:49] neg_lo:[0,1] neg_hi:[0,1]
	v_pk_add_f32 v[72:73], v[40:41], v[52:53] op_sel:[0,1] op_sel_hi:[1,0] neg_hi:[0,1]
	v_pk_add_f32 v[40:41], v[40:41], v[52:53] op_sel:[0,1] op_sel_hi:[1,0] neg_lo:[0,1]
	v_pk_add_f32 v[52:53], v[42:43], v[50:51]
	v_pk_add_f32 v[42:43], v[42:43], v[50:51] neg_lo:[0,1] neg_hi:[0,1]
	v_pk_add_f32 v[50:51], v[54:55], v[62:63]
	v_pk_add_f32 v[54:55], v[54:55], v[62:63] neg_lo:[0,1] neg_hi:[0,1]
	v_pk_add_f32 v[62:63], v[52:53], v[50:51]
	v_pk_add_f32 v[50:51], v[52:53], v[50:51] neg_lo:[0,1] neg_hi:[0,1]
	v_pk_add_f32 v[52:53], v[42:43], v[54:55] op_sel:[0,1] op_sel_hi:[1,0] neg_hi:[0,1]
	v_pk_add_f32 v[42:43], v[42:43], v[54:55] op_sel:[0,1] op_sel_hi:[1,0] neg_lo:[0,1]
	s_waitcnt lgkmcnt(1)
	v_pk_add_f32 v[54:55], v[44:45], v[64:65]
	v_pk_add_f32 v[44:45], v[44:45], v[64:65] neg_lo:[0,1] neg_hi:[0,1]
	s_waitcnt lgkmcnt(0)
	v_pk_add_f32 v[64:65], v[56:57], v[68:69]
	v_pk_add_f32 v[56:57], v[56:57], v[68:69] neg_lo:[0,1] neg_hi:[0,1]
	v_pk_add_f32 v[68:69], v[54:55], v[64:65]
	v_pk_add_f32 v[54:55], v[54:55], v[64:65] neg_lo:[0,1] neg_hi:[0,1]
	v_pk_add_f32 v[64:65], v[44:45], v[56:57] op_sel:[0,1] op_sel_hi:[1,0] neg_hi:[0,1]
	v_pk_add_f32 v[44:45], v[44:45], v[56:57] op_sel:[0,1] op_sel_hi:[1,0] neg_lo:[0,1]
	v_pk_add_f32 v[56:57], v[46:47], v[66:67]
	v_pk_add_f32 v[46:47], v[46:47], v[66:67] neg_lo:[0,1] neg_hi:[0,1]
	v_pk_add_f32 v[66:67], v[58:59], v[70:71]
	v_pk_add_f32 v[58:59], v[58:59], v[70:71] neg_lo:[0,1] neg_hi:[0,1]
	v_pk_add_f32 v[70:71], v[56:57], v[66:67]
	v_pk_add_f32 v[56:57], v[56:57], v[66:67] neg_lo:[0,1] neg_hi:[0,1]
	v_pk_add_f32 v[66:67], v[46:47], v[58:59] op_sel:[0,1] op_sel_hi:[1,0] neg_hi:[0,1]
	v_pk_add_f32 v[46:47], v[46:47], v[58:59] op_sel:[0,1] op_sel_hi:[1,0] neg_lo:[0,1]
	v_pk_mul_f32 v[58:59], v[52:53], v[24:25] op_sel:[0,0] op_sel_hi:[0,1]
	v_pk_fma_f32 v[24:25], v[52:53], v[24:25], v[58:59] op_sel:[1,1,0] op_sel_hi:[1,0,1] neg_lo:[0,1,0]
	v_pk_mul_f32 v[52:53], v[64:65], v[20:21] op_sel:[0,0] op_sel_hi:[0,1]
	v_pk_mul_f32 v[58:59], v[66:67], v[18:19] op_sel:[0,0] op_sel_hi:[0,1]
	s_barrier
	v_pk_fma_f32 v[52:53], v[64:65], v[20:21], v[52:53] op_sel:[1,1,0] op_sel_hi:[1,0,1] neg_lo:[0,1,0]
	v_pk_mul_f32 v[64:65], v[50:51], v[20:21] op_sel:[0,0] op_sel_hi:[0,1]
	v_pk_fma_f32 v[58:59], v[66:67], v[18:19], v[58:59] op_sel:[1,1,0] op_sel_hi:[1,0,1] neg_lo:[0,1,0]
	v_pk_fma_f32 v[20:21], v[50:51], v[20:21], v[64:65] op_sel:[1,1,0] op_sel_hi:[1,0,1] neg_lo:[0,1,0]
	v_pk_mul_f32 v[50:51], v[54:55], v[26:27] op_sel:[0,0] op_sel_hi:[0,1]
	v_pk_fma_f32 v[26:27], v[54:55], v[26:27], v[50:51] op_sel:[1,1,0] op_sel_hi:[1,0,1] neg_lo:[0,1,0]
	v_pk_mul_f32 v[50:51], v[56:57], v[22:23] op_sel:[0,0] op_sel_hi:[0,1]
	v_pk_mul_f32 v[54:55], v[42:43], v[18:19] op_sel:[0,0] op_sel_hi:[0,1]
	v_pk_fma_f32 v[18:19], v[42:43], v[18:19], v[54:55] op_sel:[1,1,0] op_sel_hi:[1,0,1] neg_lo:[0,1,0]
	v_pk_mul_f32 v[42:43], v[44:45], v[22:23] op_sel:[0,0] op_sel_hi:[0,1]
	v_pk_fma_f32 v[50:51], v[56:57], v[22:23], v[50:51] op_sel:[1,1,0] op_sel_hi:[1,0,1] neg_lo:[0,1,0]
	v_pk_add_f32 v[54:55], v[24:25], v[58:59] neg_lo:[0,1] neg_hi:[0,1]
	v_pk_fma_f32 v[22:23], v[44:45], v[22:23], v[42:43] op_sel:[1,1,0] op_sel_hi:[1,0,1] neg_lo:[0,1,0]
	v_pk_mul_f32 v[42:43], v[46:47], v[28:29] op_sel:[0,0] op_sel_hi:[0,1]
	v_pk_add_f32 v[44:45], v[62:63], v[70:71] neg_lo:[0,1] neg_hi:[0,1]
	v_pk_fma_f32 v[28:29], v[46:47], v[28:29], v[42:43] op_sel:[1,1,0] op_sel_hi:[1,0,1] neg_lo:[0,1,0]
	v_pk_add_f32 v[42:43], v[60:61], v[68:69] neg_lo:[0,1] neg_hi:[0,1]
	v_pk_add_f32 v[74:75], v[18:19], v[28:29] neg_lo:[0,1] neg_hi:[0,1]
	v_pk_add_f32 v[46:47], v[42:43], v[44:45] op_sel:[0,1] op_sel_hi:[1,0] neg_hi:[0,1]
	v_pk_add_f32 v[42:43], v[42:43], v[44:45] op_sel:[0,1] op_sel_hi:[1,0] neg_lo:[0,1]
	v_pk_add_f32 v[44:45], v[72:73], v[52:53] neg_lo:[0,1] neg_hi:[0,1]
	v_and_b32_e32 v19, 0xf0, v36
	v_pk_add_f32 v[56:57], v[44:45], v[54:55] op_sel:[0,1] op_sel_hi:[1,0] neg_hi:[0,1]
	v_pk_add_f32 v[44:45], v[44:45], v[54:55] op_sel:[0,1] op_sel_hi:[1,0] neg_lo:[0,1]
	v_pk_add_f32 v[54:55], v[48:49], v[26:27] neg_lo:[0,1] neg_hi:[0,1]
	v_pk_add_f32 v[64:65], v[20:21], v[50:51] neg_lo:[0,1] neg_hi:[0,1]
	v_mul_i32_i24_e32 v21, 0xfffff804, v38
	v_lshlrev_b32_e32 v19, 2, v19
	v_pk_add_f32 v[66:67], v[54:55], v[64:65] op_sel:[0,1] op_sel_hi:[1,0] neg_hi:[0,1]
	v_pk_add_f32 v[54:55], v[54:55], v[64:65] op_sel:[0,1] op_sel_hi:[1,0] neg_lo:[0,1]
	v_pk_add_f32 v[64:65], v[40:41], v[22:23] neg_lo:[0,1] neg_hi:[0,1]
	v_add3_u32 v19, v78, v21, v19
	v_add_f32_e32 v21, v62, v70
	v_add_f32_e32 v23, v60, v68
	v_add_f32_e32 v24, v24, v58
	v_add_f32_e32 v27, v72, v52
	v_add_f32_e32 v25, v23, v21
	v_add_f32_e32 v29, v27, v24
	v_mul_f32_e32 v25, 0x3a800000, v25
	v_mul_f32_e32 v29, 0x3a800000, v29
	ds_write2st64_b32 v19, v25, v29 offset1:4
	v_add_f32_e32 v20, v20, v50
	v_add_f32_e32 v25, v48, v26
	v_add_f32_e32 v18, v18, v28
	v_add_f32_e32 v22, v40, v22
	v_add_f32_e32 v26, v25, v20
	v_add_f32_e32 v28, v22, v18
	v_sub_f32_e32 v20, v25, v20
	v_sub_f32_e32 v18, v22, v18
	v_mul_f32_e32 v26, 0x3a800000, v26
	v_mul_f32_e32 v28, 0x3a800000, v28
	v_mul_f32_e32 v20, 0x3a800000, v20
	v_mul_f32_e32 v18, 0x3a800000, v18
	ds_write2st64_b32 v19, v26, v28 offset0:8 offset1:12
	v_mul_f32_e32 v26, 0x3a800000, v46
	v_mul_f32_e32 v28, 0x3a800000, v56
	v_sub_f32_e32 v21, v23, v21
	v_sub_f32_e32 v23, v27, v24
	ds_write2st64_b32 v19, v20, v18 offset0:40 offset1:44
	v_mul_f32_e32 v18, 0x3a800000, v42
	v_mul_f32_e32 v20, 0x3a800000, v44
	v_pk_add_f32 v[76:77], v[64:65], v[74:75] op_sel:[0,1] op_sel_hi:[1,0] neg_hi:[0,1]
	v_pk_add_f32 v[64:65], v[64:65], v[74:75] op_sel:[0,1] op_sel_hi:[1,0] neg_lo:[0,1]
	ds_write2st64_b32 v19, v26, v28 offset0:16 offset1:20
	v_mul_f32_e32 v26, 0x3a800000, v66
	v_mul_f32_e32 v28, 0x3a800000, v76
	v_mul_f32_e32 v21, 0x3a800000, v21
	v_mul_f32_e32 v23, 0x3a800000, v23
	ds_write2st64_b32 v19, v18, v20 offset0:48 offset1:52
	v_mul_f32_e32 v18, 0x3a800000, v54
	v_mul_f32_e32 v20, 0x3a800000, v64
	v_mov_b32_e32 v22, v34
	ds_write2st64_b32 v19, v26, v28 offset0:24 offset1:28
	ds_write2st64_b32 v19, v21, v23 offset0:32 offset1:36
	ds_write2st64_b32 v19, v18, v20 offset0:56 offset1:60
	s_waitcnt lgkmcnt(0)
	s_barrier
	v_lshlrev_b32_e32 v26, 12, v37
	v_lshl_add_u32 v23, v22, 5, v35
	ds_read_b128 v[18:21], v23
	v_lshlrev_b32_e32 v28, 3, v22
	ds_read_b128 v[22:25], v23 offset:16
	v_ashrrev_i32_e32 v27, 31, v26
	v_lshlrev_b64 v[26:27], 1, v[26:27]
	s_waitcnt lgkmcnt(1)
	v_bfe_u32 v29, v18, 16, 1
	v_add3_u32 v18, v18, v29, s55
	v_bfe_u32 v29, v19, 16, 1
	v_lshrrev_b32_e32 v18, 16, v18
	v_add3_u32 v19, v19, v29, s55
	v_and_or_b32 v18, v19, s56, v18
	v_cvt_pk_bf16_f32 v19, v20, v21
	s_waitcnt lgkmcnt(0)
	v_cvt_pk_bf16_f32 v20, v22, v23
	v_cvt_pk_bf16_f32 v21, v24, v25
	v_ashrrev_i32_e32 v29, 31, v28
	v_lshl_add_u64 v[22:23], v[28:29], 1, v[26:27]
	v_lshl_add_u64 v[22:23], s[6:7], 0, v[22:23]
	global_store_dwordx4 v[22:23], v[18:21], off
	s_nop 0
	v_lshl_add_u32 v22, v34, 5, v35
	ds_read_b128 v[18:21], v22 offset:8192
	ds_read_b128 v[22:25], v22 offset:8208
	v_lshl_add_u32 v28, v34, 3, v33
	s_waitcnt lgkmcnt(1)
	v_bfe_u32 v29, v18, 16, 1
	v_add3_u32 v18, v18, v29, s55
	v_bfe_u32 v29, v19, 16, 1
	v_lshrrev_b32_e32 v18, 16, v18
	v_add3_u32 v19, v19, v29, s55
	v_and_or_b32 v18, v19, s56, v18
	v_cvt_pk_bf16_f32 v19, v20, v21
	s_waitcnt lgkmcnt(0)
	v_cvt_pk_bf16_f32 v20, v22, v23
	v_cvt_pk_bf16_f32 v21, v24, v25
	v_ashrrev_i32_e32 v29, 31, v28
	v_lshl_add_u64 v[22:23], v[28:29], 1, v[26:27]
	v_lshl_add_u64 v[22:23], s[6:7], 0, v[22:23]
	s_add_u32 s6, s6, s20
	s_addc_u32 s7, s7, s21
	s_and_b64 vcc, exec, s[44:45]
	global_store_dwordx4 v[22:23], v[18:21], off
	s_barrier
	s_cbranch_vccnz .LBB0_3755

.LBB0_3805:
	s_or_b64 exec, exec, s[52:53]
	s_lshl_b64 s[52:53], s[50:51], 15
	v_ashrrev_i32_e32 v91, 6, v38
	s_add_u32 s28, s64, s52
	v_lshlrev_b32_e32 v50, 3, v91
	v_lshlrev_b32_e32 v34, 1, v34
	s_addc_u32 s29, s63, s53
	v_add_u32_e32 v90, 0, v34
	v_lshl_add_u64 v[54:55], s[28:29], 0, v[34:35]
	v_add_u32_e32 v34, s91, v50
	v_and_b32_e32 v34, 0xfffffef8, v34
	v_cmp_eq_u32_e32 vcc, 0, v34
	s_waitcnt vmcnt(25)
	v_lshlrev_b32_e32 v96, 16, v66
	v_and_b32_e32 v94, 0xffff0000, v66
	v_lshlrev_b32_e32 v97, 16, v67
	v_and_b32_e32 v95, 0xffff0000, v67
	v_lshlrev_b32_e32 v67, 16, v59
	v_lshlrev_b32_e32 v66, 16, v58
	v_and_b32_e32 v101, 0xffff0000, v59
	v_and_b32_e32 v100, 0xffff0000, v58
	s_waitcnt vmcnt(3)
	v_mov_b32_e32 v58, v2
	v_mov_b32_e32 v59, v4
	v_mov_b32_e32 v4, v3
	v_mov_b32_e32 v2, v30
	v_mov_b32_e32 v3, v32
	v_cndmask_b32_e64 v34, 1.0, 0, vcc
	v_lshlrev_b32_e32 v87, 16, v65
	v_lshlrev_b32_e32 v86, 16, v64
	v_and_b32_e32 v105, 0xffff0000, v65
	v_and_b32_e32 v104, 0xffff0000, v64
	v_pk_mul_f32 v[64:65], v[2:3], v[66:67]
	v_pk_mul_f32 v[102:103], v[58:59], v[86:87]
	v_pk_mul_f32 v[66:67], v[64:65], v[34:35] op_sel_hi:[1,0]
	v_mov_b32_e32 v64, v26
	v_mov_b32_e32 v65, v28
	v_lshlrev_b32_e32 v89, 16, v69
	v_lshlrev_b32_e32 v88, 16, v68
	v_and_b32_e32 v87, 0xffff0000, v69
	v_and_b32_e32 v86, 0xffff0000, v68
	v_pk_fma_f32 v[68:69], v[64:65], v[96:97], v[66:67]
	v_mov_b32_e32 v66, v18
	v_mov_b32_e32 v67, v20
	v_mov_b32_e32 v32, v31
	v_pk_fma_f32 v[106:107], v[66:67], v[88:89], v[68:69]
	v_mov_b32_e32 v68, v22
	v_mov_b32_e32 v69, v24
	v_pk_mul_f32 v[30:31], v[32:33], v[100:101]
	v_pk_add_f32 v[106:107], v[68:69], v[106:107]
	v_pk_mul_f32 v[30:31], v[30:31], v[34:35] op_sel_hi:[1,0]
	v_mov_b32_e32 v28, v27
	v_mul_f32_e32 v18, 0xbfb8aa3b, v106
	v_pk_fma_f32 v[26:27], v[28:29], v[94:95], v[30:31]
	v_mov_b32_e32 v20, v19
	v_exp_f32_e32 v22, v18
	v_pk_fma_f32 v[18:19], v[20:21], v[86:87], v[26:27]
	v_mov_b32_e32 v24, v23
	v_pk_add_f32 v[18:19], v[24:25], v[18:19]
	v_mul_f32_e32 v26, 0xbfb8aa3b, v107
	v_mul_f32_e32 v23, 0xbfb8aa3b, v18
	v_exp_f32_e32 v23, v23
	v_exp_f32_e32 v27, v26
	v_mul_f32_e32 v26, 0xbfb8aa3b, v19
	v_exp_f32_e32 v51, v26
	v_add_f32_e32 v23, 1.0, v23
	v_add_f32_e32 v22, 1.0, v22
	v_rcp_f32_e32 v26, v23
	v_add_f32_e32 v23, 1.0, v27
	v_rcp_f32_e32 v22, v22
	v_rcp_f32_e32 v23, v23
	v_add_f32_e32 v27, 1.0, v51
	v_rcp_f32_e32 v27, v27
	v_lshlrev_b32_e32 v93, 16, v81
	v_lshlrev_b32_e32 v92, 16, v80
	v_and_b32_e32 v101, 0xffff0000, v81
	v_and_b32_e32 v100, 0xffff0000, v80
	v_pk_mul_f32 v[80:81], v[106:107], v[22:23]
	v_pk_mul_f32 v[30:31], v[4:5], v[104:105]
	v_pk_mul_f32 v[104:105], v[18:19], v[26:27]
	v_cvt_pk_bf16_f32 v107, v81, v105
	v_cvt_pk_bf16_f32 v106, v80, v104
	v_pk_mul_f32 v[22:23], v[34:35], v[102:103] op_sel_hi:[0,1]
	s_waitcnt vmcnt(2)
	v_mov_b32_e32 v18, v14
	v_mov_b32_e32 v19, v16
	v_lshlrev_b32_e32 v84, 16, v82
	v_lshlrev_b32_e32 v85, 16, v83
	v_pk_fma_f32 v[26:27], v[18:19], v[92:93], v[22:23]
	s_waitcnt vmcnt(1)
	v_mov_b32_e32 v22, v10
	v_mov_b32_e32 v23, v12
	v_pk_fma_f32 v[102:103], v[22:23], v[84:85], v[26:27]
	s_waitcnt vmcnt(0)
	v_mov_b32_e32 v26, v6
	v_mov_b32_e32 v27, v8
	v_pk_mul_f32 v[30:31], v[34:35], v[30:31] op_sel_hi:[0,1]
	v_mov_b32_e32 v16, v15
	v_and_b32_e32 v82, 0xffff0000, v82
	v_and_b32_e32 v83, 0xffff0000, v83
	v_pk_add_f32 v[102:103], v[26:27], v[102:103]
	v_pk_fma_f32 v[14:15], v[16:17], v[100:101], v[30:31]
	v_mov_b32_e32 v12, v11
	v_mul_f32_e32 v6, 0xbfb8aa3b, v102
	v_pk_fma_f32 v[10:11], v[12:13], v[82:83], v[14:15]
	v_mov_b32_e32 v8, v7
	v_exp_f32_e32 v108, v6
	v_pk_add_f32 v[6:7], v[8:9], v[10:11]
	v_mul_f32_e32 v14, 0xbfb8aa3b, v103
	v_mul_f32_e32 v10, 0xbfb8aa3b, v6
	v_exp_f32_e32 v11, v10
	v_exp_f32_e32 v15, v14
	v_mul_f32_e32 v14, 0xbfb8aa3b, v7
	v_exp_f32_e32 v30, v14
	v_add_f32_e32 v11, 1.0, v11
	v_add_f32_e32 v10, 1.0, v108
	v_rcp_f32_e32 v14, v11
	v_add_f32_e32 v11, 1.0, v15
	v_rcp_f32_e32 v10, v10
	v_rcp_f32_e32 v11, v11
	v_add_f32_e32 v15, 1.0, v30
	v_rcp_f32_e32 v15, v15
	s_movk_i32 s28, 0x1080
	v_pk_mul_f32 v[10:11], v[102:103], v[10:11]
	v_mad_u64_u32 v[30:31], s[28:29], v91, s28, v[90:91]
	v_pk_mul_f32 v[10:11], v[10:11], s[48:49] op_sel_hi:[1,0]
	v_pk_mul_f32 v[6:7], v[6:7], v[14:15]
	v_pk_mul_f32 v[6:7], v[6:7], s[48:49] op_sel_hi:[1,0]
	v_cvt_pk_bf16_f32 v15, v11, v7
	v_cvt_pk_bf16_f32 v14, v10, v6
	s_add_i32 s54, 0, 0x1be00
	v_lshlrev_b32_e32 v34, 5, v91
	s_waitcnt lgkmcnt(0)
	s_barrier
	ds_write2st64_b64 v30, v[106:107], v[14:15] offset1:66
	v_add_u32_e32 v14, s54, v34
	ds_read_b32 v14, v14
	s_add_i32 s55, 0, 0x1bf00
	v_add_u32_e32 v15, s55, v34
	ds_read_b32 v102, v15
	v_ashrrev_i32_e32 v51, 31, v50
	s_waitcnt lgkmcnt(1)
	v_pk_mul_f32 v[30:31], v[80:81], v[14:15] op_sel_hi:[1,0]
	v_pk_mul_f32 v[14:15], v[104:105], v[14:15] op_sel_hi:[1,0]
	v_and_b32_sdwa v80, v31, v98 dst_sel:DWORD dst_unused:UNUSED_PAD src0_sel:WORD_1 src1_sel:DWORD
	v_and_b32_sdwa v81, v30, v98 dst_sel:DWORD dst_unused:UNUSED_PAD src0_sel:WORD_1 src1_sel:DWORD
	v_add3_u32 v30, v30, v81, s79
	v_add3_u32 v31, v31, v80, s79
	v_and_b32_sdwa v80, v15, v98 dst_sel:DWORD dst_unused:UNUSED_PAD src0_sel:WORD_1 src1_sel:DWORD
	v_and_b32_sdwa v81, v14, v98 dst_sel:DWORD dst_unused:UNUSED_PAD src0_sel:WORD_1 src1_sel:DWORD
	v_add3_u32 v15, v15, v80, s79
	v_add3_u32 v14, v14, v81, s79
	v_and_b32_e32 v15, 0xffff0000, v15
	v_and_b32_e32 v14, 0xffff0000, v14
	v_or_b32_sdwa v15, v15, v31 dst_sel:DWORD dst_unused:UNUSED_PAD src0_sel:DWORD src1_sel:WORD_1
	v_or_b32_sdwa v14, v14, v30 dst_sel:DWORD dst_unused:UNUSED_PAD src0_sel:DWORD src1_sel:WORD_1
	v_lshlrev_b64 v[30:31], 9, v[50:51]
	v_lshl_add_u64 v[30:31], v[54:55], 0, v[30:31]
	s_waitcnt lgkmcnt(0)
	v_mul_f32_e32 v10, v10, v102
	global_store_dwordx2 v[30:31], v[14:15], off
	v_bfe_u32 v14, v10, 16, 1
	v_add3_u32 v10, v10, v14, s79
	v_mov_b32_e32 v14, s80
	s_movk_i32 s28, 0x240
	v_mad_u32_u24 v51, v99, s28, v14
	v_lshl_add_u32 v14, v91, 4, v51
	v_mul_f32_e32 v6, v6, v102
	ds_write_b16_d16_hi v14, v10
	v_bfe_u32 v10, v6, 16, 1
	v_add3_u32 v6, v6, v10, s79
	ds_write_b16_d16_hi v14, v6 offset:144
	v_mul_f32_e32 v6, v11, v102
	v_bfe_u32 v10, v6, 16, 1
	v_add3_u32 v6, v6, v10, s79
	ds_write_b16_d16_hi v14, v6 offset:288
	v_mul_f32_e32 v6, v7, v102
	v_bfe_u32 v7, v6, 16, 1
	v_add3_u32 v6, v6, v7, s79
	ds_write_b16_d16_hi v14, v6 offset:432
	v_pk_mul_f32 v[6:7], v[64:65], v[88:89]
	v_lshlrev_b32_e32 v81, 16, v79
	v_lshlrev_b32_e32 v80, 16, v78
	v_pk_fma_f32 v[6:7], v[2:3], v[96:97], v[6:7]
	v_pk_mul_f32 v[14:15], v[28:29], v[86:87]
	v_and_b32_e32 v79, 0xffff0000, v79
	v_and_b32_e32 v78, 0xffff0000, v78
	v_pk_fma_f32 v[6:7], v[66:67], v[80:81], v[6:7]
	v_pk_fma_f32 v[14:15], v[32:33], v[94:95], v[14:15]
	v_pk_add_f32 v[6:7], v[68:69], v[6:7]
	v_pk_fma_f32 v[14:15], v[20:21], v[78:79], v[14:15]
	v_mul_f32_e32 v11, 0xbfb8aa3b, v6
	v_pk_add_f32 v[94:95], v[24:25], v[14:15]
	v_exp_f32_e32 v11, v11
	v_mul_f32_e32 v14, 0xbfb8aa3b, v94
	v_exp_f32_e32 v15, v14
	v_mul_f32_e32 v31, 0xbfb8aa3b, v95
	v_add_f32_e32 v11, 1.0, v11
	v_rcp_f32_e32 v96, v11
	v_add_f32_e32 v11, 1.0, v15
	v_mul_f32_e32 v15, 0xbfb8aa3b, v7
	v_exp_f32_e32 v15, v15
	v_exp_f32_e32 v31, v31
	v_rcp_f32_e32 v102, v11
	v_lshlrev_b32_e32 v10, 16, v76
	v_add_f32_e32 v11, 1.0, v15
	v_rcp_f32_e32 v97, v11
	v_add_f32_e32 v11, 1.0, v31
	v_rcp_f32_e32 v103, v11
	v_and_b32_e32 v14, 0xffff0000, v76
	v_lshlrev_b32_e32 v11, 16, v77
	v_and_b32_e32 v15, 0xffff0000, v77
	v_pk_mul_f32 v[94:95], v[94:95], v[102:103]
	v_pk_mul_f32 v[76:77], v[6:7], v[96:97]
	v_cvt_pk_bf16_f32 v97, v77, v95
	v_cvt_pk_bf16_f32 v96, v76, v94
	v_pk_mul_f32 v[6:7], v[18:19], v[84:85]
	v_or_b32_e32 v30, 1, v50
	v_pk_fma_f32 v[6:7], v[58:59], v[92:93], v[6:7]
	v_and_b32_e32 v39, 15, v38
	v_pk_fma_f32 v[6:7], v[22:23], v[10:11], v[6:7]
	s_nop 0
	v_pk_add_f32 v[92:93], v[26:27], v[6:7]
	s_nop 0
	v_mul_f32_e32 v6, 0xbfb8aa3b, v92
	v_exp_f32_e32 v31, v6
	v_pk_mul_f32 v[6:7], v[16:17], v[82:83]
	s_nop 0
	v_pk_fma_f32 v[6:7], v[4:5], v[100:101], v[6:7]
	s_nop 0
	v_pk_fma_f32 v[6:7], v[12:13], v[14:15], v[6:7]
	s_nop 0
	v_pk_add_f32 v[100:101], v[8:9], v[6:7]
	s_nop 0
	v_mul_f32_e32 v6, 0xbfb8aa3b, v100
	v_exp_f32_e32 v91, v6
	s_nop 0
	v_mad_u64_u32 v[6:7], s[28:29], v30, s81, v[90:91]
	v_add_f32_e32 v7, 1.0, v31
	v_mul_f32_e32 v31, 0xbfb8aa3b, v93
	v_rcp_f32_e32 v90, v7
	v_add_f32_e32 v7, 1.0, v91
	v_exp_f32_e32 v31, v31
	v_mul_f32_e32 v91, 0xbfb8aa3b, v101
	v_exp_f32_e32 v103, v91
	v_rcp_f32_e32 v102, v7
	v_add_f32_e32 v7, 1.0, v31
	v_rcp_f32_e32 v91, v7
	v_add_f32_e32 v7, 1.0, v103
	v_rcp_f32_e32 v103, v7
	ds_write_b64 v6, v[96:97]
	v_pk_mul_f32 v[90:91], v[92:93], v[90:91]
	s_mov_b32 s28, 0xffffff0
	v_pk_mul_f32 v[92:93], v[100:101], v[102:103]
	v_pk_mul_f32 v[90:91], v[90:91], s[48:49] op_sel_hi:[1,0]
	v_pk_mul_f32 v[92:93], v[92:93], s[48:49] op_sel_hi:[1,0]
	v_cvt_pk_bf16_f32 v97, v91, v93
	v_cvt_pk_bf16_f32 v96, v90, v92
	ds_write_b64 v6, v[96:97] offset:33792
	v_lshlrev_b32_e32 v97, 2, v30
	v_add_u32_e32 v7, s54, v97
	ds_read_b32 v96, v7
	v_add_u32_e32 v97, s55, v97
	ds_read_b32 v100, v97
	v_ashrrev_i32_e32 v31, 31, v30
	v_mul_u32_u24_e32 v7, 0x240, v99
	s_waitcnt lgkmcnt(1)
	v_pk_mul_f32 v[76:77], v[76:77], v[96:97] op_sel_hi:[1,0]
	v_pk_mul_f32 v[94:95], v[94:95], v[96:97] op_sel_hi:[1,0]
	v_and_b32_sdwa v96, v77, v98 dst_sel:DWORD dst_unused:UNUSED_PAD src0_sel:WORD_1 src1_sel:DWORD
	v_and_b32_sdwa v97, v76, v98 dst_sel:DWORD dst_unused:UNUSED_PAD src0_sel:WORD_1 src1_sel:DWORD
	v_add3_u32 v76, v76, v97, s79
	v_add3_u32 v77, v77, v96, s79
	v_and_b32_sdwa v96, v95, v98 dst_sel:DWORD dst_unused:UNUSED_PAD src0_sel:WORD_1 src1_sel:DWORD
	v_and_b32_sdwa v97, v94, v98 dst_sel:DWORD dst_unused:UNUSED_PAD src0_sel:WORD_1 src1_sel:DWORD
	v_add3_u32 v95, v95, v96, s79
	v_add3_u32 v94, v94, v97, s79
	v_and_b32_e32 v95, 0xffff0000, v95
	v_and_b32_e32 v94, 0xffff0000, v94
	v_or_b32_sdwa v95, v95, v77 dst_sel:DWORD dst_unused:UNUSED_PAD src0_sel:DWORD src1_sel:WORD_1
	v_or_b32_sdwa v94, v94, v76 dst_sel:DWORD dst_unused:UNUSED_PAD src0_sel:DWORD src1_sel:WORD_1
	v_lshlrev_b64 v[76:77], 9, v[30:31]
	s_waitcnt lgkmcnt(0)
	v_mul_f32_e32 v31, v90, v100
	v_lshl_add_u64 v[96:97], v[54:55], 0, v[76:77]
	v_lshlrev_b32_e32 v30, 1, v30
	v_bfe_u32 v76, v31, 16, 1
	v_add3_u32 v31, v31, v76, s79
	v_add_u32_e32 v76, v51, v30
	ds_write_b16_d16_hi v76, v31
	v_mul_f32_e32 v31, v92, v100
	v_bfe_u32 v76, v31, 16, 1
	v_add3_u32 v31, v31, v76, s79
	v_add3_u32 v30, s80, v30, v7
	ds_write_b16_d16_hi v30, v31 offset:144
	v_mul_f32_e32 v31, v91, v100
	v_bfe_u32 v76, v31, 16, 1
	v_add3_u32 v31, v31, v76, s79
	ds_write_b16_d16_hi v30, v31 offset:288
	v_mul_f32_e32 v31, v93, v100
	v_pk_mul_f32 v[92:93], v[64:65], v[80:81]
	v_lshlrev_b32_e32 v91, 16, v75
	v_lshlrev_b32_e32 v90, 16, v74
	v_pk_fma_f32 v[88:89], v[2:3], v[88:89], v[92:93]
	v_pk_mul_f32 v[92:93], v[28:29], v[78:79]
	v_bfe_u32 v76, v31, 16, 1
	v_and_b32_e32 v75, 0xffff0000, v75
	v_and_b32_e32 v74, 0xffff0000, v74
	v_pk_fma_f32 v[88:89], v[66:67], v[90:91], v[88:89]
	v_pk_fma_f32 v[86:87], v[32:33], v[86:87], v[92:93]
	v_add3_u32 v31, v31, v76, s79
	v_pk_add_f32 v[88:89], v[68:69], v[88:89]
	v_pk_fma_f32 v[86:87], v[20:21], v[74:75], v[86:87]
	ds_write_b16_d16_hi v30, v31 offset:432
	v_mul_f32_e32 v31, 0xbfb8aa3b, v88
	v_pk_add_f32 v[86:87], v[24:25], v[86:87]
	v_exp_f32_e32 v31, v31
	v_mul_f32_e32 v77, 0xbfb8aa3b, v86
	v_exp_f32_e32 v77, v77
	v_mul_f32_e32 v93, 0xbfb8aa3b, v87
	v_add_f32_e32 v31, 1.0, v31
	v_rcp_f32_e32 v92, v31
	v_add_f32_e32 v31, 1.0, v77
	v_mul_f32_e32 v77, 0xbfb8aa3b, v89
	v_exp_f32_e32 v77, v77
	v_exp_f32_e32 v101, v93
	v_rcp_f32_e32 v100, v31
	v_lshlrev_b32_e32 v76, 16, v72
	v_add_f32_e32 v31, 1.0, v77
	v_rcp_f32_e32 v93, v31
	v_add_f32_e32 v31, 1.0, v101
	v_rcp_f32_e32 v101, v31
	v_lshlrev_b32_e32 v77, 16, v73
	v_pk_mul_f32 v[88:89], v[88:89], v[92:93]
	v_and_b32_e32 v72, 0xffff0000, v72
	v_pk_mul_f32 v[86:87], v[86:87], v[100:101]
	v_and_b32_e32 v73, 0xffff0000, v73
	v_pk_mul_f32 v[100:101], v[18:19], v[10:11]
	v_pk_fma_f32 v[84:85], v[58:59], v[84:85], v[100:101]
	v_pk_mul_f32 v[100:101], v[16:17], v[14:15]
	v_cvt_pk_bf16_f32 v93, v89, v87
	v_pk_fma_f32 v[84:85], v[22:23], v[76:77], v[84:85]
	v_pk_fma_f32 v[82:83], v[4:5], v[82:83], v[100:101]
	v_pk_add_f32 v[84:85], v[26:27], v[84:85]
	v_pk_fma_f32 v[82:83], v[12:13], v[72:73], v[82:83]
	v_mul_f32_e32 v31, 0xbfb8aa3b, v84
	v_pk_add_f32 v[82:83], v[8:9], v[82:83]
	v_exp_f32_e32 v31, v31
	v_mul_f32_e32 v100, 0xbfb8aa3b, v82
	v_exp_f32_e32 v101, v100
	v_cvt_pk_bf16_f32 v92, v88, v86
	v_add_f32_e32 v31, 1.0, v31
	v_rcp_f32_e32 v100, v31
	v_add_f32_e32 v31, 1.0, v101
	v_mul_f32_e32 v101, 0xbfb8aa3b, v85
	v_exp_f32_e32 v101, v101
	v_mul_f32_e32 v102, 0xbfb8aa3b, v83
	v_exp_f32_e32 v103, v102
	v_rcp_f32_e32 v102, v31
	v_add_f32_e32 v31, 1.0, v101
	v_rcp_f32_e32 v101, v31
	v_add_f32_e32 v31, 1.0, v103
	v_rcp_f32_e32 v103, v31
	ds_write_b64 v6, v[92:93] offset:528
	v_pk_mul_f32 v[84:85], v[84:85], v[100:101]
	v_or_b32_e32 v30, 2, v50
	v_pk_mul_f32 v[82:83], v[82:83], v[102:103]
	v_pk_mul_f32 v[84:85], v[84:85], s[48:49] op_sel_hi:[1,0]
	v_pk_mul_f32 v[82:83], v[82:83], s[48:49] op_sel_hi:[1,0]
	v_cvt_pk_bf16_f32 v93, v85, v83
	v_cvt_pk_bf16_f32 v92, v84, v82
	ds_write_b64 v6, v[92:93] offset:34320
	v_lshlrev_b32_e32 v93, 2, v30
	v_add_u32_e32 v31, s54, v93
	v_add_u32_e32 v93, s55, v93
	ds_read_b32 v92, v31
	ds_read_b32 v93, v93
	global_store_dwordx2 v[96:97], v[94:95], off
	v_ashrrev_i32_e32 v31, 31, v30
	s_waitcnt lgkmcnt(0)
	v_pk_mul_f32 v[88:89], v[88:89], v[92:93] op_sel_hi:[1,0]
	v_pk_mul_f32 v[86:87], v[86:87], v[92:93] op_sel_hi:[1,0]
	v_and_b32_sdwa v92, v89, v98 dst_sel:DWORD dst_unused:UNUSED_PAD src0_sel:WORD_1 src1_sel:DWORD
	v_and_b32_sdwa v94, v88, v98 dst_sel:DWORD dst_unused:UNUSED_PAD src0_sel:WORD_1 src1_sel:DWORD
	v_add3_u32 v88, v88, v94, s79
	v_add3_u32 v89, v89, v92, s79
	v_and_b32_sdwa v92, v87, v98 dst_sel:DWORD dst_unused:UNUSED_PAD src0_sel:WORD_1 src1_sel:DWORD
	v_and_b32_sdwa v94, v86, v98 dst_sel:DWORD dst_unused:UNUSED_PAD src0_sel:WORD_1 src1_sel:DWORD
	v_add3_u32 v87, v87, v92, s79
	v_add3_u32 v86, v86, v94, s79
	v_and_b32_e32 v87, 0xffff0000, v87
	v_and_b32_e32 v86, 0xffff0000, v86
	v_or_b32_sdwa v87, v87, v89 dst_sel:DWORD dst_unused:UNUSED_PAD src0_sel:DWORD src1_sel:WORD_1
	v_or_b32_sdwa v86, v86, v88 dst_sel:DWORD dst_unused:UNUSED_PAD src0_sel:DWORD src1_sel:WORD_1
	v_lshlrev_b64 v[88:89], 9, v[30:31]
	v_mul_f32_e32 v31, v84, v93
	v_lshlrev_b32_e32 v30, 1, v30
	v_bfe_u32 v84, v31, 16, 1
	v_add3_u32 v31, v31, v84, s79
	v_add_u32_e32 v84, v51, v30
	ds_write_b16_d16_hi v84, v31
	v_mul_f32_e32 v31, v82, v93
	v_bfe_u32 v82, v31, 16, 1
	v_add3_u32 v31, v31, v82, s79
	v_add3_u32 v30, s80, v30, v7
	ds_write_b16_d16_hi v30, v31 offset:144
	v_mul_f32_e32 v31, v85, v93
	v_bfe_u32 v82, v31, 16, 1
	v_add3_u32 v31, v31, v82, s79
	ds_write_b16_d16_hi v30, v31 offset:288
	v_mul_f32_e32 v31, v83, v93
	v_bfe_u32 v82, v31, 16, 1
	v_pk_mul_f32 v[92:93], v[64:65], v[90:91]
	v_add3_u32 v31, v31, v82, s79
	v_lshlrev_b32_e32 v83, 16, v71
	v_lshlrev_b32_e32 v82, 16, v70
	v_pk_fma_f32 v[80:81], v[2:3], v[80:81], v[92:93]
	v_pk_mul_f32 v[92:93], v[28:29], v[74:75]
	v_and_b32_e32 v71, 0xffff0000, v71
	v_and_b32_e32 v70, 0xffff0000, v70
	v_pk_fma_f32 v[80:81], v[66:67], v[82:83], v[80:81]
	v_pk_fma_f32 v[78:79], v[32:33], v[78:79], v[92:93]
	v_pk_add_f32 v[80:81], v[68:69], v[80:81]
	v_pk_fma_f32 v[78:79], v[20:21], v[70:71], v[78:79]
	ds_write_b16_d16_hi v30, v31 offset:432
	v_mul_f32_e32 v31, 0xbfb8aa3b, v80
	v_pk_add_f32 v[78:79], v[24:25], v[78:79]
	v_exp_f32_e32 v31, v31
	v_mul_f32_e32 v85, 0xbfb8aa3b, v78
	v_exp_f32_e32 v85, v85
	v_mul_f32_e32 v93, 0xbfb8aa3b, v79
	v_add_f32_e32 v31, 1.0, v31
	v_rcp_f32_e32 v92, v31
	v_add_f32_e32 v31, 1.0, v85
	v_mul_f32_e32 v85, 0xbfb8aa3b, v81
	v_exp_f32_e32 v85, v85
	v_exp_f32_e32 v95, v93
	v_rcp_f32_e32 v94, v31
	v_lshlrev_b32_e32 v30, 16, v62
	v_add_f32_e32 v31, 1.0, v85
	v_rcp_f32_e32 v93, v31
	v_add_f32_e32 v31, 1.0, v95
	v_rcp_f32_e32 v95, v31
	v_lshlrev_b32_e32 v31, 16, v63
	v_pk_mul_f32 v[80:81], v[80:81], v[92:93]
	v_and_b32_e32 v62, 0xffff0000, v62
	v_pk_mul_f32 v[78:79], v[78:79], v[94:95]
	v_and_b32_e32 v63, 0xffff0000, v63
	v_pk_mul_f32 v[94:95], v[18:19], v[76:77]
	v_pk_fma_f32 v[10:11], v[58:59], v[10:11], v[94:95]
	v_pk_mul_f32 v[94:95], v[16:17], v[72:73]
	v_cvt_pk_bf16_f32 v93, v81, v79
	v_pk_fma_f32 v[10:11], v[22:23], v[30:31], v[10:11]
	v_pk_fma_f32 v[14:15], v[4:5], v[14:15], v[94:95]
	v_pk_add_f32 v[10:11], v[26:27], v[10:11]
	v_pk_fma_f32 v[14:15], v[12:13], v[62:63], v[14:15]
	v_mul_f32_e32 v85, 0xbfb8aa3b, v10
	v_pk_add_f32 v[14:15], v[8:9], v[14:15]
	v_exp_f32_e32 v85, v85
	v_mul_f32_e32 v94, 0xbfb8aa3b, v14
	v_exp_f32_e32 v95, v94
	v_cvt_pk_bf16_f32 v92, v80, v78
	v_add_f32_e32 v85, 1.0, v85
	v_rcp_f32_e32 v94, v85
	v_add_f32_e32 v85, 1.0, v95
	v_mul_f32_e32 v95, 0xbfb8aa3b, v11
	v_exp_f32_e32 v95, v95
	v_mul_f32_e32 v96, 0xbfb8aa3b, v15
	v_exp_f32_e32 v97, v96
	v_rcp_f32_e32 v96, v85
	v_add_f32_e32 v85, 1.0, v95
	v_rcp_f32_e32 v95, v85
	v_add_f32_e32 v85, 1.0, v97
	v_rcp_f32_e32 v97, v85
	ds_write_b64 v6, v[92:93] offset:1056
	v_pk_mul_f32 v[10:11], v[10:11], v[94:95]
	v_or_b32_e32 v84, 3, v50
	v_pk_mul_f32 v[14:15], v[14:15], v[96:97]
	v_pk_mul_f32 v[10:11], v[10:11], s[48:49] op_sel_hi:[1,0]
	v_pk_mul_f32 v[14:15], v[14:15], s[48:49] op_sel_hi:[1,0]
	v_cvt_pk_bf16_f32 v93, v11, v15
	v_cvt_pk_bf16_f32 v92, v10, v14
	ds_write_b64 v6, v[92:93] offset:34848
	v_lshlrev_b32_e32 v93, 2, v84
	v_add_u32_e32 v85, s54, v93
	ds_read_b32 v92, v85
	v_lshl_add_u64 v[88:89], v[54:55], 0, v[88:89]
	global_store_dwordx2 v[88:89], v[86:87], off
	v_add_u32_e32 v86, s55, v93
	ds_read_b32 v88, v86
	s_waitcnt lgkmcnt(1)
	v_pk_mul_f32 v[80:81], v[80:81], v[92:93] op_sel_hi:[1,0]
	v_pk_mul_f32 v[78:79], v[78:79], v[92:93] op_sel_hi:[1,0]
	v_and_b32_sdwa v86, v81, v98 dst_sel:DWORD dst_unused:UNUSED_PAD src0_sel:WORD_1 src1_sel:DWORD
	v_and_b32_sdwa v87, v80, v98 dst_sel:DWORD dst_unused:UNUSED_PAD src0_sel:WORD_1 src1_sel:DWORD
	v_add3_u32 v80, v80, v87, s79
	v_add3_u32 v81, v81, v86, s79
	v_and_b32_sdwa v86, v79, v98 dst_sel:DWORD dst_unused:UNUSED_PAD src0_sel:WORD_1 src1_sel:DWORD
	v_and_b32_sdwa v87, v78, v98 dst_sel:DWORD dst_unused:UNUSED_PAD src0_sel:WORD_1 src1_sel:DWORD
	v_add3_u32 v79, v79, v86, s79
	v_add3_u32 v78, v78, v87, s79
	v_ashrrev_i32_e32 v85, 31, v84
	v_and_b32_e32 v79, 0xffff0000, v79
	v_and_b32_e32 v78, 0xffff0000, v78
	v_or_b32_sdwa v81, v79, v81 dst_sel:DWORD dst_unused:UNUSED_PAD src0_sel:DWORD src1_sel:WORD_1
	v_or_b32_sdwa v80, v78, v80 dst_sel:DWORD dst_unused:UNUSED_PAD src0_sel:DWORD src1_sel:WORD_1
	v_lshlrev_b64 v[78:79], 9, v[84:85]
	s_waitcnt lgkmcnt(0)
	v_mul_f32_e32 v10, v10, v88
	v_lshl_add_u64 v[86:87], v[54:55], 0, v[78:79]
	v_lshlrev_b32_e32 v78, 1, v84
	v_bfe_u32 v79, v10, 16, 1
	v_add3_u32 v10, v10, v79, s79
	v_add_u32_e32 v79, v51, v78
	ds_write_b16_d16_hi v79, v10
	v_mul_f32_e32 v10, v14, v88
	v_bfe_u32 v14, v10, 16, 1
	v_add3_u32 v10, v10, v14, s79
	v_add3_u32 v14, s80, v78, v7
	ds_write_b16_d16_hi v14, v10 offset:144
	v_mul_f32_e32 v10, v11, v88
	v_bfe_u32 v11, v10, 16, 1
	v_add3_u32 v10, v10, v11, s79
	v_pk_mul_f32 v[84:85], v[64:65], v[82:83]
	ds_write_b16_d16_hi v14, v10 offset:288
	v_mul_f32_e32 v10, v15, v88
	v_lshlrev_b32_e32 v79, 16, v61
	v_lshlrev_b32_e32 v78, 16, v60
	v_pk_fma_f32 v[84:85], v[2:3], v[90:91], v[84:85]
	v_pk_mul_f32 v[88:89], v[28:29], v[70:71]
	v_and_b32_e32 v61, 0xffff0000, v61
	v_and_b32_e32 v60, 0xffff0000, v60
	v_pk_fma_f32 v[84:85], v[66:67], v[78:79], v[84:85]
	v_pk_fma_f32 v[74:75], v[32:33], v[74:75], v[88:89]
	v_bfe_u32 v11, v10, 16, 1
	v_pk_add_f32 v[84:85], v[68:69], v[84:85]
	v_pk_fma_f32 v[74:75], v[20:21], v[60:61], v[74:75]
	v_add3_u32 v10, v10, v11, s79
	v_mul_f32_e32 v11, 0xbfb8aa3b, v84
	v_pk_add_f32 v[74:75], v[24:25], v[74:75]
	v_exp_f32_e32 v11, v11
	v_mul_f32_e32 v15, 0xbfb8aa3b, v74
	v_exp_f32_e32 v15, v15
	v_mul_f32_e32 v89, 0xbfb8aa3b, v75
	v_add_f32_e32 v11, 1.0, v11
	v_rcp_f32_e32 v88, v11
	v_add_f32_e32 v11, 1.0, v15
	v_mul_f32_e32 v15, 0xbfb8aa3b, v85
	v_exp_f32_e32 v15, v15
	v_exp_f32_e32 v91, v89
	v_rcp_f32_e32 v90, v11
	ds_write_b16_d16_hi v14, v10 offset:432
	v_add_f32_e32 v11, 1.0, v15
	v_rcp_f32_e32 v89, v11
	v_add_f32_e32 v11, 1.0, v91
	v_rcp_f32_e32 v91, v11
	v_lshlrev_b32_e32 v14, 16, v56
	v_lshlrev_b32_e32 v15, 16, v57
	v_pk_mul_f32 v[84:85], v[84:85], v[88:89]
	v_pk_mul_f32 v[74:75], v[74:75], v[90:91]
	v_and_b32_e32 v56, 0xffff0000, v56
	v_pk_mul_f32 v[90:91], v[18:19], v[30:31]
	v_pk_fma_f32 v[76:77], v[58:59], v[76:77], v[90:91]
	v_pk_mul_f32 v[90:91], v[16:17], v[62:63]
	v_and_b32_e32 v57, 0xffff0000, v57
	v_cvt_pk_bf16_f32 v89, v85, v75
	v_pk_fma_f32 v[76:77], v[22:23], v[14:15], v[76:77]
	v_pk_fma_f32 v[72:73], v[4:5], v[72:73], v[90:91]
	v_pk_add_f32 v[76:77], v[26:27], v[76:77]
	v_pk_fma_f32 v[72:73], v[12:13], v[56:57], v[72:73]
	v_mul_f32_e32 v11, 0xbfb8aa3b, v76
	v_pk_add_f32 v[72:73], v[8:9], v[72:73]
	v_exp_f32_e32 v11, v11
	v_mul_f32_e32 v90, 0xbfb8aa3b, v72
	v_exp_f32_e32 v91, v90
	v_cvt_pk_bf16_f32 v88, v84, v74
	v_add_f32_e32 v11, 1.0, v11
	v_rcp_f32_e32 v90, v11
	v_add_f32_e32 v11, 1.0, v91
	v_mul_f32_e32 v91, 0xbfb8aa3b, v77
	v_exp_f32_e32 v91, v91
	v_mul_f32_e32 v92, 0xbfb8aa3b, v73
	v_exp_f32_e32 v93, v92
	v_rcp_f32_e32 v92, v11
	v_add_f32_e32 v11, 1.0, v91
	v_rcp_f32_e32 v91, v11
	v_add_f32_e32 v11, 1.0, v93
	v_rcp_f32_e32 v93, v11
	ds_write_b64 v6, v[88:89] offset:1584
	v_pk_mul_f32 v[76:77], v[76:77], v[90:91]
	v_or_b32_e32 v10, 4, v50
	v_pk_mul_f32 v[72:73], v[72:73], v[92:93]
	v_pk_mul_f32 v[76:77], v[76:77], s[48:49] op_sel_hi:[1,0]
	v_pk_mul_f32 v[72:73], v[72:73], s[48:49] op_sel_hi:[1,0]
	v_cvt_pk_bf16_f32 v89, v77, v73
	v_cvt_pk_bf16_f32 v88, v76, v72
	ds_write_b64 v6, v[88:89] offset:35376
	v_lshlrev_b32_e32 v89, 2, v10
	v_add_u32_e32 v11, s54, v89
	ds_read_b32 v88, v11
	global_store_dwordx2 v[86:87], v[80:81], off
	v_add_u32_e32 v80, s55, v89
	ds_read_b32 v86, v80
	v_ashrrev_i32_e32 v11, 31, v10
	s_waitcnt lgkmcnt(1)
	v_pk_mul_f32 v[80:81], v[84:85], v[88:89] op_sel_hi:[1,0]
	v_pk_mul_f32 v[74:75], v[74:75], v[88:89] op_sel_hi:[1,0]
	v_and_b32_sdwa v84, v81, v98 dst_sel:DWORD dst_unused:UNUSED_PAD src0_sel:WORD_1 src1_sel:DWORD
	v_and_b32_sdwa v85, v80, v98 dst_sel:DWORD dst_unused:UNUSED_PAD src0_sel:WORD_1 src1_sel:DWORD
	v_add3_u32 v80, v80, v85, s79
	v_add3_u32 v81, v81, v84, s79
	v_and_b32_sdwa v84, v75, v98 dst_sel:DWORD dst_unused:UNUSED_PAD src0_sel:WORD_1 src1_sel:DWORD
	v_and_b32_sdwa v85, v74, v98 dst_sel:DWORD dst_unused:UNUSED_PAD src0_sel:WORD_1 src1_sel:DWORD
	v_add3_u32 v75, v75, v84, s79
	v_add3_u32 v74, v74, v85, s79
	v_and_b32_e32 v75, 0xffff0000, v75
	v_and_b32_e32 v74, 0xffff0000, v74
	v_or_b32_sdwa v75, v75, v81 dst_sel:DWORD dst_unused:UNUSED_PAD src0_sel:DWORD src1_sel:WORD_1
	v_or_b32_sdwa v74, v74, v80 dst_sel:DWORD dst_unused:UNUSED_PAD src0_sel:DWORD src1_sel:WORD_1
	v_lshlrev_b64 v[80:81], 9, v[10:11]
	s_waitcnt lgkmcnt(0)
	v_mul_f32_e32 v11, v76, v86
	v_lshlrev_b32_e32 v10, 1, v10
	v_bfe_u32 v76, v11, 16, 1
	v_add3_u32 v11, v11, v76, s79
	v_add_u32_e32 v76, v51, v10
	ds_write_b16_d16_hi v76, v11
	v_mul_f32_e32 v11, v72, v86
	v_bfe_u32 v72, v11, 16, 1
	v_add3_u32 v11, v11, v72, s79
	v_add3_u32 v10, s80, v10, v7
	ds_write_b16_d16_hi v10, v11 offset:144
	v_mul_f32_e32 v11, v77, v86
	v_bfe_u32 v72, v11, 16, 1
	v_add3_u32 v11, v11, v72, s79
	ds_write_b16_d16_hi v10, v11 offset:288
	v_mul_f32_e32 v11, v73, v86
	v_bfe_u32 v72, v11, 16, 1
	v_pk_mul_f32 v[84:85], v[64:65], v[78:79]
	v_add3_u32 v11, v11, v72, s79
	v_lshlrev_b32_e32 v73, 16, v53
	v_lshlrev_b32_e32 v72, 16, v52
	v_pk_fma_f32 v[82:83], v[2:3], v[82:83], v[84:85]
	v_pk_mul_f32 v[84:85], v[28:29], v[60:61]
	v_and_b32_e32 v53, 0xffff0000, v53
	v_and_b32_e32 v52, 0xffff0000, v52
	v_pk_fma_f32 v[82:83], v[66:67], v[72:73], v[82:83]
	v_pk_fma_f32 v[70:71], v[32:33], v[70:71], v[84:85]
	v_pk_add_f32 v[82:83], v[68:69], v[82:83]
	v_pk_fma_f32 v[70:71], v[20:21], v[52:53], v[70:71]
	ds_write_b16_d16_hi v10, v11 offset:432
	v_mul_f32_e32 v11, 0xbfb8aa3b, v82
	v_pk_add_f32 v[70:71], v[24:25], v[70:71]
	v_exp_f32_e32 v11, v11
	v_mul_f32_e32 v77, 0xbfb8aa3b, v70
	v_exp_f32_e32 v77, v77
	v_mul_f32_e32 v85, 0xbfb8aa3b, v71
	v_add_f32_e32 v11, 1.0, v11
	v_rcp_f32_e32 v84, v11
	v_add_f32_e32 v11, 1.0, v77
	v_mul_f32_e32 v77, 0xbfb8aa3b, v83
	v_exp_f32_e32 v77, v77
	v_exp_f32_e32 v87, v85
	v_rcp_f32_e32 v86, v11
	v_lshlrev_b32_e32 v10, 16, v48
	v_add_f32_e32 v11, 1.0, v77
	v_rcp_f32_e32 v85, v11
	v_add_f32_e32 v11, 1.0, v87
	v_rcp_f32_e32 v87, v11
	v_lshlrev_b32_e32 v11, 16, v49
	v_pk_mul_f32 v[82:83], v[82:83], v[84:85]
	v_and_b32_e32 v48, 0xffff0000, v48
	v_pk_mul_f32 v[70:71], v[70:71], v[86:87]
	v_and_b32_e32 v49, 0xffff0000, v49
	v_pk_mul_f32 v[86:87], v[18:19], v[14:15]
	v_pk_fma_f32 v[30:31], v[58:59], v[30:31], v[86:87]
	v_pk_mul_f32 v[86:87], v[16:17], v[56:57]
	v_cvt_pk_bf16_f32 v85, v83, v71
	v_pk_fma_f32 v[30:31], v[22:23], v[10:11], v[30:31]
	v_pk_fma_f32 v[62:63], v[4:5], v[62:63], v[86:87]
	v_pk_add_f32 v[30:31], v[26:27], v[30:31]
	v_pk_fma_f32 v[62:63], v[12:13], v[48:49], v[62:63]
	v_mul_f32_e32 v77, 0xbfb8aa3b, v30
	v_pk_add_f32 v[62:63], v[8:9], v[62:63]
	v_exp_f32_e32 v77, v77
	v_mul_f32_e32 v86, 0xbfb8aa3b, v62
	v_exp_f32_e32 v87, v86
	v_cvt_pk_bf16_f32 v84, v82, v70
	v_add_f32_e32 v77, 1.0, v77
	v_rcp_f32_e32 v86, v77
	v_add_f32_e32 v77, 1.0, v87
	v_mul_f32_e32 v87, 0xbfb8aa3b, v31
	v_exp_f32_e32 v87, v87
	v_mul_f32_e32 v88, 0xbfb8aa3b, v63
	v_exp_f32_e32 v89, v88
	v_rcp_f32_e32 v88, v77
	v_add_f32_e32 v77, 1.0, v87
	v_rcp_f32_e32 v87, v77
	v_add_f32_e32 v77, 1.0, v89
	v_rcp_f32_e32 v89, v77
	ds_write_b64 v6, v[84:85] offset:2112
	v_pk_mul_f32 v[30:31], v[30:31], v[86:87]
	v_or_b32_e32 v76, 5, v50
	v_pk_mul_f32 v[62:63], v[62:63], v[88:89]
	v_pk_mul_f32 v[30:31], v[30:31], s[48:49] op_sel_hi:[1,0]
	v_pk_mul_f32 v[62:63], v[62:63], s[48:49] op_sel_hi:[1,0]
	v_cvt_pk_bf16_f32 v85, v31, v63
	v_cvt_pk_bf16_f32 v84, v30, v62
	ds_write_b64 v6, v[84:85] offset:35904
	v_lshlrev_b32_e32 v85, 2, v76
	v_add_u32_e32 v77, s54, v85
	ds_read_b32 v84, v77
	v_lshl_add_u64 v[80:81], v[54:55], 0, v[80:81]
	global_store_dwordx2 v[80:81], v[74:75], off
	v_add_u32_e32 v74, s55, v85
	ds_read_b32 v80, v74
	s_waitcnt lgkmcnt(1)
	v_pk_mul_f32 v[74:75], v[82:83], v[84:85] op_sel_hi:[1,0]
	v_pk_mul_f32 v[70:71], v[70:71], v[84:85] op_sel_hi:[1,0]
	v_and_b32_sdwa v81, v75, v98 dst_sel:DWORD dst_unused:UNUSED_PAD src0_sel:WORD_1 src1_sel:DWORD
	v_and_b32_sdwa v82, v74, v98 dst_sel:DWORD dst_unused:UNUSED_PAD src0_sel:WORD_1 src1_sel:DWORD
	v_add3_u32 v74, v74, v82, s79
	v_add3_u32 v75, v75, v81, s79
	v_and_b32_sdwa v81, v71, v98 dst_sel:DWORD dst_unused:UNUSED_PAD src0_sel:WORD_1 src1_sel:DWORD
	v_and_b32_sdwa v82, v70, v98 dst_sel:DWORD dst_unused:UNUSED_PAD src0_sel:WORD_1 src1_sel:DWORD
	v_add3_u32 v71, v71, v81, s79
	v_add3_u32 v70, v70, v82, s79
	v_ashrrev_i32_e32 v77, 31, v76
	v_and_b32_e32 v71, 0xffff0000, v71
	v_and_b32_e32 v70, 0xffff0000, v70
	s_waitcnt lgkmcnt(0)
	v_mul_f32_e32 v30, v30, v80
	v_or_b32_sdwa v71, v71, v75 dst_sel:DWORD dst_unused:UNUSED_PAD src0_sel:DWORD src1_sel:WORD_1
	v_or_b32_sdwa v70, v70, v74 dst_sel:DWORD dst_unused:UNUSED_PAD src0_sel:DWORD src1_sel:WORD_1
	v_lshlrev_b64 v[74:75], 9, v[76:77]
	v_lshlrev_b32_e32 v76, 1, v76
	v_bfe_u32 v77, v30, 16, 1
	v_add3_u32 v30, v30, v77, s79
	v_add_u32_e32 v77, v51, v76
	ds_write_b16_d16_hi v77, v30
	v_mul_f32_e32 v30, v62, v80
	v_bfe_u32 v62, v30, 16, 1
	v_add3_u32 v30, v30, v62, s79
	v_add3_u32 v62, s80, v76, v7
	ds_write_b16_d16_hi v62, v30 offset:144
	v_mul_f32_e32 v30, v31, v80
	v_bfe_u32 v31, v30, 16, 1
	v_add3_u32 v30, v30, v31, s79
	ds_write_b16_d16_hi v62, v30 offset:288
	v_mul_f32_e32 v30, v63, v80
	v_pk_mul_f32 v[80:81], v[64:65], v[72:73]
	v_lshlrev_b32_e32 v77, 16, v47
	v_lshlrev_b32_e32 v76, 16, v46
	v_pk_fma_f32 v[78:79], v[2:3], v[78:79], v[80:81]
	v_pk_mul_f32 v[80:81], v[28:29], v[52:53]
	v_and_b32_e32 v47, 0xffff0000, v47
	v_and_b32_e32 v46, 0xffff0000, v46
	v_pk_fma_f32 v[78:79], v[66:67], v[76:77], v[78:79]
	v_pk_fma_f32 v[60:61], v[32:33], v[60:61], v[80:81]
	v_bfe_u32 v31, v30, 16, 1
	v_pk_add_f32 v[78:79], v[68:69], v[78:79]
	v_pk_fma_f32 v[60:61], v[20:21], v[46:47], v[60:61]
	v_add3_u32 v30, v30, v31, s79
	v_mul_f32_e32 v31, 0xbfb8aa3b, v78
	v_pk_add_f32 v[60:61], v[24:25], v[60:61]
	v_exp_f32_e32 v31, v31
	v_mul_f32_e32 v63, 0xbfb8aa3b, v60
	v_exp_f32_e32 v63, v63
	v_mul_f32_e32 v81, 0xbfb8aa3b, v61
	v_add_f32_e32 v31, 1.0, v31
	v_rcp_f32_e32 v80, v31
	v_add_f32_e32 v31, 1.0, v63
	v_mul_f32_e32 v63, 0xbfb8aa3b, v79
	v_exp_f32_e32 v63, v63
	v_exp_f32_e32 v83, v81
	v_rcp_f32_e32 v82, v31
	ds_write_b16_d16_hi v62, v30 offset:432
	v_add_f32_e32 v31, 1.0, v63
	v_rcp_f32_e32 v81, v31
	v_add_f32_e32 v31, 1.0, v83
	v_rcp_f32_e32 v83, v31
	v_lshlrev_b32_e32 v62, 16, v44
	v_lshlrev_b32_e32 v63, 16, v45
	v_pk_mul_f32 v[78:79], v[78:79], v[80:81]
	v_pk_mul_f32 v[60:61], v[60:61], v[82:83]
	v_and_b32_e32 v44, 0xffff0000, v44
	v_pk_mul_f32 v[82:83], v[18:19], v[10:11]
	v_pk_fma_f32 v[14:15], v[58:59], v[14:15], v[82:83]
	v_pk_mul_f32 v[82:83], v[16:17], v[48:49]
	v_and_b32_e32 v45, 0xffff0000, v45
	v_cvt_pk_bf16_f32 v81, v79, v61
	v_pk_fma_f32 v[14:15], v[22:23], v[62:63], v[14:15]
	v_pk_fma_f32 v[56:57], v[4:5], v[56:57], v[82:83]
	v_pk_add_f32 v[14:15], v[26:27], v[14:15]
	v_pk_fma_f32 v[56:57], v[12:13], v[44:45], v[56:57]
	v_mul_f32_e32 v31, 0xbfb8aa3b, v14
	v_pk_add_f32 v[56:57], v[8:9], v[56:57]
	v_exp_f32_e32 v31, v31
	v_mul_f32_e32 v82, 0xbfb8aa3b, v56
	v_exp_f32_e32 v83, v82
	v_cvt_pk_bf16_f32 v80, v78, v60
	v_add_f32_e32 v31, 1.0, v31
	v_rcp_f32_e32 v82, v31
	v_add_f32_e32 v31, 1.0, v83
	v_mul_f32_e32 v83, 0xbfb8aa3b, v15
	v_exp_f32_e32 v83, v83
	v_mul_f32_e32 v84, 0xbfb8aa3b, v57
	v_exp_f32_e32 v85, v84
	v_rcp_f32_e32 v84, v31
	v_add_f32_e32 v31, 1.0, v83
	v_rcp_f32_e32 v83, v31
	v_add_f32_e32 v31, 1.0, v85
	v_rcp_f32_e32 v85, v31
	ds_write_b64 v6, v[80:81] offset:2640
	v_pk_mul_f32 v[14:15], v[14:15], v[82:83]
	v_or_b32_e32 v30, 6, v50
	v_pk_mul_f32 v[56:57], v[56:57], v[84:85]
	v_pk_mul_f32 v[14:15], v[14:15], s[48:49] op_sel_hi:[1,0]
	v_pk_mul_f32 v[56:57], v[56:57], s[48:49] op_sel_hi:[1,0]
	v_cvt_pk_bf16_f32 v81, v15, v57
	v_cvt_pk_bf16_f32 v80, v14, v56
	ds_write_b64 v6, v[80:81] offset:36432
	v_lshlrev_b32_e32 v81, 2, v30
	v_add_u32_e32 v31, s54, v81
	ds_read_b32 v80, v31
	v_lshl_add_u64 v[74:75], v[54:55], 0, v[74:75]
	global_store_dwordx2 v[74:75], v[70:71], off
	v_add_u32_e32 v70, s55, v81
	ds_read_b32 v74, v70
	s_waitcnt lgkmcnt(1)
	v_pk_mul_f32 v[70:71], v[78:79], v[80:81] op_sel_hi:[1,0]
	v_pk_mul_f32 v[60:61], v[60:61], v[80:81] op_sel_hi:[1,0]
	v_and_b32_sdwa v75, v71, v98 dst_sel:DWORD dst_unused:UNUSED_PAD src0_sel:WORD_1 src1_sel:DWORD
	v_and_b32_sdwa v78, v70, v98 dst_sel:DWORD dst_unused:UNUSED_PAD src0_sel:WORD_1 src1_sel:DWORD
	v_add3_u32 v70, v70, v78, s79
	v_add3_u32 v71, v71, v75, s79
	v_and_b32_sdwa v75, v61, v98 dst_sel:DWORD dst_unused:UNUSED_PAD src0_sel:WORD_1 src1_sel:DWORD
	v_and_b32_sdwa v78, v60, v98 dst_sel:DWORD dst_unused:UNUSED_PAD src0_sel:WORD_1 src1_sel:DWORD
	v_add3_u32 v61, v61, v75, s79
	v_add3_u32 v60, v60, v78, s79
	v_ashrrev_i32_e32 v31, 31, v30
	v_and_b32_e32 v61, 0xffff0000, v61
	v_and_b32_e32 v60, 0xffff0000, v60
	s_waitcnt lgkmcnt(0)
	v_mul_f32_e32 v14, v14, v74
	v_or_b32_sdwa v61, v61, v71 dst_sel:DWORD dst_unused:UNUSED_PAD src0_sel:DWORD src1_sel:WORD_1
	v_or_b32_sdwa v60, v60, v70 dst_sel:DWORD dst_unused:UNUSED_PAD src0_sel:DWORD src1_sel:WORD_1
	v_lshlrev_b64 v[70:71], 9, v[30:31]
	v_lshlrev_b32_e32 v30, 1, v30
	v_bfe_u32 v31, v14, 16, 1
	v_add3_u32 v14, v14, v31, s79
	v_add_u32_e32 v31, v51, v30
	ds_write_b16_d16_hi v31, v14
	v_mul_f32_e32 v14, v56, v74
	v_bfe_u32 v31, v14, 16, 1
	v_add3_u32 v14, v14, v31, s79
	v_add3_u32 v30, s80, v30, v7
	ds_write_b16_d16_hi v30, v14 offset:144
	v_mul_f32_e32 v14, v15, v74
	v_bfe_u32 v15, v14, 16, 1
	v_add3_u32 v14, v14, v15, s79
	ds_write_b16_d16_hi v30, v14 offset:288
	v_mul_f32_e32 v14, v57, v74
	v_bfe_u32 v15, v14, 16, 1
	v_add3_u32 v14, v14, v15, s79
	ds_write_b16_d16_hi v30, v14 offset:432
	v_or_b32_e32 v14, 7, v50
	v_add_u32_e32 v15, s91, v14
	v_and_b32_e32 v15, 0xffffefff, v15
	v_cmp_eq_u32_e32 vcc, s82, v15
	v_lshlrev_b32_e32 v56, 16, v42
	v_lshlrev_b32_e32 v57, 16, v43
	v_pk_mul_f32 v[64:65], v[64:65], v[76:77]
	v_cndmask_b32_e64 v30, 1.0, 0, vcc
	v_and_b32_e32 v42, 0xffff0000, v42
	v_and_b32_e32 v43, 0xffff0000, v43
	v_pk_fma_f32 v[2:3], v[2:3], v[72:73], v[64:65]
	v_pk_mul_f32 v[56:57], v[66:67], v[56:57]
	v_pk_mul_f32 v[28:29], v[28:29], v[46:47]
	v_pk_fma_f32 v[2:3], v[56:57], v[30:31], v[2:3] op_sel_hi:[1,0,1]
	v_pk_fma_f32 v[28:29], v[32:33], v[52:53], v[28:29]
	v_pk_mul_f32 v[20:21], v[20:21], v[42:43]
	v_pk_add_f32 v[2:3], v[68:69], v[2:3]
	v_pk_fma_f32 v[20:21], v[20:21], v[30:31], v[28:29] op_sel_hi:[1,0,1]
	v_mul_f32_e32 v15, 0xbfb8aa3b, v2
	v_pk_add_f32 v[20:21], v[24:25], v[20:21]
	v_exp_f32_e32 v15, v15
	v_mul_f32_e32 v24, 0xbfb8aa3b, v20
	v_exp_f32_e32 v25, v24
	v_mul_f32_e32 v28, 0xbfb8aa3b, v21
	v_add_f32_e32 v15, 1.0, v15
	v_rcp_f32_e32 v24, v15
	v_add_f32_e32 v15, 1.0, v25
	v_mul_f32_e32 v25, 0xbfb8aa3b, v3
	v_exp_f32_e32 v25, v25
	v_exp_f32_e32 v29, v28
	v_rcp_f32_e32 v28, v15
	v_lshlrev_b32_e32 v75, 16, v41
	v_add_f32_e32 v15, 1.0, v25
	v_rcp_f32_e32 v25, v15
	v_add_f32_e32 v15, 1.0, v29
	v_rcp_f32_e32 v29, v15
	v_lshlrev_b32_e32 v74, 16, v40
	v_pk_mul_f32 v[18:19], v[18:19], v[62:63]
	v_pk_mul_f32 v[2:3], v[2:3], v[24:25]
	v_pk_mul_f32 v[20:21], v[20:21], v[28:29]
	v_pk_fma_f32 v[10:11], v[58:59], v[10:11], v[18:19]
	v_pk_mul_f32 v[18:19], v[22:23], v[74:75]
	v_and_b32_e32 v33, 0xffff0000, v41
	v_and_b32_e32 v32, 0xffff0000, v40
	v_cvt_pk_bf16_f32 v25, v3, v21
	v_pk_fma_f32 v[10:11], v[30:31], v[18:19], v[10:11] op_sel_hi:[0,1,1]
	v_pk_mul_f32 v[16:17], v[16:17], v[44:45]
	v_pk_add_f32 v[10:11], v[26:27], v[10:11]
	v_pk_fma_f32 v[4:5], v[4:5], v[48:49], v[16:17]
	v_pk_mul_f32 v[12:13], v[12:13], v[32:33]
	v_mul_f32_e32 v15, 0xbfb8aa3b, v10
	v_pk_fma_f32 v[4:5], v[30:31], v[12:13], v[4:5] op_sel_hi:[0,1,1]
	v_exp_f32_e32 v15, v15
	v_pk_add_f32 v[4:5], v[8:9], v[4:5]
	v_mul_f32_e32 v12, 0xbfb8aa3b, v11
	v_mul_f32_e32 v8, 0xbfb8aa3b, v4
	v_exp_f32_e32 v9, v8
	v_exp_f32_e32 v13, v12
	v_mul_f32_e32 v12, 0xbfb8aa3b, v5
	v_add_f32_e32 v8, 1.0, v15
	v_exp_f32_e32 v15, v12
	v_add_f32_e32 v9, 1.0, v9
	v_rcp_f32_e32 v12, v9
	v_add_f32_e32 v9, 1.0, v13
	v_rcp_f32_e32 v8, v8
	v_rcp_f32_e32 v9, v9
	v_add_f32_e32 v13, 1.0, v15
	v_rcp_f32_e32 v13, v13
	v_cvt_pk_bf16_f32 v24, v2, v20
	v_pk_mul_f32 v[8:9], v[10:11], v[8:9]
	v_pk_mul_f32 v[8:9], v[8:9], s[48:49] op_sel_hi:[1,0]
	v_pk_mul_f32 v[4:5], v[4:5], v[12:13]
	v_pk_mul_f32 v[4:5], v[4:5], s[48:49] op_sel_hi:[1,0]
	v_cvt_pk_bf16_f32 v11, v9, v5
	v_cvt_pk_bf16_f32 v10, v8, v4
	ds_write_b64 v6, v[10:11] offset:36960
	v_lshlrev_b32_e32 v10, 2, v14
	ds_write_b64 v6, v[24:25] offset:3168
	v_add_u32_e32 v6, s54, v10
	ds_read_b32 v6, v6
	v_add_u32_e32 v10, s55, v10
	ds_read_b32 v12, v10
	v_ashrrev_i32_e32 v15, 31, v14
	v_lshl_add_u64 v[70:71], v[54:55], 0, v[70:71]
	s_waitcnt lgkmcnt(1)
	v_pk_mul_f32 v[2:3], v[2:3], v[6:7] op_sel_hi:[1,0]
	v_pk_mul_f32 v[10:11], v[20:21], v[6:7] op_sel_hi:[1,0]
	v_and_b32_sdwa v13, v2, v98 dst_sel:DWORD dst_unused:UNUSED_PAD src0_sel:WORD_1 src1_sel:DWORD
	v_and_b32_sdwa v6, v3, v98 dst_sel:DWORD dst_unused:UNUSED_PAD src0_sel:WORD_1 src1_sel:DWORD
	v_add3_u32 v2, v2, v13, s79
	v_and_b32_sdwa v13, v10, v98 dst_sel:DWORD dst_unused:UNUSED_PAD src0_sel:WORD_1 src1_sel:DWORD
	v_add3_u32 v3, v3, v6, s79
	v_and_b32_sdwa v6, v11, v98 dst_sel:DWORD dst_unused:UNUSED_PAD src0_sel:WORD_1 src1_sel:DWORD
	v_add3_u32 v10, v10, v13, s79
	v_add3_u32 v6, v11, v6, s79
	v_and_b32_e32 v10, 0xffff0000, v10
	v_and_b32_e32 v6, 0xffff0000, v6
	v_or_b32_sdwa v2, v10, v2 dst_sel:DWORD dst_unused:UNUSED_PAD src0_sel:DWORD src1_sel:WORD_1
	v_lshlrev_b64 v[10:11], 9, v[14:15]
	v_or_b32_sdwa v3, v6, v3 dst_sel:DWORD dst_unused:UNUSED_PAD src0_sel:DWORD src1_sel:WORD_1
	v_lshl_add_u64 v[10:11], v[54:55], 0, v[10:11]
	global_store_dwordx2 v[10:11], v[2:3], off
	s_waitcnt lgkmcnt(0)
	v_mul_f32_e32 v3, v8, v12
	v_lshlrev_b32_e32 v2, 1, v14
	v_bfe_u32 v6, v3, 16, 1
	v_add3_u32 v3, v3, v6, s79
	v_add_u32_e32 v6, v51, v2
	ds_write_b16_d16_hi v6, v3
	v_mul_f32_e32 v3, v4, v12
	v_bfe_u32 v4, v3, 16, 1
	v_add3_u32 v3, v3, v4, s79
	v_add3_u32 v2, s80, v2, v7
	ds_write_b16_d16_hi v2, v3 offset:144
	v_mul_f32_e32 v3, v9, v12
	v_bfe_u32 v4, v3, 16, 1
	v_add3_u32 v3, v3, v4, s79
	ds_write_b16_d16_hi v2, v3 offset:288
	v_mul_f32_e32 v3, v5, v12
	v_bfe_u32 v4, v3, 16, 1
	v_add3_u32 v3, v3, v4, s79
	ds_write_b16_d16_hi v2, v3 offset:432
	v_and_b32_e32 v3, 48, v99
	v_and_or_b32 v2, v50, s28, v39
	v_add_u32_e32 v6, 0, v3
	v_mad_u64_u32 v[32:33], s[28:29], v2, s81, v[6:7]
	global_store_dwordx2 v[70:71], v[60:61], off
	s_waitcnt lgkmcnt(0)
	s_barrier
	ds_read_b128 v[2:5], v32
	v_and_or_b32 v10, v34, 32, v39
	v_mad_u32_u24 v11, v10, s81, v6
	ds_read_b128 v[12:15], v32 offset:64
	ds_read_b128 v[6:9], v11 offset:33792
	ds_read_b128 v[16:19], v11 offset:33856
	ds_read_b128 v[20:23], v32 offset:128
	s_waitcnt lgkmcnt(2)
	v_mfma_f32_16x16x32_bf16 v[6:9], v[2:5], v[6:9], 0
	s_add_i32 s28, 0, 0x1bd00
	s_waitcnt lgkmcnt(1)
	v_mfma_f32_16x16x32_bf16 v[6:9], v[12:15], v[16:19], v[6:9]
	ds_read_b128 v[16:19], v32 offset:192
	ds_read_b128 v[24:27], v11 offset:33920
	ds_read_b128 v[28:31], v11 offset:33984
	s_waitcnt lgkmcnt(1)
	v_mfma_f32_16x16x32_bf16 v[6:9], v[20:23], v[24:27], v[6:9]
	ds_read_b128 v[24:27], v32 offset:256
	s_waitcnt lgkmcnt(1)
	v_mfma_f32_16x16x32_bf16 v[6:9], v[16:19], v[28:31], v[6:9]
	ds_read_b128 v[28:31], v32 offset:320
	ds_read_b128 v[40:43], v11 offset:34048
	ds_read_b128 v[44:47], v11 offset:34112
	s_waitcnt lgkmcnt(1)
	v_mfma_f32_16x16x32_bf16 v[6:9], v[24:27], v[40:43], v[6:9]
	ds_read_b128 v[40:43], v32 offset:384
	s_waitcnt lgkmcnt(1)
	v_mfma_f32_16x16x32_bf16 v[6:9], v[28:31], v[44:47], v[6:9]
	ds_read_b128 v[44:47], v32 offset:448
	ds_read_b128 v[48:51], v11 offset:34176
	ds_read_b128 v[52:55], v11 offset:34240
	s_waitcnt lgkmcnt(1)
	v_mfma_f32_16x16x32_bf16 v[6:9], v[40:43], v[48:51], v[6:9]
	s_waitcnt lgkmcnt(0)
	v_mfma_f32_16x16x32_bf16 v[6:9], v[44:47], v[52:55], v[6:9]
	ds_read_b128 v[48:51], v11 offset:42240
	ds_read_b128 v[52:55], v11 offset:42304
	s_waitcnt lgkmcnt(1)
	v_mfma_f32_16x16x32_bf16 v[2:5], v[2:5], v[48:51], 0
	s_waitcnt lgkmcnt(0)
	v_mfma_f32_16x16x32_bf16 v[2:5], v[12:15], v[52:55], v[2:5]
	ds_read_b128 v[12:15], v11 offset:42368
	ds_read_b128 v[48:51], v11 offset:42432
	s_waitcnt lgkmcnt(1)
	v_mfma_f32_16x16x32_bf16 v[2:5], v[20:23], v[12:15], v[2:5]
	s_waitcnt lgkmcnt(0)
	v_mfma_f32_16x16x32_bf16 v[2:5], v[16:19], v[48:51], v[2:5]
	ds_read_b128 v[12:15], v11 offset:42496
	ds_read_b128 v[16:19], v11 offset:42560
	s_waitcnt lgkmcnt(1)
	v_mfma_f32_16x16x32_bf16 v[2:5], v[24:27], v[12:15], v[2:5]
	s_waitcnt lgkmcnt(0)
	v_mfma_f32_16x16x32_bf16 v[2:5], v[28:31], v[16:19], v[2:5]
	ds_read_b128 v[12:15], v11 offset:42624
	ds_read_b128 v[16:19], v11 offset:42688
	v_ashrrev_i32_e32 v11, 3, v38
	v_and_b32_e32 v11, -16, v11
	s_waitcnt lgkmcnt(1)
	v_mfma_f32_16x16x32_bf16 v[2:5], v[40:43], v[12:15], v[2:5]
	v_lshrrev_b32_e32 v12, 2, v99
	v_and_or_b32 v11, v12, 12, v11
	v_cmp_le_i32_e32 vcc, v10, v11
	s_waitcnt lgkmcnt(0)
	v_mfma_f32_16x16x32_bf16 v[2:5], v[44:47], v[16:19], v[2:5]
	v_mov_b32_e32 v15, 0
	v_cndmask_b32_e64 v12, 0, 1, vcc
	v_cmp_ge_i32_e32 vcc, v10, v11
	v_lshl_add_u32 v19, v10, 2, s28
	s_nop 0
	v_cndmask_b32_e64 v13, 0, 1, vcc
	v_cndmask_b32_e64 v12, v13, v12, s[6:7]
	v_and_b32_e32 v12, 1, v12
	v_cmp_eq_u32_e32 vcc, 1, v12
	v_lshl_add_u32 v12, v11, 2, 0
	v_mov_b32_e32 v13, 0
	s_and_saveexec_b64 s[54:55], vcc
	s_cbranch_execz .LBB0_3807
	v_add_u32_e32 v13, 0x1bc00, v12
	ds_read_b32 v13, v13
	ds_read_b32 v14, v19
	s_waitcnt lgkmcnt(0)
	v_add_f32_e32 v13, v13, v14
	v_mul_f32_e32 v13, 0x3fb8aa3b, v13
	v_exp_f32_e32 v13, v13
	s_nop 0
	v_mul_f32_e32 v13, v6, v13

.LBB0_3906:
	ds_read2_b32 v[20:21], v18 offset1:65
	ds_read2_b32 v[22:23], v18 offset0:130 offset1:195
	v_add_u32_e32 v19, 0x400, v18
	ds_read2_b32 v[26:27], v19 offset0:4 offset1:69
	ds_read2_b32 v[28:29], v19 offset0:134 offset1:199
	s_and_b32 s8, s46, 0xffffffc0
	s_waitcnt lgkmcnt(3)
	v_cvt_pk_bf16_f32 v20, v20, v21
	s_waitcnt lgkmcnt(2)
	v_cvt_pk_bf16_f32 v21, v22, v23
	s_waitcnt lgkmcnt(1)
	v_cvt_pk_bf16_f32 v22, v26, v27
	v_add_u32_e32 v24, s8, v15
	v_ashrrev_i32_e32 v25, 31, v24
	s_and_b32 s0, s0, 0x3c0
	s_waitcnt lgkmcnt(0)
	v_cvt_pk_bf16_f32 v23, v28, v29
	v_lshlrev_b64 v[24:25], 11, v[24:25]
	v_lshl_add_u64 v[24:25], s[14:15], 0, v[24:25]
	s_lshl_b32 s0, s0, 1
	v_lshl_add_u64 v[24:25], v[24:25], 0, s[0:1]
	v_lshl_add_u64 v[24:25], v[24:25], 0, v[10:11]
	global_store_dwordx4 v[24:25], v[20:23], off
	s_waitcnt lgkmcnt(0)
	s_barrier
	s_andn2_b64 vcc, exec, s[6:7]
	s_mov_b32 s0, s47
	s_mov_b32 s46, s45
	s_cbranch_vccz .LBB0_3911

.LBB0_3970:
	ds_read2_b32 v[20:21], v18 offset1:65
	ds_read2_b32 v[22:23], v18 offset0:130 offset1:195
	v_add_u32_e32 v19, 0x400, v18
	ds_read2_b32 v[26:27], v19 offset0:4 offset1:69
	ds_read2_b32 v[28:29], v19 offset0:134 offset1:199
	s_and_b32 s0, s10, 0xffffffc0
	s_waitcnt lgkmcnt(3)
	v_cvt_pk_bf16_f32 v20, v20, v21
	s_waitcnt lgkmcnt(2)
	v_cvt_pk_bf16_f32 v21, v22, v23
	s_waitcnt lgkmcnt(1)
	v_cvt_pk_bf16_f32 v22, v26, v27
	v_add_u32_e32 v24, s0, v15
	v_ashrrev_i32_e32 v25, 31, v24
	s_and_b32 s3, s3, 0x3c0
	s_waitcnt lgkmcnt(0)
	v_cvt_pk_bf16_f32 v23, v28, v29
	v_lshlrev_b64 v[24:25], 11, v[24:25]
	v_lshl_add_u64 v[24:25], s[14:15], 0, v[24:25]
	s_lshl_b32 s0, s3, 1
	v_lshl_add_u64 v[24:25], v[24:25], 0, s[0:1]
	v_lshl_add_u64 v[24:25], v[24:25], 0, v[10:11]
	global_store_dwordx4 v[24:25], v[20:23], off
	s_waitcnt lgkmcnt(0)
	s_barrier
	s_andn2_b64 vcc, exec, s[4:5]
	s_mov_b32 s3, s19
	s_mov_b32 s10, s17
	s_cbranch_vccz .LBB0_3975

.LBB0_4050:
	v_pk_add_f32 v[28:29], v[28:29], v[32:33]
	v_pk_add_f32 v[30:31], v[30:31], v[34:35]
	v_pk_mul_f32 v[34:35], v[28:29], v[28:29]
	v_pk_mul_f32 v[32:33], v[30:31], v[30:31]
	v_add_f32_e32 v34, v34, v35
	v_add_f32_e32 v32, v32, v34
	v_add_f32_e32 v32, v33, v32
	ds_bpermute_b32 v33, v1, v32
	v_pk_add_f32 v[22:23], v[22:23], v[26:27]
	v_pk_add_f32 v[20:21], v[20:21], v[24:25]
	v_lshlrev_b32_e32 v25, 16, v60
	v_mul_f32_e32 v25, 0xbfb8aa3b, v25
	s_waitcnt lgkmcnt(0)
	v_add_f32_e32 v26, v32, v33
	ds_bpermute_b32 v27, v62, v26
	v_and_b32_e32 v32, 0xffff0000, v60
	v_exp_f32_e32 v25, v25
	v_lshlrev_b32_e32 v33, 16, v61
	v_and_b32_e32 v34, 0xffff0000, v61
	s_waitcnt lgkmcnt(0)
	v_add_f32_e32 v26, v26, v27
	ds_bpermute_b32 v27, v63, v26
	v_add_f32_e32 v25, 1.0, v25
	v_mul_f32_e32 v33, 0xbfb8aa3b, v33
	v_mul_f32_e32 v34, 0xbfb8aa3b, v34
	v_lshlrev_b32_e32 v24, 16, v58
	s_waitcnt lgkmcnt(0)
	v_add_f32_e32 v26, v26, v27
	ds_bpermute_b32 v27, v64, v26
	v_exp_f32_e32 v33, v33
	v_exp_f32_e32 v34, v34
	v_mul_f32_e32 v35, 0xbfb8aa3b, v24
	v_exp_f32_e32 v35, v35
	s_waitcnt lgkmcnt(0)
	v_add_f32_e32 v26, v26, v27
	ds_bpermute_b32 v27, v65, v26
	v_add_f32_e32 v33, 1.0, v33
	v_add_f32_e32 v34, 1.0, v34
	v_and_b32_e32 v58, 0xffff0000, v58
	v_add_f32_e32 v35, 1.0, v35
	s_waitcnt lgkmcnt(0)
	v_add_f32_e32 v27, v26, v27
	ds_bpermute_b32 v60, v66, v27
	v_rcp_f32_e32 v26, v25
	v_mov_b32_e32 v72, v20
	v_mul_f32_e32 v32, 0xbfb8aa3b, v32
	v_exp_f32_e32 v32, v32
	s_waitcnt lgkmcnt(0)
	v_add_f32_e32 v25, v27, v60
	v_fmamk_f32 v25, v25, 0x3b800000, v67
	v_mul_f32_e32 v27, 0x4b800000, v25
	v_cmp_gt_f32_e32 vcc, s3, v25
	v_mul_f32_e32 v60, 0xbfb8aa3b, v58
	v_exp_f32_e32 v61, v60
	v_cndmask_b32_e32 v25, v25, v27, vcc
	v_rsq_f32_e32 v25, v25
	v_rcp_f32_e32 v27, v33
	v_rcp_f32_e32 v33, v34
	v_rcp_f32_e32 v60, v35
	v_mul_f32_e32 v34, 0x45800000, v25
	v_cndmask_b32_e32 v34, v25, v34, vcc
	v_lshlrev_b32_e32 v25, 16, v59
	v_mul_f32_e32 v35, 0xbfb8aa3b, v25
	v_exp_f32_e32 v35, v35
	v_and_b32_e32 v59, 0xffff0000, v59
	v_add_f32_e32 v61, 1.0, v61
	v_rcp_f32_e32 v70, v61
	v_add_f32_e32 v20, 1.0, v35
	v_rcp_f32_e32 v61, v20
	v_mul_f32_e32 v20, 0xbfb8aa3b, v59
	v_exp_f32_e32 v20, v20
	v_add_f32_e32 v32, 1.0, v32
	v_rcp_f32_e32 v32, v32
	v_mov_b32_e32 v73, v22
	v_add_f32_e32 v20, 1.0, v20
	v_rcp_f32_e32 v71, v20
	v_pk_mul_f32 v[26:27], v[72:73], v[26:27]
	v_pk_mul_f32 v[24:25], v[60:61], v[24:25]
	v_mov_b32_e32 v22, v21
	v_pk_mul_f32 v[24:25], v[26:27], v[24:25]
	v_pk_mul_f32 v[20:21], v[22:23], v[32:33]
	v_pk_mul_f32 v[22:23], v[70:71], v[58:59]
	v_lshl_add_u64 v[40:41], v[40:41], 0, s[0:1]
	v_pk_mul_f32 v[20:21], v[20:21], v[22:23]
	v_and_b32_sdwa v23, v24, v68 dst_sel:DWORD dst_unused:UNUSED_PAD src0_sel:WORD_1 src1_sel:DWORD
	v_add3_u32 v23, v24, v23, s11
	v_cvt_pk_bf16_f32 v21, v25, v21
	v_and_b32_sdwa v25, v20, v68 dst_sel:DWORD dst_unused:UNUSED_PAD src0_sel:WORD_1 src1_sel:DWORD
	v_add3_u32 v20, v20, v25, s11
	v_and_b32_e32 v20, 0xffff0000, v20
	v_or_b32_sdwa v20, v20, v23 dst_sel:DWORD dst_unused:UNUSED_PAD src0_sel:DWORD src1_sel:WORD_1
	v_lshl_add_u64 v[22:23], v[50:51], 0, v[36:37]
	v_add_co_u32_e32 v22, vcc, s10, v22
	v_and_b32_e32 v24, 0xffff0000, v44
	s_nop 0
	v_addc_co_u32_e32 v23, vcc, 0, v23, vcc
	global_store_dwordx2 v[22:23], v[20:21], off
	v_lshlrev_b32_e32 v20, 16, v44
	v_mul_f32_e32 v25, 0xbfb8aa3b, v20
	v_exp_f32_e32 v26, v25
	v_mul_f32_e32 v25, 0xbfb8aa3b, v24
	v_exp_f32_e32 v27, v25
	v_lshlrev_b32_e32 v21, 16, v45
	v_and_b32_e32 v25, 0xffff0000, v45
	v_add_f32_e32 v26, 1.0, v26
	v_add_f32_e32 v27, 1.0, v27
	v_rcp_f32_e32 v32, v27
	v_mul_f32_e32 v27, 0xbfb8aa3b, v21
	v_exp_f32_e32 v27, v27
	v_mov_b32_e32 v44, v28
	v_mul_f32_e32 v28, 0xbfb8aa3b, v25
	v_rcp_f32_e32 v26, v26
	v_add_f32_e32 v27, 1.0, v27
	v_rcp_f32_e32 v27, v27
	v_exp_f32_e32 v28, v28
	v_mov_b32_e32 v45, v30
	v_pk_mul_f32 v[44:45], v[44:45], v[34:35] op_sel_hi:[1,0]
	v_pk_mul_f32 v[20:21], v[26:27], v[20:21]
	v_add_f32_e32 v26, 1.0, v28
	v_rcp_f32_e32 v33, v26
	v_mov_b32_e32 v30, v29
	v_pk_mul_f32 v[44:45], v[2:3], v[44:45]
	v_pk_mul_f32 v[26:27], v[30:31], v[34:35] op_sel_hi:[1,0]
	v_pk_mul_f32 v[20:21], v[20:21], v[44:45]
	v_pk_mul_f32 v[26:27], v[38:39], v[26:27]
	v_pk_mul_f32 v[24:25], v[32:33], v[24:25]
	s_waitcnt vmcnt(5)
	v_mov_b64_e32 v[30:31], v[14:15]
	v_pk_mul_f32 v[24:25], v[24:25], v[26:27]
	v_and_b32_sdwa v26, v21, v68 dst_sel:DWORD dst_unused:UNUSED_PAD src0_sel:WORD_1 src1_sel:DWORD
	v_and_b32_sdwa v27, v20, v68 dst_sel:DWORD dst_unused:UNUSED_PAD src0_sel:WORD_1 src1_sel:DWORD
	v_add3_u32 v20, v20, v27, s11
	v_add3_u32 v21, v21, v26, s11
	v_and_b32_sdwa v26, v25, v68 dst_sel:DWORD dst_unused:UNUSED_PAD src0_sel:WORD_1 src1_sel:DWORD
	v_and_b32_sdwa v27, v24, v68 dst_sel:DWORD dst_unused:UNUSED_PAD src0_sel:WORD_1 src1_sel:DWORD
	v_add3_u32 v25, v25, v26, s11
	v_add3_u32 v24, v24, v27, s11
	v_and_b32_e32 v25, 0xffff0000, v25
	v_and_b32_e32 v24, 0xffff0000, v24
	v_or_b32_sdwa v21, v25, v21 dst_sel:DWORD dst_unused:UNUSED_PAD src0_sel:DWORD src1_sel:WORD_1
	v_or_b32_sdwa v20, v24, v20 dst_sel:DWORD dst_unused:UNUSED_PAD src0_sel:DWORD src1_sel:WORD_1
	global_store_dwordx2 v[22:23], v[20:21], off offset:2048
	v_mov_b64_e32 v[22:23], v[6:7]
	v_mov_b64_e32 v[26:27], v[10:11]
	s_waitcnt vmcnt(5)
	v_mov_b64_e32 v[34:35], v[18:19]
	v_lshl_add_u64 v[46:47], v[46:47], 0, s[20:21]
	v_lshl_add_u64 v[48:49], v[48:49], 0, s[20:21]
	v_lshl_add_u64 v[50:51], v[50:51], 0, s[22:23]
	s_andn2_b64 vcc, exec, s[26:27]
	v_mov_b64_e32 v[20:21], v[4:5]
	v_mov_b64_e32 v[24:25], v[8:9]
	v_mov_b64_e32 v[28:29], v[12:13]
	v_mov_b64_e32 v[32:33], v[16:17]
	s_waitcnt vmcnt(4)
	v_mov_b64_e32 v[60:61], v[54:55]
	s_waitcnt vmcnt(3)
	v_mov_b64_e32 v[58:59], v[52:53]
	s_waitcnt vmcnt(2)
	v_mov_b64_e32 v[44:45], v[56:57]
	s_cbranch_vccz .LBB0_4053

.LBB0_4057:
	v_pk_add_f32 v[28:29], v[28:29], v[32:33]
	v_pk_add_f32 v[30:31], v[30:31], v[34:35]
	v_pk_mul_f32 v[34:35], v[28:29], v[28:29]
	v_pk_mul_f32 v[32:33], v[30:31], v[30:31]
	v_add_f32_e32 v34, v34, v35
	v_add_f32_e32 v32, v32, v34
	v_add_f32_e32 v32, v33, v32
	ds_bpermute_b32 v33, v1, v32
	v_pk_add_f32 v[22:23], v[22:23], v[26:27]
	v_pk_add_f32 v[20:21], v[20:21], v[24:25]
	v_lshlrev_b32_e32 v25, 16, v60
	v_mul_f32_e32 v25, 0xbfb8aa3b, v25
	s_waitcnt lgkmcnt(0)
	v_add_f32_e32 v26, v32, v33
	ds_bpermute_b32 v27, v62, v26
	v_exp_f32_e32 v25, v25
	v_lshlrev_b32_e32 v33, 16, v61
	v_and_b32_e32 v34, 0xffff0000, v61
	v_mul_f32_e32 v33, 0xbfb8aa3b, v33
	s_waitcnt lgkmcnt(0)
	v_add_f32_e32 v26, v26, v27
	ds_bpermute_b32 v27, v63, v26
	v_add_f32_e32 v25, 1.0, v25
	v_mul_f32_e32 v34, 0xbfb8aa3b, v34
	v_exp_f32_e32 v33, v33
	v_exp_f32_e32 v34, v34
	s_waitcnt lgkmcnt(0)
	v_add_f32_e32 v26, v26, v27
	ds_bpermute_b32 v27, v64, v26
	v_add_f32_e32 v33, 1.0, v33
	v_add_f32_e32 v34, 1.0, v34
	v_lshlrev_b32_e32 v24, 16, v58
	v_and_b32_e32 v58, 0xffff0000, v58
	s_waitcnt lgkmcnt(0)
	v_add_f32_e32 v26, v26, v27
	ds_bpermute_b32 v27, v65, v26
	v_and_b32_e32 v32, 0xffff0000, v60
	v_mul_f32_e32 v60, 0xbfb8aa3b, v58
	v_exp_f32_e32 v61, v60
	v_mov_b32_e32 v72, v20
	s_waitcnt lgkmcnt(0)
	v_add_f32_e32 v27, v26, v27
	ds_bpermute_b32 v35, v66, v27
	v_rcp_f32_e32 v26, v25
	v_add_f32_e32 v61, 1.0, v61
	v_mul_f32_e32 v32, 0xbfb8aa3b, v32
	v_rcp_f32_e32 v70, v61
	s_waitcnt lgkmcnt(0)
	v_add_f32_e32 v25, v27, v35
	v_fmamk_f32 v25, v25, 0x3b800000, v67
	v_mul_f32_e32 v27, 0x4b800000, v25
	v_cmp_gt_f32_e32 vcc, s10, v25
	v_exp_f32_e32 v32, v32
	v_mov_b32_e32 v73, v22
	v_cndmask_b32_e32 v25, v25, v27, vcc
	v_rsq_f32_e32 v25, v25
	v_rcp_f32_e32 v27, v33
	v_rcp_f32_e32 v33, v34
	v_add_f32_e32 v32, 1.0, v32
	v_mul_f32_e32 v34, 0x45800000, v25
	v_cndmask_b32_e32 v34, v25, v34, vcc
	v_mul_f32_e32 v25, 0xbfb8aa3b, v24
	v_exp_f32_e32 v35, v25
	v_lshlrev_b32_e32 v25, 16, v59
	v_and_b32_e32 v59, 0xffff0000, v59
	v_rcp_f32_e32 v32, v32
	v_add_f32_e32 v35, 1.0, v35
	v_rcp_f32_e32 v60, v35
	v_mul_f32_e32 v35, 0xbfb8aa3b, v25
	v_exp_f32_e32 v35, v35
	v_pk_mul_f32 v[26:27], v[72:73], v[26:27]
	v_mov_b32_e32 v22, v21
	s_addk_i32 s20, 0x80
	v_add_f32_e32 v20, 1.0, v35
	v_rcp_f32_e32 v61, v20
	v_mul_f32_e32 v20, 0xbfb8aa3b, v59
	v_exp_f32_e32 v20, v20
	v_lshl_add_u64 v[40:41], v[40:41], 0, s[0:1]
	v_pk_mul_f32 v[24:25], v[60:61], v[24:25]
	v_lshl_add_u64 v[44:45], v[44:45], 0, s[22:23]
	v_add_f32_e32 v20, 1.0, v20
	v_rcp_f32_e32 v71, v20
	v_pk_mul_f32 v[24:25], v[26:27], v[24:25]
	v_pk_mul_f32 v[20:21], v[22:23], v[32:33]
	v_lshl_add_u64 v[46:47], v[46:47], 0, s[22:23]
	v_pk_mul_f32 v[22:23], v[70:71], v[58:59]
	s_waitcnt vmcnt(2)
	v_mov_b64_e32 v[60:61], v[54:55]
	v_pk_mul_f32 v[20:21], v[20:21], v[22:23]
	v_and_b32_sdwa v23, v24, v68 dst_sel:DWORD dst_unused:UNUSED_PAD src0_sel:WORD_1 src1_sel:DWORD
	v_add3_u32 v23, v24, v23, s11
	v_cvt_pk_bf16_f32 v21, v25, v21
	v_and_b32_sdwa v25, v20, v68 dst_sel:DWORD dst_unused:UNUSED_PAD src0_sel:WORD_1 src1_sel:DWORD
	v_add3_u32 v20, v20, v25, s11
	v_and_b32_e32 v20, 0xffff0000, v20
	v_or_b32_sdwa v20, v20, v23 dst_sel:DWORD dst_unused:UNUSED_PAD src0_sel:DWORD src1_sel:WORD_1
	v_lshl_add_u64 v[22:23], v[50:51], 0, v[36:37]
	v_add_co_u32_e32 v22, vcc, s3, v22
	v_and_b32_e32 v24, 0xffff0000, v48
	s_nop 0
	v_addc_co_u32_e32 v23, vcc, 0, v23, vcc
	global_store_dwordx2 v[22:23], v[20:21], off
	v_lshlrev_b32_e32 v20, 16, v48
	v_mul_f32_e32 v25, 0xbfb8aa3b, v20
	v_exp_f32_e32 v26, v25
	v_mul_f32_e32 v25, 0xbfb8aa3b, v24
	v_exp_f32_e32 v27, v25
	v_lshlrev_b32_e32 v21, 16, v49
	v_and_b32_e32 v25, 0xffff0000, v49
	v_add_f32_e32 v26, 1.0, v26
	v_add_f32_e32 v27, 1.0, v27
	v_rcp_f32_e32 v32, v27
	v_mul_f32_e32 v27, 0xbfb8aa3b, v21
	v_exp_f32_e32 v27, v27
	v_mov_b32_e32 v48, v28
	v_mul_f32_e32 v28, 0xbfb8aa3b, v25
	v_rcp_f32_e32 v26, v26
	v_add_f32_e32 v27, 1.0, v27
	v_rcp_f32_e32 v27, v27
	v_exp_f32_e32 v28, v28
	v_mov_b32_e32 v49, v30
	v_pk_mul_f32 v[48:49], v[48:49], v[34:35] op_sel_hi:[1,0]
	v_pk_mul_f32 v[20:21], v[26:27], v[20:21]
	v_add_f32_e32 v26, 1.0, v28
	v_rcp_f32_e32 v33, v26
	v_mov_b32_e32 v30, v29
	v_pk_mul_f32 v[48:49], v[2:3], v[48:49]
	v_pk_mul_f32 v[26:27], v[30:31], v[34:35] op_sel_hi:[1,0]
	v_pk_mul_f32 v[20:21], v[20:21], v[48:49]
	v_pk_mul_f32 v[26:27], v[38:39], v[26:27]
	v_pk_mul_f32 v[24:25], v[32:33], v[24:25]
	v_mov_b64_e32 v[30:31], v[14:15]
	v_pk_mul_f32 v[24:25], v[24:25], v[26:27]
	v_and_b32_sdwa v26, v21, v68 dst_sel:DWORD dst_unused:UNUSED_PAD src0_sel:WORD_1 src1_sel:DWORD
	v_and_b32_sdwa v27, v20, v68 dst_sel:DWORD dst_unused:UNUSED_PAD src0_sel:WORD_1 src1_sel:DWORD
	v_add3_u32 v20, v20, v27, s11
	v_add3_u32 v21, v21, v26, s11
	v_and_b32_sdwa v26, v25, v68 dst_sel:DWORD dst_unused:UNUSED_PAD src0_sel:WORD_1 src1_sel:DWORD
	v_and_b32_sdwa v27, v24, v68 dst_sel:DWORD dst_unused:UNUSED_PAD src0_sel:WORD_1 src1_sel:DWORD
	v_add3_u32 v25, v25, v26, s11
	v_add3_u32 v24, v24, v27, s11
	v_and_b32_e32 v25, 0xffff0000, v25
	v_and_b32_e32 v24, 0xffff0000, v24
	v_or_b32_sdwa v21, v25, v21 dst_sel:DWORD dst_unused:UNUSED_PAD src0_sel:DWORD src1_sel:WORD_1
	v_or_b32_sdwa v20, v24, v20 dst_sel:DWORD dst_unused:UNUSED_PAD src0_sel:DWORD src1_sel:WORD_1
	global_store_dwordx2 v[22:23], v[20:21], off offset:2048
	v_mov_b64_e32 v[22:23], v[6:7]
	v_mov_b64_e32 v[26:27], v[10:11]
	v_mov_b64_e32 v[34:35], v[18:19]
	v_lshl_add_u64 v[50:51], v[50:51], 0, s[26:27]
	s_and_b64 vcc, exec, s[34:35]
	v_mov_b64_e32 v[20:21], v[4:5]
	v_mov_b64_e32 v[24:25], v[8:9]
	v_mov_b64_e32 v[28:29], v[12:13]
	v_mov_b64_e32 v[32:33], v[16:17]
	s_waitcnt vmcnt(3)
	v_mov_b64_e32 v[58:59], v[52:53]
	s_waitcnt vmcnt(2)
	v_mov_b64_e32 v[48:49], v[56:57]
	s_cbranch_vccnz .LBB0_4060

.LBB0_4064:
	v_pk_add_f32 v[28:29], v[28:29], v[32:33]
	v_pk_add_f32 v[30:31], v[30:31], v[34:35]
	v_pk_mul_f32 v[34:35], v[28:29], v[28:29]
	v_pk_mul_f32 v[32:33], v[30:31], v[30:31]
	v_add_f32_e32 v34, v34, v35
	v_add_f32_e32 v32, v32, v34
	v_add_f32_e32 v32, v33, v32
	ds_bpermute_b32 v33, v1, v32
	v_pk_add_f32 v[22:23], v[22:23], v[26:27]
	v_pk_add_f32 v[20:21], v[20:21], v[24:25]
	v_lshlrev_b32_e32 v25, 16, v60
	v_mul_f32_e32 v25, 0xbfb8aa3b, v25
	s_waitcnt lgkmcnt(0)
	v_add_f32_e32 v26, v32, v33
	ds_bpermute_b32 v27, v62, v26
	v_and_b32_e32 v32, 0xffff0000, v60
	v_exp_f32_e32 v25, v25
	v_lshlrev_b32_e32 v33, 16, v61
	v_and_b32_e32 v34, 0xffff0000, v61
	s_waitcnt lgkmcnt(0)
	v_add_f32_e32 v26, v26, v27
	ds_bpermute_b32 v27, v63, v26
	v_add_f32_e32 v25, 1.0, v25
	v_mul_f32_e32 v33, 0xbfb8aa3b, v33
	v_mul_f32_e32 v34, 0xbfb8aa3b, v34
	v_lshlrev_b32_e32 v24, 16, v58
	s_waitcnt lgkmcnt(0)
	v_add_f32_e32 v26, v26, v27
	ds_bpermute_b32 v27, v64, v26
	v_exp_f32_e32 v33, v33
	v_exp_f32_e32 v34, v34
	v_mul_f32_e32 v35, 0xbfb8aa3b, v24
	v_exp_f32_e32 v35, v35
	s_waitcnt lgkmcnt(0)
	v_add_f32_e32 v26, v26, v27
	ds_bpermute_b32 v27, v65, v26
	v_add_f32_e32 v33, 1.0, v33
	v_add_f32_e32 v34, 1.0, v34
	v_and_b32_e32 v58, 0xffff0000, v58
	v_add_f32_e32 v35, 1.0, v35
	s_waitcnt lgkmcnt(0)
	v_add_f32_e32 v27, v26, v27
	ds_bpermute_b32 v60, v66, v27
	v_rcp_f32_e32 v26, v25
	v_mov_b32_e32 v72, v20
	v_mul_f32_e32 v32, 0xbfb8aa3b, v32
	v_exp_f32_e32 v32, v32
	s_waitcnt lgkmcnt(0)
	v_add_f32_e32 v25, v27, v60
	v_fmamk_f32 v25, v25, 0x3b800000, v67
	v_mul_f32_e32 v27, 0x4b800000, v25
	v_cmp_gt_f32_e32 vcc, s11, v25
	v_mul_f32_e32 v60, 0xbfb8aa3b, v58
	v_exp_f32_e32 v61, v60
	v_cndmask_b32_e32 v25, v25, v27, vcc
	v_rsq_f32_e32 v25, v25
	v_rcp_f32_e32 v27, v33
	v_rcp_f32_e32 v33, v34
	v_rcp_f32_e32 v60, v35
	v_mul_f32_e32 v34, 0x45800000, v25
	v_cndmask_b32_e32 v34, v25, v34, vcc
	v_lshlrev_b32_e32 v25, 16, v59
	v_mul_f32_e32 v35, 0xbfb8aa3b, v25
	v_exp_f32_e32 v35, v35
	v_and_b32_e32 v59, 0xffff0000, v59
	v_add_f32_e32 v61, 1.0, v61
	v_rcp_f32_e32 v70, v61
	v_add_f32_e32 v20, 1.0, v35
	v_rcp_f32_e32 v61, v20
	v_mul_f32_e32 v20, 0xbfb8aa3b, v59
	v_exp_f32_e32 v20, v20
	v_add_f32_e32 v32, 1.0, v32
	v_rcp_f32_e32 v32, v32
	v_mov_b32_e32 v73, v22
	v_add_f32_e32 v20, 1.0, v20
	v_rcp_f32_e32 v71, v20
	v_pk_mul_f32 v[26:27], v[72:73], v[26:27]
	v_pk_mul_f32 v[24:25], v[60:61], v[24:25]
	v_mov_b32_e32 v22, v21
	v_pk_mul_f32 v[24:25], v[26:27], v[24:25]
	v_pk_mul_f32 v[20:21], v[22:23], v[32:33]
	v_pk_mul_f32 v[22:23], v[70:71], v[58:59]
	s_add_i32 s20, s20, s22
	v_pk_mul_f32 v[20:21], v[20:21], v[22:23]
	v_and_b32_sdwa v23, v24, v68 dst_sel:DWORD dst_unused:UNUSED_PAD src0_sel:WORD_1 src1_sel:DWORD
	v_add3_u32 v23, v24, v23, s12
	v_cvt_pk_bf16_f32 v21, v25, v21
	v_and_b32_sdwa v25, v20, v68 dst_sel:DWORD dst_unused:UNUSED_PAD src0_sel:WORD_1 src1_sel:DWORD
	v_add3_u32 v20, v20, v25, s12
	v_and_b32_e32 v20, 0xffff0000, v20
	v_or_b32_sdwa v20, v20, v23 dst_sel:DWORD dst_unused:UNUSED_PAD src0_sel:DWORD src1_sel:WORD_1
	v_lshl_add_u64 v[22:23], v[50:51], 0, v[36:37]
	v_add_co_u32_e32 v22, vcc, s10, v22
	v_and_b32_e32 v24, 0xffff0000, v44
	s_nop 0
	v_addc_co_u32_e32 v23, vcc, 0, v23, vcc
	global_store_dwordx2 v[22:23], v[20:21], off
	v_lshlrev_b32_e32 v20, 16, v44
	v_mul_f32_e32 v25, 0xbfb8aa3b, v20
	v_exp_f32_e32 v26, v25
	v_mul_f32_e32 v25, 0xbfb8aa3b, v24
	v_exp_f32_e32 v27, v25
	v_lshlrev_b32_e32 v21, 16, v45
	v_and_b32_e32 v25, 0xffff0000, v45
	v_add_f32_e32 v26, 1.0, v26
	v_add_f32_e32 v27, 1.0, v27
	v_rcp_f32_e32 v32, v27
	v_mul_f32_e32 v27, 0xbfb8aa3b, v21
	v_exp_f32_e32 v27, v27
	v_mov_b32_e32 v44, v28
	v_mul_f32_e32 v28, 0xbfb8aa3b, v25
	v_rcp_f32_e32 v26, v26
	v_add_f32_e32 v27, 1.0, v27
	v_rcp_f32_e32 v27, v27
	v_exp_f32_e32 v28, v28
	v_mov_b32_e32 v45, v30
	v_pk_mul_f32 v[44:45], v[44:45], v[34:35] op_sel_hi:[1,0]
	v_pk_mul_f32 v[20:21], v[26:27], v[20:21]
	v_add_f32_e32 v26, 1.0, v28
	v_rcp_f32_e32 v33, v26
	v_mov_b32_e32 v30, v29
	v_pk_mul_f32 v[44:45], v[2:3], v[44:45]
	v_pk_mul_f32 v[26:27], v[30:31], v[34:35] op_sel_hi:[1,0]
	v_pk_mul_f32 v[20:21], v[20:21], v[44:45]
	v_pk_mul_f32 v[26:27], v[38:39], v[26:27]
	v_pk_mul_f32 v[24:25], v[32:33], v[24:25]
	s_waitcnt vmcnt(5)
	v_mov_b64_e32 v[30:31], v[14:15]
	v_pk_mul_f32 v[24:25], v[24:25], v[26:27]
	v_and_b32_sdwa v26, v21, v68 dst_sel:DWORD dst_unused:UNUSED_PAD src0_sel:WORD_1 src1_sel:DWORD
	v_and_b32_sdwa v27, v20, v68 dst_sel:DWORD dst_unused:UNUSED_PAD src0_sel:WORD_1 src1_sel:DWORD
	v_add3_u32 v20, v20, v27, s12
	v_add3_u32 v21, v21, v26, s12
	v_and_b32_sdwa v26, v25, v68 dst_sel:DWORD dst_unused:UNUSED_PAD src0_sel:WORD_1 src1_sel:DWORD
	v_and_b32_sdwa v27, v24, v68 dst_sel:DWORD dst_unused:UNUSED_PAD src0_sel:WORD_1 src1_sel:DWORD
	v_add3_u32 v25, v25, v26, s12
	v_add3_u32 v24, v24, v27, s12
	v_and_b32_e32 v25, 0xffff0000, v25
	v_and_b32_e32 v24, 0xffff0000, v24
	v_or_b32_sdwa v21, v25, v21 dst_sel:DWORD dst_unused:UNUSED_PAD src0_sel:DWORD src1_sel:WORD_1
	v_or_b32_sdwa v20, v24, v20 dst_sel:DWORD dst_unused:UNUSED_PAD src0_sel:DWORD src1_sel:WORD_1
	global_store_dwordx2 v[22:23], v[20:21], off offset:2048
	v_mov_b64_e32 v[22:23], v[6:7]
	v_mov_b64_e32 v[26:27], v[10:11]
	s_waitcnt vmcnt(5)
	v_mov_b64_e32 v[34:35], v[18:19]
	v_lshl_add_u64 v[40:41], v[40:41], 0, s[0:1]
	v_lshl_add_u64 v[46:47], v[46:47], 0, s[4:5]
	v_lshl_add_u64 v[48:49], v[48:49], 0, s[4:5]
	v_lshl_add_u64 v[50:51], v[50:51], 0, s[8:9]
	s_cmp_ge_i32 s20, s3
	v_mov_b64_e32 v[20:21], v[4:5]
	v_mov_b64_e32 v[24:25], v[8:9]
	v_mov_b64_e32 v[28:29], v[12:13]
	v_mov_b64_e32 v[32:33], v[16:17]
	s_waitcnt vmcnt(4)
	v_mov_b64_e32 v[60:61], v[54:55]
	s_waitcnt vmcnt(3)
	v_mov_b64_e32 v[58:59], v[52:53]
	s_waitcnt vmcnt(2)
	v_mov_b64_e32 v[44:45], v[56:57]
	s_cbranch_scc1 .LBB0_4067
